# speedup vs baseline: 1.0080x; 1.0007x over previous
;     ...
;       const int tid3 = opaque_tid(wave);
;       const int wr3 = tid3 >> 8, wc3 = (tid3 >> 6) & 3, fr3 = tid3 & 15, fq3 = (tid3 & 63) >> 4;
;       const int ebase3 = (brow + wr3 * 64 + fr3) * DM + pn * BM + wc3 * 32 + fq3 * 4;
;       const int vo4b = ebase3 * 4, vo2 = ebase3 * 2, vo1 = ebase3;
;       (void)vo4b; (void)vo2; (void)vo1;
;       if constexpr (OUTF) {
;         _Pragma("unroll") for (int bj = 0; bj < 2; ++bj) _Pragma("unroll") for (int n = 0; n < 2; ++n) {
;           const int col = pn * BM + bj * HALF + wc3 * 32 + n * 16 + fq3 * 4;
;           const float4 gm = *reinterpret_cast<const float4*>(g.gam + col), bt = *reinterpret_cast<const float4*>(g.bet + col);
;           _Pragma("unroll") for (int ai = 0; ai < 2; ++ai) _Pragma("unroll") for (int m = 0; m < 4; ++m) {
;             const int rl = ai * HALF + wr3 * 64 + m * 16 + fr3;
;             const float2 ms = *reinterpret_cast<const float2*>(mr + rl * 2);
;             f32x4 y = acc[ai][bj][m][n];
;             u32x4 o;
;             o[0] = __float_as_uint((y[0] - ms.x) * ms.y * gm.x + bt.x); o[1] = __float_as_uint((y[1] - ms.x) * ms.y * gm.y + bt.y);
;             o[2] = __float_as_uint((y[2] - ms.x) * ms.y * gm.z + bt.z); o[3] = __float_as_uint((y[3] - ms.x) * ms.y * gm.w + bt.w);
;             __builtin_amdgcn_raw_buffer_store_b128(o, rsO, vo4b + ((ai * HALF + m * 16) * DM + bj * HALF + n * 16) * 4, 0, 0);
;           }
;         }
;       } else {
;         constexpr int PIECE = 1024 + 16, LOBASE = 64 * PIECE;
;         const int lane3 = tid3 & 63;
;         const int hvo = (lane3 >> 5) * (DM * 2) + (lane3 & 31) * 16;
;         const int lvo = (lane3 >> 4) * DM + (lane3 & 15) * 16;
;         _Pragma("unroll") for (int ai = 0; ai < 2; ++ai) {
;           _Pragma("unroll") for (int bj = 0; bj < 2; ++bj) _Pragma("unroll") for (int n = 0; n < 2; ++n) {
;             const int cc = bj * HALF + wc3 * 32 + n * 16 + fq3 * 4;
;             const float4 gm = *reinterpret_cast<const float4*>(g.gam + pn * BM + cc), bt = *reinterpret_cast<const float4*>(g.bet + pn * BM + cc);
;             _Pragma("unroll") for (int m = 0; m < 4; ++m) {
;               const int rr = wr3 * 64 + m * 16 + fr3;
;               const float2 ms = *reinterpret_cast<const float2*>(mr + (ai * HALF + rr) * 2);
;               f32x4 y = acc[ai][bj][m][n];
.LBB0_177:
	s_or_b64 exec, exec, s[6:7]
	s_waitcnt lgkmcnt(0)
	s_barrier
	v_mbcnt_lo_u32_b32 v0, -1, 0
	v_mbcnt_hi_u32_b32 v0, -1, v0
	s_movk_i32 s4, 0x1000
	v_add_u32_e32 v1, s29, v0
	v_ashrrev_i32_e32 v5, 2, v1
	v_lshrrev_b32_e32 v6, 1, v1
	v_lshlrev_b32_e32 v1, 4, v1
	v_lshlrev_b32_e32 v12, 7, v0
	v_and_b32_e32 v13, 0x1f0, v1
	v_and_b32_e32 v2, 15, v0
	v_and_or_b32 v70, v12, s4, v13
	s_lshl_b32 s4, s0, 8
	s_movk_i32 s0, 0xffc0
	v_and_or_b32 v97, v5, s0, v2
	s_lshl_b32 s0, s18, 19
	v_bfe_u32 v4, v0, 4, 2
	s_ashr_i32 s5, s4, 31
	s_add_i32 s0, s0, s42
	v_lshlrev_b32_e32 v7, 2, v4
	s_add_i32 s0, s0, s4
	s_lshl_b64 s[4:5], s[4:5], 2
	v_and_or_b32 v12, v6, s61, v7
	s_add_u32 s6, s78, s4
	v_and_b32_e32 v3, 63, v0
	v_and_b32_e32 v1, 0xf0, v1
	v_lshlrev_b32_e32 v13, 9, v0
	v_lshlrev_b32_e32 v0, 8, v0
	s_addc_u32 s7, s79, s5
	v_lshlrev_b32_e32 v72, 2, v12
	v_lshl_or_b32 v68, v4, 11, v1
	v_and_b32_e32 v14, 0x300, v0
	v_lshlrev_b32_e32 v74, 4, v3
	global_load_dwordx4 v[196:199], v72, s[6:7]
	global_load_dwordx4 v[200:203], v72, s[6:7] offset:64
	global_load_dwordx4 v[204:207], v72, s[6:7] offset:512
	global_load_dwordx4 v[208:211], v72, s[6:7] offset:576
	s_add_u32 s4, s80, s4
	s_addc_u32 s5, s81, s5
	global_load_dwordx4 v[212:215], v72, s[4:5]
	global_load_dwordx4 v[220:223], v72, s[4:5] offset:64
	global_load_dwordx4 v[240:243], v72, s[4:5] offset:512
	global_load_dwordx4 v[248:251], v72, s[4:5] offset:576
	v_lshl_add_u32 v71, v97, 3, v246
	s_mov_b32 s18, 0x10400
	v_lshrrev_b32_e32 v67, 1, v97
	v_mul_lo_u32 v105, v67, s68
	v_add_u32_e32 v69, s59, v74
	s_lshl_b32 s22, s0, 1
	s_mov_b32 s23, s75
	s_andn2_b64 vcc, exec, s[14:15]
	s_waitcnt vmcnt(0)
	v_mov_b32_e32 v0, v196
	v_mov_b32_e32 v1, v197
	v_mov_b32_e32 v2, v198
	v_mov_b32_e32 v3, v199
	v_mov_b32_e32 v4, v212
	v_mov_b32_e32 v5, v213
	v_mov_b32_e32 v6, v214
	v_mov_b32_e32 v7, v215
	v_mov_b32_e32 v22, v1
	v_lshlrev_b32_e32 v1, 1, v12
	v_mov_b32_e32 v23, v2
	v_and_or_b32 v109, v13, s66, v1
	v_or3_b32 v2, v14, v12, s18
	ds_read_b64 v[12:13], v71
	v_mov_b32_e32 v64, v5
	v_mov_b32_e32 v65, v6
	v_mov_b32_e32 v1, v3
	v_mov_b32_e32 v5, v7
	s_waitcnt lgkmcnt(0)
	v_mov_b32_e32 v180, v12
	v_mov_b32_e32 v181, v13
	v_pk_add_f32 v[14:15], v[238:239], v[12:13] op_sel_hi:[1,0] neg_lo:[0,1] neg_hi:[0,1]
	v_pk_add_f32 v[20:21], v[236:237], v[12:13] op_sel_hi:[1,0] neg_lo:[0,1] neg_hi:[0,1]
	v_pk_mul_f32 v[14:15], v[12:13], v[14:15] op_sel:[1,0]
	v_pk_mul_f32 v[12:13], v[12:13], v[20:21] op_sel:[1,0]
	v_pk_fma_f32 v[14:15], v[22:23], v[14:15], v[64:65]
	v_pk_fma_f32 v[6:7], v[0:1], v[12:13], v[4:5]
	v_and_b32_sdwa v12, v14, v244 dst_sel:DWORD dst_unused:UNUSED_PAD src0_sel:WORD_1 src1_sel:DWORD
	v_add3_u32 v12, v14, v12, s67
	v_and_b32_e32 v20, 0xffff0000, v12
	v_and_b32_sdwa v12, v7, v244 dst_sel:DWORD dst_unused:UNUSED_PAD src0_sel:WORD_1 src1_sel:DWORD
	v_and_b32_sdwa v3, v15, v244 dst_sel:DWORD dst_unused:UNUSED_PAD src0_sel:WORD_1 src1_sel:DWORD
	v_and_b32_sdwa v13, v6, v244 dst_sel:DWORD dst_unused:UNUSED_PAD src0_sel:WORD_1 src1_sel:DWORD
	v_add3_u32 v12, v7, v12, s67
	v_add3_u32 v3, v15, v3, s67
	v_add3_u32 v21, v6, v13, s67
	v_and_b32_e32 v66, 0xffff0000, v12
	v_or_b32_sdwa v13, v66, v3 dst_sel:DWORD dst_unused:UNUSED_PAD src0_sel:DWORD src1_sel:WORD_1
	v_or_b32_sdwa v12, v21, v20 dst_sel:DWORD dst_unused:UNUSED_PAD src0_sel:WORD_1 src1_sel:DWORD
	v_add_u32_e32 v73, v109, v105
	ds_write_b64 v73, v[12:13]
	v_and_b32_e32 v12, 0xffff0000, v21
	v_sub_u32_e32 v6, v6, v12
	v_sub_u32_e32 v12, v14, v20
	v_and_b32_e32 v3, 0xffff0000, v3
	v_add_u32_e32 v12, 0x80, v12
	v_sub_u32_e32 v3, v15, v3
	v_sub_u32_e32 v7, v7, v66
	v_add_u32_e32 v6, 0x80, v6
	v_ashrrev_i32_e32 v12, 8, v12
	v_add_u32_e32 v3, 0x80, v3
	v_add_u32_e32 v7, 0x80, v7
	v_ashrrev_i32_e32 v6, 8, v6
	v_min_i32_e32 v12, 0x7f, v12
	v_ashrrev_i32_e32 v3, 8, v3
	v_ashrrev_i32_e32 v7, 8, v7
	v_min_i32_e32 v6, 0x7f, v6
	v_min_i32_sdwa v3, v3, s69 dst_sel:WORD_1 dst_unused:UNUSED_PAD src0_sel:DWORD src1_sel:DWORD
	v_min_i32_e32 v7, 0x7f, v7
	v_lshlrev_b32_e32 v12, 8, v12
	v_and_b32_e32 v12, 0xff00, v12
	v_and_b32_e32 v3, 0xff0000, v3
	v_perm_b32 v6, v7, v6, s76
	v_or3_b32 v3, v6, v12, v3
	v_lshrrev_b32_e32 v6, 2, v97
	v_mad_u64_u32 v[12:13], s[18:19], v6, s68, v[2:3]
	ds_write_b32 v12, v3
	v_or_b32_e32 v3, 16, v97
	v_lshl_add_u32 v13, v3, 3, v246
	ds_read_b64 v[6:7], v13
	v_lshrrev_b32_e32 v75, 1, v3
	v_mul_lo_u32 v106, v75, s68
	v_add_u32_e32 v75, v109, v106
	v_lshrrev_b32_e32 v3, 2, v3
	s_waitcnt lgkmcnt(0)
	v_mov_b32_e32 v182, v6
	v_mov_b32_e32 v183, v7
	v_pk_add_f32 v[14:15], v[218:219], v[6:7] op_sel_hi:[1,0] neg_lo:[0,1] neg_hi:[0,1]
	v_pk_add_f32 v[20:21], v[216:217], v[6:7] op_sel_hi:[1,0] neg_lo:[0,1] neg_hi:[0,1]
	v_pk_mul_f32 v[14:15], v[6:7], v[14:15] op_sel:[1,0]
	v_pk_mul_f32 v[6:7], v[6:7], v[20:21] op_sel:[1,0]
	v_pk_fma_f32 v[14:15], v[22:23], v[14:15], v[64:65]
	v_pk_fma_f32 v[6:7], v[0:1], v[6:7], v[4:5]
	v_and_b32_sdwa v20, v15, v244 dst_sel:DWORD dst_unused:UNUSED_PAD src0_sel:WORD_1 src1_sel:DWORD
	v_and_b32_sdwa v21, v14, v244 dst_sel:DWORD dst_unused:UNUSED_PAD src0_sel:WORD_1 src1_sel:DWORD
	v_add3_u32 v66, v15, v20, s67
	v_add3_u32 v20, v14, v21, s67
	v_and_b32_e32 v67, 0xffff0000, v20
	v_and_b32_sdwa v20, v7, v244 dst_sel:DWORD dst_unused:UNUSED_PAD src0_sel:WORD_1 src1_sel:DWORD
	v_and_b32_sdwa v21, v6, v244 dst_sel:DWORD dst_unused:UNUSED_PAD src0_sel:WORD_1 src1_sel:DWORD
	v_add3_u32 v20, v7, v20, s67
	v_add3_u32 v96, v6, v21, s67
	v_and_b32_e32 v98, 0xffff0000, v20
	v_or_b32_sdwa v21, v98, v66 dst_sel:DWORD dst_unused:UNUSED_PAD src0_sel:DWORD src1_sel:WORD_1
	v_or_b32_sdwa v20, v96, v67 dst_sel:DWORD dst_unused:UNUSED_PAD src0_sel:WORD_1 src1_sel:DWORD
	ds_write_b64 v75, v[20:21]
	v_and_b32_e32 v20, 0xffff0000, v96
	v_sub_u32_e32 v6, v6, v20
	v_sub_u32_e32 v14, v14, v67
	v_and_b32_e32 v20, 0xffff0000, v66
	v_add_u32_e32 v14, 0x80, v14
	v_sub_u32_e32 v15, v15, v20
	v_sub_u32_e32 v7, v7, v98
	v_add_u32_e32 v6, 0x80, v6
	v_ashrrev_i32_e32 v14, 8, v14
	v_add_u32_e32 v15, 0x80, v15
	v_add_u32_e32 v7, 0x80, v7
	v_ashrrev_i32_e32 v6, 8, v6
	v_min_i32_e32 v14, 0x7f, v14
	v_ashrrev_i32_e32 v15, 8, v15
	v_ashrrev_i32_e32 v7, 8, v7
	v_min_i32_e32 v6, 0x7f, v6
	v_min_i32_sdwa v15, v15, s69 dst_sel:WORD_1 dst_unused:UNUSED_PAD src0_sel:DWORD src1_sel:DWORD
	v_min_i32_e32 v7, 0x7f, v7
	v_lshlrev_b32_e32 v14, 8, v14
	v_and_b32_e32 v14, 0xff00, v14
	v_and_b32_e32 v15, 0xff0000, v15
	v_perm_b32 v6, v7, v6, s76
	v_or3_b32 v6, v6, v14, v15
	v_mad_u64_u32 v[14:15], s[18:19], v3, s68, v[2:3]
	v_or_b32_e32 v3, 32, v97
	ds_write_b32 v14, v6
	v_lshl_add_u32 v15, v3, 3, v246
	ds_read_b64 v[6:7], v15
	v_lshrrev_b32_e32 v96, 1, v3
	v_mul_lo_u32 v107, v96, s68
	v_add_u32_e32 v96, v109, v107
	v_lshrrev_b32_e32 v3, 2, v3
	s_waitcnt lgkmcnt(0)
;     ...
;             _Pragma("unroll") for (int m = 0; m < 4; ++m) {
;               const int rr = wr3 * 64 + m * 16 + fr3;
;               const float2 ms = *reinterpret_cast<const float2*>(mr + (ai * HALF + rr) * 2);
;               f32x4 y = acc[ai][bj][m][n];
;               const float o0 = (y[0] - ms.x) * ms.y * gm.x + bt.x, o1 = (y[1] - ms.x) * ms.y * gm.y + bt.y;
;               const float o2 = (y[2] - ms.x) * ms.y * gm.z + bt.z, o3 = (y[3] - ms.x) * ms.y * gm.w + bt.w;
;               const unsigned h0 = f2bf(o0), h1 = f2bf(o1), h2 = f2bf(o2), h3 = f2bf(o3);
;               u32x2 ob; ob[0] = h0 | (h1 << 16); ob[1] = h2 | (h3 << 16);
;               *reinterpret_cast<u32x2*>(smem + (rr >> 1) * PIECE + (rr & 1) * 512 + cc * 2) = ob;
;               const int l0 = min(((int)__float_as_uint(o0) - (int)(h0 << 16) + 128) >> 8, 127);
;               const int l1 = min(((int)__float_as_uint(o1) - (int)(h1 << 16) + 128) >> 8, 127);
;               const int l2 = min(((int)__float_as_uint(o2) - (int)(h2 << 16) + 128) >> 8, 127);
;               const int l3 = min(((int)__float_as_uint(o3) - (int)(h3 << 16) + 128) >> 8, 127);
;               *reinterpret_cast<unsigned*>(smem + LOBASE + (rr >> 2) * PIECE + (rr & 3) * 256 + cc) =
;                   (unsigned)(l0 & 255) | ((unsigned)(l1 & 255) << 8) | ((unsigned)(l2 & 255) << 16) | ((unsigned)l3 << 24);
;             }
	v_mov_b32_e32 v184, v6
	v_mov_b32_e32 v185, v7
	v_pk_add_f32 v[20:21], v[194:195], v[6:7] op_sel_hi:[1,0] neg_lo:[0,1] neg_hi:[0,1]
	v_pk_add_f32 v[66:67], v[192:193], v[6:7] op_sel_hi:[1,0] neg_lo:[0,1] neg_hi:[0,1]
	v_pk_mul_f32 v[20:21], v[6:7], v[20:21] op_sel:[1,0]
	v_pk_mul_f32 v[6:7], v[6:7], v[66:67] op_sel:[1,0]
	v_pk_fma_f32 v[20:21], v[22:23], v[20:21], v[64:65]
	v_pk_fma_f32 v[6:7], v[0:1], v[6:7], v[4:5]
	v_and_b32_sdwa v66, v21, v244 dst_sel:DWORD dst_unused:UNUSED_PAD src0_sel:WORD_1 src1_sel:DWORD
	v_and_b32_sdwa v67, v20, v244 dst_sel:DWORD dst_unused:UNUSED_PAD src0_sel:WORD_1 src1_sel:DWORD
	v_add3_u32 v98, v21, v66, s67
	v_add3_u32 v66, v20, v67, s67
	v_and_b32_e32 v99, 0xffff0000, v66
	v_and_b32_sdwa v66, v7, v244 dst_sel:DWORD dst_unused:UNUSED_PAD src0_sel:WORD_1 src1_sel:DWORD
	v_and_b32_sdwa v67, v6, v244 dst_sel:DWORD dst_unused:UNUSED_PAD src0_sel:WORD_1 src1_sel:DWORD
	v_add3_u32 v66, v7, v66, s67
	v_add3_u32 v100, v6, v67, s67
	v_and_b32_e32 v101, 0xffff0000, v66
	v_or_b32_sdwa v67, v101, v98 dst_sel:DWORD dst_unused:UNUSED_PAD src0_sel:DWORD src1_sel:WORD_1
	v_or_b32_sdwa v66, v100, v99 dst_sel:DWORD dst_unused:UNUSED_PAD src0_sel:WORD_1 src1_sel:DWORD
	ds_write_b64 v96, v[66:67]
	v_and_b32_e32 v66, 0xffff0000, v100
	v_sub_u32_e32 v6, v6, v66
	v_sub_u32_e32 v20, v20, v99
	v_and_b32_e32 v66, 0xffff0000, v98
	v_add_u32_e32 v20, 0x80, v20
	v_sub_u32_e32 v21, v21, v66
	v_sub_u32_e32 v7, v7, v101
	v_add_u32_e32 v6, 0x80, v6
	v_ashrrev_i32_e32 v20, 8, v20
	v_add_u32_e32 v21, 0x80, v21
	v_add_u32_e32 v7, 0x80, v7
	v_ashrrev_i32_e32 v6, 8, v6
	v_min_i32_e32 v20, 0x7f, v20
	v_ashrrev_i32_e32 v21, 8, v21
	v_ashrrev_i32_e32 v7, 8, v7
	v_min_i32_e32 v6, 0x7f, v6
	v_min_i32_sdwa v21, v21, s69 dst_sel:WORD_1 dst_unused:UNUSED_PAD src0_sel:DWORD src1_sel:DWORD
	v_min_i32_e32 v7, 0x7f, v7
	v_lshlrev_b32_e32 v20, 8, v20
	v_and_b32_e32 v20, 0xff00, v20
	v_and_b32_e32 v21, 0xff0000, v21
	v_perm_b32 v6, v7, v6, s76
	v_or3_b32 v6, v6, v20, v21
	v_mad_u64_u32 v[20:21], s[18:19], v3, s68, v[2:3]
	v_or_b32_e32 v3, 48, v97
	ds_write_b32 v20, v6
	v_lshl_add_u32 v21, v3, 3, v246
	ds_read_b64 v[6:7], v21
	s_waitcnt lgkmcnt(0)
	v_mov_b32_e32 v186, v6
	v_mov_b32_e32 v187, v7
	v_pk_add_f32 v[66:67], v[190:191], v[6:7] op_sel_hi:[1,0] neg_lo:[0,1] neg_hi:[0,1]
	s_nop 0
	v_pk_mul_f32 v[66:67], v[6:7], v[66:67] op_sel:[1,0]
	s_nop 0
	v_pk_fma_f32 v[22:23], v[22:23], v[66:67], v[64:65]
	v_pk_add_f32 v[64:65], v[188:189], v[6:7] op_sel_hi:[1,0] neg_lo:[0,1] neg_hi:[0,1]
	v_lshrrev_b32_e32 v66, 1, v3
	v_pk_mul_f32 v[6:7], v[6:7], v[64:65] op_sel:[1,0]
	v_mul_lo_u32 v108, v66, s68
	v_pk_fma_f32 v[0:1], v[0:1], v[6:7], v[4:5]
	v_and_b32_sdwa v4, v23, v244 dst_sel:DWORD dst_unused:UNUSED_PAD src0_sel:WORD_1 src1_sel:DWORD
	v_and_b32_sdwa v5, v22, v244 dst_sel:DWORD dst_unused:UNUSED_PAD src0_sel:WORD_1 src1_sel:DWORD
	v_add3_u32 v6, v23, v4, s67
	v_add3_u32 v4, v22, v5, s67
	v_and_b32_e32 v7, 0xffff0000, v4
	v_and_b32_sdwa v4, v1, v244 dst_sel:DWORD dst_unused:UNUSED_PAD src0_sel:WORD_1 src1_sel:DWORD
	v_and_b32_sdwa v5, v0, v244 dst_sel:DWORD dst_unused:UNUSED_PAD src0_sel:WORD_1 src1_sel:DWORD
	v_add3_u32 v4, v1, v4, s67
	v_add3_u32 v64, v0, v5, s67
	v_and_b32_e32 v65, 0xffff0000, v4
	v_or_b32_sdwa v5, v65, v6 dst_sel:DWORD dst_unused:UNUSED_PAD src0_sel:DWORD src1_sel:WORD_1
	v_or_b32_sdwa v4, v64, v7 dst_sel:DWORD dst_unused:UNUSED_PAD src0_sel:WORD_1 src1_sel:DWORD
	v_add_u32_e32 v97, v109, v108
	ds_write_b64 v97, v[4:5]
	v_and_b32_e32 v4, 0xffff0000, v64
	v_sub_u32_e32 v0, v0, v4
	v_sub_u32_e32 v4, v22, v7
	v_and_b32_e32 v5, 0xffff0000, v6
	v_add_u32_e32 v4, 0x80, v4
	v_sub_u32_e32 v5, v23, v5
	v_sub_u32_e32 v1, v1, v65
	v_add_u32_e32 v0, 0x80, v0
	v_ashrrev_i32_e32 v4, 8, v4
	v_add_u32_e32 v5, 0x80, v5
	v_add_u32_e32 v1, 0x80, v1
	v_ashrrev_i32_e32 v0, 8, v0
	v_min_i32_e32 v4, 0x7f, v4
	v_ashrrev_i32_e32 v5, 8, v5
	v_ashrrev_i32_e32 v1, 8, v1
	v_min_i32_e32 v0, 0x7f, v0
	v_min_i32_sdwa v5, v5, s69 dst_sel:WORD_1 dst_unused:UNUSED_PAD src0_sel:DWORD src1_sel:DWORD
	v_min_i32_e32 v1, 0x7f, v1
	v_lshlrev_b32_e32 v4, 8, v4
	v_and_b32_e32 v4, 0xff00, v4
	v_and_b32_e32 v5, 0xff0000, v5
	v_perm_b32 v0, v1, v0, s76
	v_lshrrev_b32_e32 v1, 2, v3
	v_or3_b32 v0, v0, v4, v5
	v_mad_u64_u32 v[22:23], s[18:19], v1, s68, v[2:3]
	ds_write_b32 v22, v0
	v_mov_b32_e32 v0, v200
	v_mov_b32_e32 v1, v201
	v_mov_b32_e32 v2, v202
	v_mov_b32_e32 v3, v203
	v_mov_b32_e32 v4, v220
	v_mov_b32_e32 v5, v221
	v_mov_b32_e32 v6, v222
	v_mov_b32_e32 v7, v223
	v_mov_b32_e32 v98, v180
	v_mov_b32_e32 v99, v181
	s_mul_i32 s18, s52, 0x2080
	v_add_u32_e32 v74, s18, v74
	s_mov_b32 s18, s74
	s_mov_b32 s19, s75
	v_pk_add_f32 v[100:101], v[234:235], v[98:99] op_sel_hi:[1,0] neg_lo:[0,1] neg_hi:[0,1]
	v_pk_add_f32 v[102:103], v[232:233], v[98:99] op_sel_hi:[1,0] neg_lo:[0,1] neg_hi:[0,1]
	v_pk_mul_f32 v[100:101], v[98:99], v[100:101] op_sel:[1,0]
	v_pk_mul_f32 v[98:99], v[98:99], v[102:103] op_sel:[1,0]
	v_mov_b32_e32 v64, v1
	v_mov_b32_e32 v65, v2
	v_mov_b32_e32 v66, v5
	v_mov_b32_e32 v67, v6
	v_pk_fma_f32 v[100:101], v[64:65], v[100:101], v[66:67]
	v_mov_b32_e32 v1, v3
	v_mov_b32_e32 v5, v7
	v_and_b32_sdwa v23, v100, v244 dst_sel:DWORD dst_unused:UNUSED_PAD src0_sel:WORD_1 src1_sel:DWORD
	v_pk_fma_f32 v[6:7], v[0:1], v[98:99], v[4:5]
	v_add3_u32 v23, v100, v23, s67
	v_and_b32_e32 v102, 0xffff0000, v23
	v_and_b32_sdwa v23, v7, v244 dst_sel:DWORD dst_unused:UNUSED_PAD src0_sel:WORD_1 src1_sel:DWORD
	v_and_b32_sdwa v3, v101, v244 dst_sel:DWORD dst_unused:UNUSED_PAD src0_sel:WORD_1 src1_sel:DWORD
	v_and_b32_sdwa v98, v6, v244 dst_sel:DWORD dst_unused:UNUSED_PAD src0_sel:WORD_1 src1_sel:DWORD
;     ...
;             _Pragma("unroll") for (int m = 0; m < 4; ++m) {
;               const int rr = wr3 * 64 + m * 16 + fr3;
;               const float2 ms = *reinterpret_cast<const float2*>(mr + (ai * HALF + rr) * 2);
;               f32x4 y = acc[ai][bj][m][n];
;               const float o0 = (y[0] - ms.x) * ms.y * gm.x + bt.x, o1 = (y[1] - ms.x) * ms.y * gm.y + bt.y;
;               const float o2 = (y[2] - ms.x) * ms.y * gm.z + bt.z, o3 = (y[3] - ms.x) * ms.y * gm.w + bt.w;
;               const unsigned h0 = f2bf(o0), h1 = f2bf(o1), h2 = f2bf(o2), h3 = f2bf(o3);
;               u32x2 ob; ob[0] = h0 | (h1 << 16); ob[1] = h2 | (h3 << 16);
;               *reinterpret_cast<u32x2*>(smem + (rr >> 1) * PIECE + (rr & 1) * 512 + cc * 2) = ob;
;               const int l0 = min(((int)__float_as_uint(o0) - (int)(h0 << 16) + 128) >> 8, 127);
;               const int l1 = min(((int)__float_as_uint(o1) - (int)(h1 << 16) + 128) >> 8, 127);
;               const int l2 = min(((int)__float_as_uint(o2) - (int)(h2 << 16) + 128) >> 8, 127);
;               const int l3 = min(((int)__float_as_uint(o3) - (int)(h3 << 16) + 128) >> 8, 127);
;               *reinterpret_cast<unsigned*>(smem + LOBASE + (rr >> 2) * PIECE + (rr & 3) * 256 + cc) =
;                   (unsigned)(l0 & 255) | ((unsigned)(l1 & 255) << 8) | ((unsigned)(l2 & 255) << 16) | ((unsigned)l3 << 24);
;             }
	v_add3_u32 v23, v7, v23, s67
	v_or_b32_e32 v2, 32, v109
	v_add3_u32 v3, v101, v3, s67
	v_add3_u32 v103, v6, v98, s67
	v_and_b32_e32 v104, 0xffff0000, v23
	v_or_b32_sdwa v99, v104, v3 dst_sel:DWORD dst_unused:UNUSED_PAD src0_sel:DWORD src1_sel:WORD_1
	v_or_b32_sdwa v98, v103, v102 dst_sel:DWORD dst_unused:UNUSED_PAD src0_sel:WORD_1 src1_sel:DWORD
	v_add_u32_e32 v23, v2, v105
	ds_write_b64 v23, v[98:99]
	v_and_b32_e32 v98, 0xffff0000, v103
	v_sub_u32_e32 v6, v6, v98
	v_sub_u32_e32 v98, v100, v102
	v_and_b32_e32 v3, 0xffff0000, v3
	v_add_u32_e32 v98, 0x80, v98
	v_sub_u32_e32 v3, v101, v3
	v_sub_u32_e32 v7, v7, v104
	v_add_u32_e32 v6, 0x80, v6
	v_ashrrev_i32_e32 v98, 8, v98
	v_add_u32_e32 v3, 0x80, v3
	v_add_u32_e32 v7, 0x80, v7
	v_ashrrev_i32_e32 v6, 8, v6
	v_min_i32_e32 v98, 0x7f, v98
	v_ashrrev_i32_e32 v3, 8, v3
	v_ashrrev_i32_e32 v7, 8, v7
	v_min_i32_e32 v6, 0x7f, v6
	v_min_i32_sdwa v3, v3, s69 dst_sel:WORD_1 dst_unused:UNUSED_PAD src0_sel:DWORD src1_sel:DWORD
	v_min_i32_e32 v7, 0x7f, v7
	v_lshlrev_b32_e32 v98, 8, v98
	v_and_b32_e32 v98, 0xff00, v98
	v_and_b32_e32 v3, 0xff0000, v3
	v_perm_b32 v6, v7, v6, s76
	v_or3_b32 v3, v6, v98, v3
	ds_write_b32 v12, v3 offset:16
	v_mov_b32_e32 v6, v182
	v_mov_b32_e32 v7, v183
	v_pk_add_f32 v[98:99], v[158:159], v[6:7] op_sel_hi:[1,0] neg_lo:[0,1] neg_hi:[0,1]
	s_nop 0
	v_pk_mul_f32 v[98:99], v[6:7], v[98:99] op_sel:[1,0]
	s_nop 0
	v_pk_fma_f32 v[100:101], v[64:65], v[98:99], v[66:67]
	v_pk_add_f32 v[98:99], v[156:157], v[6:7] op_sel_hi:[1,0] neg_lo:[0,1] neg_hi:[0,1]
	v_and_b32_sdwa v3, v101, v244 dst_sel:DWORD dst_unused:UNUSED_PAD src0_sel:WORD_1 src1_sel:DWORD
	v_pk_mul_f32 v[6:7], v[6:7], v[98:99] op_sel:[1,0]
	v_and_b32_sdwa v98, v100, v244 dst_sel:DWORD dst_unused:UNUSED_PAD src0_sel:WORD_1 src1_sel:DWORD
	v_pk_fma_f32 v[6:7], v[0:1], v[6:7], v[4:5]
	v_add3_u32 v98, v100, v98, s67
	v_and_b32_e32 v99, 0xffff0000, v98
	v_and_b32_sdwa v98, v7, v244 dst_sel:DWORD dst_unused:UNUSED_PAD src0_sel:WORD_1 src1_sel:DWORD
	v_and_b32_sdwa v102, v6, v244 dst_sel:DWORD dst_unused:UNUSED_PAD src0_sel:WORD_1 src1_sel:DWORD
	v_add3_u32 v98, v7, v98, s67
	v_add3_u32 v3, v101, v3, s67
	v_add3_u32 v104, v6, v102, s67
	v_and_b32_e32 v110, 0xffff0000, v98
	v_or_b32_sdwa v103, v110, v3 dst_sel:DWORD dst_unused:UNUSED_PAD src0_sel:DWORD src1_sel:WORD_1
	v_or_b32_sdwa v102, v104, v99 dst_sel:DWORD dst_unused:UNUSED_PAD src0_sel:WORD_1 src1_sel:DWORD
	v_add_u32_e32 v98, v2, v106
	ds_write_b64 v98, v[102:103]
	v_and_b32_e32 v102, 0xffff0000, v104
	v_sub_u32_e32 v99, v100, v99
	v_and_b32_e32 v3, 0xffff0000, v3
	v_sub_u32_e32 v6, v6, v102
	v_add_u32_e32 v99, 0x80, v99
	v_sub_u32_e32 v3, v101, v3
	v_sub_u32_e32 v7, v7, v110
	v_add_u32_e32 v6, 0x80, v6
	v_ashrrev_i32_e32 v99, 8, v99
	v_add_u32_e32 v3, 0x80, v3
	v_add_u32_e32 v7, 0x80, v7
	v_ashrrev_i32_e32 v6, 8, v6
	v_min_i32_e32 v99, 0x7f, v99
	v_ashrrev_i32_e32 v3, 8, v3
	v_ashrrev_i32_e32 v7, 8, v7
	v_min_i32_e32 v6, 0x7f, v6
	v_min_i32_sdwa v3, v3, s69 dst_sel:WORD_1 dst_unused:UNUSED_PAD src0_sel:DWORD src1_sel:DWORD
	v_min_i32_e32 v7, 0x7f, v7
	v_lshlrev_b32_e32 v99, 8, v99
	v_and_b32_e32 v99, 0xff00, v99
	v_and_b32_e32 v3, 0xff0000, v3
	v_perm_b32 v6, v7, v6, s76
	v_or3_b32 v3, v6, v99, v3
	ds_write_b32 v14, v3 offset:16
	v_mov_b32_e32 v6, v184
	v_mov_b32_e32 v7, v185
	v_pk_add_f32 v[100:101], v[126:127], v[6:7] op_sel_hi:[1,0] neg_lo:[0,1] neg_hi:[0,1]
	s_nop 0
	v_pk_mul_f32 v[100:101], v[6:7], v[100:101] op_sel:[1,0]
	v_pk_add_f32 v[102:103], v[124:125], v[6:7] op_sel_hi:[1,0] neg_lo:[0,1] neg_hi:[0,1]
	v_pk_fma_f32 v[100:101], v[64:65], v[100:101], v[66:67]
	v_pk_mul_f32 v[6:7], v[6:7], v[102:103] op_sel:[1,0]
	v_and_b32_sdwa v99, v100, v244 dst_sel:DWORD dst_unused:UNUSED_PAD src0_sel:WORD_1 src1_sel:DWORD
	v_pk_fma_f32 v[6:7], v[0:1], v[6:7], v[4:5]
	v_add3_u32 v99, v100, v99, s67
	v_and_b32_e32 v104, 0xffff0000, v99
	v_and_b32_sdwa v99, v7, v244 dst_sel:DWORD dst_unused:UNUSED_PAD src0_sel:WORD_1 src1_sel:DWORD
	v_and_b32_sdwa v3, v101, v244 dst_sel:DWORD dst_unused:UNUSED_PAD src0_sel:WORD_1 src1_sel:DWORD
	v_and_b32_sdwa v102, v6, v244 dst_sel:DWORD dst_unused:UNUSED_PAD src0_sel:WORD_1 src1_sel:DWORD
	v_add3_u32 v99, v7, v99, s67
	v_add3_u32 v3, v101, v3, s67
	v_add3_u32 v110, v6, v102, s67
	v_and_b32_e32 v111, 0xffff0000, v99
	v_or_b32_sdwa v103, v111, v3 dst_sel:DWORD dst_unused:UNUSED_PAD src0_sel:DWORD src1_sel:WORD_1
	v_or_b32_sdwa v102, v110, v104 dst_sel:DWORD dst_unused:UNUSED_PAD src0_sel:WORD_1 src1_sel:DWORD
	v_add_u32_e32 v99, v2, v107
	ds_write_b64 v99, v[102:103]
	v_and_b32_e32 v102, 0xffff0000, v110
	v_sub_u32_e32 v100, v100, v104
	v_and_b32_e32 v3, 0xffff0000, v3
	v_sub_u32_e32 v6, v6, v102
	v_add_u32_e32 v100, 0x80, v100
	v_sub_u32_e32 v3, v101, v3
	v_sub_u32_e32 v7, v7, v111
	v_add_u32_e32 v6, 0x80, v6
	v_ashrrev_i32_e32 v100, 8, v100
	v_add_u32_e32 v3, 0x80, v3
	v_add_u32_e32 v7, 0x80, v7
	v_ashrrev_i32_e32 v6, 8, v6
	v_min_i32_e32 v100, 0x7f, v100
	v_ashrrev_i32_e32 v3, 8, v3
	v_ashrrev_i32_e32 v7, 8, v7
	v_min_i32_e32 v6, 0x7f, v6
	v_min_i32_sdwa v3, v3, s69 dst_sel:WORD_1 dst_unused:UNUSED_PAD src0_sel:DWORD src1_sel:DWORD
	v_min_i32_e32 v7, 0x7f, v7
	v_lshlrev_b32_e32 v100, 8, v100
	v_and_b32_e32 v100, 0xff00, v100
	v_and_b32_e32 v3, 0xff0000, v3
	v_perm_b32 v6, v7, v6, s76
	v_or3_b32 v3, v6, v100, v3
	ds_write_b32 v20, v3 offset:16
	v_mov_b32_e32 v6, v186
	v_mov_b32_e32 v7, v187
	v_or_b32_e32 v104, 0x100, v109
	v_pk_add_f32 v[100:101], v[154:155], v[6:7] op_sel_hi:[1,0] neg_lo:[0,1] neg_hi:[0,1]
	s_nop 0
	v_pk_mul_f32 v[100:101], v[6:7], v[100:101] op_sel:[1,0]
	s_nop 0
	v_pk_fma_f32 v[64:65], v[64:65], v[100:101], v[66:67]
;     ...
;             _Pragma("unroll") for (int m = 0; m < 4; ++m) {
;               const int rr = wr3 * 64 + m * 16 + fr3;
;               const float2 ms = *reinterpret_cast<const float2*>(mr + (ai * HALF + rr) * 2);
;               f32x4 y = acc[ai][bj][m][n];
;               const float o0 = (y[0] - ms.x) * ms.y * gm.x + bt.x, o1 = (y[1] - ms.x) * ms.y * gm.y + bt.y;
;               const float o2 = (y[2] - ms.x) * ms.y * gm.z + bt.z, o3 = (y[3] - ms.x) * ms.y * gm.w + bt.w;
;               const unsigned h0 = f2bf(o0), h1 = f2bf(o1), h2 = f2bf(o2), h3 = f2bf(o3);
;               u32x2 ob; ob[0] = h0 | (h1 << 16); ob[1] = h2 | (h3 << 16);
;               *reinterpret_cast<u32x2*>(smem + (rr >> 1) * PIECE + (rr & 1) * 512 + cc * 2) = ob;
;               const int l0 = min(((int)__float_as_uint(o0) - (int)(h0 << 16) + 128) >> 8, 127);
;               const int l1 = min(((int)__float_as_uint(o1) - (int)(h1 << 16) + 128) >> 8, 127);
;               const int l2 = min(((int)__float_as_uint(o2) - (int)(h2 << 16) + 128) >> 8, 127);
;               const int l3 = min(((int)__float_as_uint(o3) - (int)(h3 << 16) + 128) >> 8, 127);
;               *reinterpret_cast<unsigned*>(smem + LOBASE + (rr >> 2) * PIECE + (rr & 3) * 256 + cc) =
;                   (unsigned)(l0 & 255) | ((unsigned)(l1 & 255) << 8) | ((unsigned)(l2 & 255) << 16) | ((unsigned)l3 << 24);
;             }
	v_pk_add_f32 v[66:67], v[152:153], v[6:7] op_sel_hi:[1,0] neg_lo:[0,1] neg_hi:[0,1]
	v_and_b32_sdwa v3, v65, v244 dst_sel:DWORD dst_unused:UNUSED_PAD src0_sel:WORD_1 src1_sel:DWORD
	v_pk_mul_f32 v[6:7], v[6:7], v[66:67] op_sel:[1,0]
	v_add3_u32 v3, v65, v3, s67
	v_pk_fma_f32 v[0:1], v[0:1], v[6:7], v[4:5]
	v_and_b32_sdwa v4, v64, v244 dst_sel:DWORD dst_unused:UNUSED_PAD src0_sel:WORD_1 src1_sel:DWORD
	v_add3_u32 v4, v64, v4, s67
	v_and_b32_e32 v6, 0xffff0000, v4
	v_and_b32_sdwa v4, v1, v244 dst_sel:DWORD dst_unused:UNUSED_PAD src0_sel:WORD_1 src1_sel:DWORD
	v_and_b32_sdwa v5, v0, v244 dst_sel:DWORD dst_unused:UNUSED_PAD src0_sel:WORD_1 src1_sel:DWORD
	v_add3_u32 v4, v1, v4, s67
	v_add3_u32 v7, v0, v5, s67
	v_and_b32_e32 v66, 0xffff0000, v4
	v_add_u32_e32 v100, v2, v108
	v_and_b32_e32 v2, 0xffff0000, v7
	v_or_b32_sdwa v5, v66, v3 dst_sel:DWORD dst_unused:UNUSED_PAD src0_sel:DWORD src1_sel:WORD_1
	v_sub_u32_e32 v0, v0, v2
	v_sub_u32_e32 v2, v64, v6
	v_and_b32_e32 v3, 0xffff0000, v3
	v_add_u32_e32 v2, 0x80, v2
	v_sub_u32_e32 v3, v65, v3
	v_sub_u32_e32 v1, v1, v66
	v_add_u32_e32 v0, 0x80, v0
	v_ashrrev_i32_e32 v2, 8, v2
	v_add_u32_e32 v3, 0x80, v3
	v_add_u32_e32 v1, 0x80, v1
	v_ashrrev_i32_e32 v0, 8, v0
	v_min_i32_e32 v2, 0x7f, v2
	v_ashrrev_i32_e32 v3, 8, v3
	v_ashrrev_i32_e32 v1, 8, v1
	v_min_i32_e32 v0, 0x7f, v0
	v_min_i32_sdwa v3, v3, s69 dst_sel:WORD_1 dst_unused:UNUSED_PAD src0_sel:DWORD src1_sel:DWORD
	v_min_i32_e32 v1, 0x7f, v1
	v_lshlrev_b32_e32 v2, 8, v2
	v_and_b32_e32 v2, 0xff00, v2
	v_and_b32_e32 v3, 0xff0000, v3
	v_perm_b32 v0, v1, v0, s76
	v_or_b32_sdwa v4, v7, v6 dst_sel:DWORD dst_unused:UNUSED_PAD src0_sel:WORD_1 src1_sel:DWORD
	v_or3_b32 v0, v0, v2, v3
	ds_write_b64 v100, v[4:5]
	ds_write_b32 v22, v0 offset:16
	v_mov_b32_e32 v0, v204
	v_mov_b32_e32 v1, v205
	v_mov_b32_e32 v2, v206
	v_mov_b32_e32 v3, v207
	v_mov_b32_e32 v4, v240
	v_mov_b32_e32 v5, v241
	v_mov_b32_e32 v6, v242
	v_mov_b32_e32 v7, v243
	v_mov_b32_e32 v102, v180
	v_mov_b32_e32 v103, v181
	v_add_u32_e32 v101, v104, v105
	v_pk_add_f32 v[110:111], v[230:231], v[102:103] op_sel_hi:[1,0] neg_lo:[0,1] neg_hi:[0,1]
	s_nop 0
	v_pk_mul_f32 v[110:111], v[102:103], v[110:111] op_sel:[1,0]
	v_pk_add_f32 v[124:125], v[228:229], v[102:103] op_sel_hi:[1,0] neg_lo:[0,1] neg_hi:[0,1]
	v_mov_b32_e32 v64, v1
	v_mov_b32_e32 v65, v2
	v_mov_b32_e32 v66, v5
	v_mov_b32_e32 v67, v6
	v_pk_fma_f32 v[110:111], v[64:65], v[110:111], v[66:67]
	v_pk_mul_f32 v[102:103], v[102:103], v[124:125] op_sel:[1,0]
	v_mov_b32_e32 v1, v3
	v_mov_b32_e32 v5, v7
	v_and_b32_sdwa v6, v111, v244 dst_sel:DWORD dst_unused:UNUSED_PAD src0_sel:WORD_1 src1_sel:DWORD
	v_and_b32_sdwa v7, v110, v244 dst_sel:DWORD dst_unused:UNUSED_PAD src0_sel:WORD_1 src1_sel:DWORD
	v_pk_fma_f32 v[2:3], v[0:1], v[102:103], v[4:5]
	v_add3_u32 v102, v111, v6, s67
	v_add3_u32 v6, v110, v7, s67
	v_and_b32_e32 v103, 0xffff0000, v6
	v_and_b32_sdwa v6, v3, v244 dst_sel:DWORD dst_unused:UNUSED_PAD src0_sel:WORD_1 src1_sel:DWORD
	v_and_b32_sdwa v7, v2, v244 dst_sel:DWORD dst_unused:UNUSED_PAD src0_sel:WORD_1 src1_sel:DWORD
	v_add3_u32 v6, v3, v6, s67
	v_add3_u32 v124, v2, v7, s67
	v_and_b32_e32 v125, 0xffff0000, v6
	v_or_b32_sdwa v7, v125, v102 dst_sel:DWORD dst_unused:UNUSED_PAD src0_sel:DWORD src1_sel:WORD_1
	v_or_b32_sdwa v6, v124, v103 dst_sel:DWORD dst_unused:UNUSED_PAD src0_sel:WORD_1 src1_sel:DWORD
	ds_write_b64 v101, v[6:7]
	v_and_b32_e32 v6, 0xffff0000, v124
	v_sub_u32_e32 v2, v2, v6
	v_sub_u32_e32 v6, v110, v103
	v_and_b32_e32 v7, 0xffff0000, v102
	v_add_u32_e32 v6, 0x80, v6
	v_sub_u32_e32 v7, v111, v7
	v_sub_u32_e32 v3, v3, v125
	v_add_u32_e32 v2, 0x80, v2
	v_ashrrev_i32_e32 v6, 8, v6
	v_add_u32_e32 v7, 0x80, v7
	v_add_u32_e32 v3, 0x80, v3
	v_ashrrev_i32_e32 v2, 8, v2
	v_min_i32_e32 v6, 0x7f, v6
	v_ashrrev_i32_e32 v7, 8, v7
	v_ashrrev_i32_e32 v3, 8, v3
	v_min_i32_e32 v2, 0x7f, v2
	v_min_i32_sdwa v7, v7, s69 dst_sel:WORD_1 dst_unused:UNUSED_PAD src0_sel:DWORD src1_sel:DWORD
	v_min_i32_e32 v3, 0x7f, v3
	v_lshlrev_b32_e32 v6, 8, v6
	v_and_b32_e32 v6, 0xff00, v6
	v_and_b32_e32 v7, 0xff0000, v7
	v_perm_b32 v2, v3, v2, s76
	v_or3_b32 v2, v2, v6, v7
	ds_write_b32 v12, v2 offset:128
	v_mov_b32_e32 v2, v182
	v_mov_b32_e32 v3, v183
	v_pk_add_f32 v[6:7], v[150:151], v[2:3] op_sel_hi:[1,0] neg_lo:[0,1] neg_hi:[0,1]
	s_nop 0
	v_pk_mul_f32 v[6:7], v[2:3], v[6:7] op_sel:[1,0]
	v_pk_add_f32 v[102:103], v[148:149], v[2:3] op_sel_hi:[1,0] neg_lo:[0,1] neg_hi:[0,1]
	v_pk_fma_f32 v[6:7], v[64:65], v[6:7], v[66:67]
	v_pk_mul_f32 v[2:3], v[2:3], v[102:103] op_sel:[1,0]
	v_and_b32_sdwa v102, v7, v244 dst_sel:DWORD dst_unused:UNUSED_PAD src0_sel:WORD_1 src1_sel:DWORD
	v_and_b32_sdwa v103, v6, v244 dst_sel:DWORD dst_unused:UNUSED_PAD src0_sel:WORD_1 src1_sel:DWORD
	v_pk_fma_f32 v[2:3], v[0:1], v[2:3], v[4:5]
	v_add3_u32 v124, v7, v102, s67
	v_add3_u32 v102, v6, v103, s67
	v_and_b32_e32 v103, 0xffff0000, v102
	v_and_b32_sdwa v102, v3, v244 dst_sel:DWORD dst_unused:UNUSED_PAD src0_sel:WORD_1 src1_sel:DWORD
	v_and_b32_sdwa v110, v2, v244 dst_sel:DWORD dst_unused:UNUSED_PAD src0_sel:WORD_1 src1_sel:DWORD
	v_add3_u32 v102, v3, v102, s67
	v_add3_u32 v125, v2, v110, s67
	v_and_b32_e32 v126, 0xffff0000, v102
	v_or_b32_sdwa v111, v126, v124 dst_sel:DWORD dst_unused:UNUSED_PAD src0_sel:DWORD src1_sel:WORD_1
	v_or_b32_sdwa v110, v125, v103 dst_sel:DWORD dst_unused:UNUSED_PAD src0_sel:WORD_1 src1_sel:DWORD
	v_add_u32_e32 v102, v104, v106
	ds_write_b64 v102, v[110:111]
	v_and_b32_e32 v110, 0xffff0000, v125
	v_sub_u32_e32 v6, v6, v103
	v_and_b32_e32 v103, 0xffff0000, v124
	v_sub_u32_e32 v2, v2, v110
	v_add_u32_e32 v6, 0x80, v6
	v_sub_u32_e32 v7, v7, v103
;     ...
;             _Pragma("unroll") for (int m = 0; m < 4; ++m) {
;               const int rr = wr3 * 64 + m * 16 + fr3;
;               const float2 ms = *reinterpret_cast<const float2*>(mr + (ai * HALF + rr) * 2);
;               f32x4 y = acc[ai][bj][m][n];
;               const float o0 = (y[0] - ms.x) * ms.y * gm.x + bt.x, o1 = (y[1] - ms.x) * ms.y * gm.y + bt.y;
;               const float o2 = (y[2] - ms.x) * ms.y * gm.z + bt.z, o3 = (y[3] - ms.x) * ms.y * gm.w + bt.w;
;               const unsigned h0 = f2bf(o0), h1 = f2bf(o1), h2 = f2bf(o2), h3 = f2bf(o3);
;               u32x2 ob; ob[0] = h0 | (h1 << 16); ob[1] = h2 | (h3 << 16);
;               *reinterpret_cast<u32x2*>(smem + (rr >> 1) * PIECE + (rr & 1) * 512 + cc * 2) = ob;
;               const int l0 = min(((int)__float_as_uint(o0) - (int)(h0 << 16) + 128) >> 8, 127);
;               const int l1 = min(((int)__float_as_uint(o1) - (int)(h1 << 16) + 128) >> 8, 127);
;               const int l2 = min(((int)__float_as_uint(o2) - (int)(h2 << 16) + 128) >> 8, 127);
;               const int l3 = min(((int)__float_as_uint(o3) - (int)(h3 << 16) + 128) >> 8, 127);
;               *reinterpret_cast<unsigned*>(smem + LOBASE + (rr >> 2) * PIECE + (rr & 3) * 256 + cc) =
;                   (unsigned)(l0 & 255) | ((unsigned)(l1 & 255) << 8) | ((unsigned)(l2 & 255) << 16) | ((unsigned)l3 << 24);
;             }
	v_sub_u32_e32 v3, v3, v126
	v_add_u32_e32 v2, 0x80, v2
	v_ashrrev_i32_e32 v6, 8, v6
	v_add_u32_e32 v7, 0x80, v7
	v_add_u32_e32 v3, 0x80, v3
	v_ashrrev_i32_e32 v2, 8, v2
	v_min_i32_e32 v6, 0x7f, v6
	v_ashrrev_i32_e32 v7, 8, v7
	v_ashrrev_i32_e32 v3, 8, v3
	v_min_i32_e32 v2, 0x7f, v2
	v_min_i32_sdwa v7, v7, s69 dst_sel:WORD_1 dst_unused:UNUSED_PAD src0_sel:DWORD src1_sel:DWORD
	v_min_i32_e32 v3, 0x7f, v3
	v_lshlrev_b32_e32 v6, 8, v6
	v_and_b32_e32 v6, 0xff00, v6
	v_and_b32_e32 v7, 0xff0000, v7
	v_perm_b32 v2, v3, v2, s76
	v_or3_b32 v2, v2, v6, v7
	ds_write_b32 v14, v2 offset:128
	v_mov_b32_e32 v2, v184
	v_mov_b32_e32 v3, v185
	v_pk_add_f32 v[6:7], v[118:119], v[2:3] op_sel_hi:[1,0] neg_lo:[0,1] neg_hi:[0,1]
	s_nop 0
	v_pk_mul_f32 v[6:7], v[2:3], v[6:7] op_sel:[1,0]
	v_pk_add_f32 v[110:111], v[116:117], v[2:3] op_sel_hi:[1,0] neg_lo:[0,1] neg_hi:[0,1]
	v_pk_fma_f32 v[6:7], v[64:65], v[6:7], v[66:67]
	v_pk_mul_f32 v[2:3], v[2:3], v[110:111] op_sel:[1,0]
	v_and_b32_sdwa v103, v7, v244 dst_sel:DWORD dst_unused:UNUSED_PAD src0_sel:WORD_1 src1_sel:DWORD
	v_and_b32_sdwa v110, v6, v244 dst_sel:DWORD dst_unused:UNUSED_PAD src0_sel:WORD_1 src1_sel:DWORD
	v_pk_fma_f32 v[2:3], v[0:1], v[2:3], v[4:5]
	v_add3_u32 v116, v7, v103, s67
	v_add3_u32 v103, v6, v110, s67
	v_and_b32_e32 v117, 0xffff0000, v103
	v_and_b32_sdwa v103, v3, v244 dst_sel:DWORD dst_unused:UNUSED_PAD src0_sel:WORD_1 src1_sel:DWORD
	v_and_b32_sdwa v110, v2, v244 dst_sel:DWORD dst_unused:UNUSED_PAD src0_sel:WORD_1 src1_sel:DWORD
	v_add3_u32 v103, v3, v103, s67
	v_add3_u32 v118, v2, v110, s67
	v_and_b32_e32 v119, 0xffff0000, v103
	v_or_b32_sdwa v111, v119, v116 dst_sel:DWORD dst_unused:UNUSED_PAD src0_sel:DWORD src1_sel:WORD_1
	v_or_b32_sdwa v110, v118, v117 dst_sel:DWORD dst_unused:UNUSED_PAD src0_sel:WORD_1 src1_sel:DWORD
	v_add_u32_e32 v103, v104, v107
	ds_write_b64 v103, v[110:111]
	v_and_b32_e32 v110, 0xffff0000, v118
	v_sub_u32_e32 v2, v2, v110
	v_sub_u32_e32 v6, v6, v117
	v_and_b32_e32 v110, 0xffff0000, v116
	v_add_u32_e32 v6, 0x80, v6
	v_sub_u32_e32 v7, v7, v110
	v_sub_u32_e32 v3, v3, v119
	v_add_u32_e32 v2, 0x80, v2
	v_ashrrev_i32_e32 v6, 8, v6
	v_add_u32_e32 v7, 0x80, v7
	v_add_u32_e32 v3, 0x80, v3
	v_ashrrev_i32_e32 v2, 8, v2
	v_min_i32_e32 v6, 0x7f, v6
	v_ashrrev_i32_e32 v7, 8, v7
	v_ashrrev_i32_e32 v3, 8, v3
	v_min_i32_e32 v2, 0x7f, v2
	v_min_i32_sdwa v7, v7, s69 dst_sel:WORD_1 dst_unused:UNUSED_PAD src0_sel:DWORD src1_sel:DWORD
	v_min_i32_e32 v3, 0x7f, v3
	v_lshlrev_b32_e32 v6, 8, v6
	v_and_b32_e32 v6, 0xff00, v6
	v_and_b32_e32 v7, 0xff0000, v7
	v_perm_b32 v2, v3, v2, s76
	v_or3_b32 v2, v2, v6, v7
	ds_write_b32 v20, v2 offset:128
	v_mov_b32_e32 v2, v186
	v_mov_b32_e32 v3, v187
	v_add_u32_e32 v104, v104, v108
	v_pk_add_f32 v[6:7], v[122:123], v[2:3] op_sel_hi:[1,0] neg_lo:[0,1] neg_hi:[0,1]
	s_nop 0
	v_pk_mul_f32 v[6:7], v[2:3], v[6:7] op_sel:[1,0]
	s_nop 0
	v_pk_fma_f32 v[6:7], v[64:65], v[6:7], v[66:67]
	v_pk_add_f32 v[64:65], v[120:121], v[2:3] op_sel_hi:[1,0] neg_lo:[0,1] neg_hi:[0,1]
	s_nop 0
	v_pk_mul_f32 v[2:3], v[2:3], v[64:65] op_sel:[1,0]
	s_nop 0
	v_pk_fma_f32 v[0:1], v[0:1], v[2:3], v[4:5]
	v_and_b32_sdwa v2, v7, v244 dst_sel:DWORD dst_unused:UNUSED_PAD src0_sel:WORD_1 src1_sel:DWORD
	v_and_b32_sdwa v3, v6, v244 dst_sel:DWORD dst_unused:UNUSED_PAD src0_sel:WORD_1 src1_sel:DWORD
	v_add3_u32 v4, v7, v2, s67
	v_add3_u32 v2, v6, v3, s67
	v_and_b32_e32 v5, 0xffff0000, v2
	v_and_b32_sdwa v2, v1, v244 dst_sel:DWORD dst_unused:UNUSED_PAD src0_sel:WORD_1 src1_sel:DWORD
	v_and_b32_sdwa v3, v0, v244 dst_sel:DWORD dst_unused:UNUSED_PAD src0_sel:WORD_1 src1_sel:DWORD
	v_add3_u32 v2, v1, v2, s67
	v_add3_u32 v64, v0, v3, s67
	v_and_b32_e32 v65, 0xffff0000, v2
	v_or_b32_sdwa v3, v65, v4 dst_sel:DWORD dst_unused:UNUSED_PAD src0_sel:DWORD src1_sel:WORD_1
	v_or_b32_sdwa v2, v64, v5 dst_sel:DWORD dst_unused:UNUSED_PAD src0_sel:WORD_1 src1_sel:DWORD
	ds_write_b64 v104, v[2:3]
	v_and_b32_e32 v2, 0xffff0000, v64
	v_sub_u32_e32 v0, v0, v2
	v_sub_u32_e32 v2, v6, v5
	v_and_b32_e32 v3, 0xffff0000, v4
	v_add_u32_e32 v2, 0x80, v2
	v_sub_u32_e32 v3, v7, v3
	v_sub_u32_e32 v1, v1, v65
	v_add_u32_e32 v0, 0x80, v0
	v_ashrrev_i32_e32 v2, 8, v2
	v_add_u32_e32 v3, 0x80, v3
	v_add_u32_e32 v1, 0x80, v1
	v_ashrrev_i32_e32 v0, 8, v0
	v_min_i32_e32 v2, 0x7f, v2
	v_ashrrev_i32_e32 v3, 8, v3
	v_ashrrev_i32_e32 v1, 8, v1
	v_min_i32_e32 v0, 0x7f, v0
	v_min_i32_sdwa v3, v3, s69 dst_sel:WORD_1 dst_unused:UNUSED_PAD src0_sel:DWORD src1_sel:DWORD
	v_min_i32_e32 v1, 0x7f, v1
	v_lshlrev_b32_e32 v2, 8, v2
	v_and_b32_e32 v2, 0xff00, v2
	v_and_b32_e32 v3, 0xff0000, v3
	v_perm_b32 v0, v1, v0, s76
	v_or3_b32 v0, v0, v2, v3
	ds_write_b32 v22, v0 offset:128
	v_mov_b32_e32 v0, v208
	v_mov_b32_e32 v1, v209
	v_mov_b32_e32 v2, v210
	v_mov_b32_e32 v3, v211
	v_mov_b32_e32 v4, v248
	v_mov_b32_e32 v5, v249
	v_mov_b32_e32 v6, v250
	v_mov_b32_e32 v7, v251
	v_mov_b32_e32 v110, v180
	v_mov_b32_e32 v111, v181
	v_pk_add_f32 v[116:117], v[226:227], v[110:111] op_sel_hi:[1,0] neg_lo:[0,1] neg_hi:[0,1]
	v_pk_add_f32 v[118:119], v[224:225], v[110:111] op_sel_hi:[1,0] neg_lo:[0,1] neg_hi:[0,1]
	v_pk_mul_f32 v[116:117], v[110:111], v[116:117] op_sel:[1,0]
	v_pk_mul_f32 v[110:111], v[110:111], v[118:119] op_sel:[1,0]
	v_mov_b32_e32 v64, v1
	v_mov_b32_e32 v65, v2
	v_mov_b32_e32 v66, v5
	v_mov_b32_e32 v67, v6
	v_mov_b32_e32 v1, v3
	v_mov_b32_e32 v5, v7
	v_pk_fma_f32 v[116:117], v[64:65], v[116:117], v[66:67]
	v_pk_fma_f32 v[6:7], v[0:1], v[110:111], v[4:5]
	v_or_b32_e32 v2, 0x120, v109
	v_and_b32_sdwa v109, v116, v244 dst_sel:DWORD dst_unused:UNUSED_PAD src0_sel:WORD_1 src1_sel:DWORD
	v_and_b32_sdwa v110, v7, v244 dst_sel:DWORD dst_unused:UNUSED_PAD src0_sel:WORD_1 src1_sel:DWORD
;     ...
;             _Pragma("unroll") for (int m = 0; m < 4; ++m) {
;               const int rr = wr3 * 64 + m * 16 + fr3;
;               const float2 ms = *reinterpret_cast<const float2*>(mr + (ai * HALF + rr) * 2);
;               f32x4 y = acc[ai][bj][m][n];
;               const float o0 = (y[0] - ms.x) * ms.y * gm.x + bt.x, o1 = (y[1] - ms.x) * ms.y * gm.y + bt.y;
;               const float o2 = (y[2] - ms.x) * ms.y * gm.z + bt.z, o3 = (y[3] - ms.x) * ms.y * gm.w + bt.w;
;               const unsigned h0 = f2bf(o0), h1 = f2bf(o1), h2 = f2bf(o2), h3 = f2bf(o3);
;               u32x2 ob; ob[0] = h0 | (h1 << 16); ob[1] = h2 | (h3 << 16);
;               *reinterpret_cast<u32x2*>(smem + (rr >> 1) * PIECE + (rr & 1) * 512 + cc * 2) = ob;
;               const int l0 = min(((int)__float_as_uint(o0) - (int)(h0 << 16) + 128) >> 8, 127);
;               const int l1 = min(((int)__float_as_uint(o1) - (int)(h1 << 16) + 128) >> 8, 127);
;               const int l2 = min(((int)__float_as_uint(o2) - (int)(h2 << 16) + 128) >> 8, 127);
;               const int l3 = min(((int)__float_as_uint(o3) - (int)(h3 << 16) + 128) >> 8, 127);
;               *reinterpret_cast<unsigned*>(smem + LOBASE + (rr >> 2) * PIECE + (rr & 3) * 256 + cc) =
;                   (unsigned)(l0 & 255) | ((unsigned)(l1 & 255) << 8) | ((unsigned)(l2 & 255) << 16) | ((unsigned)l3 << 24);
;             }
	v_and_b32_sdwa v3, v117, v244 dst_sel:DWORD dst_unused:UNUSED_PAD src0_sel:WORD_1 src1_sel:DWORD
	v_add3_u32 v109, v116, v109, s67
	v_and_b32_sdwa v111, v6, v244 dst_sel:DWORD dst_unused:UNUSED_PAD src0_sel:WORD_1 src1_sel:DWORD
	v_add3_u32 v110, v7, v110, s67
	v_add3_u32 v3, v117, v3, s67
	v_and_b32_e32 v109, 0xffff0000, v109
	v_add3_u32 v118, v6, v111, s67
	v_and_b32_e32 v119, 0xffff0000, v110
	v_or_b32_sdwa v111, v119, v3 dst_sel:DWORD dst_unused:UNUSED_PAD src0_sel:DWORD src1_sel:WORD_1
	v_or_b32_sdwa v110, v118, v109 dst_sel:DWORD dst_unused:UNUSED_PAD src0_sel:WORD_1 src1_sel:DWORD
	v_add_u32_e32 v105, v2, v105
	ds_write_b64 v105, v[110:111]
	v_and_b32_e32 v110, 0xffff0000, v118
	v_sub_u32_e32 v109, v116, v109
	v_and_b32_e32 v3, 0xffff0000, v3
	v_sub_u32_e32 v6, v6, v110
	v_add_u32_e32 v109, 0x80, v109
	v_sub_u32_e32 v3, v117, v3
	v_sub_u32_e32 v7, v7, v119
	v_add_u32_e32 v6, 0x80, v6
	v_ashrrev_i32_e32 v109, 8, v109
	v_add_u32_e32 v3, 0x80, v3
	v_add_u32_e32 v7, 0x80, v7
	v_ashrrev_i32_e32 v6, 8, v6
	v_min_i32_e32 v109, 0x7f, v109
	v_ashrrev_i32_e32 v3, 8, v3
	v_ashrrev_i32_e32 v7, 8, v7
	v_min_i32_e32 v6, 0x7f, v6
	v_min_i32_sdwa v3, v3, s69 dst_sel:WORD_1 dst_unused:UNUSED_PAD src0_sel:DWORD src1_sel:DWORD
	v_min_i32_e32 v7, 0x7f, v7
	v_lshlrev_b32_e32 v109, 8, v109
	v_and_b32_e32 v109, 0xff00, v109
	v_and_b32_e32 v3, 0xff0000, v3
	v_perm_b32 v6, v7, v6, s76
	v_or3_b32 v3, v6, v109, v3
	ds_write_b32 v12, v3 offset:144
	v_mov_b32_e32 v6, v182
	v_mov_b32_e32 v7, v183
	v_add_u32_e32 v106, v2, v106
	v_add_u32_e32 v107, v2, v107
	v_pk_add_f32 v[110:111], v[146:147], v[6:7] op_sel_hi:[1,0] neg_lo:[0,1] neg_hi:[0,1]
	v_pk_add_f32 v[116:117], v[144:145], v[6:7] op_sel_hi:[1,0] neg_lo:[0,1] neg_hi:[0,1]
	v_pk_mul_f32 v[110:111], v[6:7], v[110:111] op_sel:[1,0]
	v_pk_mul_f32 v[6:7], v[6:7], v[116:117] op_sel:[1,0]
	v_pk_fma_f32 v[110:111], v[64:65], v[110:111], v[66:67]
	v_pk_fma_f32 v[6:7], v[0:1], v[6:7], v[4:5]
	v_and_b32_sdwa v109, v110, v244 dst_sel:DWORD dst_unused:UNUSED_PAD src0_sel:WORD_1 src1_sel:DWORD
	v_and_b32_sdwa v116, v7, v244 dst_sel:DWORD dst_unused:UNUSED_PAD src0_sel:WORD_1 src1_sel:DWORD
	v_and_b32_sdwa v3, v111, v244 dst_sel:DWORD dst_unused:UNUSED_PAD src0_sel:WORD_1 src1_sel:DWORD
	v_add3_u32 v109, v110, v109, s67
	v_and_b32_sdwa v117, v6, v244 dst_sel:DWORD dst_unused:UNUSED_PAD src0_sel:WORD_1 src1_sel:DWORD
	v_add3_u32 v116, v7, v116, s67
	v_add3_u32 v3, v111, v3, s67
	v_and_b32_e32 v109, 0xffff0000, v109
	v_add3_u32 v118, v6, v117, s67
	v_and_b32_e32 v119, 0xffff0000, v116
	v_or_b32_sdwa v117, v119, v3 dst_sel:DWORD dst_unused:UNUSED_PAD src0_sel:DWORD src1_sel:WORD_1
	v_or_b32_sdwa v116, v118, v109 dst_sel:DWORD dst_unused:UNUSED_PAD src0_sel:WORD_1 src1_sel:DWORD
	ds_write_b64 v106, v[116:117]
	v_and_b32_e32 v116, 0xffff0000, v118
	v_sub_u32_e32 v109, v110, v109
	v_and_b32_e32 v3, 0xffff0000, v3
	v_sub_u32_e32 v6, v6, v116
	v_add_u32_e32 v109, 0x80, v109
	v_sub_u32_e32 v3, v111, v3
	v_sub_u32_e32 v7, v7, v119
	v_add_u32_e32 v6, 0x80, v6
	v_ashrrev_i32_e32 v109, 8, v109
	v_add_u32_e32 v3, 0x80, v3
	v_add_u32_e32 v7, 0x80, v7
	v_ashrrev_i32_e32 v6, 8, v6
	v_min_i32_e32 v109, 0x7f, v109
	v_ashrrev_i32_e32 v3, 8, v3
	v_ashrrev_i32_e32 v7, 8, v7
	v_min_i32_e32 v6, 0x7f, v6
	v_min_i32_sdwa v3, v3, s69 dst_sel:WORD_1 dst_unused:UNUSED_PAD src0_sel:DWORD src1_sel:DWORD
	v_min_i32_e32 v7, 0x7f, v7
	v_lshlrev_b32_e32 v109, 8, v109
	v_and_b32_e32 v109, 0xff00, v109
	v_and_b32_e32 v3, 0xff0000, v3
	v_perm_b32 v6, v7, v6, s76
	v_or3_b32 v3, v6, v109, v3
	ds_write_b32 v14, v3 offset:144
	v_mov_b32_e32 v6, v184
	v_mov_b32_e32 v7, v185
	v_pk_add_f32 v[110:111], v[114:115], v[6:7] op_sel_hi:[1,0] neg_lo:[0,1] neg_hi:[0,1]
	v_pk_add_f32 v[112:113], v[112:113], v[6:7] op_sel_hi:[1,0] neg_lo:[0,1] neg_hi:[0,1]
	v_pk_mul_f32 v[110:111], v[6:7], v[110:111] op_sel:[1,0]
	v_pk_mul_f32 v[6:7], v[6:7], v[112:113] op_sel:[1,0]
	v_pk_fma_f32 v[110:111], v[64:65], v[110:111], v[66:67]
	v_pk_fma_f32 v[6:7], v[0:1], v[6:7], v[4:5]
	v_and_b32_sdwa v109, v110, v244 dst_sel:DWORD dst_unused:UNUSED_PAD src0_sel:WORD_1 src1_sel:DWORD
	v_and_b32_sdwa v112, v7, v244 dst_sel:DWORD dst_unused:UNUSED_PAD src0_sel:WORD_1 src1_sel:DWORD
	v_and_b32_sdwa v3, v111, v244 dst_sel:DWORD dst_unused:UNUSED_PAD src0_sel:WORD_1 src1_sel:DWORD
	v_add3_u32 v109, v110, v109, s67
	v_and_b32_sdwa v113, v6, v244 dst_sel:DWORD dst_unused:UNUSED_PAD src0_sel:WORD_1 src1_sel:DWORD
	v_add3_u32 v112, v7, v112, s67
	v_add3_u32 v3, v111, v3, s67
	v_and_b32_e32 v109, 0xffff0000, v109
	v_add3_u32 v114, v6, v113, s67
	v_and_b32_e32 v115, 0xffff0000, v112
	v_or_b32_sdwa v113, v115, v3 dst_sel:DWORD dst_unused:UNUSED_PAD src0_sel:DWORD src1_sel:WORD_1
	v_or_b32_sdwa v112, v114, v109 dst_sel:DWORD dst_unused:UNUSED_PAD src0_sel:WORD_1 src1_sel:DWORD
	ds_write_b64 v107, v[112:113]
	v_and_b32_e32 v112, 0xffff0000, v114
	v_sub_u32_e32 v109, v110, v109
	v_and_b32_e32 v3, 0xffff0000, v3
	v_sub_u32_e32 v6, v6, v112
	v_add_u32_e32 v109, 0x80, v109
	v_sub_u32_e32 v3, v111, v3
	v_sub_u32_e32 v7, v7, v115
	v_add_u32_e32 v6, 0x80, v6
	v_ashrrev_i32_e32 v109, 8, v109
	v_add_u32_e32 v3, 0x80, v3
	v_add_u32_e32 v7, 0x80, v7
	v_ashrrev_i32_e32 v6, 8, v6
	v_min_i32_e32 v109, 0x7f, v109
	v_ashrrev_i32_e32 v3, 8, v3
	v_ashrrev_i32_e32 v7, 8, v7
	v_min_i32_e32 v6, 0x7f, v6
	v_min_i32_sdwa v3, v3, s69 dst_sel:WORD_1 dst_unused:UNUSED_PAD src0_sel:DWORD src1_sel:DWORD
	v_min_i32_e32 v7, 0x7f, v7
	v_lshlrev_b32_e32 v109, 8, v109
	v_and_b32_e32 v109, 0xff00, v109
	v_and_b32_e32 v3, 0xff0000, v3
	v_perm_b32 v6, v7, v6, s76
	v_or3_b32 v3, v6, v109, v3
	ds_write_b32 v20, v3 offset:144
	v_mov_b32_e32 v6, v186
; #define WAIT_L(n) asm volatile("s_waitcnt lgkmcnt(" #n ")" ::: "memory")
; #define BAR __builtin_amdgcn_s_barrier()
;     ...
;             _Pragma("unroll") for (int m = 0; m < 4; ++m) {
;               const int rr = wr3 * 64 + m * 16 + fr3;
;               const float2 ms = *reinterpret_cast<const float2*>(mr + (ai * HALF + rr) * 2);
;               f32x4 y = acc[ai][bj][m][n];
;               const float o0 = (y[0] - ms.x) * ms.y * gm.x + bt.x, o1 = (y[1] - ms.x) * ms.y * gm.y + bt.y;
;               const float o2 = (y[2] - ms.x) * ms.y * gm.z + bt.z, o3 = (y[3] - ms.x) * ms.y * gm.w + bt.w;
;               const unsigned h0 = f2bf(o0), h1 = f2bf(o1), h2 = f2bf(o2), h3 = f2bf(o3);
;               u32x2 ob; ob[0] = h0 | (h1 << 16); ob[1] = h2 | (h3 << 16);
;               *reinterpret_cast<u32x2*>(smem + (rr >> 1) * PIECE + (rr & 1) * 512 + cc * 2) = ob;
;               const int l0 = min(((int)__float_as_uint(o0) - (int)(h0 << 16) + 128) >> 8, 127);
;               const int l1 = min(((int)__float_as_uint(o1) - (int)(h1 << 16) + 128) >> 8, 127);
;               const int l2 = min(((int)__float_as_uint(o2) - (int)(h2 << 16) + 128) >> 8, 127);
;               const int l3 = min(((int)__float_as_uint(o3) - (int)(h3 << 16) + 128) >> 8, 127);
;               *reinterpret_cast<unsigned*>(smem + LOBASE + (rr >> 2) * PIECE + (rr & 3) * 256 + cc) =
;                   (unsigned)(l0 & 255) | ((unsigned)(l1 & 255) << 8) | ((unsigned)(l2 & 255) << 16) | ((unsigned)l3 << 24);
;             }
;     ...
;           WAIT_L(0); BAR;
;           const int hso = ((brow + ai * HALF + 16 * wave) * DM + pn * BM) * 2;
;           const int lso = (brow + ai * HALF + 16 * wave) * DM + pn * BM;
;           _Pragma("unroll") for (int i = 0; i < 8; ++i) {
;             const u32x4 v = *reinterpret_cast<const u32x4*>(smem + (wave * 8 + i) * PIECE + lane3 * 16);
;             __builtin_amdgcn_raw_buffer_store_b128(v, rsXB, hvo + i * (2 * DM * 2), hso, 0);
;           }
;           _Pragma("unroll") for (int i = 0; i < 4; ++i) {
;             const u32x4 v = *reinterpret_cast<const u32x4*>(smem + LOBASE + (wave * 4 + i) * PIECE + lane3 * 16);
;             __builtin_amdgcn_raw_buffer_store_b128(v, rsLO, lvo + i * (4 * DM), lso, 0);
;           }
;           WAIT_L(0); BAR;
	v_mov_b32_e32 v7, v187
	v_or_b32_e32 v109, 0xa000, v70
	v_or_b32_e32 v110, 0xc000, v70
	v_or_b32_e32 v111, 0xe000, v70
	v_or_b32_e32 v112, 0x2000, v68
	v_pk_add_f32 v[90:91], v[90:91], v[6:7] op_sel_hi:[1,0] neg_lo:[0,1] neg_hi:[0,1]
	v_or_b32_e32 v113, 0x4000, v68
	v_pk_mul_f32 v[90:91], v[6:7], v[90:91] op_sel:[1,0]
	v_or_b32_e32 v114, 0x6000, v68
	v_pk_fma_f32 v[64:65], v[64:65], v[90:91], v[66:67]
	v_pk_add_f32 v[66:67], v[88:89], v[6:7] op_sel_hi:[1,0] neg_lo:[0,1] neg_hi:[0,1]
	v_and_b32_sdwa v3, v65, v244 dst_sel:DWORD dst_unused:UNUSED_PAD src0_sel:WORD_1 src1_sel:DWORD
	v_pk_mul_f32 v[6:7], v[6:7], v[66:67] op_sel:[1,0]
	v_add3_u32 v3, v65, v3, s67
	v_pk_fma_f32 v[0:1], v[0:1], v[6:7], v[4:5]
	v_and_b32_sdwa v4, v64, v244 dst_sel:DWORD dst_unused:UNUSED_PAD src0_sel:WORD_1 src1_sel:DWORD
	v_add3_u32 v4, v64, v4, s67
	v_and_b32_e32 v6, 0xffff0000, v4
	v_and_b32_sdwa v4, v1, v244 dst_sel:DWORD dst_unused:UNUSED_PAD src0_sel:WORD_1 src1_sel:DWORD
	v_and_b32_sdwa v5, v0, v244 dst_sel:DWORD dst_unused:UNUSED_PAD src0_sel:WORD_1 src1_sel:DWORD
	v_add3_u32 v4, v1, v4, s67
	v_add3_u32 v7, v0, v5, s67
	v_and_b32_e32 v66, 0xffff0000, v4
	v_add_u32_e32 v88, v2, v108
	v_and_b32_e32 v2, 0xffff0000, v7
	v_or_b32_sdwa v5, v66, v3 dst_sel:DWORD dst_unused:UNUSED_PAD src0_sel:DWORD src1_sel:WORD_1
	v_sub_u32_e32 v0, v0, v2
	v_sub_u32_e32 v2, v64, v6
	v_and_b32_e32 v3, 0xffff0000, v3
	v_add_u32_e32 v2, 0x80, v2
	v_sub_u32_e32 v3, v65, v3
	v_sub_u32_e32 v1, v1, v66
	v_add_u32_e32 v0, 0x80, v0
	v_ashrrev_i32_e32 v2, 8, v2
	v_add_u32_e32 v3, 0x80, v3
	v_add_u32_e32 v1, 0x80, v1
	v_ashrrev_i32_e32 v0, 8, v0
	v_min_i32_e32 v2, 0x7f, v2
	v_ashrrev_i32_e32 v3, 8, v3
	v_ashrrev_i32_e32 v1, 8, v1
	v_min_i32_e32 v0, 0x7f, v0
	v_min_i32_sdwa v3, v3, s69 dst_sel:WORD_1 dst_unused:UNUSED_PAD src0_sel:DWORD src1_sel:DWORD
	v_min_i32_e32 v1, 0x7f, v1
	v_lshlrev_b32_e32 v2, 8, v2
	v_and_b32_e32 v2, 0xff00, v2
	v_and_b32_e32 v3, 0xff0000, v3
	v_perm_b32 v0, v1, v0, s76
	v_or_b32_sdwa v4, v7, v6 dst_sel:DWORD dst_unused:UNUSED_PAD src0_sel:WORD_1 src1_sel:DWORD
	v_or3_b32 v0, v0, v2, v3
	ds_write_b64 v88, v[4:5]
	ds_write_b32 v22, v0 offset:144
	s_waitcnt lgkmcnt(0)
	s_barrier
	ds_read_b128 v[0:3], v74
	v_or_b32_e32 v89, 0x2000, v70
	v_or_b32_e32 v90, 0x4000, v70
	v_or_b32_e32 v91, 0x6000, v70
	v_or_b32_e32 v108, 0x8000, v70
	s_waitcnt lgkmcnt(0)
	buffer_store_dwordx4 v[0:3], v70, s[16:19], s22 offen
	ds_read_b128 v[0:3], v74 offset:1040
	s_waitcnt lgkmcnt(0)
	buffer_store_dwordx4 v[0:3], v89, s[16:19], s22 offen
	ds_read_b128 v[0:3], v74 offset:2080
	s_waitcnt lgkmcnt(0)
	buffer_store_dwordx4 v[0:3], v90, s[16:19], s22 offen
	ds_read_b128 v[0:3], v74 offset:3120
	s_waitcnt lgkmcnt(0)
	buffer_store_dwordx4 v[0:3], v91, s[16:19], s22 offen
	ds_read_b128 v[0:3], v74 offset:4160
	s_waitcnt lgkmcnt(0)
	buffer_store_dwordx4 v[0:3], v108, s[16:19], s22 offen
	ds_read_b128 v[0:3], v74 offset:5200
	s_waitcnt lgkmcnt(0)
	buffer_store_dwordx4 v[0:3], v109, s[16:19], s22 offen
	ds_read_b128 v[0:3], v74 offset:6240
	s_waitcnt lgkmcnt(0)
	buffer_store_dwordx4 v[0:3], v110, s[16:19], s22 offen
	ds_read_b128 v[0:3], v74 offset:7280
	s_waitcnt lgkmcnt(0)
	buffer_store_dwordx4 v[0:3], v111, s[16:19], s22 offen
	ds_read_b128 v[0:3], v69
	s_mov_b32 s22, s74
	s_waitcnt lgkmcnt(0)
	buffer_store_dwordx4 v[0:3], v68, s[20:23], s0 offen
	ds_read_b128 v[0:3], v69 offset:1040
	s_waitcnt lgkmcnt(0)
	buffer_store_dwordx4 v[0:3], v112, s[20:23], s0 offen
	ds_read_b128 v[0:3], v69 offset:2080
	s_waitcnt lgkmcnt(0)
	buffer_store_dwordx4 v[0:3], v113, s[20:23], s0 offen
	ds_read_b128 v[0:3], v69 offset:3120
	s_waitcnt lgkmcnt(0)
	buffer_store_dwordx4 v[0:3], v114, s[20:23], s0 offen
	s_waitcnt lgkmcnt(0)
	s_barrier
	s_nop 1
	v_mov_b32_e32 v0, v196
	v_mov_b32_e32 v1, v197
	v_mov_b32_e32 v2, v198
	v_mov_b32_e32 v3, v199
	v_mov_b32_e32 v4, v212
	v_mov_b32_e32 v5, v213
	v_mov_b32_e32 v6, v214
	v_mov_b32_e32 v7, v215
	ds_read_b64 v[116:117], v71 offset:1024
	s_add_i32 s0, s0, 0x40000
	s_waitcnt lgkmcnt(0)
	v_mov_b32_e32 v180, v116
	v_mov_b32_e32 v181, v117
	v_pk_add_f32 v[82:83], v[82:83], v[116:117] op_sel_hi:[1,0] neg_lo:[0,1] neg_hi:[0,1]
	s_nop 0
	v_pk_mul_f32 v[82:83], v[116:117], v[82:83] op_sel:[1,0]
	v_pk_add_f32 v[80:81], v[80:81], v[116:117] op_sel_hi:[1,0] neg_lo:[0,1] neg_hi:[0,1]
	v_mov_b32_e32 v64, v1
	v_mov_b32_e32 v65, v2
	v_mov_b32_e32 v66, v5
	v_mov_b32_e32 v67, v6
	v_pk_fma_f32 v[82:83], v[64:65], v[82:83], v[66:67]
	v_pk_mul_f32 v[80:81], v[116:117], v[80:81] op_sel:[1,0]
	v_mov_b32_e32 v1, v3
	v_mov_b32_e32 v5, v7
	v_and_b32_sdwa v6, v83, v244 dst_sel:DWORD dst_unused:UNUSED_PAD src0_sel:WORD_1 src1_sel:DWORD
	v_and_b32_sdwa v7, v82, v244 dst_sel:DWORD dst_unused:UNUSED_PAD src0_sel:WORD_1 src1_sel:DWORD
	v_pk_fma_f32 v[2:3], v[0:1], v[80:81], v[4:5]
	v_add3_u32 v80, v83, v6, s67
	v_add3_u32 v6, v82, v7, s67
	v_and_b32_e32 v81, 0xffff0000, v6
	v_and_b32_sdwa v6, v3, v244 dst_sel:DWORD dst_unused:UNUSED_PAD src0_sel:WORD_1 src1_sel:DWORD
	v_and_b32_sdwa v7, v2, v244 dst_sel:DWORD dst_unused:UNUSED_PAD src0_sel:WORD_1 src1_sel:DWORD
	v_add3_u32 v6, v3, v6, s67
	v_add3_u32 v115, v2, v7, s67
	v_and_b32_e32 v116, 0xffff0000, v6
	v_or_b32_sdwa v7, v116, v80 dst_sel:DWORD dst_unused:UNUSED_PAD src0_sel:DWORD src1_sel:WORD_1
	v_or_b32_sdwa v6, v115, v81 dst_sel:DWORD dst_unused:UNUSED_PAD src0_sel:WORD_1 src1_sel:DWORD
	ds_write_b64 v73, v[6:7]
	v_and_b32_e32 v6, 0xffff0000, v115
	v_sub_u32_e32 v2, v2, v6
	v_sub_u32_e32 v6, v82, v81
	v_and_b32_e32 v7, 0xffff0000, v80
	v_add_u32_e32 v6, 0x80, v6
	v_sub_u32_e32 v7, v83, v7
	v_sub_u32_e32 v3, v3, v116
	v_add_u32_e32 v2, 0x80, v2
	v_ashrrev_i32_e32 v6, 8, v6
	v_add_u32_e32 v7, 0x80, v7
	v_add_u32_e32 v3, 0x80, v3
	v_ashrrev_i32_e32 v2, 8, v2
	v_min_i32_e32 v6, 0x7f, v6
	v_ashrrev_i32_e32 v7, 8, v7
	v_ashrrev_i32_e32 v3, 8, v3
	v_min_i32_e32 v2, 0x7f, v2
	v_min_i32_sdwa v7, v7, s69 dst_sel:WORD_1 dst_unused:UNUSED_PAD src0_sel:DWORD src1_sel:DWORD
	v_min_i32_e32 v3, 0x7f, v3
	v_lshlrev_b32_e32 v6, 8, v6
	v_and_b32_e32 v6, 0xff00, v6
	v_and_b32_e32 v7, 0xff0000, v7
	v_perm_b32 v2, v3, v2, s76
	v_or3_b32 v2, v2, v6, v7
	ds_write_b32 v12, v2
	ds_read_b64 v[2:3], v13 offset:1024
	s_waitcnt lgkmcnt(0)
;     ...
;             _Pragma("unroll") for (int m = 0; m < 4; ++m) {
;               const int rr = wr3 * 64 + m * 16 + fr3;
;               const float2 ms = *reinterpret_cast<const float2*>(mr + (ai * HALF + rr) * 2);
;               f32x4 y = acc[ai][bj][m][n];
;               const float o0 = (y[0] - ms.x) * ms.y * gm.x + bt.x, o1 = (y[1] - ms.x) * ms.y * gm.y + bt.y;
;               const float o2 = (y[2] - ms.x) * ms.y * gm.z + bt.z, o3 = (y[3] - ms.x) * ms.y * gm.w + bt.w;
;               const unsigned h0 = f2bf(o0), h1 = f2bf(o1), h2 = f2bf(o2), h3 = f2bf(o3);
;               u32x2 ob; ob[0] = h0 | (h1 << 16); ob[1] = h2 | (h3 << 16);
;               *reinterpret_cast<u32x2*>(smem + (rr >> 1) * PIECE + (rr & 1) * 512 + cc * 2) = ob;
;               const int l0 = min(((int)__float_as_uint(o0) - (int)(h0 << 16) + 128) >> 8, 127);
;               const int l1 = min(((int)__float_as_uint(o1) - (int)(h1 << 16) + 128) >> 8, 127);
;               const int l2 = min(((int)__float_as_uint(o2) - (int)(h2 << 16) + 128) >> 8, 127);
;               const int l3 = min(((int)__float_as_uint(o3) - (int)(h3 << 16) + 128) >> 8, 127);
;               *reinterpret_cast<unsigned*>(smem + LOBASE + (rr >> 2) * PIECE + (rr & 3) * 256 + cc) =
;                   (unsigned)(l0 & 255) | ((unsigned)(l1 & 255) << 8) | ((unsigned)(l2 & 255) << 16) | ((unsigned)l3 << 24);
;             }
	v_mov_b32_e32 v182, v2
	v_mov_b32_e32 v183, v3
	v_pk_add_f32 v[6:7], v[86:87], v[2:3] op_sel_hi:[1,0] neg_lo:[0,1] neg_hi:[0,1]
	s_nop 0
	v_pk_mul_f32 v[6:7], v[2:3], v[6:7] op_sel:[1,0]
	v_pk_add_f32 v[80:81], v[84:85], v[2:3] op_sel_hi:[1,0] neg_lo:[0,1] neg_hi:[0,1]
	v_pk_fma_f32 v[6:7], v[64:65], v[6:7], v[66:67]
	v_pk_mul_f32 v[2:3], v[2:3], v[80:81] op_sel:[1,0]
	v_and_b32_sdwa v80, v6, v244 dst_sel:DWORD dst_unused:UNUSED_PAD src0_sel:WORD_1 src1_sel:DWORD
	v_pk_fma_f32 v[2:3], v[0:1], v[2:3], v[4:5]
	v_add3_u32 v80, v6, v80, s67
	v_and_b32_e32 v82, 0xffff0000, v80
	v_and_b32_sdwa v80, v3, v244 dst_sel:DWORD dst_unused:UNUSED_PAD src0_sel:WORD_1 src1_sel:DWORD
	v_and_b32_sdwa v73, v7, v244 dst_sel:DWORD dst_unused:UNUSED_PAD src0_sel:WORD_1 src1_sel:DWORD
	v_and_b32_sdwa v81, v2, v244 dst_sel:DWORD dst_unused:UNUSED_PAD src0_sel:WORD_1 src1_sel:DWORD
	v_add3_u32 v80, v3, v80, s67
	v_add3_u32 v73, v7, v73, s67
	v_add3_u32 v83, v2, v81, s67
	v_and_b32_e32 v84, 0xffff0000, v80
	v_or_b32_sdwa v81, v84, v73 dst_sel:DWORD dst_unused:UNUSED_PAD src0_sel:DWORD src1_sel:WORD_1
	v_or_b32_sdwa v80, v83, v82 dst_sel:DWORD dst_unused:UNUSED_PAD src0_sel:WORD_1 src1_sel:DWORD
	ds_write_b64 v75, v[80:81]
	v_and_b32_e32 v75, 0xffff0000, v83
	v_sub_u32_e32 v6, v6, v82
	v_and_b32_e32 v73, 0xffff0000, v73
	v_sub_u32_e32 v2, v2, v75
	v_add_u32_e32 v6, 0x80, v6
	v_sub_u32_e32 v7, v7, v73
	v_sub_u32_e32 v3, v3, v84
	v_add_u32_e32 v2, 0x80, v2
	v_ashrrev_i32_e32 v6, 8, v6
	v_add_u32_e32 v7, 0x80, v7
	v_add_u32_e32 v3, 0x80, v3
	v_ashrrev_i32_e32 v2, 8, v2
	v_min_i32_e32 v6, 0x7f, v6
	v_ashrrev_i32_e32 v7, 8, v7
	v_ashrrev_i32_e32 v3, 8, v3
	v_min_i32_e32 v2, 0x7f, v2
	v_min_i32_sdwa v7, v7, s69 dst_sel:WORD_1 dst_unused:UNUSED_PAD src0_sel:DWORD src1_sel:DWORD
	v_min_i32_e32 v3, 0x7f, v3
	v_lshlrev_b32_e32 v6, 8, v6
	v_and_b32_e32 v6, 0xff00, v6
	v_and_b32_e32 v7, 0xff0000, v7
	v_perm_b32 v2, v3, v2, s76
	v_or3_b32 v2, v2, v6, v7
	ds_write_b32 v14, v2
	ds_read_b64 v[2:3], v15 offset:1024
	s_waitcnt lgkmcnt(0)
	v_mov_b32_e32 v184, v2
	v_mov_b32_e32 v185, v3
	v_pk_add_f32 v[6:7], v[94:95], v[2:3] op_sel_hi:[1,0] neg_lo:[0,1] neg_hi:[0,1]
	v_pk_add_f32 v[80:81], v[92:93], v[2:3] op_sel_hi:[1,0] neg_lo:[0,1] neg_hi:[0,1]
	v_pk_mul_f32 v[6:7], v[2:3], v[6:7] op_sel:[1,0]
	v_pk_mul_f32 v[2:3], v[2:3], v[80:81] op_sel:[1,0]
	v_pk_fma_f32 v[6:7], v[64:65], v[6:7], v[66:67]
	v_pk_fma_f32 v[2:3], v[0:1], v[2:3], v[4:5]
	v_and_b32_sdwa v75, v6, v244 dst_sel:DWORD dst_unused:UNUSED_PAD src0_sel:WORD_1 src1_sel:DWORD
	v_and_b32_sdwa v80, v3, v244 dst_sel:DWORD dst_unused:UNUSED_PAD src0_sel:WORD_1 src1_sel:DWORD
	v_and_b32_sdwa v73, v7, v244 dst_sel:DWORD dst_unused:UNUSED_PAD src0_sel:WORD_1 src1_sel:DWORD
	v_add3_u32 v75, v6, v75, s67
	v_and_b32_sdwa v81, v2, v244 dst_sel:DWORD dst_unused:UNUSED_PAD src0_sel:WORD_1 src1_sel:DWORD
	v_add3_u32 v80, v3, v80, s67
	v_add3_u32 v73, v7, v73, s67
	v_and_b32_e32 v75, 0xffff0000, v75
	v_add3_u32 v82, v2, v81, s67
	v_and_b32_e32 v83, 0xffff0000, v80
	v_or_b32_sdwa v81, v83, v73 dst_sel:DWORD dst_unused:UNUSED_PAD src0_sel:DWORD src1_sel:WORD_1
	v_or_b32_sdwa v80, v82, v75 dst_sel:DWORD dst_unused:UNUSED_PAD src0_sel:WORD_1 src1_sel:DWORD
	ds_write_b64 v96, v[80:81]
	v_and_b32_e32 v80, 0xffff0000, v82
	v_sub_u32_e32 v6, v6, v75
	v_and_b32_e32 v73, 0xffff0000, v73
	v_sub_u32_e32 v2, v2, v80
	v_add_u32_e32 v6, 0x80, v6
	v_sub_u32_e32 v7, v7, v73
	v_sub_u32_e32 v3, v3, v83
	v_add_u32_e32 v2, 0x80, v2
	v_ashrrev_i32_e32 v6, 8, v6
	v_add_u32_e32 v7, 0x80, v7
	v_add_u32_e32 v3, 0x80, v3
	v_ashrrev_i32_e32 v2, 8, v2
	v_min_i32_e32 v6, 0x7f, v6
	v_ashrrev_i32_e32 v7, 8, v7
	v_ashrrev_i32_e32 v3, 8, v3
	v_min_i32_e32 v2, 0x7f, v2
	v_min_i32_sdwa v7, v7, s69 dst_sel:WORD_1 dst_unused:UNUSED_PAD src0_sel:DWORD src1_sel:DWORD
	v_min_i32_e32 v3, 0x7f, v3
	v_lshlrev_b32_e32 v6, 8, v6
	v_and_b32_e32 v6, 0xff00, v6
	v_and_b32_e32 v7, 0xff0000, v7
	v_perm_b32 v2, v3, v2, s76
	v_or3_b32 v2, v2, v6, v7
	ds_write_b32 v20, v2
	ds_read_b64 v[2:3], v21 offset:1024
	s_waitcnt lgkmcnt(0)
	v_mov_b32_e32 v186, v2
	v_mov_b32_e32 v187, v3
	v_pk_add_f32 v[6:7], v[78:79], v[2:3] op_sel_hi:[1,0] neg_lo:[0,1] neg_hi:[0,1]
	s_nop 0
	v_pk_mul_f32 v[6:7], v[2:3], v[6:7] op_sel:[1,0]
	s_nop 0
	v_pk_fma_f32 v[6:7], v[64:65], v[6:7], v[66:67]
	v_pk_add_f32 v[64:65], v[76:77], v[2:3] op_sel_hi:[1,0] neg_lo:[0,1] neg_hi:[0,1]
	s_nop 0
	v_pk_mul_f32 v[2:3], v[2:3], v[64:65] op_sel:[1,0]
	s_nop 0
	v_pk_fma_f32 v[0:1], v[0:1], v[2:3], v[4:5]
	v_and_b32_sdwa v2, v7, v244 dst_sel:DWORD dst_unused:UNUSED_PAD src0_sel:WORD_1 src1_sel:DWORD
	v_and_b32_sdwa v3, v6, v244 dst_sel:DWORD dst_unused:UNUSED_PAD src0_sel:WORD_1 src1_sel:DWORD
	v_add3_u32 v4, v7, v2, s67
	v_add3_u32 v2, v6, v3, s67
	v_and_b32_e32 v5, 0xffff0000, v2
	v_and_b32_sdwa v2, v1, v244 dst_sel:DWORD dst_unused:UNUSED_PAD src0_sel:WORD_1 src1_sel:DWORD
	v_and_b32_sdwa v3, v0, v244 dst_sel:DWORD dst_unused:UNUSED_PAD src0_sel:WORD_1 src1_sel:DWORD
	v_add3_u32 v2, v1, v2, s67
	v_add3_u32 v64, v0, v3, s67
	v_and_b32_e32 v65, 0xffff0000, v2
	v_or_b32_sdwa v3, v65, v4 dst_sel:DWORD dst_unused:UNUSED_PAD src0_sel:DWORD src1_sel:WORD_1
	v_or_b32_sdwa v2, v64, v5 dst_sel:DWORD dst_unused:UNUSED_PAD src0_sel:WORD_1 src1_sel:DWORD
	ds_write_b64 v97, v[2:3]
	v_and_b32_e32 v2, 0xffff0000, v64
	v_sub_u32_e32 v0, v0, v2
	v_sub_u32_e32 v2, v6, v5
	v_and_b32_e32 v3, 0xffff0000, v4
	v_add_u32_e32 v2, 0x80, v2
	v_sub_u32_e32 v3, v7, v3
	v_sub_u32_e32 v1, v1, v65
	v_add_u32_e32 v0, 0x80, v0
	v_ashrrev_i32_e32 v2, 8, v2
	v_add_u32_e32 v3, 0x80, v3
	v_add_u32_e32 v1, 0x80, v1
	v_ashrrev_i32_e32 v0, 8, v0
	v_min_i32_e32 v2, 0x7f, v2
;     ...
;         _Pragma("unroll") for (int ai = 0; ai < 2; ++ai) {
;           _Pragma("unroll") for (int bj = 0; bj < 2; ++bj) _Pragma("unroll") for (int n = 0; n < 2; ++n) {
;             const int cc = bj * HALF + wc3 * 32 + n * 16 + fq3 * 4;
;             const float4 gm = *reinterpret_cast<const float4*>(g.gam + pn * BM + cc), bt = *reinterpret_cast<const float4*>(g.bet + pn * BM + cc);
;             _Pragma("unroll") for (int m = 0; m < 4; ++m) {
;               const int rr = wr3 * 64 + m * 16 + fr3;
;               const float2 ms = *reinterpret_cast<const float2*>(mr + (ai * HALF + rr) * 2);
;               f32x4 y = acc[ai][bj][m][n];
;               const float o0 = (y[0] - ms.x) * ms.y * gm.x + bt.x, o1 = (y[1] - ms.x) * ms.y * gm.y + bt.y;
;               const float o2 = (y[2] - ms.x) * ms.y * gm.z + bt.z, o3 = (y[3] - ms.x) * ms.y * gm.w + bt.w;
;               const unsigned h0 = f2bf(o0), h1 = f2bf(o1), h2 = f2bf(o2), h3 = f2bf(o3);
;               u32x2 ob; ob[0] = h0 | (h1 << 16); ob[1] = h2 | (h3 << 16);
;               *reinterpret_cast<u32x2*>(smem + (rr >> 1) * PIECE + (rr & 1) * 512 + cc * 2) = ob;
;               const int l0 = min(((int)__float_as_uint(o0) - (int)(h0 << 16) + 128) >> 8, 127);
;               const int l1 = min(((int)__float_as_uint(o1) - (int)(h1 << 16) + 128) >> 8, 127);
;               const int l2 = min(((int)__float_as_uint(o2) - (int)(h2 << 16) + 128) >> 8, 127);
;               const int l3 = min(((int)__float_as_uint(o3) - (int)(h3 << 16) + 128) >> 8, 127);
;               *reinterpret_cast<unsigned*>(smem + LOBASE + (rr >> 2) * PIECE + (rr & 3) * 256 + cc) =
;                   (unsigned)(l0 & 255) | ((unsigned)(l1 & 255) << 8) | ((unsigned)(l2 & 255) << 16) | ((unsigned)l3 << 24);
;             }
	v_ashrrev_i32_e32 v3, 8, v3
	v_ashrrev_i32_e32 v1, 8, v1
	v_min_i32_e32 v0, 0x7f, v0
	v_min_i32_sdwa v3, v3, s69 dst_sel:WORD_1 dst_unused:UNUSED_PAD src0_sel:DWORD src1_sel:DWORD
	v_min_i32_e32 v1, 0x7f, v1
	v_lshlrev_b32_e32 v2, 8, v2
	v_and_b32_e32 v2, 0xff00, v2
	v_and_b32_e32 v3, 0xff0000, v3
	v_perm_b32 v0, v1, v0, s76
	v_or3_b32 v0, v0, v2, v3
	ds_write_b32 v22, v0
	v_mov_b32_e32 v0, v200
	v_mov_b32_e32 v1, v201
	v_mov_b32_e32 v2, v202
	v_mov_b32_e32 v3, v203
	v_mov_b32_e32 v4, v220
	v_mov_b32_e32 v5, v221
	v_mov_b32_e32 v6, v222
	v_mov_b32_e32 v7, v223
	v_mov_b32_e32 v76, v180
	v_mov_b32_e32 v77, v181
	v_pk_add_f32 v[62:63], v[62:63], v[76:77] op_sel_hi:[1,0] neg_lo:[0,1] neg_hi:[0,1]
	s_nop 0
	v_pk_mul_f32 v[62:63], v[76:77], v[62:63] op_sel:[1,0]
	v_pk_add_f32 v[60:61], v[60:61], v[76:77] op_sel_hi:[1,0] neg_lo:[0,1] neg_hi:[0,1]
	v_mov_b32_e32 v64, v1
	v_mov_b32_e32 v65, v2
	v_mov_b32_e32 v66, v5
	v_mov_b32_e32 v67, v6
	v_pk_fma_f32 v[62:63], v[64:65], v[62:63], v[66:67]
	v_pk_mul_f32 v[60:61], v[76:77], v[60:61] op_sel:[1,0]
	v_mov_b32_e32 v1, v3
	v_mov_b32_e32 v5, v7
	v_and_b32_sdwa v6, v63, v244 dst_sel:DWORD dst_unused:UNUSED_PAD src0_sel:WORD_1 src1_sel:DWORD
	v_and_b32_sdwa v7, v62, v244 dst_sel:DWORD dst_unused:UNUSED_PAD src0_sel:WORD_1 src1_sel:DWORD
	v_pk_fma_f32 v[2:3], v[0:1], v[60:61], v[4:5]
	v_add3_u32 v60, v63, v6, s67
	v_add3_u32 v6, v62, v7, s67
	v_and_b32_e32 v61, 0xffff0000, v6
	v_and_b32_sdwa v6, v3, v244 dst_sel:DWORD dst_unused:UNUSED_PAD src0_sel:WORD_1 src1_sel:DWORD
	v_and_b32_sdwa v7, v2, v244 dst_sel:DWORD dst_unused:UNUSED_PAD src0_sel:WORD_1 src1_sel:DWORD
	v_add3_u32 v6, v3, v6, s67
	v_add3_u32 v73, v2, v7, s67
	v_and_b32_e32 v75, 0xffff0000, v6
	v_or_b32_sdwa v7, v75, v60 dst_sel:DWORD dst_unused:UNUSED_PAD src0_sel:DWORD src1_sel:WORD_1
	v_or_b32_sdwa v6, v73, v61 dst_sel:DWORD dst_unused:UNUSED_PAD src0_sel:WORD_1 src1_sel:DWORD
	ds_write_b64 v23, v[6:7]
	v_and_b32_e32 v6, 0xffff0000, v73
	v_sub_u32_e32 v2, v2, v6
	v_sub_u32_e32 v6, v62, v61
	v_and_b32_e32 v7, 0xffff0000, v60
	v_add_u32_e32 v6, 0x80, v6
	v_sub_u32_e32 v7, v63, v7
	v_sub_u32_e32 v3, v3, v75
	v_add_u32_e32 v2, 0x80, v2
	v_ashrrev_i32_e32 v6, 8, v6
	v_add_u32_e32 v7, 0x80, v7
	v_add_u32_e32 v3, 0x80, v3
	v_ashrrev_i32_e32 v2, 8, v2
	v_min_i32_e32 v6, 0x7f, v6
	v_ashrrev_i32_e32 v7, 8, v7
	v_ashrrev_i32_e32 v3, 8, v3
	v_min_i32_e32 v2, 0x7f, v2
	v_min_i32_sdwa v7, v7, s69 dst_sel:WORD_1 dst_unused:UNUSED_PAD src0_sel:DWORD src1_sel:DWORD
	v_min_i32_e32 v3, 0x7f, v3
	v_lshlrev_b32_e32 v6, 8, v6
	v_and_b32_e32 v6, 0xff00, v6
	v_and_b32_e32 v7, 0xff0000, v7
	v_perm_b32 v2, v3, v2, s76
	v_or3_b32 v2, v2, v6, v7
	ds_write_b32 v12, v2 offset:16
	v_mov_b32_e32 v2, v182
	v_mov_b32_e32 v3, v183
	v_pk_add_f32 v[6:7], v[46:47], v[2:3] op_sel_hi:[1,0] neg_lo:[0,1] neg_hi:[0,1]
	s_nop 0
	v_pk_mul_f32 v[6:7], v[2:3], v[6:7] op_sel:[1,0]
	v_pk_add_f32 v[44:45], v[44:45], v[2:3] op_sel_hi:[1,0] neg_lo:[0,1] neg_hi:[0,1]
	v_pk_fma_f32 v[6:7], v[64:65], v[6:7], v[66:67]
	v_pk_mul_f32 v[2:3], v[2:3], v[44:45] op_sel:[1,0]
	v_and_b32_sdwa v44, v6, v244 dst_sel:DWORD dst_unused:UNUSED_PAD src0_sel:WORD_1 src1_sel:DWORD
	v_pk_fma_f32 v[2:3], v[0:1], v[2:3], v[4:5]
	v_add3_u32 v44, v6, v44, s67
	v_and_b32_e32 v46, 0xffff0000, v44
	v_and_b32_sdwa v44, v3, v244 dst_sel:DWORD dst_unused:UNUSED_PAD src0_sel:WORD_1 src1_sel:DWORD
	v_and_b32_sdwa v23, v7, v244 dst_sel:DWORD dst_unused:UNUSED_PAD src0_sel:WORD_1 src1_sel:DWORD
	v_and_b32_sdwa v45, v2, v244 dst_sel:DWORD dst_unused:UNUSED_PAD src0_sel:WORD_1 src1_sel:DWORD
	v_add3_u32 v44, v3, v44, s67
	v_add3_u32 v23, v7, v23, s67
	v_add3_u32 v47, v2, v45, s67
	v_and_b32_e32 v60, 0xffff0000, v44
	v_or_b32_sdwa v45, v60, v23 dst_sel:DWORD dst_unused:UNUSED_PAD src0_sel:DWORD src1_sel:WORD_1
	v_or_b32_sdwa v44, v47, v46 dst_sel:DWORD dst_unused:UNUSED_PAD src0_sel:WORD_1 src1_sel:DWORD
	ds_write_b64 v98, v[44:45]
	v_and_b32_e32 v44, 0xffff0000, v47
	v_sub_u32_e32 v6, v6, v46
	v_and_b32_e32 v23, 0xffff0000, v23
	v_sub_u32_e32 v2, v2, v44
	v_add_u32_e32 v6, 0x80, v6
	v_sub_u32_e32 v7, v7, v23
	v_sub_u32_e32 v3, v3, v60
	v_add_u32_e32 v2, 0x80, v2
	v_ashrrev_i32_e32 v6, 8, v6
	v_add_u32_e32 v7, 0x80, v7
	v_add_u32_e32 v3, 0x80, v3
	v_ashrrev_i32_e32 v2, 8, v2
	v_min_i32_e32 v6, 0x7f, v6
	v_ashrrev_i32_e32 v7, 8, v7
	v_ashrrev_i32_e32 v3, 8, v3
	v_min_i32_e32 v2, 0x7f, v2
	v_min_i32_sdwa v7, v7, s69 dst_sel:WORD_1 dst_unused:UNUSED_PAD src0_sel:DWORD src1_sel:DWORD
	v_min_i32_e32 v3, 0x7f, v3
	v_lshlrev_b32_e32 v6, 8, v6
	v_and_b32_e32 v6, 0xff00, v6
	v_and_b32_e32 v7, 0xff0000, v7
	v_perm_b32 v2, v3, v2, s76
	v_or3_b32 v2, v2, v6, v7
	ds_write_b32 v14, v2 offset:16
	v_mov_b32_e32 v2, v184
	v_mov_b32_e32 v3, v185
	v_pk_add_f32 v[6:7], v[42:43], v[2:3] op_sel_hi:[1,0] neg_lo:[0,1] neg_hi:[0,1]
	s_nop 0
	v_pk_mul_f32 v[6:7], v[2:3], v[6:7] op_sel:[1,0]
	v_pk_add_f32 v[40:41], v[40:41], v[2:3] op_sel_hi:[1,0] neg_lo:[0,1] neg_hi:[0,1]
	v_pk_fma_f32 v[6:7], v[64:65], v[6:7], v[66:67]
	v_pk_mul_f32 v[2:3], v[2:3], v[40:41] op_sel:[1,0]
	v_and_b32_sdwa v40, v6, v244 dst_sel:DWORD dst_unused:UNUSED_PAD src0_sel:WORD_1 src1_sel:DWORD
	v_pk_fma_f32 v[2:3], v[0:1], v[2:3], v[4:5]
	v_add3_u32 v40, v6, v40, s67
	v_and_b32_e32 v42, 0xffff0000, v40
	v_and_b32_sdwa v40, v3, v244 dst_sel:DWORD dst_unused:UNUSED_PAD src0_sel:WORD_1 src1_sel:DWORD
	v_and_b32_sdwa v23, v7, v244 dst_sel:DWORD dst_unused:UNUSED_PAD src0_sel:WORD_1 src1_sel:DWORD
	v_and_b32_sdwa v41, v2, v244 dst_sel:DWORD dst_unused:UNUSED_PAD src0_sel:WORD_1 src1_sel:DWORD
	v_add3_u32 v40, v3, v40, s67
	v_add3_u32 v23, v7, v23, s67
	v_add3_u32 v43, v2, v41, s67
;     ...
;         _Pragma("unroll") for (int ai = 0; ai < 2; ++ai) {
;           _Pragma("unroll") for (int bj = 0; bj < 2; ++bj) _Pragma("unroll") for (int n = 0; n < 2; ++n) {
;             const int cc = bj * HALF + wc3 * 32 + n * 16 + fq3 * 4;
;             const float4 gm = *reinterpret_cast<const float4*>(g.gam + pn * BM + cc), bt = *reinterpret_cast<const float4*>(g.bet + pn * BM + cc);
;             _Pragma("unroll") for (int m = 0; m < 4; ++m) {
;               const int rr = wr3 * 64 + m * 16 + fr3;
;               const float2 ms = *reinterpret_cast<const float2*>(mr + (ai * HALF + rr) * 2);
;               f32x4 y = acc[ai][bj][m][n];
;               const float o0 = (y[0] - ms.x) * ms.y * gm.x + bt.x, o1 = (y[1] - ms.x) * ms.y * gm.y + bt.y;
;               const float o2 = (y[2] - ms.x) * ms.y * gm.z + bt.z, o3 = (y[3] - ms.x) * ms.y * gm.w + bt.w;
;               const unsigned h0 = f2bf(o0), h1 = f2bf(o1), h2 = f2bf(o2), h3 = f2bf(o3);
;               u32x2 ob; ob[0] = h0 | (h1 << 16); ob[1] = h2 | (h3 << 16);
;               *reinterpret_cast<u32x2*>(smem + (rr >> 1) * PIECE + (rr & 1) * 512 + cc * 2) = ob;
;               const int l0 = min(((int)__float_as_uint(o0) - (int)(h0 << 16) + 128) >> 8, 127);
;               const int l1 = min(((int)__float_as_uint(o1) - (int)(h1 << 16) + 128) >> 8, 127);
;               const int l2 = min(((int)__float_as_uint(o2) - (int)(h2 << 16) + 128) >> 8, 127);
;               const int l3 = min(((int)__float_as_uint(o3) - (int)(h3 << 16) + 128) >> 8, 127);
;               *reinterpret_cast<unsigned*>(smem + LOBASE + (rr >> 2) * PIECE + (rr & 3) * 256 + cc) =
;                   (unsigned)(l0 & 255) | ((unsigned)(l1 & 255) << 8) | ((unsigned)(l2 & 255) << 16) | ((unsigned)l3 << 24);
;             }
	v_and_b32_e32 v44, 0xffff0000, v40
	v_or_b32_sdwa v41, v44, v23 dst_sel:DWORD dst_unused:UNUSED_PAD src0_sel:DWORD src1_sel:WORD_1
	v_or_b32_sdwa v40, v43, v42 dst_sel:DWORD dst_unused:UNUSED_PAD src0_sel:WORD_1 src1_sel:DWORD
	ds_write_b64 v99, v[40:41]
	v_and_b32_e32 v40, 0xffff0000, v43
	v_sub_u32_e32 v6, v6, v42
	v_and_b32_e32 v23, 0xffff0000, v23
	v_sub_u32_e32 v2, v2, v40
	v_add_u32_e32 v6, 0x80, v6
	v_sub_u32_e32 v7, v7, v23
	v_sub_u32_e32 v3, v3, v44
	v_add_u32_e32 v2, 0x80, v2
	v_ashrrev_i32_e32 v6, 8, v6
	v_add_u32_e32 v7, 0x80, v7
	v_add_u32_e32 v3, 0x80, v3
	v_ashrrev_i32_e32 v2, 8, v2
	v_min_i32_e32 v6, 0x7f, v6
	v_ashrrev_i32_e32 v7, 8, v7
	v_ashrrev_i32_e32 v3, 8, v3
	v_min_i32_e32 v2, 0x7f, v2
	v_min_i32_sdwa v7, v7, s69 dst_sel:WORD_1 dst_unused:UNUSED_PAD src0_sel:DWORD src1_sel:DWORD
	v_min_i32_e32 v3, 0x7f, v3
	v_lshlrev_b32_e32 v6, 8, v6
	v_and_b32_e32 v6, 0xff00, v6
	v_and_b32_e32 v7, 0xff0000, v7
	v_perm_b32 v2, v3, v2, s76
	v_or3_b32 v2, v2, v6, v7
	ds_write_b32 v20, v2 offset:16
	v_mov_b32_e32 v2, v186
	v_mov_b32_e32 v3, v187
	v_pk_add_f32 v[6:7], v[58:59], v[2:3] op_sel_hi:[1,0] neg_lo:[0,1] neg_hi:[0,1]
	s_nop 0
	v_pk_mul_f32 v[6:7], v[2:3], v[6:7] op_sel:[1,0]
	v_pk_add_f32 v[40:41], v[56:57], v[2:3] op_sel_hi:[1,0] neg_lo:[0,1] neg_hi:[0,1]
	v_pk_fma_f32 v[6:7], v[64:65], v[6:7], v[66:67]
	v_pk_mul_f32 v[2:3], v[2:3], v[40:41] op_sel:[1,0]
	s_nop 0
	v_pk_fma_f32 v[0:1], v[0:1], v[2:3], v[4:5]
	v_and_b32_sdwa v2, v7, v244 dst_sel:DWORD dst_unused:UNUSED_PAD src0_sel:WORD_1 src1_sel:DWORD
	v_and_b32_sdwa v3, v6, v244 dst_sel:DWORD dst_unused:UNUSED_PAD src0_sel:WORD_1 src1_sel:DWORD
	v_add3_u32 v4, v7, v2, s67
	v_add3_u32 v2, v6, v3, s67
	v_and_b32_e32 v5, 0xffff0000, v2
	v_and_b32_sdwa v2, v1, v244 dst_sel:DWORD dst_unused:UNUSED_PAD src0_sel:WORD_1 src1_sel:DWORD
	v_and_b32_sdwa v3, v0, v244 dst_sel:DWORD dst_unused:UNUSED_PAD src0_sel:WORD_1 src1_sel:DWORD
	v_add3_u32 v2, v1, v2, s67
	v_add3_u32 v23, v0, v3, s67
	v_and_b32_e32 v40, 0xffff0000, v2
	v_or_b32_sdwa v3, v40, v4 dst_sel:DWORD dst_unused:UNUSED_PAD src0_sel:DWORD src1_sel:WORD_1
	v_or_b32_sdwa v2, v23, v5 dst_sel:DWORD dst_unused:UNUSED_PAD src0_sel:WORD_1 src1_sel:DWORD
	ds_write_b64 v100, v[2:3]
	v_and_b32_e32 v2, 0xffff0000, v23
	v_sub_u32_e32 v0, v0, v2
	v_sub_u32_e32 v2, v6, v5
	v_and_b32_e32 v3, 0xffff0000, v4
	v_add_u32_e32 v2, 0x80, v2
	v_sub_u32_e32 v3, v7, v3
	v_sub_u32_e32 v1, v1, v40
	v_add_u32_e32 v0, 0x80, v0
	v_ashrrev_i32_e32 v2, 8, v2
	v_add_u32_e32 v3, 0x80, v3
	v_add_u32_e32 v1, 0x80, v1
	v_ashrrev_i32_e32 v0, 8, v0
	v_min_i32_e32 v2, 0x7f, v2
	v_ashrrev_i32_e32 v3, 8, v3
	v_ashrrev_i32_e32 v1, 8, v1
	v_min_i32_e32 v0, 0x7f, v0
	v_min_i32_sdwa v3, v3, s69 dst_sel:WORD_1 dst_unused:UNUSED_PAD src0_sel:DWORD src1_sel:DWORD
	v_min_i32_e32 v1, 0x7f, v1
	v_lshlrev_b32_e32 v2, 8, v2
	v_and_b32_e32 v2, 0xff00, v2
	v_and_b32_e32 v3, 0xff0000, v3
	v_perm_b32 v0, v1, v0, s76
	v_or3_b32 v0, v0, v2, v3
	ds_write_b32 v22, v0 offset:16
	v_mov_b32_e32 v0, v204
	v_mov_b32_e32 v1, v205
	v_mov_b32_e32 v2, v206
	v_mov_b32_e32 v3, v207
	v_mov_b32_e32 v4, v240
	v_mov_b32_e32 v5, v241
	v_mov_b32_e32 v6, v242
	v_mov_b32_e32 v7, v243
	v_mov_b32_e32 v44, v180
	v_mov_b32_e32 v45, v181
	v_pk_add_f32 v[46:47], v[54:55], v[44:45] op_sel_hi:[1,0] neg_lo:[0,1] neg_hi:[0,1]
	s_nop 0
	v_pk_mul_f32 v[46:47], v[44:45], v[46:47] op_sel:[1,0]
	v_pk_add_f32 v[52:53], v[52:53], v[44:45] op_sel_hi:[1,0] neg_lo:[0,1] neg_hi:[0,1]
	v_mov_b32_e32 v40, v1
	v_mov_b32_e32 v41, v2
	v_mov_b32_e32 v42, v5
	v_mov_b32_e32 v43, v6
	v_pk_fma_f32 v[46:47], v[40:41], v[46:47], v[42:43]
	v_pk_mul_f32 v[44:45], v[44:45], v[52:53] op_sel:[1,0]
	v_mov_b32_e32 v1, v3
	v_mov_b32_e32 v5, v7
	v_and_b32_sdwa v6, v47, v244 dst_sel:DWORD dst_unused:UNUSED_PAD src0_sel:WORD_1 src1_sel:DWORD
	v_and_b32_sdwa v7, v46, v244 dst_sel:DWORD dst_unused:UNUSED_PAD src0_sel:WORD_1 src1_sel:DWORD
	v_pk_fma_f32 v[2:3], v[0:1], v[44:45], v[4:5]
	v_add3_u32 v23, v47, v6, s67
	v_add3_u32 v6, v46, v7, s67
	v_and_b32_e32 v44, 0xffff0000, v6
	v_and_b32_sdwa v6, v3, v244 dst_sel:DWORD dst_unused:UNUSED_PAD src0_sel:WORD_1 src1_sel:DWORD
	v_and_b32_sdwa v7, v2, v244 dst_sel:DWORD dst_unused:UNUSED_PAD src0_sel:WORD_1 src1_sel:DWORD
	v_add3_u32 v6, v3, v6, s67
	v_add3_u32 v45, v2, v7, s67
	v_and_b32_e32 v52, 0xffff0000, v6
	v_or_b32_sdwa v7, v52, v23 dst_sel:DWORD dst_unused:UNUSED_PAD src0_sel:DWORD src1_sel:WORD_1
	v_or_b32_sdwa v6, v45, v44 dst_sel:DWORD dst_unused:UNUSED_PAD src0_sel:WORD_1 src1_sel:DWORD
	ds_write_b64 v101, v[6:7]
	v_and_b32_e32 v6, 0xffff0000, v45
	v_sub_u32_e32 v2, v2, v6
	v_sub_u32_e32 v6, v46, v44
	v_and_b32_e32 v7, 0xffff0000, v23
	v_add_u32_e32 v6, 0x80, v6
	v_sub_u32_e32 v7, v47, v7
	v_sub_u32_e32 v3, v3, v52
	v_add_u32_e32 v2, 0x80, v2
	v_ashrrev_i32_e32 v6, 8, v6
	v_add_u32_e32 v7, 0x80, v7
	v_add_u32_e32 v3, 0x80, v3
	v_ashrrev_i32_e32 v2, 8, v2
	v_min_i32_e32 v6, 0x7f, v6
	v_ashrrev_i32_e32 v7, 8, v7
	v_ashrrev_i32_e32 v3, 8, v3
	v_min_i32_e32 v2, 0x7f, v2
	v_min_i32_sdwa v7, v7, s69 dst_sel:WORD_1 dst_unused:UNUSED_PAD src0_sel:DWORD src1_sel:DWORD
	v_min_i32_e32 v3, 0x7f, v3
	v_lshlrev_b32_e32 v6, 8, v6
	v_and_b32_e32 v6, 0xff00, v6
	v_and_b32_e32 v7, 0xff0000, v7
	v_perm_b32 v2, v3, v2, s76
	v_or3_b32 v2, v2, v6, v7
	ds_write_b32 v12, v2 offset:128
	v_mov_b32_e32 v2, v182
	v_mov_b32_e32 v3, v183
	v_pk_add_f32 v[6:7], v[38:39], v[2:3] op_sel_hi:[1,0] neg_lo:[0,1] neg_hi:[0,1]
	s_nop 0
	v_pk_mul_f32 v[6:7], v[2:3], v[6:7] op_sel:[1,0]
	v_pk_add_f32 v[36:37], v[36:37], v[2:3] op_sel_hi:[1,0] neg_lo:[0,1] neg_hi:[0,1]
	v_pk_fma_f32 v[6:7], v[40:41], v[6:7], v[42:43]
;     ...
;         _Pragma("unroll") for (int ai = 0; ai < 2; ++ai) {
;           _Pragma("unroll") for (int bj = 0; bj < 2; ++bj) _Pragma("unroll") for (int n = 0; n < 2; ++n) {
;             const int cc = bj * HALF + wc3 * 32 + n * 16 + fq3 * 4;
;             const float4 gm = *reinterpret_cast<const float4*>(g.gam + pn * BM + cc), bt = *reinterpret_cast<const float4*>(g.bet + pn * BM + cc);
;             _Pragma("unroll") for (int m = 0; m < 4; ++m) {
;               const int rr = wr3 * 64 + m * 16 + fr3;
;               const float2 ms = *reinterpret_cast<const float2*>(mr + (ai * HALF + rr) * 2);
;               f32x4 y = acc[ai][bj][m][n];
;               const float o0 = (y[0] - ms.x) * ms.y * gm.x + bt.x, o1 = (y[1] - ms.x) * ms.y * gm.y + bt.y;
;               const float o2 = (y[2] - ms.x) * ms.y * gm.z + bt.z, o3 = (y[3] - ms.x) * ms.y * gm.w + bt.w;
;               const unsigned h0 = f2bf(o0), h1 = f2bf(o1), h2 = f2bf(o2), h3 = f2bf(o3);
;               u32x2 ob; ob[0] = h0 | (h1 << 16); ob[1] = h2 | (h3 << 16);
;               *reinterpret_cast<u32x2*>(smem + (rr >> 1) * PIECE + (rr & 1) * 512 + cc * 2) = ob;
;               const int l0 = min(((int)__float_as_uint(o0) - (int)(h0 << 16) + 128) >> 8, 127);
;               const int l1 = min(((int)__float_as_uint(o1) - (int)(h1 << 16) + 128) >> 8, 127);
;               const int l2 = min(((int)__float_as_uint(o2) - (int)(h2 << 16) + 128) >> 8, 127);
;               const int l3 = min(((int)__float_as_uint(o3) - (int)(h3 << 16) + 128) >> 8, 127);
;               *reinterpret_cast<unsigned*>(smem + LOBASE + (rr >> 2) * PIECE + (rr & 3) * 256 + cc) =
;                   (unsigned)(l0 & 255) | ((unsigned)(l1 & 255) << 8) | ((unsigned)(l2 & 255) << 16) | ((unsigned)l3 << 24);
;             }
	v_pk_mul_f32 v[2:3], v[2:3], v[36:37] op_sel:[1,0]
	v_and_b32_sdwa v36, v6, v244 dst_sel:DWORD dst_unused:UNUSED_PAD src0_sel:WORD_1 src1_sel:DWORD
	v_pk_fma_f32 v[2:3], v[0:1], v[2:3], v[4:5]
	v_add3_u32 v36, v6, v36, s67
	v_and_b32_e32 v38, 0xffff0000, v36
	v_and_b32_sdwa v36, v3, v244 dst_sel:DWORD dst_unused:UNUSED_PAD src0_sel:WORD_1 src1_sel:DWORD
	v_and_b32_sdwa v23, v7, v244 dst_sel:DWORD dst_unused:UNUSED_PAD src0_sel:WORD_1 src1_sel:DWORD
	v_and_b32_sdwa v37, v2, v244 dst_sel:DWORD dst_unused:UNUSED_PAD src0_sel:WORD_1 src1_sel:DWORD
	v_add3_u32 v36, v3, v36, s67
	v_add3_u32 v23, v7, v23, s67
	v_add3_u32 v39, v2, v37, s67
	v_and_b32_e32 v44, 0xffff0000, v36
	v_or_b32_sdwa v37, v44, v23 dst_sel:DWORD dst_unused:UNUSED_PAD src0_sel:DWORD src1_sel:WORD_1
	v_or_b32_sdwa v36, v39, v38 dst_sel:DWORD dst_unused:UNUSED_PAD src0_sel:WORD_1 src1_sel:DWORD
	ds_write_b64 v102, v[36:37]
	v_and_b32_e32 v36, 0xffff0000, v39
	v_sub_u32_e32 v6, v6, v38
	v_and_b32_e32 v23, 0xffff0000, v23
	v_sub_u32_e32 v2, v2, v36
	v_add_u32_e32 v6, 0x80, v6
	v_sub_u32_e32 v7, v7, v23
	v_sub_u32_e32 v3, v3, v44
	v_add_u32_e32 v2, 0x80, v2
	v_ashrrev_i32_e32 v6, 8, v6
	v_add_u32_e32 v7, 0x80, v7
	v_add_u32_e32 v3, 0x80, v3
	v_ashrrev_i32_e32 v2, 8, v2
	v_min_i32_e32 v6, 0x7f, v6
	v_ashrrev_i32_e32 v7, 8, v7
	v_ashrrev_i32_e32 v3, 8, v3
	v_min_i32_e32 v2, 0x7f, v2
	v_min_i32_sdwa v7, v7, s69 dst_sel:WORD_1 dst_unused:UNUSED_PAD src0_sel:DWORD src1_sel:DWORD
	v_min_i32_e32 v3, 0x7f, v3
	v_lshlrev_b32_e32 v6, 8, v6
	v_and_b32_e32 v6, 0xff00, v6
	v_and_b32_e32 v7, 0xff0000, v7
	v_perm_b32 v2, v3, v2, s76
	v_or3_b32 v2, v2, v6, v7
	ds_write_b32 v14, v2 offset:128
	v_mov_b32_e32 v2, v184
	v_mov_b32_e32 v3, v185
	v_pk_add_f32 v[6:7], v[26:27], v[2:3] op_sel_hi:[1,0] neg_lo:[0,1] neg_hi:[0,1]
	s_nop 0
	v_pk_mul_f32 v[6:7], v[2:3], v[6:7] op_sel:[1,0]
	v_pk_add_f32 v[24:25], v[24:25], v[2:3] op_sel_hi:[1,0] neg_lo:[0,1] neg_hi:[0,1]
	v_pk_fma_f32 v[6:7], v[40:41], v[6:7], v[42:43]
	v_pk_mul_f32 v[2:3], v[2:3], v[24:25] op_sel:[1,0]
	v_and_b32_sdwa v24, v6, v244 dst_sel:DWORD dst_unused:UNUSED_PAD src0_sel:WORD_1 src1_sel:DWORD
	v_pk_fma_f32 v[2:3], v[0:1], v[2:3], v[4:5]
	v_add3_u32 v24, v6, v24, s67
	v_and_b32_e32 v26, 0xffff0000, v24
	v_and_b32_sdwa v24, v3, v244 dst_sel:DWORD dst_unused:UNUSED_PAD src0_sel:WORD_1 src1_sel:DWORD
	v_and_b32_sdwa v23, v7, v244 dst_sel:DWORD dst_unused:UNUSED_PAD src0_sel:WORD_1 src1_sel:DWORD
	v_and_b32_sdwa v25, v2, v244 dst_sel:DWORD dst_unused:UNUSED_PAD src0_sel:WORD_1 src1_sel:DWORD
	v_add3_u32 v24, v3, v24, s67
	v_add3_u32 v23, v7, v23, s67
	v_add3_u32 v27, v2, v25, s67
	v_and_b32_e32 v36, 0xffff0000, v24
	v_or_b32_sdwa v25, v36, v23 dst_sel:DWORD dst_unused:UNUSED_PAD src0_sel:DWORD src1_sel:WORD_1
	v_or_b32_sdwa v24, v27, v26 dst_sel:DWORD dst_unused:UNUSED_PAD src0_sel:WORD_1 src1_sel:DWORD
	ds_write_b64 v103, v[24:25]
	v_and_b32_e32 v24, 0xffff0000, v27
	v_sub_u32_e32 v6, v6, v26
	v_and_b32_e32 v23, 0xffff0000, v23
	v_sub_u32_e32 v2, v2, v24
	v_add_u32_e32 v6, 0x80, v6
	v_sub_u32_e32 v7, v7, v23
	v_sub_u32_e32 v3, v3, v36
	v_add_u32_e32 v2, 0x80, v2
	v_ashrrev_i32_e32 v6, 8, v6
	v_add_u32_e32 v7, 0x80, v7
	v_add_u32_e32 v3, 0x80, v3
	v_ashrrev_i32_e32 v2, 8, v2
	v_min_i32_e32 v6, 0x7f, v6
	v_ashrrev_i32_e32 v7, 8, v7
	v_ashrrev_i32_e32 v3, 8, v3
	v_min_i32_e32 v2, 0x7f, v2
	v_min_i32_sdwa v7, v7, s69 dst_sel:WORD_1 dst_unused:UNUSED_PAD src0_sel:DWORD src1_sel:DWORD
	v_min_i32_e32 v3, 0x7f, v3
	v_lshlrev_b32_e32 v6, 8, v6
	v_and_b32_e32 v6, 0xff00, v6
	v_and_b32_e32 v7, 0xff0000, v7
	v_perm_b32 v2, v3, v2, s76
	v_or3_b32 v2, v2, v6, v7
	ds_write_b32 v20, v2 offset:128
	v_mov_b32_e32 v2, v186
	v_mov_b32_e32 v3, v187
	v_pk_add_f32 v[6:7], v[30:31], v[2:3] op_sel_hi:[1,0] neg_lo:[0,1] neg_hi:[0,1]
	s_nop 0
	v_pk_mul_f32 v[6:7], v[2:3], v[6:7] op_sel:[1,0]
	v_pk_add_f32 v[24:25], v[28:29], v[2:3] op_sel_hi:[1,0] neg_lo:[0,1] neg_hi:[0,1]
	v_pk_fma_f32 v[6:7], v[40:41], v[6:7], v[42:43]
	v_pk_mul_f32 v[2:3], v[2:3], v[24:25] op_sel:[1,0]
	s_nop 0
	v_pk_fma_f32 v[0:1], v[0:1], v[2:3], v[4:5]
	v_and_b32_sdwa v2, v7, v244 dst_sel:DWORD dst_unused:UNUSED_PAD src0_sel:WORD_1 src1_sel:DWORD
	v_and_b32_sdwa v3, v6, v244 dst_sel:DWORD dst_unused:UNUSED_PAD src0_sel:WORD_1 src1_sel:DWORD
	v_add3_u32 v4, v7, v2, s67
	v_add3_u32 v2, v6, v3, s67
	v_and_b32_e32 v5, 0xffff0000, v2
	v_and_b32_sdwa v2, v1, v244 dst_sel:DWORD dst_unused:UNUSED_PAD src0_sel:WORD_1 src1_sel:DWORD
	v_and_b32_sdwa v3, v0, v244 dst_sel:DWORD dst_unused:UNUSED_PAD src0_sel:WORD_1 src1_sel:DWORD
	v_add3_u32 v2, v1, v2, s67
	v_add3_u32 v23, v0, v3, s67
	v_and_b32_e32 v24, 0xffff0000, v2
	v_or_b32_sdwa v3, v24, v4 dst_sel:DWORD dst_unused:UNUSED_PAD src0_sel:DWORD src1_sel:WORD_1
	v_or_b32_sdwa v2, v23, v5 dst_sel:DWORD dst_unused:UNUSED_PAD src0_sel:WORD_1 src1_sel:DWORD
	ds_write_b64 v104, v[2:3]
	v_and_b32_e32 v2, 0xffff0000, v23
	v_sub_u32_e32 v0, v0, v2
	v_sub_u32_e32 v2, v6, v5
	v_and_b32_e32 v3, 0xffff0000, v4
	v_add_u32_e32 v2, 0x80, v2
	v_sub_u32_e32 v3, v7, v3
	v_sub_u32_e32 v1, v1, v24
	v_add_u32_e32 v0, 0x80, v0
	v_ashrrev_i32_e32 v2, 8, v2
	v_add_u32_e32 v3, 0x80, v3
	v_add_u32_e32 v1, 0x80, v1
	v_ashrrev_i32_e32 v0, 8, v0
	v_min_i32_e32 v2, 0x7f, v2
	v_ashrrev_i32_e32 v3, 8, v3
	v_ashrrev_i32_e32 v1, 8, v1
	v_min_i32_e32 v0, 0x7f, v0
	v_min_i32_sdwa v3, v3, s69 dst_sel:WORD_1 dst_unused:UNUSED_PAD src0_sel:DWORD src1_sel:DWORD
	v_min_i32_e32 v1, 0x7f, v1
	v_lshlrev_b32_e32 v2, 8, v2
	v_and_b32_e32 v2, 0xff00, v2
	v_and_b32_e32 v3, 0xff0000, v3
	v_perm_b32 v0, v1, v0, s76
	v_or3_b32 v0, v0, v2, v3
	ds_write_b32 v22, v0 offset:128
	v_mov_b32_e32 v0, v208
;     ...
;         _Pragma("unroll") for (int ai = 0; ai < 2; ++ai) {
;           _Pragma("unroll") for (int bj = 0; bj < 2; ++bj) _Pragma("unroll") for (int n = 0; n < 2; ++n) {
;             const int cc = bj * HALF + wc3 * 32 + n * 16 + fq3 * 4;
;             const float4 gm = *reinterpret_cast<const float4*>(g.gam + pn * BM + cc), bt = *reinterpret_cast<const float4*>(g.bet + pn * BM + cc);
;             _Pragma("unroll") for (int m = 0; m < 4; ++m) {
;               const int rr = wr3 * 64 + m * 16 + fr3;
;               const float2 ms = *reinterpret_cast<const float2*>(mr + (ai * HALF + rr) * 2);
;               f32x4 y = acc[ai][bj][m][n];
;               const float o0 = (y[0] - ms.x) * ms.y * gm.x + bt.x, o1 = (y[1] - ms.x) * ms.y * gm.y + bt.y;
;               const float o2 = (y[2] - ms.x) * ms.y * gm.z + bt.z, o3 = (y[3] - ms.x) * ms.y * gm.w + bt.w;
;               const unsigned h0 = f2bf(o0), h1 = f2bf(o1), h2 = f2bf(o2), h3 = f2bf(o3);
;               u32x2 ob; ob[0] = h0 | (h1 << 16); ob[1] = h2 | (h3 << 16);
;               *reinterpret_cast<u32x2*>(smem + (rr >> 1) * PIECE + (rr & 1) * 512 + cc * 2) = ob;
;               const int l0 = min(((int)__float_as_uint(o0) - (int)(h0 << 16) + 128) >> 8, 127);
;               const int l1 = min(((int)__float_as_uint(o1) - (int)(h1 << 16) + 128) >> 8, 127);
;               const int l2 = min(((int)__float_as_uint(o2) - (int)(h2 << 16) + 128) >> 8, 127);
;               const int l3 = min(((int)__float_as_uint(o3) - (int)(h3 << 16) + 128) >> 8, 127);
;               *reinterpret_cast<unsigned*>(smem + LOBASE + (rr >> 2) * PIECE + (rr & 3) * 256 + cc) =
;                   (unsigned)(l0 & 255) | ((unsigned)(l1 & 255) << 8) | ((unsigned)(l2 & 255) << 16) | ((unsigned)l3 << 24);
;             }
	v_mov_b32_e32 v1, v209
	v_mov_b32_e32 v2, v210
	v_mov_b32_e32 v3, v211
	v_mov_b32_e32 v4, v248
	v_mov_b32_e32 v5, v249
	v_mov_b32_e32 v6, v250
	v_mov_b32_e32 v7, v251
	v_mov_b32_e32 v28, v180
	v_mov_b32_e32 v29, v181
	s_lshl_b32 s4, s0, 1
	s_mov_b64 s[6:7], -1
	v_pk_add_f32 v[30:31], v[50:51], v[28:29] op_sel_hi:[1,0] neg_lo:[0,1] neg_hi:[0,1]
	s_nop 0
	v_pk_mul_f32 v[30:31], v[28:29], v[30:31] op_sel:[1,0]
	v_pk_add_f32 v[36:37], v[48:49], v[28:29] op_sel_hi:[1,0] neg_lo:[0,1] neg_hi:[0,1]
	v_mov_b32_e32 v24, v1
	v_mov_b32_e32 v25, v2
	v_mov_b32_e32 v26, v5
	v_mov_b32_e32 v27, v6
	v_pk_fma_f32 v[30:31], v[24:25], v[30:31], v[26:27]
	v_pk_mul_f32 v[28:29], v[28:29], v[36:37] op_sel:[1,0]
	v_mov_b32_e32 v1, v3
	v_mov_b32_e32 v5, v7
	v_and_b32_sdwa v6, v31, v244 dst_sel:DWORD dst_unused:UNUSED_PAD src0_sel:WORD_1 src1_sel:DWORD
	v_and_b32_sdwa v7, v30, v244 dst_sel:DWORD dst_unused:UNUSED_PAD src0_sel:WORD_1 src1_sel:DWORD
	v_pk_fma_f32 v[2:3], v[0:1], v[28:29], v[4:5]
	v_add3_u32 v23, v31, v6, s67
	v_add3_u32 v6, v30, v7, s67
	v_and_b32_e32 v28, 0xffff0000, v6
	v_and_b32_sdwa v6, v3, v244 dst_sel:DWORD dst_unused:UNUSED_PAD src0_sel:WORD_1 src1_sel:DWORD
	v_and_b32_sdwa v7, v2, v244 dst_sel:DWORD dst_unused:UNUSED_PAD src0_sel:WORD_1 src1_sel:DWORD
	v_add3_u32 v6, v3, v6, s67
	v_add3_u32 v29, v2, v7, s67
	v_and_b32_e32 v36, 0xffff0000, v6
	v_or_b32_sdwa v7, v36, v23 dst_sel:DWORD dst_unused:UNUSED_PAD src0_sel:DWORD src1_sel:WORD_1
	v_or_b32_sdwa v6, v29, v28 dst_sel:DWORD dst_unused:UNUSED_PAD src0_sel:WORD_1 src1_sel:DWORD
	ds_write_b64 v105, v[6:7]
	v_and_b32_e32 v6, 0xffff0000, v29
	v_sub_u32_e32 v2, v2, v6
	v_sub_u32_e32 v6, v30, v28
	v_and_b32_e32 v7, 0xffff0000, v23
	v_add_u32_e32 v6, 0x80, v6
	v_sub_u32_e32 v7, v31, v7
	v_sub_u32_e32 v3, v3, v36
	v_add_u32_e32 v2, 0x80, v2
	v_ashrrev_i32_e32 v6, 8, v6
	v_add_u32_e32 v7, 0x80, v7
	v_add_u32_e32 v3, 0x80, v3
	v_ashrrev_i32_e32 v2, 8, v2
	v_min_i32_e32 v6, 0x7f, v6
	v_ashrrev_i32_e32 v7, 8, v7
	v_ashrrev_i32_e32 v3, 8, v3
	v_min_i32_e32 v2, 0x7f, v2
	v_min_i32_sdwa v7, v7, s69 dst_sel:WORD_1 dst_unused:UNUSED_PAD src0_sel:DWORD src1_sel:DWORD
	v_min_i32_e32 v3, 0x7f, v3
	v_lshlrev_b32_e32 v6, 8, v6
	v_and_b32_e32 v6, 0xff00, v6
	v_and_b32_e32 v7, 0xff0000, v7
	v_perm_b32 v2, v3, v2, s76
	v_or3_b32 v2, v2, v6, v7
	ds_write_b32 v12, v2 offset:144
	v_mov_b32_e32 v2, v182
	v_mov_b32_e32 v3, v183
	v_pk_add_f32 v[6:7], v[34:35], v[2:3] op_sel_hi:[1,0] neg_lo:[0,1] neg_hi:[0,1]
	s_nop 0
	v_pk_mul_f32 v[6:7], v[2:3], v[6:7] op_sel:[1,0]
	v_pk_add_f32 v[12:13], v[32:33], v[2:3] op_sel_hi:[1,0] neg_lo:[0,1] neg_hi:[0,1]
	v_pk_fma_f32 v[6:7], v[24:25], v[6:7], v[26:27]
	v_pk_mul_f32 v[2:3], v[2:3], v[12:13] op_sel:[1,0]
	v_and_b32_sdwa v12, v7, v244 dst_sel:DWORD dst_unused:UNUSED_PAD src0_sel:WORD_1 src1_sel:DWORD
	v_and_b32_sdwa v13, v6, v244 dst_sel:DWORD dst_unused:UNUSED_PAD src0_sel:WORD_1 src1_sel:DWORD
	v_pk_fma_f32 v[2:3], v[0:1], v[2:3], v[4:5]
	v_add3_u32 v23, v7, v12, s67
	v_add3_u32 v12, v6, v13, s67
	v_and_b32_e32 v28, 0xffff0000, v12
	v_and_b32_sdwa v12, v3, v244 dst_sel:DWORD dst_unused:UNUSED_PAD src0_sel:WORD_1 src1_sel:DWORD
	v_and_b32_sdwa v13, v2, v244 dst_sel:DWORD dst_unused:UNUSED_PAD src0_sel:WORD_1 src1_sel:DWORD
	v_add3_u32 v12, v3, v12, s67
	v_add3_u32 v29, v2, v13, s67
	v_and_b32_e32 v30, 0xffff0000, v12
	v_or_b32_sdwa v13, v30, v23 dst_sel:DWORD dst_unused:UNUSED_PAD src0_sel:DWORD src1_sel:WORD_1
	v_or_b32_sdwa v12, v29, v28 dst_sel:DWORD dst_unused:UNUSED_PAD src0_sel:WORD_1 src1_sel:DWORD
	ds_write_b64 v106, v[12:13]
	v_and_b32_e32 v12, 0xffff0000, v29
	v_sub_u32_e32 v2, v2, v12
	v_sub_u32_e32 v6, v6, v28
	v_and_b32_e32 v12, 0xffff0000, v23
	v_add_u32_e32 v6, 0x80, v6
	v_sub_u32_e32 v7, v7, v12
	v_sub_u32_e32 v3, v3, v30
	v_add_u32_e32 v2, 0x80, v2
	v_ashrrev_i32_e32 v6, 8, v6
	v_add_u32_e32 v7, 0x80, v7
	v_add_u32_e32 v3, 0x80, v3
	v_ashrrev_i32_e32 v2, 8, v2
	v_min_i32_e32 v6, 0x7f, v6
	v_ashrrev_i32_e32 v7, 8, v7
	v_ashrrev_i32_e32 v3, 8, v3
	v_min_i32_e32 v2, 0x7f, v2
	v_min_i32_sdwa v7, v7, s69 dst_sel:WORD_1 dst_unused:UNUSED_PAD src0_sel:DWORD src1_sel:DWORD
	v_min_i32_e32 v3, 0x7f, v3
	v_lshlrev_b32_e32 v6, 8, v6
	v_and_b32_e32 v6, 0xff00, v6
	v_and_b32_e32 v7, 0xff0000, v7
	v_perm_b32 v2, v3, v2, s76
	v_or3_b32 v2, v2, v6, v7
	ds_write_b32 v14, v2 offset:144
	v_mov_b32_e32 v2, v184
	v_mov_b32_e32 v3, v185
	v_pk_add_f32 v[6:7], v[18:19], v[2:3] op_sel_hi:[1,0] neg_lo:[0,1] neg_hi:[0,1]
	s_nop 0
	v_pk_mul_f32 v[6:7], v[2:3], v[6:7] op_sel:[1,0]
	v_pk_add_f32 v[12:13], v[16:17], v[2:3] op_sel_hi:[1,0] neg_lo:[0,1] neg_hi:[0,1]
	v_pk_fma_f32 v[6:7], v[24:25], v[6:7], v[26:27]
	v_pk_mul_f32 v[2:3], v[2:3], v[12:13] op_sel:[1,0]
	v_and_b32_sdwa v12, v7, v244 dst_sel:DWORD dst_unused:UNUSED_PAD src0_sel:WORD_1 src1_sel:DWORD
	v_and_b32_sdwa v13, v6, v244 dst_sel:DWORD dst_unused:UNUSED_PAD src0_sel:WORD_1 src1_sel:DWORD
	v_pk_fma_f32 v[2:3], v[0:1], v[2:3], v[4:5]
	v_add3_u32 v14, v7, v12, s67
	v_add3_u32 v12, v6, v13, s67
	v_and_b32_e32 v15, 0xffff0000, v12
	v_and_b32_sdwa v12, v3, v244 dst_sel:DWORD dst_unused:UNUSED_PAD src0_sel:WORD_1 src1_sel:DWORD
	v_and_b32_sdwa v13, v2, v244 dst_sel:DWORD dst_unused:UNUSED_PAD src0_sel:WORD_1 src1_sel:DWORD
	v_add3_u32 v12, v3, v12, s67
	v_add3_u32 v16, v2, v13, s67
	v_and_b32_e32 v17, 0xffff0000, v12
	v_or_b32_sdwa v13, v17, v14 dst_sel:DWORD dst_unused:UNUSED_PAD src0_sel:DWORD src1_sel:WORD_1
	v_or_b32_sdwa v12, v16, v15 dst_sel:DWORD dst_unused:UNUSED_PAD src0_sel:WORD_1 src1_sel:DWORD
	ds_write_b64 v107, v[12:13]
	v_and_b32_e32 v12, 0xffff0000, v16
	v_sub_u32_e32 v2, v2, v12
	v_sub_u32_e32 v6, v6, v15
;     ...
;   auto issue_prologue = [&](int sA0, int sA1, int sB0, int sB1) {
;     const int tid = opaque_tid(wave);
;     int offA[2], offB[2];
;     _Pragma("unroll") for (int i = 0; i < 2; ++i) {
;       int r, c; stage_rc(tid * 16 + i * 8192, r, c);
;       offA[i] = (r * lda + c) * 2; offB[i] = (r * ldb + c) * 2;
;     }
;     STAGE(SB(0, 0), rsB, sB0, offB, 0); STAGE(SA(0, 0), rsA, sA0, offA, 0);
;     STAGE(SB(0, 1), rsB, sB1, offB, 0); STAGE(SA(0, 1), rsA, sA1, offA, 0);
;     ...
;               const float o0 = (y[0] - ms.x) * ms.y * gm.x + bt.x, o1 = (y[1] - ms.x) * ms.y * gm.y + bt.y;
;               const float o2 = (y[2] - ms.x) * ms.y * gm.z + bt.z, o3 = (y[3] - ms.x) * ms.y * gm.w + bt.w;
;               const unsigned h0 = f2bf(o0), h1 = f2bf(o1), h2 = f2bf(o2), h3 = f2bf(o3);
;               u32x2 ob; ob[0] = h0 | (h1 << 16); ob[1] = h2 | (h3 << 16);
;               *reinterpret_cast<u32x2*>(smem + (rr >> 1) * PIECE + (rr & 1) * 512 + cc * 2) = ob;
;               const int l0 = min(((int)__float_as_uint(o0) - (int)(h0 << 16) + 128) >> 8, 127);
;               const int l1 = min(((int)__float_as_uint(o1) - (int)(h1 << 16) + 128) >> 8, 127);
;               const int l2 = min(((int)__float_as_uint(o2) - (int)(h2 << 16) + 128) >> 8, 127);
;               const int l3 = min(((int)__float_as_uint(o3) - (int)(h3 << 16) + 128) >> 8, 127);
;               *reinterpret_cast<unsigned*>(smem + LOBASE + (rr >> 2) * PIECE + (rr & 3) * 256 + cc) =
;                   (unsigned)(l0 & 255) | ((unsigned)(l1 & 255) << 8) | ((unsigned)(l2 & 255) << 16) | ((unsigned)l3 << 24);
;             }
;           }
;           WAIT_L(0); BAR;
;           const int hso = ((brow + ai * HALF + 16 * wave) * DM + pn * BM) * 2;
;           const int lso = (brow + ai * HALF + 16 * wave) * DM + pn * BM;
;           _Pragma("unroll") for (int i = 0; i < 8; ++i) {
;             const u32x4 v = *reinterpret_cast<const u32x4*>(smem + (wave * 8 + i) * PIECE + lane3 * 16);
;             __builtin_amdgcn_raw_buffer_store_b128(v, rsXB, hvo + i * (2 * DM * 2), hso, 0);
;           }
;           _Pragma("unroll") for (int i = 0; i < 4; ++i) {
;             const u32x4 v = *reinterpret_cast<const u32x4*>(smem + LOBASE + (wave * 4 + i) * PIECE + lane3 * 16);
;             __builtin_amdgcn_raw_buffer_store_b128(v, rsLO, lvo + i * (4 * DM), lso, 0);
;           }
;           WAIT_L(0); BAR;
	v_and_b32_e32 v12, 0xffff0000, v14
	v_add_u32_e32 v6, 0x80, v6
	v_sub_u32_e32 v7, v7, v12
	v_sub_u32_e32 v3, v3, v17
	v_add_u32_e32 v2, 0x80, v2
	v_ashrrev_i32_e32 v6, 8, v6
	v_add_u32_e32 v7, 0x80, v7
	v_add_u32_e32 v3, 0x80, v3
	v_ashrrev_i32_e32 v2, 8, v2
	v_min_i32_e32 v6, 0x7f, v6
	v_ashrrev_i32_e32 v7, 8, v7
	v_ashrrev_i32_e32 v3, 8, v3
	v_min_i32_e32 v2, 0x7f, v2
	v_min_i32_sdwa v7, v7, s69 dst_sel:WORD_1 dst_unused:UNUSED_PAD src0_sel:DWORD src1_sel:DWORD
	v_min_i32_e32 v3, 0x7f, v3
	v_lshlrev_b32_e32 v6, 8, v6
	v_and_b32_e32 v6, 0xff00, v6
	v_and_b32_e32 v7, 0xff0000, v7
	v_perm_b32 v2, v3, v2, s76
	v_or3_b32 v2, v2, v6, v7
	ds_write_b32 v20, v2 offset:144
	v_mov_b32_e32 v2, v186
	v_mov_b32_e32 v3, v187
	v_pk_add_f32 v[6:7], v[10:11], v[2:3] op_sel_hi:[1,0] neg_lo:[0,1] neg_hi:[0,1]
	s_nop 0
	v_pk_mul_f32 v[6:7], v[2:3], v[6:7] op_sel:[1,0]
	v_pk_add_f32 v[8:9], v[8:9], v[2:3] op_sel_hi:[1,0] neg_lo:[0,1] neg_hi:[0,1]
	v_pk_fma_f32 v[6:7], v[24:25], v[6:7], v[26:27]
	v_pk_mul_f32 v[2:3], v[2:3], v[8:9] op_sel:[1,0]
	s_nop 0
	v_pk_fma_f32 v[0:1], v[0:1], v[2:3], v[4:5]
	v_and_b32_sdwa v2, v7, v244 dst_sel:DWORD dst_unused:UNUSED_PAD src0_sel:WORD_1 src1_sel:DWORD
	v_and_b32_sdwa v3, v6, v244 dst_sel:DWORD dst_unused:UNUSED_PAD src0_sel:WORD_1 src1_sel:DWORD
	v_add3_u32 v4, v7, v2, s67
	v_add3_u32 v2, v6, v3, s67
	v_and_b32_e32 v5, 0xffff0000, v2
	v_and_b32_sdwa v2, v1, v244 dst_sel:DWORD dst_unused:UNUSED_PAD src0_sel:WORD_1 src1_sel:DWORD
	v_and_b32_sdwa v3, v0, v244 dst_sel:DWORD dst_unused:UNUSED_PAD src0_sel:WORD_1 src1_sel:DWORD
	v_add3_u32 v2, v1, v2, s67
	v_add3_u32 v8, v0, v3, s67
	v_and_b32_e32 v9, 0xffff0000, v2
	v_or_b32_sdwa v3, v9, v4 dst_sel:DWORD dst_unused:UNUSED_PAD src0_sel:DWORD src1_sel:WORD_1
	v_or_b32_sdwa v2, v8, v5 dst_sel:DWORD dst_unused:UNUSED_PAD src0_sel:WORD_1 src1_sel:DWORD
	ds_write_b64 v88, v[2:3]
	v_and_b32_e32 v2, 0xffff0000, v8
	v_sub_u32_e32 v0, v0, v2
	v_sub_u32_e32 v2, v6, v5
	v_and_b32_e32 v3, 0xffff0000, v4
	v_add_u32_e32 v2, 0x80, v2
	v_sub_u32_e32 v3, v7, v3
	v_sub_u32_e32 v1, v1, v9
	v_add_u32_e32 v0, 0x80, v0
	v_ashrrev_i32_e32 v2, 8, v2
	v_add_u32_e32 v3, 0x80, v3
	v_add_u32_e32 v1, 0x80, v1
	v_ashrrev_i32_e32 v0, 8, v0
	v_min_i32_e32 v2, 0x7f, v2
	v_ashrrev_i32_e32 v3, 8, v3
	v_ashrrev_i32_e32 v1, 8, v1
	v_min_i32_e32 v0, 0x7f, v0
	v_min_i32_sdwa v3, v3, s69 dst_sel:WORD_1 dst_unused:UNUSED_PAD src0_sel:DWORD src1_sel:DWORD
	v_min_i32_e32 v1, 0x7f, v1
	v_lshlrev_b32_e32 v2, 8, v2
	v_and_b32_e32 v2, 0xff00, v2
	v_and_b32_e32 v3, 0xff0000, v3
	v_perm_b32 v0, v1, v0, s76
	v_or3_b32 v0, v0, v2, v3
	ds_write_b32 v22, v0 offset:144
	s_waitcnt lgkmcnt(0)
	s_barrier
	ds_read_b128 v[128:131], v74
	ds_read_b128 v[132:135], v74 offset:1040
	ds_read_b128 v[136:139], v74 offset:2080
	ds_read_b128 v[140:143], v74 offset:3120
	ds_read_b128 v[144:147], v74 offset:4160
	ds_read_b128 v[148:151], v74 offset:5200
	ds_read_b128 v[152:155], v74 offset:6240
	ds_read_b128 v[156:159], v74 offset:7280
	ds_read_b128 v[160:163], v69
	ds_read_b128 v[164:167], v69 offset:1040
	ds_read_b128 v[168:171], v69 offset:2080
	ds_read_b128 v[172:175], v69 offset:3120
	s_waitcnt lgkmcnt(0)
	s_barrier
	s_mov_b32 s98, s0
	s_cbranch_vccnz .Lmy_s1n_135
	v_mbcnt_lo_u32_b32 v0, -1, 0
	v_mbcnt_hi_u32_b32 v0, -1, v0
	s_mov_b32 m0, s34
	v_lshl_add_u32 v0, v0, 4, s30
	v_ashrrev_i32_e32 v1, 31, v0
	v_lshrrev_b32_e32 v1, 22, v1
	v_add_u32_e32 v1, v0, v1
	v_ashrrev_i32_e32 v1, 10, v1
	v_mul_i32_i24_e32 v2, 0x400, v1
	v_sub_u32_e32 v2, v0, v2
	v_lshrrev_b32_e32 v3, 4, v2
	v_bitop3_b32 v2, v3, v2, 32 bitop3:0x6c
	v_ashrrev_i32_e32 v4, 31, v2
	v_lshrrev_b32_e32 v4, 26, v4
	v_add_u32_e32 v4, v2, v4
	v_lshrrev_b32_e32 v5, 6, v4
	v_and_b32_e32 v4, 0xc0, v4
	v_lshlrev_b32_e32 v3, 3, v1
	v_lshlrev_b32_e32 v1, 5, v1
	v_sub_u32_e32 v2, v2, v4
	v_and_b32_e32 v3, 0x7fff0, v3
	v_and_b32_e32 v1, 32, v1
	v_ashrrev_i16_sdwa v2, v244, sext(v2) dst_sel:DWORD dst_unused:UNUSED_PAD src0_sel:DWORD src1_sel:BYTE_0
	v_add_u32_sdwa v1, v1, sext(v2) dst_sel:DWORD dst_unused:UNUSED_PAD src0_sel:DWORD src1_sel:WORD_0
	v_add_lshl_u32 v2, v5, v3, 13
	v_add_u32_e32 v0, 0x2000, v0
	v_lshl_add_u32 v1, v1, 1, v2
	v_ashrrev_i32_e32 v2, 31, v0
	v_lshrrev_b32_e32 v2, 22, v2
	v_add_u32_e32 v2, v0, v2
	v_ashrrev_i32_e32 v2, 10, v2
	v_mul_i32_i24_e32 v3, 0x400, v2
	v_sub_u32_e32 v0, v0, v3
	v_lshrrev_b32_e32 v3, 4, v0
	v_bitop3_b32 v0, v3, v0, 32 bitop3:0x6c
	v_ashrrev_i32_e32 v4, 31, v0
	v_lshrrev_b32_e32 v4, 26, v4
	v_add_u32_e32 v4, v0, v4
	v_lshrrev_b32_e32 v5, 6, v4
	v_and_b32_e32 v4, 0xffc0, v4
	v_sub_u32_e32 v0, v0, v4
	v_lshrrev_b16_e32 v4, 7, v0
	v_and_b32_e32 v4, 1, v4
	v_lshlrev_b32_e32 v3, 3, v2
	v_lshlrev_b32_e32 v2, 5, v2
	v_add_u16_e32 v0, v0, v4
	v_and_b32_e32 v3, 0x7fff0, v3
	v_and_b32_e32 v2, 32, v2
	v_ashrrev_i16_sdwa v0, v244, sext(v0) dst_sel:DWORD dst_unused:UNUSED_PAD src0_sel:DWORD src1_sel:BYTE_0
	v_add_u32_sdwa v0, v2, sext(v0) dst_sel:DWORD dst_unused:UNUSED_PAD src0_sel:DWORD src1_sel:WORD_0
	v_add_lshl_u32 v2, v5, v3, 13
	s_mov_b32 s14, s10
	s_mov_b32 s15, s11
	v_lshl_add_u32 v0, v0, 1, v2
	buffer_load_dwordx4 v1, s[12:15], s84 offen lds
	s_mov_b32 m0, s43
	s_or_b32 s0, s84, 0x80
	buffer_load_dwordx4 v0, s[12:15], s84 offen lds
	s_mov_b32 m0, s30
	s_mov_b64 s[6:7], 0
	buffer_load_dwordx4 v1, s[8:11], s83 offen lds
	s_mov_b32 m0, s44
	s_nop 0
	buffer_load_dwordx4 v0, s[8:11], s83 offen lds
	s_mov_b32 m0, s35
	s_nop 0
	buffer_load_dwordx4 v1, s[12:15], s85 offen lds
	s_mov_b32 m0, s45
	s_nop 0
	buffer_load_dwordx4 v0, s[12:15], s85 offen lds
	s_mov_b32 m0, s36
	s_nop 0
	buffer_load_dwordx4 v1, s[8:11], s82 offen lds
	s_mov_b32 m0, s48
	s_nop 0
	buffer_load_dwordx4 v0, s[8:11], s82 offen lds
	s_mov_b32 m0, s37
	s_nop 0
	buffer_load_dwordx4 v1, s[12:15], s0 offen lds
	s_mov_b32 m0, s49
	s_nop 0
	buffer_load_dwordx4 v0, s[12:15], s0 offen lds
	s_or_b32 s0, s83, 0x80
	s_mov_b32 m0, s38
	s_nop 0
	buffer_load_dwordx4 v1, s[8:11], s0 offen lds
	s_mov_b32 m0, s54
	s_nop 0
	buffer_load_dwordx4 v0, s[8:11], s0 offen lds
	s_add_i32 s0, s85, 0x80
	s_mov_b32 m0, s39
	s_nop 0
	buffer_load_dwordx4 v1, s[12:15], s0 offen lds
	s_mov_b32 m0, s55
	s_nop 0
	buffer_load_dwordx4 v0, s[12:15], s0 offen lds
	buffer_store_dwordx4 v[128:131], v70, s[16:19], s4 offen
	buffer_store_dwordx4 v[132:135], v89, s[16:19], s4 offen
	buffer_store_dwordx4 v[136:139], v90, s[16:19], s4 offen
	buffer_store_dwordx4 v[140:143], v91, s[16:19], s4 offen
	buffer_store_dwordx4 v[144:147], v108, s[16:19], s4 offen
	buffer_store_dwordx4 v[148:151], v109, s[16:19], s4 offen
	buffer_store_dwordx4 v[152:155], v110, s[16:19], s4 offen
	buffer_store_dwordx4 v[156:159], v111, s[16:19], s4 offen
	buffer_store_dwordx4 v[160:163], v68, s[20:23], s98 offen
	buffer_store_dwordx4 v[164:167], v112, s[20:23], s98 offen
	buffer_store_dwordx4 v[168:171], v113, s[20:23], s98 offen
	buffer_store_dwordx4 v[172:175], v114, s[20:23], s98 offen
	s_branch .LBB0_140

;     ...
;       const int tid3 = opaque_tid(wave);
;       const int wr3 = tid3 >> 8, wc3 = (tid3 >> 6) & 3, fr3 = tid3 & 15, fq3 = (tid3 & 63) >> 4;
;       const int ebase3 = (brow + wr3 * 64 + fr3) * DM + pn * BM + wc3 * 32 + fq3 * 4;
;       const int vo4b = ebase3 * 4, vo2 = ebase3 * 2, vo1 = ebase3;
;       (void)vo4b; (void)vo2; (void)vo1;
;       if constexpr (OUTF) {
;         _Pragma("unroll") for (int bj = 0; bj < 2; ++bj) _Pragma("unroll") for (int n = 0; n < 2; ++n) {
;           const int col = pn * BM + bj * HALF + wc3 * 32 + n * 16 + fq3 * 4;
;           const float4 gm = *reinterpret_cast<const float4*>(g.gam + col), bt = *reinterpret_cast<const float4*>(g.bet + col);
;           _Pragma("unroll") for (int ai = 0; ai < 2; ++ai) _Pragma("unroll") for (int m = 0; m < 4; ++m) {
;             const int rl = ai * HALF + wr3 * 64 + m * 16 + fr3;
;             const float2 ms = *reinterpret_cast<const float2*>(mr + rl * 2);
;             f32x4 y = acc[ai][bj][m][n];
;             u32x4 o;
;             o[0] = __float_as_uint((y[0] - ms.x) * ms.y * gm.x + bt.x); o[1] = __float_as_uint((y[1] - ms.x) * ms.y * gm.y + bt.y);
;             o[2] = __float_as_uint((y[2] - ms.x) * ms.y * gm.z + bt.z); o[3] = __float_as_uint((y[3] - ms.x) * ms.y * gm.w + bt.w);
;             __builtin_amdgcn_raw_buffer_store_b128(o, rsO, vo4b + ((ai * HALF + m * 16) * DM + bj * HALF + n * 16) * 4, 0, 0);
;           }
;         }
;       } else {
;         constexpr int PIECE = 1024 + 16, LOBASE = 64 * PIECE;
;         const int lane3 = tid3 & 63;
;         const int hvo = (lane3 >> 5) * (DM * 2) + (lane3 & 31) * 16;
;         const int lvo = (lane3 >> 4) * DM + (lane3 & 15) * 16;
;         _Pragma("unroll") for (int ai = 0; ai < 2; ++ai) {
;           _Pragma("unroll") for (int bj = 0; bj < 2; ++bj) _Pragma("unroll") for (int n = 0; n < 2; ++n) {
;             const int cc = bj * HALF + wc3 * 32 + n * 16 + fq3 * 4;
;             const float4 gm = *reinterpret_cast<const float4*>(g.gam + pn * BM + cc), bt = *reinterpret_cast<const float4*>(g.bet + pn * BM + cc);
;             _Pragma("unroll") for (int m = 0; m < 4; ++m) {
;               const int rr = wr3 * 64 + m * 16 + fr3;
;               const float2 ms = *reinterpret_cast<const float2*>(mr + (ai * HALF + rr) * 2);
;               f32x4 y = acc[ai][bj][m][n];
.LBB0_320:
	s_or_b64 exec, exec, s[6:7]
	s_waitcnt lgkmcnt(0)
	s_barrier
	v_mbcnt_lo_u32_b32 v0, -1, 0
	v_mbcnt_hi_u32_b32 v0, -1, v0
	s_movk_i32 s4, 0x60
	v_add_u32_e32 v1, s34, v0
	v_ashrrev_i32_e32 v5, 2, v1
	v_lshrrev_b32_e32 v6, 1, v1
	v_lshlrev_b32_e32 v1, 4, v1
	v_bfe_u32 v4, v0, 4, 2
	v_lshlrev_b32_e32 v12, 7, v0
	v_and_b32_e32 v13, 0x1f0, v1
	v_lshlrev_b32_e32 v7, 2, v4
	v_and_or_b32 v148, v12, s29, v13
	s_ashr_i32 s29, s28, 31
	v_and_or_b32 v12, v6, s4, v7
	s_lshl_b64 s[4:5], s[28:29], 2
	s_add_u32 s6, s86, s4
	v_and_b32_e32 v2, 15, v0
	v_and_b32_e32 v3, 63, v0
	v_and_b32_e32 v1, 0xf0, v1
	v_lshlrev_b32_e32 v13, 9, v0
	v_lshlrev_b32_e32 v0, 8, v0
	s_addc_u32 s7, s87, s5
	v_lshlrev_b32_e32 v150, 2, v12
	v_lshl_or_b32 v146, v4, 11, v1
	v_and_or_b32 v155, v5, s64, v2
	v_and_b32_e32 v14, 0x300, v0
	v_lshlrev_b32_e32 v151, 4, v3
	global_load_dwordx4 v[220:223], v150, s[6:7]
	global_load_dwordx4 v[224:227], v150, s[6:7] offset:64
	global_load_dwordx4 v[228:231], v150, s[6:7] offset:512
	global_load_dwordx4 v[232:235], v150, s[6:7] offset:576
	v_readlane_b32 s64, v255, 0
	v_readlane_b32 s65, v255, 1
	s_add_u32 s4, s64, s4
	s_addc_u32 s5, s65, s5
	global_load_dwordx4 v[236:239], v150, s[4:5]
	global_load_dwordx4 v[240:243], v150, s[4:5] offset:64
	global_load_dwordx4 v[244:247], v150, s[4:5] offset:512
	global_load_dwordx4 v[248:251], v150, s[4:5] offset:576
	s_movk_i32 s22, 0x200
	v_lshl_add_u32 v149, v155, 3, v219
	v_add_u32_e32 v147, s56, v151
	s_andn2_b64 vcc, exec, s[14:15]
	s_movk_i32 s46, 0x100
	v_readlane_b32 s66, v255, 2
	v_readlane_b32 s67, v255, 3
	v_readlane_b32 s68, v255, 4
	v_readlane_b32 s69, v255, 5
	v_readlane_b32 s70, v255, 6
	v_readlane_b32 s71, v255, 7
	v_readlane_b32 s72, v255, 8
	v_readlane_b32 s73, v255, 9
	v_readlane_b32 s74, v255, 10
	v_readlane_b32 s75, v255, 11
	v_readlane_b32 s76, v255, 12
	v_readlane_b32 s77, v255, 13
	v_readlane_b32 s78, v255, 14
	v_readlane_b32 s79, v255, 15
	s_waitcnt vmcnt(0)
	v_mov_b32_e32 v0, v220
	v_mov_b32_e32 v1, v221
	v_mov_b32_e32 v2, v222
	v_mov_b32_e32 v3, v223
	v_mov_b32_e32 v4, v236
	v_mov_b32_e32 v5, v237
	v_mov_b32_e32 v6, v238
	v_mov_b32_e32 v7, v239
	v_mov_b32_e32 v22, v1
	v_lshlrev_b32_e32 v1, 1, v12
	v_and_or_b32 v154, v13, s22, v1
	s_mov_b32 s22, 0x10400
	v_mov_b32_e32 v23, v2
	v_or3_b32 v2, v14, v12, s22
	ds_read_b64 v[12:13], v149
	v_mov_b32_e32 v144, v5
	v_mov_b32_e32 v145, v6
	v_mov_b32_e32 v1, v3
	v_mov_b32_e32 v5, v7
	s_waitcnt lgkmcnt(0)
	v_mov_b32_e32 v210, v12
	v_mov_b32_e32 v211, v13
	v_pk_add_f32 v[14:15], v[132:133], v[12:13] op_sel_hi:[1,0] neg_lo:[0,1] neg_hi:[0,1]
	v_pk_add_f32 v[18:19], v[130:131], v[12:13] op_sel_hi:[1,0] neg_lo:[0,1] neg_hi:[0,1]
	v_pk_mul_f32 v[14:15], v[12:13], v[14:15] op_sel:[1,0]
	v_pk_mul_f32 v[12:13], v[12:13], v[18:19] op_sel:[1,0]
	v_pk_fma_f32 v[14:15], v[22:23], v[14:15], v[144:145]
	v_pk_fma_f32 v[6:7], v[0:1], v[12:13], v[4:5]
	v_and_b32_sdwa v12, v14, v216 dst_sel:DWORD dst_unused:UNUSED_PAD src0_sel:WORD_1 src1_sel:DWORD
	v_add3_u32 v12, v14, v12, s84
	v_and_b32_e32 v18, 0xffff0000, v12
	v_and_b32_sdwa v12, v7, v216 dst_sel:DWORD dst_unused:UNUSED_PAD src0_sel:WORD_1 src1_sel:DWORD
	v_and_b32_sdwa v3, v15, v216 dst_sel:DWORD dst_unused:UNUSED_PAD src0_sel:WORD_1 src1_sel:DWORD
	v_and_b32_sdwa v13, v6, v216 dst_sel:DWORD dst_unused:UNUSED_PAD src0_sel:WORD_1 src1_sel:DWORD
	v_add3_u32 v12, v7, v12, s84
	v_lshrrev_b32_e32 v131, 1, v155
	v_add3_u32 v3, v15, v3, s84
	v_add3_u32 v19, v6, v13, s84
	v_and_b32_e32 v130, 0xffff0000, v12
	v_mul_lo_u32 v152, v131, s63
	v_or_b32_sdwa v13, v130, v3 dst_sel:DWORD dst_unused:UNUSED_PAD src0_sel:DWORD src1_sel:WORD_1
	v_or_b32_sdwa v12, v19, v18 dst_sel:DWORD dst_unused:UNUSED_PAD src0_sel:WORD_1 src1_sel:DWORD
	v_add_u32_e32 v132, v154, v152
	ds_write_b64 v132, v[12:13]
	v_and_b32_e32 v12, 0xffff0000, v19
	v_sub_u32_e32 v6, v6, v12
	v_sub_u32_e32 v12, v14, v18
	v_and_b32_e32 v3, 0xffff0000, v3
	v_add_u32_e32 v12, 0x80, v12
	v_sub_u32_e32 v3, v15, v3
	v_sub_u32_e32 v7, v7, v130
	v_add_u32_e32 v6, 0x80, v6
	v_ashrrev_i32_e32 v12, 8, v12
	v_add_u32_e32 v3, 0x80, v3
	v_add_u32_e32 v7, 0x80, v7
	v_ashrrev_i32_e32 v6, 8, v6
	v_min_i32_e32 v12, 0x7f, v12
	v_ashrrev_i32_e32 v3, 8, v3
	v_ashrrev_i32_e32 v7, 8, v7
	v_min_i32_e32 v6, 0x7f, v6
	v_min_i32_sdwa v3, v3, s85 dst_sel:WORD_1 dst_unused:UNUSED_PAD src0_sel:DWORD src1_sel:DWORD
	v_min_i32_e32 v7, 0x7f, v7
	v_lshlrev_b32_e32 v12, 8, v12
	v_and_b32_e32 v12, 0xff00, v12
	v_and_b32_e32 v3, 0xff0000, v3
	v_perm_b32 v6, v7, v6, s92
	v_or3_b32 v3, v6, v12, v3
	v_lshrrev_b32_e32 v6, 2, v155
	v_mad_u64_u32 v[12:13], s[22:23], v6, s63, v[2:3]
	ds_write_b32 v12, v3
	v_or_b32_e32 v3, 16, v155
	v_lshl_add_u32 v13, v3, 3, v219
	ds_read_b64 v[6:7], v13
	v_lshrrev_b32_e32 v133, 1, v3
	v_mul_lo_u32 v153, v133, s63
	v_add_u32_e32 v133, v154, v153
	v_lshrrev_b32_e32 v3, 2, v3
	s_waitcnt lgkmcnt(0)
;     ...
;         _Pragma("unroll") for (int ai = 0; ai < 2; ++ai) {
;           _Pragma("unroll") for (int bj = 0; bj < 2; ++bj) _Pragma("unroll") for (int n = 0; n < 2; ++n) {
;             const int cc = bj * HALF + wc3 * 32 + n * 16 + fq3 * 4;
;             const float4 gm = *reinterpret_cast<const float4*>(g.gam + pn * BM + cc), bt = *reinterpret_cast<const float4*>(g.bet + pn * BM + cc);
;             _Pragma("unroll") for (int m = 0; m < 4; ++m) {
;               const int rr = wr3 * 64 + m * 16 + fr3;
;               const float2 ms = *reinterpret_cast<const float2*>(mr + (ai * HALF + rr) * 2);
;               f32x4 y = acc[ai][bj][m][n];
;               const float o0 = (y[0] - ms.x) * ms.y * gm.x + bt.x, o1 = (y[1] - ms.x) * ms.y * gm.y + bt.y;
;               const float o2 = (y[2] - ms.x) * ms.y * gm.z + bt.z, o3 = (y[3] - ms.x) * ms.y * gm.w + bt.w;
;               const unsigned h0 = f2bf(o0), h1 = f2bf(o1), h2 = f2bf(o2), h3 = f2bf(o3);
;               u32x2 ob; ob[0] = h0 | (h1 << 16); ob[1] = h2 | (h3 << 16);
;               *reinterpret_cast<u32x2*>(smem + (rr >> 1) * PIECE + (rr & 1) * 512 + cc * 2) = ob;
;               const int l0 = min(((int)__float_as_uint(o0) - (int)(h0 << 16) + 128) >> 8, 127);
;               const int l1 = min(((int)__float_as_uint(o1) - (int)(h1 << 16) + 128) >> 8, 127);
;               const int l2 = min(((int)__float_as_uint(o2) - (int)(h2 << 16) + 128) >> 8, 127);
;               const int l3 = min(((int)__float_as_uint(o3) - (int)(h3 << 16) + 128) >> 8, 127);
;               *reinterpret_cast<unsigned*>(smem + LOBASE + (rr >> 2) * PIECE + (rr & 3) * 256 + cc) =
;                   (unsigned)(l0 & 255) | ((unsigned)(l1 & 255) << 8) | ((unsigned)(l2 & 255) << 16) | ((unsigned)l3 << 24);
;             }
	v_mov_b32_e32 v212, v6
	v_mov_b32_e32 v213, v7
	v_pk_add_f32 v[14:15], v[122:123], v[6:7] op_sel_hi:[1,0] neg_lo:[0,1] neg_hi:[0,1]
	v_pk_add_f32 v[18:19], v[134:135], v[6:7] op_sel_hi:[1,0] neg_lo:[0,1] neg_hi:[0,1]
	v_pk_mul_f32 v[14:15], v[6:7], v[14:15] op_sel:[1,0]
	v_pk_mul_f32 v[6:7], v[6:7], v[18:19] op_sel:[1,0]
	v_pk_fma_f32 v[14:15], v[22:23], v[14:15], v[144:145]
	v_pk_fma_f32 v[6:7], v[0:1], v[6:7], v[4:5]
	v_and_b32_sdwa v18, v15, v216 dst_sel:DWORD dst_unused:UNUSED_PAD src0_sel:WORD_1 src1_sel:DWORD
	v_and_b32_sdwa v19, v14, v216 dst_sel:DWORD dst_unused:UNUSED_PAD src0_sel:WORD_1 src1_sel:DWORD
	v_add3_u32 v122, v15, v18, s84
	v_add3_u32 v18, v14, v19, s84
	v_and_b32_e32 v123, 0xffff0000, v18
	v_and_b32_sdwa v18, v7, v216 dst_sel:DWORD dst_unused:UNUSED_PAD src0_sel:WORD_1 src1_sel:DWORD
	v_and_b32_sdwa v19, v6, v216 dst_sel:DWORD dst_unused:UNUSED_PAD src0_sel:WORD_1 src1_sel:DWORD
	v_add3_u32 v18, v7, v18, s84
	v_add3_u32 v130, v6, v19, s84
	v_and_b32_e32 v131, 0xffff0000, v18
	v_or_b32_sdwa v19, v131, v122 dst_sel:DWORD dst_unused:UNUSED_PAD src0_sel:DWORD src1_sel:WORD_1
	v_or_b32_sdwa v18, v130, v123 dst_sel:DWORD dst_unused:UNUSED_PAD src0_sel:WORD_1 src1_sel:DWORD
	ds_write_b64 v133, v[18:19]
	v_and_b32_e32 v18, 0xffff0000, v130
	v_sub_u32_e32 v6, v6, v18
	v_sub_u32_e32 v14, v14, v123
	v_and_b32_e32 v18, 0xffff0000, v122
	v_add_u32_e32 v14, 0x80, v14
	v_sub_u32_e32 v15, v15, v18
	v_sub_u32_e32 v7, v7, v131
	v_add_u32_e32 v6, 0x80, v6
	v_ashrrev_i32_e32 v14, 8, v14
	v_add_u32_e32 v15, 0x80, v15
	v_add_u32_e32 v7, 0x80, v7
	v_ashrrev_i32_e32 v6, 8, v6
	v_min_i32_e32 v14, 0x7f, v14
	v_ashrrev_i32_e32 v15, 8, v15
	v_ashrrev_i32_e32 v7, 8, v7
	v_min_i32_e32 v6, 0x7f, v6
	v_min_i32_sdwa v15, v15, s85 dst_sel:WORD_1 dst_unused:UNUSED_PAD src0_sel:DWORD src1_sel:DWORD
	v_min_i32_e32 v7, 0x7f, v7
	v_lshlrev_b32_e32 v14, 8, v14
	v_and_b32_e32 v14, 0xff00, v14
	v_and_b32_e32 v15, 0xff0000, v15
	v_perm_b32 v6, v7, v6, s92
	v_or3_b32 v6, v6, v14, v15
	v_mad_u64_u32 v[14:15], s[22:23], v3, s63, v[2:3]
	v_or_b32_e32 v3, 32, v155
	ds_write_b32 v14, v6
	v_lshl_add_u32 v15, v3, 3, v219
	ds_read_b64 v[6:7], v15
	v_lshrrev_b32_e32 v134, 1, v3
	v_lshrrev_b32_e32 v3, 2, v3
	s_waitcnt lgkmcnt(0)
	v_mov_b32_e32 v214, v6
	v_mov_b32_e32 v215, v7
	v_pk_add_f32 v[18:19], v[136:137], v[6:7] op_sel_hi:[1,0] neg_lo:[0,1] neg_hi:[0,1]
	s_nop 0
	v_pk_mul_f32 v[18:19], v[6:7], v[18:19] op_sel:[1,0]
	v_pk_add_f32 v[122:123], v[138:139], v[6:7] op_sel_hi:[1,0] neg_lo:[0,1] neg_hi:[0,1]
	v_pk_fma_f32 v[18:19], v[22:23], v[18:19], v[144:145]
	v_pk_mul_f32 v[6:7], v[6:7], v[122:123] op_sel:[1,0]
	v_and_b32_sdwa v122, v19, v216 dst_sel:DWORD dst_unused:UNUSED_PAD src0_sel:WORD_1 src1_sel:DWORD
	v_and_b32_sdwa v123, v18, v216 dst_sel:DWORD dst_unused:UNUSED_PAD src0_sel:WORD_1 src1_sel:DWORD
	v_pk_fma_f32 v[6:7], v[0:1], v[6:7], v[4:5]
	v_add3_u32 v130, v19, v122, s84
	v_add3_u32 v122, v18, v123, s84
	v_and_b32_e32 v131, 0xffff0000, v122
	v_and_b32_sdwa v122, v7, v216 dst_sel:DWORD dst_unused:UNUSED_PAD src0_sel:WORD_1 src1_sel:DWORD
	v_and_b32_sdwa v123, v6, v216 dst_sel:DWORD dst_unused:UNUSED_PAD src0_sel:WORD_1 src1_sel:DWORD
	v_add3_u32 v122, v7, v122, s84
	v_add3_u32 v135, v6, v123, s84
	v_and_b32_e32 v136, 0xffff0000, v122
	v_mul_lo_u32 v137, v134, s63
	v_or_b32_sdwa v123, v136, v130 dst_sel:DWORD dst_unused:UNUSED_PAD src0_sel:DWORD src1_sel:WORD_1
	v_or_b32_sdwa v122, v135, v131 dst_sel:DWORD dst_unused:UNUSED_PAD src0_sel:WORD_1 src1_sel:DWORD
	v_add_u32_e32 v134, v154, v137
	ds_write_b64 v134, v[122:123]
	v_and_b32_e32 v122, 0xffff0000, v135
	v_sub_u32_e32 v6, v6, v122
	v_sub_u32_e32 v18, v18, v131
	v_and_b32_e32 v122, 0xffff0000, v130
	v_add_u32_e32 v18, 0x80, v18
	v_sub_u32_e32 v19, v19, v122
	v_sub_u32_e32 v7, v7, v136
	v_add_u32_e32 v6, 0x80, v6
	v_ashrrev_i32_e32 v18, 8, v18
	v_add_u32_e32 v19, 0x80, v19
	v_add_u32_e32 v7, 0x80, v7
	v_ashrrev_i32_e32 v6, 8, v6
	v_min_i32_e32 v18, 0x7f, v18
	v_ashrrev_i32_e32 v19, 8, v19
	v_ashrrev_i32_e32 v7, 8, v7
	v_min_i32_e32 v6, 0x7f, v6
	v_min_i32_sdwa v19, v19, s85 dst_sel:WORD_1 dst_unused:UNUSED_PAD src0_sel:DWORD src1_sel:DWORD
	v_min_i32_e32 v7, 0x7f, v7
	v_lshlrev_b32_e32 v18, 8, v18
	v_and_b32_e32 v18, 0xff00, v18
	v_and_b32_e32 v19, 0xff0000, v19
	v_perm_b32 v6, v7, v6, s92
	v_or3_b32 v6, v6, v18, v19
	v_mad_u64_u32 v[18:19], s[22:23], v3, s63, v[2:3]
	v_or_b32_e32 v3, 48, v155
	ds_write_b32 v18, v6
	v_lshl_add_u32 v19, v3, 3, v219
	ds_read_b64 v[6:7], v19
	v_lshrrev_b32_e32 v130, 1, v3
	v_mul_lo_u32 v136, v130, s63
	v_add_u32_e32 v135, v154, v136
	s_waitcnt lgkmcnt(0)
;     ...
;         _Pragma("unroll") for (int ai = 0; ai < 2; ++ai) {
;           _Pragma("unroll") for (int bj = 0; bj < 2; ++bj) _Pragma("unroll") for (int n = 0; n < 2; ++n) {
;             const int cc = bj * HALF + wc3 * 32 + n * 16 + fq3 * 4;
;             const float4 gm = *reinterpret_cast<const float4*>(g.gam + pn * BM + cc), bt = *reinterpret_cast<const float4*>(g.bet + pn * BM + cc);
;             _Pragma("unroll") for (int m = 0; m < 4; ++m) {
;               const int rr = wr3 * 64 + m * 16 + fr3;
;               const float2 ms = *reinterpret_cast<const float2*>(mr + (ai * HALF + rr) * 2);
;               f32x4 y = acc[ai][bj][m][n];
;               const float o0 = (y[0] - ms.x) * ms.y * gm.x + bt.x, o1 = (y[1] - ms.x) * ms.y * gm.y + bt.y;
;               const float o2 = (y[2] - ms.x) * ms.y * gm.z + bt.z, o3 = (y[3] - ms.x) * ms.y * gm.w + bt.w;
;               const unsigned h0 = f2bf(o0), h1 = f2bf(o1), h2 = f2bf(o2), h3 = f2bf(o3);
;               u32x2 ob; ob[0] = h0 | (h1 << 16); ob[1] = h2 | (h3 << 16);
;               *reinterpret_cast<u32x2*>(smem + (rr >> 1) * PIECE + (rr & 1) * 512 + cc * 2) = ob;
;               const int l0 = min(((int)__float_as_uint(o0) - (int)(h0 << 16) + 128) >> 8, 127);
;               const int l1 = min(((int)__float_as_uint(o1) - (int)(h1 << 16) + 128) >> 8, 127);
;               const int l2 = min(((int)__float_as_uint(o2) - (int)(h2 << 16) + 128) >> 8, 127);
;               const int l3 = min(((int)__float_as_uint(o3) - (int)(h3 << 16) + 128) >> 8, 127);
;               *reinterpret_cast<unsigned*>(smem + LOBASE + (rr >> 2) * PIECE + (rr & 3) * 256 + cc) =
;                   (unsigned)(l0 & 255) | ((unsigned)(l1 & 255) << 8) | ((unsigned)(l2 & 255) << 16) | ((unsigned)l3 << 24);
;             }
	v_mov_b32_e32 v252, v6
	v_mov_b32_e32 v253, v7
	v_pk_add_f32 v[122:123], v[140:141], v[6:7] op_sel_hi:[1,0] neg_lo:[0,1] neg_hi:[0,1]
	s_nop 0
	v_pk_mul_f32 v[122:123], v[6:7], v[122:123] op_sel:[1,0]
	s_nop 0
	v_pk_fma_f32 v[22:23], v[22:23], v[122:123], v[144:145]
	v_pk_add_f32 v[122:123], v[142:143], v[6:7] op_sel_hi:[1,0] neg_lo:[0,1] neg_hi:[0,1]
	s_nop 0
	v_pk_mul_f32 v[6:7], v[6:7], v[122:123] op_sel:[1,0]
	s_nop 0
	v_pk_fma_f32 v[0:1], v[0:1], v[6:7], v[4:5]
	v_and_b32_sdwa v4, v23, v216 dst_sel:DWORD dst_unused:UNUSED_PAD src0_sel:WORD_1 src1_sel:DWORD
	v_and_b32_sdwa v5, v22, v216 dst_sel:DWORD dst_unused:UNUSED_PAD src0_sel:WORD_1 src1_sel:DWORD
	v_add3_u32 v6, v23, v4, s84
	v_add3_u32 v4, v22, v5, s84
	v_and_b32_e32 v7, 0xffff0000, v4
	v_and_b32_sdwa v4, v1, v216 dst_sel:DWORD dst_unused:UNUSED_PAD src0_sel:WORD_1 src1_sel:DWORD
	v_and_b32_sdwa v5, v0, v216 dst_sel:DWORD dst_unused:UNUSED_PAD src0_sel:WORD_1 src1_sel:DWORD
	v_add3_u32 v4, v1, v4, s84
	v_add3_u32 v122, v0, v5, s84
	v_and_b32_e32 v123, 0xffff0000, v4
	v_or_b32_sdwa v5, v123, v6 dst_sel:DWORD dst_unused:UNUSED_PAD src0_sel:DWORD src1_sel:WORD_1
	v_or_b32_sdwa v4, v122, v7 dst_sel:DWORD dst_unused:UNUSED_PAD src0_sel:WORD_1 src1_sel:DWORD
	ds_write_b64 v135, v[4:5]
	v_and_b32_e32 v4, 0xffff0000, v122
	v_sub_u32_e32 v0, v0, v4
	v_sub_u32_e32 v4, v22, v7
	v_and_b32_e32 v5, 0xffff0000, v6
	v_add_u32_e32 v4, 0x80, v4
	v_sub_u32_e32 v5, v23, v5
	v_sub_u32_e32 v1, v1, v123
	v_add_u32_e32 v0, 0x80, v0
	v_ashrrev_i32_e32 v4, 8, v4
	v_add_u32_e32 v5, 0x80, v5
	v_add_u32_e32 v1, 0x80, v1
	v_ashrrev_i32_e32 v0, 8, v0
	v_min_i32_e32 v4, 0x7f, v4
	v_ashrrev_i32_e32 v5, 8, v5
	v_ashrrev_i32_e32 v1, 8, v1
	v_min_i32_e32 v0, 0x7f, v0
	v_min_i32_sdwa v5, v5, s85 dst_sel:WORD_1 dst_unused:UNUSED_PAD src0_sel:DWORD src1_sel:DWORD
	v_min_i32_e32 v1, 0x7f, v1
	v_lshlrev_b32_e32 v4, 8, v4
	v_and_b32_e32 v4, 0xff00, v4
	v_and_b32_e32 v5, 0xff0000, v5
	v_perm_b32 v0, v1, v0, s92
	v_lshrrev_b32_e32 v1, 2, v3
	v_or3_b32 v0, v0, v4, v5
	v_mad_u64_u32 v[22:23], s[22:23], v1, s63, v[2:3]
	ds_write_b32 v22, v0
	v_mov_b32_e32 v0, v224
	v_mov_b32_e32 v1, v225
	v_mov_b32_e32 v2, v226
	v_mov_b32_e32 v3, v227
	v_mov_b32_e32 v4, v240
	v_mov_b32_e32 v5, v241
	v_mov_b32_e32 v6, v242
	v_mov_b32_e32 v7, v243
	v_mov_b32_e32 v138, v210
	v_mov_b32_e32 v139, v211
	s_mov_b32 s22, s18
	s_mov_b32 s23, s19
	v_pk_add_f32 v[128:129], v[128:129], v[138:139] op_sel_hi:[1,0] neg_lo:[0,1] neg_hi:[0,1]
	s_nop 0
	v_pk_mul_f32 v[128:129], v[138:139], v[128:129] op_sel:[1,0]
	v_pk_add_f32 v[126:127], v[126:127], v[138:139] op_sel_hi:[1,0] neg_lo:[0,1] neg_hi:[0,1]
	v_mov_b32_e32 v122, v1
	v_mov_b32_e32 v123, v2
	v_mov_b32_e32 v130, v5
	v_mov_b32_e32 v131, v6
	v_pk_fma_f32 v[128:129], v[122:123], v[128:129], v[130:131]
	v_pk_mul_f32 v[126:127], v[138:139], v[126:127] op_sel:[1,0]
	v_mov_b32_e32 v1, v3
	v_mov_b32_e32 v5, v7
	v_and_b32_sdwa v23, v128, v216 dst_sel:DWORD dst_unused:UNUSED_PAD src0_sel:WORD_1 src1_sel:DWORD
	v_pk_fma_f32 v[6:7], v[0:1], v[126:127], v[4:5]
	v_add3_u32 v23, v128, v23, s84
	v_and_b32_e32 v138, 0xffff0000, v23
	v_and_b32_sdwa v23, v7, v216 dst_sel:DWORD dst_unused:UNUSED_PAD src0_sel:WORD_1 src1_sel:DWORD
	v_and_b32_sdwa v3, v129, v216 dst_sel:DWORD dst_unused:UNUSED_PAD src0_sel:WORD_1 src1_sel:DWORD
	v_and_b32_sdwa v126, v6, v216 dst_sel:DWORD dst_unused:UNUSED_PAD src0_sel:WORD_1 src1_sel:DWORD
	v_add3_u32 v23, v7, v23, s84
	v_or_b32_e32 v2, 32, v154
	v_add3_u32 v3, v129, v3, s84
	v_add3_u32 v139, v6, v126, s84
	v_and_b32_e32 v140, 0xffff0000, v23
	v_or_b32_sdwa v127, v140, v3 dst_sel:DWORD dst_unused:UNUSED_PAD src0_sel:DWORD src1_sel:WORD_1
	v_or_b32_sdwa v126, v139, v138 dst_sel:DWORD dst_unused:UNUSED_PAD src0_sel:WORD_1 src1_sel:DWORD
	v_add_u32_e32 v23, v2, v152
	ds_write_b64 v23, v[126:127]
	v_and_b32_e32 v126, 0xffff0000, v139
	v_sub_u32_e32 v6, v6, v126
	v_sub_u32_e32 v126, v128, v138
	v_and_b32_e32 v3, 0xffff0000, v3
	v_add_u32_e32 v126, 0x80, v126
	v_sub_u32_e32 v3, v129, v3
	v_sub_u32_e32 v7, v7, v140
	v_add_u32_e32 v6, 0x80, v6
	v_ashrrev_i32_e32 v126, 8, v126
	v_add_u32_e32 v3, 0x80, v3
	v_add_u32_e32 v7, 0x80, v7
	v_ashrrev_i32_e32 v6, 8, v6
	v_min_i32_e32 v126, 0x7f, v126
	v_ashrrev_i32_e32 v3, 8, v3
	v_ashrrev_i32_e32 v7, 8, v7
	v_min_i32_e32 v6, 0x7f, v6
	v_min_i32_sdwa v3, v3, s85 dst_sel:WORD_1 dst_unused:UNUSED_PAD src0_sel:DWORD src1_sel:DWORD
	v_min_i32_e32 v7, 0x7f, v7
	v_lshlrev_b32_e32 v126, 8, v126
	v_and_b32_e32 v126, 0xff00, v126
	v_and_b32_e32 v3, 0xff0000, v3
	v_perm_b32 v6, v7, v6, s92
	v_or3_b32 v3, v6, v126, v3
	ds_write_b32 v12, v3 offset:16
	v_mov_b32_e32 v6, v212
	v_mov_b32_e32 v7, v213
	v_pk_add_f32 v[108:109], v[108:109], v[6:7] op_sel_hi:[1,0] neg_lo:[0,1] neg_hi:[0,1]
	s_nop 0
	v_pk_mul_f32 v[108:109], v[6:7], v[108:109] op_sel:[1,0]
	s_nop 0
	v_pk_fma_f32 v[126:127], v[122:123], v[108:109], v[130:131]
	v_pk_add_f32 v[108:109], v[110:111], v[6:7] op_sel_hi:[1,0] neg_lo:[0,1] neg_hi:[0,1]
	v_and_b32_sdwa v3, v127, v216 dst_sel:DWORD dst_unused:UNUSED_PAD src0_sel:WORD_1 src1_sel:DWORD
	v_pk_mul_f32 v[6:7], v[6:7], v[108:109] op_sel:[1,0]
	v_and_b32_sdwa v108, v126, v216 dst_sel:DWORD dst_unused:UNUSED_PAD src0_sel:WORD_1 src1_sel:DWORD
	v_pk_fma_f32 v[6:7], v[0:1], v[6:7], v[4:5]
	v_add3_u32 v108, v126, v108, s84
	v_and_b32_e32 v109, 0xffff0000, v108
	v_and_b32_sdwa v108, v7, v216 dst_sel:DWORD dst_unused:UNUSED_PAD src0_sel:WORD_1 src1_sel:DWORD
	v_and_b32_sdwa v110, v6, v216 dst_sel:DWORD dst_unused:UNUSED_PAD src0_sel:WORD_1 src1_sel:DWORD
	v_add3_u32 v108, v7, v108, s84
	v_add3_u32 v3, v127, v3, s84
	v_add3_u32 v128, v6, v110, s84
;     ...
;         _Pragma("unroll") for (int ai = 0; ai < 2; ++ai) {
;           _Pragma("unroll") for (int bj = 0; bj < 2; ++bj) _Pragma("unroll") for (int n = 0; n < 2; ++n) {
;             const int cc = bj * HALF + wc3 * 32 + n * 16 + fq3 * 4;
;             const float4 gm = *reinterpret_cast<const float4*>(g.gam + pn * BM + cc), bt = *reinterpret_cast<const float4*>(g.bet + pn * BM + cc);
;             _Pragma("unroll") for (int m = 0; m < 4; ++m) {
;               const int rr = wr3 * 64 + m * 16 + fr3;
;               const float2 ms = *reinterpret_cast<const float2*>(mr + (ai * HALF + rr) * 2);
;               f32x4 y = acc[ai][bj][m][n];
;               const float o0 = (y[0] - ms.x) * ms.y * gm.x + bt.x, o1 = (y[1] - ms.x) * ms.y * gm.y + bt.y;
;               const float o2 = (y[2] - ms.x) * ms.y * gm.z + bt.z, o3 = (y[3] - ms.x) * ms.y * gm.w + bt.w;
;               const unsigned h0 = f2bf(o0), h1 = f2bf(o1), h2 = f2bf(o2), h3 = f2bf(o3);
;               u32x2 ob; ob[0] = h0 | (h1 << 16); ob[1] = h2 | (h3 << 16);
;               *reinterpret_cast<u32x2*>(smem + (rr >> 1) * PIECE + (rr & 1) * 512 + cc * 2) = ob;
;               const int l0 = min(((int)__float_as_uint(o0) - (int)(h0 << 16) + 128) >> 8, 127);
;               const int l1 = min(((int)__float_as_uint(o1) - (int)(h1 << 16) + 128) >> 8, 127);
;               const int l2 = min(((int)__float_as_uint(o2) - (int)(h2 << 16) + 128) >> 8, 127);
;               const int l3 = min(((int)__float_as_uint(o3) - (int)(h3 << 16) + 128) >> 8, 127);
;               *reinterpret_cast<unsigned*>(smem + LOBASE + (rr >> 2) * PIECE + (rr & 3) * 256 + cc) =
;                   (unsigned)(l0 & 255) | ((unsigned)(l1 & 255) << 8) | ((unsigned)(l2 & 255) << 16) | ((unsigned)l3 << 24);
;             }
	v_and_b32_e32 v129, 0xffff0000, v108
	v_or_b32_sdwa v111, v129, v3 dst_sel:DWORD dst_unused:UNUSED_PAD src0_sel:DWORD src1_sel:WORD_1
	v_or_b32_sdwa v110, v128, v109 dst_sel:DWORD dst_unused:UNUSED_PAD src0_sel:WORD_1 src1_sel:DWORD
	v_add_u32_e32 v108, v2, v153
	ds_write_b64 v108, v[110:111]
	v_and_b32_e32 v110, 0xffff0000, v128
	v_sub_u32_e32 v109, v126, v109
	v_and_b32_e32 v3, 0xffff0000, v3
	v_sub_u32_e32 v6, v6, v110
	v_add_u32_e32 v109, 0x80, v109
	v_sub_u32_e32 v3, v127, v3
	v_sub_u32_e32 v7, v7, v129
	v_add_u32_e32 v6, 0x80, v6
	v_ashrrev_i32_e32 v109, 8, v109
	v_add_u32_e32 v3, 0x80, v3
	v_add_u32_e32 v7, 0x80, v7
	v_ashrrev_i32_e32 v6, 8, v6
	v_min_i32_e32 v109, 0x7f, v109
	v_ashrrev_i32_e32 v3, 8, v3
	v_ashrrev_i32_e32 v7, 8, v7
	v_min_i32_e32 v6, 0x7f, v6
	v_min_i32_sdwa v3, v3, s85 dst_sel:WORD_1 dst_unused:UNUSED_PAD src0_sel:DWORD src1_sel:DWORD
	v_min_i32_e32 v7, 0x7f, v7
	v_lshlrev_b32_e32 v109, 8, v109
	v_and_b32_e32 v109, 0xff00, v109
	v_and_b32_e32 v3, 0xff0000, v3
	v_perm_b32 v6, v7, v6, s92
	v_or3_b32 v3, v6, v109, v3
	ds_write_b32 v14, v3 offset:16
	v_mov_b32_e32 v6, v214
	v_mov_b32_e32 v7, v215
	v_pk_add_f32 v[98:99], v[98:99], v[6:7] op_sel_hi:[1,0] neg_lo:[0,1] neg_hi:[0,1]
	s_nop 0
	v_pk_mul_f32 v[98:99], v[6:7], v[98:99] op_sel:[1,0]
	s_nop 0
	v_pk_fma_f32 v[110:111], v[122:123], v[98:99], v[130:131]
	v_pk_add_f32 v[98:99], v[106:107], v[6:7] op_sel_hi:[1,0] neg_lo:[0,1] neg_hi:[0,1]
	v_and_b32_sdwa v3, v111, v216 dst_sel:DWORD dst_unused:UNUSED_PAD src0_sel:WORD_1 src1_sel:DWORD
	v_pk_mul_f32 v[6:7], v[6:7], v[98:99] op_sel:[1,0]
	v_and_b32_sdwa v98, v110, v216 dst_sel:DWORD dst_unused:UNUSED_PAD src0_sel:WORD_1 src1_sel:DWORD
	v_pk_fma_f32 v[6:7], v[0:1], v[6:7], v[4:5]
	v_add3_u32 v98, v110, v98, s84
	v_and_b32_e32 v99, 0xffff0000, v98
	v_and_b32_sdwa v98, v7, v216 dst_sel:DWORD dst_unused:UNUSED_PAD src0_sel:WORD_1 src1_sel:DWORD
	v_and_b32_sdwa v106, v6, v216 dst_sel:DWORD dst_unused:UNUSED_PAD src0_sel:WORD_1 src1_sel:DWORD
	v_add3_u32 v98, v7, v98, s84
	v_add3_u32 v3, v111, v3, s84
	v_add3_u32 v109, v6, v106, s84
	v_and_b32_e32 v126, 0xffff0000, v98
	v_or_b32_sdwa v107, v126, v3 dst_sel:DWORD dst_unused:UNUSED_PAD src0_sel:DWORD src1_sel:WORD_1
	v_or_b32_sdwa v106, v109, v99 dst_sel:DWORD dst_unused:UNUSED_PAD src0_sel:WORD_1 src1_sel:DWORD
	v_add_u32_e32 v98, v2, v137
	ds_write_b64 v98, v[106:107]
	v_and_b32_e32 v106, 0xffff0000, v109
	v_sub_u32_e32 v99, v110, v99
	v_and_b32_e32 v3, 0xffff0000, v3
	v_sub_u32_e32 v6, v6, v106
	v_add_u32_e32 v99, 0x80, v99
	v_sub_u32_e32 v3, v111, v3
	v_sub_u32_e32 v7, v7, v126
	v_add_u32_e32 v6, 0x80, v6
	v_ashrrev_i32_e32 v99, 8, v99
	v_add_u32_e32 v3, 0x80, v3
	v_add_u32_e32 v7, 0x80, v7
	v_ashrrev_i32_e32 v6, 8, v6
	v_min_i32_e32 v99, 0x7f, v99
	v_ashrrev_i32_e32 v3, 8, v3
	v_ashrrev_i32_e32 v7, 8, v7
	v_min_i32_e32 v6, 0x7f, v6
	v_min_i32_sdwa v3, v3, s85 dst_sel:WORD_1 dst_unused:UNUSED_PAD src0_sel:DWORD src1_sel:DWORD
	v_min_i32_e32 v7, 0x7f, v7
	v_lshlrev_b32_e32 v99, 8, v99
	v_and_b32_e32 v99, 0xff00, v99
	v_and_b32_e32 v3, 0xff0000, v3
	v_perm_b32 v6, v7, v6, s92
	v_or3_b32 v3, v6, v99, v3
	ds_write_b32 v18, v3 offset:16
	v_mov_b32_e32 v6, v252
	v_mov_b32_e32 v7, v253
	v_add_u32_e32 v99, v2, v136
	v_pk_add_f32 v[106:107], v[114:115], v[6:7] op_sel_hi:[1,0] neg_lo:[0,1] neg_hi:[0,1]
	s_nop 0
	v_pk_mul_f32 v[106:107], v[6:7], v[106:107] op_sel:[1,0]
	v_pk_add_f32 v[110:111], v[120:121], v[6:7] op_sel_hi:[1,0] neg_lo:[0,1] neg_hi:[0,1]
	v_pk_fma_f32 v[106:107], v[122:123], v[106:107], v[130:131]
	v_pk_mul_f32 v[6:7], v[6:7], v[110:111] op_sel:[1,0]
	v_and_b32_sdwa v3, v107, v216 dst_sel:DWORD dst_unused:UNUSED_PAD src0_sel:WORD_1 src1_sel:DWORD
	v_pk_fma_f32 v[0:1], v[0:1], v[6:7], v[4:5]
	v_and_b32_sdwa v4, v106, v216 dst_sel:DWORD dst_unused:UNUSED_PAD src0_sel:WORD_1 src1_sel:DWORD
	v_add3_u32 v4, v106, v4, s84
	v_and_b32_e32 v6, 0xffff0000, v4
	v_and_b32_sdwa v4, v1, v216 dst_sel:DWORD dst_unused:UNUSED_PAD src0_sel:WORD_1 src1_sel:DWORD
	v_and_b32_sdwa v5, v0, v216 dst_sel:DWORD dst_unused:UNUSED_PAD src0_sel:WORD_1 src1_sel:DWORD
	v_add3_u32 v4, v1, v4, s84
	v_add3_u32 v7, v0, v5, s84
	v_add3_u32 v3, v107, v3, s84
	v_and_b32_e32 v109, 0xffff0000, v4
	v_and_b32_e32 v2, 0xffff0000, v7
	v_or_b32_sdwa v5, v109, v3 dst_sel:DWORD dst_unused:UNUSED_PAD src0_sel:DWORD src1_sel:WORD_1
	v_sub_u32_e32 v0, v0, v2
	v_sub_u32_e32 v2, v106, v6
	v_and_b32_e32 v3, 0xffff0000, v3
	v_add_u32_e32 v2, 0x80, v2
	v_sub_u32_e32 v3, v107, v3
	v_sub_u32_e32 v1, v1, v109
	v_add_u32_e32 v0, 0x80, v0
	v_ashrrev_i32_e32 v2, 8, v2
	v_add_u32_e32 v3, 0x80, v3
	v_add_u32_e32 v1, 0x80, v1
	v_ashrrev_i32_e32 v0, 8, v0
	v_min_i32_e32 v2, 0x7f, v2
	v_ashrrev_i32_e32 v3, 8, v3
	v_ashrrev_i32_e32 v1, 8, v1
	v_min_i32_e32 v0, 0x7f, v0
	v_min_i32_sdwa v3, v3, s85 dst_sel:WORD_1 dst_unused:UNUSED_PAD src0_sel:DWORD src1_sel:DWORD
	v_min_i32_e32 v1, 0x7f, v1
	v_lshlrev_b32_e32 v2, 8, v2
	v_and_b32_e32 v2, 0xff00, v2
	v_and_b32_e32 v3, 0xff0000, v3
	v_perm_b32 v0, v1, v0, s92
	v_or_b32_sdwa v4, v7, v6 dst_sel:DWORD dst_unused:UNUSED_PAD src0_sel:WORD_1 src1_sel:DWORD
	v_or3_b32 v0, v0, v2, v3
	ds_write_b64 v99, v[4:5]
	ds_write_b32 v22, v0 offset:16
	v_mov_b32_e32 v0, v228
	v_mov_b32_e32 v1, v229
	v_mov_b32_e32 v2, v230
	v_mov_b32_e32 v3, v231
	v_mov_b32_e32 v4, v244
	v_mov_b32_e32 v5, v245
	v_mov_b32_e32 v6, v246
	v_mov_b32_e32 v7, v247
	v_mov_b32_e32 v106, v210
	v_mov_b32_e32 v107, v211
	v_or_b32_e32 v109, 0x100, v154
	v_pk_add_f32 v[120:121], v[124:125], v[106:107] op_sel_hi:[1,0] neg_lo:[0,1] neg_hi:[0,1]
	s_nop 0
	v_pk_mul_f32 v[120:121], v[106:107], v[120:121] op_sel:[1,0]
;     ...
;         _Pragma("unroll") for (int ai = 0; ai < 2; ++ai) {
;           _Pragma("unroll") for (int bj = 0; bj < 2; ++bj) _Pragma("unroll") for (int n = 0; n < 2; ++n) {
;             const int cc = bj * HALF + wc3 * 32 + n * 16 + fq3 * 4;
;             const float4 gm = *reinterpret_cast<const float4*>(g.gam + pn * BM + cc), bt = *reinterpret_cast<const float4*>(g.bet + pn * BM + cc);
;             _Pragma("unroll") for (int m = 0; m < 4; ++m) {
;               const int rr = wr3 * 64 + m * 16 + fr3;
;               const float2 ms = *reinterpret_cast<const float2*>(mr + (ai * HALF + rr) * 2);
;               f32x4 y = acc[ai][bj][m][n];
;               const float o0 = (y[0] - ms.x) * ms.y * gm.x + bt.x, o1 = (y[1] - ms.x) * ms.y * gm.y + bt.y;
;               const float o2 = (y[2] - ms.x) * ms.y * gm.z + bt.z, o3 = (y[3] - ms.x) * ms.y * gm.w + bt.w;
;               const unsigned h0 = f2bf(o0), h1 = f2bf(o1), h2 = f2bf(o2), h3 = f2bf(o3);
;               u32x2 ob; ob[0] = h0 | (h1 << 16); ob[1] = h2 | (h3 << 16);
;               *reinterpret_cast<u32x2*>(smem + (rr >> 1) * PIECE + (rr & 1) * 512 + cc * 2) = ob;
;               const int l0 = min(((int)__float_as_uint(o0) - (int)(h0 << 16) + 128) >> 8, 127);
;               const int l1 = min(((int)__float_as_uint(o1) - (int)(h1 << 16) + 128) >> 8, 127);
;               const int l2 = min(((int)__float_as_uint(o2) - (int)(h2 << 16) + 128) >> 8, 127);
;               const int l3 = min(((int)__float_as_uint(o3) - (int)(h3 << 16) + 128) >> 8, 127);
;               *reinterpret_cast<unsigned*>(smem + LOBASE + (rr >> 2) * PIECE + (rr & 3) * 256 + cc) =
;                   (unsigned)(l0 & 255) | ((unsigned)(l1 & 255) << 8) | ((unsigned)(l2 & 255) << 16) | ((unsigned)l3 << 24);
;             }
	v_pk_add_f32 v[118:119], v[118:119], v[106:107] op_sel_hi:[1,0] neg_lo:[0,1] neg_hi:[0,1]
	v_mov_b32_e32 v110, v1
	v_mov_b32_e32 v111, v2
	v_mov_b32_e32 v114, v5
	v_mov_b32_e32 v115, v6
	v_pk_fma_f32 v[120:121], v[110:111], v[120:121], v[114:115]
	v_pk_mul_f32 v[106:107], v[106:107], v[118:119] op_sel:[1,0]
	v_mov_b32_e32 v1, v3
	v_mov_b32_e32 v5, v7
	v_and_b32_sdwa v6, v121, v216 dst_sel:DWORD dst_unused:UNUSED_PAD src0_sel:WORD_1 src1_sel:DWORD
	v_and_b32_sdwa v7, v120, v216 dst_sel:DWORD dst_unused:UNUSED_PAD src0_sel:WORD_1 src1_sel:DWORD
	v_pk_fma_f32 v[2:3], v[0:1], v[106:107], v[4:5]
	v_add3_u32 v107, v121, v6, s84
	v_add3_u32 v6, v120, v7, s84
	v_and_b32_e32 v118, 0xffff0000, v6
	v_and_b32_sdwa v6, v3, v216 dst_sel:DWORD dst_unused:UNUSED_PAD src0_sel:WORD_1 src1_sel:DWORD
	v_and_b32_sdwa v7, v2, v216 dst_sel:DWORD dst_unused:UNUSED_PAD src0_sel:WORD_1 src1_sel:DWORD
	v_add3_u32 v6, v3, v6, s84
	v_add3_u32 v119, v2, v7, s84
	v_and_b32_e32 v122, 0xffff0000, v6
	v_or_b32_sdwa v7, v122, v107 dst_sel:DWORD dst_unused:UNUSED_PAD src0_sel:DWORD src1_sel:WORD_1
	v_or_b32_sdwa v6, v119, v118 dst_sel:DWORD dst_unused:UNUSED_PAD src0_sel:WORD_1 src1_sel:DWORD
	v_add_u32_e32 v106, v109, v152
	ds_write_b64 v106, v[6:7]
	v_and_b32_e32 v6, 0xffff0000, v119
	v_sub_u32_e32 v2, v2, v6
	v_sub_u32_e32 v6, v120, v118
	v_and_b32_e32 v7, 0xffff0000, v107
	v_add_u32_e32 v6, 0x80, v6
	v_sub_u32_e32 v7, v121, v7
	v_sub_u32_e32 v3, v3, v122
	v_add_u32_e32 v2, 0x80, v2
	v_ashrrev_i32_e32 v6, 8, v6
	v_add_u32_e32 v7, 0x80, v7
	v_add_u32_e32 v3, 0x80, v3
	v_ashrrev_i32_e32 v2, 8, v2
	v_min_i32_e32 v6, 0x7f, v6
	v_ashrrev_i32_e32 v7, 8, v7
	v_ashrrev_i32_e32 v3, 8, v3
	v_min_i32_e32 v2, 0x7f, v2
	v_min_i32_sdwa v7, v7, s85 dst_sel:WORD_1 dst_unused:UNUSED_PAD src0_sel:DWORD src1_sel:DWORD
	v_min_i32_e32 v3, 0x7f, v3
	v_lshlrev_b32_e32 v6, 8, v6
	v_and_b32_e32 v6, 0xff00, v6
	v_and_b32_e32 v7, 0xff0000, v7
	v_perm_b32 v2, v3, v2, s92
	v_or3_b32 v2, v2, v6, v7
	ds_write_b32 v12, v2 offset:128
	v_mov_b32_e32 v2, v212
	v_mov_b32_e32 v3, v213
	v_pk_add_f32 v[6:7], v[102:103], v[2:3] op_sel_hi:[1,0] neg_lo:[0,1] neg_hi:[0,1]
	s_nop 0
	v_pk_mul_f32 v[6:7], v[2:3], v[6:7] op_sel:[1,0]
	v_pk_add_f32 v[102:103], v[104:105], v[2:3] op_sel_hi:[1,0] neg_lo:[0,1] neg_hi:[0,1]
	v_pk_fma_f32 v[6:7], v[110:111], v[6:7], v[114:115]
	v_pk_mul_f32 v[2:3], v[2:3], v[102:103] op_sel:[1,0]
	v_and_b32_sdwa v102, v7, v216 dst_sel:DWORD dst_unused:UNUSED_PAD src0_sel:WORD_1 src1_sel:DWORD
	v_and_b32_sdwa v103, v6, v216 dst_sel:DWORD dst_unused:UNUSED_PAD src0_sel:WORD_1 src1_sel:DWORD
	v_pk_fma_f32 v[2:3], v[0:1], v[2:3], v[4:5]
	v_add3_u32 v107, v7, v102, s84
	v_add3_u32 v102, v6, v103, s84
	v_and_b32_e32 v103, 0xffff0000, v102
	v_and_b32_sdwa v102, v3, v216 dst_sel:DWORD dst_unused:UNUSED_PAD src0_sel:WORD_1 src1_sel:DWORD
	v_and_b32_sdwa v104, v2, v216 dst_sel:DWORD dst_unused:UNUSED_PAD src0_sel:WORD_1 src1_sel:DWORD
	v_add3_u32 v102, v3, v102, s84
	v_add3_u32 v118, v2, v104, s84
	v_and_b32_e32 v119, 0xffff0000, v102
	v_or_b32_sdwa v105, v119, v107 dst_sel:DWORD dst_unused:UNUSED_PAD src0_sel:DWORD src1_sel:WORD_1
	v_or_b32_sdwa v104, v118, v103 dst_sel:DWORD dst_unused:UNUSED_PAD src0_sel:WORD_1 src1_sel:DWORD
	v_add_u32_e32 v102, v109, v153
	ds_write_b64 v102, v[104:105]
	v_and_b32_e32 v104, 0xffff0000, v118
	v_sub_u32_e32 v6, v6, v103
	v_and_b32_e32 v103, 0xffff0000, v107
	v_sub_u32_e32 v2, v2, v104
	v_add_u32_e32 v6, 0x80, v6
	v_sub_u32_e32 v7, v7, v103
	v_sub_u32_e32 v3, v3, v119
	v_add_u32_e32 v2, 0x80, v2
	v_ashrrev_i32_e32 v6, 8, v6
	v_add_u32_e32 v7, 0x80, v7
	v_add_u32_e32 v3, 0x80, v3
	v_ashrrev_i32_e32 v2, 8, v2
	v_min_i32_e32 v6, 0x7f, v6
	v_ashrrev_i32_e32 v7, 8, v7
	v_ashrrev_i32_e32 v3, 8, v3
	v_min_i32_e32 v2, 0x7f, v2
	v_min_i32_sdwa v7, v7, s85 dst_sel:WORD_1 dst_unused:UNUSED_PAD src0_sel:DWORD src1_sel:DWORD
	v_min_i32_e32 v3, 0x7f, v3
	v_lshlrev_b32_e32 v6, 8, v6
	v_and_b32_e32 v6, 0xff00, v6
	v_and_b32_e32 v7, 0xff0000, v7
	v_perm_b32 v2, v3, v2, s92
	v_or3_b32 v2, v2, v6, v7
	ds_write_b32 v14, v2 offset:128
	v_mov_b32_e32 v2, v214
	v_mov_b32_e32 v3, v215
	v_pk_add_f32 v[6:7], v[92:93], v[2:3] op_sel_hi:[1,0] neg_lo:[0,1] neg_hi:[0,1]
	s_nop 0
	v_pk_mul_f32 v[6:7], v[2:3], v[6:7] op_sel:[1,0]
	v_pk_add_f32 v[88:89], v[88:89], v[2:3] op_sel_hi:[1,0] neg_lo:[0,1] neg_hi:[0,1]
	v_pk_fma_f32 v[6:7], v[110:111], v[6:7], v[114:115]
	v_pk_mul_f32 v[2:3], v[2:3], v[88:89] op_sel:[1,0]
	v_and_b32_sdwa v88, v7, v216 dst_sel:DWORD dst_unused:UNUSED_PAD src0_sel:WORD_1 src1_sel:DWORD
	v_and_b32_sdwa v89, v6, v216 dst_sel:DWORD dst_unused:UNUSED_PAD src0_sel:WORD_1 src1_sel:DWORD
	v_pk_fma_f32 v[2:3], v[0:1], v[2:3], v[4:5]
	v_add3_u32 v93, v7, v88, s84
	v_add3_u32 v88, v6, v89, s84
	v_and_b32_e32 v103, 0xffff0000, v88
	v_and_b32_sdwa v88, v3, v216 dst_sel:DWORD dst_unused:UNUSED_PAD src0_sel:WORD_1 src1_sel:DWORD
	v_and_b32_sdwa v89, v2, v216 dst_sel:DWORD dst_unused:UNUSED_PAD src0_sel:WORD_1 src1_sel:DWORD
	v_add3_u32 v88, v3, v88, s84
	v_add3_u32 v104, v2, v89, s84
	v_and_b32_e32 v105, 0xffff0000, v88
	v_or_b32_sdwa v89, v105, v93 dst_sel:DWORD dst_unused:UNUSED_PAD src0_sel:DWORD src1_sel:WORD_1
	v_or_b32_sdwa v88, v104, v103 dst_sel:DWORD dst_unused:UNUSED_PAD src0_sel:WORD_1 src1_sel:DWORD
	v_add_u32_e32 v92, v109, v137
	ds_write_b64 v92, v[88:89]
	v_and_b32_e32 v88, 0xffff0000, v104
	v_sub_u32_e32 v2, v2, v88
	v_sub_u32_e32 v6, v6, v103
	v_and_b32_e32 v88, 0xffff0000, v93
	v_add_u32_e32 v6, 0x80, v6
	v_sub_u32_e32 v7, v7, v88
	v_sub_u32_e32 v3, v3, v105
	v_add_u32_e32 v2, 0x80, v2
	v_ashrrev_i32_e32 v6, 8, v6
	v_add_u32_e32 v7, 0x80, v7
	v_add_u32_e32 v3, 0x80, v3
;     ...
;         _Pragma("unroll") for (int ai = 0; ai < 2; ++ai) {
;           _Pragma("unroll") for (int bj = 0; bj < 2; ++bj) _Pragma("unroll") for (int n = 0; n < 2; ++n) {
;             const int cc = bj * HALF + wc3 * 32 + n * 16 + fq3 * 4;
;             const float4 gm = *reinterpret_cast<const float4*>(g.gam + pn * BM + cc), bt = *reinterpret_cast<const float4*>(g.bet + pn * BM + cc);
;             _Pragma("unroll") for (int m = 0; m < 4; ++m) {
;               const int rr = wr3 * 64 + m * 16 + fr3;
;               const float2 ms = *reinterpret_cast<const float2*>(mr + (ai * HALF + rr) * 2);
;               f32x4 y = acc[ai][bj][m][n];
;               const float o0 = (y[0] - ms.x) * ms.y * gm.x + bt.x, o1 = (y[1] - ms.x) * ms.y * gm.y + bt.y;
;               const float o2 = (y[2] - ms.x) * ms.y * gm.z + bt.z, o3 = (y[3] - ms.x) * ms.y * gm.w + bt.w;
;               const unsigned h0 = f2bf(o0), h1 = f2bf(o1), h2 = f2bf(o2), h3 = f2bf(o3);
;               u32x2 ob; ob[0] = h0 | (h1 << 16); ob[1] = h2 | (h3 << 16);
;               *reinterpret_cast<u32x2*>(smem + (rr >> 1) * PIECE + (rr & 1) * 512 + cc * 2) = ob;
;               const int l0 = min(((int)__float_as_uint(o0) - (int)(h0 << 16) + 128) >> 8, 127);
;               const int l1 = min(((int)__float_as_uint(o1) - (int)(h1 << 16) + 128) >> 8, 127);
;               const int l2 = min(((int)__float_as_uint(o2) - (int)(h2 << 16) + 128) >> 8, 127);
;               const int l3 = min(((int)__float_as_uint(o3) - (int)(h3 << 16) + 128) >> 8, 127);
;               *reinterpret_cast<unsigned*>(smem + LOBASE + (rr >> 2) * PIECE + (rr & 3) * 256 + cc) =
;                   (unsigned)(l0 & 255) | ((unsigned)(l1 & 255) << 8) | ((unsigned)(l2 & 255) << 16) | ((unsigned)l3 << 24);
;             }
	v_ashrrev_i32_e32 v2, 8, v2
	v_min_i32_e32 v6, 0x7f, v6
	v_ashrrev_i32_e32 v7, 8, v7
	v_ashrrev_i32_e32 v3, 8, v3
	v_min_i32_e32 v2, 0x7f, v2
	v_min_i32_sdwa v7, v7, s85 dst_sel:WORD_1 dst_unused:UNUSED_PAD src0_sel:DWORD src1_sel:DWORD
	v_min_i32_e32 v3, 0x7f, v3
	v_lshlrev_b32_e32 v6, 8, v6
	v_and_b32_e32 v6, 0xff00, v6
	v_and_b32_e32 v7, 0xff0000, v7
	v_perm_b32 v2, v3, v2, s92
	v_or3_b32 v2, v2, v6, v7
	ds_write_b32 v18, v2 offset:128
	v_mov_b32_e32 v2, v252
	v_mov_b32_e32 v3, v253
	v_add_u32_e32 v93, v109, v136
	v_pk_add_f32 v[6:7], v[90:91], v[2:3] op_sel_hi:[1,0] neg_lo:[0,1] neg_hi:[0,1]
	s_nop 0
	v_pk_mul_f32 v[6:7], v[2:3], v[6:7] op_sel:[1,0]
	v_pk_add_f32 v[88:89], v[94:95], v[2:3] op_sel_hi:[1,0] neg_lo:[0,1] neg_hi:[0,1]
	v_pk_fma_f32 v[6:7], v[110:111], v[6:7], v[114:115]
	v_pk_mul_f32 v[2:3], v[2:3], v[88:89] op_sel:[1,0]
	s_nop 0
	v_pk_fma_f32 v[0:1], v[0:1], v[2:3], v[4:5]
	v_and_b32_sdwa v2, v7, v216 dst_sel:DWORD dst_unused:UNUSED_PAD src0_sel:WORD_1 src1_sel:DWORD
	v_and_b32_sdwa v3, v6, v216 dst_sel:DWORD dst_unused:UNUSED_PAD src0_sel:WORD_1 src1_sel:DWORD
	v_add3_u32 v4, v7, v2, s84
	v_add3_u32 v2, v6, v3, s84
	v_and_b32_e32 v5, 0xffff0000, v2
	v_and_b32_sdwa v2, v1, v216 dst_sel:DWORD dst_unused:UNUSED_PAD src0_sel:WORD_1 src1_sel:DWORD
	v_and_b32_sdwa v3, v0, v216 dst_sel:DWORD dst_unused:UNUSED_PAD src0_sel:WORD_1 src1_sel:DWORD
	v_add3_u32 v2, v1, v2, s84
	v_add3_u32 v88, v0, v3, s84
	v_and_b32_e32 v89, 0xffff0000, v2
	v_or_b32_sdwa v3, v89, v4 dst_sel:DWORD dst_unused:UNUSED_PAD src0_sel:DWORD src1_sel:WORD_1
	v_or_b32_sdwa v2, v88, v5 dst_sel:DWORD dst_unused:UNUSED_PAD src0_sel:WORD_1 src1_sel:DWORD
	ds_write_b64 v93, v[2:3]
	v_and_b32_e32 v2, 0xffff0000, v88
	v_sub_u32_e32 v0, v0, v2
	v_sub_u32_e32 v2, v6, v5
	v_and_b32_e32 v3, 0xffff0000, v4
	v_add_u32_e32 v2, 0x80, v2
	v_sub_u32_e32 v3, v7, v3
	v_sub_u32_e32 v1, v1, v89
	v_add_u32_e32 v0, 0x80, v0
	v_ashrrev_i32_e32 v2, 8, v2
	v_add_u32_e32 v3, 0x80, v3
	v_add_u32_e32 v1, 0x80, v1
	v_ashrrev_i32_e32 v0, 8, v0
	v_min_i32_e32 v2, 0x7f, v2
	v_ashrrev_i32_e32 v3, 8, v3
	v_ashrrev_i32_e32 v1, 8, v1
	v_min_i32_e32 v0, 0x7f, v0
	v_min_i32_sdwa v3, v3, s85 dst_sel:WORD_1 dst_unused:UNUSED_PAD src0_sel:DWORD src1_sel:DWORD
	v_min_i32_e32 v1, 0x7f, v1
	v_lshlrev_b32_e32 v2, 8, v2
	v_and_b32_e32 v2, 0xff00, v2
	v_and_b32_e32 v3, 0xff0000, v3
	v_perm_b32 v0, v1, v0, s92
	v_or3_b32 v0, v0, v2, v3
	ds_write_b32 v22, v0 offset:128
	v_mov_b32_e32 v0, v232
	v_mov_b32_e32 v1, v233
	v_mov_b32_e32 v2, v234
	v_mov_b32_e32 v3, v235
	v_mov_b32_e32 v4, v248
	v_mov_b32_e32 v5, v249
	v_mov_b32_e32 v6, v250
	v_mov_b32_e32 v7, v251
	v_mov_b32_e32 v94, v210
	v_mov_b32_e32 v95, v211
	v_pk_add_f32 v[104:105], v[116:117], v[94:95] op_sel_hi:[1,0] neg_lo:[0,1] neg_hi:[0,1]
	s_nop 0
	v_pk_mul_f32 v[104:105], v[94:95], v[104:105] op_sel:[1,0]
	v_pk_add_f32 v[110:111], v[112:113], v[94:95] op_sel_hi:[1,0] neg_lo:[0,1] neg_hi:[0,1]
	v_mov_b32_e32 v88, v1
	v_mov_b32_e32 v89, v2
	v_mov_b32_e32 v90, v5
	v_mov_b32_e32 v91, v6
	v_pk_fma_f32 v[104:105], v[88:89], v[104:105], v[90:91]
	v_pk_mul_f32 v[94:95], v[94:95], v[110:111] op_sel:[1,0]
	v_mov_b32_e32 v1, v3
	v_mov_b32_e32 v5, v7
	v_pk_fma_f32 v[6:7], v[0:1], v[94:95], v[4:5]
	v_and_b32_sdwa v94, v104, v216 dst_sel:DWORD dst_unused:UNUSED_PAD src0_sel:WORD_1 src1_sel:DWORD
	v_add3_u32 v94, v104, v94, s84
	v_and_b32_e32 v95, 0xffff0000, v94
	v_and_b32_sdwa v94, v7, v216 dst_sel:DWORD dst_unused:UNUSED_PAD src0_sel:WORD_1 src1_sel:DWORD
	v_and_b32_sdwa v3, v105, v216 dst_sel:DWORD dst_unused:UNUSED_PAD src0_sel:WORD_1 src1_sel:DWORD
	v_and_b32_sdwa v103, v6, v216 dst_sel:DWORD dst_unused:UNUSED_PAD src0_sel:WORD_1 src1_sel:DWORD
	v_add3_u32 v94, v7, v94, s84
	v_add3_u32 v3, v105, v3, s84
	v_add3_u32 v103, v6, v103, s84
	v_and_b32_e32 v107, 0xffff0000, v94
	v_or_b32_sdwa v111, v107, v3 dst_sel:DWORD dst_unused:UNUSED_PAD src0_sel:DWORD src1_sel:WORD_1
	v_or_b32_sdwa v110, v103, v95 dst_sel:DWORD dst_unused:UNUSED_PAD src0_sel:WORD_1 src1_sel:DWORD
	v_and_b32_e32 v103, 0xffff0000, v103
	v_sub_u32_e32 v95, v104, v95
	v_and_b32_e32 v3, 0xffff0000, v3
	v_sub_u32_e32 v6, v6, v103
	v_add_u32_e32 v95, 0x80, v95
	v_sub_u32_e32 v3, v105, v3
	v_sub_u32_e32 v7, v7, v107
	v_add_u32_e32 v6, 0x80, v6
	v_ashrrev_i32_e32 v95, 8, v95
	v_add_u32_e32 v3, 0x80, v3
	v_add_u32_e32 v7, 0x80, v7
	v_ashrrev_i32_e32 v6, 8, v6
	v_min_i32_e32 v95, 0x7f, v95
	v_ashrrev_i32_e32 v3, 8, v3
	v_ashrrev_i32_e32 v7, 8, v7
	v_min_i32_e32 v6, 0x7f, v6
	v_min_i32_sdwa v3, v3, s85 dst_sel:WORD_1 dst_unused:UNUSED_PAD src0_sel:DWORD src1_sel:DWORD
	v_min_i32_e32 v7, 0x7f, v7
	v_lshlrev_b32_e32 v95, 8, v95
	v_or_b32_e32 v2, 0x120, v154
	v_and_b32_e32 v95, 0xff00, v95
	v_and_b32_e32 v3, 0xff0000, v3
	v_perm_b32 v6, v7, v6, s92
	v_add_u32_e32 v94, v2, v152
	v_or3_b32 v3, v6, v95, v3
	ds_write_b64 v94, v[110:111]
	ds_write_b32 v12, v3 offset:144
	v_mov_b32_e32 v6, v212
	v_mov_b32_e32 v7, v213
	v_pk_add_f32 v[100:101], v[100:101], v[6:7] op_sel_hi:[1,0] neg_lo:[0,1] neg_hi:[0,1]
	s_nop 0
	v_pk_mul_f32 v[100:101], v[6:7], v[100:101] op_sel:[1,0]
	v_pk_add_f32 v[96:97], v[96:97], v[6:7] op_sel_hi:[1,0] neg_lo:[0,1] neg_hi:[0,1]
	v_pk_fma_f32 v[100:101], v[88:89], v[100:101], v[90:91]
	v_pk_mul_f32 v[6:7], v[6:7], v[96:97] op_sel:[1,0]
	v_and_b32_sdwa v95, v100, v216 dst_sel:DWORD dst_unused:UNUSED_PAD src0_sel:WORD_1 src1_sel:DWORD
	v_pk_fma_f32 v[6:7], v[0:1], v[6:7], v[4:5]
	v_add3_u32 v95, v100, v95, s84
	v_and_b32_e32 v103, 0xffff0000, v95
	v_and_b32_sdwa v95, v7, v216 dst_sel:DWORD dst_unused:UNUSED_PAD src0_sel:WORD_1 src1_sel:DWORD
	v_and_b32_sdwa v3, v101, v216 dst_sel:DWORD dst_unused:UNUSED_PAD src0_sel:WORD_1 src1_sel:DWORD
; #define WAIT_L(n) asm volatile("s_waitcnt lgkmcnt(" #n ")" ::: "memory")
; #define BAR __builtin_amdgcn_s_barrier()
;     ...
;         _Pragma("unroll") for (int ai = 0; ai < 2; ++ai) {
;           _Pragma("unroll") for (int bj = 0; bj < 2; ++bj) _Pragma("unroll") for (int n = 0; n < 2; ++n) {
;             const int cc = bj * HALF + wc3 * 32 + n * 16 + fq3 * 4;
;             const float4 gm = *reinterpret_cast<const float4*>(g.gam + pn * BM + cc), bt = *reinterpret_cast<const float4*>(g.bet + pn * BM + cc);
;             _Pragma("unroll") for (int m = 0; m < 4; ++m) {
;               const int rr = wr3 * 64 + m * 16 + fr3;
;               const float2 ms = *reinterpret_cast<const float2*>(mr + (ai * HALF + rr) * 2);
;               f32x4 y = acc[ai][bj][m][n];
;               const float o0 = (y[0] - ms.x) * ms.y * gm.x + bt.x, o1 = (y[1] - ms.x) * ms.y * gm.y + bt.y;
;               const float o2 = (y[2] - ms.x) * ms.y * gm.z + bt.z, o3 = (y[3] - ms.x) * ms.y * gm.w + bt.w;
;               const unsigned h0 = f2bf(o0), h1 = f2bf(o1), h2 = f2bf(o2), h3 = f2bf(o3);
;               u32x2 ob; ob[0] = h0 | (h1 << 16); ob[1] = h2 | (h3 << 16);
;               *reinterpret_cast<u32x2*>(smem + (rr >> 1) * PIECE + (rr & 1) * 512 + cc * 2) = ob;
;               const int l0 = min(((int)__float_as_uint(o0) - (int)(h0 << 16) + 128) >> 8, 127);
;               const int l1 = min(((int)__float_as_uint(o1) - (int)(h1 << 16) + 128) >> 8, 127);
;               const int l2 = min(((int)__float_as_uint(o2) - (int)(h2 << 16) + 128) >> 8, 127);
;               const int l3 = min(((int)__float_as_uint(o3) - (int)(h3 << 16) + 128) >> 8, 127);
;               *reinterpret_cast<unsigned*>(smem + LOBASE + (rr >> 2) * PIECE + (rr & 3) * 256 + cc) =
;                   (unsigned)(l0 & 255) | ((unsigned)(l1 & 255) << 8) | ((unsigned)(l2 & 255) << 16) | ((unsigned)l3 << 24);
;             }
;           }
;           WAIT_L(0); BAR;
	v_and_b32_sdwa v96, v6, v216 dst_sel:DWORD dst_unused:UNUSED_PAD src0_sel:WORD_1 src1_sel:DWORD
	v_add3_u32 v95, v7, v95, s84
	v_add3_u32 v3, v101, v3, s84
	v_add3_u32 v104, v6, v96, s84
	v_and_b32_e32 v105, 0xffff0000, v95
	v_or_b32_sdwa v97, v105, v3 dst_sel:DWORD dst_unused:UNUSED_PAD src0_sel:DWORD src1_sel:WORD_1
	v_or_b32_sdwa v96, v104, v103 dst_sel:DWORD dst_unused:UNUSED_PAD src0_sel:WORD_1 src1_sel:DWORD
	v_add_u32_e32 v95, v2, v153
	ds_write_b64 v95, v[96:97]
	v_and_b32_e32 v96, 0xffff0000, v104
	v_sub_u32_e32 v6, v6, v96
	v_sub_u32_e32 v96, v100, v103
	v_and_b32_e32 v3, 0xffff0000, v3
	v_add_u32_e32 v96, 0x80, v96
	v_sub_u32_e32 v3, v101, v3
	v_sub_u32_e32 v7, v7, v105
	v_add_u32_e32 v6, 0x80, v6
	v_ashrrev_i32_e32 v96, 8, v96
	v_add_u32_e32 v3, 0x80, v3
	v_add_u32_e32 v7, 0x80, v7
	v_ashrrev_i32_e32 v6, 8, v6
	v_min_i32_e32 v96, 0x7f, v96
	v_ashrrev_i32_e32 v3, 8, v3
	v_ashrrev_i32_e32 v7, 8, v7
	v_min_i32_e32 v6, 0x7f, v6
	v_min_i32_sdwa v3, v3, s85 dst_sel:WORD_1 dst_unused:UNUSED_PAD src0_sel:DWORD src1_sel:DWORD
	v_min_i32_e32 v7, 0x7f, v7
	v_lshlrev_b32_e32 v96, 8, v96
	v_and_b32_e32 v96, 0xff00, v96
	v_and_b32_e32 v3, 0xff0000, v3
	v_perm_b32 v6, v7, v6, s92
	v_or3_b32 v3, v6, v96, v3
	ds_write_b32 v14, v3 offset:144
	v_mov_b32_e32 v6, v214
	v_mov_b32_e32 v7, v215
	v_pk_add_f32 v[84:85], v[84:85], v[6:7] op_sel_hi:[1,0] neg_lo:[0,1] neg_hi:[0,1]
	s_nop 0
	v_pk_mul_f32 v[84:85], v[6:7], v[84:85] op_sel:[1,0]
	v_pk_add_f32 v[80:81], v[80:81], v[6:7] op_sel_hi:[1,0] neg_lo:[0,1] neg_hi:[0,1]
	v_pk_fma_f32 v[84:85], v[88:89], v[84:85], v[90:91]
	v_pk_mul_f32 v[6:7], v[6:7], v[80:81] op_sel:[1,0]
	v_and_b32_sdwa v80, v84, v216 dst_sel:DWORD dst_unused:UNUSED_PAD src0_sel:WORD_1 src1_sel:DWORD
	v_pk_fma_f32 v[6:7], v[0:1], v[6:7], v[4:5]
	v_add3_u32 v80, v84, v80, s84
	v_and_b32_e32 v81, 0xffff0000, v80
	v_and_b32_sdwa v80, v7, v216 dst_sel:DWORD dst_unused:UNUSED_PAD src0_sel:WORD_1 src1_sel:DWORD
	v_and_b32_sdwa v3, v85, v216 dst_sel:DWORD dst_unused:UNUSED_PAD src0_sel:WORD_1 src1_sel:DWORD
	v_and_b32_sdwa v96, v6, v216 dst_sel:DWORD dst_unused:UNUSED_PAD src0_sel:WORD_1 src1_sel:DWORD
	v_add3_u32 v80, v7, v80, s84
	v_add3_u32 v3, v85, v3, s84
	v_add3_u32 v100, v6, v96, s84
	v_and_b32_e32 v101, 0xffff0000, v80
	v_or_b32_sdwa v97, v101, v3 dst_sel:DWORD dst_unused:UNUSED_PAD src0_sel:DWORD src1_sel:WORD_1
	v_or_b32_sdwa v96, v100, v81 dst_sel:DWORD dst_unused:UNUSED_PAD src0_sel:WORD_1 src1_sel:DWORD
	v_add_u32_e32 v80, v2, v137
	ds_write_b64 v80, v[96:97]
	v_and_b32_e32 v96, 0xffff0000, v100
	v_sub_u32_e32 v81, v84, v81
	v_and_b32_e32 v3, 0xffff0000, v3
	v_sub_u32_e32 v6, v6, v96
	v_add_u32_e32 v81, 0x80, v81
	v_sub_u32_e32 v3, v85, v3
	v_sub_u32_e32 v7, v7, v101
	v_add_u32_e32 v6, 0x80, v6
	v_ashrrev_i32_e32 v81, 8, v81
	v_add_u32_e32 v3, 0x80, v3
	v_add_u32_e32 v7, 0x80, v7
	v_ashrrev_i32_e32 v6, 8, v6
	v_min_i32_e32 v81, 0x7f, v81
	v_ashrrev_i32_e32 v3, 8, v3
	v_ashrrev_i32_e32 v7, 8, v7
	v_min_i32_e32 v6, 0x7f, v6
	v_min_i32_sdwa v3, v3, s85 dst_sel:WORD_1 dst_unused:UNUSED_PAD src0_sel:DWORD src1_sel:DWORD
	v_min_i32_e32 v7, 0x7f, v7
	v_lshlrev_b32_e32 v81, 8, v81
	v_and_b32_e32 v81, 0xff00, v81
	v_and_b32_e32 v3, 0xff0000, v3
	v_perm_b32 v6, v7, v6, s92
	v_or3_b32 v3, v6, v81, v3
	ds_write_b32 v18, v3 offset:144
	v_mov_b32_e32 v6, v252
	v_mov_b32_e32 v7, v253
	v_or_b32_e32 v81, 0x6000, v148
	v_or_b32_e32 v96, 0x6000, v146
	v_pk_add_f32 v[72:73], v[72:73], v[6:7] op_sel_hi:[1,0] neg_lo:[0,1] neg_hi:[0,1]
	s_nop 0
	v_pk_mul_f32 v[72:73], v[6:7], v[72:73] op_sel:[1,0]
	s_nop 0
	v_pk_fma_f32 v[84:85], v[88:89], v[72:73], v[90:91]
	v_pk_add_f32 v[72:73], v[74:75], v[6:7] op_sel_hi:[1,0] neg_lo:[0,1] neg_hi:[0,1]
	v_and_b32_sdwa v3, v85, v216 dst_sel:DWORD dst_unused:UNUSED_PAD src0_sel:WORD_1 src1_sel:DWORD
	v_pk_mul_f32 v[6:7], v[6:7], v[72:73] op_sel:[1,0]
	v_add3_u32 v3, v85, v3, s84
	v_pk_fma_f32 v[0:1], v[0:1], v[6:7], v[4:5]
	v_and_b32_sdwa v4, v84, v216 dst_sel:DWORD dst_unused:UNUSED_PAD src0_sel:WORD_1 src1_sel:DWORD
	v_add3_u32 v4, v84, v4, s84
	v_and_b32_e32 v6, 0xffff0000, v4
	v_and_b32_sdwa v4, v1, v216 dst_sel:DWORD dst_unused:UNUSED_PAD src0_sel:WORD_1 src1_sel:DWORD
	v_and_b32_sdwa v5, v0, v216 dst_sel:DWORD dst_unused:UNUSED_PAD src0_sel:WORD_1 src1_sel:DWORD
	v_add3_u32 v4, v1, v4, s84
	v_add3_u32 v7, v0, v5, s84
	v_and_b32_e32 v72, 0xffff0000, v4
	v_add_u32_e32 v73, v2, v136
	v_and_b32_e32 v2, 0xffff0000, v7
	v_or_b32_sdwa v5, v72, v3 dst_sel:DWORD dst_unused:UNUSED_PAD src0_sel:DWORD src1_sel:WORD_1
	v_sub_u32_e32 v0, v0, v2
	v_sub_u32_e32 v2, v84, v6
	v_and_b32_e32 v3, 0xffff0000, v3
	v_add_u32_e32 v2, 0x80, v2
	v_sub_u32_e32 v3, v85, v3
	v_sub_u32_e32 v1, v1, v72
	v_add_u32_e32 v0, 0x80, v0
	v_ashrrev_i32_e32 v2, 8, v2
	v_add_u32_e32 v3, 0x80, v3
	v_add_u32_e32 v1, 0x80, v1
	v_ashrrev_i32_e32 v0, 8, v0
	v_min_i32_e32 v2, 0x7f, v2
	v_ashrrev_i32_e32 v3, 8, v3
	v_ashrrev_i32_e32 v1, 8, v1
	v_min_i32_e32 v0, 0x7f, v0
	v_min_i32_sdwa v3, v3, s85 dst_sel:WORD_1 dst_unused:UNUSED_PAD src0_sel:DWORD src1_sel:DWORD
	v_min_i32_e32 v1, 0x7f, v1
	v_lshlrev_b32_e32 v2, 8, v2
	v_and_b32_e32 v2, 0xff00, v2
	v_and_b32_e32 v3, 0xff0000, v3
	v_perm_b32 v0, v1, v0, s92
	v_or_b32_sdwa v4, v7, v6 dst_sel:DWORD dst_unused:UNUSED_PAD src0_sel:WORD_1 src1_sel:DWORD
	v_or3_b32 v0, v0, v2, v3
	ds_write_b64 v73, v[4:5]
	ds_write_b32 v22, v0 offset:144
	v_add_u32_e32 v72, s2, v151
	s_waitcnt lgkmcnt(0)
	s_barrier
; #define WAIT_L(n) asm volatile("s_waitcnt lgkmcnt(" #n ")" ::: "memory")
;     ...
;         _Pragma("unroll") for (int ai = 0; ai < 2; ++ai) {
;           _Pragma("unroll") for (int bj = 0; bj < 2; ++bj) _Pragma("unroll") for (int n = 0; n < 2; ++n) {
;             const int cc = bj * HALF + wc3 * 32 + n * 16 + fq3 * 4;
;             const float4 gm = *reinterpret_cast<const float4*>(g.gam + pn * BM + cc), bt = *reinterpret_cast<const float4*>(g.bet + pn * BM + cc);
;             _Pragma("unroll") for (int m = 0; m < 4; ++m) {
;               const int rr = wr3 * 64 + m * 16 + fr3;
;               const float2 ms = *reinterpret_cast<const float2*>(mr + (ai * HALF + rr) * 2);
;               f32x4 y = acc[ai][bj][m][n];
;               const float o0 = (y[0] - ms.x) * ms.y * gm.x + bt.x, o1 = (y[1] - ms.x) * ms.y * gm.y + bt.y;
;               const float o2 = (y[2] - ms.x) * ms.y * gm.z + bt.z, o3 = (y[3] - ms.x) * ms.y * gm.w + bt.w;
;               const unsigned h0 = f2bf(o0), h1 = f2bf(o1), h2 = f2bf(o2), h3 = f2bf(o3);
;               u32x2 ob; ob[0] = h0 | (h1 << 16); ob[1] = h2 | (h3 << 16);
;               *reinterpret_cast<u32x2*>(smem + (rr >> 1) * PIECE + (rr & 1) * 512 + cc * 2) = ob;
;               const int l0 = min(((int)__float_as_uint(o0) - (int)(h0 << 16) + 128) >> 8, 127);
;               const int l1 = min(((int)__float_as_uint(o1) - (int)(h1 << 16) + 128) >> 8, 127);
;               const int l2 = min(((int)__float_as_uint(o2) - (int)(h2 << 16) + 128) >> 8, 127);
;               const int l3 = min(((int)__float_as_uint(o3) - (int)(h3 << 16) + 128) >> 8, 127);
;               *reinterpret_cast<unsigned*>(smem + LOBASE + (rr >> 2) * PIECE + (rr & 3) * 256 + cc) =
;                   (unsigned)(l0 & 255) | ((unsigned)(l1 & 255) << 8) | ((unsigned)(l2 & 255) << 16) | ((unsigned)l3 << 24);
;             }
;           }
;           WAIT_L(0); BAR;
;           const int hso = ((brow + ai * HALF + 16 * wave) * DM + pn * BM) * 2;
;           const int lso = (brow + ai * HALF + 16 * wave) * DM + pn * BM;
;           _Pragma("unroll") for (int i = 0; i < 8; ++i) {
;             const u32x4 v = *reinterpret_cast<const u32x4*>(smem + (wave * 8 + i) * PIECE + lane3 * 16);
;             __builtin_amdgcn_raw_buffer_store_b128(v, rsXB, hvo + i * (2 * DM * 2), hso, 0);
;           }
;           _Pragma("unroll") for (int i = 0; i < 4; ++i) {
	ds_read_b128 v[128:131], v72
	v_or_b32_e32 v74, 0x2000, v148
	v_or_b32_e32 v75, 0x4000, v148
	v_or_b32_e32 v84, 0x8000, v148
	v_or_b32_e32 v85, 0xa000, v148
	ds_read_b128 v[136:139], v72 offset:1040
	v_or_b32_e32 v88, 0xc000, v148
	v_or_b32_e32 v89, 0xe000, v148
	v_or_b32_e32 v90, 0x2000, v146
	v_or_b32_e32 v91, 0x4000, v146
	ds_read_b128 v[140:143], v72 offset:2080
	ds_read_b128 v[152:155], v72 offset:3120
	ds_read_b128 v[156:159], v72 offset:4160
	ds_read_b128 v[160:163], v72 offset:5200
	ds_read_b128 v[164:167], v72 offset:6240
	ds_read_b128 v[168:171], v72 offset:7280
	ds_read_b128 v[172:175], v147
	ds_read_b128 v[176:179], v147 offset:1040
	ds_read_b128 v[180:183], v147 offset:2080
	ds_read_b128 v[184:187], v147 offset:3120
	s_waitcnt lgkmcnt(0)
	s_barrier
	s_nop 1
	v_mov_b32_e32 v0, v220
	v_mov_b32_e32 v1, v221
	v_mov_b32_e32 v2, v222
	v_mov_b32_e32 v3, v223
	v_mov_b32_e32 v4, v236
	v_mov_b32_e32 v5, v237
	v_mov_b32_e32 v6, v238
	v_mov_b32_e32 v7, v239
	ds_read_b64 v[110:111], v149 offset:1024
	s_waitcnt lgkmcnt(0)
	v_mov_b32_e32 v210, v110
	v_mov_b32_e32 v211, v111
	v_pk_add_f32 v[64:65], v[64:65], v[110:111] op_sel_hi:[1,0] neg_lo:[0,1] neg_hi:[0,1]
	s_nop 0
	v_pk_mul_f32 v[64:65], v[110:111], v[64:65] op_sel:[1,0]
	v_pk_add_f32 v[66:67], v[66:67], v[110:111] op_sel_hi:[1,0] neg_lo:[0,1] neg_hi:[0,1]
	v_mov_b32_e32 v100, v1
	v_mov_b32_e32 v101, v2
	v_mov_b32_e32 v104, v5
	v_mov_b32_e32 v105, v6
	v_pk_fma_f32 v[64:65], v[100:101], v[64:65], v[104:105]
	v_pk_mul_f32 v[66:67], v[110:111], v[66:67] op_sel:[1,0]
	v_mov_b32_e32 v1, v3
	v_mov_b32_e32 v5, v7
	v_and_b32_sdwa v6, v65, v216 dst_sel:DWORD dst_unused:UNUSED_PAD src0_sel:WORD_1 src1_sel:DWORD
	v_and_b32_sdwa v7, v64, v216 dst_sel:DWORD dst_unused:UNUSED_PAD src0_sel:WORD_1 src1_sel:DWORD
	v_pk_fma_f32 v[2:3], v[0:1], v[66:67], v[4:5]
	v_add3_u32 v66, v65, v6, s84
	v_add3_u32 v6, v64, v7, s84
	v_and_b32_e32 v67, 0xffff0000, v6
	v_and_b32_sdwa v6, v3, v216 dst_sel:DWORD dst_unused:UNUSED_PAD src0_sel:WORD_1 src1_sel:DWORD
	v_and_b32_sdwa v7, v2, v216 dst_sel:DWORD dst_unused:UNUSED_PAD src0_sel:WORD_1 src1_sel:DWORD
	v_add3_u32 v6, v3, v6, s84
	v_add3_u32 v97, v2, v7, s84
	v_and_b32_e32 v103, 0xffff0000, v6
	v_or_b32_sdwa v7, v103, v66 dst_sel:DWORD dst_unused:UNUSED_PAD src0_sel:DWORD src1_sel:WORD_1
	v_or_b32_sdwa v6, v97, v67 dst_sel:DWORD dst_unused:UNUSED_PAD src0_sel:WORD_1 src1_sel:DWORD
	ds_write_b64 v132, v[6:7]
	v_and_b32_e32 v6, 0xffff0000, v97
	v_sub_u32_e32 v2, v2, v6
	v_sub_u32_e32 v6, v64, v67
	v_and_b32_e32 v7, 0xffff0000, v66
	v_add_u32_e32 v6, 0x80, v6
	v_sub_u32_e32 v7, v65, v7
	v_sub_u32_e32 v3, v3, v103
	v_add_u32_e32 v2, 0x80, v2
	v_ashrrev_i32_e32 v6, 8, v6
	v_add_u32_e32 v7, 0x80, v7
	v_add_u32_e32 v3, 0x80, v3
	v_ashrrev_i32_e32 v2, 8, v2
	v_min_i32_e32 v6, 0x7f, v6
	v_ashrrev_i32_e32 v7, 8, v7
	v_ashrrev_i32_e32 v3, 8, v3
	v_min_i32_e32 v2, 0x7f, v2
	v_min_i32_sdwa v7, v7, s85 dst_sel:WORD_1 dst_unused:UNUSED_PAD src0_sel:DWORD src1_sel:DWORD
	v_min_i32_e32 v3, 0x7f, v3
	v_lshlrev_b32_e32 v6, 8, v6
	v_and_b32_e32 v6, 0xff00, v6
	v_and_b32_e32 v7, 0xff0000, v7
	v_perm_b32 v2, v3, v2, s92
	v_or3_b32 v2, v2, v6, v7
	ds_write_b32 v12, v2
	buffer_store_dwordx4 v[128:131], v148, s[16:19], s41 offen
	ds_read_b64 v[2:3], v13 offset:1024
	s_waitcnt lgkmcnt(0)
	v_mov_b32_e32 v212, v2
	v_mov_b32_e32 v213, v3
	v_pk_add_f32 v[6:7], v[68:69], v[2:3] op_sel_hi:[1,0] neg_lo:[0,1] neg_hi:[0,1]
	s_nop 0
	v_pk_mul_f32 v[6:7], v[2:3], v[6:7] op_sel:[1,0]
	v_pk_add_f32 v[64:65], v[70:71], v[2:3] op_sel_hi:[1,0] neg_lo:[0,1] neg_hi:[0,1]
	v_pk_fma_f32 v[6:7], v[100:101], v[6:7], v[104:105]
	v_pk_mul_f32 v[2:3], v[2:3], v[64:65] op_sel:[1,0]
	v_and_b32_sdwa v64, v7, v216 dst_sel:DWORD dst_unused:UNUSED_PAD src0_sel:WORD_1 src1_sel:DWORD
	v_and_b32_sdwa v65, v6, v216 dst_sel:DWORD dst_unused:UNUSED_PAD src0_sel:WORD_1 src1_sel:DWORD
	v_pk_fma_f32 v[2:3], v[0:1], v[2:3], v[4:5]
	v_add3_u32 v66, v7, v64, s84
	v_add3_u32 v64, v6, v65, s84
	v_and_b32_e32 v67, 0xffff0000, v64
	v_and_b32_sdwa v64, v3, v216 dst_sel:DWORD dst_unused:UNUSED_PAD src0_sel:WORD_1 src1_sel:DWORD
	v_and_b32_sdwa v65, v2, v216 dst_sel:DWORD dst_unused:UNUSED_PAD src0_sel:WORD_1 src1_sel:DWORD
	v_add3_u32 v64, v3, v64, s84
	v_add3_u32 v68, v2, v65, s84
	v_and_b32_e32 v69, 0xffff0000, v64
	v_or_b32_sdwa v65, v69, v66 dst_sel:DWORD dst_unused:UNUSED_PAD src0_sel:DWORD src1_sel:WORD_1
	v_or_b32_sdwa v64, v68, v67 dst_sel:DWORD dst_unused:UNUSED_PAD src0_sel:WORD_1 src1_sel:DWORD
	ds_write_b64 v133, v[64:65]
	v_and_b32_e32 v64, 0xffff0000, v68
	v_sub_u32_e32 v2, v2, v64
	v_sub_u32_e32 v6, v6, v67
	v_and_b32_e32 v64, 0xffff0000, v66
	v_add_u32_e32 v6, 0x80, v6
	v_sub_u32_e32 v7, v7, v64
	v_sub_u32_e32 v3, v3, v69
	v_add_u32_e32 v2, 0x80, v2
	v_ashrrev_i32_e32 v6, 8, v6
	v_add_u32_e32 v7, 0x80, v7
	v_add_u32_e32 v3, 0x80, v3
	v_ashrrev_i32_e32 v2, 8, v2
	v_min_i32_e32 v6, 0x7f, v6
	v_ashrrev_i32_e32 v7, 8, v7
	v_ashrrev_i32_e32 v3, 8, v3
	v_min_i32_e32 v2, 0x7f, v2
	v_min_i32_sdwa v7, v7, s85 dst_sel:WORD_1 dst_unused:UNUSED_PAD src0_sel:DWORD src1_sel:DWORD
	v_min_i32_e32 v3, 0x7f, v3
	v_lshlrev_b32_e32 v6, 8, v6
	v_and_b32_e32 v6, 0xff00, v6
	v_and_b32_e32 v7, 0xff0000, v7
	v_perm_b32 v2, v3, v2, s92
	v_or3_b32 v2, v2, v6, v7
	ds_write_b32 v14, v2
	buffer_store_dwordx4 v[136:139], v74, s[16:19], s41 offen
	ds_read_b64 v[2:3], v15 offset:1024
	s_waitcnt lgkmcnt(0)
; #define WAIT_L(n) asm volatile("s_waitcnt lgkmcnt(" #n ")" ::: "memory")
;     ...
;         _Pragma("unroll") for (int ai = 0; ai < 2; ++ai) {
;           _Pragma("unroll") for (int bj = 0; bj < 2; ++bj) _Pragma("unroll") for (int n = 0; n < 2; ++n) {
;             const int cc = bj * HALF + wc3 * 32 + n * 16 + fq3 * 4;
;             const float4 gm = *reinterpret_cast<const float4*>(g.gam + pn * BM + cc), bt = *reinterpret_cast<const float4*>(g.bet + pn * BM + cc);
;             _Pragma("unroll") for (int m = 0; m < 4; ++m) {
;               const int rr = wr3 * 64 + m * 16 + fr3;
;               const float2 ms = *reinterpret_cast<const float2*>(mr + (ai * HALF + rr) * 2);
;               f32x4 y = acc[ai][bj][m][n];
;               const float o0 = (y[0] - ms.x) * ms.y * gm.x + bt.x, o1 = (y[1] - ms.x) * ms.y * gm.y + bt.y;
;               const float o2 = (y[2] - ms.x) * ms.y * gm.z + bt.z, o3 = (y[3] - ms.x) * ms.y * gm.w + bt.w;
;               const unsigned h0 = f2bf(o0), h1 = f2bf(o1), h2 = f2bf(o2), h3 = f2bf(o3);
;               u32x2 ob; ob[0] = h0 | (h1 << 16); ob[1] = h2 | (h3 << 16);
;               *reinterpret_cast<u32x2*>(smem + (rr >> 1) * PIECE + (rr & 1) * 512 + cc * 2) = ob;
;               const int l0 = min(((int)__float_as_uint(o0) - (int)(h0 << 16) + 128) >> 8, 127);
;               const int l1 = min(((int)__float_as_uint(o1) - (int)(h1 << 16) + 128) >> 8, 127);
;               const int l2 = min(((int)__float_as_uint(o2) - (int)(h2 << 16) + 128) >> 8, 127);
;               const int l3 = min(((int)__float_as_uint(o3) - (int)(h3 << 16) + 128) >> 8, 127);
;               *reinterpret_cast<unsigned*>(smem + LOBASE + (rr >> 2) * PIECE + (rr & 3) * 256 + cc) =
;                   (unsigned)(l0 & 255) | ((unsigned)(l1 & 255) << 8) | ((unsigned)(l2 & 255) << 16) | ((unsigned)l3 << 24);
;             }
;           }
;           WAIT_L(0); BAR;
;           const int hso = ((brow + ai * HALF + 16 * wave) * DM + pn * BM) * 2;
;           const int lso = (brow + ai * HALF + 16 * wave) * DM + pn * BM;
;           _Pragma("unroll") for (int i = 0; i < 8; ++i) {
;             const u32x4 v = *reinterpret_cast<const u32x4*>(smem + (wave * 8 + i) * PIECE + lane3 * 16);
;             __builtin_amdgcn_raw_buffer_store_b128(v, rsXB, hvo + i * (2 * DM * 2), hso, 0);
;           }
;           _Pragma("unroll") for (int i = 0; i < 4; ++i) {
	v_mov_b32_e32 v214, v2
	v_mov_b32_e32 v215, v3
	v_pk_add_f32 v[6:7], v[76:77], v[2:3] op_sel_hi:[1,0] neg_lo:[0,1] neg_hi:[0,1]
	s_nop 0
	v_pk_mul_f32 v[6:7], v[2:3], v[6:7] op_sel:[1,0]
	v_pk_add_f32 v[64:65], v[78:79], v[2:3] op_sel_hi:[1,0] neg_lo:[0,1] neg_hi:[0,1]
	v_pk_fma_f32 v[6:7], v[100:101], v[6:7], v[104:105]
	v_pk_mul_f32 v[2:3], v[2:3], v[64:65] op_sel:[1,0]
	v_and_b32_sdwa v64, v7, v216 dst_sel:DWORD dst_unused:UNUSED_PAD src0_sel:WORD_1 src1_sel:DWORD
	v_and_b32_sdwa v65, v6, v216 dst_sel:DWORD dst_unused:UNUSED_PAD src0_sel:WORD_1 src1_sel:DWORD
	v_pk_fma_f32 v[2:3], v[0:1], v[2:3], v[4:5]
	v_add3_u32 v66, v7, v64, s84
	v_add3_u32 v64, v6, v65, s84
	v_and_b32_e32 v67, 0xffff0000, v64
	v_and_b32_sdwa v64, v3, v216 dst_sel:DWORD dst_unused:UNUSED_PAD src0_sel:WORD_1 src1_sel:DWORD
	v_and_b32_sdwa v65, v2, v216 dst_sel:DWORD dst_unused:UNUSED_PAD src0_sel:WORD_1 src1_sel:DWORD
	v_add3_u32 v64, v3, v64, s84
	v_add3_u32 v68, v2, v65, s84
	v_and_b32_e32 v69, 0xffff0000, v64
	v_or_b32_sdwa v65, v69, v66 dst_sel:DWORD dst_unused:UNUSED_PAD src0_sel:DWORD src1_sel:WORD_1
	v_or_b32_sdwa v64, v68, v67 dst_sel:DWORD dst_unused:UNUSED_PAD src0_sel:WORD_1 src1_sel:DWORD
	ds_write_b64 v134, v[64:65]
	v_and_b32_e32 v64, 0xffff0000, v68
	v_sub_u32_e32 v2, v2, v64
	v_sub_u32_e32 v6, v6, v67
	v_and_b32_e32 v64, 0xffff0000, v66
	v_add_u32_e32 v6, 0x80, v6
	v_sub_u32_e32 v7, v7, v64
	v_sub_u32_e32 v3, v3, v69
	v_add_u32_e32 v2, 0x80, v2
	v_ashrrev_i32_e32 v6, 8, v6
	v_add_u32_e32 v7, 0x80, v7
	v_add_u32_e32 v3, 0x80, v3
	v_ashrrev_i32_e32 v2, 8, v2
	v_min_i32_e32 v6, 0x7f, v6
	v_ashrrev_i32_e32 v7, 8, v7
	v_ashrrev_i32_e32 v3, 8, v3
	v_min_i32_e32 v2, 0x7f, v2
	v_min_i32_sdwa v7, v7, s85 dst_sel:WORD_1 dst_unused:UNUSED_PAD src0_sel:DWORD src1_sel:DWORD
	v_min_i32_e32 v3, 0x7f, v3
	v_lshlrev_b32_e32 v6, 8, v6
	v_and_b32_e32 v6, 0xff00, v6
	v_and_b32_e32 v7, 0xff0000, v7
	v_perm_b32 v2, v3, v2, s92
	v_or3_b32 v2, v2, v6, v7
	ds_write_b32 v18, v2
	buffer_store_dwordx4 v[140:143], v75, s[16:19], s41 offen
	ds_read_b64 v[2:3], v19 offset:1024
	s_waitcnt lgkmcnt(0)
	v_mov_b32_e32 v252, v2
	v_mov_b32_e32 v253, v3
	v_pk_add_f32 v[6:7], v[82:83], v[2:3] op_sel_hi:[1,0] neg_lo:[0,1] neg_hi:[0,1]
	s_nop 0
	v_pk_mul_f32 v[6:7], v[2:3], v[6:7] op_sel:[1,0]
	v_pk_add_f32 v[64:65], v[86:87], v[2:3] op_sel_hi:[1,0] neg_lo:[0,1] neg_hi:[0,1]
	v_pk_fma_f32 v[6:7], v[100:101], v[6:7], v[104:105]
	v_pk_mul_f32 v[2:3], v[2:3], v[64:65] op_sel:[1,0]
	s_nop 0
	v_pk_fma_f32 v[0:1], v[0:1], v[2:3], v[4:5]
	v_and_b32_sdwa v2, v7, v216 dst_sel:DWORD dst_unused:UNUSED_PAD src0_sel:WORD_1 src1_sel:DWORD
	v_and_b32_sdwa v3, v6, v216 dst_sel:DWORD dst_unused:UNUSED_PAD src0_sel:WORD_1 src1_sel:DWORD
	v_add3_u32 v4, v7, v2, s84
	v_add3_u32 v2, v6, v3, s84
	v_and_b32_e32 v5, 0xffff0000, v2
	v_and_b32_sdwa v2, v1, v216 dst_sel:DWORD dst_unused:UNUSED_PAD src0_sel:WORD_1 src1_sel:DWORD
	v_and_b32_sdwa v3, v0, v216 dst_sel:DWORD dst_unused:UNUSED_PAD src0_sel:WORD_1 src1_sel:DWORD
	v_add3_u32 v2, v1, v2, s84
	v_add3_u32 v64, v0, v3, s84
	v_and_b32_e32 v65, 0xffff0000, v2
	v_or_b32_sdwa v3, v65, v4 dst_sel:DWORD dst_unused:UNUSED_PAD src0_sel:DWORD src1_sel:WORD_1
	v_or_b32_sdwa v2, v64, v5 dst_sel:DWORD dst_unused:UNUSED_PAD src0_sel:WORD_1 src1_sel:DWORD
	ds_write_b64 v135, v[2:3]
	v_and_b32_e32 v2, 0xffff0000, v64
	v_sub_u32_e32 v0, v0, v2
	v_sub_u32_e32 v2, v6, v5
	v_and_b32_e32 v3, 0xffff0000, v4
	v_add_u32_e32 v2, 0x80, v2
	v_sub_u32_e32 v3, v7, v3
	v_sub_u32_e32 v1, v1, v65
	v_add_u32_e32 v0, 0x80, v0
	v_ashrrev_i32_e32 v2, 8, v2
	v_add_u32_e32 v3, 0x80, v3
	v_add_u32_e32 v1, 0x80, v1
	v_ashrrev_i32_e32 v0, 8, v0
	v_min_i32_e32 v2, 0x7f, v2
	v_ashrrev_i32_e32 v3, 8, v3
	v_ashrrev_i32_e32 v1, 8, v1
	v_min_i32_e32 v0, 0x7f, v0
	v_min_i32_sdwa v3, v3, s85 dst_sel:WORD_1 dst_unused:UNUSED_PAD src0_sel:DWORD src1_sel:DWORD
	v_min_i32_e32 v1, 0x7f, v1
	v_lshlrev_b32_e32 v2, 8, v2
	v_and_b32_e32 v2, 0xff00, v2
	v_and_b32_e32 v3, 0xff0000, v3
	v_perm_b32 v0, v1, v0, s92
	v_or3_b32 v0, v0, v2, v3
	ds_write_b32 v22, v0
	buffer_store_dwordx4 v[152:155], v81, s[16:19], s41 offen
	v_mov_b32_e32 v0, v224
	v_mov_b32_e32 v1, v225
	v_mov_b32_e32 v2, v226
	v_mov_b32_e32 v3, v227
	v_mov_b32_e32 v4, v240
	v_mov_b32_e32 v5, v241
	v_mov_b32_e32 v6, v242
	v_mov_b32_e32 v7, v243
	v_mov_b32_e32 v68, v210
	v_mov_b32_e32 v69, v211
	v_pk_add_f32 v[60:61], v[60:61], v[68:69] op_sel_hi:[1,0] neg_lo:[0,1] neg_hi:[0,1]
	s_nop 0
	v_pk_mul_f32 v[60:61], v[68:69], v[60:61] op_sel:[1,0]
	v_pk_add_f32 v[58:59], v[58:59], v[68:69] op_sel_hi:[1,0] neg_lo:[0,1] neg_hi:[0,1]
	v_mov_b32_e32 v64, v1
	v_mov_b32_e32 v65, v2
	v_mov_b32_e32 v66, v5
	v_mov_b32_e32 v67, v6
	v_pk_fma_f32 v[60:61], v[64:65], v[60:61], v[66:67]
	v_pk_mul_f32 v[58:59], v[68:69], v[58:59] op_sel:[1,0]
	v_mov_b32_e32 v1, v3
	v_mov_b32_e32 v5, v7
	v_and_b32_sdwa v6, v61, v216 dst_sel:DWORD dst_unused:UNUSED_PAD src0_sel:WORD_1 src1_sel:DWORD
	v_and_b32_sdwa v7, v60, v216 dst_sel:DWORD dst_unused:UNUSED_PAD src0_sel:WORD_1 src1_sel:DWORD
	v_pk_fma_f32 v[2:3], v[0:1], v[58:59], v[4:5]
	v_add3_u32 v58, v61, v6, s84
	v_add3_u32 v6, v60, v7, s84
	v_and_b32_e32 v59, 0xffff0000, v6
	v_and_b32_sdwa v6, v3, v216 dst_sel:DWORD dst_unused:UNUSED_PAD src0_sel:WORD_1 src1_sel:DWORD
	v_and_b32_sdwa v7, v2, v216 dst_sel:DWORD dst_unused:UNUSED_PAD src0_sel:WORD_1 src1_sel:DWORD
	v_add3_u32 v6, v3, v6, s84
	v_add3_u32 v68, v2, v7, s84
	v_and_b32_e32 v69, 0xffff0000, v6
	v_or_b32_sdwa v7, v69, v58 dst_sel:DWORD dst_unused:UNUSED_PAD src0_sel:DWORD src1_sel:WORD_1
	v_or_b32_sdwa v6, v68, v59 dst_sel:DWORD dst_unused:UNUSED_PAD src0_sel:WORD_1 src1_sel:DWORD
; #define WAIT_L(n) asm volatile("s_waitcnt lgkmcnt(" #n ")" ::: "memory")
;     ...
;         _Pragma("unroll") for (int ai = 0; ai < 2; ++ai) {
;           _Pragma("unroll") for (int bj = 0; bj < 2; ++bj) _Pragma("unroll") for (int n = 0; n < 2; ++n) {
;             const int cc = bj * HALF + wc3 * 32 + n * 16 + fq3 * 4;
;             const float4 gm = *reinterpret_cast<const float4*>(g.gam + pn * BM + cc), bt = *reinterpret_cast<const float4*>(g.bet + pn * BM + cc);
;             _Pragma("unroll") for (int m = 0; m < 4; ++m) {
;               const int rr = wr3 * 64 + m * 16 + fr3;
;               const float2 ms = *reinterpret_cast<const float2*>(mr + (ai * HALF + rr) * 2);
;               f32x4 y = acc[ai][bj][m][n];
;               const float o0 = (y[0] - ms.x) * ms.y * gm.x + bt.x, o1 = (y[1] - ms.x) * ms.y * gm.y + bt.y;
;               const float o2 = (y[2] - ms.x) * ms.y * gm.z + bt.z, o3 = (y[3] - ms.x) * ms.y * gm.w + bt.w;
;               const unsigned h0 = f2bf(o0), h1 = f2bf(o1), h2 = f2bf(o2), h3 = f2bf(o3);
;               u32x2 ob; ob[0] = h0 | (h1 << 16); ob[1] = h2 | (h3 << 16);
;               *reinterpret_cast<u32x2*>(smem + (rr >> 1) * PIECE + (rr & 1) * 512 + cc * 2) = ob;
;               const int l0 = min(((int)__float_as_uint(o0) - (int)(h0 << 16) + 128) >> 8, 127);
;               const int l1 = min(((int)__float_as_uint(o1) - (int)(h1 << 16) + 128) >> 8, 127);
;               const int l2 = min(((int)__float_as_uint(o2) - (int)(h2 << 16) + 128) >> 8, 127);
;               const int l3 = min(((int)__float_as_uint(o3) - (int)(h3 << 16) + 128) >> 8, 127);
;               *reinterpret_cast<unsigned*>(smem + LOBASE + (rr >> 2) * PIECE + (rr & 3) * 256 + cc) =
;                   (unsigned)(l0 & 255) | ((unsigned)(l1 & 255) << 8) | ((unsigned)(l2 & 255) << 16) | ((unsigned)l3 << 24);
;             }
;           }
;           WAIT_L(0); BAR;
;           const int hso = ((brow + ai * HALF + 16 * wave) * DM + pn * BM) * 2;
;           const int lso = (brow + ai * HALF + 16 * wave) * DM + pn * BM;
;           _Pragma("unroll") for (int i = 0; i < 8; ++i) {
;             const u32x4 v = *reinterpret_cast<const u32x4*>(smem + (wave * 8 + i) * PIECE + lane3 * 16);
;             __builtin_amdgcn_raw_buffer_store_b128(v, rsXB, hvo + i * (2 * DM * 2), hso, 0);
;           }
;           _Pragma("unroll") for (int i = 0; i < 4; ++i) {
	ds_write_b64 v23, v[6:7]
	v_and_b32_e32 v6, 0xffff0000, v68
	v_sub_u32_e32 v2, v2, v6
	v_sub_u32_e32 v6, v60, v59
	v_and_b32_e32 v7, 0xffff0000, v58
	v_add_u32_e32 v6, 0x80, v6
	v_sub_u32_e32 v7, v61, v7
	v_sub_u32_e32 v3, v3, v69
	v_add_u32_e32 v2, 0x80, v2
	v_ashrrev_i32_e32 v6, 8, v6
	v_add_u32_e32 v7, 0x80, v7
	v_add_u32_e32 v3, 0x80, v3
	v_ashrrev_i32_e32 v2, 8, v2
	v_min_i32_e32 v6, 0x7f, v6
	v_ashrrev_i32_e32 v7, 8, v7
	v_ashrrev_i32_e32 v3, 8, v3
	v_min_i32_e32 v2, 0x7f, v2
	v_min_i32_sdwa v7, v7, s85 dst_sel:WORD_1 dst_unused:UNUSED_PAD src0_sel:DWORD src1_sel:DWORD
	v_min_i32_e32 v3, 0x7f, v3
	v_lshlrev_b32_e32 v6, 8, v6
	v_and_b32_e32 v6, 0xff00, v6
	v_and_b32_e32 v7, 0xff0000, v7
	v_perm_b32 v2, v3, v2, s92
	v_or3_b32 v2, v2, v6, v7
	ds_write_b32 v12, v2 offset:16
	buffer_store_dwordx4 v[156:159], v84, s[16:19], s41 offen
	v_mov_b32_e32 v2, v212
	v_mov_b32_e32 v3, v213
	v_pk_add_f32 v[6:7], v[44:45], v[2:3] op_sel_hi:[1,0] neg_lo:[0,1] neg_hi:[0,1]
	s_nop 0
	v_pk_mul_f32 v[6:7], v[2:3], v[6:7] op_sel:[1,0]
	v_pk_add_f32 v[42:43], v[42:43], v[2:3] op_sel_hi:[1,0] neg_lo:[0,1] neg_hi:[0,1]
	v_pk_fma_f32 v[6:7], v[64:65], v[6:7], v[66:67]
	v_pk_mul_f32 v[2:3], v[2:3], v[42:43] op_sel:[1,0]
	v_and_b32_sdwa v42, v6, v216 dst_sel:DWORD dst_unused:UNUSED_PAD src0_sel:WORD_1 src1_sel:DWORD
	v_pk_fma_f32 v[2:3], v[0:1], v[2:3], v[4:5]
	v_add3_u32 v42, v6, v42, s84
	v_and_b32_e32 v44, 0xffff0000, v42
	v_and_b32_sdwa v42, v3, v216 dst_sel:DWORD dst_unused:UNUSED_PAD src0_sel:WORD_1 src1_sel:DWORD
	v_and_b32_sdwa v23, v7, v216 dst_sel:DWORD dst_unused:UNUSED_PAD src0_sel:WORD_1 src1_sel:DWORD
	v_and_b32_sdwa v43, v2, v216 dst_sel:DWORD dst_unused:UNUSED_PAD src0_sel:WORD_1 src1_sel:DWORD
	v_add3_u32 v42, v3, v42, s84
	v_add3_u32 v23, v7, v23, s84
	v_add3_u32 v45, v2, v43, s84
	v_and_b32_e32 v58, 0xffff0000, v42
	v_or_b32_sdwa v43, v58, v23 dst_sel:DWORD dst_unused:UNUSED_PAD src0_sel:DWORD src1_sel:WORD_1
	v_or_b32_sdwa v42, v45, v44 dst_sel:DWORD dst_unused:UNUSED_PAD src0_sel:WORD_1 src1_sel:DWORD
	ds_write_b64 v108, v[42:43]
	v_and_b32_e32 v42, 0xffff0000, v45
	v_sub_u32_e32 v6, v6, v44
	v_and_b32_e32 v23, 0xffff0000, v23
	v_sub_u32_e32 v2, v2, v42
	v_add_u32_e32 v6, 0x80, v6
	v_sub_u32_e32 v7, v7, v23
	v_sub_u32_e32 v3, v3, v58
	v_add_u32_e32 v2, 0x80, v2
	v_ashrrev_i32_e32 v6, 8, v6
	v_add_u32_e32 v7, 0x80, v7
	v_add_u32_e32 v3, 0x80, v3
	v_ashrrev_i32_e32 v2, 8, v2
	v_min_i32_e32 v6, 0x7f, v6
	v_ashrrev_i32_e32 v7, 8, v7
	v_ashrrev_i32_e32 v3, 8, v3
	v_min_i32_e32 v2, 0x7f, v2
	v_min_i32_sdwa v7, v7, s85 dst_sel:WORD_1 dst_unused:UNUSED_PAD src0_sel:DWORD src1_sel:DWORD
	v_min_i32_e32 v3, 0x7f, v3
	v_lshlrev_b32_e32 v6, 8, v6
	v_and_b32_e32 v6, 0xff00, v6
	v_and_b32_e32 v7, 0xff0000, v7
	v_perm_b32 v2, v3, v2, s92
	v_or3_b32 v2, v2, v6, v7
	ds_write_b32 v14, v2 offset:16
	buffer_store_dwordx4 v[160:163], v85, s[16:19], s41 offen
	v_mov_b32_e32 v2, v214
	v_mov_b32_e32 v3, v215
	v_pk_add_f32 v[6:7], v[34:35], v[2:3] op_sel_hi:[1,0] neg_lo:[0,1] neg_hi:[0,1]
	s_nop 0
	v_pk_mul_f32 v[6:7], v[2:3], v[6:7] op_sel:[1,0]
	v_pk_add_f32 v[34:35], v[46:47], v[2:3] op_sel_hi:[1,0] neg_lo:[0,1] neg_hi:[0,1]
	v_pk_fma_f32 v[6:7], v[64:65], v[6:7], v[66:67]
	v_pk_mul_f32 v[2:3], v[2:3], v[34:35] op_sel:[1,0]
	v_and_b32_sdwa v34, v6, v216 dst_sel:DWORD dst_unused:UNUSED_PAD src0_sel:WORD_1 src1_sel:DWORD
	v_pk_fma_f32 v[2:3], v[0:1], v[2:3], v[4:5]
	v_add3_u32 v34, v6, v34, s84
	v_and_b32_e32 v42, 0xffff0000, v34
	v_and_b32_sdwa v34, v3, v216 dst_sel:DWORD dst_unused:UNUSED_PAD src0_sel:WORD_1 src1_sel:DWORD
	v_and_b32_sdwa v23, v7, v216 dst_sel:DWORD dst_unused:UNUSED_PAD src0_sel:WORD_1 src1_sel:DWORD
	v_and_b32_sdwa v35, v2, v216 dst_sel:DWORD dst_unused:UNUSED_PAD src0_sel:WORD_1 src1_sel:DWORD
	v_add3_u32 v34, v3, v34, s84
	v_add3_u32 v23, v7, v23, s84
	v_add3_u32 v43, v2, v35, s84
	v_and_b32_e32 v44, 0xffff0000, v34
	v_or_b32_sdwa v35, v44, v23 dst_sel:DWORD dst_unused:UNUSED_PAD src0_sel:DWORD src1_sel:WORD_1
	v_or_b32_sdwa v34, v43, v42 dst_sel:DWORD dst_unused:UNUSED_PAD src0_sel:WORD_1 src1_sel:DWORD
	ds_write_b64 v98, v[34:35]
	v_and_b32_e32 v34, 0xffff0000, v43
	v_sub_u32_e32 v6, v6, v42
	v_and_b32_e32 v23, 0xffff0000, v23
	v_sub_u32_e32 v2, v2, v34
	v_add_u32_e32 v6, 0x80, v6
	v_sub_u32_e32 v7, v7, v23
	v_sub_u32_e32 v3, v3, v44
	v_add_u32_e32 v2, 0x80, v2
	v_ashrrev_i32_e32 v6, 8, v6
	v_add_u32_e32 v7, 0x80, v7
	v_add_u32_e32 v3, 0x80, v3
	v_ashrrev_i32_e32 v2, 8, v2
	v_min_i32_e32 v6, 0x7f, v6
	v_ashrrev_i32_e32 v7, 8, v7
	v_ashrrev_i32_e32 v3, 8, v3
	v_min_i32_e32 v2, 0x7f, v2
	v_min_i32_sdwa v7, v7, s85 dst_sel:WORD_1 dst_unused:UNUSED_PAD src0_sel:DWORD src1_sel:DWORD
	v_min_i32_e32 v3, 0x7f, v3
	v_lshlrev_b32_e32 v6, 8, v6
	v_and_b32_e32 v6, 0xff00, v6
	v_and_b32_e32 v7, 0xff0000, v7
	v_perm_b32 v2, v3, v2, s92
	v_or3_b32 v2, v2, v6, v7
	ds_write_b32 v18, v2 offset:16
	buffer_store_dwordx4 v[164:167], v88, s[16:19], s41 offen
	v_mov_b32_e32 v2, v252
	v_mov_b32_e32 v3, v253
	v_pk_add_f32 v[6:7], v[50:51], v[2:3] op_sel_hi:[1,0] neg_lo:[0,1] neg_hi:[0,1]
	s_nop 0
	v_pk_mul_f32 v[6:7], v[2:3], v[6:7] op_sel:[1,0]
	v_pk_add_f32 v[34:35], v[62:63], v[2:3] op_sel_hi:[1,0] neg_lo:[0,1] neg_hi:[0,1]
	v_pk_fma_f32 v[6:7], v[64:65], v[6:7], v[66:67]
	v_pk_mul_f32 v[2:3], v[2:3], v[34:35] op_sel:[1,0]
	s_nop 0
	v_pk_fma_f32 v[0:1], v[0:1], v[2:3], v[4:5]
	v_and_b32_sdwa v2, v7, v216 dst_sel:DWORD dst_unused:UNUSED_PAD src0_sel:WORD_1 src1_sel:DWORD
	v_and_b32_sdwa v3, v6, v216 dst_sel:DWORD dst_unused:UNUSED_PAD src0_sel:WORD_1 src1_sel:DWORD
	v_add3_u32 v4, v7, v2, s84
	v_add3_u32 v2, v6, v3, s84
	v_and_b32_e32 v5, 0xffff0000, v2
; #define WAIT_L(n) asm volatile("s_waitcnt lgkmcnt(" #n ")" ::: "memory")
;     ...
;         _Pragma("unroll") for (int ai = 0; ai < 2; ++ai) {
;           _Pragma("unroll") for (int bj = 0; bj < 2; ++bj) _Pragma("unroll") for (int n = 0; n < 2; ++n) {
;             const int cc = bj * HALF + wc3 * 32 + n * 16 + fq3 * 4;
;             const float4 gm = *reinterpret_cast<const float4*>(g.gam + pn * BM + cc), bt = *reinterpret_cast<const float4*>(g.bet + pn * BM + cc);
;             _Pragma("unroll") for (int m = 0; m < 4; ++m) {
;               const int rr = wr3 * 64 + m * 16 + fr3;
;               const float2 ms = *reinterpret_cast<const float2*>(mr + (ai * HALF + rr) * 2);
;               f32x4 y = acc[ai][bj][m][n];
;               const float o0 = (y[0] - ms.x) * ms.y * gm.x + bt.x, o1 = (y[1] - ms.x) * ms.y * gm.y + bt.y;
;               const float o2 = (y[2] - ms.x) * ms.y * gm.z + bt.z, o3 = (y[3] - ms.x) * ms.y * gm.w + bt.w;
;               const unsigned h0 = f2bf(o0), h1 = f2bf(o1), h2 = f2bf(o2), h3 = f2bf(o3);
;               u32x2 ob; ob[0] = h0 | (h1 << 16); ob[1] = h2 | (h3 << 16);
;               *reinterpret_cast<u32x2*>(smem + (rr >> 1) * PIECE + (rr & 1) * 512 + cc * 2) = ob;
;               const int l0 = min(((int)__float_as_uint(o0) - (int)(h0 << 16) + 128) >> 8, 127);
;               const int l1 = min(((int)__float_as_uint(o1) - (int)(h1 << 16) + 128) >> 8, 127);
;               const int l2 = min(((int)__float_as_uint(o2) - (int)(h2 << 16) + 128) >> 8, 127);
;               const int l3 = min(((int)__float_as_uint(o3) - (int)(h3 << 16) + 128) >> 8, 127);
;               *reinterpret_cast<unsigned*>(smem + LOBASE + (rr >> 2) * PIECE + (rr & 3) * 256 + cc) =
;                   (unsigned)(l0 & 255) | ((unsigned)(l1 & 255) << 8) | ((unsigned)(l2 & 255) << 16) | ((unsigned)l3 << 24);
;             }
;           }
;           WAIT_L(0); BAR;
;           const int hso = ((brow + ai * HALF + 16 * wave) * DM + pn * BM) * 2;
;           const int lso = (brow + ai * HALF + 16 * wave) * DM + pn * BM;
;           _Pragma("unroll") for (int i = 0; i < 8; ++i) {
;             const u32x4 v = *reinterpret_cast<const u32x4*>(smem + (wave * 8 + i) * PIECE + lane3 * 16);
;             __builtin_amdgcn_raw_buffer_store_b128(v, rsXB, hvo + i * (2 * DM * 2), hso, 0);
;           }
;           _Pragma("unroll") for (int i = 0; i < 4; ++i) {
	v_and_b32_sdwa v2, v1, v216 dst_sel:DWORD dst_unused:UNUSED_PAD src0_sel:WORD_1 src1_sel:DWORD
	v_and_b32_sdwa v3, v0, v216 dst_sel:DWORD dst_unused:UNUSED_PAD src0_sel:WORD_1 src1_sel:DWORD
	v_add3_u32 v2, v1, v2, s84
	v_add3_u32 v23, v0, v3, s84
	v_and_b32_e32 v34, 0xffff0000, v2
	v_or_b32_sdwa v3, v34, v4 dst_sel:DWORD dst_unused:UNUSED_PAD src0_sel:DWORD src1_sel:WORD_1
	v_or_b32_sdwa v2, v23, v5 dst_sel:DWORD dst_unused:UNUSED_PAD src0_sel:WORD_1 src1_sel:DWORD
	ds_write_b64 v99, v[2:3]
	v_and_b32_e32 v2, 0xffff0000, v23
	v_sub_u32_e32 v0, v0, v2
	v_sub_u32_e32 v2, v6, v5
	v_and_b32_e32 v3, 0xffff0000, v4
	v_add_u32_e32 v2, 0x80, v2
	v_sub_u32_e32 v3, v7, v3
	v_sub_u32_e32 v1, v1, v34
	v_add_u32_e32 v0, 0x80, v0
	v_ashrrev_i32_e32 v2, 8, v2
	v_add_u32_e32 v3, 0x80, v3
	v_add_u32_e32 v1, 0x80, v1
	v_ashrrev_i32_e32 v0, 8, v0
	v_min_i32_e32 v2, 0x7f, v2
	v_ashrrev_i32_e32 v3, 8, v3
	v_ashrrev_i32_e32 v1, 8, v1
	v_min_i32_e32 v0, 0x7f, v0
	v_min_i32_sdwa v3, v3, s85 dst_sel:WORD_1 dst_unused:UNUSED_PAD src0_sel:DWORD src1_sel:DWORD
	v_min_i32_e32 v1, 0x7f, v1
	v_lshlrev_b32_e32 v2, 8, v2
	v_and_b32_e32 v2, 0xff00, v2
	v_and_b32_e32 v3, 0xff0000, v3
	v_perm_b32 v0, v1, v0, s92
	v_or3_b32 v0, v0, v2, v3
	ds_write_b32 v22, v0 offset:16
	buffer_store_dwordx4 v[168:171], v89, s[16:19], s41 offen
	v_mov_b32_e32 v0, v228
	v_mov_b32_e32 v1, v229
	v_mov_b32_e32 v2, v230
	v_mov_b32_e32 v3, v231
	v_mov_b32_e32 v4, v244
	v_mov_b32_e32 v5, v245
	v_mov_b32_e32 v6, v246
	v_mov_b32_e32 v7, v247
	v_mov_b32_e32 v44, v210
	v_mov_b32_e32 v45, v211
	v_pk_add_f32 v[46:47], v[56:57], v[44:45] op_sel_hi:[1,0] neg_lo:[0,1] neg_hi:[0,1]
	s_nop 0
	v_pk_mul_f32 v[46:47], v[44:45], v[46:47] op_sel:[1,0]
	v_pk_add_f32 v[50:51], v[54:55], v[44:45] op_sel_hi:[1,0] neg_lo:[0,1] neg_hi:[0,1]
	v_mov_b32_e32 v34, v1
	v_mov_b32_e32 v35, v2
	v_mov_b32_e32 v42, v5
	v_mov_b32_e32 v43, v6
	v_pk_fma_f32 v[46:47], v[34:35], v[46:47], v[42:43]
	v_pk_mul_f32 v[44:45], v[44:45], v[50:51] op_sel:[1,0]
	v_mov_b32_e32 v1, v3
	v_mov_b32_e32 v5, v7
	v_and_b32_sdwa v6, v47, v216 dst_sel:DWORD dst_unused:UNUSED_PAD src0_sel:WORD_1 src1_sel:DWORD
	v_and_b32_sdwa v7, v46, v216 dst_sel:DWORD dst_unused:UNUSED_PAD src0_sel:WORD_1 src1_sel:DWORD
	v_pk_fma_f32 v[2:3], v[0:1], v[44:45], v[4:5]
	v_add3_u32 v23, v47, v6, s84
	v_add3_u32 v6, v46, v7, s84
	v_and_b32_e32 v44, 0xffff0000, v6
	v_and_b32_sdwa v6, v3, v216 dst_sel:DWORD dst_unused:UNUSED_PAD src0_sel:WORD_1 src1_sel:DWORD
	v_and_b32_sdwa v7, v2, v216 dst_sel:DWORD dst_unused:UNUSED_PAD src0_sel:WORD_1 src1_sel:DWORD
	v_add3_u32 v6, v3, v6, s84
	v_add3_u32 v45, v2, v7, s84
	v_and_b32_e32 v50, 0xffff0000, v6
	v_or_b32_sdwa v7, v50, v23 dst_sel:DWORD dst_unused:UNUSED_PAD src0_sel:DWORD src1_sel:WORD_1
	v_or_b32_sdwa v6, v45, v44 dst_sel:DWORD dst_unused:UNUSED_PAD src0_sel:WORD_1 src1_sel:DWORD
	ds_write_b64 v106, v[6:7]
	v_and_b32_e32 v6, 0xffff0000, v45
	v_sub_u32_e32 v2, v2, v6
	v_sub_u32_e32 v6, v46, v44
	v_and_b32_e32 v7, 0xffff0000, v23
	v_add_u32_e32 v6, 0x80, v6
	v_sub_u32_e32 v7, v47, v7
	v_sub_u32_e32 v3, v3, v50
	v_add_u32_e32 v2, 0x80, v2
	v_ashrrev_i32_e32 v6, 8, v6
	v_add_u32_e32 v7, 0x80, v7
	v_add_u32_e32 v3, 0x80, v3
	v_ashrrev_i32_e32 v2, 8, v2
	v_min_i32_e32 v6, 0x7f, v6
	v_ashrrev_i32_e32 v7, 8, v7
	v_ashrrev_i32_e32 v3, 8, v3
	v_min_i32_e32 v2, 0x7f, v2
	v_min_i32_sdwa v7, v7, s85 dst_sel:WORD_1 dst_unused:UNUSED_PAD src0_sel:DWORD src1_sel:DWORD
	v_min_i32_e32 v3, 0x7f, v3
	v_lshlrev_b32_e32 v6, 8, v6
	v_and_b32_e32 v6, 0xff00, v6
	v_and_b32_e32 v7, 0xff0000, v7
	v_perm_b32 v2, v3, v2, s92
	v_or3_b32 v2, v2, v6, v7
	ds_write_b32 v12, v2 offset:128
	buffer_store_dwordx4 v[172:175], v146, s[20:23], s1 offen
	v_mov_b32_e32 v2, v212
	v_mov_b32_e32 v3, v213
	v_pk_add_f32 v[6:7], v[40:41], v[2:3] op_sel_hi:[1,0] neg_lo:[0,1] neg_hi:[0,1]
	s_nop 0
	v_pk_mul_f32 v[6:7], v[2:3], v[6:7] op_sel:[1,0]
	v_pk_add_f32 v[38:39], v[38:39], v[2:3] op_sel_hi:[1,0] neg_lo:[0,1] neg_hi:[0,1]
	v_pk_fma_f32 v[6:7], v[34:35], v[6:7], v[42:43]
	v_pk_mul_f32 v[2:3], v[2:3], v[38:39] op_sel:[1,0]
	v_and_b32_sdwa v38, v6, v216 dst_sel:DWORD dst_unused:UNUSED_PAD src0_sel:WORD_1 src1_sel:DWORD
	v_pk_fma_f32 v[2:3], v[0:1], v[2:3], v[4:5]
	v_add3_u32 v38, v6, v38, s84
	v_and_b32_e32 v40, 0xffff0000, v38
	v_and_b32_sdwa v38, v3, v216 dst_sel:DWORD dst_unused:UNUSED_PAD src0_sel:WORD_1 src1_sel:DWORD
	v_and_b32_sdwa v23, v7, v216 dst_sel:DWORD dst_unused:UNUSED_PAD src0_sel:WORD_1 src1_sel:DWORD
	v_and_b32_sdwa v39, v2, v216 dst_sel:DWORD dst_unused:UNUSED_PAD src0_sel:WORD_1 src1_sel:DWORD
	v_add3_u32 v38, v3, v38, s84
	v_add3_u32 v23, v7, v23, s84
	v_add3_u32 v41, v2, v39, s84
	v_and_b32_e32 v44, 0xffff0000, v38
	v_or_b32_sdwa v39, v44, v23 dst_sel:DWORD dst_unused:UNUSED_PAD src0_sel:DWORD src1_sel:WORD_1
	v_or_b32_sdwa v38, v41, v40 dst_sel:DWORD dst_unused:UNUSED_PAD src0_sel:WORD_1 src1_sel:DWORD
	ds_write_b64 v102, v[38:39]
	v_and_b32_e32 v38, 0xffff0000, v41
	v_sub_u32_e32 v6, v6, v40
	v_and_b32_e32 v23, 0xffff0000, v23
	v_sub_u32_e32 v2, v2, v38
	v_add_u32_e32 v6, 0x80, v6
	v_sub_u32_e32 v7, v7, v23
	v_sub_u32_e32 v3, v3, v44
	v_add_u32_e32 v2, 0x80, v2
	v_ashrrev_i32_e32 v6, 8, v6
	v_add_u32_e32 v7, 0x80, v7
	v_add_u32_e32 v3, 0x80, v3
	v_ashrrev_i32_e32 v2, 8, v2
	v_min_i32_e32 v6, 0x7f, v6
	v_ashrrev_i32_e32 v7, 8, v7
	v_ashrrev_i32_e32 v3, 8, v3
	v_min_i32_e32 v2, 0x7f, v2
	v_min_i32_sdwa v7, v7, s85 dst_sel:WORD_1 dst_unused:UNUSED_PAD src0_sel:DWORD src1_sel:DWORD
	v_min_i32_e32 v3, 0x7f, v3
	v_lshlrev_b32_e32 v6, 8, v6
	v_and_b32_e32 v6, 0xff00, v6
	v_and_b32_e32 v7, 0xff0000, v7
	v_perm_b32 v2, v3, v2, s92
	v_or3_b32 v2, v2, v6, v7
; #define WAIT_L(n) asm volatile("s_waitcnt lgkmcnt(" #n ")" ::: "memory")
;     ...
;         _Pragma("unroll") for (int ai = 0; ai < 2; ++ai) {
;           _Pragma("unroll") for (int bj = 0; bj < 2; ++bj) _Pragma("unroll") for (int n = 0; n < 2; ++n) {
;             const int cc = bj * HALF + wc3 * 32 + n * 16 + fq3 * 4;
;             const float4 gm = *reinterpret_cast<const float4*>(g.gam + pn * BM + cc), bt = *reinterpret_cast<const float4*>(g.bet + pn * BM + cc);
;             _Pragma("unroll") for (int m = 0; m < 4; ++m) {
;               const int rr = wr3 * 64 + m * 16 + fr3;
;               const float2 ms = *reinterpret_cast<const float2*>(mr + (ai * HALF + rr) * 2);
;               f32x4 y = acc[ai][bj][m][n];
;               const float o0 = (y[0] - ms.x) * ms.y * gm.x + bt.x, o1 = (y[1] - ms.x) * ms.y * gm.y + bt.y;
;               const float o2 = (y[2] - ms.x) * ms.y * gm.z + bt.z, o3 = (y[3] - ms.x) * ms.y * gm.w + bt.w;
;               const unsigned h0 = f2bf(o0), h1 = f2bf(o1), h2 = f2bf(o2), h3 = f2bf(o3);
;               u32x2 ob; ob[0] = h0 | (h1 << 16); ob[1] = h2 | (h3 << 16);
;               *reinterpret_cast<u32x2*>(smem + (rr >> 1) * PIECE + (rr & 1) * 512 + cc * 2) = ob;
;               const int l0 = min(((int)__float_as_uint(o0) - (int)(h0 << 16) + 128) >> 8, 127);
;               const int l1 = min(((int)__float_as_uint(o1) - (int)(h1 << 16) + 128) >> 8, 127);
;               const int l2 = min(((int)__float_as_uint(o2) - (int)(h2 << 16) + 128) >> 8, 127);
;               const int l3 = min(((int)__float_as_uint(o3) - (int)(h3 << 16) + 128) >> 8, 127);
;               *reinterpret_cast<unsigned*>(smem + LOBASE + (rr >> 2) * PIECE + (rr & 3) * 256 + cc) =
;                   (unsigned)(l0 & 255) | ((unsigned)(l1 & 255) << 8) | ((unsigned)(l2 & 255) << 16) | ((unsigned)l3 << 24);
;             }
;           }
;           WAIT_L(0); BAR;
;           const int hso = ((brow + ai * HALF + 16 * wave) * DM + pn * BM) * 2;
;           const int lso = (brow + ai * HALF + 16 * wave) * DM + pn * BM;
;           _Pragma("unroll") for (int i = 0; i < 8; ++i) {
;             const u32x4 v = *reinterpret_cast<const u32x4*>(smem + (wave * 8 + i) * PIECE + lane3 * 16);
;             __builtin_amdgcn_raw_buffer_store_b128(v, rsXB, hvo + i * (2 * DM * 2), hso, 0);
;           }
;           _Pragma("unroll") for (int i = 0; i < 4; ++i) {
	ds_write_b32 v14, v2 offset:128
	buffer_store_dwordx4 v[176:179], v90, s[20:23], s1 offen
	v_mov_b32_e32 v2, v214
	v_mov_b32_e32 v3, v215
	v_pk_add_f32 v[6:7], v[24:25], v[2:3] op_sel_hi:[1,0] neg_lo:[0,1] neg_hi:[0,1]
	s_nop 0
	v_pk_mul_f32 v[6:7], v[2:3], v[6:7] op_sel:[1,0]
	v_pk_add_f32 v[24:25], v[26:27], v[2:3] op_sel_hi:[1,0] neg_lo:[0,1] neg_hi:[0,1]
	v_pk_fma_f32 v[6:7], v[34:35], v[6:7], v[42:43]
	v_pk_mul_f32 v[2:3], v[2:3], v[24:25] op_sel:[1,0]
	v_and_b32_sdwa v24, v6, v216 dst_sel:DWORD dst_unused:UNUSED_PAD src0_sel:WORD_1 src1_sel:DWORD
	v_pk_fma_f32 v[2:3], v[0:1], v[2:3], v[4:5]
	v_add3_u32 v24, v6, v24, s84
	v_and_b32_e32 v26, 0xffff0000, v24
	v_and_b32_sdwa v24, v3, v216 dst_sel:DWORD dst_unused:UNUSED_PAD src0_sel:WORD_1 src1_sel:DWORD
	v_and_b32_sdwa v23, v7, v216 dst_sel:DWORD dst_unused:UNUSED_PAD src0_sel:WORD_1 src1_sel:DWORD
	v_and_b32_sdwa v25, v2, v216 dst_sel:DWORD dst_unused:UNUSED_PAD src0_sel:WORD_1 src1_sel:DWORD
	v_add3_u32 v24, v3, v24, s84
	v_add3_u32 v23, v7, v23, s84
	v_add3_u32 v27, v2, v25, s84
	v_and_b32_e32 v38, 0xffff0000, v24
	v_or_b32_sdwa v25, v38, v23 dst_sel:DWORD dst_unused:UNUSED_PAD src0_sel:DWORD src1_sel:WORD_1
	v_or_b32_sdwa v24, v27, v26 dst_sel:DWORD dst_unused:UNUSED_PAD src0_sel:WORD_1 src1_sel:DWORD
	ds_write_b64 v92, v[24:25]
	v_and_b32_e32 v24, 0xffff0000, v27
	v_sub_u32_e32 v6, v6, v26
	v_and_b32_e32 v23, 0xffff0000, v23
	v_sub_u32_e32 v2, v2, v24
	v_add_u32_e32 v6, 0x80, v6
	v_sub_u32_e32 v7, v7, v23
	v_sub_u32_e32 v3, v3, v38
	v_add_u32_e32 v2, 0x80, v2
	v_ashrrev_i32_e32 v6, 8, v6
	v_add_u32_e32 v7, 0x80, v7
	v_add_u32_e32 v3, 0x80, v3
	v_ashrrev_i32_e32 v2, 8, v2
	v_min_i32_e32 v6, 0x7f, v6
	v_ashrrev_i32_e32 v7, 8, v7
	v_ashrrev_i32_e32 v3, 8, v3
	v_min_i32_e32 v2, 0x7f, v2
	v_min_i32_sdwa v7, v7, s85 dst_sel:WORD_1 dst_unused:UNUSED_PAD src0_sel:DWORD src1_sel:DWORD
	v_min_i32_e32 v3, 0x7f, v3
	v_lshlrev_b32_e32 v6, 8, v6
	v_and_b32_e32 v6, 0xff00, v6
	v_and_b32_e32 v7, 0xff0000, v7
	v_perm_b32 v2, v3, v2, s92
	v_or3_b32 v2, v2, v6, v7
	ds_write_b32 v18, v2 offset:128
	buffer_store_dwordx4 v[180:183], v91, s[20:23], s1 offen
	v_mov_b32_e32 v2, v252
	v_mov_b32_e32 v3, v253
	v_pk_add_f32 v[6:7], v[28:29], v[2:3] op_sel_hi:[1,0] neg_lo:[0,1] neg_hi:[0,1]
	s_nop 0
	v_pk_mul_f32 v[6:7], v[2:3], v[6:7] op_sel:[1,0]
	v_pk_add_f32 v[24:25], v[30:31], v[2:3] op_sel_hi:[1,0] neg_lo:[0,1] neg_hi:[0,1]
	v_pk_fma_f32 v[6:7], v[34:35], v[6:7], v[42:43]
	v_pk_mul_f32 v[2:3], v[2:3], v[24:25] op_sel:[1,0]
	s_nop 0
	v_pk_fma_f32 v[0:1], v[0:1], v[2:3], v[4:5]
	v_and_b32_sdwa v2, v7, v216 dst_sel:DWORD dst_unused:UNUSED_PAD src0_sel:WORD_1 src1_sel:DWORD
	v_and_b32_sdwa v3, v6, v216 dst_sel:DWORD dst_unused:UNUSED_PAD src0_sel:WORD_1 src1_sel:DWORD
	v_add3_u32 v4, v7, v2, s84
	v_add3_u32 v2, v6, v3, s84
	v_and_b32_e32 v5, 0xffff0000, v2
	v_and_b32_sdwa v2, v1, v216 dst_sel:DWORD dst_unused:UNUSED_PAD src0_sel:WORD_1 src1_sel:DWORD
	v_and_b32_sdwa v3, v0, v216 dst_sel:DWORD dst_unused:UNUSED_PAD src0_sel:WORD_1 src1_sel:DWORD
	v_add3_u32 v2, v1, v2, s84
	v_add3_u32 v23, v0, v3, s84
	v_and_b32_e32 v24, 0xffff0000, v2
	v_or_b32_sdwa v3, v24, v4 dst_sel:DWORD dst_unused:UNUSED_PAD src0_sel:DWORD src1_sel:WORD_1
	v_or_b32_sdwa v2, v23, v5 dst_sel:DWORD dst_unused:UNUSED_PAD src0_sel:WORD_1 src1_sel:DWORD
	ds_write_b64 v93, v[2:3]
	v_and_b32_e32 v2, 0xffff0000, v23
	v_sub_u32_e32 v0, v0, v2
	v_sub_u32_e32 v2, v6, v5
	v_and_b32_e32 v3, 0xffff0000, v4
	v_add_u32_e32 v2, 0x80, v2
	v_sub_u32_e32 v3, v7, v3
	v_sub_u32_e32 v1, v1, v24
	v_add_u32_e32 v0, 0x80, v0
	v_ashrrev_i32_e32 v2, 8, v2
	v_add_u32_e32 v3, 0x80, v3
	v_add_u32_e32 v1, 0x80, v1
	v_ashrrev_i32_e32 v0, 8, v0
	v_min_i32_e32 v2, 0x7f, v2
	v_ashrrev_i32_e32 v3, 8, v3
	v_ashrrev_i32_e32 v1, 8, v1
	v_min_i32_e32 v0, 0x7f, v0
	v_min_i32_sdwa v3, v3, s85 dst_sel:WORD_1 dst_unused:UNUSED_PAD src0_sel:DWORD src1_sel:DWORD
	v_min_i32_e32 v1, 0x7f, v1
	v_lshlrev_b32_e32 v2, 8, v2
	v_and_b32_e32 v2, 0xff00, v2
	v_and_b32_e32 v3, 0xff0000, v3
	v_perm_b32 v0, v1, v0, s92
	v_or3_b32 v0, v0, v2, v3
	ds_write_b32 v22, v0 offset:128
	buffer_store_dwordx4 v[184:187], v96, s[20:23], s1 offen
	v_mov_b32_e32 v0, v232
	v_mov_b32_e32 v1, v233
	v_mov_b32_e32 v2, v234
	v_mov_b32_e32 v3, v235
	v_mov_b32_e32 v4, v248
	v_mov_b32_e32 v5, v249
	v_mov_b32_e32 v6, v250
	v_mov_b32_e32 v7, v251
	v_mov_b32_e32 v28, v210
	v_mov_b32_e32 v29, v211
	s_mov_b64 s[4:5], -1
	v_pk_add_f32 v[30:31], v[52:53], v[28:29] op_sel_hi:[1,0] neg_lo:[0,1] neg_hi:[0,1]
	s_nop 0
	v_pk_mul_f32 v[30:31], v[28:29], v[30:31] op_sel:[1,0]
	v_pk_add_f32 v[34:35], v[48:49], v[28:29] op_sel_hi:[1,0] neg_lo:[0,1] neg_hi:[0,1]
	v_mov_b32_e32 v24, v1
	v_mov_b32_e32 v25, v2
	v_mov_b32_e32 v26, v5
	v_mov_b32_e32 v27, v6
	v_pk_fma_f32 v[30:31], v[24:25], v[30:31], v[26:27]
	v_pk_mul_f32 v[28:29], v[28:29], v[34:35] op_sel:[1,0]
	v_mov_b32_e32 v1, v3
	v_mov_b32_e32 v5, v7
	v_and_b32_sdwa v6, v31, v216 dst_sel:DWORD dst_unused:UNUSED_PAD src0_sel:WORD_1 src1_sel:DWORD
	v_and_b32_sdwa v7, v30, v216 dst_sel:DWORD dst_unused:UNUSED_PAD src0_sel:WORD_1 src1_sel:DWORD
	v_pk_fma_f32 v[2:3], v[0:1], v[28:29], v[4:5]
	v_add3_u32 v23, v31, v6, s84
	v_add3_u32 v6, v30, v7, s84
	v_and_b32_e32 v28, 0xffff0000, v6
	v_and_b32_sdwa v6, v3, v216 dst_sel:DWORD dst_unused:UNUSED_PAD src0_sel:WORD_1 src1_sel:DWORD
	v_and_b32_sdwa v7, v2, v216 dst_sel:DWORD dst_unused:UNUSED_PAD src0_sel:WORD_1 src1_sel:DWORD
	v_add3_u32 v6, v3, v6, s84
	v_add3_u32 v29, v2, v7, s84
	v_and_b32_e32 v34, 0xffff0000, v6
	v_or_b32_sdwa v7, v34, v23 dst_sel:DWORD dst_unused:UNUSED_PAD src0_sel:DWORD src1_sel:WORD_1
; #define WAIT_L(n) asm volatile("s_waitcnt lgkmcnt(" #n ")" ::: "memory")
; #define BAR __builtin_amdgcn_s_barrier()
;     ...
;         _Pragma("unroll") for (int ai = 0; ai < 2; ++ai) {
;           _Pragma("unroll") for (int bj = 0; bj < 2; ++bj) _Pragma("unroll") for (int n = 0; n < 2; ++n) {
;             const int cc = bj * HALF + wc3 * 32 + n * 16 + fq3 * 4;
;             const float4 gm = *reinterpret_cast<const float4*>(g.gam + pn * BM + cc), bt = *reinterpret_cast<const float4*>(g.bet + pn * BM + cc);
;             _Pragma("unroll") for (int m = 0; m < 4; ++m) {
;               const int rr = wr3 * 64 + m * 16 + fr3;
;               const float2 ms = *reinterpret_cast<const float2*>(mr + (ai * HALF + rr) * 2);
;               f32x4 y = acc[ai][bj][m][n];
;               const float o0 = (y[0] - ms.x) * ms.y * gm.x + bt.x, o1 = (y[1] - ms.x) * ms.y * gm.y + bt.y;
;               const float o2 = (y[2] - ms.x) * ms.y * gm.z + bt.z, o3 = (y[3] - ms.x) * ms.y * gm.w + bt.w;
;               const unsigned h0 = f2bf(o0), h1 = f2bf(o1), h2 = f2bf(o2), h3 = f2bf(o3);
;               u32x2 ob; ob[0] = h0 | (h1 << 16); ob[1] = h2 | (h3 << 16);
;               *reinterpret_cast<u32x2*>(smem + (rr >> 1) * PIECE + (rr & 1) * 512 + cc * 2) = ob;
;               const int l0 = min(((int)__float_as_uint(o0) - (int)(h0 << 16) + 128) >> 8, 127);
;               const int l1 = min(((int)__float_as_uint(o1) - (int)(h1 << 16) + 128) >> 8, 127);
;               const int l2 = min(((int)__float_as_uint(o2) - (int)(h2 << 16) + 128) >> 8, 127);
;               const int l3 = min(((int)__float_as_uint(o3) - (int)(h3 << 16) + 128) >> 8, 127);
;               *reinterpret_cast<unsigned*>(smem + LOBASE + (rr >> 2) * PIECE + (rr & 3) * 256 + cc) =
;                   (unsigned)(l0 & 255) | ((unsigned)(l1 & 255) << 8) | ((unsigned)(l2 & 255) << 16) | ((unsigned)l3 << 24);
;             }
;           }
;           WAIT_L(0); BAR;
	v_or_b32_sdwa v6, v29, v28 dst_sel:DWORD dst_unused:UNUSED_PAD src0_sel:WORD_1 src1_sel:DWORD
	ds_write_b64 v94, v[6:7]
	v_and_b32_e32 v6, 0xffff0000, v29
	v_sub_u32_e32 v2, v2, v6
	v_sub_u32_e32 v6, v30, v28
	v_and_b32_e32 v7, 0xffff0000, v23
	v_add_u32_e32 v6, 0x80, v6
	v_sub_u32_e32 v7, v31, v7
	v_sub_u32_e32 v3, v3, v34
	v_add_u32_e32 v2, 0x80, v2
	v_ashrrev_i32_e32 v6, 8, v6
	v_add_u32_e32 v7, 0x80, v7
	v_add_u32_e32 v3, 0x80, v3
	v_ashrrev_i32_e32 v2, 8, v2
	v_min_i32_e32 v6, 0x7f, v6
	v_ashrrev_i32_e32 v7, 8, v7
	v_ashrrev_i32_e32 v3, 8, v3
	v_min_i32_e32 v2, 0x7f, v2
	v_min_i32_sdwa v7, v7, s85 dst_sel:WORD_1 dst_unused:UNUSED_PAD src0_sel:DWORD src1_sel:DWORD
	v_min_i32_e32 v3, 0x7f, v3
	v_lshlrev_b32_e32 v6, 8, v6
	v_and_b32_e32 v6, 0xff00, v6
	v_and_b32_e32 v7, 0xff0000, v7
	v_perm_b32 v2, v3, v2, s92
	v_or3_b32 v2, v2, v6, v7
	ds_write_b32 v12, v2 offset:144
	v_mov_b32_e32 v2, v212
	v_mov_b32_e32 v3, v213
	v_pk_add_f32 v[6:7], v[36:37], v[2:3] op_sel_hi:[1,0] neg_lo:[0,1] neg_hi:[0,1]
	s_nop 0
	v_pk_mul_f32 v[6:7], v[2:3], v[6:7] op_sel:[1,0]
	v_pk_add_f32 v[12:13], v[32:33], v[2:3] op_sel_hi:[1,0] neg_lo:[0,1] neg_hi:[0,1]
	v_pk_fma_f32 v[6:7], v[24:25], v[6:7], v[26:27]
	v_pk_mul_f32 v[2:3], v[2:3], v[12:13] op_sel:[1,0]
	v_and_b32_sdwa v12, v7, v216 dst_sel:DWORD dst_unused:UNUSED_PAD src0_sel:WORD_1 src1_sel:DWORD
	v_and_b32_sdwa v13, v6, v216 dst_sel:DWORD dst_unused:UNUSED_PAD src0_sel:WORD_1 src1_sel:DWORD
	v_pk_fma_f32 v[2:3], v[0:1], v[2:3], v[4:5]
	v_add3_u32 v23, v7, v12, s84
	v_add3_u32 v12, v6, v13, s84
	v_and_b32_e32 v28, 0xffff0000, v12
	v_and_b32_sdwa v12, v3, v216 dst_sel:DWORD dst_unused:UNUSED_PAD src0_sel:WORD_1 src1_sel:DWORD
	v_and_b32_sdwa v13, v2, v216 dst_sel:DWORD dst_unused:UNUSED_PAD src0_sel:WORD_1 src1_sel:DWORD
	v_add3_u32 v12, v3, v12, s84
	v_add3_u32 v29, v2, v13, s84
	v_and_b32_e32 v30, 0xffff0000, v12
	v_or_b32_sdwa v13, v30, v23 dst_sel:DWORD dst_unused:UNUSED_PAD src0_sel:DWORD src1_sel:WORD_1
	v_or_b32_sdwa v12, v29, v28 dst_sel:DWORD dst_unused:UNUSED_PAD src0_sel:WORD_1 src1_sel:DWORD
	ds_write_b64 v95, v[12:13]
	v_and_b32_e32 v12, 0xffff0000, v29
	v_sub_u32_e32 v2, v2, v12
	v_sub_u32_e32 v6, v6, v28
	v_and_b32_e32 v12, 0xffff0000, v23
	v_add_u32_e32 v6, 0x80, v6
	v_sub_u32_e32 v7, v7, v12
	v_sub_u32_e32 v3, v3, v30
	v_add_u32_e32 v2, 0x80, v2
	v_ashrrev_i32_e32 v6, 8, v6
	v_add_u32_e32 v7, 0x80, v7
	v_add_u32_e32 v3, 0x80, v3
	v_ashrrev_i32_e32 v2, 8, v2
	v_min_i32_e32 v6, 0x7f, v6
	v_ashrrev_i32_e32 v7, 8, v7
	v_ashrrev_i32_e32 v3, 8, v3
	v_min_i32_e32 v2, 0x7f, v2
	v_min_i32_sdwa v7, v7, s85 dst_sel:WORD_1 dst_unused:UNUSED_PAD src0_sel:DWORD src1_sel:DWORD
	v_min_i32_e32 v3, 0x7f, v3
	v_lshlrev_b32_e32 v6, 8, v6
	v_and_b32_e32 v6, 0xff00, v6
	v_and_b32_e32 v7, 0xff0000, v7
	v_perm_b32 v2, v3, v2, s92
	v_or3_b32 v2, v2, v6, v7
	ds_write_b32 v14, v2 offset:144
	v_mov_b32_e32 v2, v214
	v_mov_b32_e32 v3, v215
	v_pk_add_f32 v[6:7], v[20:21], v[2:3] op_sel_hi:[1,0] neg_lo:[0,1] neg_hi:[0,1]
	s_nop 0
	v_pk_mul_f32 v[6:7], v[2:3], v[6:7] op_sel:[1,0]
	v_pk_add_f32 v[12:13], v[16:17], v[2:3] op_sel_hi:[1,0] neg_lo:[0,1] neg_hi:[0,1]
	v_pk_fma_f32 v[6:7], v[24:25], v[6:7], v[26:27]
	v_pk_mul_f32 v[2:3], v[2:3], v[12:13] op_sel:[1,0]
	v_and_b32_sdwa v12, v7, v216 dst_sel:DWORD dst_unused:UNUSED_PAD src0_sel:WORD_1 src1_sel:DWORD
	v_and_b32_sdwa v13, v6, v216 dst_sel:DWORD dst_unused:UNUSED_PAD src0_sel:WORD_1 src1_sel:DWORD
	v_pk_fma_f32 v[2:3], v[0:1], v[2:3], v[4:5]
	v_add3_u32 v14, v7, v12, s84
	v_add3_u32 v12, v6, v13, s84
	v_and_b32_e32 v15, 0xffff0000, v12
	v_and_b32_sdwa v12, v3, v216 dst_sel:DWORD dst_unused:UNUSED_PAD src0_sel:WORD_1 src1_sel:DWORD
	v_and_b32_sdwa v13, v2, v216 dst_sel:DWORD dst_unused:UNUSED_PAD src0_sel:WORD_1 src1_sel:DWORD
	v_add3_u32 v12, v3, v12, s84
	v_add3_u32 v16, v2, v13, s84
	v_and_b32_e32 v17, 0xffff0000, v12
	v_or_b32_sdwa v13, v17, v14 dst_sel:DWORD dst_unused:UNUSED_PAD src0_sel:DWORD src1_sel:WORD_1
	v_or_b32_sdwa v12, v16, v15 dst_sel:DWORD dst_unused:UNUSED_PAD src0_sel:WORD_1 src1_sel:DWORD
	ds_write_b64 v80, v[12:13]
	v_and_b32_e32 v12, 0xffff0000, v16
	v_sub_u32_e32 v2, v2, v12
	v_sub_u32_e32 v6, v6, v15
	v_and_b32_e32 v12, 0xffff0000, v14
	v_add_u32_e32 v6, 0x80, v6
	v_sub_u32_e32 v7, v7, v12
	v_sub_u32_e32 v3, v3, v17
	v_add_u32_e32 v2, 0x80, v2
	v_ashrrev_i32_e32 v6, 8, v6
	v_add_u32_e32 v7, 0x80, v7
	v_add_u32_e32 v3, 0x80, v3
	v_ashrrev_i32_e32 v2, 8, v2
	v_min_i32_e32 v6, 0x7f, v6
	v_ashrrev_i32_e32 v7, 8, v7
	v_ashrrev_i32_e32 v3, 8, v3
	v_min_i32_e32 v2, 0x7f, v2
	v_min_i32_sdwa v7, v7, s85 dst_sel:WORD_1 dst_unused:UNUSED_PAD src0_sel:DWORD src1_sel:DWORD
	v_min_i32_e32 v3, 0x7f, v3
	v_lshlrev_b32_e32 v6, 8, v6
	v_and_b32_e32 v6, 0xff00, v6
	v_and_b32_e32 v7, 0xff0000, v7
	v_perm_b32 v2, v3, v2, s92
	v_or3_b32 v2, v2, v6, v7
	ds_write_b32 v18, v2 offset:144
	v_mov_b32_e32 v2, v252
	v_mov_b32_e32 v3, v253
	v_pk_add_f32 v[6:7], v[8:9], v[2:3] op_sel_hi:[1,0] neg_lo:[0,1] neg_hi:[0,1]
	s_nop 0
	v_pk_mul_f32 v[6:7], v[2:3], v[6:7] op_sel:[1,0]
	v_pk_add_f32 v[8:9], v[10:11], v[2:3] op_sel_hi:[1,0] neg_lo:[0,1] neg_hi:[0,1]
	v_pk_fma_f32 v[6:7], v[24:25], v[6:7], v[26:27]
	v_pk_mul_f32 v[2:3], v[2:3], v[8:9] op_sel:[1,0]
	s_nop 0
	v_pk_fma_f32 v[0:1], v[0:1], v[2:3], v[4:5]
	v_and_b32_sdwa v2, v7, v216 dst_sel:DWORD dst_unused:UNUSED_PAD src0_sel:WORD_1 src1_sel:DWORD
	v_and_b32_sdwa v3, v6, v216 dst_sel:DWORD dst_unused:UNUSED_PAD src0_sel:WORD_1 src1_sel:DWORD
	v_add3_u32 v4, v7, v2, s84
	v_add3_u32 v2, v6, v3, s84
	v_and_b32_e32 v5, 0xffff0000, v2
	v_and_b32_sdwa v2, v1, v216 dst_sel:DWORD dst_unused:UNUSED_PAD src0_sel:WORD_1 src1_sel:DWORD
	v_and_b32_sdwa v3, v0, v216 dst_sel:DWORD dst_unused:UNUSED_PAD src0_sel:WORD_1 src1_sel:DWORD
	v_add3_u32 v2, v1, v2, s84
	v_add3_u32 v8, v0, v3, s84
	v_and_b32_e32 v9, 0xffff0000, v2
	v_or_b32_sdwa v3, v9, v4 dst_sel:DWORD dst_unused:UNUSED_PAD src0_sel:DWORD src1_sel:WORD_1
	v_or_b32_sdwa v2, v8, v5 dst_sel:DWORD dst_unused:UNUSED_PAD src0_sel:WORD_1 src1_sel:DWORD
	ds_write_b64 v73, v[2:3]
	v_and_b32_e32 v2, 0xffff0000, v8
	v_sub_u32_e32 v0, v0, v2
	v_sub_u32_e32 v2, v6, v5
	v_and_b32_e32 v3, 0xffff0000, v4
	v_add_u32_e32 v2, 0x80, v2
	v_sub_u32_e32 v3, v7, v3
	v_sub_u32_e32 v1, v1, v9
	v_add_u32_e32 v0, 0x80, v0
	v_ashrrev_i32_e32 v2, 8, v2
	v_add_u32_e32 v3, 0x80, v3
	v_add_u32_e32 v1, 0x80, v1
	v_ashrrev_i32_e32 v0, 8, v0
	v_min_i32_e32 v2, 0x7f, v2
	v_ashrrev_i32_e32 v3, 8, v3
	v_ashrrev_i32_e32 v1, 8, v1
	v_min_i32_e32 v0, 0x7f, v0
	v_min_i32_sdwa v3, v3, s85 dst_sel:WORD_1 dst_unused:UNUSED_PAD src0_sel:DWORD src1_sel:DWORD
	v_min_i32_e32 v1, 0x7f, v1
	v_lshlrev_b32_e32 v2, 8, v2
	v_and_b32_e32 v2, 0xff00, v2
	v_and_b32_e32 v3, 0xff0000, v3
	v_perm_b32 v0, v1, v0, s92
	v_or3_b32 v0, v0, v2, v3
	ds_write_b32 v22, v0 offset:144
	s_waitcnt lgkmcnt(0)
	s_barrier
; #define STAGE(P, RS, SOFF, OFF, kt) do { const int _so = (SOFF) + (kt) * (BK * 2); \
;     _Pragma("unroll") for (int _i = 0; _i < 2; ++_i) { \
;       __builtin_amdgcn_raw_ptr_buffer_load_lds(RS, (__attribute__((address_space(3))) void*)((P) + wave * 1024 + _i * 8192), 16, OFF[_i], _so, 0, 0); } } while (0)
; #define WAIT_L(n) asm volatile("s_waitcnt lgkmcnt(" #n ")" ::: "memory")
; #define BAR __builtin_amdgcn_s_barrier()
;     ...
;   auto issue_prologue = [&](int sA0, int sA1, int sB0, int sB1) {
;     const int tid = opaque_tid(wave);
;     int offA[2], offB[2];
;     _Pragma("unroll") for (int i = 0; i < 2; ++i) {
;       int r, c; stage_rc(tid * 16 + i * 8192, r, c);
;       offA[i] = (r * lda + c) * 2; offB[i] = (r * ldb + c) * 2;
;     }
;     STAGE(SB(0, 0), rsB, sB0, offB, 0); STAGE(SA(0, 0), rsA, sA0, offA, 0);
;     STAGE(SB(0, 1), rsB, sB1, offB, 0); STAGE(SA(0, 1), rsA, sA1, offA, 0);
;     STAGE(SB(1, 0), rsB, sB0, offB, 1); STAGE(SA(1, 0), rsA, sA0, offA, 1); STAGE(SB(1, 1), rsB, sB1, offB, 1);
;     ...
;           WAIT_L(0); BAR;
;           const int hso = ((brow + ai * HALF + 16 * wave) * DM + pn * BM) * 2;
;           const int lso = (brow + ai * HALF + 16 * wave) * DM + pn * BM;
;           _Pragma("unroll") for (int i = 0; i < 8; ++i) {
;             const u32x4 v = *reinterpret_cast<const u32x4*>(smem + (wave * 8 + i) * PIECE + lane3 * 16);
;             __builtin_amdgcn_raw_buffer_store_b128(v, rsXB, hvo + i * (2 * DM * 2), hso, 0);
;           }
;           _Pragma("unroll") for (int i = 0; i < 4; ++i) {
;             const u32x4 v = *reinterpret_cast<const u32x4*>(smem + LOBASE + (wave * 4 + i) * PIECE + lane3 * 16);
;             __builtin_amdgcn_raw_buffer_store_b128(v, rsLO, lvo + i * (4 * DM), lso, 0);
;           }
;           WAIT_L(0); BAR;
	ds_read_b128 v[128:131], v72
	ds_read_b128 v[132:135], v72 offset:1040
	ds_read_b128 v[136:139], v72 offset:2080
	ds_read_b128 v[140:143], v72 offset:3120
	ds_read_b128 v[152:155], v72 offset:4160
	ds_read_b128 v[156:159], v72 offset:5200
	ds_read_b128 v[160:163], v72 offset:6240
	ds_read_b128 v[164:167], v72 offset:7280
	ds_read_b128 v[168:171], v147
	ds_read_b128 v[172:175], v147 offset:1040
	ds_read_b128 v[176:179], v147 offset:2080
	ds_read_b128 v[180:183], v147 offset:3120
	s_waitcnt lgkmcnt(0)
	s_barrier
	s_mov_b32 s98, s0
	s_cbranch_vccnz .Lmy_s1n_278
	v_mbcnt_lo_u32_b32 v0, -1, 0
	v_mbcnt_hi_u32_b32 v0, -1, v0
	s_mov_b32 m0, s37
	v_lshl_add_u32 v0, v0, 4, s35
	v_ashrrev_i32_e32 v1, 31, v0
	v_lshrrev_b32_e32 v1, 22, v1
	v_add_u32_e32 v1, v0, v1
	v_ashrrev_i32_e32 v1, 10, v1
	v_mul_i32_i24_e32 v2, 0x400, v1
	v_sub_u32_e32 v2, v0, v2
	v_lshrrev_b32_e32 v3, 4, v2
	v_bitop3_b32 v2, v3, v2, 32 bitop3:0x6c
	v_ashrrev_i32_e32 v4, 31, v2
	v_lshrrev_b32_e32 v4, 26, v4
	v_add_u32_e32 v4, v2, v4
	v_lshrrev_b32_e32 v5, 6, v4
	v_and_b32_e32 v4, 0xc0, v4
	v_lshlrev_b32_e32 v3, 3, v1
	v_lshlrev_b32_e32 v1, 5, v1
	v_sub_u32_e32 v2, v2, v4
	v_and_b32_e32 v3, 0x1ffff0, v3
	v_and_b32_e32 v1, 32, v1
	v_ashrrev_i16_sdwa v2, v216, sext(v2) dst_sel:DWORD dst_unused:UNUSED_PAD src0_sel:DWORD src1_sel:BYTE_0
	v_add_u32_sdwa v1, v1, sext(v2) dst_sel:DWORD dst_unused:UNUSED_PAD src0_sel:DWORD src1_sel:WORD_0
	v_add_lshl_u32 v2, v5, v3, 11
	v_add_u32_e32 v0, 0x2000, v0
	v_lshl_add_u32 v1, v1, 1, v2
	v_ashrrev_i32_e32 v2, 31, v0
	v_lshrrev_b32_e32 v2, 22, v2
	v_add_u32_e32 v2, v0, v2
	v_ashrrev_i32_e32 v2, 10, v2
	v_mul_i32_i24_e32 v3, 0x400, v2
	v_sub_u32_e32 v0, v0, v3
	v_lshrrev_b32_e32 v3, 4, v0
	v_bitop3_b32 v0, v3, v0, 32 bitop3:0x6c
	v_ashrrev_i32_e32 v4, 31, v0
	v_lshrrev_b32_e32 v4, 26, v4
	v_add_u32_e32 v4, v0, v4
	v_lshrrev_b32_e32 v5, 6, v4
	v_and_b32_e32 v4, 0xffc0, v4
	v_sub_u32_e32 v0, v0, v4
	v_lshrrev_b16_e32 v4, 7, v0
	v_and_b32_e32 v4, 1, v4
	v_lshlrev_b32_e32 v3, 3, v2
	v_lshlrev_b32_e32 v2, 5, v2
	v_add_u16_e32 v0, v0, v4
	v_and_b32_e32 v3, 0x1ffff0, v3
	v_and_b32_e32 v2, 32, v2
	v_ashrrev_i16_sdwa v0, v216, sext(v0) dst_sel:DWORD dst_unused:UNUSED_PAD src0_sel:DWORD src1_sel:BYTE_0
	v_add_u32_sdwa v0, v2, sext(v0) dst_sel:DWORD dst_unused:UNUSED_PAD src0_sel:DWORD src1_sel:WORD_0
	v_add_lshl_u32 v2, v5, v3, 11
	s_mov_b32 s14, s10
	s_mov_b32 s15, s11
	v_lshl_add_u32 v0, v0, 1, v2
	buffer_load_dwordx4 v1, s[12:15], s96 offen lds
	s_mov_b32 m0, s48
	s_or_b32 s0, s96, 0x80
	buffer_load_dwordx4 v0, s[12:15], s96 offen lds
	s_mov_b32 m0, s35
	s_mov_b64 s[4:5], 0
	buffer_load_dwordx4 v1, s[8:11], s95 offen lds
	s_mov_b32 m0, s49
	s_nop 0
	buffer_load_dwordx4 v0, s[8:11], s95 offen lds
	s_mov_b32 m0, s38
	s_nop 0
	buffer_load_dwordx4 v1, s[12:15], s97 offen lds
	s_mov_b32 m0, s54
	s_nop 0
	buffer_load_dwordx4 v0, s[12:15], s97 offen lds
	s_mov_b32 m0, s39
	s_nop 0
	buffer_load_dwordx4 v1, s[8:11], s94 offen lds
	s_mov_b32 m0, s55
	s_nop 0
	buffer_load_dwordx4 v0, s[8:11], s94 offen lds
	s_mov_b32 m0, s42
	s_nop 0
	buffer_load_dwordx4 v1, s[12:15], s0 offen lds
	s_mov_b32 m0, s58
	s_nop 0
	buffer_load_dwordx4 v0, s[12:15], s0 offen lds
	s_or_b32 s0, s95, 0x80
	s_mov_b32 m0, s43
	s_nop 0
	buffer_load_dwordx4 v1, s[8:11], s0 offen lds
	s_mov_b32 m0, s59
	s_nop 0
	buffer_load_dwordx4 v0, s[8:11], s0 offen lds
	s_add_i32 s0, s97, 0x80
	s_mov_b32 m0, s44
	s_nop 0
	buffer_load_dwordx4 v1, s[12:15], s0 offen lds
	s_mov_b32 m0, s60
	s_nop 0
	buffer_load_dwordx4 v0, s[12:15], s0 offen lds
	buffer_store_dwordx4 v[128:131], v148, s[16:19], s98 offen
	buffer_store_dwordx4 v[132:135], v74, s[16:19], s98 offen
	buffer_store_dwordx4 v[136:139], v75, s[16:19], s98 offen
	buffer_store_dwordx4 v[140:143], v81, s[16:19], s98 offen
	buffer_store_dwordx4 v[152:155], v84, s[16:19], s98 offen
	buffer_store_dwordx4 v[156:159], v85, s[16:19], s98 offen
	buffer_store_dwordx4 v[160:163], v88, s[16:19], s98 offen
	buffer_store_dwordx4 v[164:167], v89, s[16:19], s98 offen
	buffer_store_dwordx4 v[168:171], v146, s[20:23], s40 offen
	buffer_store_dwordx4 v[172:175], v90, s[20:23], s40 offen
	buffer_store_dwordx4 v[176:179], v91, s[20:23], s40 offen
	buffer_store_dwordx4 v[180:183], v96, s[20:23], s40 offen
	s_branch .LBB0_283

;     ...
;       const int tid3 = opaque_tid(wave);
;       const int wr3 = tid3 >> 8, wc3 = (tid3 >> 6) & 3, fr3 = tid3 & 15, fq3 = (tid3 & 63) >> 4;
;       const int ebase3 = (brow + wr3 * 64 + fr3) * DM + pn * BM + wc3 * 32 + fq3 * 4;
;       const int vo4b = ebase3 * 4, vo2 = ebase3 * 2, vo1 = ebase3;
;       (void)vo4b; (void)vo2; (void)vo1;
;       if constexpr (OUTF) {
;         _Pragma("unroll") for (int bj = 0; bj < 2; ++bj) _Pragma("unroll") for (int n = 0; n < 2; ++n) {
;           const int col = pn * BM + bj * HALF + wc3 * 32 + n * 16 + fq3 * 4;
;           const float4 gm = *reinterpret_cast<const float4*>(g.gam + col), bt = *reinterpret_cast<const float4*>(g.bet + col);
;           _Pragma("unroll") for (int ai = 0; ai < 2; ++ai) _Pragma("unroll") for (int m = 0; m < 4; ++m) {
;             const int rl = ai * HALF + wr3 * 64 + m * 16 + fr3;
;             const float2 ms = *reinterpret_cast<const float2*>(mr + rl * 2);
;             f32x4 y = acc[ai][bj][m][n];
;             u32x4 o;
;             o[0] = __float_as_uint((y[0] - ms.x) * ms.y * gm.x + bt.x); o[1] = __float_as_uint((y[1] - ms.x) * ms.y * gm.y + bt.y);
;             o[2] = __float_as_uint((y[2] - ms.x) * ms.y * gm.z + bt.z); o[3] = __float_as_uint((y[3] - ms.x) * ms.y * gm.w + bt.w);
;             __builtin_amdgcn_raw_buffer_store_b128(o, rsO, vo4b + ((ai * HALF + m * 16) * DM + bj * HALF + n * 16) * 4, 0, 0);
;           }
;         }
;       } else {
;         constexpr int PIECE = 1024 + 16, LOBASE = 64 * PIECE;
;         const int lane3 = tid3 & 63;
;         const int hvo = (lane3 >> 5) * (DM * 2) + (lane3 & 31) * 16;
;         const int lvo = (lane3 >> 4) * DM + (lane3 & 15) * 16;
;         _Pragma("unroll") for (int ai = 0; ai < 2; ++ai) {
;           _Pragma("unroll") for (int bj = 0; bj < 2; ++bj) _Pragma("unroll") for (int n = 0; n < 2; ++n) {
;             const int cc = bj * HALF + wc3 * 32 + n * 16 + fq3 * 4;
;             const float4 gm = *reinterpret_cast<const float4*>(g.gam + pn * BM + cc), bt = *reinterpret_cast<const float4*>(g.bet + pn * BM + cc);
;             _Pragma("unroll") for (int m = 0; m < 4; ++m) {
;               const int rr = wr3 * 64 + m * 16 + fr3;
;               const float2 ms = *reinterpret_cast<const float2*>(mr + (ai * HALF + rr) * 2);
;               f32x4 y = acc[ai][bj][m][n];
.LBB0_421:
	s_or_b64 exec, exec, s[6:7]
	s_waitcnt lgkmcnt(0)
	s_barrier
	v_mbcnt_lo_u32_b32 v0, -1, 0
	v_mbcnt_hi_u32_b32 v0, -1, v0
	s_movk_i32 s4, 0x60
	v_add_u32_e32 v1, s34, v0
	v_ashrrev_i32_e32 v5, 2, v1
	v_lshrrev_b32_e32 v6, 1, v1
	v_lshlrev_b32_e32 v1, 4, v1
	v_bfe_u32 v4, v0, 4, 2
	v_lshlrev_b32_e32 v12, 7, v0
	v_and_b32_e32 v13, 0x1f0, v1
	v_lshlrev_b32_e32 v7, 2, v4
	v_and_or_b32 v148, v12, s29, v13
	s_ashr_i32 s29, s28, 31
	v_readlane_b32 s60, v255, 0
	v_and_or_b32 v12, v6, s4, v7
	s_lshl_b64 s[4:5], s[28:29], 2
	v_readlane_b32 s66, v255, 6
	v_readlane_b32 s67, v255, 7
	s_add_u32 s6, s66, s4
	v_and_b32_e32 v2, 15, v0
	v_and_b32_e32 v3, 63, v0
	v_and_b32_e32 v1, 0xf0, v1
	v_lshlrev_b32_e32 v13, 9, v0
	v_lshlrev_b32_e32 v0, 8, v0
	s_addc_u32 s7, s67, s5
	v_lshlrev_b32_e32 v150, 2, v12
	v_lshl_or_b32 v146, v4, 11, v1
	v_and_or_b32 v156, v5, s2, v2
	v_and_b32_e32 v14, 0x300, v0
	v_lshlrev_b32_e32 v152, 4, v3
	global_load_dwordx4 v[220:223], v150, s[6:7]
	global_load_dwordx4 v[224:227], v150, s[6:7] offset:64
	global_load_dwordx4 v[228:231], v150, s[6:7] offset:512
	global_load_dwordx4 v[232:235], v150, s[6:7] offset:576
	v_readlane_b32 s68, v255, 8
	v_readlane_b32 s69, v255, 9
	s_add_u32 s4, s68, s4
	s_addc_u32 s5, s69, s5
	global_load_dwordx4 v[236:239], v150, s[4:5]
	global_load_dwordx4 v[240:243], v150, s[4:5] offset:64
	global_load_dwordx4 v[244:247], v150, s[4:5] offset:512
	global_load_dwordx4 v[248:251], v150, s[4:5] offset:576
	s_movk_i32 s22, 0x200
	v_lshl_add_u32 v149, v156, 3, v219
	v_add_u32_e32 v147, s46, v152
	s_andn2_b64 vcc, exec, s[14:15]
	s_movk_i32 s40, 0x100
	v_readlane_b32 s61, v255, 1
	v_readlane_b32 s62, v255, 2
	v_readlane_b32 s63, v255, 3
	v_readlane_b32 s64, v255, 4
	v_readlane_b32 s65, v255, 5
	v_readlane_b32 s70, v255, 10
	v_readlane_b32 s71, v255, 11
	v_readlane_b32 s72, v255, 12
	v_readlane_b32 s73, v255, 13
	v_readlane_b32 s74, v255, 14
	v_readlane_b32 s75, v255, 15
	s_waitcnt vmcnt(0)
	v_mov_b32_e32 v0, v220
	v_mov_b32_e32 v1, v221
	v_mov_b32_e32 v2, v222
	v_mov_b32_e32 v3, v223
	v_mov_b32_e32 v4, v236
	v_mov_b32_e32 v5, v237
	v_mov_b32_e32 v6, v238
	v_mov_b32_e32 v7, v239
	v_mov_b32_e32 v22, v1
	v_lshlrev_b32_e32 v1, 1, v12
	v_and_or_b32 v155, v13, s22, v1
	s_mov_b32 s22, 0x10400
	v_mov_b32_e32 v23, v2
	v_or3_b32 v2, v14, v12, s22
	ds_read_b64 v[12:13], v149
	v_mov_b32_e32 v144, v5
	v_mov_b32_e32 v145, v6
	v_mov_b32_e32 v1, v3
	v_mov_b32_e32 v5, v7
	s_waitcnt lgkmcnt(0)
	v_mov_b32_e32 v210, v12
	v_mov_b32_e32 v211, v13
	v_pk_add_f32 v[14:15], v[128:129], v[12:13] op_sel_hi:[1,0] neg_lo:[0,1] neg_hi:[0,1]
	v_pk_add_f32 v[20:21], v[130:131], v[12:13] op_sel_hi:[1,0] neg_lo:[0,1] neg_hi:[0,1]
	v_pk_mul_f32 v[14:15], v[12:13], v[14:15] op_sel:[1,0]
	v_pk_mul_f32 v[12:13], v[12:13], v[20:21] op_sel:[1,0]
	v_pk_fma_f32 v[14:15], v[22:23], v[14:15], v[144:145]
	v_pk_fma_f32 v[6:7], v[0:1], v[12:13], v[4:5]
	v_and_b32_sdwa v12, v14, v216 dst_sel:DWORD dst_unused:UNUSED_PAD src0_sel:WORD_1 src1_sel:DWORD
	v_add3_u32 v12, v14, v12, s82
	v_and_b32_e32 v20, 0xffff0000, v12
	v_and_b32_sdwa v12, v7, v216 dst_sel:DWORD dst_unused:UNUSED_PAD src0_sel:WORD_1 src1_sel:DWORD
	v_and_b32_sdwa v3, v15, v216 dst_sel:DWORD dst_unused:UNUSED_PAD src0_sel:WORD_1 src1_sel:DWORD
	v_and_b32_sdwa v13, v6, v216 dst_sel:DWORD dst_unused:UNUSED_PAD src0_sel:WORD_1 src1_sel:DWORD
	v_add3_u32 v12, v7, v12, s82
	v_lshrrev_b32_e32 v129, 1, v156
	v_add3_u32 v3, v15, v3, s82
	v_add3_u32 v21, v6, v13, s82
	v_and_b32_e32 v128, 0xffff0000, v12
	v_mul_lo_u32 v153, v129, s50
	v_or_b32_sdwa v13, v128, v3 dst_sel:DWORD dst_unused:UNUSED_PAD src0_sel:DWORD src1_sel:WORD_1
	v_or_b32_sdwa v12, v21, v20 dst_sel:DWORD dst_unused:UNUSED_PAD src0_sel:WORD_1 src1_sel:DWORD
	v_add_u32_e32 v151, v155, v153
	ds_write_b64 v151, v[12:13]
	v_and_b32_e32 v12, 0xffff0000, v21
	v_sub_u32_e32 v6, v6, v12
	v_sub_u32_e32 v12, v14, v20
	v_and_b32_e32 v3, 0xffff0000, v3
	v_add_u32_e32 v12, 0x80, v12
	v_sub_u32_e32 v3, v15, v3
	v_sub_u32_e32 v7, v7, v128
	v_add_u32_e32 v6, 0x80, v6
	v_ashrrev_i32_e32 v12, 8, v12
	v_add_u32_e32 v3, 0x80, v3
	v_add_u32_e32 v7, 0x80, v7
	v_ashrrev_i32_e32 v6, 8, v6
	v_min_i32_e32 v12, 0x7f, v12
	v_ashrrev_i32_e32 v3, 8, v3
	v_ashrrev_i32_e32 v7, 8, v7
	v_min_i32_e32 v6, 0x7f, v6
	v_min_i32_sdwa v3, v3, s83 dst_sel:WORD_1 dst_unused:UNUSED_PAD src0_sel:DWORD src1_sel:DWORD
	v_min_i32_e32 v7, 0x7f, v7
	v_lshlrev_b32_e32 v12, 8, v12
	v_and_b32_e32 v12, 0xff00, v12
	v_and_b32_e32 v3, 0xff0000, v3
	v_perm_b32 v6, v7, v6, s84
	v_or3_b32 v3, v6, v12, v3
	v_lshrrev_b32_e32 v6, 2, v156
	v_mad_u64_u32 v[12:13], s[22:23], v6, s50, v[2:3]
	ds_write_b32 v12, v3
	v_or_b32_e32 v3, 16, v156
	v_lshl_add_u32 v13, v3, 3, v219
	ds_read_b64 v[6:7], v13
	s_waitcnt lgkmcnt(0)
;     ...
;         _Pragma("unroll") for (int ai = 0; ai < 2; ++ai) {
;           _Pragma("unroll") for (int bj = 0; bj < 2; ++bj) _Pragma("unroll") for (int n = 0; n < 2; ++n) {
;             const int cc = bj * HALF + wc3 * 32 + n * 16 + fq3 * 4;
;             const float4 gm = *reinterpret_cast<const float4*>(g.gam + pn * BM + cc), bt = *reinterpret_cast<const float4*>(g.bet + pn * BM + cc);
;             _Pragma("unroll") for (int m = 0; m < 4; ++m) {
;               const int rr = wr3 * 64 + m * 16 + fr3;
;               const float2 ms = *reinterpret_cast<const float2*>(mr + (ai * HALF + rr) * 2);
;               f32x4 y = acc[ai][bj][m][n];
;               const float o0 = (y[0] - ms.x) * ms.y * gm.x + bt.x, o1 = (y[1] - ms.x) * ms.y * gm.y + bt.y;
;               const float o2 = (y[2] - ms.x) * ms.y * gm.z + bt.z, o3 = (y[3] - ms.x) * ms.y * gm.w + bt.w;
;               const unsigned h0 = f2bf(o0), h1 = f2bf(o1), h2 = f2bf(o2), h3 = f2bf(o3);
;               u32x2 ob; ob[0] = h0 | (h1 << 16); ob[1] = h2 | (h3 << 16);
;               *reinterpret_cast<u32x2*>(smem + (rr >> 1) * PIECE + (rr & 1) * 512 + cc * 2) = ob;
;               const int l0 = min(((int)__float_as_uint(o0) - (int)(h0 << 16) + 128) >> 8, 127);
;               const int l1 = min(((int)__float_as_uint(o1) - (int)(h1 << 16) + 128) >> 8, 127);
;               const int l2 = min(((int)__float_as_uint(o2) - (int)(h2 << 16) + 128) >> 8, 127);
;               const int l3 = min(((int)__float_as_uint(o3) - (int)(h3 << 16) + 128) >> 8, 127);
;               *reinterpret_cast<unsigned*>(smem + LOBASE + (rr >> 2) * PIECE + (rr & 3) * 256 + cc) =
;                   (unsigned)(l0 & 255) | ((unsigned)(l1 & 255) << 8) | ((unsigned)(l2 & 255) << 16) | ((unsigned)l3 << 24);
;             }
	v_mov_b32_e32 v212, v6
	v_mov_b32_e32 v213, v7
	v_pk_add_f32 v[14:15], v[134:135], v[6:7] op_sel_hi:[1,0] neg_lo:[0,1] neg_hi:[0,1]
	s_nop 0
	v_pk_mul_f32 v[14:15], v[6:7], v[14:15] op_sel:[1,0]
	v_pk_add_f32 v[20:21], v[132:133], v[6:7] op_sel_hi:[1,0] neg_lo:[0,1] neg_hi:[0,1]
	v_pk_fma_f32 v[14:15], v[22:23], v[14:15], v[144:145]
	v_pk_mul_f32 v[6:7], v[6:7], v[20:21] op_sel:[1,0]
	v_and_b32_sdwa v20, v15, v216 dst_sel:DWORD dst_unused:UNUSED_PAD src0_sel:WORD_1 src1_sel:DWORD
	v_and_b32_sdwa v21, v14, v216 dst_sel:DWORD dst_unused:UNUSED_PAD src0_sel:WORD_1 src1_sel:DWORD
	v_pk_fma_f32 v[6:7], v[0:1], v[6:7], v[4:5]
	v_add3_u32 v128, v15, v20, s82
	v_add3_u32 v20, v14, v21, s82
	v_and_b32_e32 v129, 0xffff0000, v20
	v_and_b32_sdwa v20, v7, v216 dst_sel:DWORD dst_unused:UNUSED_PAD src0_sel:WORD_1 src1_sel:DWORD
	v_and_b32_sdwa v21, v6, v216 dst_sel:DWORD dst_unused:UNUSED_PAD src0_sel:WORD_1 src1_sel:DWORD
	v_add3_u32 v20, v7, v20, s82
	v_lshrrev_b32_e32 v132, 1, v3
	v_add3_u32 v130, v6, v21, s82
	v_and_b32_e32 v131, 0xffff0000, v20
	v_mul_lo_u32 v154, v132, s50
	v_or_b32_sdwa v21, v131, v128 dst_sel:DWORD dst_unused:UNUSED_PAD src0_sel:DWORD src1_sel:WORD_1
	v_or_b32_sdwa v20, v130, v129 dst_sel:DWORD dst_unused:UNUSED_PAD src0_sel:WORD_1 src1_sel:DWORD
	v_add_u32_e32 v132, v155, v154
	ds_write_b64 v132, v[20:21]
	v_and_b32_e32 v20, 0xffff0000, v130
	v_sub_u32_e32 v6, v6, v20
	v_sub_u32_e32 v14, v14, v129
	v_and_b32_e32 v20, 0xffff0000, v128
	v_add_u32_e32 v14, 0x80, v14
	v_sub_u32_e32 v15, v15, v20
	v_sub_u32_e32 v7, v7, v131
	v_add_u32_e32 v6, 0x80, v6
	v_ashrrev_i32_e32 v14, 8, v14
	v_add_u32_e32 v15, 0x80, v15
	v_add_u32_e32 v7, 0x80, v7
	v_ashrrev_i32_e32 v6, 8, v6
	v_min_i32_e32 v14, 0x7f, v14
	v_ashrrev_i32_e32 v15, 8, v15
	v_ashrrev_i32_e32 v7, 8, v7
	v_min_i32_e32 v6, 0x7f, v6
	v_min_i32_sdwa v15, v15, s83 dst_sel:WORD_1 dst_unused:UNUSED_PAD src0_sel:DWORD src1_sel:DWORD
	v_min_i32_e32 v7, 0x7f, v7
	v_lshlrev_b32_e32 v14, 8, v14
	v_and_b32_e32 v14, 0xff00, v14
	v_and_b32_e32 v15, 0xff0000, v15
	v_perm_b32 v6, v7, v6, s84
	v_lshrrev_b32_e32 v3, 2, v3
	v_or3_b32 v6, v6, v14, v15
	v_mad_u64_u32 v[14:15], s[22:23], v3, s50, v[2:3]
	v_or_b32_e32 v3, 32, v156
	ds_write_b32 v14, v6
	v_lshl_add_u32 v15, v3, 3, v219
	ds_read_b64 v[6:7], v15
	v_lshrrev_b32_e32 v133, 1, v3
	v_lshrrev_b32_e32 v3, 2, v3
	s_waitcnt lgkmcnt(0)
	v_mov_b32_e32 v214, v6
	v_mov_b32_e32 v215, v7
	v_pk_add_f32 v[20:21], v[138:139], v[6:7] op_sel_hi:[1,0] neg_lo:[0,1] neg_hi:[0,1]
	s_nop 0
	v_pk_mul_f32 v[20:21], v[6:7], v[20:21] op_sel:[1,0]
	v_pk_add_f32 v[128:129], v[136:137], v[6:7] op_sel_hi:[1,0] neg_lo:[0,1] neg_hi:[0,1]
	v_pk_fma_f32 v[20:21], v[22:23], v[20:21], v[144:145]
	v_pk_mul_f32 v[6:7], v[6:7], v[128:129] op_sel:[1,0]
	v_and_b32_sdwa v128, v21, v216 dst_sel:DWORD dst_unused:UNUSED_PAD src0_sel:WORD_1 src1_sel:DWORD
	v_and_b32_sdwa v129, v20, v216 dst_sel:DWORD dst_unused:UNUSED_PAD src0_sel:WORD_1 src1_sel:DWORD
	v_pk_fma_f32 v[6:7], v[0:1], v[6:7], v[4:5]
	v_add3_u32 v130, v21, v128, s82
	v_add3_u32 v128, v20, v129, s82
	v_and_b32_e32 v131, 0xffff0000, v128
	v_and_b32_sdwa v128, v7, v216 dst_sel:DWORD dst_unused:UNUSED_PAD src0_sel:WORD_1 src1_sel:DWORD
	v_and_b32_sdwa v129, v6, v216 dst_sel:DWORD dst_unused:UNUSED_PAD src0_sel:WORD_1 src1_sel:DWORD
	v_add3_u32 v128, v7, v128, s82
	v_add3_u32 v134, v6, v129, s82
	v_and_b32_e32 v135, 0xffff0000, v128
	v_mul_lo_u32 v136, v133, s50
	v_or_b32_sdwa v129, v135, v130 dst_sel:DWORD dst_unused:UNUSED_PAD src0_sel:DWORD src1_sel:WORD_1
	v_or_b32_sdwa v128, v134, v131 dst_sel:DWORD dst_unused:UNUSED_PAD src0_sel:WORD_1 src1_sel:DWORD
	v_add_u32_e32 v133, v155, v136
	ds_write_b64 v133, v[128:129]
	v_and_b32_e32 v128, 0xffff0000, v134
	v_sub_u32_e32 v6, v6, v128
	v_sub_u32_e32 v20, v20, v131
	v_and_b32_e32 v128, 0xffff0000, v130
	v_add_u32_e32 v20, 0x80, v20
	v_sub_u32_e32 v21, v21, v128
	v_sub_u32_e32 v7, v7, v135
	v_add_u32_e32 v6, 0x80, v6
	v_ashrrev_i32_e32 v20, 8, v20
	v_add_u32_e32 v21, 0x80, v21
	v_add_u32_e32 v7, 0x80, v7
	v_ashrrev_i32_e32 v6, 8, v6
	v_min_i32_e32 v20, 0x7f, v20
	v_ashrrev_i32_e32 v21, 8, v21
	v_ashrrev_i32_e32 v7, 8, v7
	v_min_i32_e32 v6, 0x7f, v6
	v_min_i32_sdwa v21, v21, s83 dst_sel:WORD_1 dst_unused:UNUSED_PAD src0_sel:DWORD src1_sel:DWORD
	v_min_i32_e32 v7, 0x7f, v7
	v_lshlrev_b32_e32 v20, 8, v20
	v_and_b32_e32 v20, 0xff00, v20
	v_and_b32_e32 v21, 0xff0000, v21
	v_perm_b32 v6, v7, v6, s84
	v_or3_b32 v6, v6, v20, v21
	v_mad_u64_u32 v[20:21], s[22:23], v3, s50, v[2:3]
	v_or_b32_e32 v3, 48, v156
	ds_write_b32 v20, v6
	v_lshl_add_u32 v21, v3, 3, v219
	ds_read_b64 v[6:7], v21
	v_lshrrev_b32_e32 v130, 1, v3
	v_mul_lo_u32 v135, v130, s50
	v_add_u32_e32 v134, v155, v135
	s_waitcnt lgkmcnt(0)
;     ...
;         _Pragma("unroll") for (int ai = 0; ai < 2; ++ai) {
;           _Pragma("unroll") for (int bj = 0; bj < 2; ++bj) _Pragma("unroll") for (int n = 0; n < 2; ++n) {
;             const int cc = bj * HALF + wc3 * 32 + n * 16 + fq3 * 4;
;             const float4 gm = *reinterpret_cast<const float4*>(g.gam + pn * BM + cc), bt = *reinterpret_cast<const float4*>(g.bet + pn * BM + cc);
;             _Pragma("unroll") for (int m = 0; m < 4; ++m) {
;               const int rr = wr3 * 64 + m * 16 + fr3;
;               const float2 ms = *reinterpret_cast<const float2*>(mr + (ai * HALF + rr) * 2);
;               f32x4 y = acc[ai][bj][m][n];
;               const float o0 = (y[0] - ms.x) * ms.y * gm.x + bt.x, o1 = (y[1] - ms.x) * ms.y * gm.y + bt.y;
;               const float o2 = (y[2] - ms.x) * ms.y * gm.z + bt.z, o3 = (y[3] - ms.x) * ms.y * gm.w + bt.w;
;               const unsigned h0 = f2bf(o0), h1 = f2bf(o1), h2 = f2bf(o2), h3 = f2bf(o3);
;               u32x2 ob; ob[0] = h0 | (h1 << 16); ob[1] = h2 | (h3 << 16);
;               *reinterpret_cast<u32x2*>(smem + (rr >> 1) * PIECE + (rr & 1) * 512 + cc * 2) = ob;
;               const int l0 = min(((int)__float_as_uint(o0) - (int)(h0 << 16) + 128) >> 8, 127);
;               const int l1 = min(((int)__float_as_uint(o1) - (int)(h1 << 16) + 128) >> 8, 127);
;               const int l2 = min(((int)__float_as_uint(o2) - (int)(h2 << 16) + 128) >> 8, 127);
;               const int l3 = min(((int)__float_as_uint(o3) - (int)(h3 << 16) + 128) >> 8, 127);
;               *reinterpret_cast<unsigned*>(smem + LOBASE + (rr >> 2) * PIECE + (rr & 3) * 256 + cc) =
;                   (unsigned)(l0 & 255) | ((unsigned)(l1 & 255) << 8) | ((unsigned)(l2 & 255) << 16) | ((unsigned)l3 << 24);
;             }
	v_mov_b32_e32 v252, v6
	v_mov_b32_e32 v253, v7
	v_pk_add_f32 v[128:129], v[142:143], v[6:7] op_sel_hi:[1,0] neg_lo:[0,1] neg_hi:[0,1]
	s_nop 0
	v_pk_mul_f32 v[128:129], v[6:7], v[128:129] op_sel:[1,0]
	s_nop 0
	v_pk_fma_f32 v[22:23], v[22:23], v[128:129], v[144:145]
	v_pk_add_f32 v[128:129], v[140:141], v[6:7] op_sel_hi:[1,0] neg_lo:[0,1] neg_hi:[0,1]
	s_nop 0
	v_pk_mul_f32 v[6:7], v[6:7], v[128:129] op_sel:[1,0]
	s_nop 0
	v_pk_fma_f32 v[0:1], v[0:1], v[6:7], v[4:5]
	v_and_b32_sdwa v4, v23, v216 dst_sel:DWORD dst_unused:UNUSED_PAD src0_sel:WORD_1 src1_sel:DWORD
	v_and_b32_sdwa v5, v22, v216 dst_sel:DWORD dst_unused:UNUSED_PAD src0_sel:WORD_1 src1_sel:DWORD
	v_add3_u32 v6, v23, v4, s82
	v_add3_u32 v4, v22, v5, s82
	v_and_b32_e32 v7, 0xffff0000, v4
	v_and_b32_sdwa v4, v1, v216 dst_sel:DWORD dst_unused:UNUSED_PAD src0_sel:WORD_1 src1_sel:DWORD
	v_and_b32_sdwa v5, v0, v216 dst_sel:DWORD dst_unused:UNUSED_PAD src0_sel:WORD_1 src1_sel:DWORD
	v_add3_u32 v4, v1, v4, s82
	v_add3_u32 v128, v0, v5, s82
	v_and_b32_e32 v129, 0xffff0000, v4
	v_or_b32_sdwa v5, v129, v6 dst_sel:DWORD dst_unused:UNUSED_PAD src0_sel:DWORD src1_sel:WORD_1
	v_or_b32_sdwa v4, v128, v7 dst_sel:DWORD dst_unused:UNUSED_PAD src0_sel:WORD_1 src1_sel:DWORD
	ds_write_b64 v134, v[4:5]
	v_and_b32_e32 v4, 0xffff0000, v128
	v_sub_u32_e32 v0, v0, v4
	v_sub_u32_e32 v4, v22, v7
	v_and_b32_e32 v5, 0xffff0000, v6
	v_add_u32_e32 v4, 0x80, v4
	v_sub_u32_e32 v5, v23, v5
	v_sub_u32_e32 v1, v1, v129
	v_add_u32_e32 v0, 0x80, v0
	v_ashrrev_i32_e32 v4, 8, v4
	v_add_u32_e32 v5, 0x80, v5
	v_add_u32_e32 v1, 0x80, v1
	v_ashrrev_i32_e32 v0, 8, v0
	v_min_i32_e32 v4, 0x7f, v4
	v_ashrrev_i32_e32 v5, 8, v5
	v_ashrrev_i32_e32 v1, 8, v1
	v_min_i32_e32 v0, 0x7f, v0
	v_min_i32_sdwa v5, v5, s83 dst_sel:WORD_1 dst_unused:UNUSED_PAD src0_sel:DWORD src1_sel:DWORD
	v_min_i32_e32 v1, 0x7f, v1
	v_lshlrev_b32_e32 v4, 8, v4
	v_and_b32_e32 v4, 0xff00, v4
	v_and_b32_e32 v5, 0xff0000, v5
	v_perm_b32 v0, v1, v0, s84
	v_lshrrev_b32_e32 v1, 2, v3
	v_or3_b32 v0, v0, v4, v5
	v_mad_u64_u32 v[22:23], s[22:23], v1, s50, v[2:3]
	ds_write_b32 v22, v0
	v_mov_b32_e32 v0, v224
	v_mov_b32_e32 v1, v225
	v_mov_b32_e32 v2, v226
	v_mov_b32_e32 v3, v227
	v_mov_b32_e32 v4, v240
	v_mov_b32_e32 v5, v241
	v_mov_b32_e32 v6, v242
	v_mov_b32_e32 v7, v243
	v_mov_b32_e32 v138, v210
	v_mov_b32_e32 v139, v211
	s_mov_b32 s22, s18
	s_mov_b32 s23, s19
	v_pk_add_f32 v[124:125], v[124:125], v[138:139] op_sel_hi:[1,0] neg_lo:[0,1] neg_hi:[0,1]
	s_nop 0
	v_pk_mul_f32 v[124:125], v[138:139], v[124:125] op_sel:[1,0]
	v_pk_add_f32 v[126:127], v[126:127], v[138:139] op_sel_hi:[1,0] neg_lo:[0,1] neg_hi:[0,1]
	v_mov_b32_e32 v128, v1
	v_mov_b32_e32 v129, v2
	v_mov_b32_e32 v130, v5
	v_mov_b32_e32 v131, v6
	v_pk_fma_f32 v[124:125], v[128:129], v[124:125], v[130:131]
	v_pk_mul_f32 v[126:127], v[138:139], v[126:127] op_sel:[1,0]
	v_mov_b32_e32 v1, v3
	v_mov_b32_e32 v5, v7
	v_and_b32_sdwa v23, v124, v216 dst_sel:DWORD dst_unused:UNUSED_PAD src0_sel:WORD_1 src1_sel:DWORD
	v_pk_fma_f32 v[6:7], v[0:1], v[126:127], v[4:5]
	v_add3_u32 v23, v124, v23, s82
	v_and_b32_e32 v137, 0xffff0000, v23
	v_and_b32_sdwa v23, v7, v216 dst_sel:DWORD dst_unused:UNUSED_PAD src0_sel:WORD_1 src1_sel:DWORD
	v_and_b32_sdwa v3, v125, v216 dst_sel:DWORD dst_unused:UNUSED_PAD src0_sel:WORD_1 src1_sel:DWORD
	v_and_b32_sdwa v126, v6, v216 dst_sel:DWORD dst_unused:UNUSED_PAD src0_sel:WORD_1 src1_sel:DWORD
	v_add3_u32 v23, v7, v23, s82
	v_or_b32_e32 v2, 32, v155
	v_add3_u32 v3, v125, v3, s82
	v_add3_u32 v138, v6, v126, s82
	v_and_b32_e32 v139, 0xffff0000, v23
	v_or_b32_sdwa v127, v139, v3 dst_sel:DWORD dst_unused:UNUSED_PAD src0_sel:DWORD src1_sel:WORD_1
	v_or_b32_sdwa v126, v138, v137 dst_sel:DWORD dst_unused:UNUSED_PAD src0_sel:WORD_1 src1_sel:DWORD
	v_add_u32_e32 v23, v2, v153
	ds_write_b64 v23, v[126:127]
	v_and_b32_e32 v126, 0xffff0000, v138
	v_sub_u32_e32 v124, v124, v137
	v_and_b32_e32 v3, 0xffff0000, v3
	v_sub_u32_e32 v6, v6, v126
	v_add_u32_e32 v124, 0x80, v124
	v_sub_u32_e32 v3, v125, v3
	v_sub_u32_e32 v7, v7, v139
	v_add_u32_e32 v6, 0x80, v6
	v_ashrrev_i32_e32 v124, 8, v124
	v_add_u32_e32 v3, 0x80, v3
	v_add_u32_e32 v7, 0x80, v7
	v_ashrrev_i32_e32 v6, 8, v6
	v_min_i32_e32 v124, 0x7f, v124
	v_ashrrev_i32_e32 v3, 8, v3
	v_ashrrev_i32_e32 v7, 8, v7
	v_min_i32_e32 v6, 0x7f, v6
	v_min_i32_sdwa v3, v3, s83 dst_sel:WORD_1 dst_unused:UNUSED_PAD src0_sel:DWORD src1_sel:DWORD
	v_min_i32_e32 v7, 0x7f, v7
	v_lshlrev_b32_e32 v124, 8, v124
	v_and_b32_e32 v124, 0xff00, v124
	v_and_b32_e32 v3, 0xff0000, v3
	v_perm_b32 v6, v7, v6, s84
	v_or3_b32 v3, v6, v124, v3
	ds_write_b32 v12, v3 offset:16
	v_mov_b32_e32 v6, v212
	v_mov_b32_e32 v7, v213
	v_pk_add_f32 v[106:107], v[106:107], v[6:7] op_sel_hi:[1,0] neg_lo:[0,1] neg_hi:[0,1]
	s_nop 0
	v_pk_mul_f32 v[106:107], v[6:7], v[106:107] op_sel:[1,0]
	v_pk_add_f32 v[104:105], v[104:105], v[6:7] op_sel_hi:[1,0] neg_lo:[0,1] neg_hi:[0,1]
	v_pk_fma_f32 v[106:107], v[128:129], v[106:107], v[130:131]
	v_pk_mul_f32 v[6:7], v[6:7], v[104:105] op_sel:[1,0]
	v_and_b32_sdwa v104, v106, v216 dst_sel:DWORD dst_unused:UNUSED_PAD src0_sel:WORD_1 src1_sel:DWORD
	v_pk_fma_f32 v[6:7], v[0:1], v[6:7], v[4:5]
	v_add3_u32 v104, v106, v104, s82
	v_and_b32_e32 v105, 0xffff0000, v104
	v_and_b32_sdwa v104, v7, v216 dst_sel:DWORD dst_unused:UNUSED_PAD src0_sel:WORD_1 src1_sel:DWORD
	v_and_b32_sdwa v3, v107, v216 dst_sel:DWORD dst_unused:UNUSED_PAD src0_sel:WORD_1 src1_sel:DWORD
	v_and_b32_sdwa v124, v6, v216 dst_sel:DWORD dst_unused:UNUSED_PAD src0_sel:WORD_1 src1_sel:DWORD
	v_add3_u32 v104, v7, v104, s82
	v_add3_u32 v3, v107, v3, s82
	v_add3_u32 v126, v6, v124, s82
	v_and_b32_e32 v127, 0xffff0000, v104
;     ...
;           _Pragma("unroll") for (int bj = 0; bj < 2; ++bj) _Pragma("unroll") for (int n = 0; n < 2; ++n) {
;             const int cc = bj * HALF + wc3 * 32 + n * 16 + fq3 * 4;
;             const float4 gm = *reinterpret_cast<const float4*>(g.gam + pn * BM + cc), bt = *reinterpret_cast<const float4*>(g.bet + pn * BM + cc);
;             _Pragma("unroll") for (int m = 0; m < 4; ++m) {
;               const int rr = wr3 * 64 + m * 16 + fr3;
;               const float2 ms = *reinterpret_cast<const float2*>(mr + (ai * HALF + rr) * 2);
;               f32x4 y = acc[ai][bj][m][n];
;               const float o0 = (y[0] - ms.x) * ms.y * gm.x + bt.x, o1 = (y[1] - ms.x) * ms.y * gm.y + bt.y;
;               const float o2 = (y[2] - ms.x) * ms.y * gm.z + bt.z, o3 = (y[3] - ms.x) * ms.y * gm.w + bt.w;
;               const unsigned h0 = f2bf(o0), h1 = f2bf(o1), h2 = f2bf(o2), h3 = f2bf(o3);
;               u32x2 ob; ob[0] = h0 | (h1 << 16); ob[1] = h2 | (h3 << 16);
;               *reinterpret_cast<u32x2*>(smem + (rr >> 1) * PIECE + (rr & 1) * 512 + cc * 2) = ob;
;               const int l0 = min(((int)__float_as_uint(o0) - (int)(h0 << 16) + 128) >> 8, 127);
;               const int l1 = min(((int)__float_as_uint(o1) - (int)(h1 << 16) + 128) >> 8, 127);
;               const int l2 = min(((int)__float_as_uint(o2) - (int)(h2 << 16) + 128) >> 8, 127);
;               const int l3 = min(((int)__float_as_uint(o3) - (int)(h3 << 16) + 128) >> 8, 127);
;               *reinterpret_cast<unsigned*>(smem + LOBASE + (rr >> 2) * PIECE + (rr & 3) * 256 + cc) =
;                   (unsigned)(l0 & 255) | ((unsigned)(l1 & 255) << 8) | ((unsigned)(l2 & 255) << 16) | ((unsigned)l3 << 24);
;             }
	v_or_b32_sdwa v125, v127, v3 dst_sel:DWORD dst_unused:UNUSED_PAD src0_sel:DWORD src1_sel:WORD_1
	v_or_b32_sdwa v124, v126, v105 dst_sel:DWORD dst_unused:UNUSED_PAD src0_sel:WORD_1 src1_sel:DWORD
	v_add_u32_e32 v104, v2, v154
	ds_write_b64 v104, v[124:125]
	v_and_b32_e32 v124, 0xffff0000, v126
	v_sub_u32_e32 v105, v106, v105
	v_and_b32_e32 v3, 0xffff0000, v3
	v_sub_u32_e32 v6, v6, v124
	v_add_u32_e32 v105, 0x80, v105
	v_sub_u32_e32 v3, v107, v3
	v_sub_u32_e32 v7, v7, v127
	v_add_u32_e32 v6, 0x80, v6
	v_ashrrev_i32_e32 v105, 8, v105
	v_add_u32_e32 v3, 0x80, v3
	v_add_u32_e32 v7, 0x80, v7
	v_ashrrev_i32_e32 v6, 8, v6
	v_min_i32_e32 v105, 0x7f, v105
	v_ashrrev_i32_e32 v3, 8, v3
	v_ashrrev_i32_e32 v7, 8, v7
	v_min_i32_e32 v6, 0x7f, v6
	v_min_i32_sdwa v3, v3, s83 dst_sel:WORD_1 dst_unused:UNUSED_PAD src0_sel:DWORD src1_sel:DWORD
	v_min_i32_e32 v7, 0x7f, v7
	v_lshlrev_b32_e32 v105, 8, v105
	v_and_b32_e32 v105, 0xff00, v105
	v_and_b32_e32 v3, 0xff0000, v3
	v_perm_b32 v6, v7, v6, s84
	v_or3_b32 v3, v6, v105, v3
	ds_write_b32 v14, v3 offset:16
	v_mov_b32_e32 v6, v214
	v_mov_b32_e32 v7, v215
	v_pk_add_f32 v[106:107], v[110:111], v[6:7] op_sel_hi:[1,0] neg_lo:[0,1] neg_hi:[0,1]
	s_nop 0
	v_pk_mul_f32 v[106:107], v[6:7], v[106:107] op_sel:[1,0]
	v_pk_add_f32 v[108:109], v[108:109], v[6:7] op_sel_hi:[1,0] neg_lo:[0,1] neg_hi:[0,1]
	v_pk_fma_f32 v[106:107], v[128:129], v[106:107], v[130:131]
	v_pk_mul_f32 v[6:7], v[6:7], v[108:109] op_sel:[1,0]
	v_and_b32_sdwa v105, v106, v216 dst_sel:DWORD dst_unused:UNUSED_PAD src0_sel:WORD_1 src1_sel:DWORD
	v_pk_fma_f32 v[6:7], v[0:1], v[6:7], v[4:5]
	v_add3_u32 v105, v106, v105, s82
	v_and_b32_e32 v110, 0xffff0000, v105
	v_and_b32_sdwa v105, v7, v216 dst_sel:DWORD dst_unused:UNUSED_PAD src0_sel:WORD_1 src1_sel:DWORD
	v_and_b32_sdwa v3, v107, v216 dst_sel:DWORD dst_unused:UNUSED_PAD src0_sel:WORD_1 src1_sel:DWORD
	v_and_b32_sdwa v108, v6, v216 dst_sel:DWORD dst_unused:UNUSED_PAD src0_sel:WORD_1 src1_sel:DWORD
	v_add3_u32 v105, v7, v105, s82
	v_add3_u32 v3, v107, v3, s82
	v_add3_u32 v111, v6, v108, s82
	v_and_b32_e32 v124, 0xffff0000, v105
	v_or_b32_sdwa v109, v124, v3 dst_sel:DWORD dst_unused:UNUSED_PAD src0_sel:DWORD src1_sel:WORD_1
	v_or_b32_sdwa v108, v111, v110 dst_sel:DWORD dst_unused:UNUSED_PAD src0_sel:WORD_1 src1_sel:DWORD
	v_add_u32_e32 v105, v2, v136
	ds_write_b64 v105, v[108:109]
	v_and_b32_e32 v108, 0xffff0000, v111
	v_sub_u32_e32 v106, v106, v110
	v_and_b32_e32 v3, 0xffff0000, v3
	v_sub_u32_e32 v6, v6, v108
	v_add_u32_e32 v106, 0x80, v106
	v_sub_u32_e32 v3, v107, v3
	v_sub_u32_e32 v7, v7, v124
	v_add_u32_e32 v6, 0x80, v6
	v_ashrrev_i32_e32 v106, 8, v106
	v_add_u32_e32 v3, 0x80, v3
	v_add_u32_e32 v7, 0x80, v7
	v_ashrrev_i32_e32 v6, 8, v6
	v_min_i32_e32 v106, 0x7f, v106
	v_ashrrev_i32_e32 v3, 8, v3
	v_ashrrev_i32_e32 v7, 8, v7
	v_min_i32_e32 v6, 0x7f, v6
	v_min_i32_sdwa v3, v3, s83 dst_sel:WORD_1 dst_unused:UNUSED_PAD src0_sel:DWORD src1_sel:DWORD
	v_min_i32_e32 v7, 0x7f, v7
	v_lshlrev_b32_e32 v106, 8, v106
	v_and_b32_e32 v106, 0xff00, v106
	v_and_b32_e32 v3, 0xff0000, v3
	v_perm_b32 v6, v7, v6, s84
	v_or3_b32 v3, v6, v106, v3
	ds_write_b32 v20, v3 offset:16
	v_mov_b32_e32 v6, v252
	v_mov_b32_e32 v7, v253
	v_pk_add_f32 v[106:107], v[122:123], v[6:7] op_sel_hi:[1,0] neg_lo:[0,1] neg_hi:[0,1]
	s_nop 0
	v_pk_mul_f32 v[106:107], v[6:7], v[106:107] op_sel:[1,0]
	v_or_b32_e32 v122, 0x100, v155
	v_pk_fma_f32 v[108:109], v[128:129], v[106:107], v[130:131]
	v_pk_add_f32 v[106:107], v[114:115], v[6:7] op_sel_hi:[1,0] neg_lo:[0,1] neg_hi:[0,1]
	v_and_b32_sdwa v3, v109, v216 dst_sel:DWORD dst_unused:UNUSED_PAD src0_sel:WORD_1 src1_sel:DWORD
	v_pk_mul_f32 v[6:7], v[6:7], v[106:107] op_sel:[1,0]
	v_add3_u32 v3, v109, v3, s82
	v_pk_fma_f32 v[0:1], v[0:1], v[6:7], v[4:5]
	v_and_b32_sdwa v4, v108, v216 dst_sel:DWORD dst_unused:UNUSED_PAD src0_sel:WORD_1 src1_sel:DWORD
	v_add3_u32 v4, v108, v4, s82
	v_and_b32_e32 v6, 0xffff0000, v4
	v_and_b32_sdwa v4, v1, v216 dst_sel:DWORD dst_unused:UNUSED_PAD src0_sel:WORD_1 src1_sel:DWORD
	v_and_b32_sdwa v5, v0, v216 dst_sel:DWORD dst_unused:UNUSED_PAD src0_sel:WORD_1 src1_sel:DWORD
	v_add3_u32 v4, v1, v4, s82
	v_add3_u32 v7, v0, v5, s82
	v_and_b32_e32 v107, 0xffff0000, v4
	v_add_u32_e32 v106, v2, v135
	v_and_b32_e32 v2, 0xffff0000, v7
	v_or_b32_sdwa v5, v107, v3 dst_sel:DWORD dst_unused:UNUSED_PAD src0_sel:DWORD src1_sel:WORD_1
	v_sub_u32_e32 v0, v0, v2
	v_sub_u32_e32 v2, v108, v6
	v_and_b32_e32 v3, 0xffff0000, v3
	v_add_u32_e32 v2, 0x80, v2
	v_sub_u32_e32 v3, v109, v3
	v_sub_u32_e32 v1, v1, v107
	v_add_u32_e32 v0, 0x80, v0
	v_ashrrev_i32_e32 v2, 8, v2
	v_add_u32_e32 v3, 0x80, v3
	v_add_u32_e32 v1, 0x80, v1
	v_ashrrev_i32_e32 v0, 8, v0
	v_min_i32_e32 v2, 0x7f, v2
	v_ashrrev_i32_e32 v3, 8, v3
	v_ashrrev_i32_e32 v1, 8, v1
	v_min_i32_e32 v0, 0x7f, v0
	v_min_i32_sdwa v3, v3, s83 dst_sel:WORD_1 dst_unused:UNUSED_PAD src0_sel:DWORD src1_sel:DWORD
	v_min_i32_e32 v1, 0x7f, v1
	v_lshlrev_b32_e32 v2, 8, v2
	v_and_b32_e32 v2, 0xff00, v2
	v_and_b32_e32 v3, 0xff0000, v3
	v_perm_b32 v0, v1, v0, s84
	v_or_b32_sdwa v4, v7, v6 dst_sel:DWORD dst_unused:UNUSED_PAD src0_sel:WORD_1 src1_sel:DWORD
	v_or3_b32 v0, v0, v2, v3
	ds_write_b64 v106, v[4:5]
	ds_write_b32 v22, v0 offset:16
	v_mov_b32_e32 v0, v228
	v_mov_b32_e32 v1, v229
	v_mov_b32_e32 v2, v230
	v_mov_b32_e32 v3, v231
	v_mov_b32_e32 v4, v244
	v_mov_b32_e32 v5, v245
	v_mov_b32_e32 v6, v246
	v_mov_b32_e32 v7, v247
	v_mov_b32_e32 v114, v210
	v_mov_b32_e32 v115, v211
	v_add_u32_e32 v107, v122, v153
	v_pk_add_f32 v[118:119], v[118:119], v[114:115] op_sel_hi:[1,0] neg_lo:[0,1] neg_hi:[0,1]
	s_nop 0
	v_pk_mul_f32 v[118:119], v[114:115], v[118:119] op_sel:[1,0]
;     ...
;           _Pragma("unroll") for (int bj = 0; bj < 2; ++bj) _Pragma("unroll") for (int n = 0; n < 2; ++n) {
;             const int cc = bj * HALF + wc3 * 32 + n * 16 + fq3 * 4;
;             const float4 gm = *reinterpret_cast<const float4*>(g.gam + pn * BM + cc), bt = *reinterpret_cast<const float4*>(g.bet + pn * BM + cc);
;             _Pragma("unroll") for (int m = 0; m < 4; ++m) {
;               const int rr = wr3 * 64 + m * 16 + fr3;
;               const float2 ms = *reinterpret_cast<const float2*>(mr + (ai * HALF + rr) * 2);
;               f32x4 y = acc[ai][bj][m][n];
;               const float o0 = (y[0] - ms.x) * ms.y * gm.x + bt.x, o1 = (y[1] - ms.x) * ms.y * gm.y + bt.y;
;               const float o2 = (y[2] - ms.x) * ms.y * gm.z + bt.z, o3 = (y[3] - ms.x) * ms.y * gm.w + bt.w;
;               const unsigned h0 = f2bf(o0), h1 = f2bf(o1), h2 = f2bf(o2), h3 = f2bf(o3);
;               u32x2 ob; ob[0] = h0 | (h1 << 16); ob[1] = h2 | (h3 << 16);
;               *reinterpret_cast<u32x2*>(smem + (rr >> 1) * PIECE + (rr & 1) * 512 + cc * 2) = ob;
;               const int l0 = min(((int)__float_as_uint(o0) - (int)(h0 << 16) + 128) >> 8, 127);
;               const int l1 = min(((int)__float_as_uint(o1) - (int)(h1 << 16) + 128) >> 8, 127);
;               const int l2 = min(((int)__float_as_uint(o2) - (int)(h2 << 16) + 128) >> 8, 127);
;               const int l3 = min(((int)__float_as_uint(o3) - (int)(h3 << 16) + 128) >> 8, 127);
;               *reinterpret_cast<unsigned*>(smem + LOBASE + (rr >> 2) * PIECE + (rr & 3) * 256 + cc) =
;                   (unsigned)(l0 & 255) | ((unsigned)(l1 & 255) << 8) | ((unsigned)(l2 & 255) << 16) | ((unsigned)l3 << 24);
;             }
	v_pk_add_f32 v[120:121], v[120:121], v[114:115] op_sel_hi:[1,0] neg_lo:[0,1] neg_hi:[0,1]
	v_mov_b32_e32 v108, v1
	v_mov_b32_e32 v109, v2
	v_mov_b32_e32 v110, v5
	v_mov_b32_e32 v111, v6
	v_pk_fma_f32 v[118:119], v[108:109], v[118:119], v[110:111]
	v_pk_mul_f32 v[114:115], v[114:115], v[120:121] op_sel:[1,0]
	v_mov_b32_e32 v1, v3
	v_mov_b32_e32 v5, v7
	v_and_b32_sdwa v6, v119, v216 dst_sel:DWORD dst_unused:UNUSED_PAD src0_sel:WORD_1 src1_sel:DWORD
	v_and_b32_sdwa v7, v118, v216 dst_sel:DWORD dst_unused:UNUSED_PAD src0_sel:WORD_1 src1_sel:DWORD
	v_pk_fma_f32 v[2:3], v[0:1], v[114:115], v[4:5]
	v_add3_u32 v114, v119, v6, s82
	v_add3_u32 v6, v118, v7, s82
	v_and_b32_e32 v115, 0xffff0000, v6
	v_and_b32_sdwa v6, v3, v216 dst_sel:DWORD dst_unused:UNUSED_PAD src0_sel:WORD_1 src1_sel:DWORD
	v_and_b32_sdwa v7, v2, v216 dst_sel:DWORD dst_unused:UNUSED_PAD src0_sel:WORD_1 src1_sel:DWORD
	v_add3_u32 v6, v3, v6, s82
	v_add3_u32 v120, v2, v7, s82
	v_and_b32_e32 v121, 0xffff0000, v6
	v_or_b32_sdwa v7, v121, v114 dst_sel:DWORD dst_unused:UNUSED_PAD src0_sel:DWORD src1_sel:WORD_1
	v_or_b32_sdwa v6, v120, v115 dst_sel:DWORD dst_unused:UNUSED_PAD src0_sel:WORD_1 src1_sel:DWORD
	ds_write_b64 v107, v[6:7]
	v_and_b32_e32 v6, 0xffff0000, v120
	v_sub_u32_e32 v2, v2, v6
	v_sub_u32_e32 v6, v118, v115
	v_and_b32_e32 v7, 0xffff0000, v114
	v_add_u32_e32 v6, 0x80, v6
	v_sub_u32_e32 v7, v119, v7
	v_sub_u32_e32 v3, v3, v121
	v_add_u32_e32 v2, 0x80, v2
	v_ashrrev_i32_e32 v6, 8, v6
	v_add_u32_e32 v7, 0x80, v7
	v_add_u32_e32 v3, 0x80, v3
	v_ashrrev_i32_e32 v2, 8, v2
	v_min_i32_e32 v6, 0x7f, v6
	v_ashrrev_i32_e32 v7, 8, v7
	v_ashrrev_i32_e32 v3, 8, v3
	v_min_i32_e32 v2, 0x7f, v2
	v_min_i32_sdwa v7, v7, s83 dst_sel:WORD_1 dst_unused:UNUSED_PAD src0_sel:DWORD src1_sel:DWORD
	v_min_i32_e32 v3, 0x7f, v3
	v_lshlrev_b32_e32 v6, 8, v6
	v_and_b32_e32 v6, 0xff00, v6
	v_and_b32_e32 v7, 0xff0000, v7
	v_perm_b32 v2, v3, v2, s84
	v_or3_b32 v2, v2, v6, v7
	ds_write_b32 v12, v2 offset:128
	v_mov_b32_e32 v2, v212
	v_mov_b32_e32 v3, v213
	v_pk_add_f32 v[6:7], v[102:103], v[2:3] op_sel_hi:[1,0] neg_lo:[0,1] neg_hi:[0,1]
	s_nop 0
	v_pk_mul_f32 v[6:7], v[2:3], v[6:7] op_sel:[1,0]
	v_pk_add_f32 v[100:101], v[100:101], v[2:3] op_sel_hi:[1,0] neg_lo:[0,1] neg_hi:[0,1]
	v_pk_fma_f32 v[6:7], v[108:109], v[6:7], v[110:111]
	v_pk_mul_f32 v[2:3], v[2:3], v[100:101] op_sel:[1,0]
	v_and_b32_sdwa v100, v7, v216 dst_sel:DWORD dst_unused:UNUSED_PAD src0_sel:WORD_1 src1_sel:DWORD
	v_and_b32_sdwa v101, v6, v216 dst_sel:DWORD dst_unused:UNUSED_PAD src0_sel:WORD_1 src1_sel:DWORD
	v_pk_fma_f32 v[2:3], v[0:1], v[2:3], v[4:5]
	v_add3_u32 v114, v7, v100, s82
	v_add3_u32 v100, v6, v101, s82
	v_and_b32_e32 v101, 0xffff0000, v100
	v_and_b32_sdwa v100, v3, v216 dst_sel:DWORD dst_unused:UNUSED_PAD src0_sel:WORD_1 src1_sel:DWORD
	v_and_b32_sdwa v102, v2, v216 dst_sel:DWORD dst_unused:UNUSED_PAD src0_sel:WORD_1 src1_sel:DWORD
	v_add3_u32 v100, v3, v100, s82
	v_add3_u32 v115, v2, v102, s82
	v_and_b32_e32 v118, 0xffff0000, v100
	v_or_b32_sdwa v103, v118, v114 dst_sel:DWORD dst_unused:UNUSED_PAD src0_sel:DWORD src1_sel:WORD_1
	v_or_b32_sdwa v102, v115, v101 dst_sel:DWORD dst_unused:UNUSED_PAD src0_sel:WORD_1 src1_sel:DWORD
	v_add_u32_e32 v100, v122, v154
	ds_write_b64 v100, v[102:103]
	v_and_b32_e32 v102, 0xffff0000, v115
	v_sub_u32_e32 v6, v6, v101
	v_and_b32_e32 v101, 0xffff0000, v114
	v_sub_u32_e32 v2, v2, v102
	v_add_u32_e32 v6, 0x80, v6
	v_sub_u32_e32 v7, v7, v101
	v_sub_u32_e32 v3, v3, v118
	v_add_u32_e32 v2, 0x80, v2
	v_ashrrev_i32_e32 v6, 8, v6
	v_add_u32_e32 v7, 0x80, v7
	v_add_u32_e32 v3, 0x80, v3
	v_ashrrev_i32_e32 v2, 8, v2
	v_min_i32_e32 v6, 0x7f, v6
	v_ashrrev_i32_e32 v7, 8, v7
	v_ashrrev_i32_e32 v3, 8, v3
	v_min_i32_e32 v2, 0x7f, v2
	v_min_i32_sdwa v7, v7, s83 dst_sel:WORD_1 dst_unused:UNUSED_PAD src0_sel:DWORD src1_sel:DWORD
	v_min_i32_e32 v3, 0x7f, v3
	v_lshlrev_b32_e32 v6, 8, v6
	v_and_b32_e32 v6, 0xff00, v6
	v_and_b32_e32 v7, 0xff0000, v7
	v_perm_b32 v2, v3, v2, s84
	v_or3_b32 v2, v2, v6, v7
	ds_write_b32 v14, v2 offset:128
	v_mov_b32_e32 v2, v214
	v_mov_b32_e32 v3, v215
	v_add_u32_e32 v101, v122, v136
	v_pk_add_f32 v[6:7], v[90:91], v[2:3] op_sel_hi:[1,0] neg_lo:[0,1] neg_hi:[0,1]
	s_nop 0
	v_pk_mul_f32 v[6:7], v[2:3], v[6:7] op_sel:[1,0]
	v_pk_add_f32 v[88:89], v[88:89], v[2:3] op_sel_hi:[1,0] neg_lo:[0,1] neg_hi:[0,1]
	v_pk_fma_f32 v[6:7], v[108:109], v[6:7], v[110:111]
	v_pk_mul_f32 v[2:3], v[2:3], v[88:89] op_sel:[1,0]
	v_and_b32_sdwa v88, v7, v216 dst_sel:DWORD dst_unused:UNUSED_PAD src0_sel:WORD_1 src1_sel:DWORD
	v_and_b32_sdwa v89, v6, v216 dst_sel:DWORD dst_unused:UNUSED_PAD src0_sel:WORD_1 src1_sel:DWORD
	v_pk_fma_f32 v[2:3], v[0:1], v[2:3], v[4:5]
	v_add3_u32 v90, v7, v88, s82
	v_add3_u32 v88, v6, v89, s82
	v_and_b32_e32 v91, 0xffff0000, v88
	v_and_b32_sdwa v88, v3, v216 dst_sel:DWORD dst_unused:UNUSED_PAD src0_sel:WORD_1 src1_sel:DWORD
	v_and_b32_sdwa v89, v2, v216 dst_sel:DWORD dst_unused:UNUSED_PAD src0_sel:WORD_1 src1_sel:DWORD
	v_add3_u32 v88, v3, v88, s82
	v_add3_u32 v102, v2, v89, s82
	v_and_b32_e32 v103, 0xffff0000, v88
	v_or_b32_sdwa v89, v103, v90 dst_sel:DWORD dst_unused:UNUSED_PAD src0_sel:DWORD src1_sel:WORD_1
	v_or_b32_sdwa v88, v102, v91 dst_sel:DWORD dst_unused:UNUSED_PAD src0_sel:WORD_1 src1_sel:DWORD
	ds_write_b64 v101, v[88:89]
	v_and_b32_e32 v88, 0xffff0000, v102
	v_sub_u32_e32 v2, v2, v88
	v_sub_u32_e32 v6, v6, v91
	v_and_b32_e32 v88, 0xffff0000, v90
	v_add_u32_e32 v6, 0x80, v6
	v_sub_u32_e32 v7, v7, v88
	v_sub_u32_e32 v3, v3, v103
	v_add_u32_e32 v2, 0x80, v2
	v_ashrrev_i32_e32 v6, 8, v6
	v_add_u32_e32 v7, 0x80, v7
	v_add_u32_e32 v3, 0x80, v3
	v_ashrrev_i32_e32 v2, 8, v2
;     ...
;           _Pragma("unroll") for (int bj = 0; bj < 2; ++bj) _Pragma("unroll") for (int n = 0; n < 2; ++n) {
;             const int cc = bj * HALF + wc3 * 32 + n * 16 + fq3 * 4;
;             const float4 gm = *reinterpret_cast<const float4*>(g.gam + pn * BM + cc), bt = *reinterpret_cast<const float4*>(g.bet + pn * BM + cc);
;             _Pragma("unroll") for (int m = 0; m < 4; ++m) {
;               const int rr = wr3 * 64 + m * 16 + fr3;
;               const float2 ms = *reinterpret_cast<const float2*>(mr + (ai * HALF + rr) * 2);
;               f32x4 y = acc[ai][bj][m][n];
;               const float o0 = (y[0] - ms.x) * ms.y * gm.x + bt.x, o1 = (y[1] - ms.x) * ms.y * gm.y + bt.y;
;               const float o2 = (y[2] - ms.x) * ms.y * gm.z + bt.z, o3 = (y[3] - ms.x) * ms.y * gm.w + bt.w;
;               const unsigned h0 = f2bf(o0), h1 = f2bf(o1), h2 = f2bf(o2), h3 = f2bf(o3);
;               u32x2 ob; ob[0] = h0 | (h1 << 16); ob[1] = h2 | (h3 << 16);
;               *reinterpret_cast<u32x2*>(smem + (rr >> 1) * PIECE + (rr & 1) * 512 + cc * 2) = ob;
;               const int l0 = min(((int)__float_as_uint(o0) - (int)(h0 << 16) + 128) >> 8, 127);
;               const int l1 = min(((int)__float_as_uint(o1) - (int)(h1 << 16) + 128) >> 8, 127);
;               const int l2 = min(((int)__float_as_uint(o2) - (int)(h2 << 16) + 128) >> 8, 127);
;               const int l3 = min(((int)__float_as_uint(o3) - (int)(h3 << 16) + 128) >> 8, 127);
;               *reinterpret_cast<unsigned*>(smem + LOBASE + (rr >> 2) * PIECE + (rr & 3) * 256 + cc) =
;                   (unsigned)(l0 & 255) | ((unsigned)(l1 & 255) << 8) | ((unsigned)(l2 & 255) << 16) | ((unsigned)l3 << 24);
;             }
	v_min_i32_e32 v6, 0x7f, v6
	v_ashrrev_i32_e32 v7, 8, v7
	v_ashrrev_i32_e32 v3, 8, v3
	v_min_i32_e32 v2, 0x7f, v2
	v_min_i32_sdwa v7, v7, s83 dst_sel:WORD_1 dst_unused:UNUSED_PAD src0_sel:DWORD src1_sel:DWORD
	v_min_i32_e32 v3, 0x7f, v3
	v_lshlrev_b32_e32 v6, 8, v6
	v_and_b32_e32 v6, 0xff00, v6
	v_and_b32_e32 v7, 0xff0000, v7
	v_perm_b32 v2, v3, v2, s84
	v_or3_b32 v2, v2, v6, v7
	ds_write_b32 v20, v2 offset:128
	v_mov_b32_e32 v2, v252
	v_mov_b32_e32 v3, v253
	v_pk_add_f32 v[6:7], v[94:95], v[2:3] op_sel_hi:[1,0] neg_lo:[0,1] neg_hi:[0,1]
	s_nop 0
	v_pk_mul_f32 v[6:7], v[2:3], v[6:7] op_sel:[1,0]
	v_pk_add_f32 v[88:89], v[92:93], v[2:3] op_sel_hi:[1,0] neg_lo:[0,1] neg_hi:[0,1]
	v_pk_fma_f32 v[6:7], v[108:109], v[6:7], v[110:111]
	v_pk_mul_f32 v[2:3], v[2:3], v[88:89] op_sel:[1,0]
	v_add_u32_e32 v92, v122, v135
	v_pk_fma_f32 v[0:1], v[0:1], v[2:3], v[4:5]
	v_and_b32_sdwa v2, v7, v216 dst_sel:DWORD dst_unused:UNUSED_PAD src0_sel:WORD_1 src1_sel:DWORD
	v_and_b32_sdwa v3, v6, v216 dst_sel:DWORD dst_unused:UNUSED_PAD src0_sel:WORD_1 src1_sel:DWORD
	v_add3_u32 v4, v7, v2, s82
	v_add3_u32 v2, v6, v3, s82
	v_and_b32_e32 v5, 0xffff0000, v2
	v_and_b32_sdwa v2, v1, v216 dst_sel:DWORD dst_unused:UNUSED_PAD src0_sel:WORD_1 src1_sel:DWORD
	v_and_b32_sdwa v3, v0, v216 dst_sel:DWORD dst_unused:UNUSED_PAD src0_sel:WORD_1 src1_sel:DWORD
	v_add3_u32 v2, v1, v2, s82
	v_add3_u32 v88, v0, v3, s82
	v_and_b32_e32 v89, 0xffff0000, v2
	v_or_b32_sdwa v3, v89, v4 dst_sel:DWORD dst_unused:UNUSED_PAD src0_sel:DWORD src1_sel:WORD_1
	v_or_b32_sdwa v2, v88, v5 dst_sel:DWORD dst_unused:UNUSED_PAD src0_sel:WORD_1 src1_sel:DWORD
	ds_write_b64 v92, v[2:3]
	v_and_b32_e32 v2, 0xffff0000, v88
	v_sub_u32_e32 v0, v0, v2
	v_sub_u32_e32 v2, v6, v5
	v_and_b32_e32 v3, 0xffff0000, v4
	v_add_u32_e32 v2, 0x80, v2
	v_sub_u32_e32 v3, v7, v3
	v_sub_u32_e32 v1, v1, v89
	v_add_u32_e32 v0, 0x80, v0
	v_ashrrev_i32_e32 v2, 8, v2
	v_add_u32_e32 v3, 0x80, v3
	v_add_u32_e32 v1, 0x80, v1
	v_ashrrev_i32_e32 v0, 8, v0
	v_min_i32_e32 v2, 0x7f, v2
	v_ashrrev_i32_e32 v3, 8, v3
	v_ashrrev_i32_e32 v1, 8, v1
	v_min_i32_e32 v0, 0x7f, v0
	v_min_i32_sdwa v3, v3, s83 dst_sel:WORD_1 dst_unused:UNUSED_PAD src0_sel:DWORD src1_sel:DWORD
	v_min_i32_e32 v1, 0x7f, v1
	v_lshlrev_b32_e32 v2, 8, v2
	v_and_b32_e32 v2, 0xff00, v2
	v_and_b32_e32 v3, 0xff0000, v3
	v_perm_b32 v0, v1, v0, s84
	v_or3_b32 v0, v0, v2, v3
	ds_write_b32 v22, v0 offset:128
	v_mov_b32_e32 v0, v232
	v_mov_b32_e32 v1, v233
	v_mov_b32_e32 v2, v234
	v_mov_b32_e32 v3, v235
	v_mov_b32_e32 v4, v248
	v_mov_b32_e32 v5, v249
	v_mov_b32_e32 v6, v250
	v_mov_b32_e32 v7, v251
	v_mov_b32_e32 v94, v210
	v_mov_b32_e32 v95, v211
	v_pk_add_f32 v[102:103], v[116:117], v[94:95] op_sel_hi:[1,0] neg_lo:[0,1] neg_hi:[0,1]
	s_nop 0
	v_pk_mul_f32 v[102:103], v[94:95], v[102:103] op_sel:[1,0]
	v_pk_add_f32 v[108:109], v[112:113], v[94:95] op_sel_hi:[1,0] neg_lo:[0,1] neg_hi:[0,1]
	v_mov_b32_e32 v88, v1
	v_mov_b32_e32 v89, v2
	v_mov_b32_e32 v90, v5
	v_mov_b32_e32 v91, v6
	v_pk_fma_f32 v[102:103], v[88:89], v[102:103], v[90:91]
	v_pk_mul_f32 v[94:95], v[94:95], v[108:109] op_sel:[1,0]
	v_mov_b32_e32 v1, v3
	v_mov_b32_e32 v5, v7
	v_and_b32_sdwa v93, v102, v216 dst_sel:DWORD dst_unused:UNUSED_PAD src0_sel:WORD_1 src1_sel:DWORD
	v_pk_fma_f32 v[6:7], v[0:1], v[94:95], v[4:5]
	v_add3_u32 v93, v102, v93, s82
	v_and_b32_e32 v108, 0xffff0000, v93
	v_and_b32_sdwa v93, v7, v216 dst_sel:DWORD dst_unused:UNUSED_PAD src0_sel:WORD_1 src1_sel:DWORD
	v_and_b32_sdwa v3, v103, v216 dst_sel:DWORD dst_unused:UNUSED_PAD src0_sel:WORD_1 src1_sel:DWORD
	v_and_b32_sdwa v94, v6, v216 dst_sel:DWORD dst_unused:UNUSED_PAD src0_sel:WORD_1 src1_sel:DWORD
	v_add3_u32 v93, v7, v93, s82
	v_or_b32_e32 v2, 0x120, v155
	v_add3_u32 v3, v103, v3, s82
	v_add3_u32 v109, v6, v94, s82
	v_and_b32_e32 v110, 0xffff0000, v93
	v_or_b32_sdwa v95, v110, v3 dst_sel:DWORD dst_unused:UNUSED_PAD src0_sel:DWORD src1_sel:WORD_1
	v_or_b32_sdwa v94, v109, v108 dst_sel:DWORD dst_unused:UNUSED_PAD src0_sel:WORD_1 src1_sel:DWORD
	v_add_u32_e32 v93, v2, v153
	ds_write_b64 v93, v[94:95]
	v_and_b32_e32 v94, 0xffff0000, v109
	v_sub_u32_e32 v6, v6, v94
	v_sub_u32_e32 v94, v102, v108
	v_and_b32_e32 v3, 0xffff0000, v3
	v_add_u32_e32 v94, 0x80, v94
	v_sub_u32_e32 v3, v103, v3
	v_sub_u32_e32 v7, v7, v110
	v_add_u32_e32 v6, 0x80, v6
	v_ashrrev_i32_e32 v94, 8, v94
	v_add_u32_e32 v3, 0x80, v3
	v_add_u32_e32 v7, 0x80, v7
	v_ashrrev_i32_e32 v6, 8, v6
	v_min_i32_e32 v94, 0x7f, v94
	v_ashrrev_i32_e32 v3, 8, v3
	v_ashrrev_i32_e32 v7, 8, v7
	v_min_i32_e32 v6, 0x7f, v6
	v_min_i32_sdwa v3, v3, s83 dst_sel:WORD_1 dst_unused:UNUSED_PAD src0_sel:DWORD src1_sel:DWORD
	v_min_i32_e32 v7, 0x7f, v7
	v_lshlrev_b32_e32 v94, 8, v94
	v_and_b32_e32 v94, 0xff00, v94
	v_and_b32_e32 v3, 0xff0000, v3
	v_perm_b32 v6, v7, v6, s84
	v_or3_b32 v3, v6, v94, v3
	ds_write_b32 v12, v3 offset:144
	v_mov_b32_e32 v6, v212
	v_mov_b32_e32 v7, v213
	v_pk_add_f32 v[94:95], v[98:99], v[6:7] op_sel_hi:[1,0] neg_lo:[0,1] neg_hi:[0,1]
	s_nop 0
	v_pk_mul_f32 v[94:95], v[6:7], v[94:95] op_sel:[1,0]
	s_nop 0
	v_pk_fma_f32 v[98:99], v[88:89], v[94:95], v[90:91]
	v_pk_add_f32 v[94:95], v[96:97], v[6:7] op_sel_hi:[1,0] neg_lo:[0,1] neg_hi:[0,1]
	v_and_b32_sdwa v3, v99, v216 dst_sel:DWORD dst_unused:UNUSED_PAD src0_sel:WORD_1 src1_sel:DWORD
	v_pk_mul_f32 v[6:7], v[6:7], v[94:95] op_sel:[1,0]
	v_and_b32_sdwa v94, v98, v216 dst_sel:DWORD dst_unused:UNUSED_PAD src0_sel:WORD_1 src1_sel:DWORD
	v_pk_fma_f32 v[6:7], v[0:1], v[6:7], v[4:5]
	v_add3_u32 v94, v98, v94, s82
	v_and_b32_e32 v95, 0xffff0000, v94
	v_and_b32_sdwa v94, v7, v216 dst_sel:DWORD dst_unused:UNUSED_PAD src0_sel:WORD_1 src1_sel:DWORD
; #define WAIT_L(n) asm volatile("s_waitcnt lgkmcnt(" #n ")" ::: "memory")
; #define BAR __builtin_amdgcn_s_barrier()
;     ...
;           _Pragma("unroll") for (int bj = 0; bj < 2; ++bj) _Pragma("unroll") for (int n = 0; n < 2; ++n) {
;             const int cc = bj * HALF + wc3 * 32 + n * 16 + fq3 * 4;
;             const float4 gm = *reinterpret_cast<const float4*>(g.gam + pn * BM + cc), bt = *reinterpret_cast<const float4*>(g.bet + pn * BM + cc);
;             _Pragma("unroll") for (int m = 0; m < 4; ++m) {
;               const int rr = wr3 * 64 + m * 16 + fr3;
;               const float2 ms = *reinterpret_cast<const float2*>(mr + (ai * HALF + rr) * 2);
;               f32x4 y = acc[ai][bj][m][n];
;               const float o0 = (y[0] - ms.x) * ms.y * gm.x + bt.x, o1 = (y[1] - ms.x) * ms.y * gm.y + bt.y;
;               const float o2 = (y[2] - ms.x) * ms.y * gm.z + bt.z, o3 = (y[3] - ms.x) * ms.y * gm.w + bt.w;
;               const unsigned h0 = f2bf(o0), h1 = f2bf(o1), h2 = f2bf(o2), h3 = f2bf(o3);
;               u32x2 ob; ob[0] = h0 | (h1 << 16); ob[1] = h2 | (h3 << 16);
;               *reinterpret_cast<u32x2*>(smem + (rr >> 1) * PIECE + (rr & 1) * 512 + cc * 2) = ob;
;               const int l0 = min(((int)__float_as_uint(o0) - (int)(h0 << 16) + 128) >> 8, 127);
;               const int l1 = min(((int)__float_as_uint(o1) - (int)(h1 << 16) + 128) >> 8, 127);
;               const int l2 = min(((int)__float_as_uint(o2) - (int)(h2 << 16) + 128) >> 8, 127);
;               const int l3 = min(((int)__float_as_uint(o3) - (int)(h3 << 16) + 128) >> 8, 127);
;               *reinterpret_cast<unsigned*>(smem + LOBASE + (rr >> 2) * PIECE + (rr & 3) * 256 + cc) =
;                   (unsigned)(l0 & 255) | ((unsigned)(l1 & 255) << 8) | ((unsigned)(l2 & 255) << 16) | ((unsigned)l3 << 24);
;             }
;           }
;           WAIT_L(0); BAR;
	v_and_b32_sdwa v96, v6, v216 dst_sel:DWORD dst_unused:UNUSED_PAD src0_sel:WORD_1 src1_sel:DWORD
	v_add3_u32 v94, v7, v94, s82
	v_add3_u32 v3, v99, v3, s82
	v_add3_u32 v102, v6, v96, s82
	v_and_b32_e32 v103, 0xffff0000, v94
	v_or_b32_sdwa v97, v103, v3 dst_sel:DWORD dst_unused:UNUSED_PAD src0_sel:DWORD src1_sel:WORD_1
	v_or_b32_sdwa v96, v102, v95 dst_sel:DWORD dst_unused:UNUSED_PAD src0_sel:WORD_1 src1_sel:DWORD
	v_add_u32_e32 v94, v2, v154
	ds_write_b64 v94, v[96:97]
	v_and_b32_e32 v96, 0xffff0000, v102
	v_sub_u32_e32 v95, v98, v95
	v_and_b32_e32 v3, 0xffff0000, v3
	v_sub_u32_e32 v6, v6, v96
	v_add_u32_e32 v95, 0x80, v95
	v_sub_u32_e32 v3, v99, v3
	v_sub_u32_e32 v7, v7, v103
	v_add_u32_e32 v6, 0x80, v6
	v_ashrrev_i32_e32 v95, 8, v95
	v_add_u32_e32 v3, 0x80, v3
	v_add_u32_e32 v7, 0x80, v7
	v_ashrrev_i32_e32 v6, 8, v6
	v_min_i32_e32 v95, 0x7f, v95
	v_ashrrev_i32_e32 v3, 8, v3
	v_ashrrev_i32_e32 v7, 8, v7
	v_min_i32_e32 v6, 0x7f, v6
	v_min_i32_sdwa v3, v3, s83 dst_sel:WORD_1 dst_unused:UNUSED_PAD src0_sel:DWORD src1_sel:DWORD
	v_min_i32_e32 v7, 0x7f, v7
	v_lshlrev_b32_e32 v95, 8, v95
	v_and_b32_e32 v95, 0xff00, v95
	v_and_b32_e32 v3, 0xff0000, v3
	v_perm_b32 v6, v7, v6, s84
	v_or3_b32 v3, v6, v95, v3
	ds_write_b32 v14, v3 offset:144
	v_mov_b32_e32 v6, v214
	v_mov_b32_e32 v7, v215
	v_pk_add_f32 v[82:83], v[82:83], v[6:7] op_sel_hi:[1,0] neg_lo:[0,1] neg_hi:[0,1]
	s_nop 0
	v_pk_mul_f32 v[82:83], v[6:7], v[82:83] op_sel:[1,0]
	v_pk_add_f32 v[80:81], v[80:81], v[6:7] op_sel_hi:[1,0] neg_lo:[0,1] neg_hi:[0,1]
	v_pk_fma_f32 v[82:83], v[88:89], v[82:83], v[90:91]
	v_pk_mul_f32 v[6:7], v[6:7], v[80:81] op_sel:[1,0]
	v_and_b32_sdwa v80, v82, v216 dst_sel:DWORD dst_unused:UNUSED_PAD src0_sel:WORD_1 src1_sel:DWORD
	v_pk_fma_f32 v[6:7], v[0:1], v[6:7], v[4:5]
	v_add3_u32 v80, v82, v80, s82
	v_and_b32_e32 v81, 0xffff0000, v80
	v_and_b32_sdwa v80, v7, v216 dst_sel:DWORD dst_unused:UNUSED_PAD src0_sel:WORD_1 src1_sel:DWORD
	v_and_b32_sdwa v3, v83, v216 dst_sel:DWORD dst_unused:UNUSED_PAD src0_sel:WORD_1 src1_sel:DWORD
	v_and_b32_sdwa v95, v6, v216 dst_sel:DWORD dst_unused:UNUSED_PAD src0_sel:WORD_1 src1_sel:DWORD
	v_add3_u32 v80, v7, v80, s82
	v_add3_u32 v3, v83, v3, s82
	v_add3_u32 v95, v6, v95, s82
	v_and_b32_e32 v98, 0xffff0000, v80
	v_or_b32_sdwa v97, v98, v3 dst_sel:DWORD dst_unused:UNUSED_PAD src0_sel:DWORD src1_sel:WORD_1
	v_or_b32_sdwa v96, v95, v81 dst_sel:DWORD dst_unused:UNUSED_PAD src0_sel:WORD_1 src1_sel:DWORD
	v_and_b32_e32 v95, 0xffff0000, v95
	v_sub_u32_e32 v81, v82, v81
	v_and_b32_e32 v3, 0xffff0000, v3
	v_sub_u32_e32 v6, v6, v95
	v_add_u32_e32 v81, 0x80, v81
	v_sub_u32_e32 v3, v83, v3
	v_sub_u32_e32 v7, v7, v98
	v_add_u32_e32 v6, 0x80, v6
	v_ashrrev_i32_e32 v81, 8, v81
	v_add_u32_e32 v3, 0x80, v3
	v_add_u32_e32 v7, 0x80, v7
	v_ashrrev_i32_e32 v6, 8, v6
	v_min_i32_e32 v81, 0x7f, v81
	v_ashrrev_i32_e32 v3, 8, v3
	v_ashrrev_i32_e32 v7, 8, v7
	v_min_i32_e32 v6, 0x7f, v6
	v_min_i32_sdwa v3, v3, s83 dst_sel:WORD_1 dst_unused:UNUSED_PAD src0_sel:DWORD src1_sel:DWORD
	v_min_i32_e32 v7, 0x7f, v7
	v_lshlrev_b32_e32 v81, 8, v81
	v_and_b32_e32 v81, 0xff00, v81
	v_and_b32_e32 v3, 0xff0000, v3
	v_perm_b32 v6, v7, v6, s84
	v_add_u32_e32 v80, v2, v136
	v_or3_b32 v3, v6, v81, v3
	ds_write_b64 v80, v[96:97]
	ds_write_b32 v20, v3 offset:144
	v_mov_b32_e32 v6, v252
	v_mov_b32_e32 v7, v253
	v_or_b32_e32 v81, 0x6000, v148
	v_or_b32_e32 v82, 0x8000, v148
	v_or_b32_e32 v83, 0xa000, v148
	v_or_b32_e32 v95, 0x6000, v146
	v_pk_add_f32 v[74:75], v[74:75], v[6:7] op_sel_hi:[1,0] neg_lo:[0,1] neg_hi:[0,1]
	v_pk_add_f32 v[72:73], v[72:73], v[6:7] op_sel_hi:[1,0] neg_lo:[0,1] neg_hi:[0,1]
	v_pk_mul_f32 v[74:75], v[6:7], v[74:75] op_sel:[1,0]
	v_pk_mul_f32 v[6:7], v[6:7], v[72:73] op_sel:[1,0]
	v_pk_fma_f32 v[74:75], v[88:89], v[74:75], v[90:91]
	v_pk_fma_f32 v[0:1], v[0:1], v[6:7], v[4:5]
	v_and_b32_sdwa v4, v74, v216 dst_sel:DWORD dst_unused:UNUSED_PAD src0_sel:WORD_1 src1_sel:DWORD
	v_add3_u32 v4, v74, v4, s82
	v_and_b32_e32 v6, 0xffff0000, v4
	v_and_b32_sdwa v4, v1, v216 dst_sel:DWORD dst_unused:UNUSED_PAD src0_sel:WORD_1 src1_sel:DWORD
	v_and_b32_sdwa v5, v0, v216 dst_sel:DWORD dst_unused:UNUSED_PAD src0_sel:WORD_1 src1_sel:DWORD
	v_and_b32_sdwa v3, v75, v216 dst_sel:DWORD dst_unused:UNUSED_PAD src0_sel:WORD_1 src1_sel:DWORD
	v_add3_u32 v4, v1, v4, s82
	v_add3_u32 v7, v0, v5, s82
	v_add3_u32 v3, v75, v3, s82
	v_and_b32_e32 v72, 0xffff0000, v4
	v_add_u32_e32 v73, v2, v135
	v_and_b32_e32 v2, 0xffff0000, v7
	v_or_b32_sdwa v5, v72, v3 dst_sel:DWORD dst_unused:UNUSED_PAD src0_sel:DWORD src1_sel:WORD_1
	v_sub_u32_e32 v0, v0, v2
	v_sub_u32_e32 v2, v74, v6
	v_and_b32_e32 v3, 0xffff0000, v3
	v_add_u32_e32 v2, 0x80, v2
	v_sub_u32_e32 v3, v75, v3
	v_sub_u32_e32 v1, v1, v72
	v_add_u32_e32 v0, 0x80, v0
	v_ashrrev_i32_e32 v2, 8, v2
	v_add_u32_e32 v3, 0x80, v3
	v_add_u32_e32 v1, 0x80, v1
	v_ashrrev_i32_e32 v0, 8, v0
	v_min_i32_e32 v2, 0x7f, v2
	v_ashrrev_i32_e32 v3, 8, v3
	v_ashrrev_i32_e32 v1, 8, v1
	v_min_i32_e32 v0, 0x7f, v0
	v_min_i32_sdwa v3, v3, s83 dst_sel:WORD_1 dst_unused:UNUSED_PAD src0_sel:DWORD src1_sel:DWORD
	v_min_i32_e32 v1, 0x7f, v1
	v_lshlrev_b32_e32 v2, 8, v2
	v_and_b32_e32 v2, 0xff00, v2
	v_and_b32_e32 v3, 0xff0000, v3
	v_perm_b32 v0, v1, v0, s84
	v_or_b32_sdwa v4, v7, v6 dst_sel:DWORD dst_unused:UNUSED_PAD src0_sel:WORD_1 src1_sel:DWORD
	v_or3_b32 v0, v0, v2, v3
	ds_write_b64 v73, v[4:5]
	ds_write_b32 v22, v0 offset:144
	v_add_u32_e32 v72, s47, v152
	s_waitcnt lgkmcnt(0)
	s_barrier
;     ...
;           _Pragma("unroll") for (int bj = 0; bj < 2; ++bj) _Pragma("unroll") for (int n = 0; n < 2; ++n) {
;             const int cc = bj * HALF + wc3 * 32 + n * 16 + fq3 * 4;
;             const float4 gm = *reinterpret_cast<const float4*>(g.gam + pn * BM + cc), bt = *reinterpret_cast<const float4*>(g.bet + pn * BM + cc);
;             _Pragma("unroll") for (int m = 0; m < 4; ++m) {
;               const int rr = wr3 * 64 + m * 16 + fr3;
;               const float2 ms = *reinterpret_cast<const float2*>(mr + (ai * HALF + rr) * 2);
;               f32x4 y = acc[ai][bj][m][n];
;               const float o0 = (y[0] - ms.x) * ms.y * gm.x + bt.x, o1 = (y[1] - ms.x) * ms.y * gm.y + bt.y;
;               const float o2 = (y[2] - ms.x) * ms.y * gm.z + bt.z, o3 = (y[3] - ms.x) * ms.y * gm.w + bt.w;
;               const unsigned h0 = f2bf(o0), h1 = f2bf(o1), h2 = f2bf(o2), h3 = f2bf(o3);
;               u32x2 ob; ob[0] = h0 | (h1 << 16); ob[1] = h2 | (h3 << 16);
;               *reinterpret_cast<u32x2*>(smem + (rr >> 1) * PIECE + (rr & 1) * 512 + cc * 2) = ob;
;               const int l0 = min(((int)__float_as_uint(o0) - (int)(h0 << 16) + 128) >> 8, 127);
;               const int l1 = min(((int)__float_as_uint(o1) - (int)(h1 << 16) + 128) >> 8, 127);
;               const int l2 = min(((int)__float_as_uint(o2) - (int)(h2 << 16) + 128) >> 8, 127);
;               const int l3 = min(((int)__float_as_uint(o3) - (int)(h3 << 16) + 128) >> 8, 127);
;               *reinterpret_cast<unsigned*>(smem + LOBASE + (rr >> 2) * PIECE + (rr & 3) * 256 + cc) =
;                   (unsigned)(l0 & 255) | ((unsigned)(l1 & 255) << 8) | ((unsigned)(l2 & 255) << 16) | ((unsigned)l3 << 24);
;             }
;     ...
;           _Pragma("unroll") for (int i = 0; i < 8; ++i) {
;             const u32x4 v = *reinterpret_cast<const u32x4*>(smem + (wave * 8 + i) * PIECE + lane3 * 16);
;             __builtin_amdgcn_raw_buffer_store_b128(v, rsXB, hvo + i * (2 * DM * 2), hso, 0);
;           }
;           _Pragma("unroll") for (int i = 0; i < 4; ++i) {
;             const u32x4 v = *reinterpret_cast<const u32x4*>(smem + LOBASE + (wave * 4 + i) * PIECE + lane3 * 16);
;             __builtin_amdgcn_raw_buffer_store_b128(v, rsLO, lvo + i * (4 * DM), lso, 0);
;           }
	ds_read_b128 v[128:131], v72
	v_or_b32_e32 v74, 0x2000, v148
	v_or_b32_e32 v75, 0x4000, v148
	v_or_b32_e32 v88, 0xc000, v148
	v_or_b32_e32 v89, 0xe000, v148
	ds_read_b128 v[136:139], v72 offset:1040
	v_or_b32_e32 v90, 0x2000, v146
	v_or_b32_e32 v91, 0x4000, v146
	ds_read_b128 v[140:143], v72 offset:2080
	ds_read_b128 v[152:155], v72 offset:3120
	ds_read_b128 v[156:159], v72 offset:4160
	ds_read_b128 v[160:163], v72 offset:5200
	ds_read_b128 v[164:167], v72 offset:6240
	ds_read_b128 v[168:171], v72 offset:7280
	ds_read_b128 v[172:175], v147
	ds_read_b128 v[176:179], v147 offset:1040
	ds_read_b128 v[180:183], v147 offset:2080
	ds_read_b128 v[184:187], v147 offset:3120
	s_waitcnt lgkmcnt(0)
	s_barrier
	s_nop 1
	v_mov_b32_e32 v0, v220
	v_mov_b32_e32 v1, v221
	v_mov_b32_e32 v2, v222
	v_mov_b32_e32 v3, v223
	v_mov_b32_e32 v4, v236
	v_mov_b32_e32 v5, v237
	v_mov_b32_e32 v6, v238
	v_mov_b32_e32 v7, v239
	ds_read_b64 v[102:103], v149 offset:1024
	s_waitcnt lgkmcnt(0)
	v_mov_b32_e32 v210, v102
	v_mov_b32_e32 v211, v103
	v_pk_add_f32 v[66:67], v[66:67], v[102:103] op_sel_hi:[1,0] neg_lo:[0,1] neg_hi:[0,1]
	s_nop 0
	v_pk_mul_f32 v[66:67], v[102:103], v[66:67] op_sel:[1,0]
	v_pk_add_f32 v[64:65], v[64:65], v[102:103] op_sel_hi:[1,0] neg_lo:[0,1] neg_hi:[0,1]
	v_mov_b32_e32 v96, v1
	v_mov_b32_e32 v97, v2
	v_mov_b32_e32 v98, v5
	v_mov_b32_e32 v99, v6
	v_pk_fma_f32 v[66:67], v[96:97], v[66:67], v[98:99]
	v_pk_mul_f32 v[64:65], v[102:103], v[64:65] op_sel:[1,0]
	v_mov_b32_e32 v1, v3
	v_mov_b32_e32 v5, v7
	v_and_b32_sdwa v6, v67, v216 dst_sel:DWORD dst_unused:UNUSED_PAD src0_sel:WORD_1 src1_sel:DWORD
	v_and_b32_sdwa v7, v66, v216 dst_sel:DWORD dst_unused:UNUSED_PAD src0_sel:WORD_1 src1_sel:DWORD
	v_pk_fma_f32 v[2:3], v[0:1], v[64:65], v[4:5]
	v_add3_u32 v64, v67, v6, s82
	v_add3_u32 v6, v66, v7, s82
	v_and_b32_e32 v65, 0xffff0000, v6
	v_and_b32_sdwa v6, v3, v216 dst_sel:DWORD dst_unused:UNUSED_PAD src0_sel:WORD_1 src1_sel:DWORD
	v_and_b32_sdwa v7, v2, v216 dst_sel:DWORD dst_unused:UNUSED_PAD src0_sel:WORD_1 src1_sel:DWORD
	v_add3_u32 v6, v3, v6, s82
	v_add3_u32 v102, v2, v7, s82
	v_and_b32_e32 v103, 0xffff0000, v6
	v_or_b32_sdwa v7, v103, v64 dst_sel:DWORD dst_unused:UNUSED_PAD src0_sel:DWORD src1_sel:WORD_1
	v_or_b32_sdwa v6, v102, v65 dst_sel:DWORD dst_unused:UNUSED_PAD src0_sel:WORD_1 src1_sel:DWORD
	ds_write_b64 v151, v[6:7]
	v_and_b32_e32 v6, 0xffff0000, v102
	v_sub_u32_e32 v2, v2, v6
	v_sub_u32_e32 v6, v66, v65
	v_and_b32_e32 v7, 0xffff0000, v64
	v_add_u32_e32 v6, 0x80, v6
	v_sub_u32_e32 v7, v67, v7
	v_sub_u32_e32 v3, v3, v103
	v_add_u32_e32 v2, 0x80, v2
	v_ashrrev_i32_e32 v6, 8, v6
	v_add_u32_e32 v7, 0x80, v7
	v_add_u32_e32 v3, 0x80, v3
	v_ashrrev_i32_e32 v2, 8, v2
	v_min_i32_e32 v6, 0x7f, v6
	v_ashrrev_i32_e32 v7, 8, v7
	v_ashrrev_i32_e32 v3, 8, v3
	v_min_i32_e32 v2, 0x7f, v2
	v_min_i32_sdwa v7, v7, s83 dst_sel:WORD_1 dst_unused:UNUSED_PAD src0_sel:DWORD src1_sel:DWORD
	v_min_i32_e32 v3, 0x7f, v3
	v_lshlrev_b32_e32 v6, 8, v6
	v_and_b32_e32 v6, 0xff00, v6
	v_and_b32_e32 v7, 0xff0000, v7
	v_perm_b32 v2, v3, v2, s84
	v_or3_b32 v2, v2, v6, v7
	ds_write_b32 v12, v2
	buffer_store_dwordx4 v[128:131], v148, s[16:19], s33 offen
	ds_read_b64 v[2:3], v13 offset:1024
	s_waitcnt lgkmcnt(0)
	v_mov_b32_e32 v212, v2
	v_mov_b32_e32 v213, v3
	v_pk_add_f32 v[6:7], v[70:71], v[2:3] op_sel_hi:[1,0] neg_lo:[0,1] neg_hi:[0,1]
	s_nop 0
	v_pk_mul_f32 v[6:7], v[2:3], v[6:7] op_sel:[1,0]
	v_pk_add_f32 v[64:65], v[68:69], v[2:3] op_sel_hi:[1,0] neg_lo:[0,1] neg_hi:[0,1]
	v_pk_fma_f32 v[6:7], v[96:97], v[6:7], v[98:99]
	v_pk_mul_f32 v[2:3], v[2:3], v[64:65] op_sel:[1,0]
	v_and_b32_sdwa v64, v7, v216 dst_sel:DWORD dst_unused:UNUSED_PAD src0_sel:WORD_1 src1_sel:DWORD
	v_and_b32_sdwa v65, v6, v216 dst_sel:DWORD dst_unused:UNUSED_PAD src0_sel:WORD_1 src1_sel:DWORD
	v_pk_fma_f32 v[2:3], v[0:1], v[2:3], v[4:5]
	v_add3_u32 v66, v7, v64, s82
	v_add3_u32 v64, v6, v65, s82
	v_and_b32_e32 v67, 0xffff0000, v64
	v_and_b32_sdwa v64, v3, v216 dst_sel:DWORD dst_unused:UNUSED_PAD src0_sel:WORD_1 src1_sel:DWORD
	v_and_b32_sdwa v65, v2, v216 dst_sel:DWORD dst_unused:UNUSED_PAD src0_sel:WORD_1 src1_sel:DWORD
	v_add3_u32 v64, v3, v64, s82
	v_add3_u32 v68, v2, v65, s82
	v_and_b32_e32 v69, 0xffff0000, v64
	v_or_b32_sdwa v65, v69, v66 dst_sel:DWORD dst_unused:UNUSED_PAD src0_sel:DWORD src1_sel:WORD_1
	v_or_b32_sdwa v64, v68, v67 dst_sel:DWORD dst_unused:UNUSED_PAD src0_sel:WORD_1 src1_sel:DWORD
	ds_write_b64 v132, v[64:65]
	v_and_b32_e32 v64, 0xffff0000, v68
	v_sub_u32_e32 v2, v2, v64
	v_sub_u32_e32 v6, v6, v67
	v_and_b32_e32 v64, 0xffff0000, v66
	v_add_u32_e32 v6, 0x80, v6
	v_sub_u32_e32 v7, v7, v64
	v_sub_u32_e32 v3, v3, v69
	v_add_u32_e32 v2, 0x80, v2
	v_ashrrev_i32_e32 v6, 8, v6
	v_add_u32_e32 v7, 0x80, v7
	v_add_u32_e32 v3, 0x80, v3
	v_ashrrev_i32_e32 v2, 8, v2
	v_min_i32_e32 v6, 0x7f, v6
	v_ashrrev_i32_e32 v7, 8, v7
	v_ashrrev_i32_e32 v3, 8, v3
	v_min_i32_e32 v2, 0x7f, v2
	v_min_i32_sdwa v7, v7, s83 dst_sel:WORD_1 dst_unused:UNUSED_PAD src0_sel:DWORD src1_sel:DWORD
	v_min_i32_e32 v3, 0x7f, v3
	v_lshlrev_b32_e32 v6, 8, v6
	v_and_b32_e32 v6, 0xff00, v6
	v_and_b32_e32 v7, 0xff0000, v7
	v_perm_b32 v2, v3, v2, s84
	v_or3_b32 v2, v2, v6, v7
	ds_write_b32 v14, v2
	buffer_store_dwordx4 v[136:139], v74, s[16:19], s33 offen
	ds_read_b64 v[2:3], v15 offset:1024
	s_waitcnt lgkmcnt(0)
;     ...
;           _Pragma("unroll") for (int bj = 0; bj < 2; ++bj) _Pragma("unroll") for (int n = 0; n < 2; ++n) {
;             const int cc = bj * HALF + wc3 * 32 + n * 16 + fq3 * 4;
;             const float4 gm = *reinterpret_cast<const float4*>(g.gam + pn * BM + cc), bt = *reinterpret_cast<const float4*>(g.bet + pn * BM + cc);
;             _Pragma("unroll") for (int m = 0; m < 4; ++m) {
;               const int rr = wr3 * 64 + m * 16 + fr3;
;               const float2 ms = *reinterpret_cast<const float2*>(mr + (ai * HALF + rr) * 2);
;               f32x4 y = acc[ai][bj][m][n];
;               const float o0 = (y[0] - ms.x) * ms.y * gm.x + bt.x, o1 = (y[1] - ms.x) * ms.y * gm.y + bt.y;
;               const float o2 = (y[2] - ms.x) * ms.y * gm.z + bt.z, o3 = (y[3] - ms.x) * ms.y * gm.w + bt.w;
;               const unsigned h0 = f2bf(o0), h1 = f2bf(o1), h2 = f2bf(o2), h3 = f2bf(o3);
;               u32x2 ob; ob[0] = h0 | (h1 << 16); ob[1] = h2 | (h3 << 16);
;               *reinterpret_cast<u32x2*>(smem + (rr >> 1) * PIECE + (rr & 1) * 512 + cc * 2) = ob;
;               const int l0 = min(((int)__float_as_uint(o0) - (int)(h0 << 16) + 128) >> 8, 127);
;               const int l1 = min(((int)__float_as_uint(o1) - (int)(h1 << 16) + 128) >> 8, 127);
;               const int l2 = min(((int)__float_as_uint(o2) - (int)(h2 << 16) + 128) >> 8, 127);
;               const int l3 = min(((int)__float_as_uint(o3) - (int)(h3 << 16) + 128) >> 8, 127);
;               *reinterpret_cast<unsigned*>(smem + LOBASE + (rr >> 2) * PIECE + (rr & 3) * 256 + cc) =
;                   (unsigned)(l0 & 255) | ((unsigned)(l1 & 255) << 8) | ((unsigned)(l2 & 255) << 16) | ((unsigned)l3 << 24);
;             }
;     ...
;             __builtin_amdgcn_raw_buffer_store_b128(v, rsXB, hvo + i * (2 * DM * 2), hso, 0);
	v_mov_b32_e32 v214, v2
	v_mov_b32_e32 v215, v3
	v_pk_add_f32 v[6:7], v[78:79], v[2:3] op_sel_hi:[1,0] neg_lo:[0,1] neg_hi:[0,1]
	s_nop 0
	v_pk_mul_f32 v[6:7], v[2:3], v[6:7] op_sel:[1,0]
	v_pk_add_f32 v[64:65], v[76:77], v[2:3] op_sel_hi:[1,0] neg_lo:[0,1] neg_hi:[0,1]
	v_pk_fma_f32 v[6:7], v[96:97], v[6:7], v[98:99]
	v_pk_mul_f32 v[2:3], v[2:3], v[64:65] op_sel:[1,0]
	v_and_b32_sdwa v64, v7, v216 dst_sel:DWORD dst_unused:UNUSED_PAD src0_sel:WORD_1 src1_sel:DWORD
	v_and_b32_sdwa v65, v6, v216 dst_sel:DWORD dst_unused:UNUSED_PAD src0_sel:WORD_1 src1_sel:DWORD
	v_pk_fma_f32 v[2:3], v[0:1], v[2:3], v[4:5]
	v_add3_u32 v66, v7, v64, s82
	v_add3_u32 v64, v6, v65, s82
	v_and_b32_e32 v67, 0xffff0000, v64
	v_and_b32_sdwa v64, v3, v216 dst_sel:DWORD dst_unused:UNUSED_PAD src0_sel:WORD_1 src1_sel:DWORD
	v_and_b32_sdwa v65, v2, v216 dst_sel:DWORD dst_unused:UNUSED_PAD src0_sel:WORD_1 src1_sel:DWORD
	v_add3_u32 v64, v3, v64, s82
	v_add3_u32 v68, v2, v65, s82
	v_and_b32_e32 v69, 0xffff0000, v64
	v_or_b32_sdwa v65, v69, v66 dst_sel:DWORD dst_unused:UNUSED_PAD src0_sel:DWORD src1_sel:WORD_1
	v_or_b32_sdwa v64, v68, v67 dst_sel:DWORD dst_unused:UNUSED_PAD src0_sel:WORD_1 src1_sel:DWORD
	ds_write_b64 v133, v[64:65]
	v_and_b32_e32 v64, 0xffff0000, v68
	v_sub_u32_e32 v2, v2, v64
	v_sub_u32_e32 v6, v6, v67
	v_and_b32_e32 v64, 0xffff0000, v66
	v_add_u32_e32 v6, 0x80, v6
	v_sub_u32_e32 v7, v7, v64
	v_sub_u32_e32 v3, v3, v69
	v_add_u32_e32 v2, 0x80, v2
	v_ashrrev_i32_e32 v6, 8, v6
	v_add_u32_e32 v7, 0x80, v7
	v_add_u32_e32 v3, 0x80, v3
	v_ashrrev_i32_e32 v2, 8, v2
	v_min_i32_e32 v6, 0x7f, v6
	v_ashrrev_i32_e32 v7, 8, v7
	v_ashrrev_i32_e32 v3, 8, v3
	v_min_i32_e32 v2, 0x7f, v2
	v_min_i32_sdwa v7, v7, s83 dst_sel:WORD_1 dst_unused:UNUSED_PAD src0_sel:DWORD src1_sel:DWORD
	v_min_i32_e32 v3, 0x7f, v3
	v_lshlrev_b32_e32 v6, 8, v6
	v_and_b32_e32 v6, 0xff00, v6
	v_and_b32_e32 v7, 0xff0000, v7
	v_perm_b32 v2, v3, v2, s84
	v_or3_b32 v2, v2, v6, v7
	ds_write_b32 v20, v2
	buffer_store_dwordx4 v[140:143], v75, s[16:19], s33 offen
	ds_read_b64 v[2:3], v21 offset:1024
	s_waitcnt lgkmcnt(0)
	v_mov_b32_e32 v252, v2
	v_mov_b32_e32 v253, v3
	v_pk_add_f32 v[6:7], v[86:87], v[2:3] op_sel_hi:[1,0] neg_lo:[0,1] neg_hi:[0,1]
	s_nop 0
	v_pk_mul_f32 v[6:7], v[2:3], v[6:7] op_sel:[1,0]
	v_pk_add_f32 v[64:65], v[84:85], v[2:3] op_sel_hi:[1,0] neg_lo:[0,1] neg_hi:[0,1]
	v_pk_fma_f32 v[6:7], v[96:97], v[6:7], v[98:99]
	v_pk_mul_f32 v[2:3], v[2:3], v[64:65] op_sel:[1,0]
	s_nop 0
	v_pk_fma_f32 v[0:1], v[0:1], v[2:3], v[4:5]
	v_and_b32_sdwa v2, v7, v216 dst_sel:DWORD dst_unused:UNUSED_PAD src0_sel:WORD_1 src1_sel:DWORD
	v_and_b32_sdwa v3, v6, v216 dst_sel:DWORD dst_unused:UNUSED_PAD src0_sel:WORD_1 src1_sel:DWORD
	v_add3_u32 v4, v7, v2, s82
	v_add3_u32 v2, v6, v3, s82
	v_and_b32_e32 v5, 0xffff0000, v2
	v_and_b32_sdwa v2, v1, v216 dst_sel:DWORD dst_unused:UNUSED_PAD src0_sel:WORD_1 src1_sel:DWORD
	v_and_b32_sdwa v3, v0, v216 dst_sel:DWORD dst_unused:UNUSED_PAD src0_sel:WORD_1 src1_sel:DWORD
	v_add3_u32 v2, v1, v2, s82
	v_add3_u32 v64, v0, v3, s82
	v_and_b32_e32 v65, 0xffff0000, v2
	v_or_b32_sdwa v3, v65, v4 dst_sel:DWORD dst_unused:UNUSED_PAD src0_sel:DWORD src1_sel:WORD_1
	v_or_b32_sdwa v2, v64, v5 dst_sel:DWORD dst_unused:UNUSED_PAD src0_sel:WORD_1 src1_sel:DWORD
	ds_write_b64 v134, v[2:3]
	v_and_b32_e32 v2, 0xffff0000, v64
	v_sub_u32_e32 v0, v0, v2
	v_sub_u32_e32 v2, v6, v5
	v_and_b32_e32 v3, 0xffff0000, v4
	v_add_u32_e32 v2, 0x80, v2
	v_sub_u32_e32 v3, v7, v3
	v_sub_u32_e32 v1, v1, v65
	v_add_u32_e32 v0, 0x80, v0
	v_ashrrev_i32_e32 v2, 8, v2
	v_add_u32_e32 v3, 0x80, v3
	v_add_u32_e32 v1, 0x80, v1
	v_ashrrev_i32_e32 v0, 8, v0
	v_min_i32_e32 v2, 0x7f, v2
	v_ashrrev_i32_e32 v3, 8, v3
	v_ashrrev_i32_e32 v1, 8, v1
	v_min_i32_e32 v0, 0x7f, v0
	v_min_i32_sdwa v3, v3, s83 dst_sel:WORD_1 dst_unused:UNUSED_PAD src0_sel:DWORD src1_sel:DWORD
	v_min_i32_e32 v1, 0x7f, v1
	v_lshlrev_b32_e32 v2, 8, v2
	v_and_b32_e32 v2, 0xff00, v2
	v_and_b32_e32 v3, 0xff0000, v3
	v_perm_b32 v0, v1, v0, s84
	v_or3_b32 v0, v0, v2, v3
	ds_write_b32 v22, v0
	buffer_store_dwordx4 v[152:155], v81, s[16:19], s33 offen
	v_mov_b32_e32 v0, v224
	v_mov_b32_e32 v1, v225
	v_mov_b32_e32 v2, v226
	v_mov_b32_e32 v3, v227
	v_mov_b32_e32 v4, v240
	v_mov_b32_e32 v5, v241
	v_mov_b32_e32 v6, v242
	v_mov_b32_e32 v7, v243
	v_mov_b32_e32 v68, v210
	v_mov_b32_e32 v69, v211
	v_pk_add_f32 v[58:59], v[58:59], v[68:69] op_sel_hi:[1,0] neg_lo:[0,1] neg_hi:[0,1]
	s_nop 0
	v_pk_mul_f32 v[58:59], v[68:69], v[58:59] op_sel:[1,0]
	v_pk_add_f32 v[56:57], v[56:57], v[68:69] op_sel_hi:[1,0] neg_lo:[0,1] neg_hi:[0,1]
	v_mov_b32_e32 v64, v1
	v_mov_b32_e32 v65, v2
	v_mov_b32_e32 v66, v5
	v_mov_b32_e32 v67, v6
	v_pk_fma_f32 v[58:59], v[64:65], v[58:59], v[66:67]
	v_pk_mul_f32 v[56:57], v[68:69], v[56:57] op_sel:[1,0]
	v_mov_b32_e32 v1, v3
	v_mov_b32_e32 v5, v7
	v_and_b32_sdwa v6, v59, v216 dst_sel:DWORD dst_unused:UNUSED_PAD src0_sel:WORD_1 src1_sel:DWORD
	v_and_b32_sdwa v7, v58, v216 dst_sel:DWORD dst_unused:UNUSED_PAD src0_sel:WORD_1 src1_sel:DWORD
	v_pk_fma_f32 v[2:3], v[0:1], v[56:57], v[4:5]
	v_add3_u32 v56, v59, v6, s82
	v_add3_u32 v6, v58, v7, s82
	v_and_b32_e32 v57, 0xffff0000, v6
	v_and_b32_sdwa v6, v3, v216 dst_sel:DWORD dst_unused:UNUSED_PAD src0_sel:WORD_1 src1_sel:DWORD
	v_and_b32_sdwa v7, v2, v216 dst_sel:DWORD dst_unused:UNUSED_PAD src0_sel:WORD_1 src1_sel:DWORD
	v_add3_u32 v6, v3, v6, s82
	v_add3_u32 v68, v2, v7, s82
	v_and_b32_e32 v69, 0xffff0000, v6
	v_or_b32_sdwa v7, v69, v56 dst_sel:DWORD dst_unused:UNUSED_PAD src0_sel:DWORD src1_sel:WORD_1
	v_or_b32_sdwa v6, v68, v57 dst_sel:DWORD dst_unused:UNUSED_PAD src0_sel:WORD_1 src1_sel:DWORD
;     ...
;           _Pragma("unroll") for (int bj = 0; bj < 2; ++bj) _Pragma("unroll") for (int n = 0; n < 2; ++n) {
;             const int cc = bj * HALF + wc3 * 32 + n * 16 + fq3 * 4;
;             const float4 gm = *reinterpret_cast<const float4*>(g.gam + pn * BM + cc), bt = *reinterpret_cast<const float4*>(g.bet + pn * BM + cc);
;             _Pragma("unroll") for (int m = 0; m < 4; ++m) {
;               const int rr = wr3 * 64 + m * 16 + fr3;
;               const float2 ms = *reinterpret_cast<const float2*>(mr + (ai * HALF + rr) * 2);
;               f32x4 y = acc[ai][bj][m][n];
;               const float o0 = (y[0] - ms.x) * ms.y * gm.x + bt.x, o1 = (y[1] - ms.x) * ms.y * gm.y + bt.y;
;               const float o2 = (y[2] - ms.x) * ms.y * gm.z + bt.z, o3 = (y[3] - ms.x) * ms.y * gm.w + bt.w;
;               const unsigned h0 = f2bf(o0), h1 = f2bf(o1), h2 = f2bf(o2), h3 = f2bf(o3);
;               u32x2 ob; ob[0] = h0 | (h1 << 16); ob[1] = h2 | (h3 << 16);
;               *reinterpret_cast<u32x2*>(smem + (rr >> 1) * PIECE + (rr & 1) * 512 + cc * 2) = ob;
;               const int l0 = min(((int)__float_as_uint(o0) - (int)(h0 << 16) + 128) >> 8, 127);
;               const int l1 = min(((int)__float_as_uint(o1) - (int)(h1 << 16) + 128) >> 8, 127);
;               const int l2 = min(((int)__float_as_uint(o2) - (int)(h2 << 16) + 128) >> 8, 127);
;               const int l3 = min(((int)__float_as_uint(o3) - (int)(h3 << 16) + 128) >> 8, 127);
;               *reinterpret_cast<unsigned*>(smem + LOBASE + (rr >> 2) * PIECE + (rr & 3) * 256 + cc) =
;                   (unsigned)(l0 & 255) | ((unsigned)(l1 & 255) << 8) | ((unsigned)(l2 & 255) << 16) | ((unsigned)l3 << 24);
;             }
;     ...
;             __builtin_amdgcn_raw_buffer_store_b128(v, rsXB, hvo + i * (2 * DM * 2), hso, 0);
	ds_write_b64 v23, v[6:7]
	v_and_b32_e32 v6, 0xffff0000, v68
	v_sub_u32_e32 v2, v2, v6
	v_sub_u32_e32 v6, v58, v57
	v_and_b32_e32 v7, 0xffff0000, v56
	v_add_u32_e32 v6, 0x80, v6
	v_sub_u32_e32 v7, v59, v7
	v_sub_u32_e32 v3, v3, v69
	v_add_u32_e32 v2, 0x80, v2
	v_ashrrev_i32_e32 v6, 8, v6
	v_add_u32_e32 v7, 0x80, v7
	v_add_u32_e32 v3, 0x80, v3
	v_ashrrev_i32_e32 v2, 8, v2
	v_min_i32_e32 v6, 0x7f, v6
	v_ashrrev_i32_e32 v7, 8, v7
	v_ashrrev_i32_e32 v3, 8, v3
	v_min_i32_e32 v2, 0x7f, v2
	v_min_i32_sdwa v7, v7, s83 dst_sel:WORD_1 dst_unused:UNUSED_PAD src0_sel:DWORD src1_sel:DWORD
	v_min_i32_e32 v3, 0x7f, v3
	v_lshlrev_b32_e32 v6, 8, v6
	v_and_b32_e32 v6, 0xff00, v6
	v_and_b32_e32 v7, 0xff0000, v7
	v_perm_b32 v2, v3, v2, s84
	v_or3_b32 v2, v2, v6, v7
	ds_write_b32 v12, v2 offset:16
	buffer_store_dwordx4 v[156:159], v82, s[16:19], s33 offen
	v_mov_b32_e32 v2, v212
	v_mov_b32_e32 v3, v213
	v_pk_add_f32 v[6:7], v[42:43], v[2:3] op_sel_hi:[1,0] neg_lo:[0,1] neg_hi:[0,1]
	s_nop 0
	v_pk_mul_f32 v[6:7], v[2:3], v[6:7] op_sel:[1,0]
	v_pk_add_f32 v[40:41], v[40:41], v[2:3] op_sel_hi:[1,0] neg_lo:[0,1] neg_hi:[0,1]
	v_pk_fma_f32 v[6:7], v[64:65], v[6:7], v[66:67]
	v_pk_mul_f32 v[2:3], v[2:3], v[40:41] op_sel:[1,0]
	v_and_b32_sdwa v40, v6, v216 dst_sel:DWORD dst_unused:UNUSED_PAD src0_sel:WORD_1 src1_sel:DWORD
	v_pk_fma_f32 v[2:3], v[0:1], v[2:3], v[4:5]
	v_add3_u32 v40, v6, v40, s82
	v_and_b32_e32 v42, 0xffff0000, v40
	v_and_b32_sdwa v40, v3, v216 dst_sel:DWORD dst_unused:UNUSED_PAD src0_sel:WORD_1 src1_sel:DWORD
	v_and_b32_sdwa v23, v7, v216 dst_sel:DWORD dst_unused:UNUSED_PAD src0_sel:WORD_1 src1_sel:DWORD
	v_and_b32_sdwa v41, v2, v216 dst_sel:DWORD dst_unused:UNUSED_PAD src0_sel:WORD_1 src1_sel:DWORD
	v_add3_u32 v40, v3, v40, s82
	v_add3_u32 v23, v7, v23, s82
	v_add3_u32 v43, v2, v41, s82
	v_and_b32_e32 v56, 0xffff0000, v40
	v_or_b32_sdwa v41, v56, v23 dst_sel:DWORD dst_unused:UNUSED_PAD src0_sel:DWORD src1_sel:WORD_1
	v_or_b32_sdwa v40, v43, v42 dst_sel:DWORD dst_unused:UNUSED_PAD src0_sel:WORD_1 src1_sel:DWORD
	ds_write_b64 v104, v[40:41]
	v_and_b32_e32 v40, 0xffff0000, v43
	v_sub_u32_e32 v6, v6, v42
	v_and_b32_e32 v23, 0xffff0000, v23
	v_sub_u32_e32 v2, v2, v40
	v_add_u32_e32 v6, 0x80, v6
	v_sub_u32_e32 v7, v7, v23
	v_sub_u32_e32 v3, v3, v56
	v_add_u32_e32 v2, 0x80, v2
	v_ashrrev_i32_e32 v6, 8, v6
	v_add_u32_e32 v7, 0x80, v7
	v_add_u32_e32 v3, 0x80, v3
	v_ashrrev_i32_e32 v2, 8, v2
	v_min_i32_e32 v6, 0x7f, v6
	v_ashrrev_i32_e32 v7, 8, v7
	v_ashrrev_i32_e32 v3, 8, v3
	v_min_i32_e32 v2, 0x7f, v2
	v_min_i32_sdwa v7, v7, s83 dst_sel:WORD_1 dst_unused:UNUSED_PAD src0_sel:DWORD src1_sel:DWORD
	v_min_i32_e32 v3, 0x7f, v3
	v_lshlrev_b32_e32 v6, 8, v6
	v_and_b32_e32 v6, 0xff00, v6
	v_and_b32_e32 v7, 0xff0000, v7
	v_perm_b32 v2, v3, v2, s84
	v_or3_b32 v2, v2, v6, v7
	ds_write_b32 v14, v2 offset:16
	buffer_store_dwordx4 v[160:163], v83, s[16:19], s33 offen
	v_mov_b32_e32 v2, v214
	v_mov_b32_e32 v3, v215
	v_pk_add_f32 v[6:7], v[46:47], v[2:3] op_sel_hi:[1,0] neg_lo:[0,1] neg_hi:[0,1]
	s_nop 0
	v_pk_mul_f32 v[6:7], v[2:3], v[6:7] op_sel:[1,0]
	v_pk_add_f32 v[40:41], v[44:45], v[2:3] op_sel_hi:[1,0] neg_lo:[0,1] neg_hi:[0,1]
	v_pk_fma_f32 v[6:7], v[64:65], v[6:7], v[66:67]
	v_pk_mul_f32 v[2:3], v[2:3], v[40:41] op_sel:[1,0]
	v_and_b32_sdwa v40, v6, v216 dst_sel:DWORD dst_unused:UNUSED_PAD src0_sel:WORD_1 src1_sel:DWORD
	v_pk_fma_f32 v[2:3], v[0:1], v[2:3], v[4:5]
	v_add3_u32 v40, v6, v40, s82
	v_and_b32_e32 v42, 0xffff0000, v40
	v_and_b32_sdwa v40, v3, v216 dst_sel:DWORD dst_unused:UNUSED_PAD src0_sel:WORD_1 src1_sel:DWORD
	v_and_b32_sdwa v23, v7, v216 dst_sel:DWORD dst_unused:UNUSED_PAD src0_sel:WORD_1 src1_sel:DWORD
	v_and_b32_sdwa v41, v2, v216 dst_sel:DWORD dst_unused:UNUSED_PAD src0_sel:WORD_1 src1_sel:DWORD
	v_add3_u32 v40, v3, v40, s82
	v_add3_u32 v23, v7, v23, s82
	v_add3_u32 v43, v2, v41, s82
	v_and_b32_e32 v44, 0xffff0000, v40
	v_or_b32_sdwa v41, v44, v23 dst_sel:DWORD dst_unused:UNUSED_PAD src0_sel:DWORD src1_sel:WORD_1
	v_or_b32_sdwa v40, v43, v42 dst_sel:DWORD dst_unused:UNUSED_PAD src0_sel:WORD_1 src1_sel:DWORD
	ds_write_b64 v105, v[40:41]
	v_and_b32_e32 v40, 0xffff0000, v43
	v_sub_u32_e32 v6, v6, v42
	v_and_b32_e32 v23, 0xffff0000, v23
	v_sub_u32_e32 v2, v2, v40
	v_add_u32_e32 v6, 0x80, v6
	v_sub_u32_e32 v7, v7, v23
	v_sub_u32_e32 v3, v3, v44
	v_add_u32_e32 v2, 0x80, v2
	v_ashrrev_i32_e32 v6, 8, v6
	v_add_u32_e32 v7, 0x80, v7
	v_add_u32_e32 v3, 0x80, v3
	v_ashrrev_i32_e32 v2, 8, v2
	v_min_i32_e32 v6, 0x7f, v6
	v_ashrrev_i32_e32 v7, 8, v7
	v_ashrrev_i32_e32 v3, 8, v3
	v_min_i32_e32 v2, 0x7f, v2
	v_min_i32_sdwa v7, v7, s83 dst_sel:WORD_1 dst_unused:UNUSED_PAD src0_sel:DWORD src1_sel:DWORD
	v_min_i32_e32 v3, 0x7f, v3
	v_lshlrev_b32_e32 v6, 8, v6
	v_and_b32_e32 v6, 0xff00, v6
	v_and_b32_e32 v7, 0xff0000, v7
	v_perm_b32 v2, v3, v2, s84
	v_or3_b32 v2, v2, v6, v7
	ds_write_b32 v20, v2 offset:16
	buffer_store_dwordx4 v[164:167], v88, s[16:19], s33 offen
	v_mov_b32_e32 v2, v252
	v_mov_b32_e32 v3, v253
	v_pk_add_f32 v[6:7], v[62:63], v[2:3] op_sel_hi:[1,0] neg_lo:[0,1] neg_hi:[0,1]
	s_nop 0
	v_pk_mul_f32 v[6:7], v[2:3], v[6:7] op_sel:[1,0]
	v_pk_add_f32 v[40:41], v[60:61], v[2:3] op_sel_hi:[1,0] neg_lo:[0,1] neg_hi:[0,1]
	v_pk_fma_f32 v[6:7], v[64:65], v[6:7], v[66:67]
	v_pk_mul_f32 v[2:3], v[2:3], v[40:41] op_sel:[1,0]
	s_nop 0
	v_pk_fma_f32 v[0:1], v[0:1], v[2:3], v[4:5]
	v_and_b32_sdwa v2, v7, v216 dst_sel:DWORD dst_unused:UNUSED_PAD src0_sel:WORD_1 src1_sel:DWORD
	v_and_b32_sdwa v3, v6, v216 dst_sel:DWORD dst_unused:UNUSED_PAD src0_sel:WORD_1 src1_sel:DWORD
	v_add3_u32 v4, v7, v2, s82
	v_add3_u32 v2, v6, v3, s82
	v_and_b32_e32 v5, 0xffff0000, v2
;     ...
;           _Pragma("unroll") for (int bj = 0; bj < 2; ++bj) _Pragma("unroll") for (int n = 0; n < 2; ++n) {
;             const int cc = bj * HALF + wc3 * 32 + n * 16 + fq3 * 4;
;             const float4 gm = *reinterpret_cast<const float4*>(g.gam + pn * BM + cc), bt = *reinterpret_cast<const float4*>(g.bet + pn * BM + cc);
;             _Pragma("unroll") for (int m = 0; m < 4; ++m) {
;               const int rr = wr3 * 64 + m * 16 + fr3;
;               const float2 ms = *reinterpret_cast<const float2*>(mr + (ai * HALF + rr) * 2);
;               f32x4 y = acc[ai][bj][m][n];
;               const float o0 = (y[0] - ms.x) * ms.y * gm.x + bt.x, o1 = (y[1] - ms.x) * ms.y * gm.y + bt.y;
;               const float o2 = (y[2] - ms.x) * ms.y * gm.z + bt.z, o3 = (y[3] - ms.x) * ms.y * gm.w + bt.w;
;               const unsigned h0 = f2bf(o0), h1 = f2bf(o1), h2 = f2bf(o2), h3 = f2bf(o3);
;               u32x2 ob; ob[0] = h0 | (h1 << 16); ob[1] = h2 | (h3 << 16);
;               *reinterpret_cast<u32x2*>(smem + (rr >> 1) * PIECE + (rr & 1) * 512 + cc * 2) = ob;
;               const int l0 = min(((int)__float_as_uint(o0) - (int)(h0 << 16) + 128) >> 8, 127);
;               const int l1 = min(((int)__float_as_uint(o1) - (int)(h1 << 16) + 128) >> 8, 127);
;               const int l2 = min(((int)__float_as_uint(o2) - (int)(h2 << 16) + 128) >> 8, 127);
;               const int l3 = min(((int)__float_as_uint(o3) - (int)(h3 << 16) + 128) >> 8, 127);
;               *reinterpret_cast<unsigned*>(smem + LOBASE + (rr >> 2) * PIECE + (rr & 3) * 256 + cc) =
;                   (unsigned)(l0 & 255) | ((unsigned)(l1 & 255) << 8) | ((unsigned)(l2 & 255) << 16) | ((unsigned)l3 << 24);
;             }
;     ...
;             __builtin_amdgcn_raw_buffer_store_b128(v, rsLO, lvo + i * (4 * DM), lso, 0);
	v_and_b32_sdwa v2, v1, v216 dst_sel:DWORD dst_unused:UNUSED_PAD src0_sel:WORD_1 src1_sel:DWORD
	v_and_b32_sdwa v3, v0, v216 dst_sel:DWORD dst_unused:UNUSED_PAD src0_sel:WORD_1 src1_sel:DWORD
	v_add3_u32 v2, v1, v2, s82
	v_add3_u32 v23, v0, v3, s82
	v_and_b32_e32 v40, 0xffff0000, v2
	v_or_b32_sdwa v3, v40, v4 dst_sel:DWORD dst_unused:UNUSED_PAD src0_sel:DWORD src1_sel:WORD_1
	v_or_b32_sdwa v2, v23, v5 dst_sel:DWORD dst_unused:UNUSED_PAD src0_sel:WORD_1 src1_sel:DWORD
	ds_write_b64 v106, v[2:3]
	v_and_b32_e32 v2, 0xffff0000, v23
	v_sub_u32_e32 v0, v0, v2
	v_sub_u32_e32 v2, v6, v5
	v_and_b32_e32 v3, 0xffff0000, v4
	v_add_u32_e32 v2, 0x80, v2
	v_sub_u32_e32 v3, v7, v3
	v_sub_u32_e32 v1, v1, v40
	v_add_u32_e32 v0, 0x80, v0
	v_ashrrev_i32_e32 v2, 8, v2
	v_add_u32_e32 v3, 0x80, v3
	v_add_u32_e32 v1, 0x80, v1
	v_ashrrev_i32_e32 v0, 8, v0
	v_min_i32_e32 v2, 0x7f, v2
	v_ashrrev_i32_e32 v3, 8, v3
	v_ashrrev_i32_e32 v1, 8, v1
	v_min_i32_e32 v0, 0x7f, v0
	v_min_i32_sdwa v3, v3, s83 dst_sel:WORD_1 dst_unused:UNUSED_PAD src0_sel:DWORD src1_sel:DWORD
	v_min_i32_e32 v1, 0x7f, v1
	v_lshlrev_b32_e32 v2, 8, v2
	v_and_b32_e32 v2, 0xff00, v2
	v_and_b32_e32 v3, 0xff0000, v3
	v_perm_b32 v0, v1, v0, s84
	v_or3_b32 v0, v0, v2, v3
	ds_write_b32 v22, v0 offset:16
	buffer_store_dwordx4 v[168:171], v89, s[16:19], s33 offen
	v_mov_b32_e32 v0, v228
	v_mov_b32_e32 v1, v229
	v_mov_b32_e32 v2, v230
	v_mov_b32_e32 v3, v231
	v_mov_b32_e32 v4, v244
	v_mov_b32_e32 v5, v245
	v_mov_b32_e32 v6, v246
	v_mov_b32_e32 v7, v247
	v_mov_b32_e32 v44, v210
	v_mov_b32_e32 v45, v211
	v_pk_add_f32 v[46:47], v[54:55], v[44:45] op_sel_hi:[1,0] neg_lo:[0,1] neg_hi:[0,1]
	s_nop 0
	v_pk_mul_f32 v[46:47], v[44:45], v[46:47] op_sel:[1,0]
	v_pk_add_f32 v[52:53], v[52:53], v[44:45] op_sel_hi:[1,0] neg_lo:[0,1] neg_hi:[0,1]
	v_mov_b32_e32 v40, v1
	v_mov_b32_e32 v41, v2
	v_mov_b32_e32 v42, v5
	v_mov_b32_e32 v43, v6
	v_pk_fma_f32 v[46:47], v[40:41], v[46:47], v[42:43]
	v_pk_mul_f32 v[44:45], v[44:45], v[52:53] op_sel:[1,0]
	v_mov_b32_e32 v1, v3
	v_mov_b32_e32 v5, v7
	v_and_b32_sdwa v6, v47, v216 dst_sel:DWORD dst_unused:UNUSED_PAD src0_sel:WORD_1 src1_sel:DWORD
	v_and_b32_sdwa v7, v46, v216 dst_sel:DWORD dst_unused:UNUSED_PAD src0_sel:WORD_1 src1_sel:DWORD
	v_pk_fma_f32 v[2:3], v[0:1], v[44:45], v[4:5]
	v_add3_u32 v23, v47, v6, s82
	v_add3_u32 v6, v46, v7, s82
	v_and_b32_e32 v44, 0xffff0000, v6
	v_and_b32_sdwa v6, v3, v216 dst_sel:DWORD dst_unused:UNUSED_PAD src0_sel:WORD_1 src1_sel:DWORD
	v_and_b32_sdwa v7, v2, v216 dst_sel:DWORD dst_unused:UNUSED_PAD src0_sel:WORD_1 src1_sel:DWORD
	v_add3_u32 v6, v3, v6, s82
	v_add3_u32 v45, v2, v7, s82
	v_and_b32_e32 v52, 0xffff0000, v6
	v_or_b32_sdwa v7, v52, v23 dst_sel:DWORD dst_unused:UNUSED_PAD src0_sel:DWORD src1_sel:WORD_1
	v_or_b32_sdwa v6, v45, v44 dst_sel:DWORD dst_unused:UNUSED_PAD src0_sel:WORD_1 src1_sel:DWORD
	ds_write_b64 v107, v[6:7]
	v_and_b32_e32 v6, 0xffff0000, v45
	v_sub_u32_e32 v2, v2, v6
	v_sub_u32_e32 v6, v46, v44
	v_and_b32_e32 v7, 0xffff0000, v23
	v_add_u32_e32 v6, 0x80, v6
	v_sub_u32_e32 v7, v47, v7
	v_sub_u32_e32 v3, v3, v52
	v_add_u32_e32 v2, 0x80, v2
	v_ashrrev_i32_e32 v6, 8, v6
	v_add_u32_e32 v7, 0x80, v7
	v_add_u32_e32 v3, 0x80, v3
	v_ashrrev_i32_e32 v2, 8, v2
	v_min_i32_e32 v6, 0x7f, v6
	v_ashrrev_i32_e32 v7, 8, v7
	v_ashrrev_i32_e32 v3, 8, v3
	v_min_i32_e32 v2, 0x7f, v2
	v_min_i32_sdwa v7, v7, s83 dst_sel:WORD_1 dst_unused:UNUSED_PAD src0_sel:DWORD src1_sel:DWORD
	v_min_i32_e32 v3, 0x7f, v3
	v_lshlrev_b32_e32 v6, 8, v6
	v_and_b32_e32 v6, 0xff00, v6
	v_and_b32_e32 v7, 0xff0000, v7
	v_perm_b32 v2, v3, v2, s84
	v_or3_b32 v2, v2, v6, v7
	ds_write_b32 v12, v2 offset:128
	buffer_store_dwordx4 v[172:175], v146, s[20:23], s0 offen
	v_mov_b32_e32 v2, v212
	v_mov_b32_e32 v3, v213
	v_pk_add_f32 v[6:7], v[38:39], v[2:3] op_sel_hi:[1,0] neg_lo:[0,1] neg_hi:[0,1]
	s_nop 0
	v_pk_mul_f32 v[6:7], v[2:3], v[6:7] op_sel:[1,0]
	v_pk_add_f32 v[36:37], v[36:37], v[2:3] op_sel_hi:[1,0] neg_lo:[0,1] neg_hi:[0,1]
	v_pk_fma_f32 v[6:7], v[40:41], v[6:7], v[42:43]
	v_pk_mul_f32 v[2:3], v[2:3], v[36:37] op_sel:[1,0]
	v_and_b32_sdwa v36, v6, v216 dst_sel:DWORD dst_unused:UNUSED_PAD src0_sel:WORD_1 src1_sel:DWORD
	v_pk_fma_f32 v[2:3], v[0:1], v[2:3], v[4:5]
	v_add3_u32 v36, v6, v36, s82
	v_and_b32_e32 v38, 0xffff0000, v36
	v_and_b32_sdwa v36, v3, v216 dst_sel:DWORD dst_unused:UNUSED_PAD src0_sel:WORD_1 src1_sel:DWORD
	v_and_b32_sdwa v23, v7, v216 dst_sel:DWORD dst_unused:UNUSED_PAD src0_sel:WORD_1 src1_sel:DWORD
	v_and_b32_sdwa v37, v2, v216 dst_sel:DWORD dst_unused:UNUSED_PAD src0_sel:WORD_1 src1_sel:DWORD
	v_add3_u32 v36, v3, v36, s82
	v_add3_u32 v23, v7, v23, s82
	v_add3_u32 v39, v2, v37, s82
	v_and_b32_e32 v44, 0xffff0000, v36
	v_or_b32_sdwa v37, v44, v23 dst_sel:DWORD dst_unused:UNUSED_PAD src0_sel:DWORD src1_sel:WORD_1
	v_or_b32_sdwa v36, v39, v38 dst_sel:DWORD dst_unused:UNUSED_PAD src0_sel:WORD_1 src1_sel:DWORD
	ds_write_b64 v100, v[36:37]
	v_and_b32_e32 v36, 0xffff0000, v39
	v_sub_u32_e32 v6, v6, v38
	v_and_b32_e32 v23, 0xffff0000, v23
	v_sub_u32_e32 v2, v2, v36
	v_add_u32_e32 v6, 0x80, v6
	v_sub_u32_e32 v7, v7, v23
	v_sub_u32_e32 v3, v3, v44
	v_add_u32_e32 v2, 0x80, v2
	v_ashrrev_i32_e32 v6, 8, v6
	v_add_u32_e32 v7, 0x80, v7
	v_add_u32_e32 v3, 0x80, v3
	v_ashrrev_i32_e32 v2, 8, v2
	v_min_i32_e32 v6, 0x7f, v6
	v_ashrrev_i32_e32 v7, 8, v7
	v_ashrrev_i32_e32 v3, 8, v3
	v_min_i32_e32 v2, 0x7f, v2
	v_min_i32_sdwa v7, v7, s83 dst_sel:WORD_1 dst_unused:UNUSED_PAD src0_sel:DWORD src1_sel:DWORD
	v_min_i32_e32 v3, 0x7f, v3
	v_lshlrev_b32_e32 v6, 8, v6
	v_and_b32_e32 v6, 0xff00, v6
	v_and_b32_e32 v7, 0xff0000, v7
	v_perm_b32 v2, v3, v2, s84
	v_or3_b32 v2, v2, v6, v7
;     ...
;           _Pragma("unroll") for (int bj = 0; bj < 2; ++bj) _Pragma("unroll") for (int n = 0; n < 2; ++n) {
;             const int cc = bj * HALF + wc3 * 32 + n * 16 + fq3 * 4;
;             const float4 gm = *reinterpret_cast<const float4*>(g.gam + pn * BM + cc), bt = *reinterpret_cast<const float4*>(g.bet + pn * BM + cc);
;             _Pragma("unroll") for (int m = 0; m < 4; ++m) {
;               const int rr = wr3 * 64 + m * 16 + fr3;
;               const float2 ms = *reinterpret_cast<const float2*>(mr + (ai * HALF + rr) * 2);
;               f32x4 y = acc[ai][bj][m][n];
;               const float o0 = (y[0] - ms.x) * ms.y * gm.x + bt.x, o1 = (y[1] - ms.x) * ms.y * gm.y + bt.y;
;               const float o2 = (y[2] - ms.x) * ms.y * gm.z + bt.z, o3 = (y[3] - ms.x) * ms.y * gm.w + bt.w;
;               const unsigned h0 = f2bf(o0), h1 = f2bf(o1), h2 = f2bf(o2), h3 = f2bf(o3);
;               u32x2 ob; ob[0] = h0 | (h1 << 16); ob[1] = h2 | (h3 << 16);
;               *reinterpret_cast<u32x2*>(smem + (rr >> 1) * PIECE + (rr & 1) * 512 + cc * 2) = ob;
;               const int l0 = min(((int)__float_as_uint(o0) - (int)(h0 << 16) + 128) >> 8, 127);
;               const int l1 = min(((int)__float_as_uint(o1) - (int)(h1 << 16) + 128) >> 8, 127);
;               const int l2 = min(((int)__float_as_uint(o2) - (int)(h2 << 16) + 128) >> 8, 127);
;               const int l3 = min(((int)__float_as_uint(o3) - (int)(h3 << 16) + 128) >> 8, 127);
;               *reinterpret_cast<unsigned*>(smem + LOBASE + (rr >> 2) * PIECE + (rr & 3) * 256 + cc) =
;                   (unsigned)(l0 & 255) | ((unsigned)(l1 & 255) << 8) | ((unsigned)(l2 & 255) << 16) | ((unsigned)l3 << 24);
;             }
;     ...
;             __builtin_amdgcn_raw_buffer_store_b128(v, rsLO, lvo + i * (4 * DM), lso, 0);
	ds_write_b32 v14, v2 offset:128
	buffer_store_dwordx4 v[176:179], v90, s[20:23], s0 offen
	v_mov_b32_e32 v2, v214
	v_mov_b32_e32 v3, v215
	v_pk_add_f32 v[6:7], v[26:27], v[2:3] op_sel_hi:[1,0] neg_lo:[0,1] neg_hi:[0,1]
	s_nop 0
	v_pk_mul_f32 v[6:7], v[2:3], v[6:7] op_sel:[1,0]
	v_pk_add_f32 v[24:25], v[24:25], v[2:3] op_sel_hi:[1,0] neg_lo:[0,1] neg_hi:[0,1]
	v_pk_fma_f32 v[6:7], v[40:41], v[6:7], v[42:43]
	v_pk_mul_f32 v[2:3], v[2:3], v[24:25] op_sel:[1,0]
	v_and_b32_sdwa v24, v6, v216 dst_sel:DWORD dst_unused:UNUSED_PAD src0_sel:WORD_1 src1_sel:DWORD
	v_pk_fma_f32 v[2:3], v[0:1], v[2:3], v[4:5]
	v_add3_u32 v24, v6, v24, s82
	v_and_b32_e32 v26, 0xffff0000, v24
	v_and_b32_sdwa v24, v3, v216 dst_sel:DWORD dst_unused:UNUSED_PAD src0_sel:WORD_1 src1_sel:DWORD
	v_and_b32_sdwa v23, v7, v216 dst_sel:DWORD dst_unused:UNUSED_PAD src0_sel:WORD_1 src1_sel:DWORD
	v_and_b32_sdwa v25, v2, v216 dst_sel:DWORD dst_unused:UNUSED_PAD src0_sel:WORD_1 src1_sel:DWORD
	v_add3_u32 v24, v3, v24, s82
	v_add3_u32 v23, v7, v23, s82
	v_add3_u32 v27, v2, v25, s82
	v_and_b32_e32 v36, 0xffff0000, v24
	v_or_b32_sdwa v25, v36, v23 dst_sel:DWORD dst_unused:UNUSED_PAD src0_sel:DWORD src1_sel:WORD_1
	v_or_b32_sdwa v24, v27, v26 dst_sel:DWORD dst_unused:UNUSED_PAD src0_sel:WORD_1 src1_sel:DWORD
	ds_write_b64 v101, v[24:25]
	v_and_b32_e32 v24, 0xffff0000, v27
	v_sub_u32_e32 v6, v6, v26
	v_and_b32_e32 v23, 0xffff0000, v23
	v_sub_u32_e32 v2, v2, v24
	v_add_u32_e32 v6, 0x80, v6
	v_sub_u32_e32 v7, v7, v23
	v_sub_u32_e32 v3, v3, v36
	v_add_u32_e32 v2, 0x80, v2
	v_ashrrev_i32_e32 v6, 8, v6
	v_add_u32_e32 v7, 0x80, v7
	v_add_u32_e32 v3, 0x80, v3
	v_ashrrev_i32_e32 v2, 8, v2
	v_min_i32_e32 v6, 0x7f, v6
	v_ashrrev_i32_e32 v7, 8, v7
	v_ashrrev_i32_e32 v3, 8, v3
	v_min_i32_e32 v2, 0x7f, v2
	v_min_i32_sdwa v7, v7, s83 dst_sel:WORD_1 dst_unused:UNUSED_PAD src0_sel:DWORD src1_sel:DWORD
	v_min_i32_e32 v3, 0x7f, v3
	v_lshlrev_b32_e32 v6, 8, v6
	v_and_b32_e32 v6, 0xff00, v6
	v_and_b32_e32 v7, 0xff0000, v7
	v_perm_b32 v2, v3, v2, s84
	v_or3_b32 v2, v2, v6, v7
	ds_write_b32 v20, v2 offset:128
	buffer_store_dwordx4 v[180:183], v91, s[20:23], s0 offen
	v_mov_b32_e32 v2, v252
	v_mov_b32_e32 v3, v253
	v_pk_add_f32 v[6:7], v[30:31], v[2:3] op_sel_hi:[1,0] neg_lo:[0,1] neg_hi:[0,1]
	s_nop 0
	v_pk_mul_f32 v[6:7], v[2:3], v[6:7] op_sel:[1,0]
	v_pk_add_f32 v[24:25], v[28:29], v[2:3] op_sel_hi:[1,0] neg_lo:[0,1] neg_hi:[0,1]
	v_pk_fma_f32 v[6:7], v[40:41], v[6:7], v[42:43]
	v_pk_mul_f32 v[2:3], v[2:3], v[24:25] op_sel:[1,0]
	s_nop 0
	v_pk_fma_f32 v[0:1], v[0:1], v[2:3], v[4:5]
	v_and_b32_sdwa v2, v7, v216 dst_sel:DWORD dst_unused:UNUSED_PAD src0_sel:WORD_1 src1_sel:DWORD
	v_and_b32_sdwa v3, v6, v216 dst_sel:DWORD dst_unused:UNUSED_PAD src0_sel:WORD_1 src1_sel:DWORD
	v_add3_u32 v4, v7, v2, s82
	v_add3_u32 v2, v6, v3, s82
	v_and_b32_e32 v5, 0xffff0000, v2
	v_and_b32_sdwa v2, v1, v216 dst_sel:DWORD dst_unused:UNUSED_PAD src0_sel:WORD_1 src1_sel:DWORD
	v_and_b32_sdwa v3, v0, v216 dst_sel:DWORD dst_unused:UNUSED_PAD src0_sel:WORD_1 src1_sel:DWORD
	v_add3_u32 v2, v1, v2, s82
	v_add3_u32 v23, v0, v3, s82
	v_and_b32_e32 v24, 0xffff0000, v2
	v_or_b32_sdwa v3, v24, v4 dst_sel:DWORD dst_unused:UNUSED_PAD src0_sel:DWORD src1_sel:WORD_1
	v_or_b32_sdwa v2, v23, v5 dst_sel:DWORD dst_unused:UNUSED_PAD src0_sel:WORD_1 src1_sel:DWORD
	ds_write_b64 v92, v[2:3]
	v_and_b32_e32 v2, 0xffff0000, v23
	v_sub_u32_e32 v0, v0, v2
	v_sub_u32_e32 v2, v6, v5
	v_and_b32_e32 v3, 0xffff0000, v4
	v_add_u32_e32 v2, 0x80, v2
	v_sub_u32_e32 v3, v7, v3
	v_sub_u32_e32 v1, v1, v24
	v_add_u32_e32 v0, 0x80, v0
	v_ashrrev_i32_e32 v2, 8, v2
	v_add_u32_e32 v3, 0x80, v3
	v_add_u32_e32 v1, 0x80, v1
	v_ashrrev_i32_e32 v0, 8, v0
	v_min_i32_e32 v2, 0x7f, v2
	v_ashrrev_i32_e32 v3, 8, v3
	v_ashrrev_i32_e32 v1, 8, v1
	v_min_i32_e32 v0, 0x7f, v0
	v_min_i32_sdwa v3, v3, s83 dst_sel:WORD_1 dst_unused:UNUSED_PAD src0_sel:DWORD src1_sel:DWORD
	v_min_i32_e32 v1, 0x7f, v1
	v_lshlrev_b32_e32 v2, 8, v2
	v_and_b32_e32 v2, 0xff00, v2
	v_and_b32_e32 v3, 0xff0000, v3
	v_perm_b32 v0, v1, v0, s84
	v_or3_b32 v0, v0, v2, v3
	ds_write_b32 v22, v0 offset:128
	buffer_store_dwordx4 v[184:187], v95, s[20:23], s0 offen
	v_mov_b32_e32 v0, v232
	v_mov_b32_e32 v1, v233
	v_mov_b32_e32 v2, v234
	v_mov_b32_e32 v3, v235
	v_mov_b32_e32 v4, v248
	v_mov_b32_e32 v5, v249
	v_mov_b32_e32 v6, v250
	v_mov_b32_e32 v7, v251
	v_mov_b32_e32 v28, v210
	v_mov_b32_e32 v29, v211
	s_mov_b64 s[4:5], -1
	v_pk_add_f32 v[30:31], v[50:51], v[28:29] op_sel_hi:[1,0] neg_lo:[0,1] neg_hi:[0,1]
	s_nop 0
	v_pk_mul_f32 v[30:31], v[28:29], v[30:31] op_sel:[1,0]
	v_pk_add_f32 v[36:37], v[48:49], v[28:29] op_sel_hi:[1,0] neg_lo:[0,1] neg_hi:[0,1]
	v_mov_b32_e32 v24, v1
	v_mov_b32_e32 v25, v2
	v_mov_b32_e32 v26, v5
	v_mov_b32_e32 v27, v6
	v_pk_fma_f32 v[30:31], v[24:25], v[30:31], v[26:27]
	v_pk_mul_f32 v[28:29], v[28:29], v[36:37] op_sel:[1,0]
	v_mov_b32_e32 v1, v3
	v_mov_b32_e32 v5, v7
	v_and_b32_sdwa v6, v31, v216 dst_sel:DWORD dst_unused:UNUSED_PAD src0_sel:WORD_1 src1_sel:DWORD
	v_and_b32_sdwa v7, v30, v216 dst_sel:DWORD dst_unused:UNUSED_PAD src0_sel:WORD_1 src1_sel:DWORD
	v_pk_fma_f32 v[2:3], v[0:1], v[28:29], v[4:5]
	v_add3_u32 v23, v31, v6, s82
	v_add3_u32 v6, v30, v7, s82
	v_and_b32_e32 v28, 0xffff0000, v6
	v_and_b32_sdwa v6, v3, v216 dst_sel:DWORD dst_unused:UNUSED_PAD src0_sel:WORD_1 src1_sel:DWORD
	v_and_b32_sdwa v7, v2, v216 dst_sel:DWORD dst_unused:UNUSED_PAD src0_sel:WORD_1 src1_sel:DWORD
	v_add3_u32 v6, v3, v6, s82
	v_add3_u32 v29, v2, v7, s82
	v_and_b32_e32 v36, 0xffff0000, v6
	v_or_b32_sdwa v7, v36, v23 dst_sel:DWORD dst_unused:UNUSED_PAD src0_sel:DWORD src1_sel:WORD_1
; #define WAIT_L(n) asm volatile("s_waitcnt lgkmcnt(" #n ")" ::: "memory")
; #define BAR __builtin_amdgcn_s_barrier()
;     ...
;           _Pragma("unroll") for (int bj = 0; bj < 2; ++bj) _Pragma("unroll") for (int n = 0; n < 2; ++n) {
;             const int cc = bj * HALF + wc3 * 32 + n * 16 + fq3 * 4;
;             const float4 gm = *reinterpret_cast<const float4*>(g.gam + pn * BM + cc), bt = *reinterpret_cast<const float4*>(g.bet + pn * BM + cc);
;             _Pragma("unroll") for (int m = 0; m < 4; ++m) {
;               const int rr = wr3 * 64 + m * 16 + fr3;
;               const float2 ms = *reinterpret_cast<const float2*>(mr + (ai * HALF + rr) * 2);
;               f32x4 y = acc[ai][bj][m][n];
;               const float o0 = (y[0] - ms.x) * ms.y * gm.x + bt.x, o1 = (y[1] - ms.x) * ms.y * gm.y + bt.y;
;               const float o2 = (y[2] - ms.x) * ms.y * gm.z + bt.z, o3 = (y[3] - ms.x) * ms.y * gm.w + bt.w;
;               const unsigned h0 = f2bf(o0), h1 = f2bf(o1), h2 = f2bf(o2), h3 = f2bf(o3);
;               u32x2 ob; ob[0] = h0 | (h1 << 16); ob[1] = h2 | (h3 << 16);
;               *reinterpret_cast<u32x2*>(smem + (rr >> 1) * PIECE + (rr & 1) * 512 + cc * 2) = ob;
;               const int l0 = min(((int)__float_as_uint(o0) - (int)(h0 << 16) + 128) >> 8, 127);
;               const int l1 = min(((int)__float_as_uint(o1) - (int)(h1 << 16) + 128) >> 8, 127);
;               const int l2 = min(((int)__float_as_uint(o2) - (int)(h2 << 16) + 128) >> 8, 127);
;               const int l3 = min(((int)__float_as_uint(o3) - (int)(h3 << 16) + 128) >> 8, 127);
;               *reinterpret_cast<unsigned*>(smem + LOBASE + (rr >> 2) * PIECE + (rr & 3) * 256 + cc) =
;                   (unsigned)(l0 & 255) | ((unsigned)(l1 & 255) << 8) | ((unsigned)(l2 & 255) << 16) | ((unsigned)l3 << 24);
;             }
;           }
;           WAIT_L(0); BAR;
	v_or_b32_sdwa v6, v29, v28 dst_sel:DWORD dst_unused:UNUSED_PAD src0_sel:WORD_1 src1_sel:DWORD
	ds_write_b64 v93, v[6:7]
	v_and_b32_e32 v6, 0xffff0000, v29
	v_sub_u32_e32 v2, v2, v6
	v_sub_u32_e32 v6, v30, v28
	v_and_b32_e32 v7, 0xffff0000, v23
	v_add_u32_e32 v6, 0x80, v6
	v_sub_u32_e32 v7, v31, v7
	v_sub_u32_e32 v3, v3, v36
	v_add_u32_e32 v2, 0x80, v2
	v_ashrrev_i32_e32 v6, 8, v6
	v_add_u32_e32 v7, 0x80, v7
	v_add_u32_e32 v3, 0x80, v3
	v_ashrrev_i32_e32 v2, 8, v2
	v_min_i32_e32 v6, 0x7f, v6
	v_ashrrev_i32_e32 v7, 8, v7
	v_ashrrev_i32_e32 v3, 8, v3
	v_min_i32_e32 v2, 0x7f, v2
	v_min_i32_sdwa v7, v7, s83 dst_sel:WORD_1 dst_unused:UNUSED_PAD src0_sel:DWORD src1_sel:DWORD
	v_min_i32_e32 v3, 0x7f, v3
	v_lshlrev_b32_e32 v6, 8, v6
	v_and_b32_e32 v6, 0xff00, v6
	v_and_b32_e32 v7, 0xff0000, v7
	v_perm_b32 v2, v3, v2, s84
	v_or3_b32 v2, v2, v6, v7
	ds_write_b32 v12, v2 offset:144
	v_mov_b32_e32 v2, v212
	v_mov_b32_e32 v3, v213
	v_pk_add_f32 v[6:7], v[34:35], v[2:3] op_sel_hi:[1,0] neg_lo:[0,1] neg_hi:[0,1]
	s_nop 0
	v_pk_mul_f32 v[6:7], v[2:3], v[6:7] op_sel:[1,0]
	v_pk_add_f32 v[12:13], v[32:33], v[2:3] op_sel_hi:[1,0] neg_lo:[0,1] neg_hi:[0,1]
	v_pk_fma_f32 v[6:7], v[24:25], v[6:7], v[26:27]
	v_pk_mul_f32 v[2:3], v[2:3], v[12:13] op_sel:[1,0]
	v_and_b32_sdwa v12, v7, v216 dst_sel:DWORD dst_unused:UNUSED_PAD src0_sel:WORD_1 src1_sel:DWORD
	v_and_b32_sdwa v13, v6, v216 dst_sel:DWORD dst_unused:UNUSED_PAD src0_sel:WORD_1 src1_sel:DWORD
	v_pk_fma_f32 v[2:3], v[0:1], v[2:3], v[4:5]
	v_add3_u32 v23, v7, v12, s82
	v_add3_u32 v12, v6, v13, s82
	v_and_b32_e32 v28, 0xffff0000, v12
	v_and_b32_sdwa v12, v3, v216 dst_sel:DWORD dst_unused:UNUSED_PAD src0_sel:WORD_1 src1_sel:DWORD
	v_and_b32_sdwa v13, v2, v216 dst_sel:DWORD dst_unused:UNUSED_PAD src0_sel:WORD_1 src1_sel:DWORD
	v_add3_u32 v12, v3, v12, s82
	v_add3_u32 v29, v2, v13, s82
	v_and_b32_e32 v30, 0xffff0000, v12
	v_or_b32_sdwa v13, v30, v23 dst_sel:DWORD dst_unused:UNUSED_PAD src0_sel:DWORD src1_sel:WORD_1
	v_or_b32_sdwa v12, v29, v28 dst_sel:DWORD dst_unused:UNUSED_PAD src0_sel:WORD_1 src1_sel:DWORD
	ds_write_b64 v94, v[12:13]
	v_and_b32_e32 v12, 0xffff0000, v29
	v_sub_u32_e32 v2, v2, v12
	v_sub_u32_e32 v6, v6, v28
	v_and_b32_e32 v12, 0xffff0000, v23
	v_add_u32_e32 v6, 0x80, v6
	v_sub_u32_e32 v7, v7, v12
	v_sub_u32_e32 v3, v3, v30
	v_add_u32_e32 v2, 0x80, v2
	v_ashrrev_i32_e32 v6, 8, v6
	v_add_u32_e32 v7, 0x80, v7
	v_add_u32_e32 v3, 0x80, v3
	v_ashrrev_i32_e32 v2, 8, v2
	v_min_i32_e32 v6, 0x7f, v6
	v_ashrrev_i32_e32 v7, 8, v7
	v_ashrrev_i32_e32 v3, 8, v3
	v_min_i32_e32 v2, 0x7f, v2
	v_min_i32_sdwa v7, v7, s83 dst_sel:WORD_1 dst_unused:UNUSED_PAD src0_sel:DWORD src1_sel:DWORD
	v_min_i32_e32 v3, 0x7f, v3
	v_lshlrev_b32_e32 v6, 8, v6
	v_and_b32_e32 v6, 0xff00, v6
	v_and_b32_e32 v7, 0xff0000, v7
	v_perm_b32 v2, v3, v2, s84
	v_or3_b32 v2, v2, v6, v7
	ds_write_b32 v14, v2 offset:144
	v_mov_b32_e32 v2, v214
	v_mov_b32_e32 v3, v215
	v_pk_add_f32 v[6:7], v[18:19], v[2:3] op_sel_hi:[1,0] neg_lo:[0,1] neg_hi:[0,1]
	s_nop 0
	v_pk_mul_f32 v[6:7], v[2:3], v[6:7] op_sel:[1,0]
	v_pk_add_f32 v[12:13], v[16:17], v[2:3] op_sel_hi:[1,0] neg_lo:[0,1] neg_hi:[0,1]
	v_pk_fma_f32 v[6:7], v[24:25], v[6:7], v[26:27]
	v_pk_mul_f32 v[2:3], v[2:3], v[12:13] op_sel:[1,0]
	v_and_b32_sdwa v12, v7, v216 dst_sel:DWORD dst_unused:UNUSED_PAD src0_sel:WORD_1 src1_sel:DWORD
	v_and_b32_sdwa v13, v6, v216 dst_sel:DWORD dst_unused:UNUSED_PAD src0_sel:WORD_1 src1_sel:DWORD
	v_pk_fma_f32 v[2:3], v[0:1], v[2:3], v[4:5]
	v_add3_u32 v14, v7, v12, s82
	v_add3_u32 v12, v6, v13, s82
	v_and_b32_e32 v15, 0xffff0000, v12
	v_and_b32_sdwa v12, v3, v216 dst_sel:DWORD dst_unused:UNUSED_PAD src0_sel:WORD_1 src1_sel:DWORD
	v_and_b32_sdwa v13, v2, v216 dst_sel:DWORD dst_unused:UNUSED_PAD src0_sel:WORD_1 src1_sel:DWORD
	v_add3_u32 v12, v3, v12, s82
	v_add3_u32 v16, v2, v13, s82
	v_and_b32_e32 v17, 0xffff0000, v12
	v_or_b32_sdwa v13, v17, v14 dst_sel:DWORD dst_unused:UNUSED_PAD src0_sel:DWORD src1_sel:WORD_1
	v_or_b32_sdwa v12, v16, v15 dst_sel:DWORD dst_unused:UNUSED_PAD src0_sel:WORD_1 src1_sel:DWORD
	ds_write_b64 v80, v[12:13]
	v_and_b32_e32 v12, 0xffff0000, v16
	v_sub_u32_e32 v2, v2, v12
	v_sub_u32_e32 v6, v6, v15
	v_and_b32_e32 v12, 0xffff0000, v14
	v_add_u32_e32 v6, 0x80, v6
	v_sub_u32_e32 v7, v7, v12
	v_sub_u32_e32 v3, v3, v17
	v_add_u32_e32 v2, 0x80, v2
	v_ashrrev_i32_e32 v6, 8, v6
	v_add_u32_e32 v7, 0x80, v7
	v_add_u32_e32 v3, 0x80, v3
	v_ashrrev_i32_e32 v2, 8, v2
	v_min_i32_e32 v6, 0x7f, v6
	v_ashrrev_i32_e32 v7, 8, v7
	v_ashrrev_i32_e32 v3, 8, v3
	v_min_i32_e32 v2, 0x7f, v2
	v_min_i32_sdwa v7, v7, s83 dst_sel:WORD_1 dst_unused:UNUSED_PAD src0_sel:DWORD src1_sel:DWORD
	v_min_i32_e32 v3, 0x7f, v3
	v_lshlrev_b32_e32 v6, 8, v6
	v_and_b32_e32 v6, 0xff00, v6
	v_and_b32_e32 v7, 0xff0000, v7
	v_perm_b32 v2, v3, v2, s84
	v_or3_b32 v2, v2, v6, v7
	ds_write_b32 v20, v2 offset:144
	v_mov_b32_e32 v2, v252
	v_mov_b32_e32 v3, v253
	v_pk_add_f32 v[6:7], v[10:11], v[2:3] op_sel_hi:[1,0] neg_lo:[0,1] neg_hi:[0,1]
	s_nop 0
	v_pk_mul_f32 v[6:7], v[2:3], v[6:7] op_sel:[1,0]
	v_pk_add_f32 v[8:9], v[8:9], v[2:3] op_sel_hi:[1,0] neg_lo:[0,1] neg_hi:[0,1]
	v_pk_fma_f32 v[6:7], v[24:25], v[6:7], v[26:27]
	v_pk_mul_f32 v[2:3], v[2:3], v[8:9] op_sel:[1,0]
	s_nop 0
	v_pk_fma_f32 v[0:1], v[0:1], v[2:3], v[4:5]
	v_and_b32_sdwa v2, v7, v216 dst_sel:DWORD dst_unused:UNUSED_PAD src0_sel:WORD_1 src1_sel:DWORD
	v_and_b32_sdwa v3, v6, v216 dst_sel:DWORD dst_unused:UNUSED_PAD src0_sel:WORD_1 src1_sel:DWORD
	v_add3_u32 v4, v7, v2, s82
	v_add3_u32 v2, v6, v3, s82
	v_and_b32_e32 v5, 0xffff0000, v2
	v_and_b32_sdwa v2, v1, v216 dst_sel:DWORD dst_unused:UNUSED_PAD src0_sel:WORD_1 src1_sel:DWORD
	v_and_b32_sdwa v3, v0, v216 dst_sel:DWORD dst_unused:UNUSED_PAD src0_sel:WORD_1 src1_sel:DWORD
	v_add3_u32 v2, v1, v2, s82
	v_add3_u32 v8, v0, v3, s82
	v_and_b32_e32 v9, 0xffff0000, v2
	v_or_b32_sdwa v3, v9, v4 dst_sel:DWORD dst_unused:UNUSED_PAD src0_sel:DWORD src1_sel:WORD_1
	v_or_b32_sdwa v2, v8, v5 dst_sel:DWORD dst_unused:UNUSED_PAD src0_sel:WORD_1 src1_sel:DWORD
	ds_write_b64 v73, v[2:3]
	v_and_b32_e32 v2, 0xffff0000, v8
	v_sub_u32_e32 v0, v0, v2
	v_sub_u32_e32 v2, v6, v5
	v_and_b32_e32 v3, 0xffff0000, v4
	v_add_u32_e32 v2, 0x80, v2
	v_sub_u32_e32 v3, v7, v3
	v_sub_u32_e32 v1, v1, v9
	v_add_u32_e32 v0, 0x80, v0
	v_ashrrev_i32_e32 v2, 8, v2
	v_add_u32_e32 v3, 0x80, v3
	v_add_u32_e32 v1, 0x80, v1
	v_ashrrev_i32_e32 v0, 8, v0
	v_min_i32_e32 v2, 0x7f, v2
	v_ashrrev_i32_e32 v3, 8, v3
	v_ashrrev_i32_e32 v1, 8, v1
	v_min_i32_e32 v0, 0x7f, v0
	v_min_i32_sdwa v3, v3, s83 dst_sel:WORD_1 dst_unused:UNUSED_PAD src0_sel:DWORD src1_sel:DWORD
	v_min_i32_e32 v1, 0x7f, v1
	v_lshlrev_b32_e32 v2, 8, v2
	v_and_b32_e32 v2, 0xff00, v2
	v_and_b32_e32 v3, 0xff0000, v3
	v_perm_b32 v0, v1, v0, s84
	v_or3_b32 v0, v0, v2, v3
	ds_write_b32 v22, v0 offset:144
	s_waitcnt lgkmcnt(0)
	s_barrier
; #define STAGE(P, RS, SOFF, OFF, kt) do { const int _so = (SOFF) + (kt) * (BK * 2); \
;     _Pragma("unroll") for (int _i = 0; _i < 2; ++_i) { \
;       __builtin_amdgcn_raw_ptr_buffer_load_lds(RS, (__attribute__((address_space(3))) void*)((P) + wave * 1024 + _i * 8192), 16, OFF[_i], _so, 0, 0); } } while (0)
;     ...
;   auto issue_prologue = [&](int sA0, int sA1, int sB0, int sB1) {
;     const int tid = opaque_tid(wave);
;     int offA[2], offB[2];
;     _Pragma("unroll") for (int i = 0; i < 2; ++i) {
;       int r, c; stage_rc(tid * 16 + i * 8192, r, c);
;       offA[i] = (r * lda + c) * 2; offB[i] = (r * ldb + c) * 2;
;     }
;     STAGE(SB(0, 0), rsB, sB0, offB, 0); STAGE(SA(0, 0), rsA, sA0, offA, 0);
;     STAGE(SB(0, 1), rsB, sB1, offB, 0); STAGE(SA(0, 1), rsA, sA1, offA, 0);
;     STAGE(SB(1, 0), rsB, sB0, offB, 1); STAGE(SA(1, 0), rsA, sA0, offA, 1); STAGE(SB(1, 1), rsB, sB1, offB, 1);
;   };
;     ...
;           _Pragma("unroll") for (int i = 0; i < 8; ++i) {
;             const u32x4 v = *reinterpret_cast<const u32x4*>(smem + (wave * 8 + i) * PIECE + lane3 * 16);
;             __builtin_amdgcn_raw_buffer_store_b128(v, rsXB, hvo + i * (2 * DM * 2), hso, 0);
;           }
;           _Pragma("unroll") for (int i = 0; i < 4; ++i) {
;             const u32x4 v = *reinterpret_cast<const u32x4*>(smem + LOBASE + (wave * 4 + i) * PIECE + lane3 * 16);
;             __builtin_amdgcn_raw_buffer_store_b128(v, rsLO, lvo + i * (4 * DM), lso, 0);
;           }
	ds_read_b128 v[128:131], v72
	ds_read_b128 v[132:135], v72 offset:1040
	ds_read_b128 v[136:139], v72 offset:2080
	ds_read_b128 v[140:143], v72 offset:3120
	ds_read_b128 v[152:155], v72 offset:4160
	ds_read_b128 v[156:159], v72 offset:5200
	ds_read_b128 v[160:163], v72 offset:6240
	ds_read_b128 v[164:167], v72 offset:7280
	ds_read_b128 v[168:171], v147
	ds_read_b128 v[172:175], v147 offset:1040
	ds_read_b128 v[176:179], v147 offset:2080
	ds_read_b128 v[180:183], v147 offset:3120
	s_waitcnt lgkmcnt(0)
	s_barrier
	s_cbranch_vccnz .Lmy_s1n_379
	v_mbcnt_lo_u32_b32 v0, -1, 0
	v_mbcnt_hi_u32_b32 v0, -1, v0
	s_mov_b32 m0, s37
	v_lshl_add_u32 v0, v0, 4, s35
	v_ashrrev_i32_e32 v1, 31, v0
	v_lshrrev_b32_e32 v1, 22, v1
	v_add_u32_e32 v1, v0, v1
	v_ashrrev_i32_e32 v1, 10, v1
	v_mul_i32_i24_e32 v2, 0x400, v1
	v_sub_u32_e32 v2, v0, v2
	v_lshrrev_b32_e32 v3, 4, v2
	v_bitop3_b32 v2, v3, v2, 32 bitop3:0x6c
	v_ashrrev_i32_e32 v4, 31, v2
	v_lshrrev_b32_e32 v4, 26, v4
	v_add_u32_e32 v4, v2, v4
	v_lshrrev_b32_e32 v5, 6, v4
	v_and_b32_e32 v4, 0xc0, v4
	v_lshlrev_b32_e32 v3, 3, v1
	v_lshlrev_b32_e32 v1, 5, v1
	v_sub_u32_e32 v2, v2, v4
	v_and_b32_e32 v3, 0x7fff0, v3
	v_and_b32_e32 v1, 32, v1
	v_ashrrev_i16_sdwa v2, v216, sext(v2) dst_sel:DWORD dst_unused:UNUSED_PAD src0_sel:DWORD src1_sel:BYTE_0
	v_add_u32_sdwa v1, v1, sext(v2) dst_sel:DWORD dst_unused:UNUSED_PAD src0_sel:DWORD src1_sel:WORD_0
	v_add_lshl_u32 v2, v5, v3, 13
	v_add_u32_e32 v0, 0x2000, v0
	v_lshl_add_u32 v1, v1, 1, v2
	v_ashrrev_i32_e32 v2, 31, v0
	v_lshrrev_b32_e32 v2, 22, v2
	v_add_u32_e32 v2, v0, v2
	v_ashrrev_i32_e32 v2, 10, v2
	v_mul_i32_i24_e32 v3, 0x400, v2
	v_sub_u32_e32 v0, v0, v3
	v_lshrrev_b32_e32 v3, 4, v0
	v_bitop3_b32 v0, v3, v0, 32 bitop3:0x6c
	v_ashrrev_i32_e32 v4, 31, v0
	v_lshrrev_b32_e32 v4, 26, v4
	v_add_u32_e32 v4, v0, v4
	v_lshrrev_b32_e32 v5, 6, v4
	v_and_b32_e32 v4, 0xffc0, v4
	v_sub_u32_e32 v0, v0, v4
	v_lshrrev_b16_e32 v4, 7, v0
	v_and_b32_e32 v4, 1, v4
	v_lshlrev_b32_e32 v3, 3, v2
	v_lshlrev_b32_e32 v2, 5, v2
	v_add_u16_e32 v0, v0, v4
	v_and_b32_e32 v3, 0x7fff0, v3
	v_and_b32_e32 v2, 32, v2
	v_ashrrev_i16_sdwa v0, v216, sext(v0) dst_sel:DWORD dst_unused:UNUSED_PAD src0_sel:DWORD src1_sel:BYTE_0
	v_add_u32_sdwa v0, v2, sext(v0) dst_sel:DWORD dst_unused:UNUSED_PAD src0_sel:DWORD src1_sel:WORD_0
	v_add_lshl_u32 v2, v5, v3, 13
	s_mov_b32 s14, s10
	s_mov_b32 s15, s11
	v_lshl_add_u32 v0, v0, 1, v2
	buffer_load_dwordx4 v1, s[12:15], s92 offen lds
	s_mov_b32 m0, s48
	s_or_b32 s0, s92, 0x80
	buffer_load_dwordx4 v0, s[12:15], s92 offen lds
	s_mov_b32 m0, s35
	s_mov_b64 s[4:5], 0
	buffer_load_dwordx4 v1, s[8:11], s87 offen lds
	s_mov_b32 m0, s49
	s_nop 0
	buffer_load_dwordx4 v0, s[8:11], s87 offen lds
	s_mov_b32 m0, s38
	s_nop 0
	buffer_load_dwordx4 v1, s[12:15], s93 offen lds
	s_mov_b32 m0, s54
	s_nop 0
	buffer_load_dwordx4 v0, s[12:15], s93 offen lds
	s_mov_b32 m0, s39
	s_nop 0
	buffer_load_dwordx4 v1, s[8:11], s86 offen lds
	s_mov_b32 m0, s55
	s_nop 0
	buffer_load_dwordx4 v0, s[8:11], s86 offen lds
	s_mov_b32 m0, s42
	s_nop 0
	buffer_load_dwordx4 v1, s[12:15], s0 offen lds
	s_mov_b32 m0, s56
	s_nop 0
	buffer_load_dwordx4 v0, s[12:15], s0 offen lds
	s_or_b32 s0, s87, 0x80
	s_mov_b32 m0, s43
	s_nop 0
	buffer_load_dwordx4 v1, s[8:11], s0 offen lds
	s_mov_b32 m0, s57
	s_nop 0
	buffer_load_dwordx4 v0, s[8:11], s0 offen lds
	s_add_i32 s0, s93, 0x80
	s_mov_b32 m0, s44
	s_nop 0
	buffer_load_dwordx4 v1, s[12:15], s0 offen lds
	s_mov_b32 m0, s58
	s_nop 0
	buffer_load_dwordx4 v0, s[12:15], s0 offen lds
	buffer_store_dwordx4 v[128:131], v148, s[16:19], s3 offen
	buffer_store_dwordx4 v[132:135], v74, s[16:19], s3 offen
	buffer_store_dwordx4 v[136:139], v75, s[16:19], s3 offen
	buffer_store_dwordx4 v[140:143], v81, s[16:19], s3 offen
	buffer_store_dwordx4 v[152:155], v82, s[16:19], s3 offen
	buffer_store_dwordx4 v[156:159], v83, s[16:19], s3 offen
	buffer_store_dwordx4 v[160:163], v88, s[16:19], s3 offen
	buffer_store_dwordx4 v[164:167], v89, s[16:19], s3 offen
	buffer_store_dwordx4 v[168:171], v146, s[20:23], s1 offen
	buffer_store_dwordx4 v[172:175], v90, s[20:23], s1 offen
	buffer_store_dwordx4 v[176:179], v91, s[20:23], s1 offen
	buffer_store_dwordx4 v[180:183], v95, s[20:23], s1 offen
	s_branch .LBB0_384

;     ...
;         constexpr int PIECE = 1024 + 16, LOBASE = 64 * PIECE;
;         const int lane3 = tid3 & 63;
;         const int hvo = (lane3 >> 5) * (DM * 2) + (lane3 & 31) * 16;
;         const int lvo = (lane3 >> 4) * DM + (lane3 & 15) * 16;
;         _Pragma("unroll") for (int ai = 0; ai < 2; ++ai) {
;           _Pragma("unroll") for (int bj = 0; bj < 2; ++bj) _Pragma("unroll") for (int n = 0; n < 2; ++n) {
;             const int cc = bj * HALF + wc3 * 32 + n * 16 + fq3 * 4;
;             const float4 gm = *reinterpret_cast<const float4*>(g.gam + pn * BM + cc), bt = *reinterpret_cast<const float4*>(g.bet + pn * BM + cc);
;             _Pragma("unroll") for (int m = 0; m < 4; ++m) {
;               const int rr = wr3 * 64 + m * 16 + fr3;
;               const float2 ms = *reinterpret_cast<const float2*>(mr + (ai * HALF + rr) * 2);
;               f32x4 y = acc[ai][bj][m][n];
;               const float o0 = (y[0] - ms.x) * ms.y * gm.x + bt.x, o1 = (y[1] - ms.x) * ms.y * gm.y + bt.y;
;               const float o2 = (y[2] - ms.x) * ms.y * gm.z + bt.z, o3 = (y[3] - ms.x) * ms.y * gm.w + bt.w;
;               const unsigned h0 = f2bf(o0), h1 = f2bf(o1), h2 = f2bf(o2), h3 = f2bf(o3);
;               u32x2 ob; ob[0] = h0 | (h1 << 16); ob[1] = h2 | (h3 << 16);
;               *reinterpret_cast<u32x2*>(smem + (rr >> 1) * PIECE + (rr & 1) * 512 + cc * 2) = ob;
;               const int l0 = min(((int)__float_as_uint(o0) - (int)(h0 << 16) + 128) >> 8, 127);
;               const int l1 = min(((int)__float_as_uint(o1) - (int)(h1 << 16) + 128) >> 8, 127);
;               const int l2 = min(((int)__float_as_uint(o2) - (int)(h2 << 16) + 128) >> 8, 127);
;               const int l3 = min(((int)__float_as_uint(o3) - (int)(h3 << 16) + 128) >> 8, 127);
;               *reinterpret_cast<unsigned*>(smem + LOBASE + (rr >> 2) * PIECE + (rr & 3) * 256 + cc) =
;                   (unsigned)(l0 & 255) | ((unsigned)(l1 & 255) << 8) | ((unsigned)(l2 & 255) << 16) | ((unsigned)l3 << 24);
;             }
.LBB0_523:
	s_or_b64 exec, exec, s[6:7]
	s_waitcnt lgkmcnt(0)
	s_barrier
	v_mbcnt_lo_u32_b32 v0, -1, 0
	v_mbcnt_hi_u32_b32 v0, -1, v0
	v_readlane_b32 s40, v255, 0
	v_add_u32_e32 v1, s34, v0
	v_bfe_u32 v4, v0, 4, 2
	v_ashrrev_i32_e32 v5, 2, v1
	v_lshrrev_b32_e32 v6, 1, v1
	v_lshlrev_b32_e32 v1, 4, v1
	v_lshlrev_b32_e32 v7, 2, v4
	v_lshlrev_b32_e32 v12, 7, v0
	v_and_b32_e32 v13, 0x1f0, v1
	s_movk_i32 s4, 0x60
	s_ashr_i32 s29, s28, 31
	v_readlane_b32 s54, v255, 14
	v_readlane_b32 s55, v255, 15
	v_and_or_b32 v148, v12, s75, v13
	v_and_or_b32 v12, v6, s4, v7
	s_lshl_b64 s[4:5], s[28:29], 2
	s_mov_b64 s[22:23], s[54:55]
	s_add_u32 s6, s22, s4
	v_and_b32_e32 v2, 15, v0
	v_and_b32_e32 v3, 63, v0
	v_and_b32_e32 v1, 0xf0, v1
	v_lshlrev_b32_e32 v13, 9, v0
	v_lshlrev_b32_e32 v0, 8, v0
	s_addc_u32 s7, s23, s5
	v_lshlrev_b32_e32 v150, 2, v12
	v_lshl_or_b32 v146, v4, 11, v1
	v_and_or_b32 v156, v5, s31, v2
	v_and_b32_e32 v14, 0x300, v0
	v_lshlrev_b32_e32 v151, 4, v3
	global_load_dwordx4 v[220:223], v150, s[6:7]
	global_load_dwordx4 v[224:227], v150, s[6:7] offset:64
	global_load_dwordx4 v[228:231], v150, s[6:7] offset:512
	global_load_dwordx4 v[232:235], v150, s[6:7] offset:576
	v_readlane_b32 s41, v255, 1
	v_readlane_b32 s42, v255, 2
	v_readlane_b32 s43, v255, 3
	v_readlane_b32 s44, v255, 4
	v_readlane_b32 s45, v255, 5
	v_readlane_b32 s46, v255, 6
	v_readlane_b32 s47, v255, 7
	v_readlane_b32 s48, v255, 8
	v_readlane_b32 s49, v255, 9
	v_readlane_b32 s50, v255, 10
	v_readlane_b32 s51, v255, 11
	v_readlane_b32 s52, v255, 12
	v_readlane_b32 s53, v255, 13
	v_readlane_b32 s40, v255, 16
	v_readlane_b32 s41, v255, 17
	s_add_u32 s4, s40, s4
	s_addc_u32 s5, s41, s5
	global_load_dwordx4 v[236:239], v150, s[4:5]
	global_load_dwordx4 v[240:243], v150, s[4:5] offset:64
	global_load_dwordx4 v[244:247], v150, s[4:5] offset:512
	global_load_dwordx4 v[248:251], v150, s[4:5] offset:576
	s_movk_i32 s22, 0x200
	v_lshl_add_u32 v149, v156, 3, v219
	v_add_u32_e32 v147, s69, v151
	s_andn2_b64 vcc, exec, s[14:15]
	v_readlane_b32 s42, v255, 18
	v_readlane_b32 s43, v255, 19
	v_readlane_b32 s44, v255, 20
	v_readlane_b32 s45, v255, 21
	v_readlane_b32 s46, v255, 22
	v_readlane_b32 s47, v255, 23
	v_readlane_b32 s48, v255, 24
	v_readlane_b32 s49, v255, 25
	v_readlane_b32 s50, v255, 26
	v_readlane_b32 s51, v255, 27
	v_readlane_b32 s52, v255, 28
	v_readlane_b32 s53, v255, 29
	v_readlane_b32 s54, v255, 30
	v_readlane_b32 s55, v255, 31
	s_waitcnt vmcnt(0)
	v_mov_b32_e32 v0, v220
	v_mov_b32_e32 v1, v221
	v_mov_b32_e32 v2, v222
	v_mov_b32_e32 v3, v223
	v_mov_b32_e32 v4, v236
	v_mov_b32_e32 v5, v237
	v_mov_b32_e32 v6, v238
	v_mov_b32_e32 v7, v239
	v_mov_b32_e32 v22, v1
	v_lshlrev_b32_e32 v1, 1, v12
	v_and_or_b32 v155, v13, s22, v1
	s_mov_b32 s22, 0x10400
	v_mov_b32_e32 v23, v2
	v_or3_b32 v2, v14, v12, s22
	ds_read_b64 v[12:13], v149
	v_mov_b32_e32 v1, v3
	s_waitcnt lgkmcnt(0)
	v_mov_b32_e32 v210, v12
	v_mov_b32_e32 v211, v13
	v_pk_add_f32 v[14:15], v[128:129], v[12:13] op_sel_hi:[1,0] neg_lo:[0,1] neg_hi:[0,1]
	s_nop 0
	v_pk_mul_f32 v[14:15], v[12:13], v[14:15] op_sel:[1,0]
	v_pk_add_f32 v[20:21], v[130:131], v[12:13] op_sel_hi:[1,0] neg_lo:[0,1] neg_hi:[0,1]
	v_lshrrev_b32_e32 v129, 1, v156
	v_pk_mul_f32 v[12:13], v[12:13], v[20:21] op_sel:[1,0]
	v_mul_lo_u32 v153, v129, s61
	v_add_u32_e32 v152, v155, v153
	v_mov_b32_e32 v144, v5
	v_mov_b32_e32 v145, v6
	v_pk_fma_f32 v[14:15], v[22:23], v[14:15], v[144:145]
	v_mov_b32_e32 v5, v7
	v_pk_fma_f32 v[6:7], v[0:1], v[12:13], v[4:5]
	v_and_b32_sdwa v12, v14, v216 dst_sel:DWORD dst_unused:UNUSED_PAD src0_sel:WORD_1 src1_sel:DWORD
	v_add3_u32 v12, v14, v12, s78
	v_and_b32_e32 v20, 0xffff0000, v12
	v_and_b32_sdwa v12, v7, v216 dst_sel:DWORD dst_unused:UNUSED_PAD src0_sel:WORD_1 src1_sel:DWORD
	v_and_b32_sdwa v3, v15, v216 dst_sel:DWORD dst_unused:UNUSED_PAD src0_sel:WORD_1 src1_sel:DWORD
	v_and_b32_sdwa v13, v6, v216 dst_sel:DWORD dst_unused:UNUSED_PAD src0_sel:WORD_1 src1_sel:DWORD
	v_add3_u32 v12, v7, v12, s78
	v_add3_u32 v3, v15, v3, s78
	v_add3_u32 v21, v6, v13, s78
	v_and_b32_e32 v128, 0xffff0000, v12
	v_or_b32_sdwa v13, v128, v3 dst_sel:DWORD dst_unused:UNUSED_PAD src0_sel:DWORD src1_sel:WORD_1
	v_or_b32_sdwa v12, v21, v20 dst_sel:DWORD dst_unused:UNUSED_PAD src0_sel:WORD_1 src1_sel:DWORD
	ds_write_b64 v152, v[12:13]
	v_and_b32_e32 v12, 0xffff0000, v21
	v_sub_u32_e32 v6, v6, v12
	v_sub_u32_e32 v12, v14, v20
	v_and_b32_e32 v3, 0xffff0000, v3
	v_add_u32_e32 v12, 0x80, v12
	v_sub_u32_e32 v3, v15, v3
	v_sub_u32_e32 v7, v7, v128
	v_add_u32_e32 v6, 0x80, v6
	v_ashrrev_i32_e32 v12, 8, v12
	v_add_u32_e32 v3, 0x80, v3
	v_add_u32_e32 v7, 0x80, v7
	v_ashrrev_i32_e32 v6, 8, v6
	v_min_i32_e32 v12, 0x7f, v12
	v_ashrrev_i32_e32 v3, 8, v3
	v_ashrrev_i32_e32 v7, 8, v7
	v_min_i32_e32 v6, 0x7f, v6
	v_min_i32_sdwa v3, v3, s79 dst_sel:WORD_1 dst_unused:UNUSED_PAD src0_sel:DWORD src1_sel:DWORD
	v_min_i32_e32 v7, 0x7f, v7
	v_lshlrev_b32_e32 v12, 8, v12
	v_and_b32_e32 v12, 0xff00, v12
	v_and_b32_e32 v3, 0xff0000, v3
	v_perm_b32 v6, v7, v6, s80
	v_or3_b32 v3, v6, v12, v3
	v_lshrrev_b32_e32 v6, 2, v156
	v_mad_u64_u32 v[12:13], s[22:23], v6, s61, v[2:3]
	ds_write_b32 v12, v3
	v_or_b32_e32 v3, 16, v156
	v_lshl_add_u32 v13, v3, 3, v219
	ds_read_b64 v[6:7], v13
	s_waitcnt lgkmcnt(0)
;     ...
;           _Pragma("unroll") for (int bj = 0; bj < 2; ++bj) _Pragma("unroll") for (int n = 0; n < 2; ++n) {
;             const int cc = bj * HALF + wc3 * 32 + n * 16 + fq3 * 4;
;             const float4 gm = *reinterpret_cast<const float4*>(g.gam + pn * BM + cc), bt = *reinterpret_cast<const float4*>(g.bet + pn * BM + cc);
;             _Pragma("unroll") for (int m = 0; m < 4; ++m) {
;               const int rr = wr3 * 64 + m * 16 + fr3;
;               const float2 ms = *reinterpret_cast<const float2*>(mr + (ai * HALF + rr) * 2);
;               f32x4 y = acc[ai][bj][m][n];
;               const float o0 = (y[0] - ms.x) * ms.y * gm.x + bt.x, o1 = (y[1] - ms.x) * ms.y * gm.y + bt.y;
;               const float o2 = (y[2] - ms.x) * ms.y * gm.z + bt.z, o3 = (y[3] - ms.x) * ms.y * gm.w + bt.w;
;               const unsigned h0 = f2bf(o0), h1 = f2bf(o1), h2 = f2bf(o2), h3 = f2bf(o3);
;               u32x2 ob; ob[0] = h0 | (h1 << 16); ob[1] = h2 | (h3 << 16);
;               *reinterpret_cast<u32x2*>(smem + (rr >> 1) * PIECE + (rr & 1) * 512 + cc * 2) = ob;
;               const int l0 = min(((int)__float_as_uint(o0) - (int)(h0 << 16) + 128) >> 8, 127);
;               const int l1 = min(((int)__float_as_uint(o1) - (int)(h1 << 16) + 128) >> 8, 127);
;               const int l2 = min(((int)__float_as_uint(o2) - (int)(h2 << 16) + 128) >> 8, 127);
;               const int l3 = min(((int)__float_as_uint(o3) - (int)(h3 << 16) + 128) >> 8, 127);
;               *reinterpret_cast<unsigned*>(smem + LOBASE + (rr >> 2) * PIECE + (rr & 3) * 256 + cc) =
;                   (unsigned)(l0 & 255) | ((unsigned)(l1 & 255) << 8) | ((unsigned)(l2 & 255) << 16) | ((unsigned)l3 << 24);
;             }
	v_mov_b32_e32 v212, v6
	v_mov_b32_e32 v213, v7
	v_pk_add_f32 v[14:15], v[134:135], v[6:7] op_sel_hi:[1,0] neg_lo:[0,1] neg_hi:[0,1]
	s_nop 0
	v_pk_mul_f32 v[14:15], v[6:7], v[14:15] op_sel:[1,0]
	v_pk_add_f32 v[20:21], v[132:133], v[6:7] op_sel_hi:[1,0] neg_lo:[0,1] neg_hi:[0,1]
	v_pk_fma_f32 v[14:15], v[22:23], v[14:15], v[144:145]
	v_pk_mul_f32 v[6:7], v[6:7], v[20:21] op_sel:[1,0]
	v_and_b32_sdwa v20, v15, v216 dst_sel:DWORD dst_unused:UNUSED_PAD src0_sel:WORD_1 src1_sel:DWORD
	v_and_b32_sdwa v21, v14, v216 dst_sel:DWORD dst_unused:UNUSED_PAD src0_sel:WORD_1 src1_sel:DWORD
	v_pk_fma_f32 v[6:7], v[0:1], v[6:7], v[4:5]
	v_add3_u32 v128, v15, v20, s78
	v_add3_u32 v20, v14, v21, s78
	v_and_b32_e32 v129, 0xffff0000, v20
	v_and_b32_sdwa v20, v7, v216 dst_sel:DWORD dst_unused:UNUSED_PAD src0_sel:WORD_1 src1_sel:DWORD
	v_and_b32_sdwa v21, v6, v216 dst_sel:DWORD dst_unused:UNUSED_PAD src0_sel:WORD_1 src1_sel:DWORD
	v_add3_u32 v20, v7, v20, s78
	v_lshrrev_b32_e32 v132, 1, v3
	v_add3_u32 v130, v6, v21, s78
	v_and_b32_e32 v131, 0xffff0000, v20
	v_mul_lo_u32 v154, v132, s61
	v_or_b32_sdwa v21, v131, v128 dst_sel:DWORD dst_unused:UNUSED_PAD src0_sel:DWORD src1_sel:WORD_1
	v_or_b32_sdwa v20, v130, v129 dst_sel:DWORD dst_unused:UNUSED_PAD src0_sel:WORD_1 src1_sel:DWORD
	v_add_u32_e32 v132, v155, v154
	ds_write_b64 v132, v[20:21]
	v_and_b32_e32 v20, 0xffff0000, v130
	v_sub_u32_e32 v6, v6, v20
	v_sub_u32_e32 v14, v14, v129
	v_and_b32_e32 v20, 0xffff0000, v128
	v_add_u32_e32 v14, 0x80, v14
	v_sub_u32_e32 v15, v15, v20
	v_sub_u32_e32 v7, v7, v131
	v_add_u32_e32 v6, 0x80, v6
	v_ashrrev_i32_e32 v14, 8, v14
	v_add_u32_e32 v15, 0x80, v15
	v_add_u32_e32 v7, 0x80, v7
	v_ashrrev_i32_e32 v6, 8, v6
	v_min_i32_e32 v14, 0x7f, v14
	v_ashrrev_i32_e32 v15, 8, v15
	v_ashrrev_i32_e32 v7, 8, v7
	v_min_i32_e32 v6, 0x7f, v6
	v_min_i32_sdwa v15, v15, s79 dst_sel:WORD_1 dst_unused:UNUSED_PAD src0_sel:DWORD src1_sel:DWORD
	v_min_i32_e32 v7, 0x7f, v7
	v_lshlrev_b32_e32 v14, 8, v14
	v_and_b32_e32 v14, 0xff00, v14
	v_and_b32_e32 v15, 0xff0000, v15
	v_perm_b32 v6, v7, v6, s80
	v_lshrrev_b32_e32 v3, 2, v3
	v_or3_b32 v6, v6, v14, v15
	v_mad_u64_u32 v[14:15], s[22:23], v3, s61, v[2:3]
	v_or_b32_e32 v3, 32, v156
	ds_write_b32 v14, v6
	v_lshl_add_u32 v15, v3, 3, v219
	ds_read_b64 v[6:7], v15
	v_lshrrev_b32_e32 v133, 1, v3
	v_lshrrev_b32_e32 v3, 2, v3
	s_waitcnt lgkmcnt(0)
	v_mov_b32_e32 v214, v6
	v_mov_b32_e32 v215, v7
	v_pk_add_f32 v[20:21], v[138:139], v[6:7] op_sel_hi:[1,0] neg_lo:[0,1] neg_hi:[0,1]
	s_nop 0
	v_pk_mul_f32 v[20:21], v[6:7], v[20:21] op_sel:[1,0]
	v_pk_add_f32 v[128:129], v[136:137], v[6:7] op_sel_hi:[1,0] neg_lo:[0,1] neg_hi:[0,1]
	v_pk_fma_f32 v[20:21], v[22:23], v[20:21], v[144:145]
	v_pk_mul_f32 v[6:7], v[6:7], v[128:129] op_sel:[1,0]
	v_and_b32_sdwa v128, v21, v216 dst_sel:DWORD dst_unused:UNUSED_PAD src0_sel:WORD_1 src1_sel:DWORD
	v_and_b32_sdwa v129, v20, v216 dst_sel:DWORD dst_unused:UNUSED_PAD src0_sel:WORD_1 src1_sel:DWORD
	v_pk_fma_f32 v[6:7], v[0:1], v[6:7], v[4:5]
	v_add3_u32 v130, v21, v128, s78
	v_add3_u32 v128, v20, v129, s78
	v_and_b32_e32 v131, 0xffff0000, v128
	v_and_b32_sdwa v128, v7, v216 dst_sel:DWORD dst_unused:UNUSED_PAD src0_sel:WORD_1 src1_sel:DWORD
	v_and_b32_sdwa v129, v6, v216 dst_sel:DWORD dst_unused:UNUSED_PAD src0_sel:WORD_1 src1_sel:DWORD
	v_add3_u32 v128, v7, v128, s78
	v_add3_u32 v134, v6, v129, s78
	v_and_b32_e32 v135, 0xffff0000, v128
	v_mul_lo_u32 v136, v133, s61
	v_or_b32_sdwa v129, v135, v130 dst_sel:DWORD dst_unused:UNUSED_PAD src0_sel:DWORD src1_sel:WORD_1
	v_or_b32_sdwa v128, v134, v131 dst_sel:DWORD dst_unused:UNUSED_PAD src0_sel:WORD_1 src1_sel:DWORD
	v_add_u32_e32 v133, v155, v136
	ds_write_b64 v133, v[128:129]
	v_and_b32_e32 v128, 0xffff0000, v134
	v_sub_u32_e32 v6, v6, v128
	v_sub_u32_e32 v20, v20, v131
	v_and_b32_e32 v128, 0xffff0000, v130
	v_add_u32_e32 v20, 0x80, v20
	v_sub_u32_e32 v21, v21, v128
	v_sub_u32_e32 v7, v7, v135
	v_add_u32_e32 v6, 0x80, v6
	v_ashrrev_i32_e32 v20, 8, v20
	v_add_u32_e32 v21, 0x80, v21
	v_add_u32_e32 v7, 0x80, v7
	v_ashrrev_i32_e32 v6, 8, v6
	v_min_i32_e32 v20, 0x7f, v20
	v_ashrrev_i32_e32 v21, 8, v21
	v_ashrrev_i32_e32 v7, 8, v7
	v_min_i32_e32 v6, 0x7f, v6
	v_min_i32_sdwa v21, v21, s79 dst_sel:WORD_1 dst_unused:UNUSED_PAD src0_sel:DWORD src1_sel:DWORD
	v_min_i32_e32 v7, 0x7f, v7
	v_lshlrev_b32_e32 v20, 8, v20
	v_and_b32_e32 v20, 0xff00, v20
	v_and_b32_e32 v21, 0xff0000, v21
	v_perm_b32 v6, v7, v6, s80
	v_or3_b32 v6, v6, v20, v21
	v_mad_u64_u32 v[20:21], s[22:23], v3, s61, v[2:3]
	v_or_b32_e32 v3, 48, v156
	ds_write_b32 v20, v6
	v_lshl_add_u32 v21, v3, 3, v219
	ds_read_b64 v[6:7], v21
	v_lshrrev_b32_e32 v130, 1, v3
	v_mul_lo_u32 v135, v130, s61
	v_add_u32_e32 v134, v155, v135
	s_waitcnt lgkmcnt(0)
;     ...
;           _Pragma("unroll") for (int bj = 0; bj < 2; ++bj) _Pragma("unroll") for (int n = 0; n < 2; ++n) {
;             const int cc = bj * HALF + wc3 * 32 + n * 16 + fq3 * 4;
;             const float4 gm = *reinterpret_cast<const float4*>(g.gam + pn * BM + cc), bt = *reinterpret_cast<const float4*>(g.bet + pn * BM + cc);
;             _Pragma("unroll") for (int m = 0; m < 4; ++m) {
;               const int rr = wr3 * 64 + m * 16 + fr3;
;               const float2 ms = *reinterpret_cast<const float2*>(mr + (ai * HALF + rr) * 2);
;               f32x4 y = acc[ai][bj][m][n];
;               const float o0 = (y[0] - ms.x) * ms.y * gm.x + bt.x, o1 = (y[1] - ms.x) * ms.y * gm.y + bt.y;
;               const float o2 = (y[2] - ms.x) * ms.y * gm.z + bt.z, o3 = (y[3] - ms.x) * ms.y * gm.w + bt.w;
;               const unsigned h0 = f2bf(o0), h1 = f2bf(o1), h2 = f2bf(o2), h3 = f2bf(o3);
;               u32x2 ob; ob[0] = h0 | (h1 << 16); ob[1] = h2 | (h3 << 16);
;               *reinterpret_cast<u32x2*>(smem + (rr >> 1) * PIECE + (rr & 1) * 512 + cc * 2) = ob;
;               const int l0 = min(((int)__float_as_uint(o0) - (int)(h0 << 16) + 128) >> 8, 127);
;               const int l1 = min(((int)__float_as_uint(o1) - (int)(h1 << 16) + 128) >> 8, 127);
;               const int l2 = min(((int)__float_as_uint(o2) - (int)(h2 << 16) + 128) >> 8, 127);
;               const int l3 = min(((int)__float_as_uint(o3) - (int)(h3 << 16) + 128) >> 8, 127);
;               *reinterpret_cast<unsigned*>(smem + LOBASE + (rr >> 2) * PIECE + (rr & 3) * 256 + cc) =
;                   (unsigned)(l0 & 255) | ((unsigned)(l1 & 255) << 8) | ((unsigned)(l2 & 255) << 16) | ((unsigned)l3 << 24);
;             }
	v_mov_b32_e32 v252, v6
	v_mov_b32_e32 v253, v7
	v_pk_add_f32 v[128:129], v[142:143], v[6:7] op_sel_hi:[1,0] neg_lo:[0,1] neg_hi:[0,1]
	s_nop 0
	v_pk_mul_f32 v[128:129], v[6:7], v[128:129] op_sel:[1,0]
	s_nop 0
	v_pk_fma_f32 v[22:23], v[22:23], v[128:129], v[144:145]
	v_pk_add_f32 v[128:129], v[140:141], v[6:7] op_sel_hi:[1,0] neg_lo:[0,1] neg_hi:[0,1]
	s_nop 0
	v_pk_mul_f32 v[6:7], v[6:7], v[128:129] op_sel:[1,0]
	s_nop 0
	v_pk_fma_f32 v[0:1], v[0:1], v[6:7], v[4:5]
	v_and_b32_sdwa v4, v23, v216 dst_sel:DWORD dst_unused:UNUSED_PAD src0_sel:WORD_1 src1_sel:DWORD
	v_and_b32_sdwa v5, v22, v216 dst_sel:DWORD dst_unused:UNUSED_PAD src0_sel:WORD_1 src1_sel:DWORD
	v_add3_u32 v6, v23, v4, s78
	v_add3_u32 v4, v22, v5, s78
	v_and_b32_e32 v7, 0xffff0000, v4
	v_and_b32_sdwa v4, v1, v216 dst_sel:DWORD dst_unused:UNUSED_PAD src0_sel:WORD_1 src1_sel:DWORD
	v_and_b32_sdwa v5, v0, v216 dst_sel:DWORD dst_unused:UNUSED_PAD src0_sel:WORD_1 src1_sel:DWORD
	v_add3_u32 v4, v1, v4, s78
	v_add3_u32 v128, v0, v5, s78
	v_and_b32_e32 v129, 0xffff0000, v4
	v_or_b32_sdwa v5, v129, v6 dst_sel:DWORD dst_unused:UNUSED_PAD src0_sel:DWORD src1_sel:WORD_1
	v_or_b32_sdwa v4, v128, v7 dst_sel:DWORD dst_unused:UNUSED_PAD src0_sel:WORD_1 src1_sel:DWORD
	ds_write_b64 v134, v[4:5]
	v_and_b32_e32 v4, 0xffff0000, v128
	v_sub_u32_e32 v0, v0, v4
	v_sub_u32_e32 v4, v22, v7
	v_and_b32_e32 v5, 0xffff0000, v6
	v_add_u32_e32 v4, 0x80, v4
	v_sub_u32_e32 v5, v23, v5
	v_sub_u32_e32 v1, v1, v129
	v_add_u32_e32 v0, 0x80, v0
	v_ashrrev_i32_e32 v4, 8, v4
	v_add_u32_e32 v5, 0x80, v5
	v_add_u32_e32 v1, 0x80, v1
	v_ashrrev_i32_e32 v0, 8, v0
	v_min_i32_e32 v4, 0x7f, v4
	v_ashrrev_i32_e32 v5, 8, v5
	v_ashrrev_i32_e32 v1, 8, v1
	v_min_i32_e32 v0, 0x7f, v0
	v_min_i32_sdwa v5, v5, s79 dst_sel:WORD_1 dst_unused:UNUSED_PAD src0_sel:DWORD src1_sel:DWORD
	v_min_i32_e32 v1, 0x7f, v1
	v_lshlrev_b32_e32 v4, 8, v4
	v_and_b32_e32 v4, 0xff00, v4
	v_and_b32_e32 v5, 0xff0000, v5
	v_perm_b32 v0, v1, v0, s80
	v_lshrrev_b32_e32 v1, 2, v3
	v_or3_b32 v0, v0, v4, v5
	v_mad_u64_u32 v[22:23], s[22:23], v1, s61, v[2:3]
	ds_write_b32 v22, v0
	v_mov_b32_e32 v0, v224
	v_mov_b32_e32 v1, v225
	v_mov_b32_e32 v2, v226
	v_mov_b32_e32 v3, v227
	v_mov_b32_e32 v4, v240
	v_mov_b32_e32 v5, v241
	v_mov_b32_e32 v6, v242
	v_mov_b32_e32 v7, v243
	v_mov_b32_e32 v138, v210
	v_mov_b32_e32 v139, v211
	s_mov_b32 s22, s18
	s_mov_b32 s23, s19
	v_pk_add_f32 v[124:125], v[124:125], v[138:139] op_sel_hi:[1,0] neg_lo:[0,1] neg_hi:[0,1]
	s_nop 0
	v_pk_mul_f32 v[124:125], v[138:139], v[124:125] op_sel:[1,0]
	v_pk_add_f32 v[126:127], v[126:127], v[138:139] op_sel_hi:[1,0] neg_lo:[0,1] neg_hi:[0,1]
	v_mov_b32_e32 v128, v1
	v_mov_b32_e32 v129, v2
	v_mov_b32_e32 v130, v5
	v_mov_b32_e32 v131, v6
	v_pk_fma_f32 v[124:125], v[128:129], v[124:125], v[130:131]
	v_pk_mul_f32 v[126:127], v[138:139], v[126:127] op_sel:[1,0]
	v_mov_b32_e32 v1, v3
	v_mov_b32_e32 v5, v7
	v_and_b32_sdwa v23, v124, v216 dst_sel:DWORD dst_unused:UNUSED_PAD src0_sel:WORD_1 src1_sel:DWORD
	v_pk_fma_f32 v[6:7], v[0:1], v[126:127], v[4:5]
	v_add3_u32 v23, v124, v23, s78
	v_and_b32_e32 v137, 0xffff0000, v23
	v_and_b32_sdwa v23, v7, v216 dst_sel:DWORD dst_unused:UNUSED_PAD src0_sel:WORD_1 src1_sel:DWORD
	v_and_b32_sdwa v3, v125, v216 dst_sel:DWORD dst_unused:UNUSED_PAD src0_sel:WORD_1 src1_sel:DWORD
	v_and_b32_sdwa v126, v6, v216 dst_sel:DWORD dst_unused:UNUSED_PAD src0_sel:WORD_1 src1_sel:DWORD
	v_add3_u32 v23, v7, v23, s78
	v_or_b32_e32 v2, 32, v155
	v_add3_u32 v3, v125, v3, s78
	v_add3_u32 v138, v6, v126, s78
	v_and_b32_e32 v139, 0xffff0000, v23
	v_or_b32_sdwa v127, v139, v3 dst_sel:DWORD dst_unused:UNUSED_PAD src0_sel:DWORD src1_sel:WORD_1
	v_or_b32_sdwa v126, v138, v137 dst_sel:DWORD dst_unused:UNUSED_PAD src0_sel:WORD_1 src1_sel:DWORD
	v_add_u32_e32 v23, v2, v153
	ds_write_b64 v23, v[126:127]
	v_and_b32_e32 v126, 0xffff0000, v138
	v_sub_u32_e32 v124, v124, v137
	v_and_b32_e32 v3, 0xffff0000, v3
	v_sub_u32_e32 v6, v6, v126
	v_add_u32_e32 v124, 0x80, v124
	v_sub_u32_e32 v3, v125, v3
	v_sub_u32_e32 v7, v7, v139
	v_add_u32_e32 v6, 0x80, v6
	v_ashrrev_i32_e32 v124, 8, v124
	v_add_u32_e32 v3, 0x80, v3
	v_add_u32_e32 v7, 0x80, v7
	v_ashrrev_i32_e32 v6, 8, v6
	v_min_i32_e32 v124, 0x7f, v124
	v_ashrrev_i32_e32 v3, 8, v3
	v_ashrrev_i32_e32 v7, 8, v7
	v_min_i32_e32 v6, 0x7f, v6
	v_min_i32_sdwa v3, v3, s79 dst_sel:WORD_1 dst_unused:UNUSED_PAD src0_sel:DWORD src1_sel:DWORD
	v_min_i32_e32 v7, 0x7f, v7
	v_lshlrev_b32_e32 v124, 8, v124
	v_and_b32_e32 v124, 0xff00, v124
	v_and_b32_e32 v3, 0xff0000, v3
	v_perm_b32 v6, v7, v6, s80
	v_or3_b32 v3, v6, v124, v3
	ds_write_b32 v12, v3 offset:16
	v_mov_b32_e32 v6, v212
	v_mov_b32_e32 v7, v213
	v_pk_add_f32 v[106:107], v[106:107], v[6:7] op_sel_hi:[1,0] neg_lo:[0,1] neg_hi:[0,1]
	s_nop 0
	v_pk_mul_f32 v[106:107], v[6:7], v[106:107] op_sel:[1,0]
	v_pk_add_f32 v[104:105], v[104:105], v[6:7] op_sel_hi:[1,0] neg_lo:[0,1] neg_hi:[0,1]
	v_pk_fma_f32 v[106:107], v[128:129], v[106:107], v[130:131]
	v_pk_mul_f32 v[6:7], v[6:7], v[104:105] op_sel:[1,0]
	v_and_b32_sdwa v104, v106, v216 dst_sel:DWORD dst_unused:UNUSED_PAD src0_sel:WORD_1 src1_sel:DWORD
	v_pk_fma_f32 v[6:7], v[0:1], v[6:7], v[4:5]
	v_add3_u32 v104, v106, v104, s78
	v_and_b32_e32 v105, 0xffff0000, v104
	v_and_b32_sdwa v104, v7, v216 dst_sel:DWORD dst_unused:UNUSED_PAD src0_sel:WORD_1 src1_sel:DWORD
	v_and_b32_sdwa v3, v107, v216 dst_sel:DWORD dst_unused:UNUSED_PAD src0_sel:WORD_1 src1_sel:DWORD
	v_and_b32_sdwa v124, v6, v216 dst_sel:DWORD dst_unused:UNUSED_PAD src0_sel:WORD_1 src1_sel:DWORD
	v_add3_u32 v104, v7, v104, s78
	v_add3_u32 v3, v107, v3, s78
	v_add3_u32 v126, v6, v124, s78
	v_and_b32_e32 v127, 0xffff0000, v104
;     ...
;           _Pragma("unroll") for (int bj = 0; bj < 2; ++bj) _Pragma("unroll") for (int n = 0; n < 2; ++n) {
;             const int cc = bj * HALF + wc3 * 32 + n * 16 + fq3 * 4;
;             const float4 gm = *reinterpret_cast<const float4*>(g.gam + pn * BM + cc), bt = *reinterpret_cast<const float4*>(g.bet + pn * BM + cc);
;             _Pragma("unroll") for (int m = 0; m < 4; ++m) {
;               const int rr = wr3 * 64 + m * 16 + fr3;
;               const float2 ms = *reinterpret_cast<const float2*>(mr + (ai * HALF + rr) * 2);
;               f32x4 y = acc[ai][bj][m][n];
;               const float o0 = (y[0] - ms.x) * ms.y * gm.x + bt.x, o1 = (y[1] - ms.x) * ms.y * gm.y + bt.y;
;               const float o2 = (y[2] - ms.x) * ms.y * gm.z + bt.z, o3 = (y[3] - ms.x) * ms.y * gm.w + bt.w;
;               const unsigned h0 = f2bf(o0), h1 = f2bf(o1), h2 = f2bf(o2), h3 = f2bf(o3);
;               u32x2 ob; ob[0] = h0 | (h1 << 16); ob[1] = h2 | (h3 << 16);
;               *reinterpret_cast<u32x2*>(smem + (rr >> 1) * PIECE + (rr & 1) * 512 + cc * 2) = ob;
;               const int l0 = min(((int)__float_as_uint(o0) - (int)(h0 << 16) + 128) >> 8, 127);
;               const int l1 = min(((int)__float_as_uint(o1) - (int)(h1 << 16) + 128) >> 8, 127);
;               const int l2 = min(((int)__float_as_uint(o2) - (int)(h2 << 16) + 128) >> 8, 127);
;               const int l3 = min(((int)__float_as_uint(o3) - (int)(h3 << 16) + 128) >> 8, 127);
;               *reinterpret_cast<unsigned*>(smem + LOBASE + (rr >> 2) * PIECE + (rr & 3) * 256 + cc) =
;                   (unsigned)(l0 & 255) | ((unsigned)(l1 & 255) << 8) | ((unsigned)(l2 & 255) << 16) | ((unsigned)l3 << 24);
;             }
	v_or_b32_sdwa v125, v127, v3 dst_sel:DWORD dst_unused:UNUSED_PAD src0_sel:DWORD src1_sel:WORD_1
	v_or_b32_sdwa v124, v126, v105 dst_sel:DWORD dst_unused:UNUSED_PAD src0_sel:WORD_1 src1_sel:DWORD
	v_add_u32_e32 v104, v2, v154
	ds_write_b64 v104, v[124:125]
	v_and_b32_e32 v124, 0xffff0000, v126
	v_sub_u32_e32 v105, v106, v105
	v_and_b32_e32 v3, 0xffff0000, v3
	v_sub_u32_e32 v6, v6, v124
	v_add_u32_e32 v105, 0x80, v105
	v_sub_u32_e32 v3, v107, v3
	v_sub_u32_e32 v7, v7, v127
	v_add_u32_e32 v6, 0x80, v6
	v_ashrrev_i32_e32 v105, 8, v105
	v_add_u32_e32 v3, 0x80, v3
	v_add_u32_e32 v7, 0x80, v7
	v_ashrrev_i32_e32 v6, 8, v6
	v_min_i32_e32 v105, 0x7f, v105
	v_ashrrev_i32_e32 v3, 8, v3
	v_ashrrev_i32_e32 v7, 8, v7
	v_min_i32_e32 v6, 0x7f, v6
	v_min_i32_sdwa v3, v3, s79 dst_sel:WORD_1 dst_unused:UNUSED_PAD src0_sel:DWORD src1_sel:DWORD
	v_min_i32_e32 v7, 0x7f, v7
	v_lshlrev_b32_e32 v105, 8, v105
	v_and_b32_e32 v105, 0xff00, v105
	v_and_b32_e32 v3, 0xff0000, v3
	v_perm_b32 v6, v7, v6, s80
	v_or3_b32 v3, v6, v105, v3
	ds_write_b32 v14, v3 offset:16
	v_mov_b32_e32 v6, v214
	v_mov_b32_e32 v7, v215
	v_pk_add_f32 v[106:107], v[110:111], v[6:7] op_sel_hi:[1,0] neg_lo:[0,1] neg_hi:[0,1]
	s_nop 0
	v_pk_mul_f32 v[106:107], v[6:7], v[106:107] op_sel:[1,0]
	v_pk_add_f32 v[108:109], v[108:109], v[6:7] op_sel_hi:[1,0] neg_lo:[0,1] neg_hi:[0,1]
	v_pk_fma_f32 v[106:107], v[128:129], v[106:107], v[130:131]
	v_pk_mul_f32 v[6:7], v[6:7], v[108:109] op_sel:[1,0]
	v_and_b32_sdwa v105, v106, v216 dst_sel:DWORD dst_unused:UNUSED_PAD src0_sel:WORD_1 src1_sel:DWORD
	v_pk_fma_f32 v[6:7], v[0:1], v[6:7], v[4:5]
	v_add3_u32 v105, v106, v105, s78
	v_and_b32_e32 v110, 0xffff0000, v105
	v_and_b32_sdwa v105, v7, v216 dst_sel:DWORD dst_unused:UNUSED_PAD src0_sel:WORD_1 src1_sel:DWORD
	v_and_b32_sdwa v3, v107, v216 dst_sel:DWORD dst_unused:UNUSED_PAD src0_sel:WORD_1 src1_sel:DWORD
	v_and_b32_sdwa v108, v6, v216 dst_sel:DWORD dst_unused:UNUSED_PAD src0_sel:WORD_1 src1_sel:DWORD
	v_add3_u32 v105, v7, v105, s78
	v_add3_u32 v3, v107, v3, s78
	v_add3_u32 v111, v6, v108, s78
	v_and_b32_e32 v124, 0xffff0000, v105
	v_or_b32_sdwa v109, v124, v3 dst_sel:DWORD dst_unused:UNUSED_PAD src0_sel:DWORD src1_sel:WORD_1
	v_or_b32_sdwa v108, v111, v110 dst_sel:DWORD dst_unused:UNUSED_PAD src0_sel:WORD_1 src1_sel:DWORD
	v_add_u32_e32 v105, v2, v136
	ds_write_b64 v105, v[108:109]
	v_and_b32_e32 v108, 0xffff0000, v111
	v_sub_u32_e32 v106, v106, v110
	v_and_b32_e32 v3, 0xffff0000, v3
	v_sub_u32_e32 v6, v6, v108
	v_add_u32_e32 v106, 0x80, v106
	v_sub_u32_e32 v3, v107, v3
	v_sub_u32_e32 v7, v7, v124
	v_add_u32_e32 v6, 0x80, v6
	v_ashrrev_i32_e32 v106, 8, v106
	v_add_u32_e32 v3, 0x80, v3
	v_add_u32_e32 v7, 0x80, v7
	v_ashrrev_i32_e32 v6, 8, v6
	v_min_i32_e32 v106, 0x7f, v106
	v_ashrrev_i32_e32 v3, 8, v3
	v_ashrrev_i32_e32 v7, 8, v7
	v_min_i32_e32 v6, 0x7f, v6
	v_min_i32_sdwa v3, v3, s79 dst_sel:WORD_1 dst_unused:UNUSED_PAD src0_sel:DWORD src1_sel:DWORD
	v_min_i32_e32 v7, 0x7f, v7
	v_lshlrev_b32_e32 v106, 8, v106
	v_and_b32_e32 v106, 0xff00, v106
	v_and_b32_e32 v3, 0xff0000, v3
	v_perm_b32 v6, v7, v6, s80
	v_or3_b32 v3, v6, v106, v3
	ds_write_b32 v20, v3 offset:16
	v_mov_b32_e32 v6, v252
	v_mov_b32_e32 v7, v253
	v_pk_add_f32 v[106:107], v[122:123], v[6:7] op_sel_hi:[1,0] neg_lo:[0,1] neg_hi:[0,1]
	s_nop 0
	v_pk_mul_f32 v[106:107], v[6:7], v[106:107] op_sel:[1,0]
	v_or_b32_e32 v122, 0x100, v155
	v_pk_fma_f32 v[108:109], v[128:129], v[106:107], v[130:131]
	v_pk_add_f32 v[106:107], v[114:115], v[6:7] op_sel_hi:[1,0] neg_lo:[0,1] neg_hi:[0,1]
	v_and_b32_sdwa v3, v109, v216 dst_sel:DWORD dst_unused:UNUSED_PAD src0_sel:WORD_1 src1_sel:DWORD
	v_pk_mul_f32 v[6:7], v[6:7], v[106:107] op_sel:[1,0]
	v_add3_u32 v3, v109, v3, s78
	v_pk_fma_f32 v[0:1], v[0:1], v[6:7], v[4:5]
	v_and_b32_sdwa v4, v108, v216 dst_sel:DWORD dst_unused:UNUSED_PAD src0_sel:WORD_1 src1_sel:DWORD
	v_add3_u32 v4, v108, v4, s78
	v_and_b32_e32 v6, 0xffff0000, v4
	v_and_b32_sdwa v4, v1, v216 dst_sel:DWORD dst_unused:UNUSED_PAD src0_sel:WORD_1 src1_sel:DWORD
	v_and_b32_sdwa v5, v0, v216 dst_sel:DWORD dst_unused:UNUSED_PAD src0_sel:WORD_1 src1_sel:DWORD
	v_add3_u32 v4, v1, v4, s78
	v_add3_u32 v7, v0, v5, s78
	v_and_b32_e32 v107, 0xffff0000, v4
	v_add_u32_e32 v106, v2, v135
	v_and_b32_e32 v2, 0xffff0000, v7
	v_or_b32_sdwa v5, v107, v3 dst_sel:DWORD dst_unused:UNUSED_PAD src0_sel:DWORD src1_sel:WORD_1
	v_sub_u32_e32 v0, v0, v2
	v_sub_u32_e32 v2, v108, v6
	v_and_b32_e32 v3, 0xffff0000, v3
	v_add_u32_e32 v2, 0x80, v2
	v_sub_u32_e32 v3, v109, v3
	v_sub_u32_e32 v1, v1, v107
	v_add_u32_e32 v0, 0x80, v0
	v_ashrrev_i32_e32 v2, 8, v2
	v_add_u32_e32 v3, 0x80, v3
	v_add_u32_e32 v1, 0x80, v1
	v_ashrrev_i32_e32 v0, 8, v0
	v_min_i32_e32 v2, 0x7f, v2
	v_ashrrev_i32_e32 v3, 8, v3
	v_ashrrev_i32_e32 v1, 8, v1
	v_min_i32_e32 v0, 0x7f, v0
	v_min_i32_sdwa v3, v3, s79 dst_sel:WORD_1 dst_unused:UNUSED_PAD src0_sel:DWORD src1_sel:DWORD
	v_min_i32_e32 v1, 0x7f, v1
	v_lshlrev_b32_e32 v2, 8, v2
	v_and_b32_e32 v2, 0xff00, v2
	v_and_b32_e32 v3, 0xff0000, v3
	v_perm_b32 v0, v1, v0, s80
	v_or_b32_sdwa v4, v7, v6 dst_sel:DWORD dst_unused:UNUSED_PAD src0_sel:WORD_1 src1_sel:DWORD
	v_or3_b32 v0, v0, v2, v3
	ds_write_b64 v106, v[4:5]
	ds_write_b32 v22, v0 offset:16
	v_mov_b32_e32 v0, v228
	v_mov_b32_e32 v1, v229
	v_mov_b32_e32 v2, v230
	v_mov_b32_e32 v3, v231
	v_mov_b32_e32 v4, v244
	v_mov_b32_e32 v5, v245
	v_mov_b32_e32 v6, v246
	v_mov_b32_e32 v7, v247
	v_mov_b32_e32 v114, v210
	v_mov_b32_e32 v115, v211
	v_add_u32_e32 v107, v122, v153
	v_pk_add_f32 v[118:119], v[118:119], v[114:115] op_sel_hi:[1,0] neg_lo:[0,1] neg_hi:[0,1]
	s_nop 0
	v_pk_mul_f32 v[118:119], v[114:115], v[118:119] op_sel:[1,0]
;     ...
;           _Pragma("unroll") for (int bj = 0; bj < 2; ++bj) _Pragma("unroll") for (int n = 0; n < 2; ++n) {
;             const int cc = bj * HALF + wc3 * 32 + n * 16 + fq3 * 4;
;             const float4 gm = *reinterpret_cast<const float4*>(g.gam + pn * BM + cc), bt = *reinterpret_cast<const float4*>(g.bet + pn * BM + cc);
;             _Pragma("unroll") for (int m = 0; m < 4; ++m) {
;               const int rr = wr3 * 64 + m * 16 + fr3;
;               const float2 ms = *reinterpret_cast<const float2*>(mr + (ai * HALF + rr) * 2);
;               f32x4 y = acc[ai][bj][m][n];
;               const float o0 = (y[0] - ms.x) * ms.y * gm.x + bt.x, o1 = (y[1] - ms.x) * ms.y * gm.y + bt.y;
;               const float o2 = (y[2] - ms.x) * ms.y * gm.z + bt.z, o3 = (y[3] - ms.x) * ms.y * gm.w + bt.w;
;               const unsigned h0 = f2bf(o0), h1 = f2bf(o1), h2 = f2bf(o2), h3 = f2bf(o3);
;               u32x2 ob; ob[0] = h0 | (h1 << 16); ob[1] = h2 | (h3 << 16);
;               *reinterpret_cast<u32x2*>(smem + (rr >> 1) * PIECE + (rr & 1) * 512 + cc * 2) = ob;
;               const int l0 = min(((int)__float_as_uint(o0) - (int)(h0 << 16) + 128) >> 8, 127);
;               const int l1 = min(((int)__float_as_uint(o1) - (int)(h1 << 16) + 128) >> 8, 127);
;               const int l2 = min(((int)__float_as_uint(o2) - (int)(h2 << 16) + 128) >> 8, 127);
;               const int l3 = min(((int)__float_as_uint(o3) - (int)(h3 << 16) + 128) >> 8, 127);
;               *reinterpret_cast<unsigned*>(smem + LOBASE + (rr >> 2) * PIECE + (rr & 3) * 256 + cc) =
;                   (unsigned)(l0 & 255) | ((unsigned)(l1 & 255) << 8) | ((unsigned)(l2 & 255) << 16) | ((unsigned)l3 << 24);
;             }
	v_pk_add_f32 v[120:121], v[120:121], v[114:115] op_sel_hi:[1,0] neg_lo:[0,1] neg_hi:[0,1]
	v_mov_b32_e32 v108, v1
	v_mov_b32_e32 v109, v2
	v_mov_b32_e32 v110, v5
	v_mov_b32_e32 v111, v6
	v_pk_fma_f32 v[118:119], v[108:109], v[118:119], v[110:111]
	v_pk_mul_f32 v[114:115], v[114:115], v[120:121] op_sel:[1,0]
	v_mov_b32_e32 v1, v3
	v_mov_b32_e32 v5, v7
	v_and_b32_sdwa v6, v119, v216 dst_sel:DWORD dst_unused:UNUSED_PAD src0_sel:WORD_1 src1_sel:DWORD
	v_and_b32_sdwa v7, v118, v216 dst_sel:DWORD dst_unused:UNUSED_PAD src0_sel:WORD_1 src1_sel:DWORD
	v_pk_fma_f32 v[2:3], v[0:1], v[114:115], v[4:5]
	v_add3_u32 v114, v119, v6, s78
	v_add3_u32 v6, v118, v7, s78
	v_and_b32_e32 v115, 0xffff0000, v6
	v_and_b32_sdwa v6, v3, v216 dst_sel:DWORD dst_unused:UNUSED_PAD src0_sel:WORD_1 src1_sel:DWORD
	v_and_b32_sdwa v7, v2, v216 dst_sel:DWORD dst_unused:UNUSED_PAD src0_sel:WORD_1 src1_sel:DWORD
	v_add3_u32 v6, v3, v6, s78
	v_add3_u32 v120, v2, v7, s78
	v_and_b32_e32 v121, 0xffff0000, v6
	v_or_b32_sdwa v7, v121, v114 dst_sel:DWORD dst_unused:UNUSED_PAD src0_sel:DWORD src1_sel:WORD_1
	v_or_b32_sdwa v6, v120, v115 dst_sel:DWORD dst_unused:UNUSED_PAD src0_sel:WORD_1 src1_sel:DWORD
	ds_write_b64 v107, v[6:7]
	v_and_b32_e32 v6, 0xffff0000, v120
	v_sub_u32_e32 v2, v2, v6
	v_sub_u32_e32 v6, v118, v115
	v_and_b32_e32 v7, 0xffff0000, v114
	v_add_u32_e32 v6, 0x80, v6
	v_sub_u32_e32 v7, v119, v7
	v_sub_u32_e32 v3, v3, v121
	v_add_u32_e32 v2, 0x80, v2
	v_ashrrev_i32_e32 v6, 8, v6
	v_add_u32_e32 v7, 0x80, v7
	v_add_u32_e32 v3, 0x80, v3
	v_ashrrev_i32_e32 v2, 8, v2
	v_min_i32_e32 v6, 0x7f, v6
	v_ashrrev_i32_e32 v7, 8, v7
	v_ashrrev_i32_e32 v3, 8, v3
	v_min_i32_e32 v2, 0x7f, v2
	v_min_i32_sdwa v7, v7, s79 dst_sel:WORD_1 dst_unused:UNUSED_PAD src0_sel:DWORD src1_sel:DWORD
	v_min_i32_e32 v3, 0x7f, v3
	v_lshlrev_b32_e32 v6, 8, v6
	v_and_b32_e32 v6, 0xff00, v6
	v_and_b32_e32 v7, 0xff0000, v7
	v_perm_b32 v2, v3, v2, s80
	v_or3_b32 v2, v2, v6, v7
	ds_write_b32 v12, v2 offset:128
	v_mov_b32_e32 v2, v212
	v_mov_b32_e32 v3, v213
	v_pk_add_f32 v[6:7], v[102:103], v[2:3] op_sel_hi:[1,0] neg_lo:[0,1] neg_hi:[0,1]
	s_nop 0
	v_pk_mul_f32 v[6:7], v[2:3], v[6:7] op_sel:[1,0]
	v_pk_add_f32 v[100:101], v[100:101], v[2:3] op_sel_hi:[1,0] neg_lo:[0,1] neg_hi:[0,1]
	v_pk_fma_f32 v[6:7], v[108:109], v[6:7], v[110:111]
	v_pk_mul_f32 v[2:3], v[2:3], v[100:101] op_sel:[1,0]
	v_and_b32_sdwa v100, v7, v216 dst_sel:DWORD dst_unused:UNUSED_PAD src0_sel:WORD_1 src1_sel:DWORD
	v_and_b32_sdwa v101, v6, v216 dst_sel:DWORD dst_unused:UNUSED_PAD src0_sel:WORD_1 src1_sel:DWORD
	v_pk_fma_f32 v[2:3], v[0:1], v[2:3], v[4:5]
	v_add3_u32 v114, v7, v100, s78
	v_add3_u32 v100, v6, v101, s78
	v_and_b32_e32 v101, 0xffff0000, v100
	v_and_b32_sdwa v100, v3, v216 dst_sel:DWORD dst_unused:UNUSED_PAD src0_sel:WORD_1 src1_sel:DWORD
	v_and_b32_sdwa v102, v2, v216 dst_sel:DWORD dst_unused:UNUSED_PAD src0_sel:WORD_1 src1_sel:DWORD
	v_add3_u32 v100, v3, v100, s78
	v_add3_u32 v115, v2, v102, s78
	v_and_b32_e32 v118, 0xffff0000, v100
	v_or_b32_sdwa v103, v118, v114 dst_sel:DWORD dst_unused:UNUSED_PAD src0_sel:DWORD src1_sel:WORD_1
	v_or_b32_sdwa v102, v115, v101 dst_sel:DWORD dst_unused:UNUSED_PAD src0_sel:WORD_1 src1_sel:DWORD
	v_add_u32_e32 v100, v122, v154
	ds_write_b64 v100, v[102:103]
	v_and_b32_e32 v102, 0xffff0000, v115
	v_sub_u32_e32 v6, v6, v101
	v_and_b32_e32 v101, 0xffff0000, v114
	v_sub_u32_e32 v2, v2, v102
	v_add_u32_e32 v6, 0x80, v6
	v_sub_u32_e32 v7, v7, v101
	v_sub_u32_e32 v3, v3, v118
	v_add_u32_e32 v2, 0x80, v2
	v_ashrrev_i32_e32 v6, 8, v6
	v_add_u32_e32 v7, 0x80, v7
	v_add_u32_e32 v3, 0x80, v3
	v_ashrrev_i32_e32 v2, 8, v2
	v_min_i32_e32 v6, 0x7f, v6
	v_ashrrev_i32_e32 v7, 8, v7
	v_ashrrev_i32_e32 v3, 8, v3
	v_min_i32_e32 v2, 0x7f, v2
	v_min_i32_sdwa v7, v7, s79 dst_sel:WORD_1 dst_unused:UNUSED_PAD src0_sel:DWORD src1_sel:DWORD
	v_min_i32_e32 v3, 0x7f, v3
	v_lshlrev_b32_e32 v6, 8, v6
	v_and_b32_e32 v6, 0xff00, v6
	v_and_b32_e32 v7, 0xff0000, v7
	v_perm_b32 v2, v3, v2, s80
	v_or3_b32 v2, v2, v6, v7
	ds_write_b32 v14, v2 offset:128
	v_mov_b32_e32 v2, v214
	v_mov_b32_e32 v3, v215
	v_add_u32_e32 v101, v122, v136
	v_pk_add_f32 v[6:7], v[90:91], v[2:3] op_sel_hi:[1,0] neg_lo:[0,1] neg_hi:[0,1]
	s_nop 0
	v_pk_mul_f32 v[6:7], v[2:3], v[6:7] op_sel:[1,0]
	v_pk_add_f32 v[88:89], v[88:89], v[2:3] op_sel_hi:[1,0] neg_lo:[0,1] neg_hi:[0,1]
	v_pk_fma_f32 v[6:7], v[108:109], v[6:7], v[110:111]
	v_pk_mul_f32 v[2:3], v[2:3], v[88:89] op_sel:[1,0]
	v_and_b32_sdwa v88, v7, v216 dst_sel:DWORD dst_unused:UNUSED_PAD src0_sel:WORD_1 src1_sel:DWORD
	v_and_b32_sdwa v89, v6, v216 dst_sel:DWORD dst_unused:UNUSED_PAD src0_sel:WORD_1 src1_sel:DWORD
	v_pk_fma_f32 v[2:3], v[0:1], v[2:3], v[4:5]
	v_add3_u32 v90, v7, v88, s78
	v_add3_u32 v88, v6, v89, s78
	v_and_b32_e32 v91, 0xffff0000, v88
	v_and_b32_sdwa v88, v3, v216 dst_sel:DWORD dst_unused:UNUSED_PAD src0_sel:WORD_1 src1_sel:DWORD
	v_and_b32_sdwa v89, v2, v216 dst_sel:DWORD dst_unused:UNUSED_PAD src0_sel:WORD_1 src1_sel:DWORD
	v_add3_u32 v88, v3, v88, s78
	v_add3_u32 v102, v2, v89, s78
	v_and_b32_e32 v103, 0xffff0000, v88
	v_or_b32_sdwa v89, v103, v90 dst_sel:DWORD dst_unused:UNUSED_PAD src0_sel:DWORD src1_sel:WORD_1
	v_or_b32_sdwa v88, v102, v91 dst_sel:DWORD dst_unused:UNUSED_PAD src0_sel:WORD_1 src1_sel:DWORD
	ds_write_b64 v101, v[88:89]
	v_and_b32_e32 v88, 0xffff0000, v102
	v_sub_u32_e32 v2, v2, v88
	v_sub_u32_e32 v6, v6, v91
	v_and_b32_e32 v88, 0xffff0000, v90
	v_add_u32_e32 v6, 0x80, v6
	v_sub_u32_e32 v7, v7, v88
	v_sub_u32_e32 v3, v3, v103
	v_add_u32_e32 v2, 0x80, v2
	v_ashrrev_i32_e32 v6, 8, v6
	v_add_u32_e32 v7, 0x80, v7
	v_add_u32_e32 v3, 0x80, v3
	v_ashrrev_i32_e32 v2, 8, v2
;     ...
;           _Pragma("unroll") for (int bj = 0; bj < 2; ++bj) _Pragma("unroll") for (int n = 0; n < 2; ++n) {
;             const int cc = bj * HALF + wc3 * 32 + n * 16 + fq3 * 4;
;             const float4 gm = *reinterpret_cast<const float4*>(g.gam + pn * BM + cc), bt = *reinterpret_cast<const float4*>(g.bet + pn * BM + cc);
;             _Pragma("unroll") for (int m = 0; m < 4; ++m) {
;               const int rr = wr3 * 64 + m * 16 + fr3;
;               const float2 ms = *reinterpret_cast<const float2*>(mr + (ai * HALF + rr) * 2);
;               f32x4 y = acc[ai][bj][m][n];
;               const float o0 = (y[0] - ms.x) * ms.y * gm.x + bt.x, o1 = (y[1] - ms.x) * ms.y * gm.y + bt.y;
;               const float o2 = (y[2] - ms.x) * ms.y * gm.z + bt.z, o3 = (y[3] - ms.x) * ms.y * gm.w + bt.w;
;               const unsigned h0 = f2bf(o0), h1 = f2bf(o1), h2 = f2bf(o2), h3 = f2bf(o3);
;               u32x2 ob; ob[0] = h0 | (h1 << 16); ob[1] = h2 | (h3 << 16);
;               *reinterpret_cast<u32x2*>(smem + (rr >> 1) * PIECE + (rr & 1) * 512 + cc * 2) = ob;
;               const int l0 = min(((int)__float_as_uint(o0) - (int)(h0 << 16) + 128) >> 8, 127);
;               const int l1 = min(((int)__float_as_uint(o1) - (int)(h1 << 16) + 128) >> 8, 127);
;               const int l2 = min(((int)__float_as_uint(o2) - (int)(h2 << 16) + 128) >> 8, 127);
;               const int l3 = min(((int)__float_as_uint(o3) - (int)(h3 << 16) + 128) >> 8, 127);
;               *reinterpret_cast<unsigned*>(smem + LOBASE + (rr >> 2) * PIECE + (rr & 3) * 256 + cc) =
;                   (unsigned)(l0 & 255) | ((unsigned)(l1 & 255) << 8) | ((unsigned)(l2 & 255) << 16) | ((unsigned)l3 << 24);
;             }
	v_min_i32_e32 v6, 0x7f, v6
	v_ashrrev_i32_e32 v7, 8, v7
	v_ashrrev_i32_e32 v3, 8, v3
	v_min_i32_e32 v2, 0x7f, v2
	v_min_i32_sdwa v7, v7, s79 dst_sel:WORD_1 dst_unused:UNUSED_PAD src0_sel:DWORD src1_sel:DWORD
	v_min_i32_e32 v3, 0x7f, v3
	v_lshlrev_b32_e32 v6, 8, v6
	v_and_b32_e32 v6, 0xff00, v6
	v_and_b32_e32 v7, 0xff0000, v7
	v_perm_b32 v2, v3, v2, s80
	v_or3_b32 v2, v2, v6, v7
	ds_write_b32 v20, v2 offset:128
	v_mov_b32_e32 v2, v252
	v_mov_b32_e32 v3, v253
	v_pk_add_f32 v[6:7], v[94:95], v[2:3] op_sel_hi:[1,0] neg_lo:[0,1] neg_hi:[0,1]
	s_nop 0
	v_pk_mul_f32 v[6:7], v[2:3], v[6:7] op_sel:[1,0]
	v_pk_add_f32 v[88:89], v[92:93], v[2:3] op_sel_hi:[1,0] neg_lo:[0,1] neg_hi:[0,1]
	v_pk_fma_f32 v[6:7], v[108:109], v[6:7], v[110:111]
	v_pk_mul_f32 v[2:3], v[2:3], v[88:89] op_sel:[1,0]
	v_add_u32_e32 v92, v122, v135
	v_pk_fma_f32 v[0:1], v[0:1], v[2:3], v[4:5]
	v_and_b32_sdwa v2, v7, v216 dst_sel:DWORD dst_unused:UNUSED_PAD src0_sel:WORD_1 src1_sel:DWORD
	v_and_b32_sdwa v3, v6, v216 dst_sel:DWORD dst_unused:UNUSED_PAD src0_sel:WORD_1 src1_sel:DWORD
	v_add3_u32 v4, v7, v2, s78
	v_add3_u32 v2, v6, v3, s78
	v_and_b32_e32 v5, 0xffff0000, v2
	v_and_b32_sdwa v2, v1, v216 dst_sel:DWORD dst_unused:UNUSED_PAD src0_sel:WORD_1 src1_sel:DWORD
	v_and_b32_sdwa v3, v0, v216 dst_sel:DWORD dst_unused:UNUSED_PAD src0_sel:WORD_1 src1_sel:DWORD
	v_add3_u32 v2, v1, v2, s78
	v_add3_u32 v88, v0, v3, s78
	v_and_b32_e32 v89, 0xffff0000, v2
	v_or_b32_sdwa v3, v89, v4 dst_sel:DWORD dst_unused:UNUSED_PAD src0_sel:DWORD src1_sel:WORD_1
	v_or_b32_sdwa v2, v88, v5 dst_sel:DWORD dst_unused:UNUSED_PAD src0_sel:WORD_1 src1_sel:DWORD
	ds_write_b64 v92, v[2:3]
	v_and_b32_e32 v2, 0xffff0000, v88
	v_sub_u32_e32 v0, v0, v2
	v_sub_u32_e32 v2, v6, v5
	v_and_b32_e32 v3, 0xffff0000, v4
	v_add_u32_e32 v2, 0x80, v2
	v_sub_u32_e32 v3, v7, v3
	v_sub_u32_e32 v1, v1, v89
	v_add_u32_e32 v0, 0x80, v0
	v_ashrrev_i32_e32 v2, 8, v2
	v_add_u32_e32 v3, 0x80, v3
	v_add_u32_e32 v1, 0x80, v1
	v_ashrrev_i32_e32 v0, 8, v0
	v_min_i32_e32 v2, 0x7f, v2
	v_ashrrev_i32_e32 v3, 8, v3
	v_ashrrev_i32_e32 v1, 8, v1
	v_min_i32_e32 v0, 0x7f, v0
	v_min_i32_sdwa v3, v3, s79 dst_sel:WORD_1 dst_unused:UNUSED_PAD src0_sel:DWORD src1_sel:DWORD
	v_min_i32_e32 v1, 0x7f, v1
	v_lshlrev_b32_e32 v2, 8, v2
	v_and_b32_e32 v2, 0xff00, v2
	v_and_b32_e32 v3, 0xff0000, v3
	v_perm_b32 v0, v1, v0, s80
	v_or3_b32 v0, v0, v2, v3
	ds_write_b32 v22, v0 offset:128
	v_mov_b32_e32 v0, v232
	v_mov_b32_e32 v1, v233
	v_mov_b32_e32 v2, v234
	v_mov_b32_e32 v3, v235
	v_mov_b32_e32 v4, v248
	v_mov_b32_e32 v5, v249
	v_mov_b32_e32 v6, v250
	v_mov_b32_e32 v7, v251
	v_mov_b32_e32 v94, v210
	v_mov_b32_e32 v95, v211
	v_pk_add_f32 v[102:103], v[116:117], v[94:95] op_sel_hi:[1,0] neg_lo:[0,1] neg_hi:[0,1]
	s_nop 0
	v_pk_mul_f32 v[102:103], v[94:95], v[102:103] op_sel:[1,0]
	v_pk_add_f32 v[108:109], v[112:113], v[94:95] op_sel_hi:[1,0] neg_lo:[0,1] neg_hi:[0,1]
	v_mov_b32_e32 v88, v1
	v_mov_b32_e32 v89, v2
	v_mov_b32_e32 v90, v5
	v_mov_b32_e32 v91, v6
	v_pk_fma_f32 v[102:103], v[88:89], v[102:103], v[90:91]
	v_pk_mul_f32 v[94:95], v[94:95], v[108:109] op_sel:[1,0]
	v_mov_b32_e32 v1, v3
	v_mov_b32_e32 v5, v7
	v_and_b32_sdwa v93, v102, v216 dst_sel:DWORD dst_unused:UNUSED_PAD src0_sel:WORD_1 src1_sel:DWORD
	v_pk_fma_f32 v[6:7], v[0:1], v[94:95], v[4:5]
	v_add3_u32 v93, v102, v93, s78
	v_and_b32_e32 v108, 0xffff0000, v93
	v_and_b32_sdwa v93, v7, v216 dst_sel:DWORD dst_unused:UNUSED_PAD src0_sel:WORD_1 src1_sel:DWORD
	v_and_b32_sdwa v3, v103, v216 dst_sel:DWORD dst_unused:UNUSED_PAD src0_sel:WORD_1 src1_sel:DWORD
	v_and_b32_sdwa v94, v6, v216 dst_sel:DWORD dst_unused:UNUSED_PAD src0_sel:WORD_1 src1_sel:DWORD
	v_add3_u32 v93, v7, v93, s78
	v_or_b32_e32 v2, 0x120, v155
	v_add3_u32 v3, v103, v3, s78
	v_add3_u32 v109, v6, v94, s78
	v_and_b32_e32 v110, 0xffff0000, v93
	v_or_b32_sdwa v95, v110, v3 dst_sel:DWORD dst_unused:UNUSED_PAD src0_sel:DWORD src1_sel:WORD_1
	v_or_b32_sdwa v94, v109, v108 dst_sel:DWORD dst_unused:UNUSED_PAD src0_sel:WORD_1 src1_sel:DWORD
	v_add_u32_e32 v93, v2, v153
	ds_write_b64 v93, v[94:95]
	v_and_b32_e32 v94, 0xffff0000, v109
	v_sub_u32_e32 v6, v6, v94
	v_sub_u32_e32 v94, v102, v108
	v_and_b32_e32 v3, 0xffff0000, v3
	v_add_u32_e32 v94, 0x80, v94
	v_sub_u32_e32 v3, v103, v3
	v_sub_u32_e32 v7, v7, v110
	v_add_u32_e32 v6, 0x80, v6
	v_ashrrev_i32_e32 v94, 8, v94
	v_add_u32_e32 v3, 0x80, v3
	v_add_u32_e32 v7, 0x80, v7
	v_ashrrev_i32_e32 v6, 8, v6
	v_min_i32_e32 v94, 0x7f, v94
	v_ashrrev_i32_e32 v3, 8, v3
	v_ashrrev_i32_e32 v7, 8, v7
	v_min_i32_e32 v6, 0x7f, v6
	v_min_i32_sdwa v3, v3, s79 dst_sel:WORD_1 dst_unused:UNUSED_PAD src0_sel:DWORD src1_sel:DWORD
	v_min_i32_e32 v7, 0x7f, v7
	v_lshlrev_b32_e32 v94, 8, v94
	v_and_b32_e32 v94, 0xff00, v94
	v_and_b32_e32 v3, 0xff0000, v3
	v_perm_b32 v6, v7, v6, s80
	v_or3_b32 v3, v6, v94, v3
	ds_write_b32 v12, v3 offset:144
	v_mov_b32_e32 v6, v212
	v_mov_b32_e32 v7, v213
	v_pk_add_f32 v[94:95], v[98:99], v[6:7] op_sel_hi:[1,0] neg_lo:[0,1] neg_hi:[0,1]
	s_nop 0
	v_pk_mul_f32 v[94:95], v[6:7], v[94:95] op_sel:[1,0]
	s_nop 0
	v_pk_fma_f32 v[98:99], v[88:89], v[94:95], v[90:91]
	v_pk_add_f32 v[94:95], v[96:97], v[6:7] op_sel_hi:[1,0] neg_lo:[0,1] neg_hi:[0,1]
	v_and_b32_sdwa v3, v99, v216 dst_sel:DWORD dst_unused:UNUSED_PAD src0_sel:WORD_1 src1_sel:DWORD
	v_pk_mul_f32 v[6:7], v[6:7], v[94:95] op_sel:[1,0]
	v_and_b32_sdwa v94, v98, v216 dst_sel:DWORD dst_unused:UNUSED_PAD src0_sel:WORD_1 src1_sel:DWORD
	v_pk_fma_f32 v[6:7], v[0:1], v[6:7], v[4:5]
	v_add3_u32 v94, v98, v94, s78
	v_and_b32_e32 v95, 0xffff0000, v94
	v_and_b32_sdwa v94, v7, v216 dst_sel:DWORD dst_unused:UNUSED_PAD src0_sel:WORD_1 src1_sel:DWORD
; #define WAIT_L(n) asm volatile("s_waitcnt lgkmcnt(" #n ")" ::: "memory")
; #define BAR __builtin_amdgcn_s_barrier()
;     ...
;           _Pragma("unroll") for (int bj = 0; bj < 2; ++bj) _Pragma("unroll") for (int n = 0; n < 2; ++n) {
;             const int cc = bj * HALF + wc3 * 32 + n * 16 + fq3 * 4;
;             const float4 gm = *reinterpret_cast<const float4*>(g.gam + pn * BM + cc), bt = *reinterpret_cast<const float4*>(g.bet + pn * BM + cc);
;             _Pragma("unroll") for (int m = 0; m < 4; ++m) {
;               const int rr = wr3 * 64 + m * 16 + fr3;
;               const float2 ms = *reinterpret_cast<const float2*>(mr + (ai * HALF + rr) * 2);
;               f32x4 y = acc[ai][bj][m][n];
;               const float o0 = (y[0] - ms.x) * ms.y * gm.x + bt.x, o1 = (y[1] - ms.x) * ms.y * gm.y + bt.y;
;               const float o2 = (y[2] - ms.x) * ms.y * gm.z + bt.z, o3 = (y[3] - ms.x) * ms.y * gm.w + bt.w;
;               const unsigned h0 = f2bf(o0), h1 = f2bf(o1), h2 = f2bf(o2), h3 = f2bf(o3);
;               u32x2 ob; ob[0] = h0 | (h1 << 16); ob[1] = h2 | (h3 << 16);
;               *reinterpret_cast<u32x2*>(smem + (rr >> 1) * PIECE + (rr & 1) * 512 + cc * 2) = ob;
;               const int l0 = min(((int)__float_as_uint(o0) - (int)(h0 << 16) + 128) >> 8, 127);
;               const int l1 = min(((int)__float_as_uint(o1) - (int)(h1 << 16) + 128) >> 8, 127);
;               const int l2 = min(((int)__float_as_uint(o2) - (int)(h2 << 16) + 128) >> 8, 127);
;               const int l3 = min(((int)__float_as_uint(o3) - (int)(h3 << 16) + 128) >> 8, 127);
;               *reinterpret_cast<unsigned*>(smem + LOBASE + (rr >> 2) * PIECE + (rr & 3) * 256 + cc) =
;                   (unsigned)(l0 & 255) | ((unsigned)(l1 & 255) << 8) | ((unsigned)(l2 & 255) << 16) | ((unsigned)l3 << 24);
;             }
;           }
;           WAIT_L(0); BAR;
	v_and_b32_sdwa v96, v6, v216 dst_sel:DWORD dst_unused:UNUSED_PAD src0_sel:WORD_1 src1_sel:DWORD
	v_add3_u32 v94, v7, v94, s78
	v_add3_u32 v3, v99, v3, s78
	v_add3_u32 v102, v6, v96, s78
	v_and_b32_e32 v103, 0xffff0000, v94
	v_or_b32_sdwa v97, v103, v3 dst_sel:DWORD dst_unused:UNUSED_PAD src0_sel:DWORD src1_sel:WORD_1
	v_or_b32_sdwa v96, v102, v95 dst_sel:DWORD dst_unused:UNUSED_PAD src0_sel:WORD_1 src1_sel:DWORD
	v_add_u32_e32 v94, v2, v154
	ds_write_b64 v94, v[96:97]
	v_and_b32_e32 v96, 0xffff0000, v102
	v_sub_u32_e32 v95, v98, v95
	v_and_b32_e32 v3, 0xffff0000, v3
	v_sub_u32_e32 v6, v6, v96
	v_add_u32_e32 v95, 0x80, v95
	v_sub_u32_e32 v3, v99, v3
	v_sub_u32_e32 v7, v7, v103
	v_add_u32_e32 v6, 0x80, v6
	v_ashrrev_i32_e32 v95, 8, v95
	v_add_u32_e32 v3, 0x80, v3
	v_add_u32_e32 v7, 0x80, v7
	v_ashrrev_i32_e32 v6, 8, v6
	v_min_i32_e32 v95, 0x7f, v95
	v_ashrrev_i32_e32 v3, 8, v3
	v_ashrrev_i32_e32 v7, 8, v7
	v_min_i32_e32 v6, 0x7f, v6
	v_min_i32_sdwa v3, v3, s79 dst_sel:WORD_1 dst_unused:UNUSED_PAD src0_sel:DWORD src1_sel:DWORD
	v_min_i32_e32 v7, 0x7f, v7
	v_lshlrev_b32_e32 v95, 8, v95
	v_and_b32_e32 v95, 0xff00, v95
	v_and_b32_e32 v3, 0xff0000, v3
	v_perm_b32 v6, v7, v6, s80
	v_or3_b32 v3, v6, v95, v3
	ds_write_b32 v14, v3 offset:144
	v_mov_b32_e32 v6, v214
	v_mov_b32_e32 v7, v215
	v_pk_add_f32 v[82:83], v[82:83], v[6:7] op_sel_hi:[1,0] neg_lo:[0,1] neg_hi:[0,1]
	s_nop 0
	v_pk_mul_f32 v[82:83], v[6:7], v[82:83] op_sel:[1,0]
	v_pk_add_f32 v[80:81], v[80:81], v[6:7] op_sel_hi:[1,0] neg_lo:[0,1] neg_hi:[0,1]
	v_pk_fma_f32 v[82:83], v[88:89], v[82:83], v[90:91]
	v_pk_mul_f32 v[6:7], v[6:7], v[80:81] op_sel:[1,0]
	v_and_b32_sdwa v80, v82, v216 dst_sel:DWORD dst_unused:UNUSED_PAD src0_sel:WORD_1 src1_sel:DWORD
	v_pk_fma_f32 v[6:7], v[0:1], v[6:7], v[4:5]
	v_add3_u32 v80, v82, v80, s78
	v_and_b32_e32 v81, 0xffff0000, v80
	v_and_b32_sdwa v80, v7, v216 dst_sel:DWORD dst_unused:UNUSED_PAD src0_sel:WORD_1 src1_sel:DWORD
	v_and_b32_sdwa v3, v83, v216 dst_sel:DWORD dst_unused:UNUSED_PAD src0_sel:WORD_1 src1_sel:DWORD
	v_and_b32_sdwa v95, v6, v216 dst_sel:DWORD dst_unused:UNUSED_PAD src0_sel:WORD_1 src1_sel:DWORD
	v_add3_u32 v80, v7, v80, s78
	v_add3_u32 v3, v83, v3, s78
	v_add3_u32 v95, v6, v95, s78
	v_and_b32_e32 v98, 0xffff0000, v80
	v_or_b32_sdwa v97, v98, v3 dst_sel:DWORD dst_unused:UNUSED_PAD src0_sel:DWORD src1_sel:WORD_1
	v_or_b32_sdwa v96, v95, v81 dst_sel:DWORD dst_unused:UNUSED_PAD src0_sel:WORD_1 src1_sel:DWORD
	v_and_b32_e32 v95, 0xffff0000, v95
	v_sub_u32_e32 v81, v82, v81
	v_and_b32_e32 v3, 0xffff0000, v3
	v_sub_u32_e32 v6, v6, v95
	v_add_u32_e32 v81, 0x80, v81
	v_sub_u32_e32 v3, v83, v3
	v_sub_u32_e32 v7, v7, v98
	v_add_u32_e32 v6, 0x80, v6
	v_ashrrev_i32_e32 v81, 8, v81
	v_add_u32_e32 v3, 0x80, v3
	v_add_u32_e32 v7, 0x80, v7
	v_ashrrev_i32_e32 v6, 8, v6
	v_min_i32_e32 v81, 0x7f, v81
	v_ashrrev_i32_e32 v3, 8, v3
	v_ashrrev_i32_e32 v7, 8, v7
	v_min_i32_e32 v6, 0x7f, v6
	v_min_i32_sdwa v3, v3, s79 dst_sel:WORD_1 dst_unused:UNUSED_PAD src0_sel:DWORD src1_sel:DWORD
	v_min_i32_e32 v7, 0x7f, v7
	v_lshlrev_b32_e32 v81, 8, v81
	v_and_b32_e32 v81, 0xff00, v81
	v_and_b32_e32 v3, 0xff0000, v3
	v_perm_b32 v6, v7, v6, s80
	v_add_u32_e32 v80, v2, v136
	v_or3_b32 v3, v6, v81, v3
	ds_write_b64 v80, v[96:97]
	ds_write_b32 v20, v3 offset:144
	v_mov_b32_e32 v6, v252
	v_mov_b32_e32 v7, v253
	v_or_b32_e32 v81, 0x6000, v148
	v_or_b32_e32 v82, 0x8000, v148
	v_or_b32_e32 v83, 0xa000, v148
	v_or_b32_e32 v95, 0x6000, v146
	v_pk_add_f32 v[74:75], v[74:75], v[6:7] op_sel_hi:[1,0] neg_lo:[0,1] neg_hi:[0,1]
	v_pk_add_f32 v[72:73], v[72:73], v[6:7] op_sel_hi:[1,0] neg_lo:[0,1] neg_hi:[0,1]
	v_pk_mul_f32 v[74:75], v[6:7], v[74:75] op_sel:[1,0]
	v_pk_mul_f32 v[6:7], v[6:7], v[72:73] op_sel:[1,0]
	v_pk_fma_f32 v[74:75], v[88:89], v[74:75], v[90:91]
	v_pk_fma_f32 v[0:1], v[0:1], v[6:7], v[4:5]
	v_and_b32_sdwa v4, v74, v216 dst_sel:DWORD dst_unused:UNUSED_PAD src0_sel:WORD_1 src1_sel:DWORD
	v_add3_u32 v4, v74, v4, s78
	v_and_b32_e32 v6, 0xffff0000, v4
	v_and_b32_sdwa v4, v1, v216 dst_sel:DWORD dst_unused:UNUSED_PAD src0_sel:WORD_1 src1_sel:DWORD
	v_and_b32_sdwa v5, v0, v216 dst_sel:DWORD dst_unused:UNUSED_PAD src0_sel:WORD_1 src1_sel:DWORD
	v_and_b32_sdwa v3, v75, v216 dst_sel:DWORD dst_unused:UNUSED_PAD src0_sel:WORD_1 src1_sel:DWORD
	v_add3_u32 v4, v1, v4, s78
	v_add3_u32 v7, v0, v5, s78
	v_add3_u32 v3, v75, v3, s78
	v_and_b32_e32 v72, 0xffff0000, v4
	v_add_u32_e32 v73, v2, v135
	v_and_b32_e32 v2, 0xffff0000, v7
	v_or_b32_sdwa v5, v72, v3 dst_sel:DWORD dst_unused:UNUSED_PAD src0_sel:DWORD src1_sel:WORD_1
	v_sub_u32_e32 v0, v0, v2
	v_sub_u32_e32 v2, v74, v6
	v_and_b32_e32 v3, 0xffff0000, v3
	v_add_u32_e32 v2, 0x80, v2
	v_sub_u32_e32 v3, v75, v3
	v_sub_u32_e32 v1, v1, v72
	v_add_u32_e32 v0, 0x80, v0
	v_ashrrev_i32_e32 v2, 8, v2
	v_add_u32_e32 v3, 0x80, v3
	v_add_u32_e32 v1, 0x80, v1
	v_ashrrev_i32_e32 v0, 8, v0
	v_min_i32_e32 v2, 0x7f, v2
	v_ashrrev_i32_e32 v3, 8, v3
	v_ashrrev_i32_e32 v1, 8, v1
	v_min_i32_e32 v0, 0x7f, v0
	v_min_i32_sdwa v3, v3, s79 dst_sel:WORD_1 dst_unused:UNUSED_PAD src0_sel:DWORD src1_sel:DWORD
	v_min_i32_e32 v1, 0x7f, v1
	v_lshlrev_b32_e32 v2, 8, v2
	v_and_b32_e32 v2, 0xff00, v2
	v_and_b32_e32 v3, 0xff0000, v3
	v_perm_b32 v0, v1, v0, s80
	v_or_b32_sdwa v4, v7, v6 dst_sel:DWORD dst_unused:UNUSED_PAD src0_sel:WORD_1 src1_sel:DWORD
	v_or3_b32 v0, v0, v2, v3
	ds_write_b64 v73, v[4:5]
	ds_write_b32 v22, v0 offset:144
	v_add_u32_e32 v72, s60, v151
	s_waitcnt lgkmcnt(0)
	s_barrier
;     ...
;           _Pragma("unroll") for (int bj = 0; bj < 2; ++bj) _Pragma("unroll") for (int n = 0; n < 2; ++n) {
;             const int cc = bj * HALF + wc3 * 32 + n * 16 + fq3 * 4;
;             const float4 gm = *reinterpret_cast<const float4*>(g.gam + pn * BM + cc), bt = *reinterpret_cast<const float4*>(g.bet + pn * BM + cc);
;             _Pragma("unroll") for (int m = 0; m < 4; ++m) {
;               const int rr = wr3 * 64 + m * 16 + fr3;
;               const float2 ms = *reinterpret_cast<const float2*>(mr + (ai * HALF + rr) * 2);
;               f32x4 y = acc[ai][bj][m][n];
;               const float o0 = (y[0] - ms.x) * ms.y * gm.x + bt.x, o1 = (y[1] - ms.x) * ms.y * gm.y + bt.y;
;               const float o2 = (y[2] - ms.x) * ms.y * gm.z + bt.z, o3 = (y[3] - ms.x) * ms.y * gm.w + bt.w;
;               const unsigned h0 = f2bf(o0), h1 = f2bf(o1), h2 = f2bf(o2), h3 = f2bf(o3);
;               u32x2 ob; ob[0] = h0 | (h1 << 16); ob[1] = h2 | (h3 << 16);
;               *reinterpret_cast<u32x2*>(smem + (rr >> 1) * PIECE + (rr & 1) * 512 + cc * 2) = ob;
;               const int l0 = min(((int)__float_as_uint(o0) - (int)(h0 << 16) + 128) >> 8, 127);
;               const int l1 = min(((int)__float_as_uint(o1) - (int)(h1 << 16) + 128) >> 8, 127);
;               const int l2 = min(((int)__float_as_uint(o2) - (int)(h2 << 16) + 128) >> 8, 127);
;               const int l3 = min(((int)__float_as_uint(o3) - (int)(h3 << 16) + 128) >> 8, 127);
;               *reinterpret_cast<unsigned*>(smem + LOBASE + (rr >> 2) * PIECE + (rr & 3) * 256 + cc) =
;                   (unsigned)(l0 & 255) | ((unsigned)(l1 & 255) << 8) | ((unsigned)(l2 & 255) << 16) | ((unsigned)l3 << 24);
;             }
;     ...
;           _Pragma("unroll") for (int i = 0; i < 8; ++i) {
;             const u32x4 v = *reinterpret_cast<const u32x4*>(smem + (wave * 8 + i) * PIECE + lane3 * 16);
;             __builtin_amdgcn_raw_buffer_store_b128(v, rsXB, hvo + i * (2 * DM * 2), hso, 0);
;           }
;           _Pragma("unroll") for (int i = 0; i < 4; ++i) {
;             const u32x4 v = *reinterpret_cast<const u32x4*>(smem + LOBASE + (wave * 4 + i) * PIECE + lane3 * 16);
;             __builtin_amdgcn_raw_buffer_store_b128(v, rsLO, lvo + i * (4 * DM), lso, 0);
;           }
	ds_read_b128 v[128:131], v72
	v_or_b32_e32 v74, 0x2000, v148
	v_or_b32_e32 v75, 0x4000, v148
	v_or_b32_e32 v88, 0xc000, v148
	v_or_b32_e32 v89, 0xe000, v148
	ds_read_b128 v[136:139], v72 offset:1040
	v_or_b32_e32 v90, 0x2000, v146
	v_or_b32_e32 v91, 0x4000, v146
	ds_read_b128 v[140:143], v72 offset:2080
	ds_read_b128 v[156:159], v72 offset:3120
	ds_read_b128 v[160:163], v72 offset:4160
	ds_read_b128 v[164:167], v72 offset:5200
	ds_read_b128 v[168:171], v72 offset:6240
	ds_read_b128 v[172:175], v72 offset:7280
	ds_read_b128 v[176:179], v147
	ds_read_b128 v[180:183], v147 offset:1040
	ds_read_b128 v[184:187], v147 offset:2080
	ds_read_b128 v[188:191], v147 offset:3120
	s_waitcnt lgkmcnt(0)
	s_barrier
	s_nop 1
	v_mov_b32_e32 v0, v220
	v_mov_b32_e32 v1, v221
	v_mov_b32_e32 v2, v222
	v_mov_b32_e32 v3, v223
	v_mov_b32_e32 v4, v236
	v_mov_b32_e32 v5, v237
	v_mov_b32_e32 v6, v238
	v_mov_b32_e32 v7, v239
	ds_read_b64 v[102:103], v149 offset:1024
	s_waitcnt lgkmcnt(0)
	v_mov_b32_e32 v210, v102
	v_mov_b32_e32 v211, v103
	v_pk_add_f32 v[66:67], v[66:67], v[102:103] op_sel_hi:[1,0] neg_lo:[0,1] neg_hi:[0,1]
	s_nop 0
	v_pk_mul_f32 v[66:67], v[102:103], v[66:67] op_sel:[1,0]
	v_pk_add_f32 v[64:65], v[64:65], v[102:103] op_sel_hi:[1,0] neg_lo:[0,1] neg_hi:[0,1]
	v_mov_b32_e32 v96, v1
	v_mov_b32_e32 v97, v2
	v_mov_b32_e32 v98, v5
	v_mov_b32_e32 v99, v6
	v_pk_fma_f32 v[66:67], v[96:97], v[66:67], v[98:99]
	v_pk_mul_f32 v[64:65], v[102:103], v[64:65] op_sel:[1,0]
	v_mov_b32_e32 v1, v3
	v_mov_b32_e32 v5, v7
	v_and_b32_sdwa v6, v67, v216 dst_sel:DWORD dst_unused:UNUSED_PAD src0_sel:WORD_1 src1_sel:DWORD
	v_and_b32_sdwa v7, v66, v216 dst_sel:DWORD dst_unused:UNUSED_PAD src0_sel:WORD_1 src1_sel:DWORD
	v_pk_fma_f32 v[2:3], v[0:1], v[64:65], v[4:5]
	v_add3_u32 v64, v67, v6, s78
	v_add3_u32 v6, v66, v7, s78
	v_and_b32_e32 v65, 0xffff0000, v6
	v_and_b32_sdwa v6, v3, v216 dst_sel:DWORD dst_unused:UNUSED_PAD src0_sel:WORD_1 src1_sel:DWORD
	v_and_b32_sdwa v7, v2, v216 dst_sel:DWORD dst_unused:UNUSED_PAD src0_sel:WORD_1 src1_sel:DWORD
	v_add3_u32 v6, v3, v6, s78
	v_add3_u32 v102, v2, v7, s78
	v_and_b32_e32 v103, 0xffff0000, v6
	v_or_b32_sdwa v7, v103, v64 dst_sel:DWORD dst_unused:UNUSED_PAD src0_sel:DWORD src1_sel:WORD_1
	v_or_b32_sdwa v6, v102, v65 dst_sel:DWORD dst_unused:UNUSED_PAD src0_sel:WORD_1 src1_sel:DWORD
	ds_write_b64 v152, v[6:7]
	v_and_b32_e32 v6, 0xffff0000, v102
	v_sub_u32_e32 v2, v2, v6
	v_sub_u32_e32 v6, v66, v65
	v_and_b32_e32 v7, 0xffff0000, v64
	v_add_u32_e32 v6, 0x80, v6
	v_sub_u32_e32 v7, v67, v7
	v_sub_u32_e32 v3, v3, v103
	v_add_u32_e32 v2, 0x80, v2
	v_ashrrev_i32_e32 v6, 8, v6
	v_add_u32_e32 v7, 0x80, v7
	v_add_u32_e32 v3, 0x80, v3
	v_ashrrev_i32_e32 v2, 8, v2
	v_min_i32_e32 v6, 0x7f, v6
	v_ashrrev_i32_e32 v7, 8, v7
	v_ashrrev_i32_e32 v3, 8, v3
	v_min_i32_e32 v2, 0x7f, v2
	v_min_i32_sdwa v7, v7, s79 dst_sel:WORD_1 dst_unused:UNUSED_PAD src0_sel:DWORD src1_sel:DWORD
	v_min_i32_e32 v3, 0x7f, v3
	v_lshlrev_b32_e32 v6, 8, v6
	v_and_b32_e32 v6, 0xff00, v6
	v_and_b32_e32 v7, 0xff0000, v7
	v_perm_b32 v2, v3, v2, s80
	v_or3_b32 v2, v2, v6, v7
	ds_write_b32 v12, v2
	buffer_store_dwordx4 v[128:131], v148, s[16:19], s33 offen
	ds_read_b64 v[2:3], v13 offset:1024
	s_waitcnt lgkmcnt(0)
	v_mov_b32_e32 v212, v2
	v_mov_b32_e32 v213, v3
	v_pk_add_f32 v[6:7], v[70:71], v[2:3] op_sel_hi:[1,0] neg_lo:[0,1] neg_hi:[0,1]
	s_nop 0
	v_pk_mul_f32 v[6:7], v[2:3], v[6:7] op_sel:[1,0]
	v_pk_add_f32 v[64:65], v[68:69], v[2:3] op_sel_hi:[1,0] neg_lo:[0,1] neg_hi:[0,1]
	v_pk_fma_f32 v[6:7], v[96:97], v[6:7], v[98:99]
	v_pk_mul_f32 v[2:3], v[2:3], v[64:65] op_sel:[1,0]
	v_and_b32_sdwa v64, v7, v216 dst_sel:DWORD dst_unused:UNUSED_PAD src0_sel:WORD_1 src1_sel:DWORD
	v_and_b32_sdwa v65, v6, v216 dst_sel:DWORD dst_unused:UNUSED_PAD src0_sel:WORD_1 src1_sel:DWORD
	v_pk_fma_f32 v[2:3], v[0:1], v[2:3], v[4:5]
	v_add3_u32 v66, v7, v64, s78
	v_add3_u32 v64, v6, v65, s78
	v_and_b32_e32 v67, 0xffff0000, v64
	v_and_b32_sdwa v64, v3, v216 dst_sel:DWORD dst_unused:UNUSED_PAD src0_sel:WORD_1 src1_sel:DWORD
	v_and_b32_sdwa v65, v2, v216 dst_sel:DWORD dst_unused:UNUSED_PAD src0_sel:WORD_1 src1_sel:DWORD
	v_add3_u32 v64, v3, v64, s78
	v_add3_u32 v68, v2, v65, s78
	v_and_b32_e32 v69, 0xffff0000, v64
	v_or_b32_sdwa v65, v69, v66 dst_sel:DWORD dst_unused:UNUSED_PAD src0_sel:DWORD src1_sel:WORD_1
	v_or_b32_sdwa v64, v68, v67 dst_sel:DWORD dst_unused:UNUSED_PAD src0_sel:WORD_1 src1_sel:DWORD
	ds_write_b64 v132, v[64:65]
	v_and_b32_e32 v64, 0xffff0000, v68
	v_sub_u32_e32 v2, v2, v64
	v_sub_u32_e32 v6, v6, v67
	v_and_b32_e32 v64, 0xffff0000, v66
	v_add_u32_e32 v6, 0x80, v6
	v_sub_u32_e32 v7, v7, v64
	v_sub_u32_e32 v3, v3, v69
	v_add_u32_e32 v2, 0x80, v2
	v_ashrrev_i32_e32 v6, 8, v6
	v_add_u32_e32 v7, 0x80, v7
	v_add_u32_e32 v3, 0x80, v3
	v_ashrrev_i32_e32 v2, 8, v2
	v_min_i32_e32 v6, 0x7f, v6
	v_ashrrev_i32_e32 v7, 8, v7
	v_ashrrev_i32_e32 v3, 8, v3
	v_min_i32_e32 v2, 0x7f, v2
	v_min_i32_sdwa v7, v7, s79 dst_sel:WORD_1 dst_unused:UNUSED_PAD src0_sel:DWORD src1_sel:DWORD
	v_min_i32_e32 v3, 0x7f, v3
	v_lshlrev_b32_e32 v6, 8, v6
	v_and_b32_e32 v6, 0xff00, v6
	v_and_b32_e32 v7, 0xff0000, v7
	v_perm_b32 v2, v3, v2, s80
	v_or3_b32 v2, v2, v6, v7
	ds_write_b32 v14, v2
	buffer_store_dwordx4 v[136:139], v74, s[16:19], s33 offen
	ds_read_b64 v[2:3], v15 offset:1024
	s_waitcnt lgkmcnt(0)
;     ...
;           _Pragma("unroll") for (int bj = 0; bj < 2; ++bj) _Pragma("unroll") for (int n = 0; n < 2; ++n) {
;             const int cc = bj * HALF + wc3 * 32 + n * 16 + fq3 * 4;
;             const float4 gm = *reinterpret_cast<const float4*>(g.gam + pn * BM + cc), bt = *reinterpret_cast<const float4*>(g.bet + pn * BM + cc);
;             _Pragma("unroll") for (int m = 0; m < 4; ++m) {
;               const int rr = wr3 * 64 + m * 16 + fr3;
;               const float2 ms = *reinterpret_cast<const float2*>(mr + (ai * HALF + rr) * 2);
;               f32x4 y = acc[ai][bj][m][n];
;               const float o0 = (y[0] - ms.x) * ms.y * gm.x + bt.x, o1 = (y[1] - ms.x) * ms.y * gm.y + bt.y;
;               const float o2 = (y[2] - ms.x) * ms.y * gm.z + bt.z, o3 = (y[3] - ms.x) * ms.y * gm.w + bt.w;
;               const unsigned h0 = f2bf(o0), h1 = f2bf(o1), h2 = f2bf(o2), h3 = f2bf(o3);
;               u32x2 ob; ob[0] = h0 | (h1 << 16); ob[1] = h2 | (h3 << 16);
;               *reinterpret_cast<u32x2*>(smem + (rr >> 1) * PIECE + (rr & 1) * 512 + cc * 2) = ob;
;               const int l0 = min(((int)__float_as_uint(o0) - (int)(h0 << 16) + 128) >> 8, 127);
;               const int l1 = min(((int)__float_as_uint(o1) - (int)(h1 << 16) + 128) >> 8, 127);
;               const int l2 = min(((int)__float_as_uint(o2) - (int)(h2 << 16) + 128) >> 8, 127);
;               const int l3 = min(((int)__float_as_uint(o3) - (int)(h3 << 16) + 128) >> 8, 127);
;               *reinterpret_cast<unsigned*>(smem + LOBASE + (rr >> 2) * PIECE + (rr & 3) * 256 + cc) =
;                   (unsigned)(l0 & 255) | ((unsigned)(l1 & 255) << 8) | ((unsigned)(l2 & 255) << 16) | ((unsigned)l3 << 24);
;             }
;     ...
;             __builtin_amdgcn_raw_buffer_store_b128(v, rsXB, hvo + i * (2 * DM * 2), hso, 0);
	v_mov_b32_e32 v214, v2
	v_mov_b32_e32 v215, v3
	v_pk_add_f32 v[6:7], v[78:79], v[2:3] op_sel_hi:[1,0] neg_lo:[0,1] neg_hi:[0,1]
	s_nop 0
	v_pk_mul_f32 v[6:7], v[2:3], v[6:7] op_sel:[1,0]
	v_pk_add_f32 v[64:65], v[76:77], v[2:3] op_sel_hi:[1,0] neg_lo:[0,1] neg_hi:[0,1]
	v_pk_fma_f32 v[6:7], v[96:97], v[6:7], v[98:99]
	v_pk_mul_f32 v[2:3], v[2:3], v[64:65] op_sel:[1,0]
	v_and_b32_sdwa v64, v7, v216 dst_sel:DWORD dst_unused:UNUSED_PAD src0_sel:WORD_1 src1_sel:DWORD
	v_and_b32_sdwa v65, v6, v216 dst_sel:DWORD dst_unused:UNUSED_PAD src0_sel:WORD_1 src1_sel:DWORD
	v_pk_fma_f32 v[2:3], v[0:1], v[2:3], v[4:5]
	v_add3_u32 v66, v7, v64, s78
	v_add3_u32 v64, v6, v65, s78
	v_and_b32_e32 v67, 0xffff0000, v64
	v_and_b32_sdwa v64, v3, v216 dst_sel:DWORD dst_unused:UNUSED_PAD src0_sel:WORD_1 src1_sel:DWORD
	v_and_b32_sdwa v65, v2, v216 dst_sel:DWORD dst_unused:UNUSED_PAD src0_sel:WORD_1 src1_sel:DWORD
	v_add3_u32 v64, v3, v64, s78
	v_add3_u32 v68, v2, v65, s78
	v_and_b32_e32 v69, 0xffff0000, v64
	v_or_b32_sdwa v65, v69, v66 dst_sel:DWORD dst_unused:UNUSED_PAD src0_sel:DWORD src1_sel:WORD_1
	v_or_b32_sdwa v64, v68, v67 dst_sel:DWORD dst_unused:UNUSED_PAD src0_sel:WORD_1 src1_sel:DWORD
	ds_write_b64 v133, v[64:65]
	v_and_b32_e32 v64, 0xffff0000, v68
	v_sub_u32_e32 v2, v2, v64
	v_sub_u32_e32 v6, v6, v67
	v_and_b32_e32 v64, 0xffff0000, v66
	v_add_u32_e32 v6, 0x80, v6
	v_sub_u32_e32 v7, v7, v64
	v_sub_u32_e32 v3, v3, v69
	v_add_u32_e32 v2, 0x80, v2
	v_ashrrev_i32_e32 v6, 8, v6
	v_add_u32_e32 v7, 0x80, v7
	v_add_u32_e32 v3, 0x80, v3
	v_ashrrev_i32_e32 v2, 8, v2
	v_min_i32_e32 v6, 0x7f, v6
	v_ashrrev_i32_e32 v7, 8, v7
	v_ashrrev_i32_e32 v3, 8, v3
	v_min_i32_e32 v2, 0x7f, v2
	v_min_i32_sdwa v7, v7, s79 dst_sel:WORD_1 dst_unused:UNUSED_PAD src0_sel:DWORD src1_sel:DWORD
	v_min_i32_e32 v3, 0x7f, v3
	v_lshlrev_b32_e32 v6, 8, v6
	v_and_b32_e32 v6, 0xff00, v6
	v_and_b32_e32 v7, 0xff0000, v7
	v_perm_b32 v2, v3, v2, s80
	v_or3_b32 v2, v2, v6, v7
	ds_write_b32 v20, v2
	buffer_store_dwordx4 v[140:143], v75, s[16:19], s33 offen
	ds_read_b64 v[2:3], v21 offset:1024
	s_waitcnt lgkmcnt(0)
	v_mov_b32_e32 v252, v2
	v_mov_b32_e32 v253, v3
	v_pk_add_f32 v[6:7], v[86:87], v[2:3] op_sel_hi:[1,0] neg_lo:[0,1] neg_hi:[0,1]
	s_nop 0
	v_pk_mul_f32 v[6:7], v[2:3], v[6:7] op_sel:[1,0]
	v_pk_add_f32 v[64:65], v[84:85], v[2:3] op_sel_hi:[1,0] neg_lo:[0,1] neg_hi:[0,1]
	v_pk_fma_f32 v[6:7], v[96:97], v[6:7], v[98:99]
	v_pk_mul_f32 v[2:3], v[2:3], v[64:65] op_sel:[1,0]
	s_nop 0
	v_pk_fma_f32 v[0:1], v[0:1], v[2:3], v[4:5]
	v_and_b32_sdwa v2, v7, v216 dst_sel:DWORD dst_unused:UNUSED_PAD src0_sel:WORD_1 src1_sel:DWORD
	v_and_b32_sdwa v3, v6, v216 dst_sel:DWORD dst_unused:UNUSED_PAD src0_sel:WORD_1 src1_sel:DWORD
	v_add3_u32 v4, v7, v2, s78
	v_add3_u32 v2, v6, v3, s78
	v_and_b32_e32 v5, 0xffff0000, v2
	v_and_b32_sdwa v2, v1, v216 dst_sel:DWORD dst_unused:UNUSED_PAD src0_sel:WORD_1 src1_sel:DWORD
	v_and_b32_sdwa v3, v0, v216 dst_sel:DWORD dst_unused:UNUSED_PAD src0_sel:WORD_1 src1_sel:DWORD
	v_add3_u32 v2, v1, v2, s78
	v_add3_u32 v64, v0, v3, s78
	v_and_b32_e32 v65, 0xffff0000, v2
	v_or_b32_sdwa v3, v65, v4 dst_sel:DWORD dst_unused:UNUSED_PAD src0_sel:DWORD src1_sel:WORD_1
	v_or_b32_sdwa v2, v64, v5 dst_sel:DWORD dst_unused:UNUSED_PAD src0_sel:WORD_1 src1_sel:DWORD
	ds_write_b64 v134, v[2:3]
	v_and_b32_e32 v2, 0xffff0000, v64
	v_sub_u32_e32 v0, v0, v2
	v_sub_u32_e32 v2, v6, v5
	v_and_b32_e32 v3, 0xffff0000, v4
	v_add_u32_e32 v2, 0x80, v2
	v_sub_u32_e32 v3, v7, v3
	v_sub_u32_e32 v1, v1, v65
	v_add_u32_e32 v0, 0x80, v0
	v_ashrrev_i32_e32 v2, 8, v2
	v_add_u32_e32 v3, 0x80, v3
	v_add_u32_e32 v1, 0x80, v1
	v_ashrrev_i32_e32 v0, 8, v0
	v_min_i32_e32 v2, 0x7f, v2
	v_ashrrev_i32_e32 v3, 8, v3
	v_ashrrev_i32_e32 v1, 8, v1
	v_min_i32_e32 v0, 0x7f, v0
	v_min_i32_sdwa v3, v3, s79 dst_sel:WORD_1 dst_unused:UNUSED_PAD src0_sel:DWORD src1_sel:DWORD
	v_min_i32_e32 v1, 0x7f, v1
	v_lshlrev_b32_e32 v2, 8, v2
	v_and_b32_e32 v2, 0xff00, v2
	v_and_b32_e32 v3, 0xff0000, v3
	v_perm_b32 v0, v1, v0, s80
	v_or3_b32 v0, v0, v2, v3
	ds_write_b32 v22, v0
	buffer_store_dwordx4 v[156:159], v81, s[16:19], s33 offen
	v_mov_b32_e32 v0, v224
	v_mov_b32_e32 v1, v225
	v_mov_b32_e32 v2, v226
	v_mov_b32_e32 v3, v227
	v_mov_b32_e32 v4, v240
	v_mov_b32_e32 v5, v241
	v_mov_b32_e32 v6, v242
	v_mov_b32_e32 v7, v243
	v_mov_b32_e32 v68, v210
	v_mov_b32_e32 v69, v211
	v_pk_add_f32 v[58:59], v[58:59], v[68:69] op_sel_hi:[1,0] neg_lo:[0,1] neg_hi:[0,1]
	s_nop 0
	v_pk_mul_f32 v[58:59], v[68:69], v[58:59] op_sel:[1,0]
	v_pk_add_f32 v[56:57], v[56:57], v[68:69] op_sel_hi:[1,0] neg_lo:[0,1] neg_hi:[0,1]
	v_mov_b32_e32 v64, v1
	v_mov_b32_e32 v65, v2
	v_mov_b32_e32 v66, v5
	v_mov_b32_e32 v67, v6
	v_pk_fma_f32 v[58:59], v[64:65], v[58:59], v[66:67]
	v_pk_mul_f32 v[56:57], v[68:69], v[56:57] op_sel:[1,0]
	v_mov_b32_e32 v1, v3
	v_mov_b32_e32 v5, v7
	v_and_b32_sdwa v6, v59, v216 dst_sel:DWORD dst_unused:UNUSED_PAD src0_sel:WORD_1 src1_sel:DWORD
	v_and_b32_sdwa v7, v58, v216 dst_sel:DWORD dst_unused:UNUSED_PAD src0_sel:WORD_1 src1_sel:DWORD
	v_pk_fma_f32 v[2:3], v[0:1], v[56:57], v[4:5]
	v_add3_u32 v56, v59, v6, s78
	v_add3_u32 v6, v58, v7, s78
	v_and_b32_e32 v57, 0xffff0000, v6
	v_and_b32_sdwa v6, v3, v216 dst_sel:DWORD dst_unused:UNUSED_PAD src0_sel:WORD_1 src1_sel:DWORD
	v_and_b32_sdwa v7, v2, v216 dst_sel:DWORD dst_unused:UNUSED_PAD src0_sel:WORD_1 src1_sel:DWORD
	v_add3_u32 v6, v3, v6, s78
	v_add3_u32 v68, v2, v7, s78
	v_and_b32_e32 v69, 0xffff0000, v6
	v_or_b32_sdwa v7, v69, v56 dst_sel:DWORD dst_unused:UNUSED_PAD src0_sel:DWORD src1_sel:WORD_1
	v_or_b32_sdwa v6, v68, v57 dst_sel:DWORD dst_unused:UNUSED_PAD src0_sel:WORD_1 src1_sel:DWORD
;     ...
;           _Pragma("unroll") for (int bj = 0; bj < 2; ++bj) _Pragma("unroll") for (int n = 0; n < 2; ++n) {
;             const int cc = bj * HALF + wc3 * 32 + n * 16 + fq3 * 4;
;             const float4 gm = *reinterpret_cast<const float4*>(g.gam + pn * BM + cc), bt = *reinterpret_cast<const float4*>(g.bet + pn * BM + cc);
;             _Pragma("unroll") for (int m = 0; m < 4; ++m) {
;               const int rr = wr3 * 64 + m * 16 + fr3;
;               const float2 ms = *reinterpret_cast<const float2*>(mr + (ai * HALF + rr) * 2);
;               f32x4 y = acc[ai][bj][m][n];
;               const float o0 = (y[0] - ms.x) * ms.y * gm.x + bt.x, o1 = (y[1] - ms.x) * ms.y * gm.y + bt.y;
;               const float o2 = (y[2] - ms.x) * ms.y * gm.z + bt.z, o3 = (y[3] - ms.x) * ms.y * gm.w + bt.w;
;               const unsigned h0 = f2bf(o0), h1 = f2bf(o1), h2 = f2bf(o2), h3 = f2bf(o3);
;               u32x2 ob; ob[0] = h0 | (h1 << 16); ob[1] = h2 | (h3 << 16);
;               *reinterpret_cast<u32x2*>(smem + (rr >> 1) * PIECE + (rr & 1) * 512 + cc * 2) = ob;
;               const int l0 = min(((int)__float_as_uint(o0) - (int)(h0 << 16) + 128) >> 8, 127);
;               const int l1 = min(((int)__float_as_uint(o1) - (int)(h1 << 16) + 128) >> 8, 127);
;               const int l2 = min(((int)__float_as_uint(o2) - (int)(h2 << 16) + 128) >> 8, 127);
;               const int l3 = min(((int)__float_as_uint(o3) - (int)(h3 << 16) + 128) >> 8, 127);
;               *reinterpret_cast<unsigned*>(smem + LOBASE + (rr >> 2) * PIECE + (rr & 3) * 256 + cc) =
;                   (unsigned)(l0 & 255) | ((unsigned)(l1 & 255) << 8) | ((unsigned)(l2 & 255) << 16) | ((unsigned)l3 << 24);
;             }
;     ...
;             __builtin_amdgcn_raw_buffer_store_b128(v, rsXB, hvo + i * (2 * DM * 2), hso, 0);
	ds_write_b64 v23, v[6:7]
	v_and_b32_e32 v6, 0xffff0000, v68
	v_sub_u32_e32 v2, v2, v6
	v_sub_u32_e32 v6, v58, v57
	v_and_b32_e32 v7, 0xffff0000, v56
	v_add_u32_e32 v6, 0x80, v6
	v_sub_u32_e32 v7, v59, v7
	v_sub_u32_e32 v3, v3, v69
	v_add_u32_e32 v2, 0x80, v2
	v_ashrrev_i32_e32 v6, 8, v6
	v_add_u32_e32 v7, 0x80, v7
	v_add_u32_e32 v3, 0x80, v3
	v_ashrrev_i32_e32 v2, 8, v2
	v_min_i32_e32 v6, 0x7f, v6
	v_ashrrev_i32_e32 v7, 8, v7
	v_ashrrev_i32_e32 v3, 8, v3
	v_min_i32_e32 v2, 0x7f, v2
	v_min_i32_sdwa v7, v7, s79 dst_sel:WORD_1 dst_unused:UNUSED_PAD src0_sel:DWORD src1_sel:DWORD
	v_min_i32_e32 v3, 0x7f, v3
	v_lshlrev_b32_e32 v6, 8, v6
	v_and_b32_e32 v6, 0xff00, v6
	v_and_b32_e32 v7, 0xff0000, v7
	v_perm_b32 v2, v3, v2, s80
	v_or3_b32 v2, v2, v6, v7
	ds_write_b32 v12, v2 offset:16
	buffer_store_dwordx4 v[160:163], v82, s[16:19], s33 offen
	v_mov_b32_e32 v2, v212
	v_mov_b32_e32 v3, v213
	v_pk_add_f32 v[6:7], v[42:43], v[2:3] op_sel_hi:[1,0] neg_lo:[0,1] neg_hi:[0,1]
	s_nop 0
	v_pk_mul_f32 v[6:7], v[2:3], v[6:7] op_sel:[1,0]
	v_pk_add_f32 v[40:41], v[40:41], v[2:3] op_sel_hi:[1,0] neg_lo:[0,1] neg_hi:[0,1]
	v_pk_fma_f32 v[6:7], v[64:65], v[6:7], v[66:67]
	v_pk_mul_f32 v[2:3], v[2:3], v[40:41] op_sel:[1,0]
	v_and_b32_sdwa v40, v6, v216 dst_sel:DWORD dst_unused:UNUSED_PAD src0_sel:WORD_1 src1_sel:DWORD
	v_pk_fma_f32 v[2:3], v[0:1], v[2:3], v[4:5]
	v_add3_u32 v40, v6, v40, s78
	v_and_b32_e32 v42, 0xffff0000, v40
	v_and_b32_sdwa v40, v3, v216 dst_sel:DWORD dst_unused:UNUSED_PAD src0_sel:WORD_1 src1_sel:DWORD
	v_and_b32_sdwa v23, v7, v216 dst_sel:DWORD dst_unused:UNUSED_PAD src0_sel:WORD_1 src1_sel:DWORD
	v_and_b32_sdwa v41, v2, v216 dst_sel:DWORD dst_unused:UNUSED_PAD src0_sel:WORD_1 src1_sel:DWORD
	v_add3_u32 v40, v3, v40, s78
	v_add3_u32 v23, v7, v23, s78
	v_add3_u32 v43, v2, v41, s78
	v_and_b32_e32 v56, 0xffff0000, v40
	v_or_b32_sdwa v41, v56, v23 dst_sel:DWORD dst_unused:UNUSED_PAD src0_sel:DWORD src1_sel:WORD_1
	v_or_b32_sdwa v40, v43, v42 dst_sel:DWORD dst_unused:UNUSED_PAD src0_sel:WORD_1 src1_sel:DWORD
	ds_write_b64 v104, v[40:41]
	v_and_b32_e32 v40, 0xffff0000, v43
	v_sub_u32_e32 v6, v6, v42
	v_and_b32_e32 v23, 0xffff0000, v23
	v_sub_u32_e32 v2, v2, v40
	v_add_u32_e32 v6, 0x80, v6
	v_sub_u32_e32 v7, v7, v23
	v_sub_u32_e32 v3, v3, v56
	v_add_u32_e32 v2, 0x80, v2
	v_ashrrev_i32_e32 v6, 8, v6
	v_add_u32_e32 v7, 0x80, v7
	v_add_u32_e32 v3, 0x80, v3
	v_ashrrev_i32_e32 v2, 8, v2
	v_min_i32_e32 v6, 0x7f, v6
	v_ashrrev_i32_e32 v7, 8, v7
	v_ashrrev_i32_e32 v3, 8, v3
	v_min_i32_e32 v2, 0x7f, v2
	v_min_i32_sdwa v7, v7, s79 dst_sel:WORD_1 dst_unused:UNUSED_PAD src0_sel:DWORD src1_sel:DWORD
	v_min_i32_e32 v3, 0x7f, v3
	v_lshlrev_b32_e32 v6, 8, v6
	v_and_b32_e32 v6, 0xff00, v6
	v_and_b32_e32 v7, 0xff0000, v7
	v_perm_b32 v2, v3, v2, s80
	v_or3_b32 v2, v2, v6, v7
	ds_write_b32 v14, v2 offset:16
	buffer_store_dwordx4 v[164:167], v83, s[16:19], s33 offen
	v_mov_b32_e32 v2, v214
	v_mov_b32_e32 v3, v215
	v_pk_add_f32 v[6:7], v[46:47], v[2:3] op_sel_hi:[1,0] neg_lo:[0,1] neg_hi:[0,1]
	s_nop 0
	v_pk_mul_f32 v[6:7], v[2:3], v[6:7] op_sel:[1,0]
	v_pk_add_f32 v[40:41], v[44:45], v[2:3] op_sel_hi:[1,0] neg_lo:[0,1] neg_hi:[0,1]
	v_pk_fma_f32 v[6:7], v[64:65], v[6:7], v[66:67]
	v_pk_mul_f32 v[2:3], v[2:3], v[40:41] op_sel:[1,0]
	v_and_b32_sdwa v40, v6, v216 dst_sel:DWORD dst_unused:UNUSED_PAD src0_sel:WORD_1 src1_sel:DWORD
	v_pk_fma_f32 v[2:3], v[0:1], v[2:3], v[4:5]
	v_add3_u32 v40, v6, v40, s78
	v_and_b32_e32 v42, 0xffff0000, v40
	v_and_b32_sdwa v40, v3, v216 dst_sel:DWORD dst_unused:UNUSED_PAD src0_sel:WORD_1 src1_sel:DWORD
	v_and_b32_sdwa v23, v7, v216 dst_sel:DWORD dst_unused:UNUSED_PAD src0_sel:WORD_1 src1_sel:DWORD
	v_and_b32_sdwa v41, v2, v216 dst_sel:DWORD dst_unused:UNUSED_PAD src0_sel:WORD_1 src1_sel:DWORD
	v_add3_u32 v40, v3, v40, s78
	v_add3_u32 v23, v7, v23, s78
	v_add3_u32 v43, v2, v41, s78
	v_and_b32_e32 v44, 0xffff0000, v40
	v_or_b32_sdwa v41, v44, v23 dst_sel:DWORD dst_unused:UNUSED_PAD src0_sel:DWORD src1_sel:WORD_1
	v_or_b32_sdwa v40, v43, v42 dst_sel:DWORD dst_unused:UNUSED_PAD src0_sel:WORD_1 src1_sel:DWORD
	ds_write_b64 v105, v[40:41]
	v_and_b32_e32 v40, 0xffff0000, v43
	v_sub_u32_e32 v6, v6, v42
	v_and_b32_e32 v23, 0xffff0000, v23
	v_sub_u32_e32 v2, v2, v40
	v_add_u32_e32 v6, 0x80, v6
	v_sub_u32_e32 v7, v7, v23
	v_sub_u32_e32 v3, v3, v44
	v_add_u32_e32 v2, 0x80, v2
	v_ashrrev_i32_e32 v6, 8, v6
	v_add_u32_e32 v7, 0x80, v7
	v_add_u32_e32 v3, 0x80, v3
	v_ashrrev_i32_e32 v2, 8, v2
	v_min_i32_e32 v6, 0x7f, v6
	v_ashrrev_i32_e32 v7, 8, v7
	v_ashrrev_i32_e32 v3, 8, v3
	v_min_i32_e32 v2, 0x7f, v2
	v_min_i32_sdwa v7, v7, s79 dst_sel:WORD_1 dst_unused:UNUSED_PAD src0_sel:DWORD src1_sel:DWORD
	v_min_i32_e32 v3, 0x7f, v3
	v_lshlrev_b32_e32 v6, 8, v6
	v_and_b32_e32 v6, 0xff00, v6
	v_and_b32_e32 v7, 0xff0000, v7
	v_perm_b32 v2, v3, v2, s80
	v_or3_b32 v2, v2, v6, v7
	ds_write_b32 v20, v2 offset:16
	buffer_store_dwordx4 v[168:171], v88, s[16:19], s33 offen
	v_mov_b32_e32 v2, v252
	v_mov_b32_e32 v3, v253
	v_pk_add_f32 v[6:7], v[62:63], v[2:3] op_sel_hi:[1,0] neg_lo:[0,1] neg_hi:[0,1]
	s_nop 0
	v_pk_mul_f32 v[6:7], v[2:3], v[6:7] op_sel:[1,0]
	v_pk_add_f32 v[40:41], v[60:61], v[2:3] op_sel_hi:[1,0] neg_lo:[0,1] neg_hi:[0,1]
	v_pk_fma_f32 v[6:7], v[64:65], v[6:7], v[66:67]
	v_pk_mul_f32 v[2:3], v[2:3], v[40:41] op_sel:[1,0]
	s_nop 0
	v_pk_fma_f32 v[0:1], v[0:1], v[2:3], v[4:5]
	v_and_b32_sdwa v2, v7, v216 dst_sel:DWORD dst_unused:UNUSED_PAD src0_sel:WORD_1 src1_sel:DWORD
	v_and_b32_sdwa v3, v6, v216 dst_sel:DWORD dst_unused:UNUSED_PAD src0_sel:WORD_1 src1_sel:DWORD
	v_add3_u32 v4, v7, v2, s78
	v_add3_u32 v2, v6, v3, s78
	v_and_b32_e32 v5, 0xffff0000, v2
;     ...
;           _Pragma("unroll") for (int bj = 0; bj < 2; ++bj) _Pragma("unroll") for (int n = 0; n < 2; ++n) {
;             const int cc = bj * HALF + wc3 * 32 + n * 16 + fq3 * 4;
;             const float4 gm = *reinterpret_cast<const float4*>(g.gam + pn * BM + cc), bt = *reinterpret_cast<const float4*>(g.bet + pn * BM + cc);
;             _Pragma("unroll") for (int m = 0; m < 4; ++m) {
;               const int rr = wr3 * 64 + m * 16 + fr3;
;               const float2 ms = *reinterpret_cast<const float2*>(mr + (ai * HALF + rr) * 2);
;               f32x4 y = acc[ai][bj][m][n];
;               const float o0 = (y[0] - ms.x) * ms.y * gm.x + bt.x, o1 = (y[1] - ms.x) * ms.y * gm.y + bt.y;
;               const float o2 = (y[2] - ms.x) * ms.y * gm.z + bt.z, o3 = (y[3] - ms.x) * ms.y * gm.w + bt.w;
;               const unsigned h0 = f2bf(o0), h1 = f2bf(o1), h2 = f2bf(o2), h3 = f2bf(o3);
;               u32x2 ob; ob[0] = h0 | (h1 << 16); ob[1] = h2 | (h3 << 16);
;               *reinterpret_cast<u32x2*>(smem + (rr >> 1) * PIECE + (rr & 1) * 512 + cc * 2) = ob;
;               const int l0 = min(((int)__float_as_uint(o0) - (int)(h0 << 16) + 128) >> 8, 127);
;               const int l1 = min(((int)__float_as_uint(o1) - (int)(h1 << 16) + 128) >> 8, 127);
;               const int l2 = min(((int)__float_as_uint(o2) - (int)(h2 << 16) + 128) >> 8, 127);
;               const int l3 = min(((int)__float_as_uint(o3) - (int)(h3 << 16) + 128) >> 8, 127);
;               *reinterpret_cast<unsigned*>(smem + LOBASE + (rr >> 2) * PIECE + (rr & 3) * 256 + cc) =
;                   (unsigned)(l0 & 255) | ((unsigned)(l1 & 255) << 8) | ((unsigned)(l2 & 255) << 16) | ((unsigned)l3 << 24);
;             }
;     ...
;             __builtin_amdgcn_raw_buffer_store_b128(v, rsLO, lvo + i * (4 * DM), lso, 0);
	v_and_b32_sdwa v2, v1, v216 dst_sel:DWORD dst_unused:UNUSED_PAD src0_sel:WORD_1 src1_sel:DWORD
	v_and_b32_sdwa v3, v0, v216 dst_sel:DWORD dst_unused:UNUSED_PAD src0_sel:WORD_1 src1_sel:DWORD
	v_add3_u32 v2, v1, v2, s78
	v_add3_u32 v23, v0, v3, s78
	v_and_b32_e32 v40, 0xffff0000, v2
	v_or_b32_sdwa v3, v40, v4 dst_sel:DWORD dst_unused:UNUSED_PAD src0_sel:DWORD src1_sel:WORD_1
	v_or_b32_sdwa v2, v23, v5 dst_sel:DWORD dst_unused:UNUSED_PAD src0_sel:WORD_1 src1_sel:DWORD
	ds_write_b64 v106, v[2:3]
	v_and_b32_e32 v2, 0xffff0000, v23
	v_sub_u32_e32 v0, v0, v2
	v_sub_u32_e32 v2, v6, v5
	v_and_b32_e32 v3, 0xffff0000, v4
	v_add_u32_e32 v2, 0x80, v2
	v_sub_u32_e32 v3, v7, v3
	v_sub_u32_e32 v1, v1, v40
	v_add_u32_e32 v0, 0x80, v0
	v_ashrrev_i32_e32 v2, 8, v2
	v_add_u32_e32 v3, 0x80, v3
	v_add_u32_e32 v1, 0x80, v1
	v_ashrrev_i32_e32 v0, 8, v0
	v_min_i32_e32 v2, 0x7f, v2
	v_ashrrev_i32_e32 v3, 8, v3
	v_ashrrev_i32_e32 v1, 8, v1
	v_min_i32_e32 v0, 0x7f, v0
	v_min_i32_sdwa v3, v3, s79 dst_sel:WORD_1 dst_unused:UNUSED_PAD src0_sel:DWORD src1_sel:DWORD
	v_min_i32_e32 v1, 0x7f, v1
	v_lshlrev_b32_e32 v2, 8, v2
	v_and_b32_e32 v2, 0xff00, v2
	v_and_b32_e32 v3, 0xff0000, v3
	v_perm_b32 v0, v1, v0, s80
	v_or3_b32 v0, v0, v2, v3
	ds_write_b32 v22, v0 offset:16
	buffer_store_dwordx4 v[172:175], v89, s[16:19], s33 offen
	v_mov_b32_e32 v0, v228
	v_mov_b32_e32 v1, v229
	v_mov_b32_e32 v2, v230
	v_mov_b32_e32 v3, v231
	v_mov_b32_e32 v4, v244
	v_mov_b32_e32 v5, v245
	v_mov_b32_e32 v6, v246
	v_mov_b32_e32 v7, v247
	v_mov_b32_e32 v44, v210
	v_mov_b32_e32 v45, v211
	v_pk_add_f32 v[46:47], v[54:55], v[44:45] op_sel_hi:[1,0] neg_lo:[0,1] neg_hi:[0,1]
	s_nop 0
	v_pk_mul_f32 v[46:47], v[44:45], v[46:47] op_sel:[1,0]
	v_pk_add_f32 v[52:53], v[52:53], v[44:45] op_sel_hi:[1,0] neg_lo:[0,1] neg_hi:[0,1]
	v_mov_b32_e32 v40, v1
	v_mov_b32_e32 v41, v2
	v_mov_b32_e32 v42, v5
	v_mov_b32_e32 v43, v6
	v_pk_fma_f32 v[46:47], v[40:41], v[46:47], v[42:43]
	v_pk_mul_f32 v[44:45], v[44:45], v[52:53] op_sel:[1,0]
	v_mov_b32_e32 v1, v3
	v_mov_b32_e32 v5, v7
	v_and_b32_sdwa v6, v47, v216 dst_sel:DWORD dst_unused:UNUSED_PAD src0_sel:WORD_1 src1_sel:DWORD
	v_and_b32_sdwa v7, v46, v216 dst_sel:DWORD dst_unused:UNUSED_PAD src0_sel:WORD_1 src1_sel:DWORD
	v_pk_fma_f32 v[2:3], v[0:1], v[44:45], v[4:5]
	v_add3_u32 v23, v47, v6, s78
	v_add3_u32 v6, v46, v7, s78
	v_and_b32_e32 v44, 0xffff0000, v6
	v_and_b32_sdwa v6, v3, v216 dst_sel:DWORD dst_unused:UNUSED_PAD src0_sel:WORD_1 src1_sel:DWORD
	v_and_b32_sdwa v7, v2, v216 dst_sel:DWORD dst_unused:UNUSED_PAD src0_sel:WORD_1 src1_sel:DWORD
	v_add3_u32 v6, v3, v6, s78
	v_add3_u32 v45, v2, v7, s78
	v_and_b32_e32 v52, 0xffff0000, v6
	v_or_b32_sdwa v7, v52, v23 dst_sel:DWORD dst_unused:UNUSED_PAD src0_sel:DWORD src1_sel:WORD_1
	v_or_b32_sdwa v6, v45, v44 dst_sel:DWORD dst_unused:UNUSED_PAD src0_sel:WORD_1 src1_sel:DWORD
	ds_write_b64 v107, v[6:7]
	v_and_b32_e32 v6, 0xffff0000, v45
	v_sub_u32_e32 v2, v2, v6
	v_sub_u32_e32 v6, v46, v44
	v_and_b32_e32 v7, 0xffff0000, v23
	v_add_u32_e32 v6, 0x80, v6
	v_sub_u32_e32 v7, v47, v7
	v_sub_u32_e32 v3, v3, v52
	v_add_u32_e32 v2, 0x80, v2
	v_ashrrev_i32_e32 v6, 8, v6
	v_add_u32_e32 v7, 0x80, v7
	v_add_u32_e32 v3, 0x80, v3
	v_ashrrev_i32_e32 v2, 8, v2
	v_min_i32_e32 v6, 0x7f, v6
	v_ashrrev_i32_e32 v7, 8, v7
	v_ashrrev_i32_e32 v3, 8, v3
	v_min_i32_e32 v2, 0x7f, v2
	v_min_i32_sdwa v7, v7, s79 dst_sel:WORD_1 dst_unused:UNUSED_PAD src0_sel:DWORD src1_sel:DWORD
	v_min_i32_e32 v3, 0x7f, v3
	v_lshlrev_b32_e32 v6, 8, v6
	v_and_b32_e32 v6, 0xff00, v6
	v_and_b32_e32 v7, 0xff0000, v7
	v_perm_b32 v2, v3, v2, s80
	v_or3_b32 v2, v2, v6, v7
	ds_write_b32 v12, v2 offset:128
	buffer_store_dwordx4 v[176:179], v146, s[20:23], s0 offen
	v_mov_b32_e32 v2, v212
	v_mov_b32_e32 v3, v213
	v_pk_add_f32 v[6:7], v[38:39], v[2:3] op_sel_hi:[1,0] neg_lo:[0,1] neg_hi:[0,1]
	s_nop 0
	v_pk_mul_f32 v[6:7], v[2:3], v[6:7] op_sel:[1,0]
	v_pk_add_f32 v[36:37], v[36:37], v[2:3] op_sel_hi:[1,0] neg_lo:[0,1] neg_hi:[0,1]
	v_pk_fma_f32 v[6:7], v[40:41], v[6:7], v[42:43]
	v_pk_mul_f32 v[2:3], v[2:3], v[36:37] op_sel:[1,0]
	v_and_b32_sdwa v36, v6, v216 dst_sel:DWORD dst_unused:UNUSED_PAD src0_sel:WORD_1 src1_sel:DWORD
	v_pk_fma_f32 v[2:3], v[0:1], v[2:3], v[4:5]
	v_add3_u32 v36, v6, v36, s78
	v_and_b32_e32 v38, 0xffff0000, v36
	v_and_b32_sdwa v36, v3, v216 dst_sel:DWORD dst_unused:UNUSED_PAD src0_sel:WORD_1 src1_sel:DWORD
	v_and_b32_sdwa v23, v7, v216 dst_sel:DWORD dst_unused:UNUSED_PAD src0_sel:WORD_1 src1_sel:DWORD
	v_and_b32_sdwa v37, v2, v216 dst_sel:DWORD dst_unused:UNUSED_PAD src0_sel:WORD_1 src1_sel:DWORD
	v_add3_u32 v36, v3, v36, s78
	v_add3_u32 v23, v7, v23, s78
	v_add3_u32 v39, v2, v37, s78
	v_and_b32_e32 v44, 0xffff0000, v36
	v_or_b32_sdwa v37, v44, v23 dst_sel:DWORD dst_unused:UNUSED_PAD src0_sel:DWORD src1_sel:WORD_1
	v_or_b32_sdwa v36, v39, v38 dst_sel:DWORD dst_unused:UNUSED_PAD src0_sel:WORD_1 src1_sel:DWORD
	ds_write_b64 v100, v[36:37]
	v_and_b32_e32 v36, 0xffff0000, v39
	v_sub_u32_e32 v6, v6, v38
	v_and_b32_e32 v23, 0xffff0000, v23
	v_sub_u32_e32 v2, v2, v36
	v_add_u32_e32 v6, 0x80, v6
	v_sub_u32_e32 v7, v7, v23
	v_sub_u32_e32 v3, v3, v44
	v_add_u32_e32 v2, 0x80, v2
	v_ashrrev_i32_e32 v6, 8, v6
	v_add_u32_e32 v7, 0x80, v7
	v_add_u32_e32 v3, 0x80, v3
	v_ashrrev_i32_e32 v2, 8, v2
	v_min_i32_e32 v6, 0x7f, v6
	v_ashrrev_i32_e32 v7, 8, v7
	v_ashrrev_i32_e32 v3, 8, v3
	v_min_i32_e32 v2, 0x7f, v2
	v_min_i32_sdwa v7, v7, s79 dst_sel:WORD_1 dst_unused:UNUSED_PAD src0_sel:DWORD src1_sel:DWORD
	v_min_i32_e32 v3, 0x7f, v3
	v_lshlrev_b32_e32 v6, 8, v6
	v_and_b32_e32 v6, 0xff00, v6
	v_and_b32_e32 v7, 0xff0000, v7
	v_perm_b32 v2, v3, v2, s80
	v_or3_b32 v2, v2, v6, v7
;     ...
;           _Pragma("unroll") for (int bj = 0; bj < 2; ++bj) _Pragma("unroll") for (int n = 0; n < 2; ++n) {
;             const int cc = bj * HALF + wc3 * 32 + n * 16 + fq3 * 4;
;             const float4 gm = *reinterpret_cast<const float4*>(g.gam + pn * BM + cc), bt = *reinterpret_cast<const float4*>(g.bet + pn * BM + cc);
;             _Pragma("unroll") for (int m = 0; m < 4; ++m) {
;               const int rr = wr3 * 64 + m * 16 + fr3;
;               const float2 ms = *reinterpret_cast<const float2*>(mr + (ai * HALF + rr) * 2);
;               f32x4 y = acc[ai][bj][m][n];
;               const float o0 = (y[0] - ms.x) * ms.y * gm.x + bt.x, o1 = (y[1] - ms.x) * ms.y * gm.y + bt.y;
;               const float o2 = (y[2] - ms.x) * ms.y * gm.z + bt.z, o3 = (y[3] - ms.x) * ms.y * gm.w + bt.w;
;               const unsigned h0 = f2bf(o0), h1 = f2bf(o1), h2 = f2bf(o2), h3 = f2bf(o3);
;               u32x2 ob; ob[0] = h0 | (h1 << 16); ob[1] = h2 | (h3 << 16);
;               *reinterpret_cast<u32x2*>(smem + (rr >> 1) * PIECE + (rr & 1) * 512 + cc * 2) = ob;
;               const int l0 = min(((int)__float_as_uint(o0) - (int)(h0 << 16) + 128) >> 8, 127);
;               const int l1 = min(((int)__float_as_uint(o1) - (int)(h1 << 16) + 128) >> 8, 127);
;               const int l2 = min(((int)__float_as_uint(o2) - (int)(h2 << 16) + 128) >> 8, 127);
;               const int l3 = min(((int)__float_as_uint(o3) - (int)(h3 << 16) + 128) >> 8, 127);
;               *reinterpret_cast<unsigned*>(smem + LOBASE + (rr >> 2) * PIECE + (rr & 3) * 256 + cc) =
;                   (unsigned)(l0 & 255) | ((unsigned)(l1 & 255) << 8) | ((unsigned)(l2 & 255) << 16) | ((unsigned)l3 << 24);
;             }
	ds_write_b32 v14, v2 offset:128
	buffer_store_dwordx4 v[180:183], v90, s[20:23], s0 offen
	v_mov_b32_e32 v2, v214
	v_mov_b32_e32 v3, v215
	v_pk_add_f32 v[6:7], v[26:27], v[2:3] op_sel_hi:[1,0] neg_lo:[0,1] neg_hi:[0,1]
	s_nop 0
	v_pk_mul_f32 v[6:7], v[2:3], v[6:7] op_sel:[1,0]
	v_pk_add_f32 v[24:25], v[24:25], v[2:3] op_sel_hi:[1,0] neg_lo:[0,1] neg_hi:[0,1]
	v_pk_fma_f32 v[6:7], v[40:41], v[6:7], v[42:43]
	v_pk_mul_f32 v[2:3], v[2:3], v[24:25] op_sel:[1,0]
	v_and_b32_sdwa v24, v6, v216 dst_sel:DWORD dst_unused:UNUSED_PAD src0_sel:WORD_1 src1_sel:DWORD
	v_pk_fma_f32 v[2:3], v[0:1], v[2:3], v[4:5]
	v_add3_u32 v24, v6, v24, s78
	v_and_b32_e32 v26, 0xffff0000, v24
	v_and_b32_sdwa v24, v3, v216 dst_sel:DWORD dst_unused:UNUSED_PAD src0_sel:WORD_1 src1_sel:DWORD
	v_and_b32_sdwa v23, v7, v216 dst_sel:DWORD dst_unused:UNUSED_PAD src0_sel:WORD_1 src1_sel:DWORD
	v_and_b32_sdwa v25, v2, v216 dst_sel:DWORD dst_unused:UNUSED_PAD src0_sel:WORD_1 src1_sel:DWORD
	v_add3_u32 v24, v3, v24, s78
	v_add3_u32 v23, v7, v23, s78
	v_add3_u32 v27, v2, v25, s78
	v_and_b32_e32 v36, 0xffff0000, v24
	v_or_b32_sdwa v25, v36, v23 dst_sel:DWORD dst_unused:UNUSED_PAD src0_sel:DWORD src1_sel:WORD_1
	v_or_b32_sdwa v24, v27, v26 dst_sel:DWORD dst_unused:UNUSED_PAD src0_sel:WORD_1 src1_sel:DWORD
	ds_write_b64 v101, v[24:25]
	v_and_b32_e32 v24, 0xffff0000, v27
	v_sub_u32_e32 v6, v6, v26
	v_and_b32_e32 v23, 0xffff0000, v23
	v_sub_u32_e32 v2, v2, v24
	v_add_u32_e32 v6, 0x80, v6
	v_sub_u32_e32 v7, v7, v23
	v_sub_u32_e32 v3, v3, v36
	v_add_u32_e32 v2, 0x80, v2
	v_ashrrev_i32_e32 v6, 8, v6
	v_add_u32_e32 v7, 0x80, v7
	v_add_u32_e32 v3, 0x80, v3
	v_ashrrev_i32_e32 v2, 8, v2
	v_min_i32_e32 v6, 0x7f, v6
	v_ashrrev_i32_e32 v7, 8, v7
	v_ashrrev_i32_e32 v3, 8, v3
	v_min_i32_e32 v2, 0x7f, v2
	v_min_i32_sdwa v7, v7, s79 dst_sel:WORD_1 dst_unused:UNUSED_PAD src0_sel:DWORD src1_sel:DWORD
	v_min_i32_e32 v3, 0x7f, v3
	v_lshlrev_b32_e32 v6, 8, v6
	v_and_b32_e32 v6, 0xff00, v6
	v_and_b32_e32 v7, 0xff0000, v7
	v_perm_b32 v2, v3, v2, s80
	v_or3_b32 v2, v2, v6, v7
	ds_write_b32 v20, v2 offset:128
	buffer_store_dwordx4 v[184:187], v91, s[20:23], s0 offen
	v_mov_b32_e32 v2, v252
	v_mov_b32_e32 v3, v253
	v_pk_add_f32 v[6:7], v[30:31], v[2:3] op_sel_hi:[1,0] neg_lo:[0,1] neg_hi:[0,1]
	s_nop 0
	v_pk_mul_f32 v[6:7], v[2:3], v[6:7] op_sel:[1,0]
	v_pk_add_f32 v[24:25], v[28:29], v[2:3] op_sel_hi:[1,0] neg_lo:[0,1] neg_hi:[0,1]
	v_pk_fma_f32 v[6:7], v[40:41], v[6:7], v[42:43]
	v_pk_mul_f32 v[2:3], v[2:3], v[24:25] op_sel:[1,0]
	s_nop 0
	v_pk_fma_f32 v[0:1], v[0:1], v[2:3], v[4:5]
	v_and_b32_sdwa v2, v7, v216 dst_sel:DWORD dst_unused:UNUSED_PAD src0_sel:WORD_1 src1_sel:DWORD
	v_and_b32_sdwa v3, v6, v216 dst_sel:DWORD dst_unused:UNUSED_PAD src0_sel:WORD_1 src1_sel:DWORD
	v_add3_u32 v4, v7, v2, s78
	v_add3_u32 v2, v6, v3, s78
	v_and_b32_e32 v5, 0xffff0000, v2
	v_and_b32_sdwa v2, v1, v216 dst_sel:DWORD dst_unused:UNUSED_PAD src0_sel:WORD_1 src1_sel:DWORD
	v_and_b32_sdwa v3, v0, v216 dst_sel:DWORD dst_unused:UNUSED_PAD src0_sel:WORD_1 src1_sel:DWORD
	v_add3_u32 v2, v1, v2, s78
	v_add3_u32 v23, v0, v3, s78
	v_and_b32_e32 v24, 0xffff0000, v2
	v_or_b32_sdwa v3, v24, v4 dst_sel:DWORD dst_unused:UNUSED_PAD src0_sel:DWORD src1_sel:WORD_1
	v_or_b32_sdwa v2, v23, v5 dst_sel:DWORD dst_unused:UNUSED_PAD src0_sel:WORD_1 src1_sel:DWORD
	ds_write_b64 v92, v[2:3]
	v_and_b32_e32 v2, 0xffff0000, v23
	v_sub_u32_e32 v0, v0, v2
	v_sub_u32_e32 v2, v6, v5
	v_and_b32_e32 v3, 0xffff0000, v4
	v_add_u32_e32 v2, 0x80, v2
	v_sub_u32_e32 v3, v7, v3
	v_sub_u32_e32 v1, v1, v24
	v_add_u32_e32 v0, 0x80, v0
	v_ashrrev_i32_e32 v2, 8, v2
	v_add_u32_e32 v3, 0x80, v3
	v_add_u32_e32 v1, 0x80, v1
	v_ashrrev_i32_e32 v0, 8, v0
	v_min_i32_e32 v2, 0x7f, v2
	v_ashrrev_i32_e32 v3, 8, v3
	v_ashrrev_i32_e32 v1, 8, v1
	v_min_i32_e32 v0, 0x7f, v0
	v_min_i32_sdwa v3, v3, s79 dst_sel:WORD_1 dst_unused:UNUSED_PAD src0_sel:DWORD src1_sel:DWORD
	v_min_i32_e32 v1, 0x7f, v1
	v_lshlrev_b32_e32 v2, 8, v2
	v_and_b32_e32 v2, 0xff00, v2
	v_and_b32_e32 v3, 0xff0000, v3
	v_perm_b32 v0, v1, v0, s80
	v_or3_b32 v0, v0, v2, v3
	ds_write_b32 v22, v0 offset:128
	buffer_store_dwordx4 v[188:191], v95, s[20:23], s0 offen
	v_mov_b32_e32 v0, v232
	v_mov_b32_e32 v1, v233
	v_mov_b32_e32 v2, v234
	v_mov_b32_e32 v3, v235
	v_mov_b32_e32 v4, v248
	v_mov_b32_e32 v5, v249
	v_mov_b32_e32 v6, v250
	v_mov_b32_e32 v7, v251
	v_mov_b32_e32 v28, v210
	v_mov_b32_e32 v29, v211
	s_mov_b64 s[4:5], -1
	v_pk_add_f32 v[30:31], v[50:51], v[28:29] op_sel_hi:[1,0] neg_lo:[0,1] neg_hi:[0,1]
	s_nop 0
	v_pk_mul_f32 v[30:31], v[28:29], v[30:31] op_sel:[1,0]
	v_pk_add_f32 v[36:37], v[48:49], v[28:29] op_sel_hi:[1,0] neg_lo:[0,1] neg_hi:[0,1]
	v_mov_b32_e32 v24, v1
	v_mov_b32_e32 v25, v2
	v_mov_b32_e32 v26, v5
	v_mov_b32_e32 v27, v6
	v_pk_fma_f32 v[30:31], v[24:25], v[30:31], v[26:27]
	v_pk_mul_f32 v[28:29], v[28:29], v[36:37] op_sel:[1,0]
	v_mov_b32_e32 v1, v3
	v_mov_b32_e32 v5, v7
	v_and_b32_sdwa v6, v31, v216 dst_sel:DWORD dst_unused:UNUSED_PAD src0_sel:WORD_1 src1_sel:DWORD
	v_and_b32_sdwa v7, v30, v216 dst_sel:DWORD dst_unused:UNUSED_PAD src0_sel:WORD_1 src1_sel:DWORD
	v_pk_fma_f32 v[2:3], v[0:1], v[28:29], v[4:5]
	v_add3_u32 v23, v31, v6, s78
	v_add3_u32 v6, v30, v7, s78
	v_and_b32_e32 v28, 0xffff0000, v6
	v_and_b32_sdwa v6, v3, v216 dst_sel:DWORD dst_unused:UNUSED_PAD src0_sel:WORD_1 src1_sel:DWORD
	v_and_b32_sdwa v7, v2, v216 dst_sel:DWORD dst_unused:UNUSED_PAD src0_sel:WORD_1 src1_sel:DWORD
	v_add3_u32 v6, v3, v6, s78
	v_add3_u32 v29, v2, v7, s78
	v_and_b32_e32 v36, 0xffff0000, v6
	v_or_b32_sdwa v7, v36, v23 dst_sel:DWORD dst_unused:UNUSED_PAD src0_sel:DWORD src1_sel:WORD_1
; #define WAIT_L(n) asm volatile("s_waitcnt lgkmcnt(" #n ")" ::: "memory")
; #define BAR __builtin_amdgcn_s_barrier()
;     ...
;           _Pragma("unroll") for (int bj = 0; bj < 2; ++bj) _Pragma("unroll") for (int n = 0; n < 2; ++n) {
;             const int cc = bj * HALF + wc3 * 32 + n * 16 + fq3 * 4;
;             const float4 gm = *reinterpret_cast<const float4*>(g.gam + pn * BM + cc), bt = *reinterpret_cast<const float4*>(g.bet + pn * BM + cc);
;             _Pragma("unroll") for (int m = 0; m < 4; ++m) {
;               const int rr = wr3 * 64 + m * 16 + fr3;
;               const float2 ms = *reinterpret_cast<const float2*>(mr + (ai * HALF + rr) * 2);
;               f32x4 y = acc[ai][bj][m][n];
;               const float o0 = (y[0] - ms.x) * ms.y * gm.x + bt.x, o1 = (y[1] - ms.x) * ms.y * gm.y + bt.y;
;               const float o2 = (y[2] - ms.x) * ms.y * gm.z + bt.z, o3 = (y[3] - ms.x) * ms.y * gm.w + bt.w;
;               const unsigned h0 = f2bf(o0), h1 = f2bf(o1), h2 = f2bf(o2), h3 = f2bf(o3);
;               u32x2 ob; ob[0] = h0 | (h1 << 16); ob[1] = h2 | (h3 << 16);
;               *reinterpret_cast<u32x2*>(smem + (rr >> 1) * PIECE + (rr & 1) * 512 + cc * 2) = ob;
;               const int l0 = min(((int)__float_as_uint(o0) - (int)(h0 << 16) + 128) >> 8, 127);
;               const int l1 = min(((int)__float_as_uint(o1) - (int)(h1 << 16) + 128) >> 8, 127);
;               const int l2 = min(((int)__float_as_uint(o2) - (int)(h2 << 16) + 128) >> 8, 127);
;               const int l3 = min(((int)__float_as_uint(o3) - (int)(h3 << 16) + 128) >> 8, 127);
;               *reinterpret_cast<unsigned*>(smem + LOBASE + (rr >> 2) * PIECE + (rr & 3) * 256 + cc) =
;                   (unsigned)(l0 & 255) | ((unsigned)(l1 & 255) << 8) | ((unsigned)(l2 & 255) << 16) | ((unsigned)l3 << 24);
;             }
;           }
;           WAIT_L(0); BAR;
	v_or_b32_sdwa v6, v29, v28 dst_sel:DWORD dst_unused:UNUSED_PAD src0_sel:WORD_1 src1_sel:DWORD
	ds_write_b64 v93, v[6:7]
	v_and_b32_e32 v6, 0xffff0000, v29
	v_sub_u32_e32 v2, v2, v6
	v_sub_u32_e32 v6, v30, v28
	v_and_b32_e32 v7, 0xffff0000, v23
	v_add_u32_e32 v6, 0x80, v6
	v_sub_u32_e32 v7, v31, v7
	v_sub_u32_e32 v3, v3, v36
	v_add_u32_e32 v2, 0x80, v2
	v_ashrrev_i32_e32 v6, 8, v6
	v_add_u32_e32 v7, 0x80, v7
	v_add_u32_e32 v3, 0x80, v3
	v_ashrrev_i32_e32 v2, 8, v2
	v_min_i32_e32 v6, 0x7f, v6
	v_ashrrev_i32_e32 v7, 8, v7
	v_ashrrev_i32_e32 v3, 8, v3
	v_min_i32_e32 v2, 0x7f, v2
	v_min_i32_sdwa v7, v7, s79 dst_sel:WORD_1 dst_unused:UNUSED_PAD src0_sel:DWORD src1_sel:DWORD
	v_min_i32_e32 v3, 0x7f, v3
	v_lshlrev_b32_e32 v6, 8, v6
	v_and_b32_e32 v6, 0xff00, v6
	v_and_b32_e32 v7, 0xff0000, v7
	v_perm_b32 v2, v3, v2, s80
	v_or3_b32 v2, v2, v6, v7
	ds_write_b32 v12, v2 offset:144
	v_mov_b32_e32 v2, v212
	v_mov_b32_e32 v3, v213
	v_pk_add_f32 v[6:7], v[34:35], v[2:3] op_sel_hi:[1,0] neg_lo:[0,1] neg_hi:[0,1]
	s_nop 0
	v_pk_mul_f32 v[6:7], v[2:3], v[6:7] op_sel:[1,0]
	v_pk_add_f32 v[12:13], v[32:33], v[2:3] op_sel_hi:[1,0] neg_lo:[0,1] neg_hi:[0,1]
	v_pk_fma_f32 v[6:7], v[24:25], v[6:7], v[26:27]
	v_pk_mul_f32 v[2:3], v[2:3], v[12:13] op_sel:[1,0]
	v_and_b32_sdwa v12, v7, v216 dst_sel:DWORD dst_unused:UNUSED_PAD src0_sel:WORD_1 src1_sel:DWORD
	v_and_b32_sdwa v13, v6, v216 dst_sel:DWORD dst_unused:UNUSED_PAD src0_sel:WORD_1 src1_sel:DWORD
	v_pk_fma_f32 v[2:3], v[0:1], v[2:3], v[4:5]
	v_add3_u32 v23, v7, v12, s78
	v_add3_u32 v12, v6, v13, s78
	v_and_b32_e32 v28, 0xffff0000, v12
	v_and_b32_sdwa v12, v3, v216 dst_sel:DWORD dst_unused:UNUSED_PAD src0_sel:WORD_1 src1_sel:DWORD
	v_and_b32_sdwa v13, v2, v216 dst_sel:DWORD dst_unused:UNUSED_PAD src0_sel:WORD_1 src1_sel:DWORD
	v_add3_u32 v12, v3, v12, s78
	v_add3_u32 v29, v2, v13, s78
	v_and_b32_e32 v30, 0xffff0000, v12
	v_or_b32_sdwa v13, v30, v23 dst_sel:DWORD dst_unused:UNUSED_PAD src0_sel:DWORD src1_sel:WORD_1
	v_or_b32_sdwa v12, v29, v28 dst_sel:DWORD dst_unused:UNUSED_PAD src0_sel:WORD_1 src1_sel:DWORD
	ds_write_b64 v94, v[12:13]
	v_and_b32_e32 v12, 0xffff0000, v29
	v_sub_u32_e32 v2, v2, v12
	v_sub_u32_e32 v6, v6, v28
	v_and_b32_e32 v12, 0xffff0000, v23
	v_add_u32_e32 v6, 0x80, v6
	v_sub_u32_e32 v7, v7, v12
	v_sub_u32_e32 v3, v3, v30
	v_add_u32_e32 v2, 0x80, v2
	v_ashrrev_i32_e32 v6, 8, v6
	v_add_u32_e32 v7, 0x80, v7
	v_add_u32_e32 v3, 0x80, v3
	v_ashrrev_i32_e32 v2, 8, v2
	v_min_i32_e32 v6, 0x7f, v6
	v_ashrrev_i32_e32 v7, 8, v7
	v_ashrrev_i32_e32 v3, 8, v3
	v_min_i32_e32 v2, 0x7f, v2
	v_min_i32_sdwa v7, v7, s79 dst_sel:WORD_1 dst_unused:UNUSED_PAD src0_sel:DWORD src1_sel:DWORD
	v_min_i32_e32 v3, 0x7f, v3
	v_lshlrev_b32_e32 v6, 8, v6
	v_and_b32_e32 v6, 0xff00, v6
	v_and_b32_e32 v7, 0xff0000, v7
	v_perm_b32 v2, v3, v2, s80
	v_or3_b32 v2, v2, v6, v7
	ds_write_b32 v14, v2 offset:144
	v_mov_b32_e32 v2, v214
	v_mov_b32_e32 v3, v215
	v_pk_add_f32 v[6:7], v[18:19], v[2:3] op_sel_hi:[1,0] neg_lo:[0,1] neg_hi:[0,1]
	s_nop 0
	v_pk_mul_f32 v[6:7], v[2:3], v[6:7] op_sel:[1,0]
	v_pk_add_f32 v[12:13], v[16:17], v[2:3] op_sel_hi:[1,0] neg_lo:[0,1] neg_hi:[0,1]
	v_pk_fma_f32 v[6:7], v[24:25], v[6:7], v[26:27]
	v_pk_mul_f32 v[2:3], v[2:3], v[12:13] op_sel:[1,0]
	v_and_b32_sdwa v12, v7, v216 dst_sel:DWORD dst_unused:UNUSED_PAD src0_sel:WORD_1 src1_sel:DWORD
	v_and_b32_sdwa v13, v6, v216 dst_sel:DWORD dst_unused:UNUSED_PAD src0_sel:WORD_1 src1_sel:DWORD
	v_pk_fma_f32 v[2:3], v[0:1], v[2:3], v[4:5]
	v_add3_u32 v14, v7, v12, s78
	v_add3_u32 v12, v6, v13, s78
	v_and_b32_e32 v15, 0xffff0000, v12
	v_and_b32_sdwa v12, v3, v216 dst_sel:DWORD dst_unused:UNUSED_PAD src0_sel:WORD_1 src1_sel:DWORD
	v_and_b32_sdwa v13, v2, v216 dst_sel:DWORD dst_unused:UNUSED_PAD src0_sel:WORD_1 src1_sel:DWORD
	v_add3_u32 v12, v3, v12, s78
	v_add3_u32 v16, v2, v13, s78
	v_and_b32_e32 v17, 0xffff0000, v12
	v_or_b32_sdwa v13, v17, v14 dst_sel:DWORD dst_unused:UNUSED_PAD src0_sel:DWORD src1_sel:WORD_1
	v_or_b32_sdwa v12, v16, v15 dst_sel:DWORD dst_unused:UNUSED_PAD src0_sel:WORD_1 src1_sel:DWORD
	ds_write_b64 v80, v[12:13]
	v_and_b32_e32 v12, 0xffff0000, v16
	v_sub_u32_e32 v2, v2, v12
	v_sub_u32_e32 v6, v6, v15
	v_and_b32_e32 v12, 0xffff0000, v14
	v_add_u32_e32 v6, 0x80, v6
	v_sub_u32_e32 v7, v7, v12
	v_sub_u32_e32 v3, v3, v17
	v_add_u32_e32 v2, 0x80, v2
	v_ashrrev_i32_e32 v6, 8, v6
	v_add_u32_e32 v7, 0x80, v7
	v_add_u32_e32 v3, 0x80, v3
	v_ashrrev_i32_e32 v2, 8, v2
	v_min_i32_e32 v6, 0x7f, v6
	v_ashrrev_i32_e32 v7, 8, v7
	v_ashrrev_i32_e32 v3, 8, v3
	v_min_i32_e32 v2, 0x7f, v2
	v_min_i32_sdwa v7, v7, s79 dst_sel:WORD_1 dst_unused:UNUSED_PAD src0_sel:DWORD src1_sel:DWORD
	v_min_i32_e32 v3, 0x7f, v3
	v_lshlrev_b32_e32 v6, 8, v6
	v_and_b32_e32 v6, 0xff00, v6
	v_and_b32_e32 v7, 0xff0000, v7
	v_perm_b32 v2, v3, v2, s80
	v_or3_b32 v2, v2, v6, v7
	ds_write_b32 v20, v2 offset:144
	v_mov_b32_e32 v2, v252
	v_mov_b32_e32 v3, v253
	v_pk_add_f32 v[6:7], v[10:11], v[2:3] op_sel_hi:[1,0] neg_lo:[0,1] neg_hi:[0,1]
	s_nop 0
	v_pk_mul_f32 v[6:7], v[2:3], v[6:7] op_sel:[1,0]
	v_pk_add_f32 v[8:9], v[8:9], v[2:3] op_sel_hi:[1,0] neg_lo:[0,1] neg_hi:[0,1]
	v_pk_fma_f32 v[6:7], v[24:25], v[6:7], v[26:27]
	v_pk_mul_f32 v[2:3], v[2:3], v[8:9] op_sel:[1,0]
	s_nop 0
	v_pk_fma_f32 v[0:1], v[0:1], v[2:3], v[4:5]
	v_and_b32_sdwa v2, v7, v216 dst_sel:DWORD dst_unused:UNUSED_PAD src0_sel:WORD_1 src1_sel:DWORD
	v_and_b32_sdwa v3, v6, v216 dst_sel:DWORD dst_unused:UNUSED_PAD src0_sel:WORD_1 src1_sel:DWORD
	v_add3_u32 v4, v7, v2, s78
	v_add3_u32 v2, v6, v3, s78
	v_and_b32_e32 v5, 0xffff0000, v2
	v_and_b32_sdwa v2, v1, v216 dst_sel:DWORD dst_unused:UNUSED_PAD src0_sel:WORD_1 src1_sel:DWORD
	v_and_b32_sdwa v3, v0, v216 dst_sel:DWORD dst_unused:UNUSED_PAD src0_sel:WORD_1 src1_sel:DWORD
	v_add3_u32 v2, v1, v2, s78
	v_add3_u32 v8, v0, v3, s78
	v_and_b32_e32 v9, 0xffff0000, v2
	v_or_b32_sdwa v3, v9, v4 dst_sel:DWORD dst_unused:UNUSED_PAD src0_sel:DWORD src1_sel:WORD_1
	v_or_b32_sdwa v2, v8, v5 dst_sel:DWORD dst_unused:UNUSED_PAD src0_sel:WORD_1 src1_sel:DWORD
	ds_write_b64 v73, v[2:3]
	v_and_b32_e32 v2, 0xffff0000, v8
	v_sub_u32_e32 v0, v0, v2
	v_sub_u32_e32 v2, v6, v5
	v_and_b32_e32 v3, 0xffff0000, v4
	v_add_u32_e32 v2, 0x80, v2
	v_sub_u32_e32 v3, v7, v3
	v_sub_u32_e32 v1, v1, v9
	v_add_u32_e32 v0, 0x80, v0
	v_ashrrev_i32_e32 v2, 8, v2
	v_add_u32_e32 v3, 0x80, v3
	v_add_u32_e32 v1, 0x80, v1
	v_ashrrev_i32_e32 v0, 8, v0
	v_min_i32_e32 v2, 0x7f, v2
	v_ashrrev_i32_e32 v3, 8, v3
	v_ashrrev_i32_e32 v1, 8, v1
	v_min_i32_e32 v0, 0x7f, v0
	v_min_i32_sdwa v3, v3, s79 dst_sel:WORD_1 dst_unused:UNUSED_PAD src0_sel:DWORD src1_sel:DWORD
	v_min_i32_e32 v1, 0x7f, v1
	v_lshlrev_b32_e32 v2, 8, v2
	v_and_b32_e32 v2, 0xff00, v2
	v_and_b32_e32 v3, 0xff0000, v3
	v_perm_b32 v0, v1, v0, s80
	v_or3_b32 v0, v0, v2, v3
	ds_write_b32 v22, v0 offset:144
	s_waitcnt lgkmcnt(0)
	s_barrier
; #define STAGE(P, RS, SOFF, OFF, kt) do { const int _so = (SOFF) + (kt) * (BK * 2); \
;     _Pragma("unroll") for (int _i = 0; _i < 2; ++_i) { \
;       __builtin_amdgcn_raw_ptr_buffer_load_lds(RS, (__attribute__((address_space(3))) void*)((P) + wave * 1024 + _i * 8192), 16, OFF[_i], _so, 0, 0); } } while (0)
; #define WAIT_L(n) asm volatile("s_waitcnt lgkmcnt(" #n ")" ::: "memory")
; #define BAR __builtin_amdgcn_s_barrier()
;     ...
;   auto issue_prologue = [&](int sA0, int sA1, int sB0, int sB1) {
;     const int tid = opaque_tid(wave);
;     int offA[2], offB[2];
;     _Pragma("unroll") for (int i = 0; i < 2; ++i) {
;       int r, c; stage_rc(tid * 16 + i * 8192, r, c);
;       offA[i] = (r * lda + c) * 2; offB[i] = (r * ldb + c) * 2;
;     }
;     STAGE(SB(0, 0), rsB, sB0, offB, 0); STAGE(SA(0, 0), rsA, sA0, offA, 0);
;     STAGE(SB(0, 1), rsB, sB1, offB, 0); STAGE(SA(0, 1), rsA, sA1, offA, 0);
;     STAGE(SB(1, 0), rsB, sB0, offB, 1); STAGE(SA(1, 0), rsA, sA0, offA, 1); STAGE(SB(1, 1), rsB, sB1, offB, 1);
;   };
;     ...
;           WAIT_L(0); BAR;
;           const int hso = ((brow + ai * HALF + 16 * wave) * DM + pn * BM) * 2;
;           const int lso = (brow + ai * HALF + 16 * wave) * DM + pn * BM;
;           _Pragma("unroll") for (int i = 0; i < 8; ++i) {
;             const u32x4 v = *reinterpret_cast<const u32x4*>(smem + (wave * 8 + i) * PIECE + lane3 * 16);
;             __builtin_amdgcn_raw_buffer_store_b128(v, rsXB, hvo + i * (2 * DM * 2), hso, 0);
;           }
;           _Pragma("unroll") for (int i = 0; i < 4; ++i) {
;             const u32x4 v = *reinterpret_cast<const u32x4*>(smem + LOBASE + (wave * 4 + i) * PIECE + lane3 * 16);
;             __builtin_amdgcn_raw_buffer_store_b128(v, rsLO, lvo + i * (4 * DM), lso, 0);
;           }
;           WAIT_L(0); BAR;
	ds_read_b128 v[128:131], v72
	ds_read_b128 v[132:135], v72 offset:1040
	ds_read_b128 v[136:139], v72 offset:2080
	ds_read_b128 v[140:143], v72 offset:3120
	ds_read_b128 v[152:155], v72 offset:4160
	ds_read_b128 v[156:159], v72 offset:5200
	ds_read_b128 v[160:163], v72 offset:6240
	ds_read_b128 v[164:167], v72 offset:7280
	ds_read_b128 v[168:171], v147
	ds_read_b128 v[172:175], v147 offset:1040
	ds_read_b128 v[176:179], v147 offset:2080
	ds_read_b128 v[180:183], v147 offset:3120
	s_waitcnt lgkmcnt(0)
	s_barrier
	s_cbranch_vccnz .Lmy_s1n_480
	v_mbcnt_lo_u32_b32 v0, -1, 0
	v_mbcnt_hi_u32_b32 v0, -1, v0
	s_mov_b32 m0, s37
	v_lshl_add_u32 v0, v0, 4, s35
	v_ashrrev_i32_e32 v1, 31, v0
	v_lshrrev_b32_e32 v1, 22, v1
	v_add_u32_e32 v1, v0, v1
	v_ashrrev_i32_e32 v1, 10, v1
	v_mul_i32_i24_e32 v2, 0x400, v1
	v_sub_u32_e32 v2, v0, v2
	v_lshrrev_b32_e32 v3, 4, v2
	v_bitop3_b32 v2, v3, v2, 32 bitop3:0x6c
	v_ashrrev_i32_e32 v4, 31, v2
	v_lshrrev_b32_e32 v4, 26, v4
	v_add_u32_e32 v4, v2, v4
	v_lshrrev_b32_e32 v5, 6, v4
	v_and_b32_e32 v4, 0xc0, v4
	v_lshlrev_b32_e32 v3, 3, v1
	v_lshlrev_b32_e32 v1, 5, v1
	v_sub_u32_e32 v2, v2, v4
	v_and_b32_e32 v3, 0x7fff0, v3
	v_and_b32_e32 v1, 32, v1
	v_ashrrev_i16_sdwa v2, v216, sext(v2) dst_sel:DWORD dst_unused:UNUSED_PAD src0_sel:DWORD src1_sel:BYTE_0
	v_add_u32_sdwa v1, v1, sext(v2) dst_sel:DWORD dst_unused:UNUSED_PAD src0_sel:DWORD src1_sel:WORD_0
	v_add_lshl_u32 v2, v5, v3, 13
	v_add_u32_e32 v0, 0x2000, v0
	v_lshl_add_u32 v1, v1, 1, v2
	v_ashrrev_i32_e32 v2, 31, v0
	v_lshrrev_b32_e32 v2, 22, v2
	v_add_u32_e32 v2, v0, v2
	v_ashrrev_i32_e32 v2, 10, v2
	v_mul_i32_i24_e32 v3, 0x400, v2
	v_sub_u32_e32 v0, v0, v3
	v_lshrrev_b32_e32 v3, 4, v0
	v_bitop3_b32 v0, v3, v0, 32 bitop3:0x6c
	v_ashrrev_i32_e32 v4, 31, v0
	v_lshrrev_b32_e32 v4, 26, v4
	v_add_u32_e32 v4, v0, v4
	v_lshrrev_b32_e32 v5, 6, v4
	v_and_b32_e32 v4, 0xffc0, v4
	v_sub_u32_e32 v0, v0, v4
	v_lshrrev_b16_e32 v4, 7, v0
	v_and_b32_e32 v4, 1, v4
	v_lshlrev_b32_e32 v3, 3, v2
	v_lshlrev_b32_e32 v2, 5, v2
	v_add_u16_e32 v0, v0, v4
	v_and_b32_e32 v3, 0x7fff0, v3
	v_and_b32_e32 v2, 32, v2
	v_ashrrev_i16_sdwa v0, v216, sext(v0) dst_sel:DWORD dst_unused:UNUSED_PAD src0_sel:DWORD src1_sel:BYTE_0
	v_add_u32_sdwa v0, v2, sext(v0) dst_sel:DWORD dst_unused:UNUSED_PAD src0_sel:DWORD src1_sel:WORD_0
	v_add_lshl_u32 v2, v5, v3, 13
	s_mov_b32 s14, s10
	s_mov_b32 s15, s11
	v_lshl_add_u32 v0, v0, 1, v2
	buffer_load_dwordx4 v1, s[12:15], s84 offen lds
	s_mov_b32 m0, s70
	s_or_b32 s0, s84, 0x80
	buffer_load_dwordx4 v0, s[12:15], s84 offen lds
	s_mov_b32 m0, s35
	s_mov_b64 s[4:5], 0
	buffer_load_dwordx4 v1, s[8:11], s83 offen lds
	s_mov_b32 m0, s95
	s_nop 0
	buffer_load_dwordx4 v0, s[8:11], s83 offen lds
	s_mov_b32 m0, s38
	s_nop 0
	buffer_load_dwordx4 v1, s[12:15], s85 offen lds
	s_mov_b32 m0, s71
	s_nop 0
	buffer_load_dwordx4 v0, s[12:15], s85 offen lds
	s_mov_b32 m0, s39
	s_nop 0
	buffer_load_dwordx4 v1, s[8:11], s82 offen lds
	s_mov_b32 m0, s97
	s_nop 0
	buffer_load_dwordx4 v0, s[8:11], s82 offen lds
	s_mov_b32 m0, s92
	s_nop 0
	buffer_load_dwordx4 v1, s[12:15], s0 offen lds
	s_mov_b32 m0, s56
	s_nop 0
	buffer_load_dwordx4 v0, s[12:15], s0 offen lds
	s_or_b32 s0, s83, 0x80
	s_mov_b32 m0, s93
	s_nop 0
	buffer_load_dwordx4 v1, s[8:11], s0 offen lds
	s_mov_b32 m0, s57
	s_nop 0
	buffer_load_dwordx4 v0, s[8:11], s0 offen lds
	s_add_i32 s0, s85, 0x80
	s_mov_b32 m0, s94
	s_nop 0
	buffer_load_dwordx4 v1, s[12:15], s0 offen lds
	s_mov_b32 m0, s58
	s_nop 0
	buffer_load_dwordx4 v0, s[12:15], s0 offen lds
	buffer_store_dwordx4 v[128:131], v148, s[16:19], s3 offen
	buffer_store_dwordx4 v[132:135], v74, s[16:19], s3 offen
	buffer_store_dwordx4 v[136:139], v75, s[16:19], s3 offen
	buffer_store_dwordx4 v[140:143], v81, s[16:19], s3 offen
	buffer_store_dwordx4 v[152:155], v82, s[16:19], s3 offen
	buffer_store_dwordx4 v[156:159], v83, s[16:19], s3 offen
	buffer_store_dwordx4 v[160:163], v88, s[16:19], s3 offen
	buffer_store_dwordx4 v[164:167], v89, s[16:19], s3 offen
	buffer_store_dwordx4 v[168:171], v146, s[20:23], s1 offen
	buffer_store_dwordx4 v[172:175], v90, s[20:23], s1 offen
	buffer_store_dwordx4 v[176:179], v91, s[20:23], s1 offen
	buffer_store_dwordx4 v[180:183], v95, s[20:23], s1 offen
	s_branch .LBB0_486

;     ...
;       __syncthreads();
;       const int tid3 = opaque_tid(wave);
;       const int wr3 = tid3 >> 8, wc3 = (tid3 >> 6) & 3, fr3 = tid3 & 15, fq3 = (tid3 & 63) >> 4;
;       const int ebase3 = (brow + wr3 * 64 + fr3) * DM + pn * BM + wc3 * 32 + fq3 * 4;
;       const int vo4b = ebase3 * 4, vo2 = ebase3 * 2, vo1 = ebase3;
;       (void)vo4b; (void)vo2; (void)vo1;
;       if constexpr (OUTF) {
;         _Pragma("unroll") for (int bj = 0; bj < 2; ++bj) _Pragma("unroll") for (int n = 0; n < 2; ++n) {
;           const int col = pn * BM + bj * HALF + wc3 * 32 + n * 16 + fq3 * 4;
;           const float4 gm = *reinterpret_cast<const float4*>(g.gam + col), bt = *reinterpret_cast<const float4*>(g.bet + col);
;           _Pragma("unroll") for (int ai = 0; ai < 2; ++ai) _Pragma("unroll") for (int m = 0; m < 4; ++m) {
;             const int rl = ai * HALF + wr3 * 64 + m * 16 + fr3;
;             const float2 ms = *reinterpret_cast<const float2*>(mr + rl * 2);
;             f32x4 y = acc[ai][bj][m][n];
;             u32x4 o;
;             o[0] = __float_as_uint((y[0] - ms.x) * ms.y * gm.x + bt.x); o[1] = __float_as_uint((y[1] - ms.x) * ms.y * gm.y + bt.y);
;             o[2] = __float_as_uint((y[2] - ms.x) * ms.y * gm.z + bt.z); o[3] = __float_as_uint((y[3] - ms.x) * ms.y * gm.w + bt.w);
;             __builtin_amdgcn_raw_buffer_store_b128(o, rsO, vo4b + ((ai * HALF + m * 16) * DM + bj * HALF + n * 16) * 4, 0, 0);
;           }
;         }
;       } else {
;         constexpr int PIECE = 1024 + 16, LOBASE = 64 * PIECE;
;         const int lane3 = tid3 & 63;
;         const int hvo = (lane3 >> 5) * (DM * 2) + (lane3 & 31) * 16;
;         const int lvo = (lane3 >> 4) * DM + (lane3 & 15) * 16;
;         _Pragma("unroll") for (int ai = 0; ai < 2; ++ai) {
;           _Pragma("unroll") for (int bj = 0; bj < 2; ++bj) _Pragma("unroll") for (int n = 0; n < 2; ++n) {
;             const int cc = bj * HALF + wc3 * 32 + n * 16 + fq3 * 4;
;             const float4 gm = *reinterpret_cast<const float4*>(g.gam + pn * BM + cc), bt = *reinterpret_cast<const float4*>(g.bet + pn * BM + cc);
;             _Pragma("unroll") for (int m = 0; m < 4; ++m) {
;               const int rr = wr3 * 64 + m * 16 + fr3;
;               const float2 ms = *reinterpret_cast<const float2*>(mr + (ai * HALF + rr) * 2);
;               f32x4 y = acc[ai][bj][m][n];
.LBB0_686:
	s_or_b64 exec, exec, s[6:7]
	s_waitcnt lgkmcnt(0)
	s_barrier
	v_mbcnt_lo_u32_b32 v0, -1, 0
	v_mbcnt_hi_u32_b32 v0, -1, v0
	s_ashr_i32 s35, s34, 31
	v_add_u32_e32 v1, s37, v0
	v_bfe_u32 v4, v0, 4, 2
	v_ashrrev_i32_e32 v5, 2, v1
	v_lshrrev_b32_e32 v6, 1, v1
	v_lshlrev_b32_e32 v1, 4, v1
	v_readlane_b32 s40, v255, 16
	v_lshlrev_b32_e32 v7, 2, v4
	v_lshlrev_b32_e32 v12, 7, v0
	v_and_b32_e32 v13, 0x1f0, v1
	s_movk_i32 s2, 0x60
	s_lshl_b64 s[4:5], s[34:35], 2
	v_readlane_b32 s50, v255, 26
	v_and_or_b32 v148, v12, s72, v13
	v_and_or_b32 v12, v6, s2, v7
	v_readlane_b32 s51, v255, 27
	s_add_u32 s6, s50, s4
	v_and_b32_e32 v2, 15, v0
	v_and_b32_e32 v3, 63, v0
	v_and_b32_e32 v1, 0xf0, v1
	v_lshlrev_b32_e32 v13, 9, v0
	v_lshlrev_b32_e32 v0, 8, v0
	s_addc_u32 s7, s51, s5
	v_lshlrev_b32_e32 v150, 2, v12
	v_lshl_or_b32 v146, v4, 11, v1
	v_and_or_b32 v155, v5, s36, v2
	v_and_b32_e32 v14, 0x300, v0
	v_lshlrev_b32_e32 v151, 4, v3
	global_load_dwordx4 v[220:223], v150, s[6:7]
	global_load_dwordx4 v[224:227], v150, s[6:7] offset:64
	global_load_dwordx4 v[228:231], v150, s[6:7] offset:512
	global_load_dwordx4 v[232:235], v150, s[6:7] offset:576
	v_readlane_b32 s52, v255, 28
	v_readlane_b32 s53, v255, 29
	s_add_u32 s4, s52, s4
	s_addc_u32 s5, s53, s5
	global_load_dwordx4 v[236:239], v150, s[4:5]
	global_load_dwordx4 v[240:243], v150, s[4:5] offset:64
	global_load_dwordx4 v[244:247], v150, s[4:5] offset:512
	global_load_dwordx4 v[248:251], v150, s[4:5] offset:576
	s_movk_i32 s22, 0x200
	v_lshl_add_u32 v149, v155, 3, v219
	v_add_u32_e32 v147, s68, v151
	s_andn2_b64 vcc, exec, s[14:15]
	v_readlane_b32 s41, v255, 17
	v_readlane_b32 s42, v255, 18
	v_readlane_b32 s43, v255, 19
	v_readlane_b32 s44, v255, 20
	v_readlane_b32 s45, v255, 21
	v_readlane_b32 s46, v255, 22
	v_readlane_b32 s47, v255, 23
	v_readlane_b32 s48, v255, 24
	v_readlane_b32 s49, v255, 25
	v_readlane_b32 s54, v255, 30
	v_readlane_b32 s55, v255, 31
	s_waitcnt vmcnt(0)
	v_mov_b32_e32 v0, v220
	v_mov_b32_e32 v1, v221
	v_mov_b32_e32 v2, v222
	v_mov_b32_e32 v3, v223
	v_mov_b32_e32 v4, v236
	v_mov_b32_e32 v5, v237
	v_mov_b32_e32 v6, v238
	v_mov_b32_e32 v7, v239
	v_mov_b32_e32 v22, v1
	v_lshlrev_b32_e32 v1, 1, v12
	v_and_or_b32 v154, v13, s22, v1
	s_mov_b32 s22, 0x10400
	v_mov_b32_e32 v23, v2
	v_or3_b32 v2, v14, v12, s22
	ds_read_b64 v[12:13], v149
	v_mov_b32_e32 v144, v5
	v_mov_b32_e32 v145, v6
	v_mov_b32_e32 v1, v3
	v_mov_b32_e32 v5, v7
	s_waitcnt lgkmcnt(0)
	v_mov_b32_e32 v210, v12
	v_mov_b32_e32 v211, v13
	v_pk_add_f32 v[14:15], v[132:133], v[12:13] op_sel_hi:[1,0] neg_lo:[0,1] neg_hi:[0,1]
	v_pk_add_f32 v[18:19], v[130:131], v[12:13] op_sel_hi:[1,0] neg_lo:[0,1] neg_hi:[0,1]
	v_pk_mul_f32 v[14:15], v[12:13], v[14:15] op_sel:[1,0]
	v_pk_mul_f32 v[12:13], v[12:13], v[18:19] op_sel:[1,0]
	v_pk_fma_f32 v[14:15], v[22:23], v[14:15], v[144:145]
	v_pk_fma_f32 v[6:7], v[0:1], v[12:13], v[4:5]
	v_and_b32_sdwa v12, v14, v216 dst_sel:DWORD dst_unused:UNUSED_PAD src0_sel:WORD_1 src1_sel:DWORD
	v_add3_u32 v12, v14, v12, s77
	v_and_b32_e32 v18, 0xffff0000, v12
	v_and_b32_sdwa v12, v7, v216 dst_sel:DWORD dst_unused:UNUSED_PAD src0_sel:WORD_1 src1_sel:DWORD
	v_and_b32_sdwa v3, v15, v216 dst_sel:DWORD dst_unused:UNUSED_PAD src0_sel:WORD_1 src1_sel:DWORD
	v_and_b32_sdwa v13, v6, v216 dst_sel:DWORD dst_unused:UNUSED_PAD src0_sel:WORD_1 src1_sel:DWORD
	v_add3_u32 v12, v7, v12, s77
	v_lshrrev_b32_e32 v131, 1, v155
	v_add3_u32 v3, v15, v3, s77
	v_add3_u32 v19, v6, v13, s77
	v_and_b32_e32 v130, 0xffff0000, v12
	v_mul_lo_u32 v152, v131, s60
	v_or_b32_sdwa v13, v130, v3 dst_sel:DWORD dst_unused:UNUSED_PAD src0_sel:DWORD src1_sel:WORD_1
	v_or_b32_sdwa v12, v19, v18 dst_sel:DWORD dst_unused:UNUSED_PAD src0_sel:WORD_1 src1_sel:DWORD
	v_add_u32_e32 v132, v154, v152
	ds_write_b64 v132, v[12:13]
	v_and_b32_e32 v12, 0xffff0000, v19
	v_sub_u32_e32 v6, v6, v12
	v_sub_u32_e32 v12, v14, v18
	v_and_b32_e32 v3, 0xffff0000, v3
	v_add_u32_e32 v12, 0x80, v12
	v_sub_u32_e32 v3, v15, v3
	v_sub_u32_e32 v7, v7, v130
	v_add_u32_e32 v6, 0x80, v6
	v_ashrrev_i32_e32 v12, 8, v12
	v_add_u32_e32 v3, 0x80, v3
	v_add_u32_e32 v7, 0x80, v7
	v_ashrrev_i32_e32 v6, 8, v6
	v_min_i32_e32 v12, 0x7f, v12
	v_ashrrev_i32_e32 v3, 8, v3
	v_ashrrev_i32_e32 v7, 8, v7
	v_min_i32_e32 v6, 0x7f, v6
	v_min_i32_sdwa v3, v3, s78 dst_sel:WORD_1 dst_unused:UNUSED_PAD src0_sel:DWORD src1_sel:DWORD
	v_min_i32_e32 v7, 0x7f, v7
	v_lshlrev_b32_e32 v12, 8, v12
	v_and_b32_e32 v12, 0xff00, v12
	v_and_b32_e32 v3, 0xff0000, v3
	v_perm_b32 v6, v7, v6, s79
	v_or3_b32 v3, v6, v12, v3
	v_lshrrev_b32_e32 v6, 2, v155
	v_mad_u64_u32 v[12:13], s[22:23], v6, s60, v[2:3]
	ds_write_b32 v12, v3
	v_or_b32_e32 v3, 16, v155
	v_lshl_add_u32 v13, v3, 3, v219
	ds_read_b64 v[6:7], v13
	v_lshrrev_b32_e32 v133, 1, v3
	v_mul_lo_u32 v153, v133, s60
	v_add_u32_e32 v133, v154, v153
	v_lshrrev_b32_e32 v3, 2, v3
	s_waitcnt lgkmcnt(0)
;     ...
;             _Pragma("unroll") for (int m = 0; m < 4; ++m) {
;               const int rr = wr3 * 64 + m * 16 + fr3;
;               const float2 ms = *reinterpret_cast<const float2*>(mr + (ai * HALF + rr) * 2);
;               f32x4 y = acc[ai][bj][m][n];
;               const float o0 = (y[0] - ms.x) * ms.y * gm.x + bt.x, o1 = (y[1] - ms.x) * ms.y * gm.y + bt.y;
;               const float o2 = (y[2] - ms.x) * ms.y * gm.z + bt.z, o3 = (y[3] - ms.x) * ms.y * gm.w + bt.w;
;               const unsigned h0 = f2bf(o0), h1 = f2bf(o1), h2 = f2bf(o2), h3 = f2bf(o3);
;               u32x2 ob; ob[0] = h0 | (h1 << 16); ob[1] = h2 | (h3 << 16);
;               *reinterpret_cast<u32x2*>(smem + (rr >> 1) * PIECE + (rr & 1) * 512 + cc * 2) = ob;
;               const int l0 = min(((int)__float_as_uint(o0) - (int)(h0 << 16) + 128) >> 8, 127);
;               const int l1 = min(((int)__float_as_uint(o1) - (int)(h1 << 16) + 128) >> 8, 127);
;               const int l2 = min(((int)__float_as_uint(o2) - (int)(h2 << 16) + 128) >> 8, 127);
;               const int l3 = min(((int)__float_as_uint(o3) - (int)(h3 << 16) + 128) >> 8, 127);
;               *reinterpret_cast<unsigned*>(smem + LOBASE + (rr >> 2) * PIECE + (rr & 3) * 256 + cc) =
;                   (unsigned)(l0 & 255) | ((unsigned)(l1 & 255) << 8) | ((unsigned)(l2 & 255) << 16) | ((unsigned)l3 << 24);
;             }
	v_mov_b32_e32 v212, v6
	v_mov_b32_e32 v213, v7
	v_pk_add_f32 v[14:15], v[122:123], v[6:7] op_sel_hi:[1,0] neg_lo:[0,1] neg_hi:[0,1]
	v_pk_add_f32 v[18:19], v[134:135], v[6:7] op_sel_hi:[1,0] neg_lo:[0,1] neg_hi:[0,1]
	v_pk_mul_f32 v[14:15], v[6:7], v[14:15] op_sel:[1,0]
	v_pk_mul_f32 v[6:7], v[6:7], v[18:19] op_sel:[1,0]
	v_pk_fma_f32 v[14:15], v[22:23], v[14:15], v[144:145]
	v_pk_fma_f32 v[6:7], v[0:1], v[6:7], v[4:5]
	v_and_b32_sdwa v18, v15, v216 dst_sel:DWORD dst_unused:UNUSED_PAD src0_sel:WORD_1 src1_sel:DWORD
	v_and_b32_sdwa v19, v14, v216 dst_sel:DWORD dst_unused:UNUSED_PAD src0_sel:WORD_1 src1_sel:DWORD
	v_add3_u32 v122, v15, v18, s77
	v_add3_u32 v18, v14, v19, s77
	v_and_b32_e32 v123, 0xffff0000, v18
	v_and_b32_sdwa v18, v7, v216 dst_sel:DWORD dst_unused:UNUSED_PAD src0_sel:WORD_1 src1_sel:DWORD
	v_and_b32_sdwa v19, v6, v216 dst_sel:DWORD dst_unused:UNUSED_PAD src0_sel:WORD_1 src1_sel:DWORD
	v_add3_u32 v18, v7, v18, s77
	v_add3_u32 v130, v6, v19, s77
	v_and_b32_e32 v131, 0xffff0000, v18
	v_or_b32_sdwa v19, v131, v122 dst_sel:DWORD dst_unused:UNUSED_PAD src0_sel:DWORD src1_sel:WORD_1
	v_or_b32_sdwa v18, v130, v123 dst_sel:DWORD dst_unused:UNUSED_PAD src0_sel:WORD_1 src1_sel:DWORD
	ds_write_b64 v133, v[18:19]
	v_and_b32_e32 v18, 0xffff0000, v130
	v_sub_u32_e32 v6, v6, v18
	v_sub_u32_e32 v14, v14, v123
	v_and_b32_e32 v18, 0xffff0000, v122
	v_add_u32_e32 v14, 0x80, v14
	v_sub_u32_e32 v15, v15, v18
	v_sub_u32_e32 v7, v7, v131
	v_add_u32_e32 v6, 0x80, v6
	v_ashrrev_i32_e32 v14, 8, v14
	v_add_u32_e32 v15, 0x80, v15
	v_add_u32_e32 v7, 0x80, v7
	v_ashrrev_i32_e32 v6, 8, v6
	v_min_i32_e32 v14, 0x7f, v14
	v_ashrrev_i32_e32 v15, 8, v15
	v_ashrrev_i32_e32 v7, 8, v7
	v_min_i32_e32 v6, 0x7f, v6
	v_min_i32_sdwa v15, v15, s78 dst_sel:WORD_1 dst_unused:UNUSED_PAD src0_sel:DWORD src1_sel:DWORD
	v_min_i32_e32 v7, 0x7f, v7
	v_lshlrev_b32_e32 v14, 8, v14
	v_and_b32_e32 v14, 0xff00, v14
	v_and_b32_e32 v15, 0xff0000, v15
	v_perm_b32 v6, v7, v6, s79
	v_or3_b32 v6, v6, v14, v15
	v_mad_u64_u32 v[14:15], s[22:23], v3, s60, v[2:3]
	v_or_b32_e32 v3, 32, v155
	ds_write_b32 v14, v6
	v_lshl_add_u32 v15, v3, 3, v219
	ds_read_b64 v[6:7], v15
	v_lshrrev_b32_e32 v134, 1, v3
	v_lshrrev_b32_e32 v3, 2, v3
	s_waitcnt lgkmcnt(0)
	v_mov_b32_e32 v214, v6
	v_mov_b32_e32 v215, v7
	v_pk_add_f32 v[18:19], v[136:137], v[6:7] op_sel_hi:[1,0] neg_lo:[0,1] neg_hi:[0,1]
	s_nop 0
	v_pk_mul_f32 v[18:19], v[6:7], v[18:19] op_sel:[1,0]
	v_pk_add_f32 v[122:123], v[138:139], v[6:7] op_sel_hi:[1,0] neg_lo:[0,1] neg_hi:[0,1]
	v_pk_fma_f32 v[18:19], v[22:23], v[18:19], v[144:145]
	v_pk_mul_f32 v[6:7], v[6:7], v[122:123] op_sel:[1,0]
	v_and_b32_sdwa v122, v19, v216 dst_sel:DWORD dst_unused:UNUSED_PAD src0_sel:WORD_1 src1_sel:DWORD
	v_and_b32_sdwa v123, v18, v216 dst_sel:DWORD dst_unused:UNUSED_PAD src0_sel:WORD_1 src1_sel:DWORD
	v_pk_fma_f32 v[6:7], v[0:1], v[6:7], v[4:5]
	v_add3_u32 v130, v19, v122, s77
	v_add3_u32 v122, v18, v123, s77
	v_and_b32_e32 v131, 0xffff0000, v122
	v_and_b32_sdwa v122, v7, v216 dst_sel:DWORD dst_unused:UNUSED_PAD src0_sel:WORD_1 src1_sel:DWORD
	v_and_b32_sdwa v123, v6, v216 dst_sel:DWORD dst_unused:UNUSED_PAD src0_sel:WORD_1 src1_sel:DWORD
	v_add3_u32 v122, v7, v122, s77
	v_add3_u32 v135, v6, v123, s77
	v_and_b32_e32 v136, 0xffff0000, v122
	v_mul_lo_u32 v137, v134, s60
	v_or_b32_sdwa v123, v136, v130 dst_sel:DWORD dst_unused:UNUSED_PAD src0_sel:DWORD src1_sel:WORD_1
	v_or_b32_sdwa v122, v135, v131 dst_sel:DWORD dst_unused:UNUSED_PAD src0_sel:WORD_1 src1_sel:DWORD
	v_add_u32_e32 v134, v154, v137
	ds_write_b64 v134, v[122:123]
	v_and_b32_e32 v122, 0xffff0000, v135
	v_sub_u32_e32 v6, v6, v122
	v_sub_u32_e32 v18, v18, v131
	v_and_b32_e32 v122, 0xffff0000, v130
	v_add_u32_e32 v18, 0x80, v18
	v_sub_u32_e32 v19, v19, v122
	v_sub_u32_e32 v7, v7, v136
	v_add_u32_e32 v6, 0x80, v6
	v_ashrrev_i32_e32 v18, 8, v18
	v_add_u32_e32 v19, 0x80, v19
	v_add_u32_e32 v7, 0x80, v7
	v_ashrrev_i32_e32 v6, 8, v6
	v_min_i32_e32 v18, 0x7f, v18
	v_ashrrev_i32_e32 v19, 8, v19
	v_ashrrev_i32_e32 v7, 8, v7
	v_min_i32_e32 v6, 0x7f, v6
	v_min_i32_sdwa v19, v19, s78 dst_sel:WORD_1 dst_unused:UNUSED_PAD src0_sel:DWORD src1_sel:DWORD
	v_min_i32_e32 v7, 0x7f, v7
	v_lshlrev_b32_e32 v18, 8, v18
	v_and_b32_e32 v18, 0xff00, v18
	v_and_b32_e32 v19, 0xff0000, v19
	v_perm_b32 v6, v7, v6, s79
	v_or3_b32 v6, v6, v18, v19
	v_mad_u64_u32 v[18:19], s[22:23], v3, s60, v[2:3]
	v_or_b32_e32 v3, 48, v155
	ds_write_b32 v18, v6
	v_lshl_add_u32 v19, v3, 3, v219
	ds_read_b64 v[6:7], v19
	v_lshrrev_b32_e32 v130, 1, v3
	v_mul_lo_u32 v136, v130, s60
	v_add_u32_e32 v135, v154, v136
	s_waitcnt lgkmcnt(0)
;     ...
;           _Pragma("unroll") for (int bj = 0; bj < 2; ++bj) _Pragma("unroll") for (int n = 0; n < 2; ++n) {
;             const int cc = bj * HALF + wc3 * 32 + n * 16 + fq3 * 4;
;             const float4 gm = *reinterpret_cast<const float4*>(g.gam + pn * BM + cc), bt = *reinterpret_cast<const float4*>(g.bet + pn * BM + cc);
;             _Pragma("unroll") for (int m = 0; m < 4; ++m) {
;               const int rr = wr3 * 64 + m * 16 + fr3;
;               const float2 ms = *reinterpret_cast<const float2*>(mr + (ai * HALF + rr) * 2);
;               f32x4 y = acc[ai][bj][m][n];
;               const float o0 = (y[0] - ms.x) * ms.y * gm.x + bt.x, o1 = (y[1] - ms.x) * ms.y * gm.y + bt.y;
;               const float o2 = (y[2] - ms.x) * ms.y * gm.z + bt.z, o3 = (y[3] - ms.x) * ms.y * gm.w + bt.w;
;               const unsigned h0 = f2bf(o0), h1 = f2bf(o1), h2 = f2bf(o2), h3 = f2bf(o3);
;               u32x2 ob; ob[0] = h0 | (h1 << 16); ob[1] = h2 | (h3 << 16);
;               *reinterpret_cast<u32x2*>(smem + (rr >> 1) * PIECE + (rr & 1) * 512 + cc * 2) = ob;
;               const int l0 = min(((int)__float_as_uint(o0) - (int)(h0 << 16) + 128) >> 8, 127);
;               const int l1 = min(((int)__float_as_uint(o1) - (int)(h1 << 16) + 128) >> 8, 127);
;               const int l2 = min(((int)__float_as_uint(o2) - (int)(h2 << 16) + 128) >> 8, 127);
;               const int l3 = min(((int)__float_as_uint(o3) - (int)(h3 << 16) + 128) >> 8, 127);
;               *reinterpret_cast<unsigned*>(smem + LOBASE + (rr >> 2) * PIECE + (rr & 3) * 256 + cc) =
;                   (unsigned)(l0 & 255) | ((unsigned)(l1 & 255) << 8) | ((unsigned)(l2 & 255) << 16) | ((unsigned)l3 << 24);
;             }
	v_mov_b32_e32 v252, v6
	v_mov_b32_e32 v253, v7
	v_pk_add_f32 v[122:123], v[140:141], v[6:7] op_sel_hi:[1,0] neg_lo:[0,1] neg_hi:[0,1]
	s_nop 0
	v_pk_mul_f32 v[122:123], v[6:7], v[122:123] op_sel:[1,0]
	s_nop 0
	v_pk_fma_f32 v[22:23], v[22:23], v[122:123], v[144:145]
	v_pk_add_f32 v[122:123], v[142:143], v[6:7] op_sel_hi:[1,0] neg_lo:[0,1] neg_hi:[0,1]
	s_nop 0
	v_pk_mul_f32 v[6:7], v[6:7], v[122:123] op_sel:[1,0]
	s_nop 0
	v_pk_fma_f32 v[0:1], v[0:1], v[6:7], v[4:5]
	v_and_b32_sdwa v4, v23, v216 dst_sel:DWORD dst_unused:UNUSED_PAD src0_sel:WORD_1 src1_sel:DWORD
	v_and_b32_sdwa v5, v22, v216 dst_sel:DWORD dst_unused:UNUSED_PAD src0_sel:WORD_1 src1_sel:DWORD
	v_add3_u32 v6, v23, v4, s77
	v_add3_u32 v4, v22, v5, s77
	v_and_b32_e32 v7, 0xffff0000, v4
	v_and_b32_sdwa v4, v1, v216 dst_sel:DWORD dst_unused:UNUSED_PAD src0_sel:WORD_1 src1_sel:DWORD
	v_and_b32_sdwa v5, v0, v216 dst_sel:DWORD dst_unused:UNUSED_PAD src0_sel:WORD_1 src1_sel:DWORD
	v_add3_u32 v4, v1, v4, s77
	v_add3_u32 v122, v0, v5, s77
	v_and_b32_e32 v123, 0xffff0000, v4
	v_or_b32_sdwa v5, v123, v6 dst_sel:DWORD dst_unused:UNUSED_PAD src0_sel:DWORD src1_sel:WORD_1
	v_or_b32_sdwa v4, v122, v7 dst_sel:DWORD dst_unused:UNUSED_PAD src0_sel:WORD_1 src1_sel:DWORD
	ds_write_b64 v135, v[4:5]
	v_and_b32_e32 v4, 0xffff0000, v122
	v_sub_u32_e32 v0, v0, v4
	v_sub_u32_e32 v4, v22, v7
	v_and_b32_e32 v5, 0xffff0000, v6
	v_add_u32_e32 v4, 0x80, v4
	v_sub_u32_e32 v5, v23, v5
	v_sub_u32_e32 v1, v1, v123
	v_add_u32_e32 v0, 0x80, v0
	v_ashrrev_i32_e32 v4, 8, v4
	v_add_u32_e32 v5, 0x80, v5
	v_add_u32_e32 v1, 0x80, v1
	v_ashrrev_i32_e32 v0, 8, v0
	v_min_i32_e32 v4, 0x7f, v4
	v_ashrrev_i32_e32 v5, 8, v5
	v_ashrrev_i32_e32 v1, 8, v1
	v_min_i32_e32 v0, 0x7f, v0
	v_min_i32_sdwa v5, v5, s78 dst_sel:WORD_1 dst_unused:UNUSED_PAD src0_sel:DWORD src1_sel:DWORD
	v_min_i32_e32 v1, 0x7f, v1
	v_lshlrev_b32_e32 v4, 8, v4
	v_and_b32_e32 v4, 0xff00, v4
	v_and_b32_e32 v5, 0xff0000, v5
	v_perm_b32 v0, v1, v0, s79
	v_lshrrev_b32_e32 v1, 2, v3
	v_or3_b32 v0, v0, v4, v5
	v_mad_u64_u32 v[22:23], s[22:23], v1, s60, v[2:3]
	ds_write_b32 v22, v0
	v_mov_b32_e32 v0, v224
	v_mov_b32_e32 v1, v225
	v_mov_b32_e32 v2, v226
	v_mov_b32_e32 v3, v227
	v_mov_b32_e32 v4, v240
	v_mov_b32_e32 v5, v241
	v_mov_b32_e32 v6, v242
	v_mov_b32_e32 v7, v243
	v_mov_b32_e32 v138, v210
	v_mov_b32_e32 v139, v211
	s_mov_b32 s22, s18
	s_mov_b32 s23, s19
	v_pk_add_f32 v[128:129], v[128:129], v[138:139] op_sel_hi:[1,0] neg_lo:[0,1] neg_hi:[0,1]
	s_nop 0
	v_pk_mul_f32 v[128:129], v[138:139], v[128:129] op_sel:[1,0]
	v_pk_add_f32 v[126:127], v[126:127], v[138:139] op_sel_hi:[1,0] neg_lo:[0,1] neg_hi:[0,1]
	v_mov_b32_e32 v122, v1
	v_mov_b32_e32 v123, v2
	v_mov_b32_e32 v130, v5
	v_mov_b32_e32 v131, v6
	v_pk_fma_f32 v[128:129], v[122:123], v[128:129], v[130:131]
	v_pk_mul_f32 v[126:127], v[138:139], v[126:127] op_sel:[1,0]
	v_mov_b32_e32 v1, v3
	v_mov_b32_e32 v5, v7
	v_and_b32_sdwa v23, v128, v216 dst_sel:DWORD dst_unused:UNUSED_PAD src0_sel:WORD_1 src1_sel:DWORD
	v_pk_fma_f32 v[6:7], v[0:1], v[126:127], v[4:5]
	v_add3_u32 v23, v128, v23, s77
	v_and_b32_e32 v138, 0xffff0000, v23
	v_and_b32_sdwa v23, v7, v216 dst_sel:DWORD dst_unused:UNUSED_PAD src0_sel:WORD_1 src1_sel:DWORD
	v_and_b32_sdwa v3, v129, v216 dst_sel:DWORD dst_unused:UNUSED_PAD src0_sel:WORD_1 src1_sel:DWORD
	v_and_b32_sdwa v126, v6, v216 dst_sel:DWORD dst_unused:UNUSED_PAD src0_sel:WORD_1 src1_sel:DWORD
	v_add3_u32 v23, v7, v23, s77
	v_or_b32_e32 v2, 32, v154
	v_add3_u32 v3, v129, v3, s77
	v_add3_u32 v139, v6, v126, s77
	v_and_b32_e32 v140, 0xffff0000, v23
	v_or_b32_sdwa v127, v140, v3 dst_sel:DWORD dst_unused:UNUSED_PAD src0_sel:DWORD src1_sel:WORD_1
	v_or_b32_sdwa v126, v139, v138 dst_sel:DWORD dst_unused:UNUSED_PAD src0_sel:WORD_1 src1_sel:DWORD
	v_add_u32_e32 v23, v2, v152
	ds_write_b64 v23, v[126:127]
	v_and_b32_e32 v126, 0xffff0000, v139
	v_sub_u32_e32 v6, v6, v126
	v_sub_u32_e32 v126, v128, v138
	v_and_b32_e32 v3, 0xffff0000, v3
	v_add_u32_e32 v126, 0x80, v126
	v_sub_u32_e32 v3, v129, v3
	v_sub_u32_e32 v7, v7, v140
	v_add_u32_e32 v6, 0x80, v6
	v_ashrrev_i32_e32 v126, 8, v126
	v_add_u32_e32 v3, 0x80, v3
	v_add_u32_e32 v7, 0x80, v7
	v_ashrrev_i32_e32 v6, 8, v6
	v_min_i32_e32 v126, 0x7f, v126
	v_ashrrev_i32_e32 v3, 8, v3
	v_ashrrev_i32_e32 v7, 8, v7
	v_min_i32_e32 v6, 0x7f, v6
	v_min_i32_sdwa v3, v3, s78 dst_sel:WORD_1 dst_unused:UNUSED_PAD src0_sel:DWORD src1_sel:DWORD
	v_min_i32_e32 v7, 0x7f, v7
	v_lshlrev_b32_e32 v126, 8, v126
	v_and_b32_e32 v126, 0xff00, v126
	v_and_b32_e32 v3, 0xff0000, v3
	v_perm_b32 v6, v7, v6, s79
	v_or3_b32 v3, v6, v126, v3
	ds_write_b32 v12, v3 offset:16
	v_mov_b32_e32 v6, v212
	v_mov_b32_e32 v7, v213
	v_pk_add_f32 v[108:109], v[108:109], v[6:7] op_sel_hi:[1,0] neg_lo:[0,1] neg_hi:[0,1]
	s_nop 0
	v_pk_mul_f32 v[108:109], v[6:7], v[108:109] op_sel:[1,0]
	s_nop 0
	v_pk_fma_f32 v[126:127], v[122:123], v[108:109], v[130:131]
	v_pk_add_f32 v[108:109], v[110:111], v[6:7] op_sel_hi:[1,0] neg_lo:[0,1] neg_hi:[0,1]
	v_and_b32_sdwa v3, v127, v216 dst_sel:DWORD dst_unused:UNUSED_PAD src0_sel:WORD_1 src1_sel:DWORD
	v_pk_mul_f32 v[6:7], v[6:7], v[108:109] op_sel:[1,0]
	v_and_b32_sdwa v108, v126, v216 dst_sel:DWORD dst_unused:UNUSED_PAD src0_sel:WORD_1 src1_sel:DWORD
	v_pk_fma_f32 v[6:7], v[0:1], v[6:7], v[4:5]
	v_add3_u32 v108, v126, v108, s77
	v_and_b32_e32 v109, 0xffff0000, v108
	v_and_b32_sdwa v108, v7, v216 dst_sel:DWORD dst_unused:UNUSED_PAD src0_sel:WORD_1 src1_sel:DWORD
	v_and_b32_sdwa v110, v6, v216 dst_sel:DWORD dst_unused:UNUSED_PAD src0_sel:WORD_1 src1_sel:DWORD
	v_add3_u32 v108, v7, v108, s77
	v_add3_u32 v3, v127, v3, s77
	v_add3_u32 v128, v6, v110, s77
;     ...
;           _Pragma("unroll") for (int bj = 0; bj < 2; ++bj) _Pragma("unroll") for (int n = 0; n < 2; ++n) {
;             const int cc = bj * HALF + wc3 * 32 + n * 16 + fq3 * 4;
;             const float4 gm = *reinterpret_cast<const float4*>(g.gam + pn * BM + cc), bt = *reinterpret_cast<const float4*>(g.bet + pn * BM + cc);
;             _Pragma("unroll") for (int m = 0; m < 4; ++m) {
;               const int rr = wr3 * 64 + m * 16 + fr3;
;               const float2 ms = *reinterpret_cast<const float2*>(mr + (ai * HALF + rr) * 2);
;               f32x4 y = acc[ai][bj][m][n];
;               const float o0 = (y[0] - ms.x) * ms.y * gm.x + bt.x, o1 = (y[1] - ms.x) * ms.y * gm.y + bt.y;
;               const float o2 = (y[2] - ms.x) * ms.y * gm.z + bt.z, o3 = (y[3] - ms.x) * ms.y * gm.w + bt.w;
;               const unsigned h0 = f2bf(o0), h1 = f2bf(o1), h2 = f2bf(o2), h3 = f2bf(o3);
;               u32x2 ob; ob[0] = h0 | (h1 << 16); ob[1] = h2 | (h3 << 16);
;               *reinterpret_cast<u32x2*>(smem + (rr >> 1) * PIECE + (rr & 1) * 512 + cc * 2) = ob;
;               const int l0 = min(((int)__float_as_uint(o0) - (int)(h0 << 16) + 128) >> 8, 127);
;               const int l1 = min(((int)__float_as_uint(o1) - (int)(h1 << 16) + 128) >> 8, 127);
;               const int l2 = min(((int)__float_as_uint(o2) - (int)(h2 << 16) + 128) >> 8, 127);
;               const int l3 = min(((int)__float_as_uint(o3) - (int)(h3 << 16) + 128) >> 8, 127);
;               *reinterpret_cast<unsigned*>(smem + LOBASE + (rr >> 2) * PIECE + (rr & 3) * 256 + cc) =
;                   (unsigned)(l0 & 255) | ((unsigned)(l1 & 255) << 8) | ((unsigned)(l2 & 255) << 16) | ((unsigned)l3 << 24);
;             }
	v_and_b32_e32 v129, 0xffff0000, v108
	v_or_b32_sdwa v111, v129, v3 dst_sel:DWORD dst_unused:UNUSED_PAD src0_sel:DWORD src1_sel:WORD_1
	v_or_b32_sdwa v110, v128, v109 dst_sel:DWORD dst_unused:UNUSED_PAD src0_sel:WORD_1 src1_sel:DWORD
	v_add_u32_e32 v108, v2, v153
	ds_write_b64 v108, v[110:111]
	v_and_b32_e32 v110, 0xffff0000, v128
	v_sub_u32_e32 v109, v126, v109
	v_and_b32_e32 v3, 0xffff0000, v3
	v_sub_u32_e32 v6, v6, v110
	v_add_u32_e32 v109, 0x80, v109
	v_sub_u32_e32 v3, v127, v3
	v_sub_u32_e32 v7, v7, v129
	v_add_u32_e32 v6, 0x80, v6
	v_ashrrev_i32_e32 v109, 8, v109
	v_add_u32_e32 v3, 0x80, v3
	v_add_u32_e32 v7, 0x80, v7
	v_ashrrev_i32_e32 v6, 8, v6
	v_min_i32_e32 v109, 0x7f, v109
	v_ashrrev_i32_e32 v3, 8, v3
	v_ashrrev_i32_e32 v7, 8, v7
	v_min_i32_e32 v6, 0x7f, v6
	v_min_i32_sdwa v3, v3, s78 dst_sel:WORD_1 dst_unused:UNUSED_PAD src0_sel:DWORD src1_sel:DWORD
	v_min_i32_e32 v7, 0x7f, v7
	v_lshlrev_b32_e32 v109, 8, v109
	v_and_b32_e32 v109, 0xff00, v109
	v_and_b32_e32 v3, 0xff0000, v3
	v_perm_b32 v6, v7, v6, s79
	v_or3_b32 v3, v6, v109, v3
	ds_write_b32 v14, v3 offset:16
	v_mov_b32_e32 v6, v214
	v_mov_b32_e32 v7, v215
	v_pk_add_f32 v[98:99], v[98:99], v[6:7] op_sel_hi:[1,0] neg_lo:[0,1] neg_hi:[0,1]
	s_nop 0
	v_pk_mul_f32 v[98:99], v[6:7], v[98:99] op_sel:[1,0]
	s_nop 0
	v_pk_fma_f32 v[110:111], v[122:123], v[98:99], v[130:131]
	v_pk_add_f32 v[98:99], v[106:107], v[6:7] op_sel_hi:[1,0] neg_lo:[0,1] neg_hi:[0,1]
	v_and_b32_sdwa v3, v111, v216 dst_sel:DWORD dst_unused:UNUSED_PAD src0_sel:WORD_1 src1_sel:DWORD
	v_pk_mul_f32 v[6:7], v[6:7], v[98:99] op_sel:[1,0]
	v_and_b32_sdwa v98, v110, v216 dst_sel:DWORD dst_unused:UNUSED_PAD src0_sel:WORD_1 src1_sel:DWORD
	v_pk_fma_f32 v[6:7], v[0:1], v[6:7], v[4:5]
	v_add3_u32 v98, v110, v98, s77
	v_and_b32_e32 v99, 0xffff0000, v98
	v_and_b32_sdwa v98, v7, v216 dst_sel:DWORD dst_unused:UNUSED_PAD src0_sel:WORD_1 src1_sel:DWORD
	v_and_b32_sdwa v106, v6, v216 dst_sel:DWORD dst_unused:UNUSED_PAD src0_sel:WORD_1 src1_sel:DWORD
	v_add3_u32 v98, v7, v98, s77
	v_add3_u32 v3, v111, v3, s77
	v_add3_u32 v109, v6, v106, s77
	v_and_b32_e32 v126, 0xffff0000, v98
	v_or_b32_sdwa v107, v126, v3 dst_sel:DWORD dst_unused:UNUSED_PAD src0_sel:DWORD src1_sel:WORD_1
	v_or_b32_sdwa v106, v109, v99 dst_sel:DWORD dst_unused:UNUSED_PAD src0_sel:WORD_1 src1_sel:DWORD
	v_add_u32_e32 v98, v2, v137
	ds_write_b64 v98, v[106:107]
	v_and_b32_e32 v106, 0xffff0000, v109
	v_sub_u32_e32 v99, v110, v99
	v_and_b32_e32 v3, 0xffff0000, v3
	v_sub_u32_e32 v6, v6, v106
	v_add_u32_e32 v99, 0x80, v99
	v_sub_u32_e32 v3, v111, v3
	v_sub_u32_e32 v7, v7, v126
	v_add_u32_e32 v6, 0x80, v6
	v_ashrrev_i32_e32 v99, 8, v99
	v_add_u32_e32 v3, 0x80, v3
	v_add_u32_e32 v7, 0x80, v7
	v_ashrrev_i32_e32 v6, 8, v6
	v_min_i32_e32 v99, 0x7f, v99
	v_ashrrev_i32_e32 v3, 8, v3
	v_ashrrev_i32_e32 v7, 8, v7
	v_min_i32_e32 v6, 0x7f, v6
	v_min_i32_sdwa v3, v3, s78 dst_sel:WORD_1 dst_unused:UNUSED_PAD src0_sel:DWORD src1_sel:DWORD
	v_min_i32_e32 v7, 0x7f, v7
	v_lshlrev_b32_e32 v99, 8, v99
	v_and_b32_e32 v99, 0xff00, v99
	v_and_b32_e32 v3, 0xff0000, v3
	v_perm_b32 v6, v7, v6, s79
	v_or3_b32 v3, v6, v99, v3
	ds_write_b32 v18, v3 offset:16
	v_mov_b32_e32 v6, v252
	v_mov_b32_e32 v7, v253
	v_add_u32_e32 v99, v2, v136
	v_pk_add_f32 v[106:107], v[114:115], v[6:7] op_sel_hi:[1,0] neg_lo:[0,1] neg_hi:[0,1]
	s_nop 0
	v_pk_mul_f32 v[106:107], v[6:7], v[106:107] op_sel:[1,0]
	v_pk_add_f32 v[110:111], v[120:121], v[6:7] op_sel_hi:[1,0] neg_lo:[0,1] neg_hi:[0,1]
	v_pk_fma_f32 v[106:107], v[122:123], v[106:107], v[130:131]
	v_pk_mul_f32 v[6:7], v[6:7], v[110:111] op_sel:[1,0]
	v_and_b32_sdwa v3, v107, v216 dst_sel:DWORD dst_unused:UNUSED_PAD src0_sel:WORD_1 src1_sel:DWORD
	v_pk_fma_f32 v[0:1], v[0:1], v[6:7], v[4:5]
	v_and_b32_sdwa v4, v106, v216 dst_sel:DWORD dst_unused:UNUSED_PAD src0_sel:WORD_1 src1_sel:DWORD
	v_add3_u32 v4, v106, v4, s77
	v_and_b32_e32 v6, 0xffff0000, v4
	v_and_b32_sdwa v4, v1, v216 dst_sel:DWORD dst_unused:UNUSED_PAD src0_sel:WORD_1 src1_sel:DWORD
	v_and_b32_sdwa v5, v0, v216 dst_sel:DWORD dst_unused:UNUSED_PAD src0_sel:WORD_1 src1_sel:DWORD
	v_add3_u32 v4, v1, v4, s77
	v_add3_u32 v7, v0, v5, s77
	v_add3_u32 v3, v107, v3, s77
	v_and_b32_e32 v109, 0xffff0000, v4
	v_and_b32_e32 v2, 0xffff0000, v7
	v_or_b32_sdwa v5, v109, v3 dst_sel:DWORD dst_unused:UNUSED_PAD src0_sel:DWORD src1_sel:WORD_1
	v_sub_u32_e32 v0, v0, v2
	v_sub_u32_e32 v2, v106, v6
	v_and_b32_e32 v3, 0xffff0000, v3
	v_add_u32_e32 v2, 0x80, v2
	v_sub_u32_e32 v3, v107, v3
	v_sub_u32_e32 v1, v1, v109
	v_add_u32_e32 v0, 0x80, v0
	v_ashrrev_i32_e32 v2, 8, v2
	v_add_u32_e32 v3, 0x80, v3
	v_add_u32_e32 v1, 0x80, v1
	v_ashrrev_i32_e32 v0, 8, v0
	v_min_i32_e32 v2, 0x7f, v2
	v_ashrrev_i32_e32 v3, 8, v3
	v_ashrrev_i32_e32 v1, 8, v1
	v_min_i32_e32 v0, 0x7f, v0
	v_min_i32_sdwa v3, v3, s78 dst_sel:WORD_1 dst_unused:UNUSED_PAD src0_sel:DWORD src1_sel:DWORD
	v_min_i32_e32 v1, 0x7f, v1
	v_lshlrev_b32_e32 v2, 8, v2
	v_and_b32_e32 v2, 0xff00, v2
	v_and_b32_e32 v3, 0xff0000, v3
	v_perm_b32 v0, v1, v0, s79
	v_or_b32_sdwa v4, v7, v6 dst_sel:DWORD dst_unused:UNUSED_PAD src0_sel:WORD_1 src1_sel:DWORD
	v_or3_b32 v0, v0, v2, v3
	ds_write_b64 v99, v[4:5]
	ds_write_b32 v22, v0 offset:16
	v_mov_b32_e32 v0, v228
	v_mov_b32_e32 v1, v229
	v_mov_b32_e32 v2, v230
	v_mov_b32_e32 v3, v231
	v_mov_b32_e32 v4, v244
	v_mov_b32_e32 v5, v245
	v_mov_b32_e32 v6, v246
	v_mov_b32_e32 v7, v247
	v_mov_b32_e32 v106, v210
	v_mov_b32_e32 v107, v211
	v_or_b32_e32 v109, 0x100, v154
	v_pk_add_f32 v[120:121], v[124:125], v[106:107] op_sel_hi:[1,0] neg_lo:[0,1] neg_hi:[0,1]
	s_nop 0
	v_pk_mul_f32 v[120:121], v[106:107], v[120:121] op_sel:[1,0]
;     ...
;           _Pragma("unroll") for (int bj = 0; bj < 2; ++bj) _Pragma("unroll") for (int n = 0; n < 2; ++n) {
;             const int cc = bj * HALF + wc3 * 32 + n * 16 + fq3 * 4;
;             const float4 gm = *reinterpret_cast<const float4*>(g.gam + pn * BM + cc), bt = *reinterpret_cast<const float4*>(g.bet + pn * BM + cc);
;             _Pragma("unroll") for (int m = 0; m < 4; ++m) {
;               const int rr = wr3 * 64 + m * 16 + fr3;
;               const float2 ms = *reinterpret_cast<const float2*>(mr + (ai * HALF + rr) * 2);
;               f32x4 y = acc[ai][bj][m][n];
;               const float o0 = (y[0] - ms.x) * ms.y * gm.x + bt.x, o1 = (y[1] - ms.x) * ms.y * gm.y + bt.y;
;               const float o2 = (y[2] - ms.x) * ms.y * gm.z + bt.z, o3 = (y[3] - ms.x) * ms.y * gm.w + bt.w;
;               const unsigned h0 = f2bf(o0), h1 = f2bf(o1), h2 = f2bf(o2), h3 = f2bf(o3);
;               u32x2 ob; ob[0] = h0 | (h1 << 16); ob[1] = h2 | (h3 << 16);
;               *reinterpret_cast<u32x2*>(smem + (rr >> 1) * PIECE + (rr & 1) * 512 + cc * 2) = ob;
;               const int l0 = min(((int)__float_as_uint(o0) - (int)(h0 << 16) + 128) >> 8, 127);
;               const int l1 = min(((int)__float_as_uint(o1) - (int)(h1 << 16) + 128) >> 8, 127);
;               const int l2 = min(((int)__float_as_uint(o2) - (int)(h2 << 16) + 128) >> 8, 127);
;               const int l3 = min(((int)__float_as_uint(o3) - (int)(h3 << 16) + 128) >> 8, 127);
;               *reinterpret_cast<unsigned*>(smem + LOBASE + (rr >> 2) * PIECE + (rr & 3) * 256 + cc) =
;                   (unsigned)(l0 & 255) | ((unsigned)(l1 & 255) << 8) | ((unsigned)(l2 & 255) << 16) | ((unsigned)l3 << 24);
;             }
	v_pk_add_f32 v[118:119], v[118:119], v[106:107] op_sel_hi:[1,0] neg_lo:[0,1] neg_hi:[0,1]
	v_mov_b32_e32 v110, v1
	v_mov_b32_e32 v111, v2
	v_mov_b32_e32 v114, v5
	v_mov_b32_e32 v115, v6
	v_pk_fma_f32 v[120:121], v[110:111], v[120:121], v[114:115]
	v_pk_mul_f32 v[106:107], v[106:107], v[118:119] op_sel:[1,0]
	v_mov_b32_e32 v1, v3
	v_mov_b32_e32 v5, v7
	v_and_b32_sdwa v6, v121, v216 dst_sel:DWORD dst_unused:UNUSED_PAD src0_sel:WORD_1 src1_sel:DWORD
	v_and_b32_sdwa v7, v120, v216 dst_sel:DWORD dst_unused:UNUSED_PAD src0_sel:WORD_1 src1_sel:DWORD
	v_pk_fma_f32 v[2:3], v[0:1], v[106:107], v[4:5]
	v_add3_u32 v107, v121, v6, s77
	v_add3_u32 v6, v120, v7, s77
	v_and_b32_e32 v118, 0xffff0000, v6
	v_and_b32_sdwa v6, v3, v216 dst_sel:DWORD dst_unused:UNUSED_PAD src0_sel:WORD_1 src1_sel:DWORD
	v_and_b32_sdwa v7, v2, v216 dst_sel:DWORD dst_unused:UNUSED_PAD src0_sel:WORD_1 src1_sel:DWORD
	v_add3_u32 v6, v3, v6, s77
	v_add3_u32 v119, v2, v7, s77
	v_and_b32_e32 v122, 0xffff0000, v6
	v_or_b32_sdwa v7, v122, v107 dst_sel:DWORD dst_unused:UNUSED_PAD src0_sel:DWORD src1_sel:WORD_1
	v_or_b32_sdwa v6, v119, v118 dst_sel:DWORD dst_unused:UNUSED_PAD src0_sel:WORD_1 src1_sel:DWORD
	v_add_u32_e32 v106, v109, v152
	ds_write_b64 v106, v[6:7]
	v_and_b32_e32 v6, 0xffff0000, v119
	v_sub_u32_e32 v2, v2, v6
	v_sub_u32_e32 v6, v120, v118
	v_and_b32_e32 v7, 0xffff0000, v107
	v_add_u32_e32 v6, 0x80, v6
	v_sub_u32_e32 v7, v121, v7
	v_sub_u32_e32 v3, v3, v122
	v_add_u32_e32 v2, 0x80, v2
	v_ashrrev_i32_e32 v6, 8, v6
	v_add_u32_e32 v7, 0x80, v7
	v_add_u32_e32 v3, 0x80, v3
	v_ashrrev_i32_e32 v2, 8, v2
	v_min_i32_e32 v6, 0x7f, v6
	v_ashrrev_i32_e32 v7, 8, v7
	v_ashrrev_i32_e32 v3, 8, v3
	v_min_i32_e32 v2, 0x7f, v2
	v_min_i32_sdwa v7, v7, s78 dst_sel:WORD_1 dst_unused:UNUSED_PAD src0_sel:DWORD src1_sel:DWORD
	v_min_i32_e32 v3, 0x7f, v3
	v_lshlrev_b32_e32 v6, 8, v6
	v_and_b32_e32 v6, 0xff00, v6
	v_and_b32_e32 v7, 0xff0000, v7
	v_perm_b32 v2, v3, v2, s79
	v_or3_b32 v2, v2, v6, v7
	ds_write_b32 v12, v2 offset:128
	v_mov_b32_e32 v2, v212
	v_mov_b32_e32 v3, v213
	v_pk_add_f32 v[6:7], v[102:103], v[2:3] op_sel_hi:[1,0] neg_lo:[0,1] neg_hi:[0,1]
	s_nop 0
	v_pk_mul_f32 v[6:7], v[2:3], v[6:7] op_sel:[1,0]
	v_pk_add_f32 v[102:103], v[104:105], v[2:3] op_sel_hi:[1,0] neg_lo:[0,1] neg_hi:[0,1]
	v_pk_fma_f32 v[6:7], v[110:111], v[6:7], v[114:115]
	v_pk_mul_f32 v[2:3], v[2:3], v[102:103] op_sel:[1,0]
	v_and_b32_sdwa v102, v7, v216 dst_sel:DWORD dst_unused:UNUSED_PAD src0_sel:WORD_1 src1_sel:DWORD
	v_and_b32_sdwa v103, v6, v216 dst_sel:DWORD dst_unused:UNUSED_PAD src0_sel:WORD_1 src1_sel:DWORD
	v_pk_fma_f32 v[2:3], v[0:1], v[2:3], v[4:5]
	v_add3_u32 v107, v7, v102, s77
	v_add3_u32 v102, v6, v103, s77
	v_and_b32_e32 v103, 0xffff0000, v102
	v_and_b32_sdwa v102, v3, v216 dst_sel:DWORD dst_unused:UNUSED_PAD src0_sel:WORD_1 src1_sel:DWORD
	v_and_b32_sdwa v104, v2, v216 dst_sel:DWORD dst_unused:UNUSED_PAD src0_sel:WORD_1 src1_sel:DWORD
	v_add3_u32 v102, v3, v102, s77
	v_add3_u32 v118, v2, v104, s77
	v_and_b32_e32 v119, 0xffff0000, v102
	v_or_b32_sdwa v105, v119, v107 dst_sel:DWORD dst_unused:UNUSED_PAD src0_sel:DWORD src1_sel:WORD_1
	v_or_b32_sdwa v104, v118, v103 dst_sel:DWORD dst_unused:UNUSED_PAD src0_sel:WORD_1 src1_sel:DWORD
	v_add_u32_e32 v102, v109, v153
	ds_write_b64 v102, v[104:105]
	v_and_b32_e32 v104, 0xffff0000, v118
	v_sub_u32_e32 v6, v6, v103
	v_and_b32_e32 v103, 0xffff0000, v107
	v_sub_u32_e32 v2, v2, v104
	v_add_u32_e32 v6, 0x80, v6
	v_sub_u32_e32 v7, v7, v103
	v_sub_u32_e32 v3, v3, v119
	v_add_u32_e32 v2, 0x80, v2
	v_ashrrev_i32_e32 v6, 8, v6
	v_add_u32_e32 v7, 0x80, v7
	v_add_u32_e32 v3, 0x80, v3
	v_ashrrev_i32_e32 v2, 8, v2
	v_min_i32_e32 v6, 0x7f, v6
	v_ashrrev_i32_e32 v7, 8, v7
	v_ashrrev_i32_e32 v3, 8, v3
	v_min_i32_e32 v2, 0x7f, v2
	v_min_i32_sdwa v7, v7, s78 dst_sel:WORD_1 dst_unused:UNUSED_PAD src0_sel:DWORD src1_sel:DWORD
	v_min_i32_e32 v3, 0x7f, v3
	v_lshlrev_b32_e32 v6, 8, v6
	v_and_b32_e32 v6, 0xff00, v6
	v_and_b32_e32 v7, 0xff0000, v7
	v_perm_b32 v2, v3, v2, s79
	v_or3_b32 v2, v2, v6, v7
	ds_write_b32 v14, v2 offset:128
	v_mov_b32_e32 v2, v214
	v_mov_b32_e32 v3, v215
	v_pk_add_f32 v[6:7], v[92:93], v[2:3] op_sel_hi:[1,0] neg_lo:[0,1] neg_hi:[0,1]
	s_nop 0
	v_pk_mul_f32 v[6:7], v[2:3], v[6:7] op_sel:[1,0]
	v_pk_add_f32 v[88:89], v[88:89], v[2:3] op_sel_hi:[1,0] neg_lo:[0,1] neg_hi:[0,1]
	v_pk_fma_f32 v[6:7], v[110:111], v[6:7], v[114:115]
	v_pk_mul_f32 v[2:3], v[2:3], v[88:89] op_sel:[1,0]
	v_and_b32_sdwa v88, v7, v216 dst_sel:DWORD dst_unused:UNUSED_PAD src0_sel:WORD_1 src1_sel:DWORD
	v_and_b32_sdwa v89, v6, v216 dst_sel:DWORD dst_unused:UNUSED_PAD src0_sel:WORD_1 src1_sel:DWORD
	v_pk_fma_f32 v[2:3], v[0:1], v[2:3], v[4:5]
	v_add3_u32 v93, v7, v88, s77
	v_add3_u32 v88, v6, v89, s77
	v_and_b32_e32 v103, 0xffff0000, v88
	v_and_b32_sdwa v88, v3, v216 dst_sel:DWORD dst_unused:UNUSED_PAD src0_sel:WORD_1 src1_sel:DWORD
	v_and_b32_sdwa v89, v2, v216 dst_sel:DWORD dst_unused:UNUSED_PAD src0_sel:WORD_1 src1_sel:DWORD
	v_add3_u32 v88, v3, v88, s77
	v_add3_u32 v104, v2, v89, s77
	v_and_b32_e32 v105, 0xffff0000, v88
	v_or_b32_sdwa v89, v105, v93 dst_sel:DWORD dst_unused:UNUSED_PAD src0_sel:DWORD src1_sel:WORD_1
	v_or_b32_sdwa v88, v104, v103 dst_sel:DWORD dst_unused:UNUSED_PAD src0_sel:WORD_1 src1_sel:DWORD
	v_add_u32_e32 v92, v109, v137
	ds_write_b64 v92, v[88:89]
	v_and_b32_e32 v88, 0xffff0000, v104
	v_sub_u32_e32 v2, v2, v88
	v_sub_u32_e32 v6, v6, v103
	v_and_b32_e32 v88, 0xffff0000, v93
	v_add_u32_e32 v6, 0x80, v6
	v_sub_u32_e32 v7, v7, v88
	v_sub_u32_e32 v3, v3, v105
	v_add_u32_e32 v2, 0x80, v2
	v_ashrrev_i32_e32 v6, 8, v6
	v_add_u32_e32 v7, 0x80, v7
	v_add_u32_e32 v3, 0x80, v3
;     ...
;           _Pragma("unroll") for (int bj = 0; bj < 2; ++bj) _Pragma("unroll") for (int n = 0; n < 2; ++n) {
;             const int cc = bj * HALF + wc3 * 32 + n * 16 + fq3 * 4;
;             const float4 gm = *reinterpret_cast<const float4*>(g.gam + pn * BM + cc), bt = *reinterpret_cast<const float4*>(g.bet + pn * BM + cc);
;             _Pragma("unroll") for (int m = 0; m < 4; ++m) {
;               const int rr = wr3 * 64 + m * 16 + fr3;
;               const float2 ms = *reinterpret_cast<const float2*>(mr + (ai * HALF + rr) * 2);
;               f32x4 y = acc[ai][bj][m][n];
;               const float o0 = (y[0] - ms.x) * ms.y * gm.x + bt.x, o1 = (y[1] - ms.x) * ms.y * gm.y + bt.y;
;               const float o2 = (y[2] - ms.x) * ms.y * gm.z + bt.z, o3 = (y[3] - ms.x) * ms.y * gm.w + bt.w;
;               const unsigned h0 = f2bf(o0), h1 = f2bf(o1), h2 = f2bf(o2), h3 = f2bf(o3);
;               u32x2 ob; ob[0] = h0 | (h1 << 16); ob[1] = h2 | (h3 << 16);
;               *reinterpret_cast<u32x2*>(smem + (rr >> 1) * PIECE + (rr & 1) * 512 + cc * 2) = ob;
;               const int l0 = min(((int)__float_as_uint(o0) - (int)(h0 << 16) + 128) >> 8, 127);
;               const int l1 = min(((int)__float_as_uint(o1) - (int)(h1 << 16) + 128) >> 8, 127);
;               const int l2 = min(((int)__float_as_uint(o2) - (int)(h2 << 16) + 128) >> 8, 127);
;               const int l3 = min(((int)__float_as_uint(o3) - (int)(h3 << 16) + 128) >> 8, 127);
;               *reinterpret_cast<unsigned*>(smem + LOBASE + (rr >> 2) * PIECE + (rr & 3) * 256 + cc) =
;                   (unsigned)(l0 & 255) | ((unsigned)(l1 & 255) << 8) | ((unsigned)(l2 & 255) << 16) | ((unsigned)l3 << 24);
;             }
	v_ashrrev_i32_e32 v2, 8, v2
	v_min_i32_e32 v6, 0x7f, v6
	v_ashrrev_i32_e32 v7, 8, v7
	v_ashrrev_i32_e32 v3, 8, v3
	v_min_i32_e32 v2, 0x7f, v2
	v_min_i32_sdwa v7, v7, s78 dst_sel:WORD_1 dst_unused:UNUSED_PAD src0_sel:DWORD src1_sel:DWORD
	v_min_i32_e32 v3, 0x7f, v3
	v_lshlrev_b32_e32 v6, 8, v6
	v_and_b32_e32 v6, 0xff00, v6
	v_and_b32_e32 v7, 0xff0000, v7
	v_perm_b32 v2, v3, v2, s79
	v_or3_b32 v2, v2, v6, v7
	ds_write_b32 v18, v2 offset:128
	v_mov_b32_e32 v2, v252
	v_mov_b32_e32 v3, v253
	v_add_u32_e32 v93, v109, v136
	v_pk_add_f32 v[6:7], v[90:91], v[2:3] op_sel_hi:[1,0] neg_lo:[0,1] neg_hi:[0,1]
	s_nop 0
	v_pk_mul_f32 v[6:7], v[2:3], v[6:7] op_sel:[1,0]
	v_pk_add_f32 v[88:89], v[94:95], v[2:3] op_sel_hi:[1,0] neg_lo:[0,1] neg_hi:[0,1]
	v_pk_fma_f32 v[6:7], v[110:111], v[6:7], v[114:115]
	v_pk_mul_f32 v[2:3], v[2:3], v[88:89] op_sel:[1,0]
	s_nop 0
	v_pk_fma_f32 v[0:1], v[0:1], v[2:3], v[4:5]
	v_and_b32_sdwa v2, v7, v216 dst_sel:DWORD dst_unused:UNUSED_PAD src0_sel:WORD_1 src1_sel:DWORD
	v_and_b32_sdwa v3, v6, v216 dst_sel:DWORD dst_unused:UNUSED_PAD src0_sel:WORD_1 src1_sel:DWORD
	v_add3_u32 v4, v7, v2, s77
	v_add3_u32 v2, v6, v3, s77
	v_and_b32_e32 v5, 0xffff0000, v2
	v_and_b32_sdwa v2, v1, v216 dst_sel:DWORD dst_unused:UNUSED_PAD src0_sel:WORD_1 src1_sel:DWORD
	v_and_b32_sdwa v3, v0, v216 dst_sel:DWORD dst_unused:UNUSED_PAD src0_sel:WORD_1 src1_sel:DWORD
	v_add3_u32 v2, v1, v2, s77
	v_add3_u32 v88, v0, v3, s77
	v_and_b32_e32 v89, 0xffff0000, v2
	v_or_b32_sdwa v3, v89, v4 dst_sel:DWORD dst_unused:UNUSED_PAD src0_sel:DWORD src1_sel:WORD_1
	v_or_b32_sdwa v2, v88, v5 dst_sel:DWORD dst_unused:UNUSED_PAD src0_sel:WORD_1 src1_sel:DWORD
	ds_write_b64 v93, v[2:3]
	v_and_b32_e32 v2, 0xffff0000, v88
	v_sub_u32_e32 v0, v0, v2
	v_sub_u32_e32 v2, v6, v5
	v_and_b32_e32 v3, 0xffff0000, v4
	v_add_u32_e32 v2, 0x80, v2
	v_sub_u32_e32 v3, v7, v3
	v_sub_u32_e32 v1, v1, v89
	v_add_u32_e32 v0, 0x80, v0
	v_ashrrev_i32_e32 v2, 8, v2
	v_add_u32_e32 v3, 0x80, v3
	v_add_u32_e32 v1, 0x80, v1
	v_ashrrev_i32_e32 v0, 8, v0
	v_min_i32_e32 v2, 0x7f, v2
	v_ashrrev_i32_e32 v3, 8, v3
	v_ashrrev_i32_e32 v1, 8, v1
	v_min_i32_e32 v0, 0x7f, v0
	v_min_i32_sdwa v3, v3, s78 dst_sel:WORD_1 dst_unused:UNUSED_PAD src0_sel:DWORD src1_sel:DWORD
	v_min_i32_e32 v1, 0x7f, v1
	v_lshlrev_b32_e32 v2, 8, v2
	v_and_b32_e32 v2, 0xff00, v2
	v_and_b32_e32 v3, 0xff0000, v3
	v_perm_b32 v0, v1, v0, s79
	v_or3_b32 v0, v0, v2, v3
	ds_write_b32 v22, v0 offset:128
	v_mov_b32_e32 v0, v232
	v_mov_b32_e32 v1, v233
	v_mov_b32_e32 v2, v234
	v_mov_b32_e32 v3, v235
	v_mov_b32_e32 v4, v248
	v_mov_b32_e32 v5, v249
	v_mov_b32_e32 v6, v250
	v_mov_b32_e32 v7, v251
	v_mov_b32_e32 v94, v210
	v_mov_b32_e32 v95, v211
	v_pk_add_f32 v[104:105], v[116:117], v[94:95] op_sel_hi:[1,0] neg_lo:[0,1] neg_hi:[0,1]
	s_nop 0
	v_pk_mul_f32 v[104:105], v[94:95], v[104:105] op_sel:[1,0]
	v_pk_add_f32 v[110:111], v[112:113], v[94:95] op_sel_hi:[1,0] neg_lo:[0,1] neg_hi:[0,1]
	v_mov_b32_e32 v88, v1
	v_mov_b32_e32 v89, v2
	v_mov_b32_e32 v90, v5
	v_mov_b32_e32 v91, v6
	v_pk_fma_f32 v[104:105], v[88:89], v[104:105], v[90:91]
	v_pk_mul_f32 v[94:95], v[94:95], v[110:111] op_sel:[1,0]
	v_mov_b32_e32 v1, v3
	v_mov_b32_e32 v5, v7
	v_pk_fma_f32 v[6:7], v[0:1], v[94:95], v[4:5]
	v_and_b32_sdwa v94, v104, v216 dst_sel:DWORD dst_unused:UNUSED_PAD src0_sel:WORD_1 src1_sel:DWORD
	v_add3_u32 v94, v104, v94, s77
	v_and_b32_e32 v95, 0xffff0000, v94
	v_and_b32_sdwa v94, v7, v216 dst_sel:DWORD dst_unused:UNUSED_PAD src0_sel:WORD_1 src1_sel:DWORD
	v_and_b32_sdwa v3, v105, v216 dst_sel:DWORD dst_unused:UNUSED_PAD src0_sel:WORD_1 src1_sel:DWORD
	v_and_b32_sdwa v103, v6, v216 dst_sel:DWORD dst_unused:UNUSED_PAD src0_sel:WORD_1 src1_sel:DWORD
	v_add3_u32 v94, v7, v94, s77
	v_add3_u32 v3, v105, v3, s77
	v_add3_u32 v103, v6, v103, s77
	v_and_b32_e32 v107, 0xffff0000, v94
	v_or_b32_sdwa v111, v107, v3 dst_sel:DWORD dst_unused:UNUSED_PAD src0_sel:DWORD src1_sel:WORD_1
	v_or_b32_sdwa v110, v103, v95 dst_sel:DWORD dst_unused:UNUSED_PAD src0_sel:WORD_1 src1_sel:DWORD
	v_and_b32_e32 v103, 0xffff0000, v103
	v_sub_u32_e32 v95, v104, v95
	v_and_b32_e32 v3, 0xffff0000, v3
	v_sub_u32_e32 v6, v6, v103
	v_add_u32_e32 v95, 0x80, v95
	v_sub_u32_e32 v3, v105, v3
	v_sub_u32_e32 v7, v7, v107
	v_add_u32_e32 v6, 0x80, v6
	v_ashrrev_i32_e32 v95, 8, v95
	v_add_u32_e32 v3, 0x80, v3
	v_add_u32_e32 v7, 0x80, v7
	v_ashrrev_i32_e32 v6, 8, v6
	v_min_i32_e32 v95, 0x7f, v95
	v_ashrrev_i32_e32 v3, 8, v3
	v_ashrrev_i32_e32 v7, 8, v7
	v_min_i32_e32 v6, 0x7f, v6
	v_min_i32_sdwa v3, v3, s78 dst_sel:WORD_1 dst_unused:UNUSED_PAD src0_sel:DWORD src1_sel:DWORD
	v_min_i32_e32 v7, 0x7f, v7
	v_lshlrev_b32_e32 v95, 8, v95
	v_or_b32_e32 v2, 0x120, v154
	v_and_b32_e32 v95, 0xff00, v95
	v_and_b32_e32 v3, 0xff0000, v3
	v_perm_b32 v6, v7, v6, s79
	v_add_u32_e32 v94, v2, v152
	v_or3_b32 v3, v6, v95, v3
	ds_write_b64 v94, v[110:111]
	ds_write_b32 v12, v3 offset:144
	v_mov_b32_e32 v6, v212
	v_mov_b32_e32 v7, v213
	v_pk_add_f32 v[100:101], v[100:101], v[6:7] op_sel_hi:[1,0] neg_lo:[0,1] neg_hi:[0,1]
	s_nop 0
	v_pk_mul_f32 v[100:101], v[6:7], v[100:101] op_sel:[1,0]
	v_pk_add_f32 v[96:97], v[96:97], v[6:7] op_sel_hi:[1,0] neg_lo:[0,1] neg_hi:[0,1]
	v_pk_fma_f32 v[100:101], v[88:89], v[100:101], v[90:91]
	v_pk_mul_f32 v[6:7], v[6:7], v[96:97] op_sel:[1,0]
	v_and_b32_sdwa v95, v100, v216 dst_sel:DWORD dst_unused:UNUSED_PAD src0_sel:WORD_1 src1_sel:DWORD
	v_pk_fma_f32 v[6:7], v[0:1], v[6:7], v[4:5]
	v_add3_u32 v95, v100, v95, s77
	v_and_b32_e32 v103, 0xffff0000, v95
	v_and_b32_sdwa v95, v7, v216 dst_sel:DWORD dst_unused:UNUSED_PAD src0_sel:WORD_1 src1_sel:DWORD
	v_and_b32_sdwa v3, v101, v216 dst_sel:DWORD dst_unused:UNUSED_PAD src0_sel:WORD_1 src1_sel:DWORD
; #define WAIT_L(n) asm volatile("s_waitcnt lgkmcnt(" #n ")" ::: "memory")
; #define BAR __builtin_amdgcn_s_barrier()
;     ...
;           _Pragma("unroll") for (int bj = 0; bj < 2; ++bj) _Pragma("unroll") for (int n = 0; n < 2; ++n) {
;             const int cc = bj * HALF + wc3 * 32 + n * 16 + fq3 * 4;
;             const float4 gm = *reinterpret_cast<const float4*>(g.gam + pn * BM + cc), bt = *reinterpret_cast<const float4*>(g.bet + pn * BM + cc);
;             _Pragma("unroll") for (int m = 0; m < 4; ++m) {
;               const int rr = wr3 * 64 + m * 16 + fr3;
;               const float2 ms = *reinterpret_cast<const float2*>(mr + (ai * HALF + rr) * 2);
;               f32x4 y = acc[ai][bj][m][n];
;               const float o0 = (y[0] - ms.x) * ms.y * gm.x + bt.x, o1 = (y[1] - ms.x) * ms.y * gm.y + bt.y;
;               const float o2 = (y[2] - ms.x) * ms.y * gm.z + bt.z, o3 = (y[3] - ms.x) * ms.y * gm.w + bt.w;
;               const unsigned h0 = f2bf(o0), h1 = f2bf(o1), h2 = f2bf(o2), h3 = f2bf(o3);
;               u32x2 ob; ob[0] = h0 | (h1 << 16); ob[1] = h2 | (h3 << 16);
;               *reinterpret_cast<u32x2*>(smem + (rr >> 1) * PIECE + (rr & 1) * 512 + cc * 2) = ob;
;               const int l0 = min(((int)__float_as_uint(o0) - (int)(h0 << 16) + 128) >> 8, 127);
;               const int l1 = min(((int)__float_as_uint(o1) - (int)(h1 << 16) + 128) >> 8, 127);
;               const int l2 = min(((int)__float_as_uint(o2) - (int)(h2 << 16) + 128) >> 8, 127);
;               const int l3 = min(((int)__float_as_uint(o3) - (int)(h3 << 16) + 128) >> 8, 127);
;               *reinterpret_cast<unsigned*>(smem + LOBASE + (rr >> 2) * PIECE + (rr & 3) * 256 + cc) =
;                   (unsigned)(l0 & 255) | ((unsigned)(l1 & 255) << 8) | ((unsigned)(l2 & 255) << 16) | ((unsigned)l3 << 24);
;             }
;           }
;           WAIT_L(0); BAR;
	v_and_b32_sdwa v96, v6, v216 dst_sel:DWORD dst_unused:UNUSED_PAD src0_sel:WORD_1 src1_sel:DWORD
	v_add3_u32 v95, v7, v95, s77
	v_add3_u32 v3, v101, v3, s77
	v_add3_u32 v104, v6, v96, s77
	v_and_b32_e32 v105, 0xffff0000, v95
	v_or_b32_sdwa v97, v105, v3 dst_sel:DWORD dst_unused:UNUSED_PAD src0_sel:DWORD src1_sel:WORD_1
	v_or_b32_sdwa v96, v104, v103 dst_sel:DWORD dst_unused:UNUSED_PAD src0_sel:WORD_1 src1_sel:DWORD
	v_add_u32_e32 v95, v2, v153
	ds_write_b64 v95, v[96:97]
	v_and_b32_e32 v96, 0xffff0000, v104
	v_sub_u32_e32 v6, v6, v96
	v_sub_u32_e32 v96, v100, v103
	v_and_b32_e32 v3, 0xffff0000, v3
	v_add_u32_e32 v96, 0x80, v96
	v_sub_u32_e32 v3, v101, v3
	v_sub_u32_e32 v7, v7, v105
	v_add_u32_e32 v6, 0x80, v6
	v_ashrrev_i32_e32 v96, 8, v96
	v_add_u32_e32 v3, 0x80, v3
	v_add_u32_e32 v7, 0x80, v7
	v_ashrrev_i32_e32 v6, 8, v6
	v_min_i32_e32 v96, 0x7f, v96
	v_ashrrev_i32_e32 v3, 8, v3
	v_ashrrev_i32_e32 v7, 8, v7
	v_min_i32_e32 v6, 0x7f, v6
	v_min_i32_sdwa v3, v3, s78 dst_sel:WORD_1 dst_unused:UNUSED_PAD src0_sel:DWORD src1_sel:DWORD
	v_min_i32_e32 v7, 0x7f, v7
	v_lshlrev_b32_e32 v96, 8, v96
	v_and_b32_e32 v96, 0xff00, v96
	v_and_b32_e32 v3, 0xff0000, v3
	v_perm_b32 v6, v7, v6, s79
	v_or3_b32 v3, v6, v96, v3
	ds_write_b32 v14, v3 offset:144
	v_mov_b32_e32 v6, v214
	v_mov_b32_e32 v7, v215
	v_pk_add_f32 v[84:85], v[84:85], v[6:7] op_sel_hi:[1,0] neg_lo:[0,1] neg_hi:[0,1]
	s_nop 0
	v_pk_mul_f32 v[84:85], v[6:7], v[84:85] op_sel:[1,0]
	v_pk_add_f32 v[80:81], v[80:81], v[6:7] op_sel_hi:[1,0] neg_lo:[0,1] neg_hi:[0,1]
	v_pk_fma_f32 v[84:85], v[88:89], v[84:85], v[90:91]
	v_pk_mul_f32 v[6:7], v[6:7], v[80:81] op_sel:[1,0]
	v_and_b32_sdwa v80, v84, v216 dst_sel:DWORD dst_unused:UNUSED_PAD src0_sel:WORD_1 src1_sel:DWORD
	v_pk_fma_f32 v[6:7], v[0:1], v[6:7], v[4:5]
	v_add3_u32 v80, v84, v80, s77
	v_and_b32_e32 v81, 0xffff0000, v80
	v_and_b32_sdwa v80, v7, v216 dst_sel:DWORD dst_unused:UNUSED_PAD src0_sel:WORD_1 src1_sel:DWORD
	v_and_b32_sdwa v3, v85, v216 dst_sel:DWORD dst_unused:UNUSED_PAD src0_sel:WORD_1 src1_sel:DWORD
	v_and_b32_sdwa v96, v6, v216 dst_sel:DWORD dst_unused:UNUSED_PAD src0_sel:WORD_1 src1_sel:DWORD
	v_add3_u32 v80, v7, v80, s77
	v_add3_u32 v3, v85, v3, s77
	v_add3_u32 v100, v6, v96, s77
	v_and_b32_e32 v101, 0xffff0000, v80
	v_or_b32_sdwa v97, v101, v3 dst_sel:DWORD dst_unused:UNUSED_PAD src0_sel:DWORD src1_sel:WORD_1
	v_or_b32_sdwa v96, v100, v81 dst_sel:DWORD dst_unused:UNUSED_PAD src0_sel:WORD_1 src1_sel:DWORD
	v_add_u32_e32 v80, v2, v137
	ds_write_b64 v80, v[96:97]
	v_and_b32_e32 v96, 0xffff0000, v100
	v_sub_u32_e32 v81, v84, v81
	v_and_b32_e32 v3, 0xffff0000, v3
	v_sub_u32_e32 v6, v6, v96
	v_add_u32_e32 v81, 0x80, v81
	v_sub_u32_e32 v3, v85, v3
	v_sub_u32_e32 v7, v7, v101
	v_add_u32_e32 v6, 0x80, v6
	v_ashrrev_i32_e32 v81, 8, v81
	v_add_u32_e32 v3, 0x80, v3
	v_add_u32_e32 v7, 0x80, v7
	v_ashrrev_i32_e32 v6, 8, v6
	v_min_i32_e32 v81, 0x7f, v81
	v_ashrrev_i32_e32 v3, 8, v3
	v_ashrrev_i32_e32 v7, 8, v7
	v_min_i32_e32 v6, 0x7f, v6
	v_min_i32_sdwa v3, v3, s78 dst_sel:WORD_1 dst_unused:UNUSED_PAD src0_sel:DWORD src1_sel:DWORD
	v_min_i32_e32 v7, 0x7f, v7
	v_lshlrev_b32_e32 v81, 8, v81
	v_and_b32_e32 v81, 0xff00, v81
	v_and_b32_e32 v3, 0xff0000, v3
	v_perm_b32 v6, v7, v6, s79
	v_or3_b32 v3, v6, v81, v3
	ds_write_b32 v18, v3 offset:144
	v_mov_b32_e32 v6, v252
	v_mov_b32_e32 v7, v253
	v_or_b32_e32 v81, 0x6000, v148
	v_or_b32_e32 v96, 0x6000, v146
	v_pk_add_f32 v[72:73], v[72:73], v[6:7] op_sel_hi:[1,0] neg_lo:[0,1] neg_hi:[0,1]
	s_nop 0
	v_pk_mul_f32 v[72:73], v[6:7], v[72:73] op_sel:[1,0]
	s_nop 0
	v_pk_fma_f32 v[84:85], v[88:89], v[72:73], v[90:91]
	v_pk_add_f32 v[72:73], v[74:75], v[6:7] op_sel_hi:[1,0] neg_lo:[0,1] neg_hi:[0,1]
	v_and_b32_sdwa v3, v85, v216 dst_sel:DWORD dst_unused:UNUSED_PAD src0_sel:WORD_1 src1_sel:DWORD
	v_pk_mul_f32 v[6:7], v[6:7], v[72:73] op_sel:[1,0]
	v_add3_u32 v3, v85, v3, s77
	v_pk_fma_f32 v[0:1], v[0:1], v[6:7], v[4:5]
	v_and_b32_sdwa v4, v84, v216 dst_sel:DWORD dst_unused:UNUSED_PAD src0_sel:WORD_1 src1_sel:DWORD
	v_add3_u32 v4, v84, v4, s77
	v_and_b32_e32 v6, 0xffff0000, v4
	v_and_b32_sdwa v4, v1, v216 dst_sel:DWORD dst_unused:UNUSED_PAD src0_sel:WORD_1 src1_sel:DWORD
	v_and_b32_sdwa v5, v0, v216 dst_sel:DWORD dst_unused:UNUSED_PAD src0_sel:WORD_1 src1_sel:DWORD
	v_add3_u32 v4, v1, v4, s77
	v_add3_u32 v7, v0, v5, s77
	v_and_b32_e32 v72, 0xffff0000, v4
	v_add_u32_e32 v73, v2, v136
	v_and_b32_e32 v2, 0xffff0000, v7
	v_or_b32_sdwa v5, v72, v3 dst_sel:DWORD dst_unused:UNUSED_PAD src0_sel:DWORD src1_sel:WORD_1
	v_sub_u32_e32 v0, v0, v2
	v_sub_u32_e32 v2, v84, v6
	v_and_b32_e32 v3, 0xffff0000, v3
	v_add_u32_e32 v2, 0x80, v2
	v_sub_u32_e32 v3, v85, v3
	v_sub_u32_e32 v1, v1, v72
	v_add_u32_e32 v0, 0x80, v0
	v_ashrrev_i32_e32 v2, 8, v2
	v_add_u32_e32 v3, 0x80, v3
	v_add_u32_e32 v1, 0x80, v1
	v_ashrrev_i32_e32 v0, 8, v0
	v_min_i32_e32 v2, 0x7f, v2
	v_ashrrev_i32_e32 v3, 8, v3
	v_ashrrev_i32_e32 v1, 8, v1
	v_min_i32_e32 v0, 0x7f, v0
	v_min_i32_sdwa v3, v3, s78 dst_sel:WORD_1 dst_unused:UNUSED_PAD src0_sel:DWORD src1_sel:DWORD
	v_min_i32_e32 v1, 0x7f, v1
	v_lshlrev_b32_e32 v2, 8, v2
	v_and_b32_e32 v2, 0xff00, v2
	v_and_b32_e32 v3, 0xff0000, v3
	v_perm_b32 v0, v1, v0, s79
	v_or_b32_sdwa v4, v7, v6 dst_sel:DWORD dst_unused:UNUSED_PAD src0_sel:WORD_1 src1_sel:DWORD
	v_or3_b32 v0, v0, v2, v3
	ds_write_b64 v73, v[4:5]
	ds_write_b32 v22, v0 offset:144
	v_add_u32_e32 v72, s59, v151
	s_waitcnt lgkmcnt(0)
	s_barrier
; #define WAIT_L(n) asm volatile("s_waitcnt lgkmcnt(" #n ")" ::: "memory")
; #define BAR __builtin_amdgcn_s_barrier()
;     ...
;             _Pragma("unroll") for (int m = 0; m < 4; ++m) {
;               const int rr = wr3 * 64 + m * 16 + fr3;
;               const float2 ms = *reinterpret_cast<const float2*>(mr + (ai * HALF + rr) * 2);
;               f32x4 y = acc[ai][bj][m][n];
;               const float o0 = (y[0] - ms.x) * ms.y * gm.x + bt.x, o1 = (y[1] - ms.x) * ms.y * gm.y + bt.y;
;               const float o2 = (y[2] - ms.x) * ms.y * gm.z + bt.z, o3 = (y[3] - ms.x) * ms.y * gm.w + bt.w;
;               const unsigned h0 = f2bf(o0), h1 = f2bf(o1), h2 = f2bf(o2), h3 = f2bf(o3);
;               u32x2 ob; ob[0] = h0 | (h1 << 16); ob[1] = h2 | (h3 << 16);
;               *reinterpret_cast<u32x2*>(smem + (rr >> 1) * PIECE + (rr & 1) * 512 + cc * 2) = ob;
;               const int l0 = min(((int)__float_as_uint(o0) - (int)(h0 << 16) + 128) >> 8, 127);
;               const int l1 = min(((int)__float_as_uint(o1) - (int)(h1 << 16) + 128) >> 8, 127);
;               const int l2 = min(((int)__float_as_uint(o2) - (int)(h2 << 16) + 128) >> 8, 127);
;               const int l3 = min(((int)__float_as_uint(o3) - (int)(h3 << 16) + 128) >> 8, 127);
;               *reinterpret_cast<unsigned*>(smem + LOBASE + (rr >> 2) * PIECE + (rr & 3) * 256 + cc) =
;                   (unsigned)(l0 & 255) | ((unsigned)(l1 & 255) << 8) | ((unsigned)(l2 & 255) << 16) | ((unsigned)l3 << 24);
;             }
;           }
;           WAIT_L(0); BAR;
;           const int hso = ((brow + ai * HALF + 16 * wave) * DM + pn * BM) * 2;
;           const int lso = (brow + ai * HALF + 16 * wave) * DM + pn * BM;
;           _Pragma("unroll") for (int i = 0; i < 8; ++i) {
;             const u32x4 v = *reinterpret_cast<const u32x4*>(smem + (wave * 8 + i) * PIECE + lane3 * 16);
;             __builtin_amdgcn_raw_buffer_store_b128(v, rsXB, hvo + i * (2 * DM * 2), hso, 0);
;           }
;           _Pragma("unroll") for (int i = 0; i < 4; ++i) {
;             const u32x4 v = *reinterpret_cast<const u32x4*>(smem + LOBASE + (wave * 4 + i) * PIECE + lane3 * 16);
;             __builtin_amdgcn_raw_buffer_store_b128(v, rsLO, lvo + i * (4 * DM), lso, 0);
	ds_read_b128 v[128:131], v72
	v_or_b32_e32 v74, 0x2000, v148
	v_or_b32_e32 v75, 0x4000, v148
	v_or_b32_e32 v84, 0x8000, v148
	v_or_b32_e32 v85, 0xa000, v148
	ds_read_b128 v[136:139], v72 offset:1040
	v_or_b32_e32 v88, 0xc000, v148
	v_or_b32_e32 v89, 0xe000, v148
	v_or_b32_e32 v90, 0x2000, v146
	v_or_b32_e32 v91, 0x4000, v146
	ds_read_b128 v[140:143], v72 offset:2080
	ds_read_b128 v[152:155], v72 offset:3120
	ds_read_b128 v[156:159], v72 offset:4160
	ds_read_b128 v[160:163], v72 offset:5200
	ds_read_b128 v[164:167], v72 offset:6240
	ds_read_b128 v[168:171], v72 offset:7280
	ds_read_b128 v[172:175], v147
	ds_read_b128 v[176:179], v147 offset:1040
	ds_read_b128 v[180:183], v147 offset:2080
	ds_read_b128 v[184:187], v147 offset:3120
	s_waitcnt lgkmcnt(0)
	s_barrier
	s_nop 1
	v_mov_b32_e32 v0, v220
	v_mov_b32_e32 v1, v221
	v_mov_b32_e32 v2, v222
	v_mov_b32_e32 v3, v223
	v_mov_b32_e32 v4, v236
	v_mov_b32_e32 v5, v237
	v_mov_b32_e32 v6, v238
	v_mov_b32_e32 v7, v239
	ds_read_b64 v[110:111], v149 offset:1024
	s_waitcnt lgkmcnt(0)
	v_mov_b32_e32 v210, v110
	v_mov_b32_e32 v211, v111
	v_pk_add_f32 v[64:65], v[64:65], v[110:111] op_sel_hi:[1,0] neg_lo:[0,1] neg_hi:[0,1]
	s_nop 0
	v_pk_mul_f32 v[64:65], v[110:111], v[64:65] op_sel:[1,0]
	v_pk_add_f32 v[66:67], v[66:67], v[110:111] op_sel_hi:[1,0] neg_lo:[0,1] neg_hi:[0,1]
	v_mov_b32_e32 v100, v1
	v_mov_b32_e32 v101, v2
	v_mov_b32_e32 v104, v5
	v_mov_b32_e32 v105, v6
	v_pk_fma_f32 v[64:65], v[100:101], v[64:65], v[104:105]
	v_pk_mul_f32 v[66:67], v[110:111], v[66:67] op_sel:[1,0]
	v_mov_b32_e32 v1, v3
	v_mov_b32_e32 v5, v7
	v_and_b32_sdwa v6, v65, v216 dst_sel:DWORD dst_unused:UNUSED_PAD src0_sel:WORD_1 src1_sel:DWORD
	v_and_b32_sdwa v7, v64, v216 dst_sel:DWORD dst_unused:UNUSED_PAD src0_sel:WORD_1 src1_sel:DWORD
	v_pk_fma_f32 v[2:3], v[0:1], v[66:67], v[4:5]
	v_add3_u32 v66, v65, v6, s77
	v_add3_u32 v6, v64, v7, s77
	v_and_b32_e32 v67, 0xffff0000, v6
	v_and_b32_sdwa v6, v3, v216 dst_sel:DWORD dst_unused:UNUSED_PAD src0_sel:WORD_1 src1_sel:DWORD
	v_and_b32_sdwa v7, v2, v216 dst_sel:DWORD dst_unused:UNUSED_PAD src0_sel:WORD_1 src1_sel:DWORD
	v_add3_u32 v6, v3, v6, s77
	v_add3_u32 v97, v2, v7, s77
	v_and_b32_e32 v103, 0xffff0000, v6
	v_or_b32_sdwa v7, v103, v66 dst_sel:DWORD dst_unused:UNUSED_PAD src0_sel:DWORD src1_sel:WORD_1
	v_or_b32_sdwa v6, v97, v67 dst_sel:DWORD dst_unused:UNUSED_PAD src0_sel:WORD_1 src1_sel:DWORD
	ds_write_b64 v132, v[6:7]
	v_and_b32_e32 v6, 0xffff0000, v97
	v_sub_u32_e32 v2, v2, v6
	v_sub_u32_e32 v6, v64, v67
	v_and_b32_e32 v7, 0xffff0000, v66
	v_add_u32_e32 v6, 0x80, v6
	v_sub_u32_e32 v7, v65, v7
	v_sub_u32_e32 v3, v3, v103
	v_add_u32_e32 v2, 0x80, v2
	v_ashrrev_i32_e32 v6, 8, v6
	v_add_u32_e32 v7, 0x80, v7
	v_add_u32_e32 v3, 0x80, v3
	v_ashrrev_i32_e32 v2, 8, v2
	v_min_i32_e32 v6, 0x7f, v6
	v_ashrrev_i32_e32 v7, 8, v7
	v_ashrrev_i32_e32 v3, 8, v3
	v_min_i32_e32 v2, 0x7f, v2
	v_min_i32_sdwa v7, v7, s78 dst_sel:WORD_1 dst_unused:UNUSED_PAD src0_sel:DWORD src1_sel:DWORD
	v_min_i32_e32 v3, 0x7f, v3
	v_lshlrev_b32_e32 v6, 8, v6
	v_and_b32_e32 v6, 0xff00, v6
	v_and_b32_e32 v7, 0xff0000, v7
	v_perm_b32 v2, v3, v2, s79
	v_or3_b32 v2, v2, v6, v7
	ds_write_b32 v12, v2
	buffer_store_dwordx4 v[128:131], v148, s[16:19], s76 offen
	ds_read_b64 v[2:3], v13 offset:1024
	s_waitcnt lgkmcnt(0)
	v_mov_b32_e32 v212, v2
	v_mov_b32_e32 v213, v3
	v_pk_add_f32 v[6:7], v[68:69], v[2:3] op_sel_hi:[1,0] neg_lo:[0,1] neg_hi:[0,1]
	s_nop 0
	v_pk_mul_f32 v[6:7], v[2:3], v[6:7] op_sel:[1,0]
	v_pk_add_f32 v[64:65], v[70:71], v[2:3] op_sel_hi:[1,0] neg_lo:[0,1] neg_hi:[0,1]
	v_pk_fma_f32 v[6:7], v[100:101], v[6:7], v[104:105]
	v_pk_mul_f32 v[2:3], v[2:3], v[64:65] op_sel:[1,0]
	v_and_b32_sdwa v64, v7, v216 dst_sel:DWORD dst_unused:UNUSED_PAD src0_sel:WORD_1 src1_sel:DWORD
	v_and_b32_sdwa v65, v6, v216 dst_sel:DWORD dst_unused:UNUSED_PAD src0_sel:WORD_1 src1_sel:DWORD
	v_pk_fma_f32 v[2:3], v[0:1], v[2:3], v[4:5]
	v_add3_u32 v66, v7, v64, s77
	v_add3_u32 v64, v6, v65, s77
	v_and_b32_e32 v67, 0xffff0000, v64
	v_and_b32_sdwa v64, v3, v216 dst_sel:DWORD dst_unused:UNUSED_PAD src0_sel:WORD_1 src1_sel:DWORD
	v_and_b32_sdwa v65, v2, v216 dst_sel:DWORD dst_unused:UNUSED_PAD src0_sel:WORD_1 src1_sel:DWORD
	v_add3_u32 v64, v3, v64, s77
	v_add3_u32 v68, v2, v65, s77
	v_and_b32_e32 v69, 0xffff0000, v64
	v_or_b32_sdwa v65, v69, v66 dst_sel:DWORD dst_unused:UNUSED_PAD src0_sel:DWORD src1_sel:WORD_1
	v_or_b32_sdwa v64, v68, v67 dst_sel:DWORD dst_unused:UNUSED_PAD src0_sel:WORD_1 src1_sel:DWORD
	ds_write_b64 v133, v[64:65]
	v_and_b32_e32 v64, 0xffff0000, v68
	v_sub_u32_e32 v2, v2, v64
	v_sub_u32_e32 v6, v6, v67
	v_and_b32_e32 v64, 0xffff0000, v66
	v_add_u32_e32 v6, 0x80, v6
	v_sub_u32_e32 v7, v7, v64
	v_sub_u32_e32 v3, v3, v69
	v_add_u32_e32 v2, 0x80, v2
	v_ashrrev_i32_e32 v6, 8, v6
	v_add_u32_e32 v7, 0x80, v7
	v_add_u32_e32 v3, 0x80, v3
	v_ashrrev_i32_e32 v2, 8, v2
	v_min_i32_e32 v6, 0x7f, v6
	v_ashrrev_i32_e32 v7, 8, v7
	v_ashrrev_i32_e32 v3, 8, v3
	v_min_i32_e32 v2, 0x7f, v2
	v_min_i32_sdwa v7, v7, s78 dst_sel:WORD_1 dst_unused:UNUSED_PAD src0_sel:DWORD src1_sel:DWORD
	v_min_i32_e32 v3, 0x7f, v3
	v_lshlrev_b32_e32 v6, 8, v6
	v_and_b32_e32 v6, 0xff00, v6
	v_and_b32_e32 v7, 0xff0000, v7
	v_perm_b32 v2, v3, v2, s79
	v_or3_b32 v2, v2, v6, v7
	ds_write_b32 v14, v2
	buffer_store_dwordx4 v[136:139], v74, s[16:19], s76 offen
	ds_read_b64 v[2:3], v15 offset:1024
	s_waitcnt lgkmcnt(0)
; #define WAIT_L(n) asm volatile("s_waitcnt lgkmcnt(" #n ")" ::: "memory")
; #define BAR __builtin_amdgcn_s_barrier()
;     ...
;             _Pragma("unroll") for (int m = 0; m < 4; ++m) {
;               const int rr = wr3 * 64 + m * 16 + fr3;
;               const float2 ms = *reinterpret_cast<const float2*>(mr + (ai * HALF + rr) * 2);
;               f32x4 y = acc[ai][bj][m][n];
;               const float o0 = (y[0] - ms.x) * ms.y * gm.x + bt.x, o1 = (y[1] - ms.x) * ms.y * gm.y + bt.y;
;               const float o2 = (y[2] - ms.x) * ms.y * gm.z + bt.z, o3 = (y[3] - ms.x) * ms.y * gm.w + bt.w;
;               const unsigned h0 = f2bf(o0), h1 = f2bf(o1), h2 = f2bf(o2), h3 = f2bf(o3);
;               u32x2 ob; ob[0] = h0 | (h1 << 16); ob[1] = h2 | (h3 << 16);
;               *reinterpret_cast<u32x2*>(smem + (rr >> 1) * PIECE + (rr & 1) * 512 + cc * 2) = ob;
;               const int l0 = min(((int)__float_as_uint(o0) - (int)(h0 << 16) + 128) >> 8, 127);
;               const int l1 = min(((int)__float_as_uint(o1) - (int)(h1 << 16) + 128) >> 8, 127);
;               const int l2 = min(((int)__float_as_uint(o2) - (int)(h2 << 16) + 128) >> 8, 127);
;               const int l3 = min(((int)__float_as_uint(o3) - (int)(h3 << 16) + 128) >> 8, 127);
;               *reinterpret_cast<unsigned*>(smem + LOBASE + (rr >> 2) * PIECE + (rr & 3) * 256 + cc) =
;                   (unsigned)(l0 & 255) | ((unsigned)(l1 & 255) << 8) | ((unsigned)(l2 & 255) << 16) | ((unsigned)l3 << 24);
;             }
;           }
;           WAIT_L(0); BAR;
;           const int hso = ((brow + ai * HALF + 16 * wave) * DM + pn * BM) * 2;
;           const int lso = (brow + ai * HALF + 16 * wave) * DM + pn * BM;
;           _Pragma("unroll") for (int i = 0; i < 8; ++i) {
;             const u32x4 v = *reinterpret_cast<const u32x4*>(smem + (wave * 8 + i) * PIECE + lane3 * 16);
;             __builtin_amdgcn_raw_buffer_store_b128(v, rsXB, hvo + i * (2 * DM * 2), hso, 0);
;           }
;           _Pragma("unroll") for (int i = 0; i < 4; ++i) {
;             const u32x4 v = *reinterpret_cast<const u32x4*>(smem + LOBASE + (wave * 4 + i) * PIECE + lane3 * 16);
;             __builtin_amdgcn_raw_buffer_store_b128(v, rsLO, lvo + i * (4 * DM), lso, 0);
	v_mov_b32_e32 v214, v2
	v_mov_b32_e32 v215, v3
	v_pk_add_f32 v[6:7], v[76:77], v[2:3] op_sel_hi:[1,0] neg_lo:[0,1] neg_hi:[0,1]
	s_nop 0
	v_pk_mul_f32 v[6:7], v[2:3], v[6:7] op_sel:[1,0]
	v_pk_add_f32 v[64:65], v[78:79], v[2:3] op_sel_hi:[1,0] neg_lo:[0,1] neg_hi:[0,1]
	v_pk_fma_f32 v[6:7], v[100:101], v[6:7], v[104:105]
	v_pk_mul_f32 v[2:3], v[2:3], v[64:65] op_sel:[1,0]
	v_and_b32_sdwa v64, v7, v216 dst_sel:DWORD dst_unused:UNUSED_PAD src0_sel:WORD_1 src1_sel:DWORD
	v_and_b32_sdwa v65, v6, v216 dst_sel:DWORD dst_unused:UNUSED_PAD src0_sel:WORD_1 src1_sel:DWORD
	v_pk_fma_f32 v[2:3], v[0:1], v[2:3], v[4:5]
	v_add3_u32 v66, v7, v64, s77
	v_add3_u32 v64, v6, v65, s77
	v_and_b32_e32 v67, 0xffff0000, v64
	v_and_b32_sdwa v64, v3, v216 dst_sel:DWORD dst_unused:UNUSED_PAD src0_sel:WORD_1 src1_sel:DWORD
	v_and_b32_sdwa v65, v2, v216 dst_sel:DWORD dst_unused:UNUSED_PAD src0_sel:WORD_1 src1_sel:DWORD
	v_add3_u32 v64, v3, v64, s77
	v_add3_u32 v68, v2, v65, s77
	v_and_b32_e32 v69, 0xffff0000, v64
	v_or_b32_sdwa v65, v69, v66 dst_sel:DWORD dst_unused:UNUSED_PAD src0_sel:DWORD src1_sel:WORD_1
	v_or_b32_sdwa v64, v68, v67 dst_sel:DWORD dst_unused:UNUSED_PAD src0_sel:WORD_1 src1_sel:DWORD
	ds_write_b64 v134, v[64:65]
	v_and_b32_e32 v64, 0xffff0000, v68
	v_sub_u32_e32 v2, v2, v64
	v_sub_u32_e32 v6, v6, v67
	v_and_b32_e32 v64, 0xffff0000, v66
	v_add_u32_e32 v6, 0x80, v6
	v_sub_u32_e32 v7, v7, v64
	v_sub_u32_e32 v3, v3, v69
	v_add_u32_e32 v2, 0x80, v2
	v_ashrrev_i32_e32 v6, 8, v6
	v_add_u32_e32 v7, 0x80, v7
	v_add_u32_e32 v3, 0x80, v3
	v_ashrrev_i32_e32 v2, 8, v2
	v_min_i32_e32 v6, 0x7f, v6
	v_ashrrev_i32_e32 v7, 8, v7
	v_ashrrev_i32_e32 v3, 8, v3
	v_min_i32_e32 v2, 0x7f, v2
	v_min_i32_sdwa v7, v7, s78 dst_sel:WORD_1 dst_unused:UNUSED_PAD src0_sel:DWORD src1_sel:DWORD
	v_min_i32_e32 v3, 0x7f, v3
	v_lshlrev_b32_e32 v6, 8, v6
	v_and_b32_e32 v6, 0xff00, v6
	v_and_b32_e32 v7, 0xff0000, v7
	v_perm_b32 v2, v3, v2, s79
	v_or3_b32 v2, v2, v6, v7
	ds_write_b32 v18, v2
	buffer_store_dwordx4 v[140:143], v75, s[16:19], s76 offen
	ds_read_b64 v[2:3], v19 offset:1024
	s_waitcnt lgkmcnt(0)
	v_mov_b32_e32 v252, v2
	v_mov_b32_e32 v253, v3
	v_pk_add_f32 v[6:7], v[82:83], v[2:3] op_sel_hi:[1,0] neg_lo:[0,1] neg_hi:[0,1]
	s_nop 0
	v_pk_mul_f32 v[6:7], v[2:3], v[6:7] op_sel:[1,0]
	v_pk_add_f32 v[64:65], v[86:87], v[2:3] op_sel_hi:[1,0] neg_lo:[0,1] neg_hi:[0,1]
	v_pk_fma_f32 v[6:7], v[100:101], v[6:7], v[104:105]
	v_pk_mul_f32 v[2:3], v[2:3], v[64:65] op_sel:[1,0]
	s_nop 0
	v_pk_fma_f32 v[0:1], v[0:1], v[2:3], v[4:5]
	v_and_b32_sdwa v2, v7, v216 dst_sel:DWORD dst_unused:UNUSED_PAD src0_sel:WORD_1 src1_sel:DWORD
	v_and_b32_sdwa v3, v6, v216 dst_sel:DWORD dst_unused:UNUSED_PAD src0_sel:WORD_1 src1_sel:DWORD
	v_add3_u32 v4, v7, v2, s77
	v_add3_u32 v2, v6, v3, s77
	v_and_b32_e32 v5, 0xffff0000, v2
	v_and_b32_sdwa v2, v1, v216 dst_sel:DWORD dst_unused:UNUSED_PAD src0_sel:WORD_1 src1_sel:DWORD
	v_and_b32_sdwa v3, v0, v216 dst_sel:DWORD dst_unused:UNUSED_PAD src0_sel:WORD_1 src1_sel:DWORD
	v_add3_u32 v2, v1, v2, s77
	v_add3_u32 v64, v0, v3, s77
	v_and_b32_e32 v65, 0xffff0000, v2
	v_or_b32_sdwa v3, v65, v4 dst_sel:DWORD dst_unused:UNUSED_PAD src0_sel:DWORD src1_sel:WORD_1
	v_or_b32_sdwa v2, v64, v5 dst_sel:DWORD dst_unused:UNUSED_PAD src0_sel:WORD_1 src1_sel:DWORD
	ds_write_b64 v135, v[2:3]
	v_and_b32_e32 v2, 0xffff0000, v64
	v_sub_u32_e32 v0, v0, v2
	v_sub_u32_e32 v2, v6, v5
	v_and_b32_e32 v3, 0xffff0000, v4
	v_add_u32_e32 v2, 0x80, v2
	v_sub_u32_e32 v3, v7, v3
	v_sub_u32_e32 v1, v1, v65
	v_add_u32_e32 v0, 0x80, v0
	v_ashrrev_i32_e32 v2, 8, v2
	v_add_u32_e32 v3, 0x80, v3
	v_add_u32_e32 v1, 0x80, v1
	v_ashrrev_i32_e32 v0, 8, v0
	v_min_i32_e32 v2, 0x7f, v2
	v_ashrrev_i32_e32 v3, 8, v3
	v_ashrrev_i32_e32 v1, 8, v1
	v_min_i32_e32 v0, 0x7f, v0
	v_min_i32_sdwa v3, v3, s78 dst_sel:WORD_1 dst_unused:UNUSED_PAD src0_sel:DWORD src1_sel:DWORD
	v_min_i32_e32 v1, 0x7f, v1
	v_lshlrev_b32_e32 v2, 8, v2
	v_and_b32_e32 v2, 0xff00, v2
	v_and_b32_e32 v3, 0xff0000, v3
	v_perm_b32 v0, v1, v0, s79
	v_or3_b32 v0, v0, v2, v3
	ds_write_b32 v22, v0
	buffer_store_dwordx4 v[152:155], v81, s[16:19], s76 offen
	v_mov_b32_e32 v0, v224
	v_mov_b32_e32 v1, v225
	v_mov_b32_e32 v2, v226
	v_mov_b32_e32 v3, v227
	v_mov_b32_e32 v4, v240
	v_mov_b32_e32 v5, v241
	v_mov_b32_e32 v6, v242
	v_mov_b32_e32 v7, v243
	v_mov_b32_e32 v68, v210
	v_mov_b32_e32 v69, v211
	v_pk_add_f32 v[60:61], v[60:61], v[68:69] op_sel_hi:[1,0] neg_lo:[0,1] neg_hi:[0,1]
	s_nop 0
	v_pk_mul_f32 v[60:61], v[68:69], v[60:61] op_sel:[1,0]
	v_pk_add_f32 v[58:59], v[58:59], v[68:69] op_sel_hi:[1,0] neg_lo:[0,1] neg_hi:[0,1]
	v_mov_b32_e32 v64, v1
	v_mov_b32_e32 v65, v2
	v_mov_b32_e32 v66, v5
	v_mov_b32_e32 v67, v6
	v_pk_fma_f32 v[60:61], v[64:65], v[60:61], v[66:67]
	v_pk_mul_f32 v[58:59], v[68:69], v[58:59] op_sel:[1,0]
	v_mov_b32_e32 v1, v3
	v_mov_b32_e32 v5, v7
	v_and_b32_sdwa v6, v61, v216 dst_sel:DWORD dst_unused:UNUSED_PAD src0_sel:WORD_1 src1_sel:DWORD
	v_and_b32_sdwa v7, v60, v216 dst_sel:DWORD dst_unused:UNUSED_PAD src0_sel:WORD_1 src1_sel:DWORD
	v_pk_fma_f32 v[2:3], v[0:1], v[58:59], v[4:5]
	v_add3_u32 v58, v61, v6, s77
	v_add3_u32 v6, v60, v7, s77
	v_and_b32_e32 v59, 0xffff0000, v6
	v_and_b32_sdwa v6, v3, v216 dst_sel:DWORD dst_unused:UNUSED_PAD src0_sel:WORD_1 src1_sel:DWORD
	v_and_b32_sdwa v7, v2, v216 dst_sel:DWORD dst_unused:UNUSED_PAD src0_sel:WORD_1 src1_sel:DWORD
	v_add3_u32 v6, v3, v6, s77
	v_add3_u32 v68, v2, v7, s77
	v_and_b32_e32 v69, 0xffff0000, v6
	v_or_b32_sdwa v7, v69, v58 dst_sel:DWORD dst_unused:UNUSED_PAD src0_sel:DWORD src1_sel:WORD_1
	v_or_b32_sdwa v6, v68, v59 dst_sel:DWORD dst_unused:UNUSED_PAD src0_sel:WORD_1 src1_sel:DWORD
; #define WAIT_L(n) asm volatile("s_waitcnt lgkmcnt(" #n ")" ::: "memory")
; #define BAR __builtin_amdgcn_s_barrier()
;     ...
;             _Pragma("unroll") for (int m = 0; m < 4; ++m) {
;               const int rr = wr3 * 64 + m * 16 + fr3;
;               const float2 ms = *reinterpret_cast<const float2*>(mr + (ai * HALF + rr) * 2);
;               f32x4 y = acc[ai][bj][m][n];
;               const float o0 = (y[0] - ms.x) * ms.y * gm.x + bt.x, o1 = (y[1] - ms.x) * ms.y * gm.y + bt.y;
;               const float o2 = (y[2] - ms.x) * ms.y * gm.z + bt.z, o3 = (y[3] - ms.x) * ms.y * gm.w + bt.w;
;               const unsigned h0 = f2bf(o0), h1 = f2bf(o1), h2 = f2bf(o2), h3 = f2bf(o3);
;               u32x2 ob; ob[0] = h0 | (h1 << 16); ob[1] = h2 | (h3 << 16);
;               *reinterpret_cast<u32x2*>(smem + (rr >> 1) * PIECE + (rr & 1) * 512 + cc * 2) = ob;
;               const int l0 = min(((int)__float_as_uint(o0) - (int)(h0 << 16) + 128) >> 8, 127);
;               const int l1 = min(((int)__float_as_uint(o1) - (int)(h1 << 16) + 128) >> 8, 127);
;               const int l2 = min(((int)__float_as_uint(o2) - (int)(h2 << 16) + 128) >> 8, 127);
;               const int l3 = min(((int)__float_as_uint(o3) - (int)(h3 << 16) + 128) >> 8, 127);
;               *reinterpret_cast<unsigned*>(smem + LOBASE + (rr >> 2) * PIECE + (rr & 3) * 256 + cc) =
;                   (unsigned)(l0 & 255) | ((unsigned)(l1 & 255) << 8) | ((unsigned)(l2 & 255) << 16) | ((unsigned)l3 << 24);
;             }
;           }
;           WAIT_L(0); BAR;
;           const int hso = ((brow + ai * HALF + 16 * wave) * DM + pn * BM) * 2;
;           const int lso = (brow + ai * HALF + 16 * wave) * DM + pn * BM;
;           _Pragma("unroll") for (int i = 0; i < 8; ++i) {
;             const u32x4 v = *reinterpret_cast<const u32x4*>(smem + (wave * 8 + i) * PIECE + lane3 * 16);
;             __builtin_amdgcn_raw_buffer_store_b128(v, rsXB, hvo + i * (2 * DM * 2), hso, 0);
;           }
;           _Pragma("unroll") for (int i = 0; i < 4; ++i) {
;             const u32x4 v = *reinterpret_cast<const u32x4*>(smem + LOBASE + (wave * 4 + i) * PIECE + lane3 * 16);
;             __builtin_amdgcn_raw_buffer_store_b128(v, rsLO, lvo + i * (4 * DM), lso, 0);
	ds_write_b64 v23, v[6:7]
	v_and_b32_e32 v6, 0xffff0000, v68
	v_sub_u32_e32 v2, v2, v6
	v_sub_u32_e32 v6, v60, v59
	v_and_b32_e32 v7, 0xffff0000, v58
	v_add_u32_e32 v6, 0x80, v6
	v_sub_u32_e32 v7, v61, v7
	v_sub_u32_e32 v3, v3, v69
	v_add_u32_e32 v2, 0x80, v2
	v_ashrrev_i32_e32 v6, 8, v6
	v_add_u32_e32 v7, 0x80, v7
	v_add_u32_e32 v3, 0x80, v3
	v_ashrrev_i32_e32 v2, 8, v2
	v_min_i32_e32 v6, 0x7f, v6
	v_ashrrev_i32_e32 v7, 8, v7
	v_ashrrev_i32_e32 v3, 8, v3
	v_min_i32_e32 v2, 0x7f, v2
	v_min_i32_sdwa v7, v7, s78 dst_sel:WORD_1 dst_unused:UNUSED_PAD src0_sel:DWORD src1_sel:DWORD
	v_min_i32_e32 v3, 0x7f, v3
	v_lshlrev_b32_e32 v6, 8, v6
	v_and_b32_e32 v6, 0xff00, v6
	v_and_b32_e32 v7, 0xff0000, v7
	v_perm_b32 v2, v3, v2, s79
	v_or3_b32 v2, v2, v6, v7
	ds_write_b32 v12, v2 offset:16
	buffer_store_dwordx4 v[156:159], v84, s[16:19], s76 offen
	v_mov_b32_e32 v2, v212
	v_mov_b32_e32 v3, v213
	v_pk_add_f32 v[6:7], v[44:45], v[2:3] op_sel_hi:[1,0] neg_lo:[0,1] neg_hi:[0,1]
	s_nop 0
	v_pk_mul_f32 v[6:7], v[2:3], v[6:7] op_sel:[1,0]
	v_pk_add_f32 v[42:43], v[42:43], v[2:3] op_sel_hi:[1,0] neg_lo:[0,1] neg_hi:[0,1]
	v_pk_fma_f32 v[6:7], v[64:65], v[6:7], v[66:67]
	v_pk_mul_f32 v[2:3], v[2:3], v[42:43] op_sel:[1,0]
	v_and_b32_sdwa v42, v6, v216 dst_sel:DWORD dst_unused:UNUSED_PAD src0_sel:WORD_1 src1_sel:DWORD
	v_pk_fma_f32 v[2:3], v[0:1], v[2:3], v[4:5]
	v_add3_u32 v42, v6, v42, s77
	v_and_b32_e32 v44, 0xffff0000, v42
	v_and_b32_sdwa v42, v3, v216 dst_sel:DWORD dst_unused:UNUSED_PAD src0_sel:WORD_1 src1_sel:DWORD
	v_and_b32_sdwa v23, v7, v216 dst_sel:DWORD dst_unused:UNUSED_PAD src0_sel:WORD_1 src1_sel:DWORD
	v_and_b32_sdwa v43, v2, v216 dst_sel:DWORD dst_unused:UNUSED_PAD src0_sel:WORD_1 src1_sel:DWORD
	v_add3_u32 v42, v3, v42, s77
	v_add3_u32 v23, v7, v23, s77
	v_add3_u32 v45, v2, v43, s77
	v_and_b32_e32 v58, 0xffff0000, v42
	v_or_b32_sdwa v43, v58, v23 dst_sel:DWORD dst_unused:UNUSED_PAD src0_sel:DWORD src1_sel:WORD_1
	v_or_b32_sdwa v42, v45, v44 dst_sel:DWORD dst_unused:UNUSED_PAD src0_sel:WORD_1 src1_sel:DWORD
	ds_write_b64 v108, v[42:43]
	v_and_b32_e32 v42, 0xffff0000, v45
	v_sub_u32_e32 v6, v6, v44
	v_and_b32_e32 v23, 0xffff0000, v23
	v_sub_u32_e32 v2, v2, v42
	v_add_u32_e32 v6, 0x80, v6
	v_sub_u32_e32 v7, v7, v23
	v_sub_u32_e32 v3, v3, v58
	v_add_u32_e32 v2, 0x80, v2
	v_ashrrev_i32_e32 v6, 8, v6
	v_add_u32_e32 v7, 0x80, v7
	v_add_u32_e32 v3, 0x80, v3
	v_ashrrev_i32_e32 v2, 8, v2
	v_min_i32_e32 v6, 0x7f, v6
	v_ashrrev_i32_e32 v7, 8, v7
	v_ashrrev_i32_e32 v3, 8, v3
	v_min_i32_e32 v2, 0x7f, v2
	v_min_i32_sdwa v7, v7, s78 dst_sel:WORD_1 dst_unused:UNUSED_PAD src0_sel:DWORD src1_sel:DWORD
	v_min_i32_e32 v3, 0x7f, v3
	v_lshlrev_b32_e32 v6, 8, v6
	v_and_b32_e32 v6, 0xff00, v6
	v_and_b32_e32 v7, 0xff0000, v7
	v_perm_b32 v2, v3, v2, s79
	v_or3_b32 v2, v2, v6, v7
	ds_write_b32 v14, v2 offset:16
	buffer_store_dwordx4 v[160:163], v85, s[16:19], s76 offen
	v_mov_b32_e32 v2, v214
	v_mov_b32_e32 v3, v215
	v_pk_add_f32 v[6:7], v[34:35], v[2:3] op_sel_hi:[1,0] neg_lo:[0,1] neg_hi:[0,1]
	s_nop 0
	v_pk_mul_f32 v[6:7], v[2:3], v[6:7] op_sel:[1,0]
	v_pk_add_f32 v[34:35], v[46:47], v[2:3] op_sel_hi:[1,0] neg_lo:[0,1] neg_hi:[0,1]
	v_pk_fma_f32 v[6:7], v[64:65], v[6:7], v[66:67]
	v_pk_mul_f32 v[2:3], v[2:3], v[34:35] op_sel:[1,0]
	v_and_b32_sdwa v34, v6, v216 dst_sel:DWORD dst_unused:UNUSED_PAD src0_sel:WORD_1 src1_sel:DWORD
	v_pk_fma_f32 v[2:3], v[0:1], v[2:3], v[4:5]
	v_add3_u32 v34, v6, v34, s77
	v_and_b32_e32 v42, 0xffff0000, v34
	v_and_b32_sdwa v34, v3, v216 dst_sel:DWORD dst_unused:UNUSED_PAD src0_sel:WORD_1 src1_sel:DWORD
	v_and_b32_sdwa v23, v7, v216 dst_sel:DWORD dst_unused:UNUSED_PAD src0_sel:WORD_1 src1_sel:DWORD
	v_and_b32_sdwa v35, v2, v216 dst_sel:DWORD dst_unused:UNUSED_PAD src0_sel:WORD_1 src1_sel:DWORD
	v_add3_u32 v34, v3, v34, s77
	v_add3_u32 v23, v7, v23, s77
	v_add3_u32 v43, v2, v35, s77
	v_and_b32_e32 v44, 0xffff0000, v34
	v_or_b32_sdwa v35, v44, v23 dst_sel:DWORD dst_unused:UNUSED_PAD src0_sel:DWORD src1_sel:WORD_1
	v_or_b32_sdwa v34, v43, v42 dst_sel:DWORD dst_unused:UNUSED_PAD src0_sel:WORD_1 src1_sel:DWORD
	ds_write_b64 v98, v[34:35]
	v_and_b32_e32 v34, 0xffff0000, v43
	v_sub_u32_e32 v6, v6, v42
	v_and_b32_e32 v23, 0xffff0000, v23
	v_sub_u32_e32 v2, v2, v34
	v_add_u32_e32 v6, 0x80, v6
	v_sub_u32_e32 v7, v7, v23
	v_sub_u32_e32 v3, v3, v44
	v_add_u32_e32 v2, 0x80, v2
	v_ashrrev_i32_e32 v6, 8, v6
	v_add_u32_e32 v7, 0x80, v7
	v_add_u32_e32 v3, 0x80, v3
	v_ashrrev_i32_e32 v2, 8, v2
	v_min_i32_e32 v6, 0x7f, v6
	v_ashrrev_i32_e32 v7, 8, v7
	v_ashrrev_i32_e32 v3, 8, v3
	v_min_i32_e32 v2, 0x7f, v2
	v_min_i32_sdwa v7, v7, s78 dst_sel:WORD_1 dst_unused:UNUSED_PAD src0_sel:DWORD src1_sel:DWORD
	v_min_i32_e32 v3, 0x7f, v3
	v_lshlrev_b32_e32 v6, 8, v6
	v_and_b32_e32 v6, 0xff00, v6
	v_and_b32_e32 v7, 0xff0000, v7
	v_perm_b32 v2, v3, v2, s79
	v_or3_b32 v2, v2, v6, v7
	ds_write_b32 v18, v2 offset:16
	buffer_store_dwordx4 v[164:167], v88, s[16:19], s76 offen
	v_mov_b32_e32 v2, v252
	v_mov_b32_e32 v3, v253
	v_pk_add_f32 v[6:7], v[50:51], v[2:3] op_sel_hi:[1,0] neg_lo:[0,1] neg_hi:[0,1]
	s_nop 0
	v_pk_mul_f32 v[6:7], v[2:3], v[6:7] op_sel:[1,0]
	v_pk_add_f32 v[34:35], v[62:63], v[2:3] op_sel_hi:[1,0] neg_lo:[0,1] neg_hi:[0,1]
	v_pk_fma_f32 v[6:7], v[64:65], v[6:7], v[66:67]
	v_pk_mul_f32 v[2:3], v[2:3], v[34:35] op_sel:[1,0]
	s_nop 0
	v_pk_fma_f32 v[0:1], v[0:1], v[2:3], v[4:5]
	v_and_b32_sdwa v2, v7, v216 dst_sel:DWORD dst_unused:UNUSED_PAD src0_sel:WORD_1 src1_sel:DWORD
	v_and_b32_sdwa v3, v6, v216 dst_sel:DWORD dst_unused:UNUSED_PAD src0_sel:WORD_1 src1_sel:DWORD
	v_add3_u32 v4, v7, v2, s77
	v_add3_u32 v2, v6, v3, s77
	v_and_b32_e32 v5, 0xffff0000, v2
; #define WAIT_L(n) asm volatile("s_waitcnt lgkmcnt(" #n ")" ::: "memory")
; #define BAR __builtin_amdgcn_s_barrier()
;     ...
;             _Pragma("unroll") for (int m = 0; m < 4; ++m) {
;               const int rr = wr3 * 64 + m * 16 + fr3;
;               const float2 ms = *reinterpret_cast<const float2*>(mr + (ai * HALF + rr) * 2);
;               f32x4 y = acc[ai][bj][m][n];
;               const float o0 = (y[0] - ms.x) * ms.y * gm.x + bt.x, o1 = (y[1] - ms.x) * ms.y * gm.y + bt.y;
;               const float o2 = (y[2] - ms.x) * ms.y * gm.z + bt.z, o3 = (y[3] - ms.x) * ms.y * gm.w + bt.w;
;               const unsigned h0 = f2bf(o0), h1 = f2bf(o1), h2 = f2bf(o2), h3 = f2bf(o3);
;               u32x2 ob; ob[0] = h0 | (h1 << 16); ob[1] = h2 | (h3 << 16);
;               *reinterpret_cast<u32x2*>(smem + (rr >> 1) * PIECE + (rr & 1) * 512 + cc * 2) = ob;
;               const int l0 = min(((int)__float_as_uint(o0) - (int)(h0 << 16) + 128) >> 8, 127);
;               const int l1 = min(((int)__float_as_uint(o1) - (int)(h1 << 16) + 128) >> 8, 127);
;               const int l2 = min(((int)__float_as_uint(o2) - (int)(h2 << 16) + 128) >> 8, 127);
;               const int l3 = min(((int)__float_as_uint(o3) - (int)(h3 << 16) + 128) >> 8, 127);
;               *reinterpret_cast<unsigned*>(smem + LOBASE + (rr >> 2) * PIECE + (rr & 3) * 256 + cc) =
;                   (unsigned)(l0 & 255) | ((unsigned)(l1 & 255) << 8) | ((unsigned)(l2 & 255) << 16) | ((unsigned)l3 << 24);
;             }
;           }
;           WAIT_L(0); BAR;
;           const int hso = ((brow + ai * HALF + 16 * wave) * DM + pn * BM) * 2;
;           const int lso = (brow + ai * HALF + 16 * wave) * DM + pn * BM;
;           _Pragma("unroll") for (int i = 0; i < 8; ++i) {
;             const u32x4 v = *reinterpret_cast<const u32x4*>(smem + (wave * 8 + i) * PIECE + lane3 * 16);
;             __builtin_amdgcn_raw_buffer_store_b128(v, rsXB, hvo + i * (2 * DM * 2), hso, 0);
;           }
;           _Pragma("unroll") for (int i = 0; i < 4; ++i) {
;             const u32x4 v = *reinterpret_cast<const u32x4*>(smem + LOBASE + (wave * 4 + i) * PIECE + lane3 * 16);
;             __builtin_amdgcn_raw_buffer_store_b128(v, rsLO, lvo + i * (4 * DM), lso, 0);
	v_and_b32_sdwa v2, v1, v216 dst_sel:DWORD dst_unused:UNUSED_PAD src0_sel:WORD_1 src1_sel:DWORD
	v_and_b32_sdwa v3, v0, v216 dst_sel:DWORD dst_unused:UNUSED_PAD src0_sel:WORD_1 src1_sel:DWORD
	v_add3_u32 v2, v1, v2, s77
	v_add3_u32 v23, v0, v3, s77
	v_and_b32_e32 v34, 0xffff0000, v2
	v_or_b32_sdwa v3, v34, v4 dst_sel:DWORD dst_unused:UNUSED_PAD src0_sel:DWORD src1_sel:WORD_1
	v_or_b32_sdwa v2, v23, v5 dst_sel:DWORD dst_unused:UNUSED_PAD src0_sel:WORD_1 src1_sel:DWORD
	ds_write_b64 v99, v[2:3]
	v_and_b32_e32 v2, 0xffff0000, v23
	v_sub_u32_e32 v0, v0, v2
	v_sub_u32_e32 v2, v6, v5
	v_and_b32_e32 v3, 0xffff0000, v4
	v_add_u32_e32 v2, 0x80, v2
	v_sub_u32_e32 v3, v7, v3
	v_sub_u32_e32 v1, v1, v34
	v_add_u32_e32 v0, 0x80, v0
	v_ashrrev_i32_e32 v2, 8, v2
	v_add_u32_e32 v3, 0x80, v3
	v_add_u32_e32 v1, 0x80, v1
	v_ashrrev_i32_e32 v0, 8, v0
	v_min_i32_e32 v2, 0x7f, v2
	v_ashrrev_i32_e32 v3, 8, v3
	v_ashrrev_i32_e32 v1, 8, v1
	v_min_i32_e32 v0, 0x7f, v0
	v_min_i32_sdwa v3, v3, s78 dst_sel:WORD_1 dst_unused:UNUSED_PAD src0_sel:DWORD src1_sel:DWORD
	v_min_i32_e32 v1, 0x7f, v1
	v_lshlrev_b32_e32 v2, 8, v2
	v_and_b32_e32 v2, 0xff00, v2
	v_and_b32_e32 v3, 0xff0000, v3
	v_perm_b32 v0, v1, v0, s79
	v_or3_b32 v0, v0, v2, v3
	ds_write_b32 v22, v0 offset:16
	buffer_store_dwordx4 v[168:171], v89, s[16:19], s76 offen
	v_mov_b32_e32 v0, v228
	v_mov_b32_e32 v1, v229
	v_mov_b32_e32 v2, v230
	v_mov_b32_e32 v3, v231
	v_mov_b32_e32 v4, v244
	v_mov_b32_e32 v5, v245
	v_mov_b32_e32 v6, v246
	v_mov_b32_e32 v7, v247
	v_mov_b32_e32 v44, v210
	v_mov_b32_e32 v45, v211
	v_pk_add_f32 v[46:47], v[56:57], v[44:45] op_sel_hi:[1,0] neg_lo:[0,1] neg_hi:[0,1]
	s_nop 0
	v_pk_mul_f32 v[46:47], v[44:45], v[46:47] op_sel:[1,0]
	v_pk_add_f32 v[50:51], v[54:55], v[44:45] op_sel_hi:[1,0] neg_lo:[0,1] neg_hi:[0,1]
	v_mov_b32_e32 v34, v1
	v_mov_b32_e32 v35, v2
	v_mov_b32_e32 v42, v5
	v_mov_b32_e32 v43, v6
	v_pk_fma_f32 v[46:47], v[34:35], v[46:47], v[42:43]
	v_pk_mul_f32 v[44:45], v[44:45], v[50:51] op_sel:[1,0]
	v_mov_b32_e32 v1, v3
	v_mov_b32_e32 v5, v7
	v_and_b32_sdwa v6, v47, v216 dst_sel:DWORD dst_unused:UNUSED_PAD src0_sel:WORD_1 src1_sel:DWORD
	v_and_b32_sdwa v7, v46, v216 dst_sel:DWORD dst_unused:UNUSED_PAD src0_sel:WORD_1 src1_sel:DWORD
	v_pk_fma_f32 v[2:3], v[0:1], v[44:45], v[4:5]
	v_add3_u32 v23, v47, v6, s77
	v_add3_u32 v6, v46, v7, s77
	v_and_b32_e32 v44, 0xffff0000, v6
	v_and_b32_sdwa v6, v3, v216 dst_sel:DWORD dst_unused:UNUSED_PAD src0_sel:WORD_1 src1_sel:DWORD
	v_and_b32_sdwa v7, v2, v216 dst_sel:DWORD dst_unused:UNUSED_PAD src0_sel:WORD_1 src1_sel:DWORD
	v_add3_u32 v6, v3, v6, s77
	v_add3_u32 v45, v2, v7, s77
	v_and_b32_e32 v50, 0xffff0000, v6
	v_or_b32_sdwa v7, v50, v23 dst_sel:DWORD dst_unused:UNUSED_PAD src0_sel:DWORD src1_sel:WORD_1
	v_or_b32_sdwa v6, v45, v44 dst_sel:DWORD dst_unused:UNUSED_PAD src0_sel:WORD_1 src1_sel:DWORD
	ds_write_b64 v106, v[6:7]
	v_and_b32_e32 v6, 0xffff0000, v45
	v_sub_u32_e32 v2, v2, v6
	v_sub_u32_e32 v6, v46, v44
	v_and_b32_e32 v7, 0xffff0000, v23
	v_add_u32_e32 v6, 0x80, v6
	v_sub_u32_e32 v7, v47, v7
	v_sub_u32_e32 v3, v3, v50
	v_add_u32_e32 v2, 0x80, v2
	v_ashrrev_i32_e32 v6, 8, v6
	v_add_u32_e32 v7, 0x80, v7
	v_add_u32_e32 v3, 0x80, v3
	v_ashrrev_i32_e32 v2, 8, v2
	v_min_i32_e32 v6, 0x7f, v6
	v_ashrrev_i32_e32 v7, 8, v7
	v_ashrrev_i32_e32 v3, 8, v3
	v_min_i32_e32 v2, 0x7f, v2
	v_min_i32_sdwa v7, v7, s78 dst_sel:WORD_1 dst_unused:UNUSED_PAD src0_sel:DWORD src1_sel:DWORD
	v_min_i32_e32 v3, 0x7f, v3
	v_lshlrev_b32_e32 v6, 8, v6
	v_and_b32_e32 v6, 0xff00, v6
	v_and_b32_e32 v7, 0xff0000, v7
	v_perm_b32 v2, v3, v2, s79
	v_or3_b32 v2, v2, v6, v7
	ds_write_b32 v12, v2 offset:128
	buffer_store_dwordx4 v[172:175], v146, s[20:23], s33 offen
	v_mov_b32_e32 v2, v212
	v_mov_b32_e32 v3, v213
	v_pk_add_f32 v[6:7], v[40:41], v[2:3] op_sel_hi:[1,0] neg_lo:[0,1] neg_hi:[0,1]
	s_nop 0
	v_pk_mul_f32 v[6:7], v[2:3], v[6:7] op_sel:[1,0]
	v_pk_add_f32 v[38:39], v[38:39], v[2:3] op_sel_hi:[1,0] neg_lo:[0,1] neg_hi:[0,1]
	v_pk_fma_f32 v[6:7], v[34:35], v[6:7], v[42:43]
	v_pk_mul_f32 v[2:3], v[2:3], v[38:39] op_sel:[1,0]
	v_and_b32_sdwa v38, v6, v216 dst_sel:DWORD dst_unused:UNUSED_PAD src0_sel:WORD_1 src1_sel:DWORD
	v_pk_fma_f32 v[2:3], v[0:1], v[2:3], v[4:5]
	v_add3_u32 v38, v6, v38, s77
	v_and_b32_e32 v40, 0xffff0000, v38
	v_and_b32_sdwa v38, v3, v216 dst_sel:DWORD dst_unused:UNUSED_PAD src0_sel:WORD_1 src1_sel:DWORD
	v_and_b32_sdwa v23, v7, v216 dst_sel:DWORD dst_unused:UNUSED_PAD src0_sel:WORD_1 src1_sel:DWORD
	v_and_b32_sdwa v39, v2, v216 dst_sel:DWORD dst_unused:UNUSED_PAD src0_sel:WORD_1 src1_sel:DWORD
	v_add3_u32 v38, v3, v38, s77
	v_add3_u32 v23, v7, v23, s77
	v_add3_u32 v41, v2, v39, s77
	v_and_b32_e32 v44, 0xffff0000, v38
	v_or_b32_sdwa v39, v44, v23 dst_sel:DWORD dst_unused:UNUSED_PAD src0_sel:DWORD src1_sel:WORD_1
	v_or_b32_sdwa v38, v41, v40 dst_sel:DWORD dst_unused:UNUSED_PAD src0_sel:WORD_1 src1_sel:DWORD
	ds_write_b64 v102, v[38:39]
	v_and_b32_e32 v38, 0xffff0000, v41
	v_sub_u32_e32 v6, v6, v40
	v_and_b32_e32 v23, 0xffff0000, v23
	v_sub_u32_e32 v2, v2, v38
	v_add_u32_e32 v6, 0x80, v6
	v_sub_u32_e32 v7, v7, v23
	v_sub_u32_e32 v3, v3, v44
	v_add_u32_e32 v2, 0x80, v2
	v_ashrrev_i32_e32 v6, 8, v6
	v_add_u32_e32 v7, 0x80, v7
	v_add_u32_e32 v3, 0x80, v3
	v_ashrrev_i32_e32 v2, 8, v2
	v_min_i32_e32 v6, 0x7f, v6
	v_ashrrev_i32_e32 v7, 8, v7
	v_ashrrev_i32_e32 v3, 8, v3
	v_min_i32_e32 v2, 0x7f, v2
	v_min_i32_sdwa v7, v7, s78 dst_sel:WORD_1 dst_unused:UNUSED_PAD src0_sel:DWORD src1_sel:DWORD
	v_min_i32_e32 v3, 0x7f, v3
	v_lshlrev_b32_e32 v6, 8, v6
	v_and_b32_e32 v6, 0xff00, v6
	v_and_b32_e32 v7, 0xff0000, v7
	v_perm_b32 v2, v3, v2, s79
	v_or3_b32 v2, v2, v6, v7
; #define WAIT_L(n) asm volatile("s_waitcnt lgkmcnt(" #n ")" ::: "memory")
; #define BAR __builtin_amdgcn_s_barrier()
;     ...
;             _Pragma("unroll") for (int m = 0; m < 4; ++m) {
;               const int rr = wr3 * 64 + m * 16 + fr3;
;               const float2 ms = *reinterpret_cast<const float2*>(mr + (ai * HALF + rr) * 2);
;               f32x4 y = acc[ai][bj][m][n];
;               const float o0 = (y[0] - ms.x) * ms.y * gm.x + bt.x, o1 = (y[1] - ms.x) * ms.y * gm.y + bt.y;
;               const float o2 = (y[2] - ms.x) * ms.y * gm.z + bt.z, o3 = (y[3] - ms.x) * ms.y * gm.w + bt.w;
;               const unsigned h0 = f2bf(o0), h1 = f2bf(o1), h2 = f2bf(o2), h3 = f2bf(o3);
;               u32x2 ob; ob[0] = h0 | (h1 << 16); ob[1] = h2 | (h3 << 16);
;               *reinterpret_cast<u32x2*>(smem + (rr >> 1) * PIECE + (rr & 1) * 512 + cc * 2) = ob;
;               const int l0 = min(((int)__float_as_uint(o0) - (int)(h0 << 16) + 128) >> 8, 127);
;               const int l1 = min(((int)__float_as_uint(o1) - (int)(h1 << 16) + 128) >> 8, 127);
;               const int l2 = min(((int)__float_as_uint(o2) - (int)(h2 << 16) + 128) >> 8, 127);
;               const int l3 = min(((int)__float_as_uint(o3) - (int)(h3 << 16) + 128) >> 8, 127);
;               *reinterpret_cast<unsigned*>(smem + LOBASE + (rr >> 2) * PIECE + (rr & 3) * 256 + cc) =
;                   (unsigned)(l0 & 255) | ((unsigned)(l1 & 255) << 8) | ((unsigned)(l2 & 255) << 16) | ((unsigned)l3 << 24);
;             }
;           }
;           WAIT_L(0); BAR;
;           const int hso = ((brow + ai * HALF + 16 * wave) * DM + pn * BM) * 2;
;           const int lso = (brow + ai * HALF + 16 * wave) * DM + pn * BM;
;           _Pragma("unroll") for (int i = 0; i < 8; ++i) {
;             const u32x4 v = *reinterpret_cast<const u32x4*>(smem + (wave * 8 + i) * PIECE + lane3 * 16);
;             __builtin_amdgcn_raw_buffer_store_b128(v, rsXB, hvo + i * (2 * DM * 2), hso, 0);
;           }
;           _Pragma("unroll") for (int i = 0; i < 4; ++i) {
;             const u32x4 v = *reinterpret_cast<const u32x4*>(smem + LOBASE + (wave * 4 + i) * PIECE + lane3 * 16);
;             __builtin_amdgcn_raw_buffer_store_b128(v, rsLO, lvo + i * (4 * DM), lso, 0);
	ds_write_b32 v14, v2 offset:128
	buffer_store_dwordx4 v[176:179], v90, s[20:23], s33 offen
	v_mov_b32_e32 v2, v214
	v_mov_b32_e32 v3, v215
	v_pk_add_f32 v[6:7], v[24:25], v[2:3] op_sel_hi:[1,0] neg_lo:[0,1] neg_hi:[0,1]
	s_nop 0
	v_pk_mul_f32 v[6:7], v[2:3], v[6:7] op_sel:[1,0]
	v_pk_add_f32 v[24:25], v[26:27], v[2:3] op_sel_hi:[1,0] neg_lo:[0,1] neg_hi:[0,1]
	v_pk_fma_f32 v[6:7], v[34:35], v[6:7], v[42:43]
	v_pk_mul_f32 v[2:3], v[2:3], v[24:25] op_sel:[1,0]
	v_and_b32_sdwa v24, v6, v216 dst_sel:DWORD dst_unused:UNUSED_PAD src0_sel:WORD_1 src1_sel:DWORD
	v_pk_fma_f32 v[2:3], v[0:1], v[2:3], v[4:5]
	v_add3_u32 v24, v6, v24, s77
	v_and_b32_e32 v26, 0xffff0000, v24
	v_and_b32_sdwa v24, v3, v216 dst_sel:DWORD dst_unused:UNUSED_PAD src0_sel:WORD_1 src1_sel:DWORD
	v_and_b32_sdwa v23, v7, v216 dst_sel:DWORD dst_unused:UNUSED_PAD src0_sel:WORD_1 src1_sel:DWORD
	v_and_b32_sdwa v25, v2, v216 dst_sel:DWORD dst_unused:UNUSED_PAD src0_sel:WORD_1 src1_sel:DWORD
	v_add3_u32 v24, v3, v24, s77
	v_add3_u32 v23, v7, v23, s77
	v_add3_u32 v27, v2, v25, s77
	v_and_b32_e32 v38, 0xffff0000, v24
	v_or_b32_sdwa v25, v38, v23 dst_sel:DWORD dst_unused:UNUSED_PAD src0_sel:DWORD src1_sel:WORD_1
	v_or_b32_sdwa v24, v27, v26 dst_sel:DWORD dst_unused:UNUSED_PAD src0_sel:WORD_1 src1_sel:DWORD
	ds_write_b64 v92, v[24:25]
	v_and_b32_e32 v24, 0xffff0000, v27
	v_sub_u32_e32 v6, v6, v26
	v_and_b32_e32 v23, 0xffff0000, v23
	v_sub_u32_e32 v2, v2, v24
	v_add_u32_e32 v6, 0x80, v6
	v_sub_u32_e32 v7, v7, v23
	v_sub_u32_e32 v3, v3, v38
	v_add_u32_e32 v2, 0x80, v2
	v_ashrrev_i32_e32 v6, 8, v6
	v_add_u32_e32 v7, 0x80, v7
	v_add_u32_e32 v3, 0x80, v3
	v_ashrrev_i32_e32 v2, 8, v2
	v_min_i32_e32 v6, 0x7f, v6
	v_ashrrev_i32_e32 v7, 8, v7
	v_ashrrev_i32_e32 v3, 8, v3
	v_min_i32_e32 v2, 0x7f, v2
	v_min_i32_sdwa v7, v7, s78 dst_sel:WORD_1 dst_unused:UNUSED_PAD src0_sel:DWORD src1_sel:DWORD
	v_min_i32_e32 v3, 0x7f, v3
	v_lshlrev_b32_e32 v6, 8, v6
	v_and_b32_e32 v6, 0xff00, v6
	v_and_b32_e32 v7, 0xff0000, v7
	v_perm_b32 v2, v3, v2, s79
	v_or3_b32 v2, v2, v6, v7
	ds_write_b32 v18, v2 offset:128
	buffer_store_dwordx4 v[180:183], v91, s[20:23], s33 offen
	v_mov_b32_e32 v2, v252
	v_mov_b32_e32 v3, v253
	v_pk_add_f32 v[6:7], v[28:29], v[2:3] op_sel_hi:[1,0] neg_lo:[0,1] neg_hi:[0,1]
	s_nop 0
	v_pk_mul_f32 v[6:7], v[2:3], v[6:7] op_sel:[1,0]
	v_pk_add_f32 v[24:25], v[30:31], v[2:3] op_sel_hi:[1,0] neg_lo:[0,1] neg_hi:[0,1]
	v_pk_fma_f32 v[6:7], v[34:35], v[6:7], v[42:43]
	v_pk_mul_f32 v[2:3], v[2:3], v[24:25] op_sel:[1,0]
	s_nop 0
	v_pk_fma_f32 v[0:1], v[0:1], v[2:3], v[4:5]
	v_and_b32_sdwa v2, v7, v216 dst_sel:DWORD dst_unused:UNUSED_PAD src0_sel:WORD_1 src1_sel:DWORD
	v_and_b32_sdwa v3, v6, v216 dst_sel:DWORD dst_unused:UNUSED_PAD src0_sel:WORD_1 src1_sel:DWORD
	v_add3_u32 v4, v7, v2, s77
	v_add3_u32 v2, v6, v3, s77
	v_and_b32_e32 v5, 0xffff0000, v2
	v_and_b32_sdwa v2, v1, v216 dst_sel:DWORD dst_unused:UNUSED_PAD src0_sel:WORD_1 src1_sel:DWORD
	v_and_b32_sdwa v3, v0, v216 dst_sel:DWORD dst_unused:UNUSED_PAD src0_sel:WORD_1 src1_sel:DWORD
	v_add3_u32 v2, v1, v2, s77
	v_add3_u32 v23, v0, v3, s77
	v_and_b32_e32 v24, 0xffff0000, v2
	v_or_b32_sdwa v3, v24, v4 dst_sel:DWORD dst_unused:UNUSED_PAD src0_sel:DWORD src1_sel:WORD_1
	v_or_b32_sdwa v2, v23, v5 dst_sel:DWORD dst_unused:UNUSED_PAD src0_sel:WORD_1 src1_sel:DWORD
	ds_write_b64 v93, v[2:3]
	v_and_b32_e32 v2, 0xffff0000, v23
	v_sub_u32_e32 v0, v0, v2
	v_sub_u32_e32 v2, v6, v5
	v_and_b32_e32 v3, 0xffff0000, v4
	v_add_u32_e32 v2, 0x80, v2
	v_sub_u32_e32 v3, v7, v3
	v_sub_u32_e32 v1, v1, v24
	v_add_u32_e32 v0, 0x80, v0
	v_ashrrev_i32_e32 v2, 8, v2
	v_add_u32_e32 v3, 0x80, v3
	v_add_u32_e32 v1, 0x80, v1
	v_ashrrev_i32_e32 v0, 8, v0
	v_min_i32_e32 v2, 0x7f, v2
	v_ashrrev_i32_e32 v3, 8, v3
	v_ashrrev_i32_e32 v1, 8, v1
	v_min_i32_e32 v0, 0x7f, v0
	v_min_i32_sdwa v3, v3, s78 dst_sel:WORD_1 dst_unused:UNUSED_PAD src0_sel:DWORD src1_sel:DWORD
	v_min_i32_e32 v1, 0x7f, v1
	v_lshlrev_b32_e32 v2, 8, v2
	v_and_b32_e32 v2, 0xff00, v2
	v_and_b32_e32 v3, 0xff0000, v3
	v_perm_b32 v0, v1, v0, s79
	v_or3_b32 v0, v0, v2, v3
	ds_write_b32 v22, v0 offset:128
	buffer_store_dwordx4 v[184:187], v96, s[20:23], s33 offen
	v_mov_b32_e32 v0, v232
	v_mov_b32_e32 v1, v233
	v_mov_b32_e32 v2, v234
	v_mov_b32_e32 v3, v235
	v_mov_b32_e32 v4, v248
	v_mov_b32_e32 v5, v249
	v_mov_b32_e32 v6, v250
	v_mov_b32_e32 v7, v251
	v_mov_b32_e32 v28, v210
	v_mov_b32_e32 v29, v211
	s_mov_b64 s[4:5], -1
	v_pk_add_f32 v[30:31], v[52:53], v[28:29] op_sel_hi:[1,0] neg_lo:[0,1] neg_hi:[0,1]
	s_nop 0
	v_pk_mul_f32 v[30:31], v[28:29], v[30:31] op_sel:[1,0]
	v_pk_add_f32 v[34:35], v[48:49], v[28:29] op_sel_hi:[1,0] neg_lo:[0,1] neg_hi:[0,1]
	v_mov_b32_e32 v24, v1
	v_mov_b32_e32 v25, v2
	v_mov_b32_e32 v26, v5
	v_mov_b32_e32 v27, v6
	v_pk_fma_f32 v[30:31], v[24:25], v[30:31], v[26:27]
	v_pk_mul_f32 v[28:29], v[28:29], v[34:35] op_sel:[1,0]
	v_mov_b32_e32 v1, v3
	v_mov_b32_e32 v5, v7
	v_and_b32_sdwa v6, v31, v216 dst_sel:DWORD dst_unused:UNUSED_PAD src0_sel:WORD_1 src1_sel:DWORD
	v_and_b32_sdwa v7, v30, v216 dst_sel:DWORD dst_unused:UNUSED_PAD src0_sel:WORD_1 src1_sel:DWORD
	v_pk_fma_f32 v[2:3], v[0:1], v[28:29], v[4:5]
	v_add3_u32 v23, v31, v6, s77
	v_add3_u32 v6, v30, v7, s77
	v_and_b32_e32 v28, 0xffff0000, v6
	v_and_b32_sdwa v6, v3, v216 dst_sel:DWORD dst_unused:UNUSED_PAD src0_sel:WORD_1 src1_sel:DWORD
	v_and_b32_sdwa v7, v2, v216 dst_sel:DWORD dst_unused:UNUSED_PAD src0_sel:WORD_1 src1_sel:DWORD
	v_add3_u32 v6, v3, v6, s77
	v_add3_u32 v29, v2, v7, s77
	v_and_b32_e32 v34, 0xffff0000, v6
	v_or_b32_sdwa v7, v34, v23 dst_sel:DWORD dst_unused:UNUSED_PAD src0_sel:DWORD src1_sel:WORD_1
; #define WAIT_L(n) asm volatile("s_waitcnt lgkmcnt(" #n ")" ::: "memory")
; #define BAR __builtin_amdgcn_s_barrier()
;     ...
;             _Pragma("unroll") for (int m = 0; m < 4; ++m) {
;               const int rr = wr3 * 64 + m * 16 + fr3;
;               const float2 ms = *reinterpret_cast<const float2*>(mr + (ai * HALF + rr) * 2);
;               f32x4 y = acc[ai][bj][m][n];
;               const float o0 = (y[0] - ms.x) * ms.y * gm.x + bt.x, o1 = (y[1] - ms.x) * ms.y * gm.y + bt.y;
;               const float o2 = (y[2] - ms.x) * ms.y * gm.z + bt.z, o3 = (y[3] - ms.x) * ms.y * gm.w + bt.w;
;               const unsigned h0 = f2bf(o0), h1 = f2bf(o1), h2 = f2bf(o2), h3 = f2bf(o3);
;               u32x2 ob; ob[0] = h0 | (h1 << 16); ob[1] = h2 | (h3 << 16);
;               *reinterpret_cast<u32x2*>(smem + (rr >> 1) * PIECE + (rr & 1) * 512 + cc * 2) = ob;
;               const int l0 = min(((int)__float_as_uint(o0) - (int)(h0 << 16) + 128) >> 8, 127);
;               const int l1 = min(((int)__float_as_uint(o1) - (int)(h1 << 16) + 128) >> 8, 127);
;               const int l2 = min(((int)__float_as_uint(o2) - (int)(h2 << 16) + 128) >> 8, 127);
;               const int l3 = min(((int)__float_as_uint(o3) - (int)(h3 << 16) + 128) >> 8, 127);
;               *reinterpret_cast<unsigned*>(smem + LOBASE + (rr >> 2) * PIECE + (rr & 3) * 256 + cc) =
;                   (unsigned)(l0 & 255) | ((unsigned)(l1 & 255) << 8) | ((unsigned)(l2 & 255) << 16) | ((unsigned)l3 << 24);
;             }
;           }
;           WAIT_L(0); BAR;
	v_or_b32_sdwa v6, v29, v28 dst_sel:DWORD dst_unused:UNUSED_PAD src0_sel:WORD_1 src1_sel:DWORD
	ds_write_b64 v94, v[6:7]
	v_and_b32_e32 v6, 0xffff0000, v29
	v_sub_u32_e32 v2, v2, v6
	v_sub_u32_e32 v6, v30, v28
	v_and_b32_e32 v7, 0xffff0000, v23
	v_add_u32_e32 v6, 0x80, v6
	v_sub_u32_e32 v7, v31, v7
	v_sub_u32_e32 v3, v3, v34
	v_add_u32_e32 v2, 0x80, v2
	v_ashrrev_i32_e32 v6, 8, v6
	v_add_u32_e32 v7, 0x80, v7
	v_add_u32_e32 v3, 0x80, v3
	v_ashrrev_i32_e32 v2, 8, v2
	v_min_i32_e32 v6, 0x7f, v6
	v_ashrrev_i32_e32 v7, 8, v7
	v_ashrrev_i32_e32 v3, 8, v3
	v_min_i32_e32 v2, 0x7f, v2
	v_min_i32_sdwa v7, v7, s78 dst_sel:WORD_1 dst_unused:UNUSED_PAD src0_sel:DWORD src1_sel:DWORD
	v_min_i32_e32 v3, 0x7f, v3
	v_lshlrev_b32_e32 v6, 8, v6
	v_and_b32_e32 v6, 0xff00, v6
	v_and_b32_e32 v7, 0xff0000, v7
	v_perm_b32 v2, v3, v2, s79
	v_or3_b32 v2, v2, v6, v7
	ds_write_b32 v12, v2 offset:144
	v_mov_b32_e32 v2, v212
	v_mov_b32_e32 v3, v213
	v_pk_add_f32 v[6:7], v[36:37], v[2:3] op_sel_hi:[1,0] neg_lo:[0,1] neg_hi:[0,1]
	s_nop 0
	v_pk_mul_f32 v[6:7], v[2:3], v[6:7] op_sel:[1,0]
	v_pk_add_f32 v[12:13], v[32:33], v[2:3] op_sel_hi:[1,0] neg_lo:[0,1] neg_hi:[0,1]
	v_pk_fma_f32 v[6:7], v[24:25], v[6:7], v[26:27]
	v_pk_mul_f32 v[2:3], v[2:3], v[12:13] op_sel:[1,0]
	v_and_b32_sdwa v12, v7, v216 dst_sel:DWORD dst_unused:UNUSED_PAD src0_sel:WORD_1 src1_sel:DWORD
	v_and_b32_sdwa v13, v6, v216 dst_sel:DWORD dst_unused:UNUSED_PAD src0_sel:WORD_1 src1_sel:DWORD
	v_pk_fma_f32 v[2:3], v[0:1], v[2:3], v[4:5]
	v_add3_u32 v23, v7, v12, s77
	v_add3_u32 v12, v6, v13, s77
	v_and_b32_e32 v28, 0xffff0000, v12
	v_and_b32_sdwa v12, v3, v216 dst_sel:DWORD dst_unused:UNUSED_PAD src0_sel:WORD_1 src1_sel:DWORD
	v_and_b32_sdwa v13, v2, v216 dst_sel:DWORD dst_unused:UNUSED_PAD src0_sel:WORD_1 src1_sel:DWORD
	v_add3_u32 v12, v3, v12, s77
	v_add3_u32 v29, v2, v13, s77
	v_and_b32_e32 v30, 0xffff0000, v12
	v_or_b32_sdwa v13, v30, v23 dst_sel:DWORD dst_unused:UNUSED_PAD src0_sel:DWORD src1_sel:WORD_1
	v_or_b32_sdwa v12, v29, v28 dst_sel:DWORD dst_unused:UNUSED_PAD src0_sel:WORD_1 src1_sel:DWORD
	ds_write_b64 v95, v[12:13]
	v_and_b32_e32 v12, 0xffff0000, v29
	v_sub_u32_e32 v2, v2, v12
	v_sub_u32_e32 v6, v6, v28
	v_and_b32_e32 v12, 0xffff0000, v23
	v_add_u32_e32 v6, 0x80, v6
	v_sub_u32_e32 v7, v7, v12
	v_sub_u32_e32 v3, v3, v30
	v_add_u32_e32 v2, 0x80, v2
	v_ashrrev_i32_e32 v6, 8, v6
	v_add_u32_e32 v7, 0x80, v7
	v_add_u32_e32 v3, 0x80, v3
	v_ashrrev_i32_e32 v2, 8, v2
	v_min_i32_e32 v6, 0x7f, v6
	v_ashrrev_i32_e32 v7, 8, v7
	v_ashrrev_i32_e32 v3, 8, v3
	v_min_i32_e32 v2, 0x7f, v2
	v_min_i32_sdwa v7, v7, s78 dst_sel:WORD_1 dst_unused:UNUSED_PAD src0_sel:DWORD src1_sel:DWORD
	v_min_i32_e32 v3, 0x7f, v3
	v_lshlrev_b32_e32 v6, 8, v6
	v_and_b32_e32 v6, 0xff00, v6
	v_and_b32_e32 v7, 0xff0000, v7
	v_perm_b32 v2, v3, v2, s79
	v_or3_b32 v2, v2, v6, v7
	ds_write_b32 v14, v2 offset:144
	v_mov_b32_e32 v2, v214
	v_mov_b32_e32 v3, v215
	v_pk_add_f32 v[6:7], v[20:21], v[2:3] op_sel_hi:[1,0] neg_lo:[0,1] neg_hi:[0,1]
	s_nop 0
	v_pk_mul_f32 v[6:7], v[2:3], v[6:7] op_sel:[1,0]
	v_pk_add_f32 v[12:13], v[16:17], v[2:3] op_sel_hi:[1,0] neg_lo:[0,1] neg_hi:[0,1]
	v_pk_fma_f32 v[6:7], v[24:25], v[6:7], v[26:27]
	v_pk_mul_f32 v[2:3], v[2:3], v[12:13] op_sel:[1,0]
	v_and_b32_sdwa v12, v7, v216 dst_sel:DWORD dst_unused:UNUSED_PAD src0_sel:WORD_1 src1_sel:DWORD
	v_and_b32_sdwa v13, v6, v216 dst_sel:DWORD dst_unused:UNUSED_PAD src0_sel:WORD_1 src1_sel:DWORD
	v_pk_fma_f32 v[2:3], v[0:1], v[2:3], v[4:5]
	v_add3_u32 v14, v7, v12, s77
	v_add3_u32 v12, v6, v13, s77
	v_and_b32_e32 v15, 0xffff0000, v12
	v_and_b32_sdwa v12, v3, v216 dst_sel:DWORD dst_unused:UNUSED_PAD src0_sel:WORD_1 src1_sel:DWORD
	v_and_b32_sdwa v13, v2, v216 dst_sel:DWORD dst_unused:UNUSED_PAD src0_sel:WORD_1 src1_sel:DWORD
	v_add3_u32 v12, v3, v12, s77
	v_add3_u32 v16, v2, v13, s77
	v_and_b32_e32 v17, 0xffff0000, v12
	v_or_b32_sdwa v13, v17, v14 dst_sel:DWORD dst_unused:UNUSED_PAD src0_sel:DWORD src1_sel:WORD_1
	v_or_b32_sdwa v12, v16, v15 dst_sel:DWORD dst_unused:UNUSED_PAD src0_sel:WORD_1 src1_sel:DWORD
	ds_write_b64 v80, v[12:13]
	v_and_b32_e32 v12, 0xffff0000, v16
	v_sub_u32_e32 v2, v2, v12
	v_sub_u32_e32 v6, v6, v15
	v_and_b32_e32 v12, 0xffff0000, v14
	v_add_u32_e32 v6, 0x80, v6
	v_sub_u32_e32 v7, v7, v12
	v_sub_u32_e32 v3, v3, v17
	v_add_u32_e32 v2, 0x80, v2
	v_ashrrev_i32_e32 v6, 8, v6
	v_add_u32_e32 v7, 0x80, v7
	v_add_u32_e32 v3, 0x80, v3
	v_ashrrev_i32_e32 v2, 8, v2
	v_min_i32_e32 v6, 0x7f, v6
	v_ashrrev_i32_e32 v7, 8, v7
	v_ashrrev_i32_e32 v3, 8, v3
	v_min_i32_e32 v2, 0x7f, v2
	v_min_i32_sdwa v7, v7, s78 dst_sel:WORD_1 dst_unused:UNUSED_PAD src0_sel:DWORD src1_sel:DWORD
	v_min_i32_e32 v3, 0x7f, v3
	v_lshlrev_b32_e32 v6, 8, v6
	v_and_b32_e32 v6, 0xff00, v6
	v_and_b32_e32 v7, 0xff0000, v7
	v_perm_b32 v2, v3, v2, s79
	v_or3_b32 v2, v2, v6, v7
	ds_write_b32 v18, v2 offset:144
	v_mov_b32_e32 v2, v252
	v_mov_b32_e32 v3, v253
	v_pk_add_f32 v[6:7], v[8:9], v[2:3] op_sel_hi:[1,0] neg_lo:[0,1] neg_hi:[0,1]
	s_nop 0
	v_pk_mul_f32 v[6:7], v[2:3], v[6:7] op_sel:[1,0]
	v_pk_add_f32 v[8:9], v[10:11], v[2:3] op_sel_hi:[1,0] neg_lo:[0,1] neg_hi:[0,1]
	v_pk_fma_f32 v[6:7], v[24:25], v[6:7], v[26:27]
	v_pk_mul_f32 v[2:3], v[2:3], v[8:9] op_sel:[1,0]
	s_nop 0
	v_pk_fma_f32 v[0:1], v[0:1], v[2:3], v[4:5]
	v_and_b32_sdwa v2, v7, v216 dst_sel:DWORD dst_unused:UNUSED_PAD src0_sel:WORD_1 src1_sel:DWORD
	v_and_b32_sdwa v3, v6, v216 dst_sel:DWORD dst_unused:UNUSED_PAD src0_sel:WORD_1 src1_sel:DWORD
	v_add3_u32 v4, v7, v2, s77
	v_add3_u32 v2, v6, v3, s77
	v_and_b32_e32 v5, 0xffff0000, v2
	v_and_b32_sdwa v2, v1, v216 dst_sel:DWORD dst_unused:UNUSED_PAD src0_sel:WORD_1 src1_sel:DWORD
	v_and_b32_sdwa v3, v0, v216 dst_sel:DWORD dst_unused:UNUSED_PAD src0_sel:WORD_1 src1_sel:DWORD
	v_add3_u32 v2, v1, v2, s77
	v_add3_u32 v8, v0, v3, s77
	v_and_b32_e32 v9, 0xffff0000, v2
	v_or_b32_sdwa v3, v9, v4 dst_sel:DWORD dst_unused:UNUSED_PAD src0_sel:DWORD src1_sel:WORD_1
	v_or_b32_sdwa v2, v8, v5 dst_sel:DWORD dst_unused:UNUSED_PAD src0_sel:WORD_1 src1_sel:DWORD
	ds_write_b64 v73, v[2:3]
	v_and_b32_e32 v2, 0xffff0000, v8
	v_sub_u32_e32 v0, v0, v2
	v_sub_u32_e32 v2, v6, v5
	v_and_b32_e32 v3, 0xffff0000, v4
	v_add_u32_e32 v2, 0x80, v2
	v_sub_u32_e32 v3, v7, v3
	v_sub_u32_e32 v1, v1, v9
	v_add_u32_e32 v0, 0x80, v0
	v_ashrrev_i32_e32 v2, 8, v2
	v_add_u32_e32 v3, 0x80, v3
	v_add_u32_e32 v1, 0x80, v1
	v_ashrrev_i32_e32 v0, 8, v0
	v_min_i32_e32 v2, 0x7f, v2
	v_ashrrev_i32_e32 v3, 8, v3
	v_ashrrev_i32_e32 v1, 8, v1
	v_min_i32_e32 v0, 0x7f, v0
	v_min_i32_sdwa v3, v3, s78 dst_sel:WORD_1 dst_unused:UNUSED_PAD src0_sel:DWORD src1_sel:DWORD
	v_min_i32_e32 v1, 0x7f, v1
	v_lshlrev_b32_e32 v2, 8, v2
	v_and_b32_e32 v2, 0xff00, v2
	v_and_b32_e32 v3, 0xff0000, v3
	v_perm_b32 v0, v1, v0, s79
	v_or3_b32 v0, v0, v2, v3
	ds_write_b32 v22, v0 offset:144
	s_waitcnt lgkmcnt(0)
	s_barrier
; #define STAGE(P, RS, SOFF, OFF, kt) do { const int _so = (SOFF) + (kt) * (BK * 2); \
;     _Pragma("unroll") for (int _i = 0; _i < 2; ++_i) { \
;       __builtin_amdgcn_raw_ptr_buffer_load_lds(RS, (__attribute__((address_space(3))) void*)((P) + wave * 1024 + _i * 8192), 16, OFF[_i], _so, 0, 0); } } while (0)
; #define WAIT_L(n) asm volatile("s_waitcnt lgkmcnt(" #n ")" ::: "memory")
; #define BAR __builtin_amdgcn_s_barrier()
;     ...
;   auto issue_prologue = [&](int sA0, int sA1, int sB0, int sB1) {
;     const int tid = opaque_tid(wave);
;     int offA[2], offB[2];
;     _Pragma("unroll") for (int i = 0; i < 2; ++i) {
;       int r, c; stage_rc(tid * 16 + i * 8192, r, c);
;       offA[i] = (r * lda + c) * 2; offB[i] = (r * ldb + c) * 2;
;     }
;     STAGE(SB(0, 0), rsB, sB0, offB, 0); STAGE(SA(0, 0), rsA, sA0, offA, 0);
;     STAGE(SB(0, 1), rsB, sB1, offB, 0); STAGE(SA(0, 1), rsA, sA1, offA, 0);
;     STAGE(SB(1, 0), rsB, sB0, offB, 1); STAGE(SA(1, 0), rsA, sA0, offA, 1); STAGE(SB(1, 1), rsB, sB1, offB, 1);
;   };
;     ...
;           _Pragma("unroll") for (int i = 0; i < 8; ++i) {
;             const u32x4 v = *reinterpret_cast<const u32x4*>(smem + (wave * 8 + i) * PIECE + lane3 * 16);
;             __builtin_amdgcn_raw_buffer_store_b128(v, rsXB, hvo + i * (2 * DM * 2), hso, 0);
;           }
;           _Pragma("unroll") for (int i = 0; i < 4; ++i) {
;             const u32x4 v = *reinterpret_cast<const u32x4*>(smem + LOBASE + (wave * 4 + i) * PIECE + lane3 * 16);
;             __builtin_amdgcn_raw_buffer_store_b128(v, rsLO, lvo + i * (4 * DM), lso, 0);
;           }
;           WAIT_L(0); BAR;
;         }
;       }
;       if (has_next) issue_prologue(nA0, nA1, nB0, nB1);
	ds_read_b128 v[128:131], v72
	ds_read_b128 v[132:135], v72 offset:1040
	ds_read_b128 v[136:139], v72 offset:2080
	ds_read_b128 v[140:143], v72 offset:3120
	ds_read_b128 v[152:155], v72 offset:4160
	ds_read_b128 v[156:159], v72 offset:5200
	ds_read_b128 v[160:163], v72 offset:6240
	ds_read_b128 v[164:167], v72 offset:7280
	ds_read_b128 v[168:171], v147
	ds_read_b128 v[172:175], v147 offset:1040
	ds_read_b128 v[176:179], v147 offset:2080
	ds_read_b128 v[180:183], v147 offset:3120
	s_waitcnt lgkmcnt(0)
	s_barrier
	s_mov_b32 s98, s0
	s_cbranch_vccnz .Lmy_s1n_643
	v_mbcnt_lo_u32_b32 v0, -1, 0
	v_mbcnt_hi_u32_b32 v0, -1, v0
	s_mov_b32 m0, s85
	v_lshl_add_u32 v0, v0, 4, s38
	v_ashrrev_i32_e32 v1, 31, v0
	v_lshrrev_b32_e32 v1, 22, v1
	v_add_u32_e32 v1, v0, v1
	v_ashrrev_i32_e32 v1, 10, v1
	v_mul_i32_i24_e32 v2, 0x400, v1
	v_sub_u32_e32 v2, v0, v2
	v_lshrrev_b32_e32 v3, 4, v2
	v_bitop3_b32 v2, v3, v2, 32 bitop3:0x6c
	v_ashrrev_i32_e32 v4, 31, v2
	v_lshrrev_b32_e32 v4, 26, v4
	v_add_u32_e32 v4, v2, v4
	v_lshrrev_b32_e32 v5, 6, v4
	v_and_b32_e32 v4, 0xc0, v4
	v_lshlrev_b32_e32 v3, 3, v1
	v_lshlrev_b32_e32 v1, 5, v1
	v_sub_u32_e32 v2, v2, v4
	v_and_b32_e32 v3, 0xffff0, v3
	v_and_b32_e32 v1, 32, v1
	v_ashrrev_i16_sdwa v2, v216, sext(v2) dst_sel:DWORD dst_unused:UNUSED_PAD src0_sel:DWORD src1_sel:BYTE_0
	v_add_u32_sdwa v1, v1, sext(v2) dst_sel:DWORD dst_unused:UNUSED_PAD src0_sel:DWORD src1_sel:WORD_0
	v_add_lshl_u32 v2, v5, v3, 12
	v_add_u32_e32 v0, 0x2000, v0
	v_lshl_add_u32 v1, v1, 1, v2
	v_ashrrev_i32_e32 v2, 31, v0
	v_lshrrev_b32_e32 v2, 22, v2
	v_add_u32_e32 v2, v0, v2
	v_ashrrev_i32_e32 v2, 10, v2
	v_mul_i32_i24_e32 v3, 0x400, v2
	v_sub_u32_e32 v0, v0, v3
	v_lshrrev_b32_e32 v3, 4, v0
	v_bitop3_b32 v0, v3, v0, 32 bitop3:0x6c
	v_ashrrev_i32_e32 v4, 31, v0
	v_lshrrev_b32_e32 v4, 26, v4
	v_add_u32_e32 v4, v0, v4
	v_lshrrev_b32_e32 v5, 6, v4
	v_and_b32_e32 v4, 0xffc0, v4
	v_sub_u32_e32 v0, v0, v4
	v_lshrrev_b16_e32 v4, 7, v0
	v_and_b32_e32 v4, 1, v4
	v_lshlrev_b32_e32 v3, 3, v2
	v_lshlrev_b32_e32 v2, 5, v2
	v_add_u16_e32 v0, v0, v4
	v_and_b32_e32 v3, 0xffff0, v3
	v_and_b32_e32 v2, 32, v2
	v_ashrrev_i16_sdwa v0, v216, sext(v0) dst_sel:DWORD dst_unused:UNUSED_PAD src0_sel:DWORD src1_sel:BYTE_0
	v_add_u32_sdwa v0, v2, sext(v0) dst_sel:DWORD dst_unused:UNUSED_PAD src0_sel:DWORD src1_sel:WORD_0
	v_add_lshl_u32 v2, v5, v3, 12
	s_mov_b32 s14, s10
	s_mov_b32 s15, s11
	v_lshl_add_u32 v0, v0, 1, v2
	buffer_load_dwordx4 v1, s[12:15], s83 offen lds
	s_mov_b32 m0, s75
	s_or_b32 s0, s83, 0x80
	buffer_load_dwordx4 v0, s[12:15], s83 offen lds
	s_mov_b32 m0, s38
	s_mov_b64 s[4:5], 0
	buffer_load_dwordx4 v1, s[8:11], s82 offen lds
	s_mov_b32 m0, s95
	s_nop 0
	buffer_load_dwordx4 v0, s[8:11], s82 offen lds
	s_mov_b32 m0, s86
	s_nop 0
	buffer_load_dwordx4 v1, s[12:15], s84 offen lds
	s_mov_b32 m0, s28
	s_nop 0
	buffer_load_dwordx4 v0, s[12:15], s84 offen lds
	s_mov_b32 m0, s87
	s_nop 0
	buffer_load_dwordx4 v1, s[8:11], s81 offen lds
	s_mov_b32 m0, s97
	s_nop 0
	buffer_load_dwordx4 v0, s[8:11], s81 offen lds
	s_mov_b32 m0, s92
	s_nop 0
	buffer_load_dwordx4 v1, s[12:15], s0 offen lds
	s_mov_b32 m0, s29
	s_nop 0
	buffer_load_dwordx4 v0, s[12:15], s0 offen lds
	s_or_b32 s0, s82, 0x80
	s_mov_b32 m0, s93
	s_nop 0
	buffer_load_dwordx4 v1, s[8:11], s0 offen lds
	s_mov_b32 m0, s56
	s_nop 0
	buffer_load_dwordx4 v0, s[8:11], s0 offen lds
	s_add_i32 s0, s84, 0x80
	s_mov_b32 m0, s94
	s_nop 0
	buffer_load_dwordx4 v1, s[12:15], s0 offen lds
	s_mov_b32 m0, s57
	s_nop 0
	buffer_load_dwordx4 v0, s[12:15], s0 offen lds
	buffer_store_dwordx4 v[128:131], v148, s[16:19], s98 offen
	buffer_store_dwordx4 v[132:135], v74, s[16:19], s98 offen
	buffer_store_dwordx4 v[136:139], v75, s[16:19], s98 offen
	buffer_store_dwordx4 v[140:143], v81, s[16:19], s98 offen
	buffer_store_dwordx4 v[152:155], v84, s[16:19], s98 offen
	buffer_store_dwordx4 v[156:159], v85, s[16:19], s98 offen
	buffer_store_dwordx4 v[160:163], v88, s[16:19], s98 offen
	buffer_store_dwordx4 v[164:167], v89, s[16:19], s98 offen
	buffer_store_dwordx4 v[168:171], v146, s[20:23], s30 offen
	buffer_store_dwordx4 v[172:175], v90, s[20:23], s30 offen
	buffer_store_dwordx4 v[176:179], v91, s[20:23], s30 offen
	buffer_store_dwordx4 v[180:183], v96, s[20:23], s30 offen
	s_branch .LBB0_649

;     ...
;       const int tid3 = opaque_tid(wave);
;       const int wr3 = tid3 >> 8, wc3 = (tid3 >> 6) & 3, fr3 = tid3 & 15, fq3 = (tid3 & 63) >> 4;
;       const int ebase3 = (brow + wr3 * 64 + fr3) * DM + pn * BM + wc3 * 32 + fq3 * 4;
;       const int vo4b = ebase3 * 4, vo2 = ebase3 * 2, vo1 = ebase3;
;       (void)vo4b; (void)vo2; (void)vo1;
;       if constexpr (OUTF) {
;         _Pragma("unroll") for (int bj = 0; bj < 2; ++bj) _Pragma("unroll") for (int n = 0; n < 2; ++n) {
;           const int col = pn * BM + bj * HALF + wc3 * 32 + n * 16 + fq3 * 4;
;           const float4 gm = *reinterpret_cast<const float4*>(g.gam + col), bt = *reinterpret_cast<const float4*>(g.bet + col);
;           _Pragma("unroll") for (int ai = 0; ai < 2; ++ai) _Pragma("unroll") for (int m = 0; m < 4; ++m) {
;             const int rl = ai * HALF + wr3 * 64 + m * 16 + fr3;
;             const float2 ms = *reinterpret_cast<const float2*>(mr + rl * 2);
;             f32x4 y = acc[ai][bj][m][n];
;             u32x4 o;
;             o[0] = __float_as_uint((y[0] - ms.x) * ms.y * gm.x + bt.x); o[1] = __float_as_uint((y[1] - ms.x) * ms.y * gm.y + bt.y);
;             o[2] = __float_as_uint((y[2] - ms.x) * ms.y * gm.z + bt.z); o[3] = __float_as_uint((y[3] - ms.x) * ms.y * gm.w + bt.w);
;             __builtin_amdgcn_raw_buffer_store_b128(o, rsO, vo4b + ((ai * HALF + m * 16) * DM + bj * HALF + n * 16) * 4, 0, 0);
;           }
;         }
.LBB0_786:
	s_or_b64 exec, exec, s[6:7]
	s_waitcnt lgkmcnt(0)
	s_barrier
	v_mbcnt_lo_u32_b32 v4, -1, 0
	v_mbcnt_hi_u32_b32 v4, -1, v4
	v_readlane_b32 s76, v255, 32
	v_add_u32_e32 v5, s31, v4
	v_lshrrev_b32_e32 v0, 1, v5
	v_lshrrev_b32_e32 v1, 2, v4
	v_and_b32_e32 v0, 0x60, v0
	v_and_b32_e32 v1, 12, v1
	v_or3_b32 v0, v1, v0, s26
	v_ashrrev_i32_e32 v1, 31, v0
	v_lshlrev_b64 v[2:3], 2, v[0:1]
	v_readlane_b32 s78, v255, 34
	v_readlane_b32 s79, v255, 35
	v_readlane_b32 s80, v255, 36
	v_readlane_b32 s81, v255, 37
	v_lshl_add_u64 v[132:133], s[78:79], 0, v[2:3]
	v_and_b32_e32 v1, 15, v4
	v_lshl_add_u64 v[134:135], s[80:81], 0, v[2:3]
	global_load_dwordx4 v[158:161], v[132:133], off
	global_load_dwordx4 v[162:165], v[134:135], off
	global_load_dwordx4 v[228:231], v[132:133], off offset:64
	global_load_dwordx4 v[232:235], v[134:135], off offset:64
	global_load_dwordx4 v[236:239], v[132:133], off offset:512
	global_load_dwordx4 v[240:243], v[134:135], off offset:512
	global_load_dwordx4 v[244:247], v[132:133], off offset:576
	global_load_dwordx4 v[248:251], v[134:135], off offset:576
	v_ashrrev_i32_e32 v2, 2, v5
	v_and_b32_e32 v2, 0xffffffc0, v2
	v_lshl_add_u32 v3, s40, 8, v2
	v_or_b32_e32 v2, v2, v1
	v_lshl_add_u32 v12, v2, 3, v219
	v_or_b32_e32 v4, v3, v1
	v_lshlrev_b32_e32 v5, 2, v0
	ds_read2_b64 v[0:3], v12 offset1:16
	v_lshl_add_u32 v138, v4, 13, v5
	ds_read2_b64 v[4:7], v12 offset0:32 offset1:48
	ds_read2_b64 v[8:11], v12 offset0:128 offset1:144
	ds_read2_b64 v[12:15], v12 offset0:160 offset1:176
	s_mov_b32 s26, s18
	s_mov_b32 s27, s19
	s_waitcnt lgkmcnt(3)
	v_sub_f32_e32 v129, v129, v0
	v_sub_f32_e32 v128, v128, v0
	v_sub_f32_e32 v131, v131, v0
	v_sub_f32_e32 v130, v130, v0
	v_sub_f32_e32 v123, v123, v2
	v_sub_f32_e32 v122, v122, v2
	v_sub_f32_e32 v121, v121, v2
	v_sub_f32_e32 v120, v120, v2
	s_waitcnt lgkmcnt(2)
	v_sub_f32_e32 v107, v107, v4
	v_sub_f32_e32 v106, v106, v4
	v_sub_f32_e32 v105, v105, v4
	v_sub_f32_e32 v104, v104, v4
	v_sub_f32_e32 v91, v91, v6
	v_sub_f32_e32 v90, v90, v6
	v_sub_f32_e32 v89, v89, v6
	v_sub_f32_e32 v88, v88, v6
	s_waitcnt lgkmcnt(1)
	v_sub_f32_e32 v63, v63, v8
	v_sub_f32_e32 v62, v62, v8
	v_sub_f32_e32 v61, v61, v8
	v_sub_f32_e32 v60, v60, v8
	v_sub_f32_e32 v47, v47, v10
	v_sub_f32_e32 v46, v46, v10
	v_sub_f32_e32 v45, v45, v10
	v_sub_f32_e32 v44, v44, v10
	v_pk_mul_f32 v[130:131], v[0:1], v[130:131] op_sel:[1,0]
	v_pk_mul_f32 v[128:129], v[0:1], v[128:129] op_sel:[1,0]
	v_pk_mul_f32 v[120:121], v[2:3], v[120:121] op_sel:[1,0]
	v_pk_mul_f32 v[122:123], v[2:3], v[122:123] op_sel:[1,0]
	v_pk_mul_f32 v[104:105], v[4:5], v[104:105] op_sel:[1,0]
	v_pk_mul_f32 v[106:107], v[4:5], v[106:107] op_sel:[1,0]
	v_pk_mul_f32 v[150:151], v[6:7], v[88:89] op_sel:[1,0]
	v_pk_mul_f32 v[154:155], v[6:7], v[90:91] op_sel:[1,0]
	v_pk_mul_f32 v[166:167], v[8:9], v[60:61] op_sel:[1,0]
	v_pk_mul_f32 v[168:169], v[8:9], v[62:63] op_sel:[1,0]
	v_pk_mul_f32 v[170:171], v[10:11], v[44:45] op_sel:[1,0]
	v_pk_mul_f32 v[172:173], v[10:11], v[46:47] op_sel:[1,0]
	v_add_u32_e32 v139, 0x20000, v138
	v_add_u32_e32 v140, 0x40000, v138
	v_add_u32_e32 v141, 0x60000, v138
	v_add_u32_e32 v148, 0x100000, v138
	v_add_u32_e32 v149, 0x120000, v138
	v_sub_f32_e32 v93, v93, v4
	v_sub_f32_e32 v92, v92, v4
	v_sub_f32_e32 v95, v95, v4
	v_sub_f32_e32 v94, v94, v4
	v_sub_f32_e32 v77, v77, v6
	v_sub_f32_e32 v76, v76, v6
	v_sub_f32_e32 v79, v79, v6
	v_sub_f32_e32 v78, v78, v6
	v_sub_f32_e32 v57, v57, v8
	v_sub_f32_e32 v56, v56, v8
	v_sub_f32_e32 v59, v59, v8
	v_sub_f32_e32 v58, v58, v8
	v_sub_f32_e32 v41, v41, v10
	v_sub_f32_e32 v40, v40, v10
	v_sub_f32_e32 v43, v43, v10
	v_sub_f32_e32 v42, v42, v10
	s_waitcnt lgkmcnt(0)
	v_sub_f32_e32 v29, v29, v12
	v_sub_f32_e32 v28, v28, v12
	v_sub_f32_e32 v73, v73, v12
	v_sub_f32_e32 v72, v72, v12
	v_pk_mul_f32 v[94:95], v[4:5], v[94:95] op_sel:[1,0]
	v_pk_mul_f32 v[92:93], v[4:5], v[92:93] op_sel:[1,0]
	v_pk_mul_f32 v[72:73], v[12:13], v[72:73] op_sel:[1,0]
	v_pk_mul_f32 v[28:29], v[12:13], v[28:29] op_sel:[1,0]
	v_sub_f32_e32 v69, v69, v6
	v_sub_f32_e32 v68, v68, v6
	s_waitcnt vmcnt(0)
	v_pk_fma_f32 v[44:45], v[158:159], v[128:129], v[162:163]
	v_pk_fma_f32 v[46:47], v[160:161], v[130:131], v[164:165]
	v_pk_fma_f32 v[62:63], v[160:161], v[122:123], v[164:165]
	v_pk_fma_f32 v[60:61], v[158:159], v[120:121], v[162:163]
	v_pk_fma_f32 v[90:91], v[160:161], v[106:107], v[164:165]
	v_pk_fma_f32 v[88:89], v[158:159], v[104:105], v[162:163]
	v_pk_fma_f32 v[106:107], v[160:161], v[154:155], v[164:165]
	v_pk_fma_f32 v[104:105], v[158:159], v[150:151], v[162:163]
	v_pk_fma_f32 v[122:123], v[160:161], v[168:169], v[164:165]
	v_pk_fma_f32 v[120:121], v[158:159], v[166:167], v[162:163]
	v_pk_fma_f32 v[130:131], v[160:161], v[172:173], v[164:165]
	v_pk_fma_f32 v[128:129], v[158:159], v[170:171], v[162:163]
	buffer_store_dwordx4 v[44:47], v138, s[24:27], 0 offen
	buffer_store_dwordx4 v[60:63], v139, s[24:27], 0 offen
	buffer_store_dwordx4 v[88:91], v140, s[24:27], 0 offen
	buffer_store_dwordx4 v[104:107], v141, s[24:27], 0 offen
	buffer_store_dwordx4 v[120:123], v148, s[24:27], 0 offen
	buffer_store_dwordx4 v[128:131], v149, s[24:27], 0 offen
	v_sub_f32_e32 v45, v153, v12
	v_sub_f32_e32 v44, v152, v12
	v_sub_f32_e32 v47, v157, v12
	v_sub_f32_e32 v46, v156, v12
	v_pk_mul_f32 v[46:47], v[12:13], v[46:47] op_sel:[1,0]
	v_pk_mul_f32 v[44:45], v[12:13], v[44:45] op_sel:[1,0]
	v_pk_fma_f32 v[60:61], v[158:159], v[46:47], v[162:163]
	v_pk_fma_f32 v[62:63], v[160:161], v[44:45], v[164:165]
	v_add_u32_e32 v44, 0x140000, v138
	buffer_store_dwordx4 v[60:63], v44, s[24:27], 0 offen
	v_sub_f32_e32 v47, v147, v14
	v_sub_f32_e32 v46, v146, v14
;     ...
;         _Pragma("unroll") for (int bj = 0; bj < 2; ++bj) _Pragma("unroll") for (int n = 0; n < 2; ++n) {
;           const int col = pn * BM + bj * HALF + wc3 * 32 + n * 16 + fq3 * 4;
;           const float4 gm = *reinterpret_cast<const float4*>(g.gam + col), bt = *reinterpret_cast<const float4*>(g.bet + col);
;           _Pragma("unroll") for (int ai = 0; ai < 2; ++ai) _Pragma("unroll") for (int m = 0; m < 4; ++m) {
;             const int rl = ai * HALF + wr3 * 64 + m * 16 + fr3;
;             const float2 ms = *reinterpret_cast<const float2*>(mr + rl * 2);
;             f32x4 y = acc[ai][bj][m][n];
;             u32x4 o;
;             o[0] = __float_as_uint((y[0] - ms.x) * ms.y * gm.x + bt.x); o[1] = __float_as_uint((y[1] - ms.x) * ms.y * gm.y + bt.y);
;             o[2] = __float_as_uint((y[2] - ms.x) * ms.y * gm.z + bt.z); o[3] = __float_as_uint((y[3] - ms.x) * ms.y * gm.w + bt.w);
;             __builtin_amdgcn_raw_buffer_store_b128(o, rsO, vo4b + ((ai * HALF + m * 16) * DM + bj * HALF + n * 16) * 4, 0, 0);
;           }
	v_sub_f32_e32 v61, v145, v14
	v_sub_f32_e32 v60, v144, v14
	v_pk_mul_f32 v[60:61], v[14:15], v[60:61] op_sel:[1,0]
	v_pk_mul_f32 v[46:47], v[14:15], v[46:47] op_sel:[1,0]
	v_pk_fma_f32 v[60:61], v[158:159], v[60:61], v[162:163]
	v_pk_fma_f32 v[62:63], v[160:161], v[46:47], v[164:165]
	v_add_u32_e32 v45, 0x160000, v138
	buffer_store_dwordx4 v[60:63], v45, s[24:27], 0 offen
	s_nop 1
	v_mov_b32_e32 v60, v228
	v_mov_b32_e32 v61, v229
	v_mov_b32_e32 v62, v230
	v_mov_b32_e32 v63, v231
	s_nop 0
	v_mov_b32_e32 v88, v232
	v_mov_b32_e32 v89, v233
	v_mov_b32_e32 v90, v234
	v_mov_b32_e32 v91, v235
	v_sub_f32_e32 v47, v125, v0
	v_sub_f32_e32 v46, v124, v0
	v_sub_f32_e32 v105, v127, v0
	v_sub_f32_e32 v104, v126, v0
	v_sub_f32_e32 v107, v109, v2
	v_sub_f32_e32 v106, v108, v2
	v_sub_f32_e32 v109, v111, v2
	v_sub_f32_e32 v108, v110, v2
	v_pk_mul_f32 v[104:105], v[0:1], v[104:105] op_sel:[1,0]
	v_pk_mul_f32 v[46:47], v[0:1], v[46:47] op_sel:[1,0]
	v_pk_mul_f32 v[108:109], v[2:3], v[108:109] op_sel:[1,0]
	v_pk_mul_f32 v[106:107], v[2:3], v[106:107] op_sel:[1,0]
	v_pk_mul_f32 v[110:111], v[6:7], v[78:79] op_sel:[1,0]
	v_pk_mul_f32 v[120:121], v[6:7], v[76:77] op_sel:[1,0]
	v_pk_mul_f32 v[122:123], v[8:9], v[58:59] op_sel:[1,0]
	v_pk_mul_f32 v[124:125], v[8:9], v[56:57] op_sel:[1,0]
	v_pk_mul_f32 v[126:127], v[10:11], v[42:43] op_sel:[1,0]
	v_pk_mul_f32 v[128:129], v[10:11], v[40:41] op_sel:[1,0]
	v_sub_f32_e32 v71, v71, v6
	v_sub_f32_e32 v70, v70, v6
	v_sub_f32_e32 v53, v53, v8
	v_sub_f32_e32 v52, v52, v8
	v_sub_f32_e32 v55, v55, v8
	v_sub_f32_e32 v54, v54, v8
	v_sub_f32_e32 v37, v37, v10
	v_sub_f32_e32 v36, v36, v10
	v_sub_f32_e32 v39, v39, v10
	v_sub_f32_e32 v38, v38, v10
	v_sub_f32_e32 v25, v25, v12
	v_sub_f32_e32 v24, v24, v12
	v_sub_f32_e32 v27, v27, v12
	v_sub_f32_e32 v26, v26, v12
	v_pk_mul_f32 v[70:71], v[6:7], v[70:71] op_sel:[1,0]
	v_pk_mul_f32 v[68:69], v[6:7], v[68:69] op_sel:[1,0]
	v_sub_f32_e32 v49, v49, v8
	v_sub_f32_e32 v48, v48, v8
	v_sub_f32_e32 v51, v51, v8
	v_sub_f32_e32 v50, v50, v8
	v_sub_f32_e32 v33, v33, v10
	v_sub_f32_e32 v32, v32, v10
	v_sub_f32_e32 v35, v35, v10
	v_sub_f32_e32 v34, v34, v10
	v_sub_f32_e32 v17, v17, v12
	v_sub_f32_e32 v16, v16, v12
	v_sub_f32_e32 v19, v19, v12
	v_sub_f32_e32 v18, v18, v12
	v_sub_f32_e32 v21, v21, v14
	v_sub_f32_e32 v20, v20, v14
	v_sub_f32_e32 v23, v23, v14
	v_sub_f32_e32 v22, v22, v14
	s_andn2_b64 vcc, exec, s[14:15]
	v_pk_mul_f32 v[50:51], v[8:9], v[50:51] op_sel:[1,0]
	v_pk_mul_f32 v[48:49], v[8:9], v[48:49] op_sel:[1,0]
	v_pk_mul_f32 v[34:35], v[10:11], v[34:35] op_sel:[1,0]
	v_pk_mul_f32 v[32:33], v[10:11], v[32:33] op_sel:[1,0]
	s_mov_b64 s[6:7], -1
	v_readlane_b32 s77, v255, 33
	v_readlane_b32 s82, v255, 38
	v_readlane_b32 s83, v255, 39
	v_pk_fma_f32 v[40:41], v[46:47], v[60:61], v[88:89]
	v_pk_fma_f32 v[42:43], v[104:105], v[62:63], v[90:91]
	v_pk_fma_f32 v[56:57], v[106:107], v[60:61], v[88:89]
	v_pk_fma_f32 v[58:59], v[108:109], v[62:63], v[90:91]
	v_pk_fma_f32 v[76:77], v[92:93], v[60:61], v[88:89]
	v_pk_fma_f32 v[78:79], v[94:95], v[62:63], v[90:91]
	v_pk_fma_f32 v[92:93], v[120:121], v[60:61], v[88:89]
	v_pk_fma_f32 v[94:95], v[110:111], v[62:63], v[90:91]
	v_pk_fma_f32 v[104:105], v[124:125], v[60:61], v[88:89]
	v_pk_fma_f32 v[106:107], v[122:123], v[62:63], v[90:91]
	v_pk_fma_f32 v[108:109], v[128:129], v[60:61], v[88:89]
	v_pk_fma_f32 v[110:111], v[126:127], v[62:63], v[90:91]
	buffer_store_dwordx4 v[40:43], v138, s[24:27], 0 offen offset:64
	buffer_store_dwordx4 v[56:59], v139, s[24:27], 0 offen offset:64
	buffer_store_dwordx4 v[76:79], v140, s[24:27], 0 offen offset:64
	buffer_store_dwordx4 v[92:95], v141, s[24:27], 0 offen offset:64
	buffer_store_dwordx4 v[104:107], v148, s[24:27], 0 offen offset:64
	buffer_store_dwordx4 v[108:111], v149, s[24:27], 0 offen offset:64
	v_pk_fma_f32 v[40:41], v[28:29], v[60:61], v[88:89]
	v_pk_fma_f32 v[42:43], v[72:73], v[62:63], v[90:91]
	buffer_store_dwordx4 v[40:43], v44, s[24:27], 0 offen offset:64
	v_sub_f32_e32 v29, v143, v14
	v_sub_f32_e32 v28, v142, v14
	v_sub_f32_e32 v41, v137, v14
	v_sub_f32_e32 v40, v136, v14
	v_pk_mul_f32 v[42:43], v[14:15], v[40:41] op_sel:[1,0]
	v_pk_mul_f32 v[28:29], v[14:15], v[28:29] op_sel:[1,0]
	v_pk_fma_f32 v[42:43], v[42:43], v[62:63], v[90:91]
	v_pk_fma_f32 v[40:41], v[28:29], v[60:61], v[88:89]
	buffer_store_dwordx4 v[40:43], v45, s[24:27], 0 offen offset:64
	s_nop 1
	v_mov_b32_e32 v40, v236
	v_mov_b32_e32 v41, v237
	v_mov_b32_e32 v42, v238
	v_mov_b32_e32 v43, v239
	s_nop 0
	v_mov_b32_e32 v56, v240
	v_mov_b32_e32 v57, v241
	v_mov_b32_e32 v58, v242
	v_mov_b32_e32 v59, v243
	v_sub_f32_e32 v29, v117, v0
	v_sub_f32_e32 v28, v116, v0
	v_sub_f32_e32 v47, v119, v0
	v_sub_f32_e32 v46, v118, v0
	v_sub_f32_e32 v61, v101, v2
	v_sub_f32_e32 v60, v100, v2
	v_sub_f32_e32 v63, v103, v2
	v_sub_f32_e32 v62, v102, v2
	v_sub_f32_e32 v73, v85, v4
	v_sub_f32_e32 v72, v84, v4
	v_sub_f32_e32 v77, v87, v4
	v_sub_f32_e32 v76, v86, v4
	v_pk_mul_f32 v[46:47], v[0:1], v[46:47] op_sel:[1,0]
	v_pk_mul_f32 v[28:29], v[0:1], v[28:29] op_sel:[1,0]
	v_sub_f32_e32 v79, v31, v14
	v_sub_f32_e32 v78, v30, v14
	v_sub_f32_e32 v31, v75, v14
	v_sub_f32_e32 v30, v74, v14
	v_pk_mul_f32 v[62:63], v[2:3], v[62:63] op_sel:[1,0]
	v_pk_mul_f32 v[60:61], v[2:3], v[60:61] op_sel:[1,0]
	v_pk_mul_f32 v[74:75], v[4:5], v[76:77] op_sel:[1,0]
	v_pk_mul_f32 v[72:73], v[4:5], v[72:73] op_sel:[1,0]
	v_pk_mul_f32 v[76:77], v[8:9], v[54:55] op_sel:[1,0]
	v_pk_mul_f32 v[84:85], v[8:9], v[52:53] op_sel:[1,0]
	v_pk_mul_f32 v[86:87], v[10:11], v[38:39] op_sel:[1,0]
	v_pk_mul_f32 v[88:89], v[10:11], v[36:37] op_sel:[1,0]
	v_pk_mul_f32 v[90:91], v[12:13], v[26:27] op_sel:[1,0]
;     ...
;         _Pragma("unroll") for (int bj = 0; bj < 2; ++bj) _Pragma("unroll") for (int n = 0; n < 2; ++n) {
;           const int col = pn * BM + bj * HALF + wc3 * 32 + n * 16 + fq3 * 4;
;           const float4 gm = *reinterpret_cast<const float4*>(g.gam + col), bt = *reinterpret_cast<const float4*>(g.bet + col);
;           _Pragma("unroll") for (int ai = 0; ai < 2; ++ai) _Pragma("unroll") for (int m = 0; m < 4; ++m) {
;             const int rl = ai * HALF + wr3 * 64 + m * 16 + fr3;
;             const float2 ms = *reinterpret_cast<const float2*>(mr + rl * 2);
;             f32x4 y = acc[ai][bj][m][n];
;             u32x4 o;
;             o[0] = __float_as_uint((y[0] - ms.x) * ms.y * gm.x + bt.x); o[1] = __float_as_uint((y[1] - ms.x) * ms.y * gm.y + bt.y);
;             o[2] = __float_as_uint((y[2] - ms.x) * ms.y * gm.z + bt.z); o[3] = __float_as_uint((y[3] - ms.x) * ms.y * gm.w + bt.w);
;             __builtin_amdgcn_raw_buffer_store_b128(o, rsO, vo4b + ((ai * HALF + m * 16) * DM + bj * HALF + n * 16) * 4, 0, 0);
;           }
	v_pk_mul_f32 v[92:93], v[12:13], v[24:25] op_sel:[1,0]
	v_pk_mul_f32 v[94:95], v[14:15], v[30:31] op_sel:[1,0]
	v_pk_fma_f32 v[24:25], v[28:29], v[40:41], v[56:57]
	v_pk_fma_f32 v[26:27], v[46:47], v[42:43], v[58:59]
	v_pk_fma_f32 v[28:29], v[60:61], v[40:41], v[56:57]
	v_pk_fma_f32 v[30:31], v[62:63], v[42:43], v[58:59]
	v_pk_fma_f32 v[36:37], v[72:73], v[40:41], v[56:57]
	v_pk_fma_f32 v[38:39], v[74:75], v[42:43], v[58:59]
	v_pk_fma_f32 v[52:53], v[68:69], v[40:41], v[56:57]
	v_pk_fma_f32 v[54:55], v[70:71], v[42:43], v[58:59]
	v_pk_fma_f32 v[60:61], v[84:85], v[40:41], v[56:57]
	v_pk_fma_f32 v[62:63], v[76:77], v[42:43], v[58:59]
	v_pk_fma_f32 v[68:69], v[88:89], v[40:41], v[56:57]
	v_pk_fma_f32 v[70:71], v[86:87], v[42:43], v[58:59]
	v_pk_fma_f32 v[72:73], v[92:93], v[40:41], v[56:57]
	v_pk_fma_f32 v[74:75], v[90:91], v[42:43], v[58:59]
	buffer_store_dwordx4 v[24:27], v138, s[24:27], 0 offen offset:512
	buffer_store_dwordx4 v[28:31], v139, s[24:27], 0 offen offset:512
	buffer_store_dwordx4 v[36:39], v140, s[24:27], 0 offen offset:512
	buffer_store_dwordx4 v[52:55], v141, s[24:27], 0 offen offset:512
	buffer_store_dwordx4 v[60:63], v148, s[24:27], 0 offen offset:512
	buffer_store_dwordx4 v[68:71], v149, s[24:27], 0 offen offset:512
	buffer_store_dwordx4 v[72:75], v44, s[24:27], 0 offen offset:512
	v_pk_mul_f32 v[24:25], v[14:15], v[78:79] op_sel:[1,0]
	v_pk_fma_f32 v[26:27], v[94:95], v[42:43], v[58:59]
	v_pk_fma_f32 v[24:25], v[24:25], v[40:41], v[56:57]
	buffer_store_dwordx4 v[24:27], v45, s[24:27], 0 offen offset:512
	s_nop 1
	v_mov_b32_e32 v24, v244
	v_mov_b32_e32 v25, v245
	v_mov_b32_e32 v26, v246
	v_mov_b32_e32 v27, v247
	s_nop 0
	v_mov_b32_e32 v28, v248
	v_mov_b32_e32 v29, v249
	v_mov_b32_e32 v30, v250
	v_mov_b32_e32 v31, v251
	v_sub_f32_e32 v37, v113, v0
	v_sub_f32_e32 v36, v112, v0
	v_sub_f32_e32 v39, v115, v0
	v_sub_f32_e32 v38, v114, v0
	v_sub_f32_e32 v41, v97, v2
	v_sub_f32_e32 v40, v96, v2
	v_sub_f32_e32 v43, v99, v2
	v_sub_f32_e32 v42, v98, v2
	v_sub_f32_e32 v47, v81, v4
	v_sub_f32_e32 v46, v80, v4
	v_sub_f32_e32 v53, v83, v4
	v_sub_f32_e32 v52, v82, v4
	v_sub_f32_e32 v55, v65, v6
	v_sub_f32_e32 v54, v64, v6
	v_sub_f32_e32 v57, v67, v6
	v_sub_f32_e32 v56, v66, v6
	v_pk_mul_f32 v[38:39], v[0:1], v[38:39] op_sel:[1,0]
	v_pk_mul_f32 v[0:1], v[0:1], v[36:37] op_sel:[1,0]
	v_pk_mul_f32 v[36:37], v[2:3], v[42:43] op_sel:[1,0]
	v_pk_mul_f32 v[40:41], v[2:3], v[40:41] op_sel:[1,0]
	v_pk_mul_f32 v[42:43], v[4:5], v[52:53] op_sel:[1,0]
	v_pk_mul_f32 v[46:47], v[4:5], v[46:47] op_sel:[1,0]
	v_pk_mul_f32 v[52:53], v[6:7], v[56:57] op_sel:[1,0]
	v_pk_mul_f32 v[54:55], v[6:7], v[54:55] op_sel:[1,0]
	v_pk_mul_f32 v[56:57], v[12:13], v[18:19] op_sel:[1,0]
	v_pk_mul_f32 v[58:59], v[12:13], v[16:17] op_sel:[1,0]
	v_pk_mul_f32 v[60:61], v[14:15], v[22:23] op_sel:[1,0]
	v_pk_mul_f32 v[62:63], v[14:15], v[20:21] op_sel:[1,0]
	v_pk_fma_f32 v[0:1], v[0:1], v[24:25], v[28:29]
	v_pk_fma_f32 v[2:3], v[38:39], v[26:27], v[30:31]
	v_pk_fma_f32 v[4:5], v[40:41], v[24:25], v[28:29]
	v_pk_fma_f32 v[6:7], v[36:37], v[26:27], v[30:31]
	v_pk_fma_f32 v[8:9], v[46:47], v[24:25], v[28:29]
	v_pk_fma_f32 v[10:11], v[42:43], v[26:27], v[30:31]
	v_pk_fma_f32 v[12:13], v[54:55], v[24:25], v[28:29]
	v_pk_fma_f32 v[14:15], v[52:53], v[26:27], v[30:31]
	v_pk_fma_f32 v[16:17], v[48:49], v[24:25], v[28:29]
	v_pk_fma_f32 v[18:19], v[50:51], v[26:27], v[30:31]
	v_pk_fma_f32 v[20:21], v[32:33], v[24:25], v[28:29]
	v_pk_fma_f32 v[22:23], v[34:35], v[26:27], v[30:31]
	v_pk_fma_f32 v[32:33], v[58:59], v[24:25], v[28:29]
	v_pk_fma_f32 v[34:35], v[56:57], v[26:27], v[30:31]
	v_pk_fma_f32 v[24:25], v[62:63], v[24:25], v[28:29]
	v_pk_fma_f32 v[26:27], v[60:61], v[26:27], v[30:31]
	buffer_store_dwordx4 v[0:3], v138, s[24:27], 0 offen offset:576
	buffer_store_dwordx4 v[4:7], v139, s[24:27], 0 offen offset:576
	buffer_store_dwordx4 v[8:11], v140, s[24:27], 0 offen offset:576
	buffer_store_dwordx4 v[12:15], v141, s[24:27], 0 offen offset:576
	buffer_store_dwordx4 v[16:19], v148, s[24:27], 0 offen offset:576
	buffer_store_dwordx4 v[20:23], v149, s[24:27], 0 offen offset:576
	buffer_store_dwordx4 v[32:35], v44, s[24:27], 0 offen offset:576
	buffer_store_dwordx4 v[24:27], v45, s[24:27], 0 offen offset:576
	s_cbranch_vccnz .LBB0_749
; #define STAGE(P, RS, SOFF, OFF, kt) do { const int _so = (SOFF) + (kt) * (BK * 2); \
;     _Pragma("unroll") for (int _i = 0; _i < 2; ++_i) { \
;       __builtin_amdgcn_raw_ptr_buffer_load_lds(RS, (__attribute__((address_space(3))) void*)((P) + wave * 1024 + _i * 8192), 16, OFF[_i], _so, 0, 0); } } while (0)
;     ...
;   auto issue_prologue = [&](int sA0, int sA1, int sB0, int sB1) {
;     const int tid = opaque_tid(wave);
;     int offA[2], offB[2];
;     _Pragma("unroll") for (int i = 0; i < 2; ++i) {
;       int r, c; stage_rc(tid * 16 + i * 8192, r, c);
;       offA[i] = (r * lda + c) * 2; offB[i] = (r * ldb + c) * 2;
;     }
;     STAGE(SB(0, 0), rsB, sB0, offB, 0); STAGE(SA(0, 0), rsA, sA0, offA, 0);
;     STAGE(SB(0, 1), rsB, sB1, offB, 0); STAGE(SA(0, 1), rsA, sA1, offA, 0);
;     STAGE(SB(1, 0), rsB, sB0, offB, 1); STAGE(SA(1, 0), rsA, sA0, offA, 1); STAGE(SB(1, 1), rsB, sB1, offB, 1);
;   };
;     ...
;       if (has_next) issue_prologue(nA0, nA1, nB0, nB1);
	v_mbcnt_lo_u32_b32 v0, -1, 0
	v_mbcnt_hi_u32_b32 v0, -1, v0
	s_mov_b32 m0, s42
	v_lshl_add_u32 v0, v0, 4, s33
	v_ashrrev_i32_e32 v1, 31, v0
	v_lshrrev_b32_e32 v1, 22, v1
	v_add_u32_e32 v1, v0, v1
	v_ashrrev_i32_e32 v1, 10, v1
	v_mul_i32_i24_e32 v2, 0x400, v1
	v_sub_u32_e32 v2, v0, v2
	v_lshrrev_b32_e32 v3, 4, v2
	v_bitop3_b32 v2, v3, v2, 32 bitop3:0x6c
	v_ashrrev_i32_e32 v4, 31, v2
	v_lshrrev_b32_e32 v4, 26, v4
	v_add_u32_e32 v4, v2, v4
	v_lshrrev_b32_e32 v5, 6, v4
	v_and_b32_e32 v4, 0xc0, v4
	v_lshlrev_b32_e32 v3, 3, v1
	v_lshlrev_b32_e32 v1, 5, v1
	v_sub_u32_e32 v2, v2, v4
	v_and_b32_e32 v3, 0x7fff0, v3
	v_and_b32_e32 v1, 32, v1
	v_ashrrev_i16_sdwa v2, v216, sext(v2) dst_sel:DWORD dst_unused:UNUSED_PAD src0_sel:DWORD src1_sel:BYTE_0
	v_add_u32_sdwa v1, v1, sext(v2) dst_sel:DWORD dst_unused:UNUSED_PAD src0_sel:DWORD src1_sel:WORD_0
	v_add_lshl_u32 v2, v5, v3, 13
	v_add_u32_e32 v0, 0x2000, v0
	v_lshl_add_u32 v1, v1, 1, v2
	v_ashrrev_i32_e32 v2, 31, v0
	v_lshrrev_b32_e32 v2, 22, v2
	v_add_u32_e32 v2, v0, v2
	v_ashrrev_i32_e32 v2, 10, v2
	v_mul_i32_i24_e32 v3, 0x400, v2
	v_sub_u32_e32 v0, v0, v3
	v_lshrrev_b32_e32 v3, 4, v0
	v_bitop3_b32 v0, v3, v0, 32 bitop3:0x6c
	v_ashrrev_i32_e32 v4, 31, v0
	v_lshrrev_b32_e32 v4, 26, v4
	v_add_u32_e32 v4, v0, v4
	v_lshrrev_b32_e32 v5, 6, v4
	v_and_b32_e32 v4, 0xffc0, v4
	v_sub_u32_e32 v0, v0, v4
	v_lshrrev_b16_e32 v4, 7, v0
	v_and_b32_e32 v4, 1, v4
	v_lshlrev_b32_e32 v3, 3, v2
	v_lshlrev_b32_e32 v2, 5, v2
	v_add_u16_e32 v0, v0, v4
	v_and_b32_e32 v3, 0x7fff0, v3
	v_and_b32_e32 v2, 32, v2
	v_ashrrev_i16_sdwa v0, v216, sext(v0) dst_sel:DWORD dst_unused:UNUSED_PAD src0_sel:DWORD src1_sel:BYTE_0
	v_add_u32_sdwa v0, v2, sext(v0) dst_sel:DWORD dst_unused:UNUSED_PAD src0_sel:DWORD src1_sel:WORD_0
	v_add_lshl_u32 v2, v5, v3, 13
	s_mov_b32 s14, s10
	s_mov_b32 s15, s11
	v_lshl_add_u32 v0, v0, 1, v2
	buffer_load_dwordx4 v1, s[12:15], s87 offen lds
	s_mov_b32 m0, s49
	s_or_b32 s4, s87, 0x80
	buffer_load_dwordx4 v0, s[12:15], s87 offen lds
	s_mov_b32 m0, s33
	s_mov_b64 s[6:7], 0
	buffer_load_dwordx4 v1, s[8:11], s86 offen lds
	s_mov_b32 m0, s50
	s_nop 0
	buffer_load_dwordx4 v0, s[8:11], s86 offen lds
	s_mov_b32 m0, s43
	s_nop 0
	buffer_load_dwordx4 v1, s[12:15], s90 offen lds
	s_mov_b32 m0, s51
	s_nop 0
	buffer_load_dwordx4 v0, s[12:15], s90 offen lds
	s_mov_b32 m0, s44
	s_nop 0
	buffer_load_dwordx4 v1, s[8:11], s85 offen lds
	s_mov_b32 m0, s52
	s_nop 0
	buffer_load_dwordx4 v0, s[8:11], s85 offen lds
	s_mov_b32 m0, s45
	s_nop 0
	buffer_load_dwordx4 v1, s[12:15], s4 offen lds
	s_mov_b32 m0, s53
	s_nop 0
	buffer_load_dwordx4 v0, s[12:15], s4 offen lds
	s_or_b32 s4, s86, 0x80
	s_mov_b32 m0, s46
	s_nop 0
	buffer_load_dwordx4 v1, s[8:11], s4 offen lds
	s_mov_b32 m0, s54
	s_nop 0
	buffer_load_dwordx4 v0, s[8:11], s4 offen lds
	s_add_i32 s4, s90, 0x80
	s_mov_b32 m0, s47
	s_nop 0
	buffer_load_dwordx4 v1, s[12:15], s4 offen lds
	s_mov_b32 m0, s55
	s_nop 0
	buffer_load_dwordx4 v0, s[12:15], s4 offen lds
	s_branch .LBB0_749
